# GEMM K-loops: tile loads use SGPR base + 32-bit VGPR offset (per-load 64-bit address adds removed), duplicate LDS waits removed
# speedup vs baseline: 1.0068x; 1.0068x over previous
; #define PG8_STAGE(bufoff, gbase, voff) do { _Pragma("unroll") for (int _i = 0; _i < 2; ++_i) \
;         __builtin_amdgcn_global_load_lds((const unsigned*)((const char*)(gbase) + (voff)[_i]), (PG8_LAS unsigned*)(lds + (bufoff) + ldsw + _i * 8192), 16, 0, 0); } while (0)
; #define PG8_LDA(dst, b, h) do { _Pragma("unroll") for (int m = 0; m < 4; ++m) _Pragma("unroll") for (int k = 0; k < 2; ++k) dst[m][k] = *(const PG8_LAS bf16x8*)(lds + PG8_SA(b, h) + aoff + m * 2048 + k * 1024); } while (0)
; #define PG8_LDB(dst, b, h) do { _Pragma("unroll") for (int n = 0; n < 2; ++n) _Pragma("unroll") for (int k = 0; k < 2; ++k) dst[n][k] = *(const PG8_LAS bf16x8*)(lds + PG8_SB(b, h) + boff + n * 2048 + k * 1024); } while (0)
; #define PG8_WAIT_L(n) asm volatile("s_waitcnt lgkmcnt(" #n ")" ::: "memory")
; #define PG8_BAR __builtin_amdgcn_s_barrier()
; #define PG8_SCHED __builtin_amdgcn_sched_barrier(0)
;     __device__ bool next(int i, pg8::Unit& u) const { if (i != 0 || !valid) return false; u.pm = pm; u.pn = pn; return true; }
; template <class Epi, class Sched, bool STAMP = false>
; __device__ __forceinline__ void gemm_phase(PG8_LAS unsigned char* lds, const Gemm g, const Sched& S, const Epi& E, unsigned long long* stamps) {
;     ...
;         const bool has_next = S.next(ui + 1, nxt);
;         const char* nA = has_next ? (const char*)g.A + (size_t)nxt.pm * tstep : cA; const char* nB = has_next ? (const char*)g.Bt + (size_t)nxt.pn * tstep : cB;
;         for (int t = 0; t < nt; t += 2) {
;             const bool last = (t == nt - 2);
;             const char* a1 = cA + (size_t)(t + 1) * kstep;
;             const char* a2 = last ? nA : cA + (size_t)(t + 2) * kstep; const char* b2 = last ? nB : cB + (size_t)(t + 2) * kstep;
;             const char* a3 = a2 + kstep; const char* b3 = b2 + kstep;
;             if (last && has_next) S.a_ready(nxt);
;             PG8_LDB(B0, 0, 0); PG8_SCHED; PG8_LDA(At, 0, 0); PG8_STAGE(PG8_SA(1, 1), a1 + hstep, voffA);
;             PG8_WAIT_L(8); PG8_BAR; PG8_WAIT_L(0); PG8_MMA(0, 0, At, B0); PG8_BAR; PG8_SCHED;
;     ...
; #pragma unroll
;         for (int a = 0; a < 2; ++a)
; #pragma unroll
;             for (int b = 0; b < 2; ++b)
; #pragma unroll
;                 for (int m = 0; m < 4; ++m)
; #pragma unroll
;                     for (int n = 0; n < 2; ++n) acc[a][b][m][n] = (f32x4){0.f, 0.f, 0.f, 0.f};
;         cur = nxt; cA = nA; cB = nB; ++ui;
.LBB0_43:
	s_ashr_i32 s7, s6, 31
	v_cmp_lt_i64_e32 vcc, s[12:13], v[132:133]
	s_lshl_b64 s[12:13], s[6:7], 19
	s_add_u32 s12, s37, s12
	s_addc_u32 s13, s40, s13
	s_and_b64 s[14:15], vcc, exec
	s_cselect_b32 s7, s13, s25
	s_cselect_b32 s57, s12, s24
	s_ashr_i32 s5, s4, 31
	s_lshl_b64 s[14:15], s[4:5], 19
	s_add_u32 s20, s41, s14
	s_addc_u32 s21, s42, s15
	s_and_b64 s[14:15], vcc, exec
	s_cselect_b32 s5, s21, s27
	s_cselect_b32 s58, s20, s26
	s_add_u32 s24, s24, 0x40080
	s_addc_u32 s25, s25, 0
	s_add_u32 s59, s26, 0x100
	v_mov_b32_e32 v0, 0
	s_addc_u32 s60, s27, 0
	s_mov_b32 s61, -2
	v_mov_b32_e32 v1, v0
	v_mov_b32_e32 v2, v0
	v_mov_b32_e32 v3, v0
	v_mov_b32_e32 v4, v0
	v_mov_b32_e32 v5, v0
	v_mov_b32_e32 v6, v0
	v_mov_b32_e32 v7, v0
	v_mov_b32_e32 v16, v0
	v_mov_b32_e32 v17, v0
	v_mov_b32_e32 v18, v0
	v_mov_b32_e32 v19, v0
	v_mov_b32_e32 v20, v0
	v_mov_b32_e32 v21, v0
	v_mov_b32_e32 v22, v0
	v_mov_b32_e32 v23, v0
	v_mov_b32_e32 v32, v0
	v_mov_b32_e32 v33, v0
	v_mov_b32_e32 v34, v0
	v_mov_b32_e32 v35, v0
	v_mov_b32_e32 v36, v0
	v_mov_b32_e32 v37, v0
	v_mov_b32_e32 v38, v0
	v_mov_b32_e32 v39, v0
	v_mov_b32_e32 v48, v0
	v_mov_b32_e32 v49, v0
	v_mov_b32_e32 v50, v0
	v_mov_b32_e32 v51, v0
	v_mov_b32_e32 v52, v0
	v_mov_b32_e32 v53, v0
	v_mov_b32_e32 v54, v0
	v_mov_b32_e32 v55, v0
	v_mov_b32_e32 v8, v0
	v_mov_b32_e32 v9, v0
	v_mov_b32_e32 v10, v0
	v_mov_b32_e32 v11, v0
	v_mov_b32_e32 v12, v0
	v_mov_b32_e32 v13, v0
	v_mov_b32_e32 v14, v0
	v_mov_b32_e32 v15, v0
	v_mov_b32_e32 v24, v0
	v_mov_b32_e32 v25, v0
	v_mov_b32_e32 v26, v0
	v_mov_b32_e32 v27, v0
	v_mov_b32_e32 v28, v0
	v_mov_b32_e32 v29, v0
	v_mov_b32_e32 v30, v0
	v_mov_b32_e32 v31, v0
	v_mov_b32_e32 v40, v0
	v_mov_b32_e32 v41, v0
	v_mov_b32_e32 v42, v0
	v_mov_b32_e32 v43, v0
	v_mov_b32_e32 v44, v0
	v_mov_b32_e32 v45, v0
	v_mov_b32_e32 v46, v0
	v_mov_b32_e32 v47, v0
	v_mov_b32_e32 v56, v0
	v_mov_b32_e32 v57, v0
	v_mov_b32_e32 v58, v0
	v_mov_b32_e32 v59, v0
	v_mov_b32_e32 v60, v0
	v_mov_b32_e32 v61, v0
	v_mov_b32_e32 v62, v0
	v_mov_b32_e32 v63, v0
	v_mov_b32_e32 v64, v0
	v_mov_b32_e32 v65, v0
	v_mov_b32_e32 v66, v0
	v_mov_b32_e32 v67, v0
	v_mov_b32_e32 v68, v0
	v_mov_b32_e32 v69, v0
	v_mov_b32_e32 v70, v0
	v_mov_b32_e32 v71, v0
	v_mov_b32_e32 v80, v0
	v_mov_b32_e32 v81, v0
	v_mov_b32_e32 v82, v0
	v_mov_b32_e32 v83, v0
	v_mov_b32_e32 v84, v0
	v_mov_b32_e32 v85, v0
	v_mov_b32_e32 v86, v0
	v_mov_b32_e32 v87, v0
	v_mov_b32_e32 v96, v0
	v_mov_b32_e32 v97, v0
	v_mov_b32_e32 v98, v0
	v_mov_b32_e32 v99, v0
	v_mov_b32_e32 v100, v0
	v_mov_b32_e32 v101, v0
	v_mov_b32_e32 v102, v0
	v_mov_b32_e32 v103, v0
	v_mov_b32_e32 v112, v0
	v_mov_b32_e32 v113, v0
	v_mov_b32_e32 v114, v0
	v_mov_b32_e32 v115, v0
	v_mov_b32_e32 v116, v0
	v_mov_b32_e32 v117, v0
	v_mov_b32_e32 v118, v0
	v_mov_b32_e32 v119, v0
	v_mov_b32_e32 v72, v0
	v_mov_b32_e32 v73, v0
	v_mov_b32_e32 v74, v0
	v_mov_b32_e32 v75, v0
	v_mov_b32_e32 v76, v0
	v_mov_b32_e32 v77, v0
	v_mov_b32_e32 v78, v0
	v_mov_b32_e32 v79, v0
	v_mov_b32_e32 v88, v0
	v_mov_b32_e32 v89, v0
	v_mov_b32_e32 v90, v0
	v_mov_b32_e32 v91, v0
	v_mov_b32_e32 v92, v0
	v_mov_b32_e32 v93, v0
	v_mov_b32_e32 v94, v0
	v_mov_b32_e32 v95, v0
	v_mov_b32_e32 v104, v0
	v_mov_b32_e32 v105, v0
	v_mov_b32_e32 v106, v0
	v_mov_b32_e32 v107, v0
	v_mov_b32_e32 v108, v0
	v_mov_b32_e32 v109, v0
	v_mov_b32_e32 v110, v0
	v_mov_b32_e32 v111, v0
	v_mov_b32_e32 v120, v0
	v_mov_b32_e32 v121, v0
	v_mov_b32_e32 v122, v0
	v_mov_b32_e32 v123, v0
	v_mov_b32_e32 v124, v0
	v_mov_b32_e32 v125, v0
	v_mov_b32_e32 v126, v0
	v_mov_b32_e32 v127, v0
	v_add_u32_e32 v244, 0x80, v128
	v_add_u32_e32 v245, 0x80, v148
	v_add_u32_e32 v246, 0x80, v152
	v_add_u32_e32 v247, 0x80, v150
.LBB0_44:
	s_add_u32 s14, s24, 0xfffc0080
	s_addc_u32 s15, s25, -1
	s_add_i32 s16, 0, 0x10000
	v_add_u32_e32 v169, s16, v166
	ds_read_b128 v[158:161], v169
	ds_read_b128 v[162:165], v169 offset:1024
	ds_read_b128 v[170:173], v169 offset:2048
	ds_read_b128 v[174:177], v169 offset:3072
	s_cmp_eq_u32 s61, 12
	s_cselect_b32 s31, s7, s15
	s_cselect_b32 s30, s57, s14
	s_cselect_b32 s27, s5, s60
	s_cselect_b32 s26, s58, s59
	s_add_i32 m0, s23, 0xc000
	ds_read_b128 v[178:181], v168
	ds_read_b128 v[192:195], v168 offset:1024
	ds_read_b128 v[196:199], v168 offset:2048
	ds_read_b128 v[200:203], v168 offset:3072
	ds_read_b128 v[204:207], v168 offset:4096
	ds_read_b128 v[208:211], v168 offset:5120
	ds_read_b128 v[212:215], v168 offset:6144
	ds_read_b128 v[216:219], v168 offset:7168
	global_load_lds_dwordx4 v154, s[24:25]
	s_add_i32 m0, s23, 0xe000
	s_nop 0
	global_load_lds_dwordx4 v156, s[24:25]
	s_waitcnt lgkmcnt(8)
	s_barrier
	s_waitcnt lgkmcnt(0)
	v_mfma_f32_16x16x32_bf16 v[124:127], v[158:161], v[178:181], v[124:127]
	v_mfma_f32_16x16x32_bf16 v[120:123], v[170:173], v[178:181], v[120:123]
	v_mfma_f32_16x16x32_bf16 v[108:111], v[158:161], v[196:199], v[108:111]
	v_mfma_f32_16x16x32_bf16 v[104:107], v[170:173], v[196:199], v[104:107]
	v_mfma_f32_16x16x32_bf16 v[92:95], v[158:161], v[204:207], v[92:95]
	v_mfma_f32_16x16x32_bf16 v[88:91], v[170:173], v[204:207], v[88:91]
	v_mfma_f32_16x16x32_bf16 v[76:79], v[158:161], v[212:215], v[76:79]
	v_mfma_f32_16x16x32_bf16 v[72:75], v[170:173], v[212:215], v[72:75]
	v_mfma_f32_16x16x32_bf16 v[124:127], v[162:165], v[192:195], v[124:127]
	v_mfma_f32_16x16x32_bf16 v[120:123], v[174:177], v[192:195], v[120:123]
	v_mfma_f32_16x16x32_bf16 v[108:111], v[162:165], v[200:203], v[108:111]
	v_mfma_f32_16x16x32_bf16 v[104:107], v[174:177], v[200:203], v[104:107]
	v_mfma_f32_16x16x32_bf16 v[92:95], v[162:165], v[208:211], v[92:95]
	v_mfma_f32_16x16x32_bf16 v[88:91], v[174:177], v[208:211], v[88:91]
	v_mfma_f32_16x16x32_bf16 v[76:79], v[162:165], v[216:219], v[76:79]
	v_mfma_f32_16x16x32_bf16 v[72:75], v[174:177], v[216:219], v[72:75]
	s_barrier
; #define PG8_STAGE(bufoff, gbase, voff) do { _Pragma("unroll") for (int _i = 0; _i < 2; ++_i) \
;         __builtin_amdgcn_global_load_lds((const unsigned*)((const char*)(gbase) + (voff)[_i]), (PG8_LAS unsigned*)(lds + (bufoff) + ldsw + _i * 8192), 16, 0, 0); } while (0)
; #define PG8_LDA(dst, b, h) do { _Pragma("unroll") for (int m = 0; m < 4; ++m) _Pragma("unroll") for (int k = 0; k < 2; ++k) dst[m][k] = *(const PG8_LAS bf16x8*)(lds + PG8_SA(b, h) + aoff + m * 2048 + k * 1024); } while (0)
; #define PG8_LDB(dst, b, h) do { _Pragma("unroll") for (int n = 0; n < 2; ++n) _Pragma("unroll") for (int k = 0; k < 2; ++k) dst[n][k] = *(const PG8_LAS bf16x8*)(lds + PG8_SB(b, h) + boff + n * 2048 + k * 1024); } while (0)
; #define PG8_MMA(ai, bj, At, Bt) do { __builtin_amdgcn_s_setprio(1); _Pragma("unroll") for (int m = 0; m < 4; ++m) _Pragma("unroll") for (int n = 0; n < 2; ++n) _Pragma("unroll") for (int k = 0; k < 2; ++k) \
;         acc[ai][bj][m][n] = __builtin_amdgcn_mfma_f32_16x16x32_bf16(Bt[n][k], At[m][k], acc[ai][bj][m][n], 0, 0, 0); __builtin_amdgcn_s_setprio(0); } while (0)
; #define PG8_WAIT_V(n) asm volatile("s_waitcnt vmcnt(" #n ")" ::: "memory")
; #define PG8_WAIT_L(n) asm volatile("s_waitcnt lgkmcnt(" #n ")" ::: "memory")
; #define PG8_BAR __builtin_amdgcn_s_barrier()
; #define PG8_SCHED __builtin_amdgcn_sched_barrier(0)
; template <class Epi, class Sched, bool STAMP = false>
; __device__ __forceinline__ void gemm_phase(PG8_LAS unsigned char* lds, const Gemm g, const Sched& S, const Epi& E, unsigned long long* stamps) {
;     ...
;             PG8_LDB(B1, 0, 1); PG8_STAGE(PG8_SB(0, 0), b2, voffB);
;             PG8_BAR; PG8_WAIT_L(0); PG8_MMA(0, 1, At, B1); PG8_BAR;
;             PG8_LDA(At, 0, 1); PG8_STAGE(PG8_SA(0, 0), a2, voffA);
;             PG8_BAR; PG8_WAIT_L(0); PG8_MMA(1, 0, At, B0); PG8_BAR; PG8_SCHED;
;             PG8_STAGE(PG8_SB(0, 1), b2 + hstep, voffB);
;             PG8_WAIT_V(6); PG8_BAR; PG8_MMA(1, 1, At, B1); PG8_BAR;
;             PG8_LDB(B0, 1, 0); PG8_SCHED; PG8_LDA(At, 1, 0); PG8_STAGE(PG8_SA(0, 1), a2 + hstep, voffA);
;             PG8_WAIT_L(8); PG8_BAR; PG8_WAIT_L(0); PG8_MMA(0, 0, At, B0); PG8_BAR; PG8_SCHED;
	s_add_i32 s17, 0, 0x14000
	s_add_i32 s14, s16, s43
	v_add_u32_e32 v169, s17, v166
	s_mov_b32 m0, s14
	ds_read_b128 v[220:223], v169
	ds_read_b128 v[224:227], v169 offset:1024
	ds_read_b128 v[228:231], v169 offset:2048
	ds_read_b128 v[232:235], v169 offset:3072
	global_load_lds_dwordx4 v128, s[26:27]
	s_add_i32 m0, s14, 0x2000
	s_nop 0
	global_load_lds_dwordx4 v148, s[26:27]
	s_barrier
	s_waitcnt lgkmcnt(0)
	v_mfma_f32_16x16x32_bf16 v[116:119], v[220:223], v[178:181], v[116:119]
	v_mfma_f32_16x16x32_bf16 v[112:115], v[228:231], v[178:181], v[112:115]
	v_mfma_f32_16x16x32_bf16 v[100:103], v[220:223], v[196:199], v[100:103]
	v_mfma_f32_16x16x32_bf16 v[96:99], v[228:231], v[196:199], v[96:99]
	v_mfma_f32_16x16x32_bf16 v[84:87], v[220:223], v[204:207], v[84:87]
	v_mfma_f32_16x16x32_bf16 v[80:83], v[228:231], v[204:207], v[80:83]
	v_mfma_f32_16x16x32_bf16 v[68:71], v[220:223], v[212:215], v[68:71]
	v_mfma_f32_16x16x32_bf16 v[64:67], v[228:231], v[212:215], v[64:67]
	v_mfma_f32_16x16x32_bf16 v[116:119], v[224:227], v[192:195], v[116:119]
	v_mfma_f32_16x16x32_bf16 v[112:115], v[232:235], v[192:195], v[112:115]
	v_mfma_f32_16x16x32_bf16 v[100:103], v[224:227], v[200:203], v[100:103]
	v_mfma_f32_16x16x32_bf16 v[96:99], v[232:235], v[200:203], v[96:99]
	v_mfma_f32_16x16x32_bf16 v[84:87], v[224:227], v[208:211], v[84:87]
	v_mfma_f32_16x16x32_bf16 v[80:83], v[232:235], v[208:211], v[80:83]
	v_mfma_f32_16x16x32_bf16 v[68:71], v[224:227], v[216:219], v[68:71]
	v_mfma_f32_16x16x32_bf16 v[64:67], v[232:235], v[216:219], v[64:67]
	s_mov_b32 m0, s23
	s_barrier
	ds_read_b128 v[178:181], v168 offset:16384
	ds_read_b128 v[192:195], v168 offset:17408
	ds_read_b128 v[196:199], v168 offset:18432
	ds_read_b128 v[200:203], v168 offset:19456
	ds_read_b128 v[204:207], v168 offset:20480
	ds_read_b128 v[208:211], v168 offset:21504
	ds_read_b128 v[212:215], v168 offset:22528
	ds_read_b128 v[216:219], v168 offset:23552
	global_load_lds_dwordx4 v152, s[30:31]
	s_mov_b32 m0, s45
	s_nop 0
	global_load_lds_dwordx4 v150, s[30:31]
	s_barrier
	s_waitcnt lgkmcnt(0)
	v_mfma_f32_16x16x32_bf16 v[60:63], v[158:161], v[178:181], v[60:63]
	v_mfma_f32_16x16x32_bf16 v[56:59], v[170:173], v[178:181], v[56:59]
	v_mfma_f32_16x16x32_bf16 v[44:47], v[158:161], v[196:199], v[44:47]
	v_mfma_f32_16x16x32_bf16 v[40:43], v[170:173], v[196:199], v[40:43]
	v_mfma_f32_16x16x32_bf16 v[28:31], v[158:161], v[204:207], v[28:31]
	v_mfma_f32_16x16x32_bf16 v[24:27], v[170:173], v[204:207], v[24:27]
	v_mfma_f32_16x16x32_bf16 v[12:15], v[158:161], v[212:215], v[12:15]
	v_mfma_f32_16x16x32_bf16 v[8:11], v[170:173], v[212:215], v[8:11]
	v_mfma_f32_16x16x32_bf16 v[60:63], v[162:165], v[192:195], v[60:63]
	v_mfma_f32_16x16x32_bf16 v[56:59], v[174:177], v[192:195], v[56:59]
	v_mfma_f32_16x16x32_bf16 v[44:47], v[162:165], v[200:203], v[44:47]
	v_mfma_f32_16x16x32_bf16 v[40:43], v[174:177], v[200:203], v[40:43]
	v_mfma_f32_16x16x32_bf16 v[28:31], v[162:165], v[208:211], v[28:31]
	v_mfma_f32_16x16x32_bf16 v[24:27], v[174:177], v[208:211], v[24:27]
	v_mfma_f32_16x16x32_bf16 v[12:15], v[162:165], v[216:219], v[12:15]
	v_mfma_f32_16x16x32_bf16 v[8:11], v[174:177], v[216:219], v[8:11]
	s_barrier
	s_add_u32 s14, s26, 0x40000
	s_addc_u32 s15, s27, 0
	s_add_i32 s16, s17, s43
	s_mov_b32 m0, s16
	s_nop 0
	global_load_lds_dwordx4 v128, s[14:15]
	s_add_i32 m0, s16, 0x2000
	s_nop 0
	global_load_lds_dwordx4 v148, s[14:15]
	s_waitcnt vmcnt(6)
	s_barrier
	v_mfma_f32_16x16x32_bf16 v[52:55], v[220:223], v[178:181], v[52:55]
	v_mfma_f32_16x16x32_bf16 v[48:51], v[228:231], v[178:181], v[48:51]
	v_mfma_f32_16x16x32_bf16 v[36:39], v[220:223], v[196:199], v[36:39]
	v_mfma_f32_16x16x32_bf16 v[32:35], v[228:231], v[196:199], v[32:35]
	v_mfma_f32_16x16x32_bf16 v[20:23], v[220:223], v[204:207], v[20:23]
	v_mfma_f32_16x16x32_bf16 v[16:19], v[228:231], v[204:207], v[16:19]
	v_mfma_f32_16x16x32_bf16 v[4:7], v[220:223], v[212:215], v[4:7]
	v_mfma_f32_16x16x32_bf16 v[0:3], v[228:231], v[212:215], v[0:3]
	v_mfma_f32_16x16x32_bf16 v[52:55], v[224:227], v[192:195], v[52:55]
	v_mfma_f32_16x16x32_bf16 v[48:51], v[232:235], v[192:195], v[48:51]
	v_mfma_f32_16x16x32_bf16 v[36:39], v[224:227], v[200:203], v[36:39]
	v_mfma_f32_16x16x32_bf16 v[32:35], v[232:235], v[200:203], v[32:35]
	v_mfma_f32_16x16x32_bf16 v[20:23], v[224:227], v[208:211], v[20:23]
	v_mfma_f32_16x16x32_bf16 v[16:19], v[232:235], v[208:211], v[16:19]
	v_mfma_f32_16x16x32_bf16 v[4:7], v[224:227], v[216:219], v[4:7]
	v_mfma_f32_16x16x32_bf16 v[0:3], v[232:235], v[216:219], v[0:3]
	s_add_i32 s16, 0, 0x18000
	v_add_u32_e32 v169, s16, v166
	s_barrier
	ds_read_b128 v[158:161], v169
	ds_read_b128 v[162:165], v169 offset:1024
	ds_read_b128 v[170:173], v169 offset:2048
	ds_read_b128 v[174:177], v169 offset:3072
	s_add_u32 s14, s30, 0x40000
	s_addc_u32 s15, s31, 0
	s_mov_b32 m0, s46
	ds_read_b128 v[178:181], v168 offset:32768
	ds_read_b128 v[192:195], v168 offset:33792
	ds_read_b128 v[196:199], v168 offset:34816
	ds_read_b128 v[200:203], v168 offset:35840
	ds_read_b128 v[204:207], v168 offset:36864
	ds_read_b128 v[208:211], v168 offset:37888
	ds_read_b128 v[212:215], v168 offset:38912
	ds_read_b128 v[216:219], v168 offset:39936
	global_load_lds_dwordx4 v152, s[14:15]
	s_mov_b32 m0, s47
	s_nop 0
	global_load_lds_dwordx4 v150, s[14:15]
	s_waitcnt lgkmcnt(8)
	s_barrier
; #define PG8_STAGE(bufoff, gbase, voff) do { _Pragma("unroll") for (int _i = 0; _i < 2; ++_i) \
;         __builtin_amdgcn_global_load_lds((const unsigned*)((const char*)(gbase) + (voff)[_i]), (PG8_LAS unsigned*)(lds + (bufoff) + ldsw + _i * 8192), 16, 0, 0); } while (0)
; #define PG8_LDA(dst, b, h) do { _Pragma("unroll") for (int m = 0; m < 4; ++m) _Pragma("unroll") for (int k = 0; k < 2; ++k) dst[m][k] = *(const PG8_LAS bf16x8*)(lds + PG8_SA(b, h) + aoff + m * 2048 + k * 1024); } while (0)
; #define PG8_LDB(dst, b, h) do { _Pragma("unroll") for (int n = 0; n < 2; ++n) _Pragma("unroll") for (int k = 0; k < 2; ++k) dst[n][k] = *(const PG8_LAS bf16x8*)(lds + PG8_SB(b, h) + boff + n * 2048 + k * 1024); } while (0)
; #define PG8_MMA(ai, bj, At, Bt) do { __builtin_amdgcn_s_setprio(1); _Pragma("unroll") for (int m = 0; m < 4; ++m) _Pragma("unroll") for (int n = 0; n < 2; ++n) _Pragma("unroll") for (int k = 0; k < 2; ++k) \
;         acc[ai][bj][m][n] = __builtin_amdgcn_mfma_f32_16x16x32_bf16(Bt[n][k], At[m][k], acc[ai][bj][m][n], 0, 0, 0); __builtin_amdgcn_s_setprio(0); } while (0)
; #define PG8_WAIT_V(n) asm volatile("s_waitcnt vmcnt(" #n ")" ::: "memory")
; #define PG8_WAIT_L(n) asm volatile("s_waitcnt lgkmcnt(" #n ")" ::: "memory")
; #define PG8_BAR __builtin_amdgcn_s_barrier()
; #define PG8_SCHED __builtin_amdgcn_sched_barrier(0)
; template <class Epi, class Sched, bool STAMP = false>
; __device__ __forceinline__ void gemm_phase(PG8_LAS unsigned char* lds, const Gemm g, const Sched& S, const Epi& E, unsigned long long* stamps) {
;     ...
;             PG8_WAIT_L(8); PG8_BAR; PG8_WAIT_L(0); PG8_MMA(0, 0, At, B0); PG8_BAR; PG8_SCHED;
;             PG8_LDB(B1, 1, 1); PG8_STAGE(PG8_SB(1, 0), b3, voffB);
;             PG8_BAR; PG8_WAIT_L(0); PG8_MMA(0, 1, At, B1); PG8_BAR;
;             PG8_LDA(At, 1, 1); PG8_STAGE(PG8_SA(1, 0), a3, voffA);
;             PG8_BAR; PG8_WAIT_L(0); PG8_MMA(1, 0, At, B0); PG8_BAR; PG8_SCHED;
;             PG8_STAGE(PG8_SB(1, 1), b3 + hstep, voffB);
;             PG8_WAIT_V(6); PG8_BAR; PG8_MMA(1, 1, At, B1); PG8_BAR;
	s_waitcnt lgkmcnt(0)
	v_mfma_f32_16x16x32_bf16 v[124:127], v[158:161], v[178:181], v[124:127]
	v_mfma_f32_16x16x32_bf16 v[120:123], v[170:173], v[178:181], v[120:123]
	v_mfma_f32_16x16x32_bf16 v[108:111], v[158:161], v[196:199], v[108:111]
	v_mfma_f32_16x16x32_bf16 v[104:107], v[170:173], v[196:199], v[104:107]
	v_mfma_f32_16x16x32_bf16 v[92:95], v[158:161], v[204:207], v[92:95]
	v_mfma_f32_16x16x32_bf16 v[88:91], v[170:173], v[204:207], v[88:91]
	v_mfma_f32_16x16x32_bf16 v[76:79], v[158:161], v[212:215], v[76:79]
	v_mfma_f32_16x16x32_bf16 v[72:75], v[170:173], v[212:215], v[72:75]
	v_mfma_f32_16x16x32_bf16 v[124:127], v[162:165], v[192:195], v[124:127]
	v_mfma_f32_16x16x32_bf16 v[120:123], v[174:177], v[192:195], v[120:123]
	v_mfma_f32_16x16x32_bf16 v[108:111], v[162:165], v[200:203], v[108:111]
	v_mfma_f32_16x16x32_bf16 v[104:107], v[174:177], v[200:203], v[104:107]
	v_mfma_f32_16x16x32_bf16 v[92:95], v[162:165], v[208:211], v[92:95]
	v_mfma_f32_16x16x32_bf16 v[88:91], v[174:177], v[208:211], v[88:91]
	v_mfma_f32_16x16x32_bf16 v[76:79], v[162:165], v[216:219], v[76:79]
	v_mfma_f32_16x16x32_bf16 v[72:75], v[174:177], v[216:219], v[72:75]
	s_barrier
	s_add_i32 s17, 0, 0x1c000
	s_add_i32 s14, s16, s43
	v_add_u32_e32 v169, s17, v166
	s_mov_b32 m0, s14
	ds_read_b128 v[220:223], v169
	ds_read_b128 v[224:227], v169 offset:1024
	ds_read_b128 v[228:231], v169 offset:2048
	ds_read_b128 v[232:235], v169 offset:3072
	global_load_lds_dwordx4 v244, s[26:27]
	s_add_i32 m0, s14, 0x2000
	s_nop 0
	global_load_lds_dwordx4 v245, s[26:27]
	s_barrier
	s_waitcnt lgkmcnt(0)
	v_mfma_f32_16x16x32_bf16 v[116:119], v[220:223], v[178:181], v[116:119]
	v_mfma_f32_16x16x32_bf16 v[112:115], v[228:231], v[178:181], v[112:115]
	v_mfma_f32_16x16x32_bf16 v[100:103], v[220:223], v[196:199], v[100:103]
	v_mfma_f32_16x16x32_bf16 v[96:99], v[228:231], v[196:199], v[96:99]
	v_mfma_f32_16x16x32_bf16 v[84:87], v[220:223], v[204:207], v[84:87]
	v_mfma_f32_16x16x32_bf16 v[80:83], v[228:231], v[204:207], v[80:83]
	v_mfma_f32_16x16x32_bf16 v[68:71], v[220:223], v[212:215], v[68:71]
	v_mfma_f32_16x16x32_bf16 v[64:67], v[228:231], v[212:215], v[64:67]
	v_mfma_f32_16x16x32_bf16 v[116:119], v[224:227], v[192:195], v[116:119]
	v_mfma_f32_16x16x32_bf16 v[112:115], v[232:235], v[192:195], v[112:115]
	v_mfma_f32_16x16x32_bf16 v[100:103], v[224:227], v[200:203], v[100:103]
	v_mfma_f32_16x16x32_bf16 v[96:99], v[232:235], v[200:203], v[96:99]
	v_mfma_f32_16x16x32_bf16 v[84:87], v[224:227], v[208:211], v[84:87]
	v_mfma_f32_16x16x32_bf16 v[80:83], v[232:235], v[208:211], v[80:83]
	v_mfma_f32_16x16x32_bf16 v[68:71], v[224:227], v[216:219], v[68:71]
	v_mfma_f32_16x16x32_bf16 v[64:67], v[232:235], v[216:219], v[64:67]
	s_mov_b32 m0, s49
	s_barrier
	ds_read_b128 v[178:181], v168 offset:49152
	ds_read_b128 v[192:195], v168 offset:50176
	ds_read_b128 v[196:199], v168 offset:51200
	ds_read_b128 v[200:203], v168 offset:52224
	ds_read_b128 v[204:207], v168 offset:53248
	ds_read_b128 v[208:211], v168 offset:54272
	ds_read_b128 v[212:215], v168 offset:55296
	ds_read_b128 v[216:219], v168 offset:56320
	global_load_lds_dwordx4 v246, s[30:31]
	s_mov_b32 m0, s53
	s_nop 0
	global_load_lds_dwordx4 v247, s[30:31]
	s_barrier
	s_waitcnt lgkmcnt(0)
	v_mfma_f32_16x16x32_bf16 v[60:63], v[158:161], v[178:181], v[60:63]
	v_mfma_f32_16x16x32_bf16 v[56:59], v[170:173], v[178:181], v[56:59]
	v_mfma_f32_16x16x32_bf16 v[44:47], v[158:161], v[196:199], v[44:47]
	v_mfma_f32_16x16x32_bf16 v[40:43], v[170:173], v[196:199], v[40:43]
	v_mfma_f32_16x16x32_bf16 v[28:31], v[158:161], v[204:207], v[28:31]
	v_mfma_f32_16x16x32_bf16 v[24:27], v[170:173], v[204:207], v[24:27]
	v_mfma_f32_16x16x32_bf16 v[12:15], v[158:161], v[212:215], v[12:15]
	v_mfma_f32_16x16x32_bf16 v[8:11], v[170:173], v[212:215], v[8:11]
	v_mfma_f32_16x16x32_bf16 v[60:63], v[162:165], v[192:195], v[60:63]
	v_mfma_f32_16x16x32_bf16 v[56:59], v[174:177], v[192:195], v[56:59]
	v_mfma_f32_16x16x32_bf16 v[44:47], v[162:165], v[200:203], v[44:47]
	v_mfma_f32_16x16x32_bf16 v[40:43], v[174:177], v[200:203], v[40:43]
	v_mfma_f32_16x16x32_bf16 v[28:31], v[162:165], v[208:211], v[28:31]
	v_mfma_f32_16x16x32_bf16 v[24:27], v[174:177], v[208:211], v[24:27]
	v_mfma_f32_16x16x32_bf16 v[12:15], v[162:165], v[216:219], v[12:15]
	v_mfma_f32_16x16x32_bf16 v[8:11], v[174:177], v[216:219], v[8:11]
	s_barrier
	s_add_u32 s14, s26, 0x40080
	s_addc_u32 s15, s27, 0
	s_add_i32 s16, s17, s43
	s_mov_b32 m0, s16
	s_nop 0
	global_load_lds_dwordx4 v128, s[14:15]
	s_add_i32 m0, s16, 0x2000
	s_nop 0
	global_load_lds_dwordx4 v148, s[14:15]
	s_waitcnt vmcnt(6)
	s_barrier
	v_mfma_f32_16x16x32_bf16 v[52:55], v[220:223], v[178:181], v[52:55]
	v_mfma_f32_16x16x32_bf16 v[48:51], v[228:231], v[178:181], v[48:51]
	v_mfma_f32_16x16x32_bf16 v[36:39], v[220:223], v[196:199], v[36:39]
	v_mfma_f32_16x16x32_bf16 v[32:35], v[228:231], v[196:199], v[32:35]
	v_mfma_f32_16x16x32_bf16 v[20:23], v[220:223], v[204:207], v[20:23]
	v_mfma_f32_16x16x32_bf16 v[16:19], v[228:231], v[204:207], v[16:19]
	v_mfma_f32_16x16x32_bf16 v[4:7], v[220:223], v[212:215], v[4:7]
	v_mfma_f32_16x16x32_bf16 v[0:3], v[228:231], v[212:215], v[0:3]
	v_mfma_f32_16x16x32_bf16 v[52:55], v[224:227], v[192:195], v[52:55]
	v_mfma_f32_16x16x32_bf16 v[48:51], v[232:235], v[192:195], v[48:51]
	v_mfma_f32_16x16x32_bf16 v[36:39], v[224:227], v[200:203], v[36:39]
	v_mfma_f32_16x16x32_bf16 v[32:35], v[232:235], v[200:203], v[32:35]
	v_mfma_f32_16x16x32_bf16 v[20:23], v[224:227], v[208:211], v[20:23]
	v_mfma_f32_16x16x32_bf16 v[16:19], v[232:235], v[208:211], v[16:19]
	v_mfma_f32_16x16x32_bf16 v[4:7], v[224:227], v[216:219], v[4:7]
	v_mfma_f32_16x16x32_bf16 v[0:3], v[232:235], v[216:219], v[0:3]
	s_add_i32 s61, s61, 2
	s_add_u32 s24, s24, 0x100
	s_addc_u32 s25, s25, 0
	s_add_u32 s59, s59, 0x100
	s_addc_u32 s60, s60, 0
	s_cmp_gt_u32 s61, 13
	s_barrier
; __device__ __forceinline__ unsigned cvt_pk_bf16(float lo, float hi) { const f32x2_cv v = {lo, hi}; const bf16x2_cv b = __builtin_convertvector(v, bf16x2_cv); return __builtin_bit_cast(unsigned, b); }
; __device__ __forceinline__ float rstd_of(const float* rowss, int row) { return rsqrtf(rowss[row] * (1.0f / 1024.0f) + 1e-6f); }
;     __device__ __forceinline__ void operator()(const f32x4 (&acc)[2][2][4][2], const pg8::Unit& u, int wr, int wc, int fr, int fq) const {
;         const int row0 = u.pm * 256 + wr * 64 + fr, col0 = u.pn * 256 + wc * 32 + 8 * fq;
; #pragma unroll
;         for (int ai = 0; ai < 2; ++ai)
; #pragma unroll
;             for (int m = 0; m < 4; ++m) {
;                 const int row = row0 + ai * 128 + m * 16;
;                 const float s = (MODE == 2) ? 1.0f : rstd_of(rowss, row);
;                 bf16_t* rowp = O + (size_t)row * ldc + col0;
; #pragma unroll
;                 for (int bj = 0; bj < 2; ++bj) {
;                     f32x4 v0 = acc[ai][bj][m][0] * s, v1 = acc[ai][bj][m][1] * s;
;                     if (MODE == 1) {
; #pragma unroll
;                         for (int j = 0; j < 4; ++j) { const float a = fmaxf(v0[j], 0.f), b = fmaxf(v1[j], 0.f); v0[j] = a * a; v1[j] = b * b; } }
;                     u32x4 w; w.x = cvt_pk_bf16(v0[0], v0[1]); w.y = cvt_pk_bf16(v0[2], v0[3]); w.z = cvt_pk_bf16(v1[0], v1[1]); w.w = cvt_pk_bf16(v1[2], v1[3]);
;                     *(u32x4*)(rowp + bj * 128) = w; } }
	s_cbranch_scc0 .LBB0_44
	v_lshl_add_u32 v162, s22, 8, v139
	v_ashrrev_i32_e32 v163, 31, v162
	v_lshl_add_u64 v[158:159], v[162:163], 2, s[0:1]
	global_load_dword v164, v[158:159], off
	global_load_dword v193, v[158:159], off offset:64
	global_load_dword v194, v[158:159], off offset:128
	global_load_dword v195, v[158:159], off offset:192
	global_load_dword v196, v[158:159], off offset:512
	global_load_dword v197, v[158:159], off offset:576
	global_load_dword v198, v[158:159], off offset:640
	global_load_dword v199, v[158:159], off offset:704
	v_lshl_or_b32 v160, s56, 8, v167
	v_ashrrev_i32_e32 v161, 31, v160
	s_mov_b32 s5, 0x100000
	s_mov_b64 s[14:15], 0x100000
	s_mov_b32 s56, s4
	s_mov_b32 s22, s6
	s_mov_b64 s[26:27], s[20:21]
	s_mov_b64 s[24:25], s[12:13]
	s_waitcnt vmcnt(0)
	v_fmamk_f32 v164, v164, 0x3a800000, v187
	v_cmp_gt_f32_e32 vcc, s67, v164
	v_mul_f32_e32 v165, 0x4b800000, v164
	s_nop 0
	v_cndmask_b32_e32 v164, v164, v165, vcc
	v_rsq_f32_e32 v164, v164
	s_nop 0
	v_mul_f32_e32 v165, 0x45800000, v164
	v_cndmask_b32_e32 v170, v164, v165, vcc
	v_lshlrev_b64 v[164:165], 13, v[162:163]
	v_pk_mul_f32 v[120:121], v[120:121], v[170:171] op_sel_hi:[1,0]
	v_lshl_add_u64 v[172:173], s[2:3], 0, v[164:165]
	v_lshlrev_b64 v[164:165], 1, v[160:161]
	v_pk_mul_f32 v[126:127], v[126:127], v[170:171] op_sel_hi:[1,0]
	v_pk_mul_f32 v[124:125], v[124:125], v[170:171] op_sel_hi:[1,0]
	v_pk_mul_f32 v[122:123], v[122:123], v[170:171] op_sel_hi:[1,0]
	v_max_f32_e32 v120, 0, v120
	v_max_f32_e32 v121, 0, v121
	v_lshl_add_u64 v[160:161], v[172:173], 0, v[164:165]
	v_max_f32_e32 v124, 0, v124
	v_max_f32_e32 v125, 0, v125
	v_pk_mul_f32 v[172:173], v[120:121], v[120:121]
	v_max_f32_e32 v120, 0, v126
	v_max_f32_e32 v122, 0, v122
	v_max_f32_e32 v121, 0, v127
	v_max_f32_e32 v123, 0, v123
	v_pk_mul_f32 v[124:125], v[124:125], v[124:125]
	v_pk_mul_f32 v[126:127], v[120:121], v[120:121]
	v_pk_mul_f32 v[174:175], v[122:123], v[122:123]
	v_pk_mul_f32 v[112:113], v[112:113], v[170:171] op_sel_hi:[1,0]
	v_cvt_pk_bf16_f32 v120, v124, v125
	v_cvt_pk_bf16_f32 v121, v126, v127
	v_cvt_pk_bf16_f32 v122, v172, v173
	v_cvt_pk_bf16_f32 v123, v174, v175
	v_pk_mul_f32 v[118:119], v[118:119], v[170:171] op_sel_hi:[1,0]
	v_pk_mul_f32 v[116:117], v[116:117], v[170:171] op_sel_hi:[1,0]
	v_pk_mul_f32 v[114:115], v[114:115], v[170:171] op_sel_hi:[1,0]
	v_max_f32_e32 v112, 0, v112
	v_max_f32_e32 v113, 0, v113
	global_store_dwordx4 v[160:161], v[120:123], off
	v_max_f32_e32 v116, 0, v116
	v_max_f32_e32 v117, 0, v117
	v_pk_mul_f32 v[120:121], v[112:113], v[112:113]
	v_max_f32_e32 v112, 0, v118
	v_max_f32_e32 v114, 0, v114
	v_max_f32_e32 v113, 0, v119
	v_max_f32_e32 v115, 0, v115
	v_pk_mul_f32 v[116:117], v[116:117], v[116:117]
	v_pk_mul_f32 v[118:119], v[112:113], v[112:113]
	v_pk_mul_f32 v[122:123], v[114:115], v[114:115]
	v_cvt_pk_bf16_f32 v112, v116, v117
	v_cvt_pk_bf16_f32 v113, v118, v119
	v_cvt_pk_bf16_f32 v114, v120, v121
	v_cvt_pk_bf16_f32 v115, v122, v123
	global_store_dwordx4 v[160:161], v[112:115], off offset:256
	s_nop 1
	v_mov_b32_e32 v114, v193
	s_nop 0
	v_or_b32_e32 v112, 16, v162
	v_ashrrev_i32_e32 v113, 31, v112
	v_lshlrev_b64 v[112:113], 13, v[112:113]
	v_lshl_add_u64 v[112:113], s[2:3], 0, v[112:113]
	v_lshl_add_u64 v[112:113], v[112:113], 0, v[164:165]
	v_fmamk_f32 v114, v114, 0x3a800000, v187
	v_cmp_gt_f32_e32 vcc, s67, v114
	v_mul_f32_e32 v115, 0x4b800000, v114
	s_nop 0
	v_cndmask_b32_e32 v114, v114, v115, vcc
	v_rsq_f32_e32 v114, v114
	s_nop 0
	v_mul_f32_e32 v115, 0x45800000, v114
	v_cndmask_b32_e32 v114, v114, v115, vcc
	v_pk_mul_f32 v[104:105], v[104:105], v[114:115] op_sel_hi:[1,0]
	v_pk_mul_f32 v[110:111], v[110:111], v[114:115] op_sel_hi:[1,0]
	v_pk_mul_f32 v[108:109], v[108:109], v[114:115] op_sel_hi:[1,0]
	v_pk_mul_f32 v[106:107], v[106:107], v[114:115] op_sel_hi:[1,0]
	v_max_f32_e32 v104, 0, v104
	v_max_f32_e32 v105, 0, v105
	v_max_f32_e32 v108, 0, v108
	v_max_f32_e32 v109, 0, v109
	v_pk_mul_f32 v[116:117], v[104:105], v[104:105]
	v_max_f32_e32 v104, 0, v110
	v_max_f32_e32 v106, 0, v106
	v_max_f32_e32 v105, 0, v111
	v_max_f32_e32 v107, 0, v107
	v_pk_mul_f32 v[108:109], v[108:109], v[108:109]
	v_pk_mul_f32 v[110:111], v[104:105], v[104:105]
	v_pk_mul_f32 v[118:119], v[106:107], v[106:107]
	v_pk_mul_f32 v[96:97], v[96:97], v[114:115] op_sel_hi:[1,0]
	v_cvt_pk_bf16_f32 v104, v108, v109
	v_cvt_pk_bf16_f32 v105, v110, v111
	v_cvt_pk_bf16_f32 v106, v116, v117
	v_cvt_pk_bf16_f32 v107, v118, v119
	v_pk_mul_f32 v[102:103], v[102:103], v[114:115] op_sel_hi:[1,0]
	v_pk_mul_f32 v[100:101], v[100:101], v[114:115] op_sel_hi:[1,0]
	v_pk_mul_f32 v[98:99], v[98:99], v[114:115] op_sel_hi:[1,0]
	v_max_f32_e32 v96, 0, v96
	v_max_f32_e32 v97, 0, v97
	global_store_dwordx4 v[112:113], v[104:107], off
	v_max_f32_e32 v100, 0, v100
	v_max_f32_e32 v101, 0, v101
	v_pk_mul_f32 v[104:105], v[96:97], v[96:97]
	v_max_f32_e32 v96, 0, v102
	v_max_f32_e32 v98, 0, v98
	v_max_f32_e32 v97, 0, v103
	v_max_f32_e32 v99, 0, v99
	v_pk_mul_f32 v[100:101], v[100:101], v[100:101]
	v_pk_mul_f32 v[102:103], v[96:97], v[96:97]
	v_pk_mul_f32 v[106:107], v[98:99], v[98:99]
	v_cvt_pk_bf16_f32 v96, v100, v101
	v_cvt_pk_bf16_f32 v97, v102, v103
	v_cvt_pk_bf16_f32 v98, v104, v105
	v_cvt_pk_bf16_f32 v99, v106, v107
	global_store_dwordx4 v[112:113], v[96:99], off offset:256
	s_nop 1
	v_mov_b32_e32 v98, v194
	s_nop 0
	v_or_b32_e32 v96, 32, v162
	v_ashrrev_i32_e32 v97, 31, v96
	v_lshlrev_b64 v[96:97], 13, v[96:97]
	v_lshl_add_u64 v[96:97], s[2:3], 0, v[96:97]
	v_lshl_add_u64 v[96:97], v[96:97], 0, v[164:165]
	v_fmamk_f32 v98, v98, 0x3a800000, v187
	v_cmp_gt_f32_e32 vcc, s67, v98
	v_mul_f32_e32 v99, 0x4b800000, v98
; __device__ __forceinline__ unsigned cvt_pk_bf16(float lo, float hi) { const f32x2_cv v = {lo, hi}; const bf16x2_cv b = __builtin_convertvector(v, bf16x2_cv); return __builtin_bit_cast(unsigned, b); }
; __device__ __forceinline__ float rstd_of(const float* rowss, int row) { return rsqrtf(rowss[row] * (1.0f / 1024.0f) + 1e-6f); }
;     __device__ __forceinline__ void operator()(const f32x4 (&acc)[2][2][4][2], const pg8::Unit& u, int wr, int wc, int fr, int fq) const {
;     ...
;             for (int m = 0; m < 4; ++m) {
;                 const int row = row0 + ai * 128 + m * 16;
;                 const float s = (MODE == 2) ? 1.0f : rstd_of(rowss, row);
;                 bf16_t* rowp = O + (size_t)row * ldc + col0;
; #pragma unroll
;                 for (int bj = 0; bj < 2; ++bj) {
;                     f32x4 v0 = acc[ai][bj][m][0] * s, v1 = acc[ai][bj][m][1] * s;
;                     if (MODE == 1) {
; #pragma unroll
;                         for (int j = 0; j < 4; ++j) { const float a = fmaxf(v0[j], 0.f), b = fmaxf(v1[j], 0.f); v0[j] = a * a; v1[j] = b * b; } }
;                     u32x4 w; w.x = cvt_pk_bf16(v0[0], v0[1]); w.y = cvt_pk_bf16(v0[2], v0[3]); w.z = cvt_pk_bf16(v1[0], v1[1]); w.w = cvt_pk_bf16(v1[2], v1[3]);
;                     *(u32x4*)(rowp + bj * 128) = w; } }
	s_nop 0
	v_cndmask_b32_e32 v98, v98, v99, vcc
	v_rsq_f32_e32 v98, v98
	s_nop 0
	v_mul_f32_e32 v99, 0x45800000, v98
	v_cndmask_b32_e32 v98, v98, v99, vcc
	v_pk_mul_f32 v[88:89], v[88:89], v[98:99] op_sel_hi:[1,0]
	v_pk_mul_f32 v[94:95], v[94:95], v[98:99] op_sel_hi:[1,0]
	v_pk_mul_f32 v[92:93], v[92:93], v[98:99] op_sel_hi:[1,0]
	v_pk_mul_f32 v[90:91], v[90:91], v[98:99] op_sel_hi:[1,0]
	v_max_f32_e32 v88, 0, v88
	v_max_f32_e32 v89, 0, v89
	v_max_f32_e32 v92, 0, v92
	v_max_f32_e32 v93, 0, v93
	v_pk_mul_f32 v[100:101], v[88:89], v[88:89]
	v_max_f32_e32 v88, 0, v94
	v_max_f32_e32 v90, 0, v90
	v_max_f32_e32 v89, 0, v95
	v_max_f32_e32 v91, 0, v91
	v_pk_mul_f32 v[92:93], v[92:93], v[92:93]
	v_pk_mul_f32 v[94:95], v[88:89], v[88:89]
	v_pk_mul_f32 v[102:103], v[90:91], v[90:91]
	v_pk_mul_f32 v[80:81], v[80:81], v[98:99] op_sel_hi:[1,0]
	v_cvt_pk_bf16_f32 v88, v92, v93
	v_cvt_pk_bf16_f32 v89, v94, v95
	v_cvt_pk_bf16_f32 v90, v100, v101
	v_cvt_pk_bf16_f32 v91, v102, v103
	v_pk_mul_f32 v[86:87], v[86:87], v[98:99] op_sel_hi:[1,0]
	v_pk_mul_f32 v[84:85], v[84:85], v[98:99] op_sel_hi:[1,0]
	v_pk_mul_f32 v[82:83], v[82:83], v[98:99] op_sel_hi:[1,0]
	v_max_f32_e32 v80, 0, v80
	v_max_f32_e32 v81, 0, v81
	global_store_dwordx4 v[96:97], v[88:91], off
	v_max_f32_e32 v84, 0, v84
	v_max_f32_e32 v85, 0, v85
	v_pk_mul_f32 v[88:89], v[80:81], v[80:81]
	v_max_f32_e32 v80, 0, v86
	v_max_f32_e32 v82, 0, v82
	v_max_f32_e32 v81, 0, v87
	v_max_f32_e32 v83, 0, v83
	v_pk_mul_f32 v[84:85], v[84:85], v[84:85]
	v_pk_mul_f32 v[86:87], v[80:81], v[80:81]
	v_pk_mul_f32 v[90:91], v[82:83], v[82:83]
	v_cvt_pk_bf16_f32 v80, v84, v85
	v_cvt_pk_bf16_f32 v81, v86, v87
	v_cvt_pk_bf16_f32 v82, v88, v89
	v_cvt_pk_bf16_f32 v83, v90, v91
	global_store_dwordx4 v[96:97], v[80:83], off offset:256
	s_nop 1
	v_mov_b32_e32 v82, v195
	s_nop 0
	v_or_b32_e32 v80, 48, v162
	v_ashrrev_i32_e32 v81, 31, v80
	v_lshlrev_b64 v[80:81], 13, v[80:81]
	v_lshl_add_u64 v[80:81], s[2:3], 0, v[80:81]
	v_lshl_add_u64 v[80:81], v[80:81], 0, v[164:165]
	v_fmamk_f32 v82, v82, 0x3a800000, v187
	v_cmp_gt_f32_e32 vcc, s67, v82
	v_mul_f32_e32 v83, 0x4b800000, v82
	s_nop 0
	v_cndmask_b32_e32 v82, v82, v83, vcc
	v_rsq_f32_e32 v82, v82
	s_nop 0
	v_mul_f32_e32 v83, 0x45800000, v82
	v_cndmask_b32_e32 v82, v82, v83, vcc
	v_pk_mul_f32 v[72:73], v[72:73], v[82:83] op_sel_hi:[1,0]
	v_pk_mul_f32 v[78:79], v[78:79], v[82:83] op_sel_hi:[1,0]
	v_pk_mul_f32 v[76:77], v[76:77], v[82:83] op_sel_hi:[1,0]
	v_pk_mul_f32 v[74:75], v[74:75], v[82:83] op_sel_hi:[1,0]
	v_max_f32_e32 v72, 0, v72
	v_max_f32_e32 v73, 0, v73
	v_max_f32_e32 v76, 0, v76
	v_max_f32_e32 v77, 0, v77
	v_pk_mul_f32 v[84:85], v[72:73], v[72:73]
	v_max_f32_e32 v72, 0, v78
	v_max_f32_e32 v74, 0, v74
	v_max_f32_e32 v73, 0, v79
	v_max_f32_e32 v75, 0, v75
	v_pk_mul_f32 v[76:77], v[76:77], v[76:77]
	v_pk_mul_f32 v[78:79], v[72:73], v[72:73]
	v_pk_mul_f32 v[86:87], v[74:75], v[74:75]
	v_pk_mul_f32 v[64:65], v[64:65], v[82:83] op_sel_hi:[1,0]
	v_cvt_pk_bf16_f32 v72, v76, v77
	v_cvt_pk_bf16_f32 v73, v78, v79
	v_cvt_pk_bf16_f32 v74, v84, v85
	v_cvt_pk_bf16_f32 v75, v86, v87
	v_pk_mul_f32 v[70:71], v[70:71], v[82:83] op_sel_hi:[1,0]
	v_pk_mul_f32 v[68:69], v[68:69], v[82:83] op_sel_hi:[1,0]
	v_pk_mul_f32 v[66:67], v[66:67], v[82:83] op_sel_hi:[1,0]
	v_max_f32_e32 v64, 0, v64
	v_max_f32_e32 v65, 0, v65
	global_store_dwordx4 v[80:81], v[72:75], off
	v_max_f32_e32 v68, 0, v68
	v_max_f32_e32 v69, 0, v69
	v_pk_mul_f32 v[72:73], v[64:65], v[64:65]
	v_max_f32_e32 v64, 0, v70
	v_max_f32_e32 v66, 0, v66
	v_max_f32_e32 v65, 0, v71
	v_max_f32_e32 v67, 0, v67
	v_pk_mul_f32 v[68:69], v[68:69], v[68:69]
	v_pk_mul_f32 v[70:71], v[64:65], v[64:65]
	v_pk_mul_f32 v[74:75], v[66:67], v[66:67]
	v_cvt_pk_bf16_f32 v64, v68, v69
	v_cvt_pk_bf16_f32 v65, v70, v71
	v_cvt_pk_bf16_f32 v66, v72, v73
	v_cvt_pk_bf16_f32 v67, v74, v75
	global_store_dwordx4 v[80:81], v[64:67], off offset:256
	s_nop 1
	v_mov_b32_e32 v64, v196
	v_fmamk_f32 v64, v64, 0x3a800000, v187
	v_cmp_gt_f32_e32 vcc, s67, v64
	v_mul_f32_e32 v65, 0x4b800000, v64
	s_nop 0
	v_cndmask_b32_e32 v64, v64, v65, vcc
	v_rsq_f32_e32 v64, v64
	s_nop 0
	v_mul_f32_e32 v65, 0x45800000, v64
	v_cndmask_b32_e32 v66, v64, v65, vcc
	v_pk_mul_f32 v[60:61], v[60:61], v[66:67] op_sel_hi:[1,0]
	v_pk_mul_f32 v[56:57], v[56:57], v[66:67] op_sel_hi:[1,0]
	v_pk_mul_f32 v[62:63], v[62:63], v[66:67] op_sel_hi:[1,0]
	v_pk_mul_f32 v[58:59], v[58:59], v[66:67] op_sel_hi:[1,0]
	v_max_f32_e32 v60, 0, v60
	v_max_f32_e32 v56, 0, v56
	v_max_f32_e32 v61, 0, v61
	v_max_f32_e32 v57, 0, v57
	v_pk_mul_f32 v[60:61], v[60:61], v[60:61]
	v_pk_mul_f32 v[68:69], v[56:57], v[56:57]
	v_max_f32_e32 v56, 0, v62
	v_max_f32_e32 v58, 0, v58
	v_max_f32_e32 v57, 0, v63
	v_max_f32_e32 v59, 0, v59
	v_pk_mul_f32 v[62:63], v[56:57], v[56:57]
	v_pk_mul_f32 v[70:71], v[58:59], v[58:59]
	v_cvt_pk_bf16_f32 v56, v60, v61
	v_add_co_u32_e32 v60, vcc, s5, v160
	v_pk_mul_f32 v[48:49], v[48:49], v[66:67] op_sel_hi:[1,0]
	v_cvt_pk_bf16_f32 v57, v62, v63
	v_cvt_pk_bf16_f32 v58, v68, v69
	v_cvt_pk_bf16_f32 v59, v70, v71
	v_addc_co_u32_e32 v61, vcc, 0, v161, vcc
	v_pk_mul_f32 v[54:55], v[54:55], v[66:67] op_sel_hi:[1,0]
	v_pk_mul_f32 v[52:53], v[52:53], v[66:67] op_sel_hi:[1,0]
	v_pk_mul_f32 v[50:51], v[50:51], v[66:67] op_sel_hi:[1,0]
	v_max_f32_e32 v48, 0, v48
	v_max_f32_e32 v49, 0, v49
	global_store_dwordx4 v[60:61], v[56:59], off
	v_max_f32_e32 v52, 0, v52
	v_max_f32_e32 v53, 0, v53
	v_pk_mul_f32 v[56:57], v[48:49], v[48:49]
	v_max_f32_e32 v48, 0, v54
	v_max_f32_e32 v50, 0, v50
	v_max_f32_e32 v49, 0, v55
	v_max_f32_e32 v51, 0, v51
	v_pk_mul_f32 v[52:53], v[52:53], v[52:53]
	v_pk_mul_f32 v[54:55], v[48:49], v[48:49]
; __device__ __forceinline__ unsigned cvt_pk_bf16(float lo, float hi) { const f32x2_cv v = {lo, hi}; const bf16x2_cv b = __builtin_convertvector(v, bf16x2_cv); return __builtin_bit_cast(unsigned, b); }
; #define PG8_WAIT_V(n) asm volatile("s_waitcnt vmcnt(" #n ")" ::: "memory")
; #define PG8_BAR __builtin_amdgcn_s_barrier()
; __device__ __forceinline__ float rstd_of(const float* rowss, int row) { return rsqrtf(rowss[row] * (1.0f / 1024.0f) + 1e-6f); }
; template <class Epi, class Sched, bool STAMP = false>
; __device__ __forceinline__ void gemm_phase(PG8_LAS unsigned char* lds, const Gemm g, const Sched& S, const Epi& E, unsigned long long* stamps) {
;     ...
;         if constexpr (!Epi::AFTER_DRAIN) { E(acc, cur, wr, wc, fr, fq); S.done(cur); }
;         if (!has_next) break;
; #pragma unroll
;         for (int a = 0; a < 2; ++a)
; #pragma unroll
;             for (int b = 0; b < 2; ++b)
; #pragma unroll
;                 for (int m = 0; m < 4; ++m)
; #pragma unroll
;                     for (int n = 0; n < 2; ++n) acc[a][b][m][n] = (f32x4){0.f, 0.f, 0.f, 0.f};
;         cur = nxt; cA = nA; cB = nB; ++ui;
;     }
;     PG8_WAIT_V(0);
;     if (wr == 0) PG8_BAR;
;     __device__ __forceinline__ void operator()(const f32x4 (&acc)[2][2][4][2], const pg8::Unit& u, int wr, int wc, int fr, int fq) const {
;     ...
;             for (int m = 0; m < 4; ++m) {
;                 const int row = row0 + ai * 128 + m * 16;
;                 const float s = (MODE == 2) ? 1.0f : rstd_of(rowss, row);
;                 bf16_t* rowp = O + (size_t)row * ldc + col0;
; #pragma unroll
;                 for (int bj = 0; bj < 2; ++bj) {
;                     f32x4 v0 = acc[ai][bj][m][0] * s, v1 = acc[ai][bj][m][1] * s;
;                     if (MODE == 1) {
; #pragma unroll
;                         for (int j = 0; j < 4; ++j) { const float a = fmaxf(v0[j], 0.f), b = fmaxf(v1[j], 0.f); v0[j] = a * a; v1[j] = b * b; } }
;                     u32x4 w; w.x = cvt_pk_bf16(v0[0], v0[1]); w.y = cvt_pk_bf16(v0[2], v0[3]); w.z = cvt_pk_bf16(v1[0], v1[1]); w.w = cvt_pk_bf16(v1[2], v1[3]);
;                     *(u32x4*)(rowp + bj * 128) = w; } }
	v_pk_mul_f32 v[58:59], v[50:51], v[50:51]
	v_lshl_add_u64 v[64:65], v[160:161], 0, s[14:15]
	v_cvt_pk_bf16_f32 v48, v52, v53
	v_cvt_pk_bf16_f32 v49, v54, v55
	v_cvt_pk_bf16_f32 v50, v56, v57
	v_cvt_pk_bf16_f32 v51, v58, v59
	global_store_dwordx4 v[64:65], v[48:51], off offset:256
	s_nop 1
	v_mov_b32_e32 v48, v197
	s_mov_b32 s5, 0x120000
	s_mov_b64 s[14:15], 0x120000
	v_fmamk_f32 v48, v48, 0x3a800000, v187
	v_cmp_gt_f32_e32 vcc, s67, v48
	v_mul_f32_e32 v49, 0x4b800000, v48
	s_nop 0
	v_cndmask_b32_e32 v48, v48, v49, vcc
	v_rsq_f32_e32 v48, v48
	s_nop 0
	v_mul_f32_e32 v49, 0x45800000, v48
	v_cndmask_b32_e32 v50, v48, v49, vcc
	v_pk_mul_f32 v[44:45], v[44:45], v[50:51] op_sel_hi:[1,0]
	v_pk_mul_f32 v[40:41], v[40:41], v[50:51] op_sel_hi:[1,0]
	v_pk_mul_f32 v[46:47], v[46:47], v[50:51] op_sel_hi:[1,0]
	v_pk_mul_f32 v[42:43], v[42:43], v[50:51] op_sel_hi:[1,0]
	v_max_f32_e32 v44, 0, v44
	v_max_f32_e32 v40, 0, v40
	v_max_f32_e32 v45, 0, v45
	v_max_f32_e32 v41, 0, v41
	v_pk_mul_f32 v[44:45], v[44:45], v[44:45]
	v_pk_mul_f32 v[52:53], v[40:41], v[40:41]
	v_max_f32_e32 v40, 0, v46
	v_max_f32_e32 v42, 0, v42
	v_max_f32_e32 v41, 0, v47
	v_max_f32_e32 v43, 0, v43
	v_pk_mul_f32 v[46:47], v[40:41], v[40:41]
	v_pk_mul_f32 v[54:55], v[42:43], v[42:43]
	v_cvt_pk_bf16_f32 v40, v44, v45
	v_add_co_u32_e32 v44, vcc, s5, v160
	v_pk_mul_f32 v[32:33], v[32:33], v[50:51] op_sel_hi:[1,0]
	v_cvt_pk_bf16_f32 v41, v46, v47
	v_cvt_pk_bf16_f32 v42, v52, v53
	v_cvt_pk_bf16_f32 v43, v54, v55
	v_addc_co_u32_e32 v45, vcc, 0, v161, vcc
	v_pk_mul_f32 v[38:39], v[38:39], v[50:51] op_sel_hi:[1,0]
	v_pk_mul_f32 v[36:37], v[36:37], v[50:51] op_sel_hi:[1,0]
	v_pk_mul_f32 v[34:35], v[34:35], v[50:51] op_sel_hi:[1,0]
	v_max_f32_e32 v32, 0, v32
	v_max_f32_e32 v33, 0, v33
	global_store_dwordx4 v[44:45], v[40:43], off
	v_max_f32_e32 v36, 0, v36
	v_max_f32_e32 v37, 0, v37
	v_pk_mul_f32 v[40:41], v[32:33], v[32:33]
	v_max_f32_e32 v32, 0, v38
	v_max_f32_e32 v34, 0, v34
	v_max_f32_e32 v33, 0, v39
	v_max_f32_e32 v35, 0, v35
	v_pk_mul_f32 v[36:37], v[36:37], v[36:37]
	v_pk_mul_f32 v[38:39], v[32:33], v[32:33]
	v_pk_mul_f32 v[42:43], v[34:35], v[34:35]
	v_lshl_add_u64 v[48:49], v[160:161], 0, s[14:15]
	v_cvt_pk_bf16_f32 v32, v36, v37
	v_cvt_pk_bf16_f32 v33, v38, v39
	v_cvt_pk_bf16_f32 v34, v40, v41
	v_cvt_pk_bf16_f32 v35, v42, v43
	global_store_dwordx4 v[48:49], v[32:35], off offset:256
	s_nop 1
	v_mov_b32_e32 v32, v198
	s_mov_b32 s5, 0x140000
	s_mov_b64 s[14:15], 0x140000
	v_fmamk_f32 v32, v32, 0x3a800000, v187
	v_cmp_gt_f32_e32 vcc, s67, v32
	v_mul_f32_e32 v33, 0x4b800000, v32
	s_nop 0
	v_cndmask_b32_e32 v32, v32, v33, vcc
	v_rsq_f32_e32 v32, v32
	s_nop 0
	v_mul_f32_e32 v33, 0x45800000, v32
	v_cndmask_b32_e32 v34, v32, v33, vcc
	v_pk_mul_f32 v[28:29], v[28:29], v[34:35] op_sel_hi:[1,0]
	v_pk_mul_f32 v[24:25], v[24:25], v[34:35] op_sel_hi:[1,0]
	v_pk_mul_f32 v[30:31], v[30:31], v[34:35] op_sel_hi:[1,0]
	v_pk_mul_f32 v[26:27], v[26:27], v[34:35] op_sel_hi:[1,0]
	v_max_f32_e32 v28, 0, v28
	v_max_f32_e32 v24, 0, v24
	v_max_f32_e32 v29, 0, v29
	v_max_f32_e32 v25, 0, v25
	v_pk_mul_f32 v[28:29], v[28:29], v[28:29]
	v_pk_mul_f32 v[36:37], v[24:25], v[24:25]
	v_max_f32_e32 v24, 0, v30
	v_max_f32_e32 v26, 0, v26
	v_max_f32_e32 v25, 0, v31
	v_max_f32_e32 v27, 0, v27
	v_pk_mul_f32 v[30:31], v[24:25], v[24:25]
	v_pk_mul_f32 v[38:39], v[26:27], v[26:27]
	v_cvt_pk_bf16_f32 v24, v28, v29
	v_add_co_u32_e32 v28, vcc, s5, v160
	v_pk_mul_f32 v[16:17], v[16:17], v[34:35] op_sel_hi:[1,0]
	v_cvt_pk_bf16_f32 v25, v30, v31
	v_cvt_pk_bf16_f32 v26, v36, v37
	v_cvt_pk_bf16_f32 v27, v38, v39
	v_addc_co_u32_e32 v29, vcc, 0, v161, vcc
	v_pk_mul_f32 v[22:23], v[22:23], v[34:35] op_sel_hi:[1,0]
	v_pk_mul_f32 v[20:21], v[20:21], v[34:35] op_sel_hi:[1,0]
	v_pk_mul_f32 v[18:19], v[18:19], v[34:35] op_sel_hi:[1,0]
	v_max_f32_e32 v16, 0, v16
	v_max_f32_e32 v17, 0, v17
	global_store_dwordx4 v[28:29], v[24:27], off
	v_max_f32_e32 v20, 0, v20
	v_max_f32_e32 v21, 0, v21
	v_pk_mul_f32 v[24:25], v[16:17], v[16:17]
	v_max_f32_e32 v16, 0, v22
	v_max_f32_e32 v18, 0, v18
	v_max_f32_e32 v17, 0, v23
	v_max_f32_e32 v19, 0, v19
	v_pk_mul_f32 v[20:21], v[20:21], v[20:21]
	v_pk_mul_f32 v[22:23], v[16:17], v[16:17]
	v_pk_mul_f32 v[26:27], v[18:19], v[18:19]
	v_lshl_add_u64 v[32:33], v[160:161], 0, s[14:15]
	v_cvt_pk_bf16_f32 v16, v20, v21
	v_cvt_pk_bf16_f32 v17, v22, v23
	v_cvt_pk_bf16_f32 v18, v24, v25
	v_cvt_pk_bf16_f32 v19, v26, v27
	global_store_dwordx4 v[32:33], v[16:19], off offset:256
	s_nop 1
	v_mov_b32_e32 v16, v199
	s_mov_b32 s5, 0x160000
	s_mov_b64 s[14:15], 0x160000
	v_lshl_add_u64 v[18:19], v[160:161], 0, s[14:15]
	v_fmamk_f32 v16, v16, 0x3a800000, v187
	v_cmp_gt_f32_e32 vcc, s67, v16
	v_mul_f32_e32 v17, 0x4b800000, v16
	s_nop 0
	v_cndmask_b32_e32 v16, v16, v17, vcc
	v_rsq_f32_e32 v16, v16
	s_nop 0
	v_mul_f32_e32 v17, 0x45800000, v16
	v_cndmask_b32_e32 v16, v16, v17, vcc
	v_pk_mul_f32 v[12:13], v[12:13], v[16:17] op_sel_hi:[1,0]
	v_pk_mul_f32 v[8:9], v[8:9], v[16:17] op_sel_hi:[1,0]
	v_pk_mul_f32 v[14:15], v[14:15], v[16:17] op_sel_hi:[1,0]
	v_pk_mul_f32 v[10:11], v[10:11], v[16:17] op_sel_hi:[1,0]
	v_max_f32_e32 v12, 0, v12
	v_max_f32_e32 v8, 0, v8
	v_max_f32_e32 v13, 0, v13
	v_max_f32_e32 v9, 0, v9
	v_pk_mul_f32 v[12:13], v[12:13], v[12:13]
	v_pk_mul_f32 v[20:21], v[8:9], v[8:9]
	v_max_f32_e32 v8, 0, v14
	v_max_f32_e32 v10, 0, v10
	v_max_f32_e32 v9, 0, v15
	v_max_f32_e32 v11, 0, v11
	v_pk_mul_f32 v[14:15], v[8:9], v[8:9]
	v_pk_mul_f32 v[22:23], v[10:11], v[10:11]
	v_cvt_pk_bf16_f32 v8, v12, v13
	v_add_co_u32_e32 v12, vcc, s5, v160
	v_pk_mul_f32 v[0:1], v[0:1], v[16:17] op_sel_hi:[1,0]
	v_cvt_pk_bf16_f32 v9, v14, v15
	v_cvt_pk_bf16_f32 v10, v20, v21
	v_cvt_pk_bf16_f32 v11, v22, v23
	v_addc_co_u32_e32 v13, vcc, 0, v161, vcc
	v_pk_mul_f32 v[6:7], v[6:7], v[16:17] op_sel_hi:[1,0]
	v_pk_mul_f32 v[4:5], v[4:5], v[16:17] op_sel_hi:[1,0]
	v_pk_mul_f32 v[2:3], v[2:3], v[16:17] op_sel_hi:[1,0]
	v_max_f32_e32 v0, 0, v0
	v_max_f32_e32 v1, 0, v1
	global_store_dwordx4 v[12:13], v[8:11], off
	v_max_f32_e32 v4, 0, v4
	v_max_f32_e32 v5, 0, v5
	v_pk_mul_f32 v[8:9], v[0:1], v[0:1]
	v_max_f32_e32 v0, 0, v6
	v_max_f32_e32 v2, 0, v2
	v_max_f32_e32 v1, 0, v7
	v_max_f32_e32 v3, 0, v3
	v_pk_mul_f32 v[4:5], v[4:5], v[4:5]
	v_pk_mul_f32 v[6:7], v[0:1], v[0:1]
	v_pk_mul_f32 v[10:11], v[2:3], v[2:3]
	v_cvt_pk_bf16_f32 v0, v4, v5
	v_cvt_pk_bf16_f32 v1, v6, v7
	v_cvt_pk_bf16_f32 v2, v8, v9
	v_cvt_pk_bf16_f32 v3, v10, v11
	s_and_b64 vcc, exec, s[38:39]
	global_store_dwordx4 v[18:19], v[0:3], off offset:256
	s_cbranch_vccz .LBB0_41
	s_cmpk_gt_u32 s36, 0xff
	s_cbranch_scc1 .LBB0_48
	s_barrier

; #define PG8_STAGE(bufoff, gbase, voff) do { _Pragma("unroll") for (int _i = 0; _i < 2; ++_i) \
;         __builtin_amdgcn_global_load_lds((const unsigned*)((const char*)(gbase) + (voff)[_i]), (PG8_LAS unsigned*)(lds + (bufoff) + ldsw + _i * 8192), 16, 0, 0); } while (0)
; #define PG8_LDA(dst, b, h) do { _Pragma("unroll") for (int m = 0; m < 4; ++m) _Pragma("unroll") for (int k = 0; k < 2; ++k) dst[m][k] = *(const PG8_LAS bf16x8*)(lds + PG8_SA(b, h) + aoff + m * 2048 + k * 1024); } while (0)
; #define PG8_LDB(dst, b, h) do { _Pragma("unroll") for (int n = 0; n < 2; ++n) _Pragma("unroll") for (int k = 0; k < 2; ++k) dst[n][k] = *(const PG8_LAS bf16x8*)(lds + PG8_SB(b, h) + boff + n * 2048 + k * 1024); } while (0)
; #define PG8_WAIT_L(n) asm volatile("s_waitcnt lgkmcnt(" #n ")" ::: "memory")
; #define PG8_BAR __builtin_amdgcn_s_barrier()
; #define PG8_SCHED __builtin_amdgcn_sched_barrier(0)
;     __device__ bool next(int i, pg8::Unit& u) const { if (i != 0 || !valid) return false; u.pm = pm; u.pn = pn; return true; }
; template <class Epi, class Sched, bool STAMP = false>
; __device__ __forceinline__ void gemm_phase(PG8_LAS unsigned char* lds, const Gemm g, const Sched& S, const Epi& E, unsigned long long* stamps) {
;     ...
;         const bool has_next = S.next(ui + 1, nxt);
;         const char* nA = has_next ? (const char*)g.A + (size_t)nxt.pm * tstep : cA; const char* nB = has_next ? (const char*)g.Bt + (size_t)nxt.pn * tstep : cB;
;         for (int t = 0; t < nt; t += 2) {
;             const bool last = (t == nt - 2);
;             const char* a1 = cA + (size_t)(t + 1) * kstep;
;             const char* a2 = last ? nA : cA + (size_t)(t + 2) * kstep; const char* b2 = last ? nB : cB + (size_t)(t + 2) * kstep;
;             const char* a3 = a2 + kstep; const char* b3 = b2 + kstep;
;             if (last && has_next) S.a_ready(nxt);
;             PG8_LDB(B0, 0, 0); PG8_SCHED; PG8_LDA(At, 0, 0); PG8_STAGE(PG8_SA(1, 1), a1 + hstep, voffA);
;             PG8_WAIT_L(8); PG8_BAR; PG8_WAIT_L(0); PG8_MMA(0, 0, At, B0); PG8_BAR; PG8_SCHED;
;     ...
; #pragma unroll
;         for (int a = 0; a < 2; ++a)
; #pragma unroll
;             for (int b = 0; b < 2; ++b)
; #pragma unroll
;                 for (int m = 0; m < 4; ++m)
; #pragma unroll
;                     for (int n = 0; n < 2; ++n) acc[a][b][m][n] = (f32x4){0.f, 0.f, 0.f, 0.f};
;         cur = nxt; cA = nA; cB = nB; ++ui;
.LBB0_140:
	s_ashr_i32 s23, s22, 31
	s_lshl_b64 s[14:15], s[22:23], 19
	v_cmp_lt_i64_e32 vcc, s[24:25], v[136:137]
	s_add_u32 s24, s60, s14
	s_addc_u32 s25, s61, s15
	s_and_b64 s[14:15], vcc, exec
	s_cselect_b32 s23, s25, s45
	s_cselect_b32 s31, s24, s44
	s_ashr_i32 s21, s20, 31
	s_lshl_b64 s[14:15], s[20:21], 19
	s_add_u32 s26, s62, s14
	s_addc_u32 s27, s63, s15
	s_and_b64 s[14:15], vcc, exec
	s_cselect_b32 s21, s27, s49
	s_cselect_b32 vcc_lo, s26, s48
	s_add_u32 vcc_hi, s48, 0x100
	v_mov_b32_e32 v0, 0
	s_addc_u32 s38, s49, 0
	s_mov_b32 s39, -2
	s_waitcnt lgkmcnt(0)
	v_mov_b32_e32 v1, v0
	v_mov_b32_e32 v2, v0
	v_mov_b32_e32 v3, v0
	v_mov_b32_e32 v4, v0
	v_mov_b32_e32 v5, v0
	v_mov_b32_e32 v6, v0
	v_mov_b32_e32 v7, v0
	v_mov_b32_e32 v16, v0
	v_mov_b32_e32 v17, v0
	v_mov_b32_e32 v18, v0
	v_mov_b32_e32 v19, v0
	v_mov_b32_e32 v20, v0
	v_mov_b32_e32 v21, v0
	v_mov_b32_e32 v22, v0
	v_mov_b32_e32 v23, v0
	v_mov_b32_e32 v32, v0
	v_mov_b32_e32 v33, v0
	v_mov_b32_e32 v34, v0
	v_mov_b32_e32 v35, v0
	v_mov_b32_e32 v36, v0
	v_mov_b32_e32 v37, v0
	v_mov_b32_e32 v38, v0
	v_mov_b32_e32 v39, v0
	v_mov_b32_e32 v48, v0
	v_mov_b32_e32 v49, v0
	v_mov_b32_e32 v50, v0
	v_mov_b32_e32 v51, v0
	v_mov_b32_e32 v52, v0
	v_mov_b32_e32 v53, v0
	v_mov_b32_e32 v54, v0
	v_mov_b32_e32 v55, v0
	v_mov_b32_e32 v8, v0
	v_mov_b32_e32 v9, v0
	v_mov_b32_e32 v10, v0
	v_mov_b32_e32 v11, v0
	v_mov_b32_e32 v12, v0
	v_mov_b32_e32 v13, v0
	v_mov_b32_e32 v14, v0
	v_mov_b32_e32 v15, v0
	v_mov_b32_e32 v24, v0
	v_mov_b32_e32 v25, v0
	v_mov_b32_e32 v26, v0
	v_mov_b32_e32 v27, v0
	v_mov_b32_e32 v28, v0
	v_mov_b32_e32 v29, v0
	v_mov_b32_e32 v30, v0
	v_mov_b32_e32 v31, v0
	v_mov_b32_e32 v40, v0
	v_mov_b32_e32 v41, v0
	v_mov_b32_e32 v42, v0
	v_mov_b32_e32 v43, v0
	v_mov_b32_e32 v44, v0
	v_mov_b32_e32 v45, v0
	v_mov_b32_e32 v46, v0
	v_mov_b32_e32 v47, v0
	v_mov_b32_e32 v56, v0
	v_mov_b32_e32 v57, v0
	v_mov_b32_e32 v58, v0
	v_mov_b32_e32 v59, v0
	v_mov_b32_e32 v60, v0
	v_mov_b32_e32 v61, v0
	v_mov_b32_e32 v62, v0
	v_mov_b32_e32 v63, v0
	v_mov_b32_e32 v64, v0
	v_mov_b32_e32 v65, v0
	v_mov_b32_e32 v66, v0
	v_mov_b32_e32 v67, v0
	v_mov_b32_e32 v68, v0
	v_mov_b32_e32 v69, v0
	v_mov_b32_e32 v70, v0
	v_mov_b32_e32 v71, v0
	v_mov_b32_e32 v80, v0
	v_mov_b32_e32 v81, v0
	v_mov_b32_e32 v82, v0
	v_mov_b32_e32 v83, v0
	v_mov_b32_e32 v84, v0
	v_mov_b32_e32 v85, v0
	v_mov_b32_e32 v86, v0
	v_mov_b32_e32 v87, v0
	v_mov_b32_e32 v96, v0
	v_mov_b32_e32 v97, v0
	v_mov_b32_e32 v98, v0
	v_mov_b32_e32 v99, v0
	v_mov_b32_e32 v100, v0
	v_mov_b32_e32 v101, v0
	v_mov_b32_e32 v102, v0
	v_mov_b32_e32 v103, v0
	v_mov_b32_e32 v112, v0
	v_mov_b32_e32 v113, v0
	v_mov_b32_e32 v114, v0
	v_mov_b32_e32 v115, v0
	v_mov_b32_e32 v116, v0
	v_mov_b32_e32 v117, v0
	v_mov_b32_e32 v118, v0
	v_mov_b32_e32 v119, v0
	v_mov_b32_e32 v72, v0
	v_mov_b32_e32 v73, v0
	v_mov_b32_e32 v74, v0
	v_mov_b32_e32 v75, v0
	v_mov_b32_e32 v76, v0
	v_mov_b32_e32 v77, v0
	v_mov_b32_e32 v78, v0
	v_mov_b32_e32 v79, v0
	v_mov_b32_e32 v88, v0
	v_mov_b32_e32 v89, v0
	v_mov_b32_e32 v90, v0
	v_mov_b32_e32 v91, v0
	v_mov_b32_e32 v92, v0
	v_mov_b32_e32 v93, v0
	v_mov_b32_e32 v94, v0
	v_mov_b32_e32 v95, v0
	v_mov_b32_e32 v104, v0
	v_mov_b32_e32 v105, v0
	v_mov_b32_e32 v106, v0
	v_mov_b32_e32 v107, v0
	v_mov_b32_e32 v108, v0
	v_mov_b32_e32 v109, v0
	v_mov_b32_e32 v110, v0
	v_mov_b32_e32 v111, v0
	v_mov_b32_e32 v120, v0
	v_mov_b32_e32 v121, v0
	v_mov_b32_e32 v122, v0
	v_mov_b32_e32 v123, v0
	v_mov_b32_e32 v124, v0
	v_mov_b32_e32 v125, v0
	v_mov_b32_e32 v126, v0
	v_mov_b32_e32 v127, v0
	v_add_u32_e32 v244, 0x80, v148
	v_add_u32_e32 v245, 0x80, v150
.LBB0_141:
	s_add_u32 s48, s44, 0x100
	s_addc_u32 s49, s45, 0
	s_add_i32 s14, 0, 0x10000
	v_add_u32_e32 v128, s14, v166
	ds_read_b128 v[156:159], v128
	ds_read_b128 v[160:163], v128 offset:1024
	ds_read_b128 v[170:173], v128 offset:2048
	ds_read_b128 v[174:177], v128 offset:3072
	s_cmp_eq_u32 s39, 12
	s_cselect_b32 s59, s23, s49
	s_cselect_b32 s58, s31, s48
	s_cselect_b32 s57, s21, s38
	s_cselect_b32 s56, vcc_lo, vcc_hi
	s_add_i32 m0, s37, 0xc000
	ds_read_b128 v[178:181], v168
	ds_read_b128 v[192:195], v168 offset:1024
	ds_read_b128 v[196:199], v168 offset:2048
	ds_read_b128 v[200:203], v168 offset:3072
	ds_read_b128 v[204:207], v168 offset:4096
	ds_read_b128 v[208:211], v168 offset:5120
	ds_read_b128 v[212:215], v168 offset:6144
	ds_read_b128 v[216:219], v168 offset:7168
	global_load_lds_dwordx4 v152, s[44:45]
	s_add_i32 m0, s37, 0xe000
	s_nop 0
	global_load_lds_dwordx4 v154, s[44:45]
	s_waitcnt lgkmcnt(8)
	s_barrier
	s_waitcnt lgkmcnt(0)
	v_mfma_f32_16x16x32_bf16 v[124:127], v[156:159], v[178:181], v[124:127]
	v_mfma_f32_16x16x32_bf16 v[120:123], v[170:173], v[178:181], v[120:123]
	v_mfma_f32_16x16x32_bf16 v[108:111], v[156:159], v[196:199], v[108:111]
	v_mfma_f32_16x16x32_bf16 v[104:107], v[170:173], v[196:199], v[104:107]
	v_mfma_f32_16x16x32_bf16 v[92:95], v[156:159], v[204:207], v[92:95]
	v_mfma_f32_16x16x32_bf16 v[88:91], v[170:173], v[204:207], v[88:91]
	v_mfma_f32_16x16x32_bf16 v[76:79], v[156:159], v[212:215], v[76:79]
	v_mfma_f32_16x16x32_bf16 v[72:75], v[170:173], v[212:215], v[72:75]
	v_mfma_f32_16x16x32_bf16 v[124:127], v[160:163], v[192:195], v[124:127]
	v_mfma_f32_16x16x32_bf16 v[120:123], v[174:177], v[192:195], v[120:123]
	v_mfma_f32_16x16x32_bf16 v[108:111], v[160:163], v[200:203], v[108:111]
	v_mfma_f32_16x16x32_bf16 v[104:107], v[174:177], v[200:203], v[104:107]
	v_mfma_f32_16x16x32_bf16 v[92:95], v[160:163], v[208:211], v[92:95]
	v_mfma_f32_16x16x32_bf16 v[88:91], v[174:177], v[208:211], v[88:91]
	v_mfma_f32_16x16x32_bf16 v[76:79], v[160:163], v[216:219], v[76:79]
	v_mfma_f32_16x16x32_bf16 v[72:75], v[174:177], v[216:219], v[72:75]
	s_barrier
; #define PG8_STAGE(bufoff, gbase, voff) do { _Pragma("unroll") for (int _i = 0; _i < 2; ++_i) \
;         __builtin_amdgcn_global_load_lds((const unsigned*)((const char*)(gbase) + (voff)[_i]), (PG8_LAS unsigned*)(lds + (bufoff) + ldsw + _i * 8192), 16, 0, 0); } while (0)
; #define PG8_LDA(dst, b, h) do { _Pragma("unroll") for (int m = 0; m < 4; ++m) _Pragma("unroll") for (int k = 0; k < 2; ++k) dst[m][k] = *(const PG8_LAS bf16x8*)(lds + PG8_SA(b, h) + aoff + m * 2048 + k * 1024); } while (0)
; #define PG8_LDB(dst, b, h) do { _Pragma("unroll") for (int n = 0; n < 2; ++n) _Pragma("unroll") for (int k = 0; k < 2; ++k) dst[n][k] = *(const PG8_LAS bf16x8*)(lds + PG8_SB(b, h) + boff + n * 2048 + k * 1024); } while (0)
; #define PG8_MMA(ai, bj, At, Bt) do { __builtin_amdgcn_s_setprio(1); _Pragma("unroll") for (int m = 0; m < 4; ++m) _Pragma("unroll") for (int n = 0; n < 2; ++n) _Pragma("unroll") for (int k = 0; k < 2; ++k) \
;         acc[ai][bj][m][n] = __builtin_amdgcn_mfma_f32_16x16x32_bf16(Bt[n][k], At[m][k], acc[ai][bj][m][n], 0, 0, 0); __builtin_amdgcn_s_setprio(0); } while (0)
; #define PG8_WAIT_V(n) asm volatile("s_waitcnt vmcnt(" #n ")" ::: "memory")
; #define PG8_WAIT_L(n) asm volatile("s_waitcnt lgkmcnt(" #n ")" ::: "memory")
; #define PG8_BAR __builtin_amdgcn_s_barrier()
; #define PG8_SCHED __builtin_amdgcn_sched_barrier(0)
; template <class Epi, class Sched, bool STAMP = false>
; __device__ __forceinline__ void gemm_phase(PG8_LAS unsigned char* lds, const Gemm g, const Sched& S, const Epi& E, unsigned long long* stamps) {
;     ...
;             PG8_LDB(B1, 0, 1); PG8_STAGE(PG8_SB(0, 0), b2, voffB);
;             PG8_BAR; PG8_WAIT_L(0); PG8_MMA(0, 1, At, B1); PG8_BAR;
;             PG8_LDA(At, 0, 1); PG8_STAGE(PG8_SA(0, 0), a2, voffA);
;             PG8_BAR; PG8_WAIT_L(0); PG8_MMA(1, 0, At, B0); PG8_BAR; PG8_SCHED;
;             PG8_STAGE(PG8_SB(0, 1), b2 + hstep, voffB);
;             PG8_WAIT_V(6); PG8_BAR; PG8_MMA(1, 1, At, B1); PG8_BAR;
;             PG8_LDB(B0, 1, 0); PG8_SCHED; PG8_LDA(At, 1, 0); PG8_STAGE(PG8_SA(0, 1), a2 + hstep, voffA);
;             PG8_WAIT_L(8); PG8_BAR; PG8_WAIT_L(0); PG8_MMA(0, 0, At, B0); PG8_BAR; PG8_SCHED;
	s_add_i32 s16, 0, 0x14000
	s_add_i32 s14, s14, s64
	v_add_u32_e32 v128, s16, v166
	s_mov_b32 m0, s14
	ds_read_b128 v[220:223], v128
	ds_read_b128 v[224:227], v128 offset:1024
	ds_read_b128 v[228:231], v128 offset:2048
	ds_read_b128 v[232:235], v128 offset:3072
	global_load_lds_dwordx4 v148, s[56:57]
	s_add_i32 m0, s14, 0x2000
	s_nop 0
	global_load_lds_dwordx4 v150, s[56:57]
	s_barrier
	s_waitcnt lgkmcnt(0)
	v_mfma_f32_16x16x32_bf16 v[116:119], v[220:223], v[178:181], v[116:119]
	v_mfma_f32_16x16x32_bf16 v[112:115], v[228:231], v[178:181], v[112:115]
	v_mfma_f32_16x16x32_bf16 v[100:103], v[220:223], v[196:199], v[100:103]
	v_mfma_f32_16x16x32_bf16 v[96:99], v[228:231], v[196:199], v[96:99]
	v_mfma_f32_16x16x32_bf16 v[84:87], v[220:223], v[204:207], v[84:87]
	v_mfma_f32_16x16x32_bf16 v[80:83], v[228:231], v[204:207], v[80:83]
	v_mfma_f32_16x16x32_bf16 v[68:71], v[220:223], v[212:215], v[68:71]
	v_mfma_f32_16x16x32_bf16 v[64:67], v[228:231], v[212:215], v[64:67]
	v_mfma_f32_16x16x32_bf16 v[116:119], v[224:227], v[192:195], v[116:119]
	v_mfma_f32_16x16x32_bf16 v[112:115], v[232:235], v[192:195], v[112:115]
	v_mfma_f32_16x16x32_bf16 v[100:103], v[224:227], v[200:203], v[100:103]
	v_mfma_f32_16x16x32_bf16 v[96:99], v[232:235], v[200:203], v[96:99]
	v_mfma_f32_16x16x32_bf16 v[84:87], v[224:227], v[208:211], v[84:87]
	v_mfma_f32_16x16x32_bf16 v[80:83], v[232:235], v[208:211], v[80:83]
	v_mfma_f32_16x16x32_bf16 v[68:71], v[224:227], v[216:219], v[68:71]
	v_mfma_f32_16x16x32_bf16 v[64:67], v[232:235], v[216:219], v[64:67]
	s_mov_b32 m0, s37
	s_barrier
	ds_read_b128 v[178:181], v168 offset:16384
	ds_read_b128 v[192:195], v168 offset:17408
	ds_read_b128 v[196:199], v168 offset:18432
	ds_read_b128 v[200:203], v168 offset:19456
	ds_read_b128 v[204:207], v168 offset:20480
	ds_read_b128 v[208:211], v168 offset:21504
	ds_read_b128 v[212:215], v168 offset:22528
	ds_read_b128 v[216:219], v168 offset:23552
	global_load_lds_dwordx4 v148, s[58:59]
	s_mov_b32 m0, s65
	s_nop 0
	global_load_lds_dwordx4 v150, s[58:59]
	s_barrier
	s_waitcnt lgkmcnt(0)
	v_mfma_f32_16x16x32_bf16 v[60:63], v[156:159], v[178:181], v[60:63]
	v_mfma_f32_16x16x32_bf16 v[56:59], v[170:173], v[178:181], v[56:59]
	v_mfma_f32_16x16x32_bf16 v[44:47], v[156:159], v[196:199], v[44:47]
	v_mfma_f32_16x16x32_bf16 v[40:43], v[170:173], v[196:199], v[40:43]
	v_mfma_f32_16x16x32_bf16 v[28:31], v[156:159], v[204:207], v[28:31]
	v_mfma_f32_16x16x32_bf16 v[24:27], v[170:173], v[204:207], v[24:27]
	v_mfma_f32_16x16x32_bf16 v[12:15], v[156:159], v[212:215], v[12:15]
	v_mfma_f32_16x16x32_bf16 v[8:11], v[170:173], v[212:215], v[8:11]
	v_mfma_f32_16x16x32_bf16 v[60:63], v[160:163], v[192:195], v[60:63]
	v_mfma_f32_16x16x32_bf16 v[56:59], v[174:177], v[192:195], v[56:59]
	v_mfma_f32_16x16x32_bf16 v[44:47], v[160:163], v[200:203], v[44:47]
	v_mfma_f32_16x16x32_bf16 v[40:43], v[174:177], v[200:203], v[40:43]
	v_mfma_f32_16x16x32_bf16 v[28:31], v[160:163], v[208:211], v[28:31]
	v_mfma_f32_16x16x32_bf16 v[24:27], v[174:177], v[208:211], v[24:27]
	v_mfma_f32_16x16x32_bf16 v[12:15], v[160:163], v[216:219], v[12:15]
	v_mfma_f32_16x16x32_bf16 v[8:11], v[174:177], v[216:219], v[8:11]
	s_barrier
	s_add_u32 s14, s56, 0x40000
	s_addc_u32 s15, s57, 0
	s_add_i32 s16, s16, s64
	s_mov_b32 m0, s16
	s_nop 0
	global_load_lds_dwordx4 v148, s[14:15]
	s_add_i32 m0, s16, 0x2000
	s_nop 0
	global_load_lds_dwordx4 v150, s[14:15]
	s_waitcnt vmcnt(6)
	s_barrier
	v_mfma_f32_16x16x32_bf16 v[52:55], v[220:223], v[178:181], v[52:55]
	v_mfma_f32_16x16x32_bf16 v[48:51], v[228:231], v[178:181], v[48:51]
	v_mfma_f32_16x16x32_bf16 v[36:39], v[220:223], v[196:199], v[36:39]
	v_mfma_f32_16x16x32_bf16 v[32:35], v[228:231], v[196:199], v[32:35]
	v_mfma_f32_16x16x32_bf16 v[20:23], v[220:223], v[204:207], v[20:23]
	v_mfma_f32_16x16x32_bf16 v[16:19], v[228:231], v[204:207], v[16:19]
	v_mfma_f32_16x16x32_bf16 v[4:7], v[220:223], v[212:215], v[4:7]
	v_mfma_f32_16x16x32_bf16 v[0:3], v[228:231], v[212:215], v[0:3]
	v_mfma_f32_16x16x32_bf16 v[52:55], v[224:227], v[192:195], v[52:55]
	v_mfma_f32_16x16x32_bf16 v[48:51], v[232:235], v[192:195], v[48:51]
	v_mfma_f32_16x16x32_bf16 v[36:39], v[224:227], v[200:203], v[36:39]
	v_mfma_f32_16x16x32_bf16 v[32:35], v[232:235], v[200:203], v[32:35]
	v_mfma_f32_16x16x32_bf16 v[20:23], v[224:227], v[208:211], v[20:23]
	v_mfma_f32_16x16x32_bf16 v[16:19], v[232:235], v[208:211], v[16:19]
	v_mfma_f32_16x16x32_bf16 v[4:7], v[224:227], v[216:219], v[4:7]
	v_mfma_f32_16x16x32_bf16 v[0:3], v[232:235], v[216:219], v[0:3]
	s_add_i32 s16, 0, 0x18000
	v_add_u32_e32 v128, s16, v166
	s_barrier
	ds_read_b128 v[156:159], v128
	ds_read_b128 v[160:163], v128 offset:1024
	ds_read_b128 v[170:173], v128 offset:2048
	ds_read_b128 v[174:177], v128 offset:3072
	s_add_u32 s14, s58, 0x40000
	s_addc_u32 s15, s59, 0
	s_mov_b32 m0, s76
	ds_read_b128 v[178:181], v168 offset:32768
	ds_read_b128 v[192:195], v168 offset:33792
	ds_read_b128 v[196:199], v168 offset:34816
	ds_read_b128 v[200:203], v168 offset:35840
	ds_read_b128 v[204:207], v168 offset:36864
	ds_read_b128 v[208:211], v168 offset:37888
	ds_read_b128 v[212:215], v168 offset:38912
	ds_read_b128 v[216:219], v168 offset:39936
	global_load_lds_dwordx4 v148, s[14:15]
	s_mov_b32 m0, s77
	s_nop 0
	global_load_lds_dwordx4 v150, s[14:15]
	s_waitcnt lgkmcnt(8)
	s_barrier
; #define PG8_STAGE(bufoff, gbase, voff) do { _Pragma("unroll") for (int _i = 0; _i < 2; ++_i) \
;         __builtin_amdgcn_global_load_lds((const unsigned*)((const char*)(gbase) + (voff)[_i]), (PG8_LAS unsigned*)(lds + (bufoff) + ldsw + _i * 8192), 16, 0, 0); } while (0)
; #define PG8_LDA(dst, b, h) do { _Pragma("unroll") for (int m = 0; m < 4; ++m) _Pragma("unroll") for (int k = 0; k < 2; ++k) dst[m][k] = *(const PG8_LAS bf16x8*)(lds + PG8_SA(b, h) + aoff + m * 2048 + k * 1024); } while (0)
; #define PG8_LDB(dst, b, h) do { _Pragma("unroll") for (int n = 0; n < 2; ++n) _Pragma("unroll") for (int k = 0; k < 2; ++k) dst[n][k] = *(const PG8_LAS bf16x8*)(lds + PG8_SB(b, h) + boff + n * 2048 + k * 1024); } while (0)
; #define PG8_WAIT_V(n) asm volatile("s_waitcnt vmcnt(" #n ")" ::: "memory")
; #define PG8_WAIT_L(n) asm volatile("s_waitcnt lgkmcnt(" #n ")" ::: "memory")
; #define PG8_BAR __builtin_amdgcn_s_barrier()
; #define PG8_SCHED __builtin_amdgcn_sched_barrier(0)
; template <class Epi, class Sched, bool STAMP = false>
; __device__ __forceinline__ void gemm_phase(PG8_LAS unsigned char* lds, const Gemm g, const Sched& S, const Epi& E, unsigned long long* stamps) {
;     ...
;             PG8_WAIT_L(8); PG8_BAR; PG8_WAIT_L(0); PG8_MMA(0, 0, At, B0); PG8_BAR; PG8_SCHED;
;             PG8_LDB(B1, 1, 1); PG8_STAGE(PG8_SB(1, 0), b3, voffB);
;             PG8_BAR; PG8_WAIT_L(0); PG8_MMA(0, 1, At, B1); PG8_BAR;
;             PG8_LDA(At, 1, 1); PG8_STAGE(PG8_SA(1, 0), a3, voffA);
;             PG8_BAR; PG8_WAIT_L(0); PG8_MMA(1, 0, At, B0); PG8_BAR; PG8_SCHED;
;             PG8_STAGE(PG8_SB(1, 1), b3 + hstep, voffB);
;             PG8_WAIT_V(6); PG8_BAR; PG8_MMA(1, 1, At, B1); PG8_BAR;
;     __device__ __forceinline__ void operator()(const f32x4 (&acc)[2][2][4][2], const pg8::Unit& u, int wr, int wc, int fr, int fq) const {
;         const int row0 = u.pm * 256 + wr * 64 + fr, col0 = u.pn * 256 + wc * 32 + 4 * fq;
; #pragma unroll
;         for (int ai = 0; ai < 2; ++ai)
; #pragma unroll
;             for (int m = 0; m < 4; ++m) {
;                 const int row = row0 + ai * 128 + m * 16;
;                 float* xp = X + (size_t)row * 1024 + col0; bf16_t* bp = XB + (size_t)row * 1024 + col0;
;                 const float* xi = Xp0 ? (row < T_P ? Xp0 + (size_t)row * 1024 + col0 : Xs0 + (size_t)(row - T_P) * 1024 + col0) : xp;
	s_waitcnt lgkmcnt(0)
	v_mfma_f32_16x16x32_bf16 v[124:127], v[156:159], v[178:181], v[124:127]
	v_mfma_f32_16x16x32_bf16 v[120:123], v[170:173], v[178:181], v[120:123]
	v_mfma_f32_16x16x32_bf16 v[108:111], v[156:159], v[196:199], v[108:111]
	v_mfma_f32_16x16x32_bf16 v[104:107], v[170:173], v[196:199], v[104:107]
	v_mfma_f32_16x16x32_bf16 v[92:95], v[156:159], v[204:207], v[92:95]
	v_mfma_f32_16x16x32_bf16 v[88:91], v[170:173], v[204:207], v[88:91]
	v_mfma_f32_16x16x32_bf16 v[76:79], v[156:159], v[212:215], v[76:79]
	v_mfma_f32_16x16x32_bf16 v[72:75], v[170:173], v[212:215], v[72:75]
	v_mfma_f32_16x16x32_bf16 v[124:127], v[160:163], v[192:195], v[124:127]
	v_mfma_f32_16x16x32_bf16 v[120:123], v[174:177], v[192:195], v[120:123]
	v_mfma_f32_16x16x32_bf16 v[108:111], v[160:163], v[200:203], v[108:111]
	v_mfma_f32_16x16x32_bf16 v[104:107], v[174:177], v[200:203], v[104:107]
	v_mfma_f32_16x16x32_bf16 v[92:95], v[160:163], v[208:211], v[92:95]
	v_mfma_f32_16x16x32_bf16 v[88:91], v[174:177], v[208:211], v[88:91]
	v_mfma_f32_16x16x32_bf16 v[76:79], v[160:163], v[216:219], v[76:79]
	v_mfma_f32_16x16x32_bf16 v[72:75], v[174:177], v[216:219], v[72:75]
	s_barrier
	s_add_i32 s17, 0, 0x1c000
	s_add_i32 s14, s16, s64
	v_add_u32_e32 v128, s17, v166
	s_mov_b32 m0, s14
	ds_read_b128 v[220:223], v128
	ds_read_b128 v[224:227], v128 offset:1024
	ds_read_b128 v[228:231], v128 offset:2048
	ds_read_b128 v[232:235], v128 offset:3072
	global_load_lds_dwordx4 v244, s[56:57]
	s_add_i32 m0, s14, 0x2000
	s_nop 0
	global_load_lds_dwordx4 v245, s[56:57]
	s_barrier
	s_waitcnt lgkmcnt(0)
	v_mfma_f32_16x16x32_bf16 v[116:119], v[220:223], v[178:181], v[116:119]
	v_mfma_f32_16x16x32_bf16 v[112:115], v[228:231], v[178:181], v[112:115]
	v_mfma_f32_16x16x32_bf16 v[100:103], v[220:223], v[196:199], v[100:103]
	v_mfma_f32_16x16x32_bf16 v[96:99], v[228:231], v[196:199], v[96:99]
	v_mfma_f32_16x16x32_bf16 v[84:87], v[220:223], v[204:207], v[84:87]
	v_mfma_f32_16x16x32_bf16 v[80:83], v[228:231], v[204:207], v[80:83]
	v_mfma_f32_16x16x32_bf16 v[68:71], v[220:223], v[212:215], v[68:71]
	v_mfma_f32_16x16x32_bf16 v[64:67], v[228:231], v[212:215], v[64:67]
	v_mfma_f32_16x16x32_bf16 v[116:119], v[224:227], v[192:195], v[116:119]
	v_mfma_f32_16x16x32_bf16 v[112:115], v[232:235], v[192:195], v[112:115]
	v_mfma_f32_16x16x32_bf16 v[100:103], v[224:227], v[200:203], v[100:103]
	v_mfma_f32_16x16x32_bf16 v[96:99], v[232:235], v[200:203], v[96:99]
	v_mfma_f32_16x16x32_bf16 v[84:87], v[224:227], v[208:211], v[84:87]
	v_mfma_f32_16x16x32_bf16 v[80:83], v[232:235], v[208:211], v[80:83]
	v_mfma_f32_16x16x32_bf16 v[68:71], v[224:227], v[216:219], v[68:71]
	v_mfma_f32_16x16x32_bf16 v[64:67], v[232:235], v[216:219], v[64:67]
	s_mov_b32 m0, s88
	s_barrier
	ds_read_b128 v[178:181], v168 offset:49152
	ds_read_b128 v[192:195], v168 offset:50176
	ds_read_b128 v[196:199], v168 offset:51200
	ds_read_b128 v[200:203], v168 offset:52224
	ds_read_b128 v[204:207], v168 offset:53248
	ds_read_b128 v[208:211], v168 offset:54272
	ds_read_b128 v[212:215], v168 offset:55296
	ds_read_b128 v[216:219], v168 offset:56320
	global_load_lds_dwordx4 v244, s[58:59]
	s_mov_b32 m0, s89
	s_nop 0
	global_load_lds_dwordx4 v245, s[58:59]
	s_barrier
	s_waitcnt lgkmcnt(0)
	v_mfma_f32_16x16x32_bf16 v[60:63], v[156:159], v[178:181], v[60:63]
	v_mfma_f32_16x16x32_bf16 v[56:59], v[170:173], v[178:181], v[56:59]
	v_mfma_f32_16x16x32_bf16 v[44:47], v[156:159], v[196:199], v[44:47]
	v_mfma_f32_16x16x32_bf16 v[40:43], v[170:173], v[196:199], v[40:43]
	v_mfma_f32_16x16x32_bf16 v[28:31], v[156:159], v[204:207], v[28:31]
	v_mfma_f32_16x16x32_bf16 v[24:27], v[170:173], v[204:207], v[24:27]
	v_mfma_f32_16x16x32_bf16 v[12:15], v[156:159], v[212:215], v[12:15]
	v_mfma_f32_16x16x32_bf16 v[8:11], v[170:173], v[212:215], v[8:11]
	v_mfma_f32_16x16x32_bf16 v[60:63], v[160:163], v[192:195], v[60:63]
	v_mfma_f32_16x16x32_bf16 v[56:59], v[174:177], v[192:195], v[56:59]
	v_mfma_f32_16x16x32_bf16 v[44:47], v[160:163], v[200:203], v[44:47]
	v_mfma_f32_16x16x32_bf16 v[40:43], v[174:177], v[200:203], v[40:43]
	v_mfma_f32_16x16x32_bf16 v[28:31], v[160:163], v[208:211], v[28:31]
	v_mfma_f32_16x16x32_bf16 v[24:27], v[174:177], v[208:211], v[24:27]
	v_mfma_f32_16x16x32_bf16 v[12:15], v[160:163], v[216:219], v[12:15]
	v_mfma_f32_16x16x32_bf16 v[8:11], v[174:177], v[216:219], v[8:11]
	s_barrier
	s_add_u32 s14, s56, 0x40080
	s_addc_u32 s15, s57, 0
	s_add_i32 s16, s17, s64
	s_mov_b32 m0, s16
	s_nop 0
	global_load_lds_dwordx4 v148, s[14:15]
	s_add_i32 m0, s16, 0x2000
	s_nop 0
	global_load_lds_dwordx4 v150, s[14:15]
	s_waitcnt vmcnt(6)
	s_barrier
	v_mfma_f32_16x16x32_bf16 v[52:55], v[220:223], v[178:181], v[52:55]
	v_mfma_f32_16x16x32_bf16 v[48:51], v[228:231], v[178:181], v[48:51]
	v_mfma_f32_16x16x32_bf16 v[36:39], v[220:223], v[196:199], v[36:39]
	v_mfma_f32_16x16x32_bf16 v[32:35], v[228:231], v[196:199], v[32:35]
	v_mfma_f32_16x16x32_bf16 v[20:23], v[220:223], v[204:207], v[20:23]
	v_mfma_f32_16x16x32_bf16 v[16:19], v[228:231], v[204:207], v[16:19]
	v_mfma_f32_16x16x32_bf16 v[4:7], v[220:223], v[212:215], v[4:7]
	v_mfma_f32_16x16x32_bf16 v[0:3], v[228:231], v[212:215], v[0:3]
	v_mfma_f32_16x16x32_bf16 v[52:55], v[224:227], v[192:195], v[52:55]
	v_mfma_f32_16x16x32_bf16 v[48:51], v[232:235], v[192:195], v[48:51]
	v_mfma_f32_16x16x32_bf16 v[36:39], v[224:227], v[200:203], v[36:39]
	v_mfma_f32_16x16x32_bf16 v[32:35], v[232:235], v[200:203], v[32:35]
	v_mfma_f32_16x16x32_bf16 v[20:23], v[224:227], v[208:211], v[20:23]
	v_mfma_f32_16x16x32_bf16 v[16:19], v[232:235], v[208:211], v[16:19]
	v_mfma_f32_16x16x32_bf16 v[4:7], v[224:227], v[216:219], v[4:7]
	v_mfma_f32_16x16x32_bf16 v[0:3], v[232:235], v[216:219], v[0:3]
	s_add_i32 s39, s39, 2
	s_add_u32 vcc_hi, vcc_hi, 0x100
	s_addc_u32 s38, s38, 0
	s_cmp_gt_u32 s39, 13
	s_mov_b64 s[44:45], s[48:49]
	s_barrier
	s_cbranch_scc0 .LBB0_141
	v_lshl_add_u32 v158, s30, 8, v139
	v_ashrrev_i32_e32 v159, 31, v158
	v_lshl_or_b32 v156, s36, 8, v167
	v_lshlrev_b64 v[160:161], 12, v[158:159]
	v_ashrrev_i32_e32 v157, 31, v156
	v_lshl_add_u64 v[160:161], s[84:85], 0, v[160:161]
	v_lshl_add_u64 v[160:161], v[156:157], 2, v[160:161]
	v_cndmask_b32_e64 v128, 0, 1, s[12:13]
	v_lshlrev_b64 v[164:165], 10, v[158:159]
	v_cmp_ne_u32_e64 s[44:45], 1, v128
	s_andn2_b64 vcc, exec, s[12:13]
	v_mov_b64_e32 v[162:163], v[160:161]
	v_readlane_b32 s39, v242, 28
	s_movk_i32 s21, 0x3fff
	s_mov_b32 s38, 0x1ffff
	s_cbranch_vccnz .LBB0_148
	v_cmp_lt_i32_e32 vcc, s21, v158
	s_and_saveexec_b64 s[14:15], vcc
	s_xor_b64 s[30:31], exec, s[14:15]
	v_add_u32_e32 v128, 0xffffc000, v158
	v_lshlrev_b64 v[162:163], 12, v[128:129]
	v_lshl_add_u64 v[162:163], s[4:5], 0, v[162:163]
	v_lshl_add_u64 v[162:163], v[156:157], 2, v[162:163]
	s_andn2_saveexec_b64 s[30:31], s[30:31]
	v_lshl_add_u64 v[162:163], v[164:165], 2, s[0:1]
	v_lshl_add_u64 v[162:163], v[156:157], 2, v[162:163]
	s_or_b64 exec, exec, s[30:31]

; #define PG8_STAGE(bufoff, gbase, voff) do { _Pragma("unroll") for (int _i = 0; _i < 2; ++_i) \
;         __builtin_amdgcn_global_load_lds((const unsigned*)((const char*)(gbase) + (voff)[_i]), (PG8_LAS unsigned*)(lds + (bufoff) + ldsw + _i * 8192), 16, 0, 0); } while (0)
; #define PG8_WAIT_V(n) asm volatile("s_waitcnt vmcnt(" #n ")" ::: "memory")
; #define PG8_BAR __builtin_amdgcn_s_barrier()
;     __device__ bool next(int i, pg8::Unit& u) const { if (i != 0 || !valid) return false; u.pm = pm; u.pn = pn; return true; }
; template <class Epi, class Sched, bool STAMP = false>
; __device__ __forceinline__ void gemm_phase(PG8_LAS unsigned char* lds, const Gemm g, const Sched& S, const Epi& E, unsigned long long* stamps) {
;     ...
;     const int aoff = lds_byte(wr * 64 + fr, fq * 8), boff = lds_byte(wc * 32 + fr, fq * 8);
;     ...
;     Unit cur, nxt; int ui = 0;
;     if (!S.next(0, cur)) return;
;     f32x4 acc[2][2][4][2];
; #pragma unroll
;     for (int a = 0; a < 2; ++a)
; #pragma unroll
;         for (int b = 0; b < 2; ++b)
; #pragma unroll
;             for (int m = 0; m < 4; ++m)
; #pragma unroll
;                 for (int n = 0; n < 2; ++n) acc[a][b][m][n] = (f32x4){0.f, 0.f, 0.f, 0.f};
;     bf16x8 At[4][2], B0[2][2], B1[2][2];
;     const char* cA = (const char*)g.A + (size_t)cur.pm * tstep; const char* cB = (const char*)g.Bt + (size_t)cur.pn * tstep;
;     S.a_ready(cur);
;     PG8_STAGE(PG8_SB(0, 0), cB, voffB); PG8_STAGE(PG8_SA(0, 0), cA, voffA); PG8_STAGE(PG8_SB(0, 1), cB + hstep, voffB); PG8_STAGE(PG8_SA(0, 1), cA + hstep, voffA);
;     if (wr == 1) PG8_BAR;
;     PG8_WAIT_V(4); PG8_BAR;
;     PG8_STAGE(PG8_SB(1, 0), cB + kstep, voffB); PG8_STAGE(PG8_SA(1, 0), cA + kstep, voffA); PG8_STAGE(PG8_SB(1, 1), cB + hstep + kstep, voffB);
;     PG8_WAIT_V(6); PG8_BAR;
.LBB0_212:
	v_bfe_u32 v139, v0, 4, 2
	s_lshl_b32 s12, s12, 5
	v_and_b32_e32 v150, 15, v0
	v_lshlrev_b32_e32 v1, 4, v139
	v_lshlrev_b32_e32 v0, 2, v0
	s_and_b32 s56, s12, 0x60
	v_lshl_add_u64 v[2:3], s[0:1], 0, v[128:129]
	v_mov_b32_e32 v149, v129
	s_lshl_b32 s53, s13, 6
	v_lshl_or_b32 v1, v150, 6, v1
	s_lshl_b32 s13, s13, 13
	v_and_b32_e32 v0, 32, v0
	s_lshl_b32 s12, s56, 7
	v_lshl_add_u64 v[4:5], s[0:1], 0, v[148:149]
	v_bitop3_b32 v10, v1, s13, v0 bitop3:0xde
	v_bitop3_b32 v151, v1, s12, v0 bitop3:0xde
	s_add_i32 m0, s45, 0x18000
	v_lshl_add_u64 v[0:1], v[2:3], 0, s[18:19]
	v_lshl_add_u64 v[6:7], s[4:5], 0, v[128:129]
	s_waitcnt vmcnt(4)
	s_barrier
	global_load_lds_dwordx4 v[0:1], off
	v_lshl_add_u64 v[0:1], v[4:5], 0, s[18:19]
	s_add_i32 m0, s45, 0x1a000
	s_add_i32 s57, s45, 0x8000
	s_add_i32 s58, s45, 0xa000
	v_lshl_add_u64 v[8:9], s[4:5], 0, v[148:149]
	global_load_lds_dwordx4 v[0:1], off
	v_lshl_add_u64 v[0:1], v[6:7], 0, s[18:19]
	s_mov_b32 m0, s57
	s_add_u32 s12, s0, 0x40080
	global_load_lds_dwordx4 v[0:1], off
	v_lshl_add_u64 v[0:1], v[8:9], 0, s[18:19]
	s_mov_b32 m0, s58
	s_addc_u32 s13, s1, 0
	global_load_lds_dwordx4 v[0:1], off
	s_add_i32 m0, s45, 0x1c000
	v_lshl_add_u64 v[0:1], s[12:13], 0, v[128:129]
	global_load_lds_dwordx4 v[0:1], off
	v_lshl_add_u64 v[0:1], s[12:13], 0, v[148:149]
	s_add_i32 m0, s45, 0x1e000
	s_mov_b32 s14, 0
	global_load_lds_dwordx4 v[0:1], off
	s_waitcnt vmcnt(6)
	v_mov_b32_e32 v0, 0
	s_mov_b64 s[12:13], -1
	s_mov_b64 s[20:21], 0
	v_add_u32_e32 v152, 0, v10
	v_mov_b32_e32 v1, v0
	v_mov_b32_e32 v2, v0
	v_mov_b32_e32 v3, v0
	v_mov_b32_e32 v4, v0
	v_mov_b32_e32 v5, v0
	v_mov_b32_e32 v6, v0
	v_mov_b32_e32 v7, v0
	v_mov_b32_e32 v8, v0
	v_mov_b32_e32 v9, v0
	v_mov_b32_e32 v10, v0
	v_mov_b32_e32 v11, v0
	v_mov_b32_e32 v12, v0
	v_mov_b32_e32 v13, v0
	v_mov_b32_e32 v14, v0
	v_mov_b32_e32 v15, v0
	v_mov_b32_e32 v24, v0
	v_mov_b32_e32 v25, v0
	v_mov_b32_e32 v26, v0
	v_mov_b32_e32 v27, v0
	v_mov_b32_e32 v28, v0
	v_mov_b32_e32 v29, v0
	v_mov_b32_e32 v30, v0
	v_mov_b32_e32 v31, v0
	v_mov_b32_e32 v40, v0
	v_mov_b32_e32 v41, v0
	v_mov_b32_e32 v42, v0
	v_mov_b32_e32 v43, v0
	v_mov_b32_e32 v44, v0
	v_mov_b32_e32 v45, v0
	v_mov_b32_e32 v46, v0
	v_mov_b32_e32 v47, v0
	v_mov_b32_e32 v16, v0
	v_mov_b32_e32 v17, v0
	v_mov_b32_e32 v18, v0
	v_mov_b32_e32 v19, v0
	v_mov_b32_e32 v20, v0
	v_mov_b32_e32 v21, v0
	v_mov_b32_e32 v22, v0
	v_mov_b32_e32 v23, v0
	v_mov_b32_e32 v32, v0
	v_mov_b32_e32 v33, v0
	v_mov_b32_e32 v34, v0
	v_mov_b32_e32 v35, v0
	v_mov_b32_e32 v36, v0
	v_mov_b32_e32 v37, v0
	v_mov_b32_e32 v38, v0
	v_mov_b32_e32 v39, v0
	v_mov_b32_e32 v48, v0
	v_mov_b32_e32 v49, v0
	v_mov_b32_e32 v50, v0
	v_mov_b32_e32 v51, v0
	v_mov_b32_e32 v52, v0
	v_mov_b32_e32 v53, v0
	v_mov_b32_e32 v54, v0
	v_mov_b32_e32 v55, v0
	v_mov_b32_e32 v56, v0
	v_mov_b32_e32 v57, v0
	v_mov_b32_e32 v58, v0
	v_mov_b32_e32 v59, v0
	v_mov_b32_e32 v60, v0
	v_mov_b32_e32 v61, v0
	v_mov_b32_e32 v62, v0
	v_mov_b32_e32 v63, v0
	v_mov_b32_e32 v64, v0
	v_mov_b32_e32 v65, v0
	v_mov_b32_e32 v66, v0
	v_mov_b32_e32 v67, v0
	v_mov_b32_e32 v68, v0
	v_mov_b32_e32 v69, v0
	v_mov_b32_e32 v70, v0
	v_mov_b32_e32 v71, v0
	v_mov_b32_e32 v72, v0
	v_mov_b32_e32 v73, v0
	v_mov_b32_e32 v74, v0
	v_mov_b32_e32 v75, v0
	v_mov_b32_e32 v76, v0
	v_mov_b32_e32 v77, v0
	v_mov_b32_e32 v78, v0
	v_mov_b32_e32 v79, v0
	v_mov_b32_e32 v84, v0
	v_mov_b32_e32 v85, v0
	v_mov_b32_e32 v86, v0
	v_mov_b32_e32 v87, v0
	v_mov_b32_e32 v92, v0
	v_mov_b32_e32 v93, v0
	v_mov_b32_e32 v94, v0
	v_mov_b32_e32 v95, v0
	v_mov_b32_e32 v100, v0
	v_mov_b32_e32 v101, v0
	v_mov_b32_e32 v102, v0
	v_mov_b32_e32 v103, v0
	v_mov_b32_e32 v108, v0
	v_mov_b32_e32 v109, v0
	v_mov_b32_e32 v110, v0
	v_mov_b32_e32 v111, v0
	v_mov_b32_e32 v80, v0
	v_mov_b32_e32 v81, v0
	v_mov_b32_e32 v82, v0
	v_mov_b32_e32 v83, v0
	v_mov_b32_e32 v88, v0
	v_mov_b32_e32 v89, v0
	v_mov_b32_e32 v90, v0
	v_mov_b32_e32 v91, v0
	v_mov_b32_e32 v96, v0
	v_mov_b32_e32 v97, v0
	v_mov_b32_e32 v98, v0
	v_mov_b32_e32 v99, v0
	v_mov_b32_e32 v104, v0
	v_mov_b32_e32 v105, v0
	v_mov_b32_e32 v106, v0
	v_mov_b32_e32 v107, v0
	v_mov_b32_e32 v112, v0
	v_mov_b32_e32 v113, v0
	v_mov_b32_e32 v114, v0
	v_mov_b32_e32 v115, v0
	v_mov_b32_e32 v116, v0
	v_mov_b32_e32 v117, v0
	v_mov_b32_e32 v118, v0
	v_mov_b32_e32 v119, v0
	v_mov_b32_e32 v120, v0
	v_mov_b32_e32 v121, v0
	v_mov_b32_e32 v122, v0
	v_mov_b32_e32 v123, v0
	v_mov_b32_e32 v124, v0
	v_mov_b32_e32 v125, v0
	v_mov_b32_e32 v126, v0
	v_mov_b32_e32 v127, v0
	s_barrier
	v_add_u32_e32 v244, 0x80, v128
	v_add_u32_e32 v245, 0x80, v148
; #define PG8_STAGE(bufoff, gbase, voff) do { _Pragma("unroll") for (int _i = 0; _i < 2; ++_i) \
;         __builtin_amdgcn_global_load_lds((const unsigned*)((const char*)(gbase) + (voff)[_i]), (PG8_LAS unsigned*)(lds + (bufoff) + ldsw + _i * 8192), 16, 0, 0); } while (0)
; #define PG8_LDA(dst, b, h) do { _Pragma("unroll") for (int m = 0; m < 4; ++m) _Pragma("unroll") for (int k = 0; k < 2; ++k) dst[m][k] = *(const PG8_LAS bf16x8*)(lds + PG8_SA(b, h) + aoff + m * 2048 + k * 1024); } while (0)
; #define PG8_LDB(dst, b, h) do { _Pragma("unroll") for (int n = 0; n < 2; ++n) _Pragma("unroll") for (int k = 0; k < 2; ++k) dst[n][k] = *(const PG8_LAS bf16x8*)(lds + PG8_SB(b, h) + boff + n * 2048 + k * 1024); } while (0)
; #define PG8_MMA(ai, bj, At, Bt) do { __builtin_amdgcn_s_setprio(1); _Pragma("unroll") for (int m = 0; m < 4; ++m) _Pragma("unroll") for (int n = 0; n < 2; ++n) _Pragma("unroll") for (int k = 0; k < 2; ++k) \
;         acc[ai][bj][m][n] = __builtin_amdgcn_mfma_f32_16x16x32_bf16(Bt[n][k], At[m][k], acc[ai][bj][m][n], 0, 0, 0); __builtin_amdgcn_s_setprio(0); } while (0)
; #define PG8_WAIT_L(n) asm volatile("s_waitcnt lgkmcnt(" #n ")" ::: "memory")
; #define PG8_BAR __builtin_amdgcn_s_barrier()
; #define PG8_SCHED __builtin_amdgcn_sched_barrier(0)
; template <class Epi, class Sched, bool STAMP = false>
; __device__ __forceinline__ void gemm_phase(PG8_LAS unsigned char* lds, const Gemm g, const Sched& S, const Epi& E, unsigned long long* stamps) {
;     ...
;         for (int t = 0; t < nt; t += 2) {
;             const bool last = (t == nt - 2);
;             const char* a1 = cA + (size_t)(t + 1) * kstep;
;             const char* a2 = last ? nA : cA + (size_t)(t + 2) * kstep; const char* b2 = last ? nB : cB + (size_t)(t + 2) * kstep;
;             const char* a3 = a2 + kstep; const char* b3 = b2 + kstep;
;             if (last && has_next) S.a_ready(nxt);
;             PG8_LDB(B0, 0, 0); PG8_SCHED; PG8_LDA(At, 0, 0); PG8_STAGE(PG8_SA(1, 1), a1 + hstep, voffA);
;             PG8_WAIT_L(8); PG8_BAR; PG8_WAIT_L(0); PG8_MMA(0, 0, At, B0); PG8_BAR; PG8_SCHED;
;             PG8_LDB(B1, 0, 1); PG8_STAGE(PG8_SB(0, 0), b2, voffB);
;             PG8_BAR; PG8_WAIT_L(0); PG8_MMA(0, 1, At, B1); PG8_BAR;
;             PG8_LDA(At, 0, 1); PG8_STAGE(PG8_SA(0, 0), a2, voffA);
;             PG8_BAR; PG8_WAIT_L(0); PG8_MMA(1, 0, At, B0); PG8_BAR; PG8_SCHED;
.LBB0_213:
	s_add_i32 s15, s14, 0x100
	s_and_b64 s[16:17], s[20:21], exec
	s_cselect_b32 s15, 0, s15
	s_cselect_b32 s16, 0, 0
	s_add_u32 s26, s4, s15
	s_addc_u32 s27, s5, s16
	s_add_i32 s21, 0, 0x10000
	s_add_u32 s30, s0, s15
	s_addc_u32 s31, s1, s16
	s_add_u32 s36, s6, s14
	s_addc_u32 s37, s7, 0
	s_add_i32 s61, s21, s44
	s_add_i32 m0, s45, 0xc000
	s_add_i32 s62, s45, 0xe000
	s_add_i32 s60, 0, 0x14000
	s_add_i32 s59, s61, 0x2000
	s_add_u32 s24, s30, 0x40000
	v_add_u32_e32 v153, s21, v151
	s_addc_u32 s25, s31, 0
	s_add_i32 s38, s60, s44
	ds_read_b128 v[154:157], v153
	ds_read_b128 v[158:161], v153 offset:1024
	ds_read_b128 v[162:165], v153 offset:2048
	ds_read_b128 v[166:169], v153 offset:3072
	s_add_i32 s29, s38, 0x2000
	s_add_i32 s17, 0, 0x18000
	s_add_u32 s22, s26, 0x40000
	s_addc_u32 s23, s27, 0
	s_add_i32 s16, s17, s44
	s_add_i32 s15, 0, 0x1c000
	s_add_i32 s14, s16, 0x2000
	s_add_u32 s20, s30, 0x40080
	s_addc_u32 s21, s31, 0
	s_add_i32 s52, s15, s44
	s_add_i32 s39, s52, 0x2000
	v_lshl_add_u64 v[182:183], s[36:37], 0, v[128:129]
	v_lshl_add_u64 v[182:183], v[182:183], 0, s[18:19]
	ds_read_b128 v[170:173], v152
	ds_read_b128 v[174:177], v152 offset:1024
	ds_read_b128 v[178:181], v152 offset:2048
	ds_read_b128 v[192:195], v152 offset:3072
	ds_read_b128 v[196:199], v152 offset:4096
	ds_read_b128 v[200:203], v152 offset:5120
	ds_read_b128 v[204:207], v152 offset:6144
	ds_read_b128 v[208:211], v152 offset:7168
	global_load_lds_dwordx4 v244, s[36:37]
	v_lshl_add_u64 v[182:183], s[36:37], 0, v[148:149]
	v_lshl_add_u64 v[182:183], v[182:183], 0, s[18:19]
	s_mov_b32 m0, s62
	s_nop 0
	global_load_lds_dwordx4 v245, s[36:37]
	s_waitcnt lgkmcnt(8)
	s_barrier
	s_waitcnt lgkmcnt(0)
	v_mfma_f32_16x16x32_bf16 v[124:127], v[154:157], v[170:173], v[124:127]
	v_mfma_f32_16x16x32_bf16 v[120:123], v[162:165], v[170:173], v[120:123]
	v_mfma_f32_16x16x32_bf16 v[116:119], v[154:157], v[178:181], v[116:119]
	v_mfma_f32_16x16x32_bf16 v[112:115], v[162:165], v[178:181], v[112:115]
	v_mfma_f32_16x16x32_bf16 v[104:107], v[154:157], v[196:199], v[104:107]
	v_mfma_f32_16x16x32_bf16 v[96:99], v[162:165], v[196:199], v[96:99]
	v_mfma_f32_16x16x32_bf16 v[88:91], v[154:157], v[204:207], v[88:91]
	v_mfma_f32_16x16x32_bf16 v[80:83], v[162:165], v[204:207], v[80:83]
	v_mfma_f32_16x16x32_bf16 v[124:127], v[158:161], v[174:177], v[124:127]
	v_mfma_f32_16x16x32_bf16 v[120:123], v[166:169], v[174:177], v[120:123]
	v_mfma_f32_16x16x32_bf16 v[116:119], v[158:161], v[192:195], v[116:119]
	v_mfma_f32_16x16x32_bf16 v[112:115], v[166:169], v[192:195], v[112:115]
	v_mfma_f32_16x16x32_bf16 v[104:107], v[158:161], v[200:203], v[104:107]
	v_mfma_f32_16x16x32_bf16 v[96:99], v[166:169], v[200:203], v[96:99]
	v_mfma_f32_16x16x32_bf16 v[88:91], v[158:161], v[208:211], v[88:91]
	v_mfma_f32_16x16x32_bf16 v[80:83], v[166:169], v[208:211], v[80:83]
	s_barrier
	s_mov_b32 m0, s61
	v_add_u32_e32 v153, s60, v151
	v_lshl_add_u64 v[182:183], s[30:31], 0, v[128:129]
	ds_read_b128 v[212:215], v153
	ds_read_b128 v[216:219], v153 offset:1024
	ds_read_b128 v[220:223], v153 offset:2048
	ds_read_b128 v[224:227], v153 offset:3072
	global_load_lds_dwordx4 v128, s[30:31]
	v_lshl_add_u64 v[228:229], s[30:31], 0, v[148:149]
	s_mov_b32 m0, s59
	s_nop 0
	global_load_lds_dwordx4 v148, s[30:31]
	s_barrier
	s_waitcnt lgkmcnt(0)
	v_mfma_f32_16x16x32_bf16 v[108:111], v[212:215], v[170:173], v[108:111]
	v_mfma_f32_16x16x32_bf16 v[100:103], v[220:223], v[170:173], v[100:103]
	v_mfma_f32_16x16x32_bf16 v[92:95], v[212:215], v[178:181], v[92:95]
	v_mfma_f32_16x16x32_bf16 v[84:87], v[220:223], v[178:181], v[84:87]
	v_mfma_f32_16x16x32_bf16 v[76:79], v[212:215], v[196:199], v[76:79]
	v_mfma_f32_16x16x32_bf16 v[72:75], v[220:223], v[196:199], v[72:75]
	v_mfma_f32_16x16x32_bf16 v[68:71], v[212:215], v[204:207], v[68:71]
	v_mfma_f32_16x16x32_bf16 v[64:67], v[220:223], v[204:207], v[64:67]
	v_mfma_f32_16x16x32_bf16 v[108:111], v[216:219], v[174:177], v[108:111]
	v_mfma_f32_16x16x32_bf16 v[100:103], v[224:227], v[174:177], v[100:103]
	v_mfma_f32_16x16x32_bf16 v[92:95], v[216:219], v[192:195], v[92:95]
	v_mfma_f32_16x16x32_bf16 v[84:87], v[224:227], v[192:195], v[84:87]
	v_mfma_f32_16x16x32_bf16 v[76:79], v[216:219], v[200:203], v[76:79]
	v_mfma_f32_16x16x32_bf16 v[72:75], v[224:227], v[200:203], v[72:75]
	v_mfma_f32_16x16x32_bf16 v[68:71], v[216:219], v[208:211], v[68:71]
	v_mfma_f32_16x16x32_bf16 v[64:67], v[224:227], v[208:211], v[64:67]
	s_mov_b32 m0, s45
	v_lshl_add_u64 v[230:231], s[26:27], 0, v[128:129]
	s_barrier
	ds_read_b128 v[170:173], v152 offset:16384
	ds_read_b128 v[174:177], v152 offset:17408
	ds_read_b128 v[178:181], v152 offset:18432
	ds_read_b128 v[192:195], v152 offset:19456
	ds_read_b128 v[196:199], v152 offset:20480
	ds_read_b128 v[200:203], v152 offset:21504
	ds_read_b128 v[204:207], v152 offset:22528
	ds_read_b128 v[208:211], v152 offset:23552
	global_load_lds_dwordx4 v128, s[26:27]
	v_lshl_add_u64 v[232:233], s[26:27], 0, v[148:149]
	s_mov_b32 m0, s47
	s_nop 0
	global_load_lds_dwordx4 v148, s[26:27]
	s_barrier
	s_waitcnt lgkmcnt(0)
	v_mfma_f32_16x16x32_bf16 v[60:63], v[154:157], v[170:173], v[60:63]
	v_mfma_f32_16x16x32_bf16 v[56:59], v[162:165], v[170:173], v[56:59]
	v_mfma_f32_16x16x32_bf16 v[52:55], v[154:157], v[178:181], v[52:55]
	v_mfma_f32_16x16x32_bf16 v[48:51], v[162:165], v[178:181], v[48:51]
	v_mfma_f32_16x16x32_bf16 v[36:39], v[154:157], v[196:199], v[36:39]
	v_mfma_f32_16x16x32_bf16 v[32:35], v[162:165], v[196:199], v[32:35]
	v_mfma_f32_16x16x32_bf16 v[20:23], v[154:157], v[204:207], v[20:23]
	v_mfma_f32_16x16x32_bf16 v[16:19], v[162:165], v[204:207], v[16:19]
	v_mfma_f32_16x16x32_bf16 v[60:63], v[158:161], v[174:177], v[60:63]
	v_mfma_f32_16x16x32_bf16 v[56:59], v[166:169], v[174:177], v[56:59]
	v_mfma_f32_16x16x32_bf16 v[52:55], v[158:161], v[192:195], v[52:55]
	v_mfma_f32_16x16x32_bf16 v[48:51], v[166:169], v[192:195], v[48:51]
	v_mfma_f32_16x16x32_bf16 v[36:39], v[158:161], v[200:203], v[36:39]
	v_mfma_f32_16x16x32_bf16 v[32:35], v[166:169], v[200:203], v[32:35]
	v_mfma_f32_16x16x32_bf16 v[20:23], v[158:161], v[208:211], v[20:23]
	v_mfma_f32_16x16x32_bf16 v[16:19], v[166:169], v[208:211], v[16:19]
	s_barrier
; #define PG8_STAGE(bufoff, gbase, voff) do { _Pragma("unroll") for (int _i = 0; _i < 2; ++_i) \
;         __builtin_amdgcn_global_load_lds((const unsigned*)((const char*)(gbase) + (voff)[_i]), (PG8_LAS unsigned*)(lds + (bufoff) + ldsw + _i * 8192), 16, 0, 0); } while (0)
; #define PG8_LDA(dst, b, h) do { _Pragma("unroll") for (int m = 0; m < 4; ++m) _Pragma("unroll") for (int k = 0; k < 2; ++k) dst[m][k] = *(const PG8_LAS bf16x8*)(lds + PG8_SA(b, h) + aoff + m * 2048 + k * 1024); } while (0)
; #define PG8_LDB(dst, b, h) do { _Pragma("unroll") for (int n = 0; n < 2; ++n) _Pragma("unroll") for (int k = 0; k < 2; ++k) dst[n][k] = *(const PG8_LAS bf16x8*)(lds + PG8_SB(b, h) + boff + n * 2048 + k * 1024); } while (0)
; #define PG8_WAIT_V(n) asm volatile("s_waitcnt vmcnt(" #n ")" ::: "memory")
; #define PG8_WAIT_L(n) asm volatile("s_waitcnt lgkmcnt(" #n ")" ::: "memory")
; #define PG8_BAR __builtin_amdgcn_s_barrier()
; template <class Epi, class Sched, bool STAMP = false>
; __device__ __forceinline__ void gemm_phase(PG8_LAS unsigned char* lds, const Gemm g, const Sched& S, const Epi& E, unsigned long long* stamps) {
;     ...
;             PG8_LDB(B0, 0, 0); PG8_SCHED; PG8_LDA(At, 0, 0); PG8_STAGE(PG8_SA(1, 1), a1 + hstep, voffA);
;             PG8_WAIT_L(8); PG8_BAR; PG8_WAIT_L(0); PG8_MMA(0, 0, At, B0); PG8_BAR; PG8_SCHED;
;             PG8_LDB(B1, 0, 1); PG8_STAGE(PG8_SB(0, 0), b2, voffB);
;             PG8_BAR; PG8_WAIT_L(0); PG8_MMA(0, 1, At, B1); PG8_BAR;
;             PG8_LDA(At, 0, 1); PG8_STAGE(PG8_SA(0, 0), a2, voffA);
;             PG8_BAR; PG8_WAIT_L(0); PG8_MMA(1, 0, At, B0); PG8_BAR; PG8_SCHED;
;             PG8_STAGE(PG8_SB(0, 1), b2 + hstep, voffB);
;             PG8_WAIT_V(6); PG8_BAR; PG8_MMA(1, 1, At, B1); PG8_BAR;
;             PG8_LDB(B0, 1, 0); PG8_SCHED; PG8_LDA(At, 1, 0); PG8_STAGE(PG8_SA(0, 1), a2 + hstep, voffA);
;             PG8_WAIT_L(8); PG8_BAR; PG8_WAIT_L(0); PG8_MMA(0, 0, At, B0); PG8_BAR; PG8_SCHED;
;             PG8_LDB(B1, 1, 1); PG8_STAGE(PG8_SB(1, 0), b3, voffB);
;             PG8_BAR; PG8_WAIT_L(0); PG8_MMA(0, 1, At, B1); PG8_BAR;
;             PG8_LDA(At, 1, 1); PG8_STAGE(PG8_SA(1, 0), a3, voffA);
;             PG8_BAR; PG8_WAIT_L(0); PG8_MMA(1, 0, At, B0); PG8_BAR; PG8_SCHED;
;             PG8_STAGE(PG8_SB(1, 1), b3 + hstep, voffB);
;             PG8_WAIT_V(6); PG8_BAR; PG8_MMA(1, 1, At, B1); PG8_BAR;
	s_mov_b32 m0, s38
	s_nop 0
	global_load_lds_dwordx4 v128, s[24:25]
	s_mov_b32 m0, s29
	s_nop 0
	global_load_lds_dwordx4 v148, s[24:25]
	s_waitcnt vmcnt(6)
	s_barrier
	v_mfma_f32_16x16x32_bf16 v[44:47], v[212:215], v[170:173], v[44:47]
	v_mfma_f32_16x16x32_bf16 v[40:43], v[220:223], v[170:173], v[40:43]
	v_mfma_f32_16x16x32_bf16 v[28:31], v[212:215], v[178:181], v[28:31]
	v_mfma_f32_16x16x32_bf16 v[24:27], v[220:223], v[178:181], v[24:27]
	v_mfma_f32_16x16x32_bf16 v[12:15], v[212:215], v[196:199], v[12:15]
	v_mfma_f32_16x16x32_bf16 v[8:11], v[220:223], v[196:199], v[8:11]
	v_mfma_f32_16x16x32_bf16 v[4:7], v[212:215], v[204:207], v[4:7]
	v_mfma_f32_16x16x32_bf16 v[0:3], v[220:223], v[204:207], v[0:3]
	v_mfma_f32_16x16x32_bf16 v[44:47], v[216:219], v[174:177], v[44:47]
	v_mfma_f32_16x16x32_bf16 v[40:43], v[224:227], v[174:177], v[40:43]
	v_mfma_f32_16x16x32_bf16 v[28:31], v[216:219], v[192:195], v[28:31]
	v_mfma_f32_16x16x32_bf16 v[24:27], v[224:227], v[192:195], v[24:27]
	v_mfma_f32_16x16x32_bf16 v[12:15], v[216:219], v[200:203], v[12:15]
	v_mfma_f32_16x16x32_bf16 v[8:11], v[224:227], v[200:203], v[8:11]
	v_mfma_f32_16x16x32_bf16 v[4:7], v[216:219], v[208:211], v[4:7]
	v_mfma_f32_16x16x32_bf16 v[0:3], v[224:227], v[208:211], v[0:3]
	v_add_u32_e32 v153, s17, v151
	s_barrier
	ds_read_b128 v[154:157], v153
	ds_read_b128 v[158:161], v153 offset:1024
	ds_read_b128 v[162:165], v153 offset:2048
	ds_read_b128 v[166:169], v153 offset:3072
	s_mov_b32 m0, s48
	ds_read_b128 v[170:173], v152 offset:32768
	ds_read_b128 v[174:177], v152 offset:33792
	ds_read_b128 v[178:181], v152 offset:34816
	ds_read_b128 v[192:195], v152 offset:35840
	ds_read_b128 v[196:199], v152 offset:36864
	ds_read_b128 v[200:203], v152 offset:37888
	ds_read_b128 v[204:207], v152 offset:38912
	ds_read_b128 v[208:211], v152 offset:39936
	global_load_lds_dwordx4 v128, s[22:23]
	s_mov_b32 m0, s49
	s_nop 0
	global_load_lds_dwordx4 v148, s[22:23]
	s_waitcnt lgkmcnt(8)
	s_barrier
	s_waitcnt lgkmcnt(0)
	v_mfma_f32_16x16x32_bf16 v[124:127], v[154:157], v[170:173], v[124:127]
	v_mfma_f32_16x16x32_bf16 v[120:123], v[162:165], v[170:173], v[120:123]
	v_mfma_f32_16x16x32_bf16 v[116:119], v[154:157], v[178:181], v[116:119]
	v_mfma_f32_16x16x32_bf16 v[112:115], v[162:165], v[178:181], v[112:115]
	v_mfma_f32_16x16x32_bf16 v[104:107], v[154:157], v[196:199], v[104:107]
	v_mfma_f32_16x16x32_bf16 v[96:99], v[162:165], v[196:199], v[96:99]
	v_mfma_f32_16x16x32_bf16 v[88:91], v[154:157], v[204:207], v[88:91]
	v_mfma_f32_16x16x32_bf16 v[80:83], v[162:165], v[204:207], v[80:83]
	v_mfma_f32_16x16x32_bf16 v[124:127], v[158:161], v[174:177], v[124:127]
	v_mfma_f32_16x16x32_bf16 v[120:123], v[166:169], v[174:177], v[120:123]
	v_mfma_f32_16x16x32_bf16 v[116:119], v[158:161], v[192:195], v[116:119]
	v_mfma_f32_16x16x32_bf16 v[112:115], v[166:169], v[192:195], v[112:115]
	v_mfma_f32_16x16x32_bf16 v[104:107], v[158:161], v[200:203], v[104:107]
	v_mfma_f32_16x16x32_bf16 v[96:99], v[166:169], v[200:203], v[96:99]
	v_mfma_f32_16x16x32_bf16 v[88:91], v[158:161], v[208:211], v[88:91]
	v_mfma_f32_16x16x32_bf16 v[80:83], v[166:169], v[208:211], v[80:83]
	s_barrier
	s_mov_b32 m0, s16
	v_add_u32_e32 v153, s15, v151
	v_lshl_add_u64 v[182:183], v[182:183], 0, s[18:19]
	ds_read_b128 v[212:215], v153
	ds_read_b128 v[216:219], v153 offset:1024
	ds_read_b128 v[220:223], v153 offset:2048
	ds_read_b128 v[224:227], v153 offset:3072
	global_load_lds_dwordx4 v244, s[30:31]
	v_lshl_add_u64 v[182:183], v[228:229], 0, s[18:19]
	s_mov_b32 m0, s14
	s_nop 0
	global_load_lds_dwordx4 v245, s[30:31]
	s_barrier
	s_waitcnt lgkmcnt(0)
	v_mfma_f32_16x16x32_bf16 v[108:111], v[212:215], v[170:173], v[108:111]
	v_mfma_f32_16x16x32_bf16 v[100:103], v[220:223], v[170:173], v[100:103]
	v_mfma_f32_16x16x32_bf16 v[92:95], v[212:215], v[178:181], v[92:95]
	v_mfma_f32_16x16x32_bf16 v[84:87], v[220:223], v[178:181], v[84:87]
	v_mfma_f32_16x16x32_bf16 v[76:79], v[212:215], v[196:199], v[76:79]
	v_mfma_f32_16x16x32_bf16 v[72:75], v[220:223], v[196:199], v[72:75]
	v_mfma_f32_16x16x32_bf16 v[68:71], v[212:215], v[204:207], v[68:71]
	v_mfma_f32_16x16x32_bf16 v[64:67], v[220:223], v[204:207], v[64:67]
	v_mfma_f32_16x16x32_bf16 v[108:111], v[216:219], v[174:177], v[108:111]
	v_mfma_f32_16x16x32_bf16 v[100:103], v[224:227], v[174:177], v[100:103]
	v_mfma_f32_16x16x32_bf16 v[92:95], v[216:219], v[192:195], v[92:95]
	v_mfma_f32_16x16x32_bf16 v[84:87], v[224:227], v[192:195], v[84:87]
	v_mfma_f32_16x16x32_bf16 v[76:79], v[216:219], v[200:203], v[76:79]
	v_mfma_f32_16x16x32_bf16 v[72:75], v[224:227], v[200:203], v[72:75]
	v_mfma_f32_16x16x32_bf16 v[68:71], v[216:219], v[208:211], v[68:71]
	v_mfma_f32_16x16x32_bf16 v[64:67], v[224:227], v[208:211], v[64:67]
	s_mov_b32 m0, s57
	v_lshl_add_u64 v[182:183], v[230:231], 0, s[18:19]
	s_barrier
	ds_read_b128 v[170:173], v152 offset:49152
	ds_read_b128 v[174:177], v152 offset:50176
	ds_read_b128 v[178:181], v152 offset:51200
	ds_read_b128 v[192:195], v152 offset:52224
	ds_read_b128 v[196:199], v152 offset:53248
	ds_read_b128 v[200:203], v152 offset:54272
	ds_read_b128 v[204:207], v152 offset:55296
	ds_read_b128 v[208:211], v152 offset:56320
	global_load_lds_dwordx4 v244, s[26:27]
	v_lshl_add_u64 v[182:183], v[232:233], 0, s[18:19]
	s_mov_b32 m0, s58
	s_nop 0
	global_load_lds_dwordx4 v245, s[26:27]
	s_barrier
; #define PG8_STAGE(bufoff, gbase, voff) do { _Pragma("unroll") for (int _i = 0; _i < 2; ++_i) \
;         __builtin_amdgcn_global_load_lds((const unsigned*)((const char*)(gbase) + (voff)[_i]), (PG8_LAS unsigned*)(lds + (bufoff) + ldsw + _i * 8192), 16, 0, 0); } while (0)
; #define PG8_MMA(ai, bj, At, Bt) do { __builtin_amdgcn_s_setprio(1); _Pragma("unroll") for (int m = 0; m < 4; ++m) _Pragma("unroll") for (int n = 0; n < 2; ++n) _Pragma("unroll") for (int k = 0; k < 2; ++k) \
;         acc[ai][bj][m][n] = __builtin_amdgcn_mfma_f32_16x16x32_bf16(Bt[n][k], At[m][k], acc[ai][bj][m][n], 0, 0, 0); __builtin_amdgcn_s_setprio(0); } while (0)
; #define PG8_WAIT_V(n) asm volatile("s_waitcnt vmcnt(" #n ")" ::: "memory")
; #define PG8_WAIT_L(n) asm volatile("s_waitcnt lgkmcnt(" #n ")" ::: "memory")
; #define PG8_BAR __builtin_amdgcn_s_barrier()
; #define PG8_SCHED __builtin_amdgcn_sched_barrier(0)
; template <class Epi, class Sched, bool STAMP = false>
; __device__ __forceinline__ void gemm_phase(PG8_LAS unsigned char* lds, const Gemm g, const Sched& S, const Epi& E, unsigned long long* stamps) {
;     ...
;             PG8_BAR; PG8_WAIT_L(0); PG8_MMA(1, 0, At, B0); PG8_BAR; PG8_SCHED;
;             PG8_STAGE(PG8_SB(1, 1), b3 + hstep, voffB);
;             PG8_WAIT_V(6); PG8_BAR; PG8_MMA(1, 1, At, B1); PG8_BAR;
;     __device__ __forceinline__ void operator()(const f32x4 (&acc)[2][2][4][2], const pg8::Unit& u, int wr, int wc, int fr, int fq) const {
;         const int row0 = (u.pm - 64) * 256 + wr * 64 + fr, col0 = u.pn * 256 + wc * 32 + 4 * fq;
; #pragma unroll
;         for (int ai = 0; ai < 2; ++ai)
; #pragma unroll
;             for (int m = 0; m < 4; ++m) { float* xp = PART + (size_t)(row0 + ai * 128 + m * 16) * ldp + col0;
; #pragma unroll
;                 for (int bj = 0; bj < 2; ++bj)
; #pragma unroll
;                     for (int n = 0; n < 2; ++n) *(f32x4*)(xp + bj * 128 + n * 16) = acc[ai][bj][m][n]; }
;     }
	s_waitcnt lgkmcnt(0)
	v_mfma_f32_16x16x32_bf16 v[60:63], v[154:157], v[170:173], v[60:63]
	v_mfma_f32_16x16x32_bf16 v[56:59], v[162:165], v[170:173], v[56:59]
	v_mfma_f32_16x16x32_bf16 v[52:55], v[154:157], v[178:181], v[52:55]
	v_mfma_f32_16x16x32_bf16 v[48:51], v[162:165], v[178:181], v[48:51]
	v_mfma_f32_16x16x32_bf16 v[36:39], v[154:157], v[196:199], v[36:39]
	v_mfma_f32_16x16x32_bf16 v[32:35], v[162:165], v[196:199], v[32:35]
	v_mfma_f32_16x16x32_bf16 v[20:23], v[154:157], v[204:207], v[20:23]
	v_mfma_f32_16x16x32_bf16 v[16:19], v[162:165], v[204:207], v[16:19]
	v_mfma_f32_16x16x32_bf16 v[60:63], v[158:161], v[174:177], v[60:63]
	v_mfma_f32_16x16x32_bf16 v[56:59], v[166:169], v[174:177], v[56:59]
	v_mfma_f32_16x16x32_bf16 v[52:55], v[158:161], v[192:195], v[52:55]
	v_mfma_f32_16x16x32_bf16 v[48:51], v[166:169], v[192:195], v[48:51]
	v_mfma_f32_16x16x32_bf16 v[36:39], v[158:161], v[200:203], v[36:39]
	v_mfma_f32_16x16x32_bf16 v[32:35], v[166:169], v[200:203], v[32:35]
	v_mfma_f32_16x16x32_bf16 v[20:23], v[158:161], v[208:211], v[20:23]
	v_mfma_f32_16x16x32_bf16 v[16:19], v[166:169], v[208:211], v[16:19]
	s_barrier
	s_mov_b32 m0, s52
	s_nop 0
	global_load_lds_dwordx4 v128, s[20:21]
	s_mov_b32 m0, s39
	s_nop 0
	global_load_lds_dwordx4 v148, s[20:21]
	s_waitcnt vmcnt(6)
	s_barrier
	v_mfma_f32_16x16x32_bf16 v[44:47], v[212:215], v[170:173], v[44:47]
	v_mfma_f32_16x16x32_bf16 v[40:43], v[220:223], v[170:173], v[40:43]
	v_mfma_f32_16x16x32_bf16 v[28:31], v[212:215], v[178:181], v[28:31]
	v_mfma_f32_16x16x32_bf16 v[24:27], v[220:223], v[178:181], v[24:27]
	v_mfma_f32_16x16x32_bf16 v[12:15], v[212:215], v[196:199], v[12:15]
	v_mfma_f32_16x16x32_bf16 v[8:11], v[220:223], v[196:199], v[8:11]
	v_mfma_f32_16x16x32_bf16 v[4:7], v[212:215], v[204:207], v[4:7]
	v_mfma_f32_16x16x32_bf16 v[0:3], v[220:223], v[204:207], v[0:3]
	v_mfma_f32_16x16x32_bf16 v[44:47], v[216:219], v[174:177], v[44:47]
	v_mfma_f32_16x16x32_bf16 v[40:43], v[224:227], v[174:177], v[40:43]
	v_mfma_f32_16x16x32_bf16 v[28:31], v[216:219], v[192:195], v[28:31]
	v_mfma_f32_16x16x32_bf16 v[24:27], v[224:227], v[192:195], v[24:27]
	v_mfma_f32_16x16x32_bf16 v[12:15], v[216:219], v[200:203], v[12:15]
	v_mfma_f32_16x16x32_bf16 v[8:11], v[224:227], v[200:203], v[8:11]
	v_mfma_f32_16x16x32_bf16 v[4:7], v[216:219], v[208:211], v[4:7]
	v_mfma_f32_16x16x32_bf16 v[0:3], v[224:227], v[208:211], v[0:3]
	s_andn2_b64 vcc, exec, s[12:13]
	s_mov_b64 s[20:21], -1
	s_mov_b64 s[12:13], 0
	s_movk_i32 s14, 0x100
	s_barrier
	s_cbranch_vccz .LBB0_213
	s_lshl_b32 s0, s43, 22
	s_add_u32 s0, s10, s0
	s_addc_u32 s1, s46, 0
	s_add_u32 s0, s0, 0xbb00000
	s_addc_u32 s1, s1, 0
	s_lshl_b32 s4, s42, 8
	s_add_i32 s4, s4, s53
	v_add_u32_e32 v150, s4, v150
	v_add_u32_e32 v148, 0xffffc000, v150
	s_lshl_b32 s4, s41, 8
	v_lshl_or_b32 v128, v139, 2, s4
	v_ashrrev_i32_e32 v149, 31, v148
	v_or_b32_e32 v128, s56, v128
	v_lshlrev_b64 v[148:149], 12, v[148:149]
	v_lshl_add_u64 v[148:149], s[0:1], 0, v[148:149]
	v_lshlrev_b32_e32 v128, 2, v128
	v_lshl_add_u64 v[148:149], v[148:149], 0, v[128:129]
	global_store_dwordx4 v[148:149], v[124:127], off
	global_store_dwordx4 v[148:149], v[120:123], off offset:64
	global_store_dwordx4 v[148:149], v[108:111], off offset:512
	global_store_dwordx4 v[148:149], v[100:103], off offset:576
	s_cmpk_lt_u32 s40, 0x100
	s_movk_i32 s58, 0xff60
	v_add_u32_e32 v100, 0xffffc010, v150
	v_ashrrev_i32_e32 v101, 31, v100
	v_lshlrev_b64 v[100:101], 12, v[100:101]
	v_lshl_add_u64 v[100:101], s[0:1], 0, v[100:101]
	v_lshl_add_u64 v[100:101], v[100:101], 0, v[128:129]
	global_store_dwordx4 v[100:101], v[116:119], off
	global_store_dwordx4 v[100:101], v[112:115], off offset:64
	global_store_dwordx4 v[100:101], v[92:95], off offset:512
	global_store_dwordx4 v[100:101], v[84:87], off offset:576
	s_nop 1
	v_add_u32_e32 v84, 0xffffc020, v150
	v_ashrrev_i32_e32 v85, 31, v84
	v_lshlrev_b64 v[84:85], 12, v[84:85]
	v_lshl_add_u64 v[84:85], s[0:1], 0, v[84:85]
	v_lshl_add_u64 v[84:85], v[84:85], 0, v[128:129]
	global_store_dwordx4 v[84:85], v[104:107], off
	global_store_dwordx4 v[84:85], v[96:99], off offset:64
	global_store_dwordx4 v[84:85], v[76:79], off offset:512
	global_store_dwordx4 v[84:85], v[72:75], off offset:576
	s_nop 1
	v_add_u32_e32 v72, 0xffffc030, v150
	v_ashrrev_i32_e32 v73, 31, v72
	v_lshlrev_b64 v[72:73], 12, v[72:73]
	v_lshl_add_u64 v[72:73], s[0:1], 0, v[72:73]
	v_lshl_add_u64 v[72:73], v[72:73], 0, v[128:129]
	s_mov_b64 s[0:1], 0x80000
	global_store_dwordx4 v[72:73], v[88:91], off
	global_store_dwordx4 v[72:73], v[80:83], off offset:64
	global_store_dwordx4 v[72:73], v[68:71], off offset:512
	global_store_dwordx4 v[72:73], v[64:67], off offset:576
	s_nop 1
	v_lshl_add_u64 v[64:65], v[148:149], 0, s[0:1]
	s_mov_b32 s0, 0x80000
	v_add_co_u32_e32 v66, vcc, s0, v148
	s_mov_b64 s[0:1], 0x90000
	s_nop 0
	v_addc_co_u32_e32 v67, vcc, 0, v149, vcc
	global_store_dwordx4 v[66:67], v[60:63], off
	global_store_dwordx4 v[64:65], v[56:59], off offset:64
	global_store_dwordx4 v[64:65], v[44:47], off offset:512
	global_store_dwordx4 v[64:65], v[40:43], off offset:576
	s_nop 1
	v_lshl_add_u64 v[40:41], v[148:149], 0, s[0:1]
	s_mov_b32 s0, 0x90000
	v_add_co_u32_e32 v42, vcc, s0, v148
	s_mov_b64 s[0:1], 0xa0000
	s_nop 0
	v_addc_co_u32_e32 v43, vcc, 0, v149, vcc
	global_store_dwordx4 v[42:43], v[52:55], off
	global_store_dwordx4 v[40:41], v[48:51], off offset:64
	global_store_dwordx4 v[40:41], v[28:31], off offset:512
	global_store_dwordx4 v[40:41], v[24:27], off offset:576
	s_nop 1
	v_lshl_add_u64 v[24:25], v[148:149], 0, s[0:1]
	s_mov_b32 s0, 0xa0000
	v_add_co_u32_e32 v26, vcc, s0, v148
	s_mov_b64 s[0:1], 0xb0000
	s_nop 0
	v_addc_co_u32_e32 v27, vcc, 0, v149, vcc
	global_store_dwordx4 v[26:27], v[36:39], off
	global_store_dwordx4 v[24:25], v[32:35], off offset:64
	global_store_dwordx4 v[24:25], v[12:15], off offset:512
	global_store_dwordx4 v[24:25], v[8:11], off offset:576
	s_nop 1
	v_add_co_u32_e32 v10, vcc, 0xb0000, v148
	v_lshl_add_u64 v[8:9], v[148:149], 0, s[0:1]
	s_nop 0
	v_addc_co_u32_e32 v11, vcc, 0, v149, vcc
	global_store_dwordx4 v[10:11], v[20:23], off
	global_store_dwordx4 v[8:9], v[16:19], off offset:64
	global_store_dwordx4 v[8:9], v[4:7], off offset:512
	global_store_dwordx4 v[8:9], v[0:3], off offset:576
	s_waitcnt vmcnt(0)
	s_cbranch_scc0 .LBB0_216
	s_barrier

; #define PG8_STAGE(bufoff, gbase, voff) do { _Pragma("unroll") for (int _i = 0; _i < 2; ++_i) \
;         __builtin_amdgcn_global_load_lds((const unsigned*)((const char*)(gbase) + (voff)[_i]), (PG8_LAS unsigned*)(lds + (bufoff) + ldsw + _i * 8192), 16, 0, 0); } while (0)
; #define PG8_LDA(dst, b, h) do { _Pragma("unroll") for (int m = 0; m < 4; ++m) _Pragma("unroll") for (int k = 0; k < 2; ++k) dst[m][k] = *(const PG8_LAS bf16x8*)(lds + PG8_SA(b, h) + aoff + m * 2048 + k * 1024); } while (0)
; #define PG8_LDB(dst, b, h) do { _Pragma("unroll") for (int n = 0; n < 2; ++n) _Pragma("unroll") for (int k = 0; k < 2; ++k) dst[n][k] = *(const PG8_LAS bf16x8*)(lds + PG8_SB(b, h) + boff + n * 2048 + k * 1024); } while (0)
; #define PG8_MMA(ai, bj, At, Bt) do { __builtin_amdgcn_s_setprio(1); _Pragma("unroll") for (int m = 0; m < 4; ++m) _Pragma("unroll") for (int n = 0; n < 2; ++n) _Pragma("unroll") for (int k = 0; k < 2; ++k) \
;         acc[ai][bj][m][n] = __builtin_amdgcn_mfma_f32_16x16x32_bf16(Bt[n][k], At[m][k], acc[ai][bj][m][n], 0, 0, 0); __builtin_amdgcn_s_setprio(0); } while (0)
; #define PG8_WAIT_L(n) asm volatile("s_waitcnt lgkmcnt(" #n ")" ::: "memory")
; #define PG8_BAR __builtin_amdgcn_s_barrier()
; #define PG8_SCHED __builtin_amdgcn_sched_barrier(0)
; template <class Epi, class Sched, bool STAMP = false>
; __device__ __forceinline__ void gemm_phase(PG8_LAS unsigned char* lds, const Gemm g, const Sched& S, const Epi& E, unsigned long long* stamps) {
;     ...
;             PG8_LDB(B0, 0, 0); PG8_SCHED; PG8_LDA(At, 0, 0); PG8_STAGE(PG8_SA(1, 1), a1 + hstep, voffA);
;             PG8_WAIT_L(8); PG8_BAR; PG8_WAIT_L(0); PG8_MMA(0, 0, At, B0); PG8_BAR; PG8_SCHED;
;     ...
; #pragma unroll
;         for (int a = 0; a < 2; ++a)
; #pragma unroll
;             for (int b = 0; b < 2; ++b)
; #pragma unroll
;                 for (int m = 0; m < 4; ++m)
; #pragma unroll
;                     for (int n = 0; n < 2; ++n) acc[a][b][m][n] = (f32x4){0.f, 0.f, 0.f, 0.f};
;         cur = nxt; cA = nA; cB = nB; ++ui;
.LBB0_292:
	s_ashr_i32 s7, s6, 31
	v_cmp_lt_i64_e32 vcc, s[12:13], v[136:137]
	s_lshl_b64 s[12:13], s[6:7], 18
	s_add_u32 s12, s20, s12
	s_addc_u32 s13, s21, s13
	s_and_b64 s[14:15], vcc, exec
	s_cselect_b32 s7, s13, s25
	s_cselect_b32 s53, s12, s24
	s_ashr_i32 s5, s4, 31
	s_lshl_b64 s[14:15], s[4:5], 18
	s_add_u32 s22, s44, s14
	s_addc_u32 s23, s45, s15
	s_and_b64 s[14:15], vcc, exec
	s_cselect_b32 s5, s23, s27
	s_cselect_b32 s56, s22, s26
	s_add_u32 s24, s24, 0x20080
	s_addc_u32 s25, s25, 0
	s_add_u32 s57, s26, 0x100
	v_mov_b32_e32 v0, 0
	s_addc_u32 s58, s27, 0
	s_mov_b32 s59, -2
	v_mov_b32_e32 v1, v0
	v_mov_b32_e32 v2, v0
	v_mov_b32_e32 v3, v0
	v_mov_b32_e32 v4, v0
	v_mov_b32_e32 v5, v0
	v_mov_b32_e32 v6, v0
	v_mov_b32_e32 v7, v0
	v_mov_b32_e32 v8, v0
	v_mov_b32_e32 v9, v0
	v_mov_b32_e32 v10, v0
	v_mov_b32_e32 v11, v0
	v_mov_b32_e32 v12, v0
	v_mov_b32_e32 v13, v0
	v_mov_b32_e32 v14, v0
	v_mov_b32_e32 v15, v0
	v_mov_b32_e32 v24, v0
	v_mov_b32_e32 v25, v0
	v_mov_b32_e32 v26, v0
	v_mov_b32_e32 v27, v0
	v_mov_b32_e32 v28, v0
	v_mov_b32_e32 v29, v0
	v_mov_b32_e32 v30, v0
	v_mov_b32_e32 v31, v0
	v_mov_b32_e32 v40, v0
	v_mov_b32_e32 v41, v0
	v_mov_b32_e32 v42, v0
	v_mov_b32_e32 v43, v0
	v_mov_b32_e32 v44, v0
	v_mov_b32_e32 v45, v0
	v_mov_b32_e32 v46, v0
	v_mov_b32_e32 v47, v0
	v_mov_b32_e32 v16, v0
	v_mov_b32_e32 v17, v0
	v_mov_b32_e32 v18, v0
	v_mov_b32_e32 v19, v0
	v_mov_b32_e32 v20, v0
	v_mov_b32_e32 v21, v0
	v_mov_b32_e32 v22, v0
	v_mov_b32_e32 v23, v0
	v_mov_b32_e32 v32, v0
	v_mov_b32_e32 v33, v0
	v_mov_b32_e32 v34, v0
	v_mov_b32_e32 v35, v0
	v_mov_b32_e32 v36, v0
	v_mov_b32_e32 v37, v0
	v_mov_b32_e32 v38, v0
	v_mov_b32_e32 v39, v0
	v_mov_b32_e32 v48, v0
	v_mov_b32_e32 v49, v0
	v_mov_b32_e32 v50, v0
	v_mov_b32_e32 v51, v0
	v_mov_b32_e32 v52, v0
	v_mov_b32_e32 v53, v0
	v_mov_b32_e32 v54, v0
	v_mov_b32_e32 v55, v0
	v_mov_b32_e32 v56, v0
	v_mov_b32_e32 v57, v0
	v_mov_b32_e32 v58, v0
	v_mov_b32_e32 v59, v0
	v_mov_b32_e32 v60, v0
	v_mov_b32_e32 v61, v0
	v_mov_b32_e32 v62, v0
	v_mov_b32_e32 v63, v0
	v_mov_b32_e32 v64, v0
	v_mov_b32_e32 v65, v0
	v_mov_b32_e32 v66, v0
	v_mov_b32_e32 v67, v0
	v_mov_b32_e32 v68, v0
	v_mov_b32_e32 v69, v0
	v_mov_b32_e32 v70, v0
	v_mov_b32_e32 v71, v0
	v_mov_b32_e32 v72, v0
	v_mov_b32_e32 v73, v0
	v_mov_b32_e32 v74, v0
	v_mov_b32_e32 v75, v0
	v_mov_b32_e32 v76, v0
	v_mov_b32_e32 v77, v0
	v_mov_b32_e32 v78, v0
	v_mov_b32_e32 v79, v0
	v_mov_b32_e32 v88, v0
	v_mov_b32_e32 v89, v0
	v_mov_b32_e32 v90, v0
	v_mov_b32_e32 v91, v0
	v_mov_b32_e32 v92, v0
	v_mov_b32_e32 v93, v0
	v_mov_b32_e32 v94, v0
	v_mov_b32_e32 v95, v0
	v_mov_b32_e32 v104, v0
	v_mov_b32_e32 v105, v0
	v_mov_b32_e32 v106, v0
	v_mov_b32_e32 v107, v0
	v_mov_b32_e32 v108, v0
	v_mov_b32_e32 v109, v0
	v_mov_b32_e32 v110, v0
	v_mov_b32_e32 v111, v0
	v_mov_b32_e32 v80, v0
	v_mov_b32_e32 v81, v0
	v_mov_b32_e32 v82, v0
	v_mov_b32_e32 v83, v0
	v_mov_b32_e32 v84, v0
	v_mov_b32_e32 v85, v0
	v_mov_b32_e32 v86, v0
	v_mov_b32_e32 v87, v0
	v_mov_b32_e32 v96, v0
	v_mov_b32_e32 v97, v0
	v_mov_b32_e32 v98, v0
	v_mov_b32_e32 v99, v0
	v_mov_b32_e32 v100, v0
	v_mov_b32_e32 v101, v0
	v_mov_b32_e32 v102, v0
	v_mov_b32_e32 v103, v0
	v_mov_b32_e32 v112, v0
	v_mov_b32_e32 v113, v0
	v_mov_b32_e32 v114, v0
	v_mov_b32_e32 v115, v0
	v_mov_b32_e32 v116, v0
	v_mov_b32_e32 v117, v0
	v_mov_b32_e32 v118, v0
	v_mov_b32_e32 v119, v0
	v_mov_b32_e32 v120, v0
	v_mov_b32_e32 v121, v0
	v_mov_b32_e32 v122, v0
	v_mov_b32_e32 v123, v0
	v_mov_b32_e32 v124, v0
	v_mov_b32_e32 v125, v0
	v_mov_b32_e32 v126, v0
	v_mov_b32_e32 v127, v0
	v_add_u32_e32 v244, 0x80, v128
	v_add_u32_e32 v245, 0x80, v152
	v_add_u32_e32 v246, 0x80, v148
	v_add_u32_e32 v247, 0x80, v150
.LBB0_293:
	s_add_u32 s14, s24, 0xfffe0080
	s_addc_u32 s15, s25, -1
	s_add_i32 s16, 0, 0x10000
	v_add_u32_e32 v161, s16, v158
	ds_read_b128 v[162:165], v161
	ds_read_b128 v[166:169], v161 offset:1024
	ds_read_b128 v[170:173], v161 offset:2048
	ds_read_b128 v[174:177], v161 offset:3072
	s_cmp_eq_u32 s59, 4
	s_cselect_b32 s31, s7, s15
	s_cselect_b32 s30, s53, s14
	s_cselect_b32 s27, s5, s58
	s_cselect_b32 s26, s56, s57
	s_add_i32 m0, s3, 0xc000
	ds_read_b128 v[178:181], v160
	ds_read_b128 v[192:195], v160 offset:1024
	ds_read_b128 v[196:199], v160 offset:2048
	ds_read_b128 v[200:203], v160 offset:3072
	ds_read_b128 v[204:207], v160 offset:4096
	ds_read_b128 v[208:211], v160 offset:5120
	ds_read_b128 v[212:215], v160 offset:6144
	ds_read_b128 v[216:219], v160 offset:7168
	global_load_lds_dwordx4 v154, s[24:25]
	s_add_i32 m0, s3, 0xe000
	s_nop 0
	global_load_lds_dwordx4 v156, s[24:25]
	s_waitcnt lgkmcnt(8)
	s_barrier
	s_waitcnt lgkmcnt(0)
	v_mfma_f32_16x16x32_bf16 v[124:127], v[162:165], v[178:181], v[124:127]
	v_mfma_f32_16x16x32_bf16 v[120:123], v[170:173], v[178:181], v[120:123]
	v_mfma_f32_16x16x32_bf16 v[116:119], v[162:165], v[196:199], v[116:119]
	v_mfma_f32_16x16x32_bf16 v[112:115], v[170:173], v[196:199], v[112:115]
	v_mfma_f32_16x16x32_bf16 v[100:103], v[162:165], v[204:207], v[100:103]
	v_mfma_f32_16x16x32_bf16 v[96:99], v[170:173], v[204:207], v[96:99]
	v_mfma_f32_16x16x32_bf16 v[84:87], v[162:165], v[212:215], v[84:87]
	v_mfma_f32_16x16x32_bf16 v[80:83], v[170:173], v[212:215], v[80:83]
	v_mfma_f32_16x16x32_bf16 v[124:127], v[166:169], v[192:195], v[124:127]
	v_mfma_f32_16x16x32_bf16 v[120:123], v[174:177], v[192:195], v[120:123]
	v_mfma_f32_16x16x32_bf16 v[116:119], v[166:169], v[200:203], v[116:119]
	v_mfma_f32_16x16x32_bf16 v[112:115], v[174:177], v[200:203], v[112:115]
	v_mfma_f32_16x16x32_bf16 v[100:103], v[166:169], v[208:211], v[100:103]
	v_mfma_f32_16x16x32_bf16 v[96:99], v[174:177], v[208:211], v[96:99]
	v_mfma_f32_16x16x32_bf16 v[84:87], v[166:169], v[216:219], v[84:87]
	v_mfma_f32_16x16x32_bf16 v[80:83], v[174:177], v[216:219], v[80:83]
	s_barrier
; #define PG8_STAGE(bufoff, gbase, voff) do { _Pragma("unroll") for (int _i = 0; _i < 2; ++_i) \
;         __builtin_amdgcn_global_load_lds((const unsigned*)((const char*)(gbase) + (voff)[_i]), (PG8_LAS unsigned*)(lds + (bufoff) + ldsw + _i * 8192), 16, 0, 0); } while (0)
; #define PG8_LDA(dst, b, h) do { _Pragma("unroll") for (int m = 0; m < 4; ++m) _Pragma("unroll") for (int k = 0; k < 2; ++k) dst[m][k] = *(const PG8_LAS bf16x8*)(lds + PG8_SA(b, h) + aoff + m * 2048 + k * 1024); } while (0)
; #define PG8_LDB(dst, b, h) do { _Pragma("unroll") for (int n = 0; n < 2; ++n) _Pragma("unroll") for (int k = 0; k < 2; ++k) dst[n][k] = *(const PG8_LAS bf16x8*)(lds + PG8_SB(b, h) + boff + n * 2048 + k * 1024); } while (0)
; #define PG8_MMA(ai, bj, At, Bt) do { __builtin_amdgcn_s_setprio(1); _Pragma("unroll") for (int m = 0; m < 4; ++m) _Pragma("unroll") for (int n = 0; n < 2; ++n) _Pragma("unroll") for (int k = 0; k < 2; ++k) \
;         acc[ai][bj][m][n] = __builtin_amdgcn_mfma_f32_16x16x32_bf16(Bt[n][k], At[m][k], acc[ai][bj][m][n], 0, 0, 0); __builtin_amdgcn_s_setprio(0); } while (0)
; #define PG8_WAIT_V(n) asm volatile("s_waitcnt vmcnt(" #n ")" ::: "memory")
; #define PG8_WAIT_L(n) asm volatile("s_waitcnt lgkmcnt(" #n ")" ::: "memory")
; #define PG8_BAR __builtin_amdgcn_s_barrier()
; #define PG8_SCHED __builtin_amdgcn_sched_barrier(0)
; template <class Epi, class Sched, bool STAMP = false>
; __device__ __forceinline__ void gemm_phase(PG8_LAS unsigned char* lds, const Gemm g, const Sched& S, const Epi& E, unsigned long long* stamps) {
;     ...
;             PG8_LDB(B1, 0, 1); PG8_STAGE(PG8_SB(0, 0), b2, voffB);
;             PG8_BAR; PG8_WAIT_L(0); PG8_MMA(0, 1, At, B1); PG8_BAR;
;             PG8_LDA(At, 0, 1); PG8_STAGE(PG8_SA(0, 0), a2, voffA);
;             PG8_BAR; PG8_WAIT_L(0); PG8_MMA(1, 0, At, B0); PG8_BAR; PG8_SCHED;
;             PG8_STAGE(PG8_SB(0, 1), b2 + hstep, voffB);
;             PG8_WAIT_V(6); PG8_BAR; PG8_MMA(1, 1, At, B1); PG8_BAR;
;             PG8_LDB(B0, 1, 0); PG8_SCHED; PG8_LDA(At, 1, 0); PG8_STAGE(PG8_SA(0, 1), a2 + hstep, voffA);
;             PG8_WAIT_L(8); PG8_BAR; PG8_WAIT_L(0); PG8_MMA(0, 0, At, B0); PG8_BAR; PG8_SCHED;
	s_add_i32 s17, 0, 0x14000
	s_add_i32 s14, s16, s40
	v_add_u32_e32 v161, s17, v158
	s_mov_b32 m0, s14
	ds_read_b128 v[220:223], v161
	ds_read_b128 v[224:227], v161 offset:1024
	ds_read_b128 v[228:231], v161 offset:2048
	ds_read_b128 v[232:235], v161 offset:3072
	global_load_lds_dwordx4 v128, s[26:27]
	s_add_i32 m0, s14, 0x2000
	s_nop 0
	global_load_lds_dwordx4 v152, s[26:27]
	s_barrier
	s_waitcnt lgkmcnt(0)
	v_mfma_f32_16x16x32_bf16 v[108:111], v[220:223], v[178:181], v[108:111]
	v_mfma_f32_16x16x32_bf16 v[104:107], v[228:231], v[178:181], v[104:107]
	v_mfma_f32_16x16x32_bf16 v[92:95], v[220:223], v[196:199], v[92:95]
	v_mfma_f32_16x16x32_bf16 v[88:91], v[228:231], v[196:199], v[88:91]
	v_mfma_f32_16x16x32_bf16 v[76:79], v[220:223], v[204:207], v[76:79]
	v_mfma_f32_16x16x32_bf16 v[72:75], v[228:231], v[204:207], v[72:75]
	v_mfma_f32_16x16x32_bf16 v[68:71], v[220:223], v[212:215], v[68:71]
	v_mfma_f32_16x16x32_bf16 v[64:67], v[228:231], v[212:215], v[64:67]
	v_mfma_f32_16x16x32_bf16 v[108:111], v[224:227], v[192:195], v[108:111]
	v_mfma_f32_16x16x32_bf16 v[104:107], v[232:235], v[192:195], v[104:107]
	v_mfma_f32_16x16x32_bf16 v[92:95], v[224:227], v[200:203], v[92:95]
	v_mfma_f32_16x16x32_bf16 v[88:91], v[232:235], v[200:203], v[88:91]
	v_mfma_f32_16x16x32_bf16 v[76:79], v[224:227], v[208:211], v[76:79]
	v_mfma_f32_16x16x32_bf16 v[72:75], v[232:235], v[208:211], v[72:75]
	v_mfma_f32_16x16x32_bf16 v[68:71], v[224:227], v[216:219], v[68:71]
	v_mfma_f32_16x16x32_bf16 v[64:67], v[232:235], v[216:219], v[64:67]
	s_mov_b32 m0, s3
	s_barrier
	ds_read_b128 v[178:181], v160 offset:16384
	ds_read_b128 v[192:195], v160 offset:17408
	ds_read_b128 v[196:199], v160 offset:18432
	ds_read_b128 v[200:203], v160 offset:19456
	ds_read_b128 v[204:207], v160 offset:20480
	ds_read_b128 v[208:211], v160 offset:21504
	ds_read_b128 v[212:215], v160 offset:22528
	ds_read_b128 v[216:219], v160 offset:23552
	global_load_lds_dwordx4 v148, s[30:31]
	s_mov_b32 m0, s41
	s_nop 0
	global_load_lds_dwordx4 v150, s[30:31]
	s_barrier
	s_waitcnt lgkmcnt(0)
	v_mfma_f32_16x16x32_bf16 v[60:63], v[162:165], v[178:181], v[60:63]
	v_mfma_f32_16x16x32_bf16 v[56:59], v[170:173], v[178:181], v[56:59]
	v_mfma_f32_16x16x32_bf16 v[52:55], v[162:165], v[196:199], v[52:55]
	v_mfma_f32_16x16x32_bf16 v[48:51], v[170:173], v[196:199], v[48:51]
	v_mfma_f32_16x16x32_bf16 v[36:39], v[162:165], v[204:207], v[36:39]
	v_mfma_f32_16x16x32_bf16 v[32:35], v[170:173], v[204:207], v[32:35]
	v_mfma_f32_16x16x32_bf16 v[20:23], v[162:165], v[212:215], v[20:23]
	v_mfma_f32_16x16x32_bf16 v[16:19], v[170:173], v[212:215], v[16:19]
	v_mfma_f32_16x16x32_bf16 v[60:63], v[166:169], v[192:195], v[60:63]
	v_mfma_f32_16x16x32_bf16 v[56:59], v[174:177], v[192:195], v[56:59]
	v_mfma_f32_16x16x32_bf16 v[52:55], v[166:169], v[200:203], v[52:55]
	v_mfma_f32_16x16x32_bf16 v[48:51], v[174:177], v[200:203], v[48:51]
	v_mfma_f32_16x16x32_bf16 v[36:39], v[166:169], v[208:211], v[36:39]
	v_mfma_f32_16x16x32_bf16 v[32:35], v[174:177], v[208:211], v[32:35]
	v_mfma_f32_16x16x32_bf16 v[20:23], v[166:169], v[216:219], v[20:23]
	v_mfma_f32_16x16x32_bf16 v[16:19], v[174:177], v[216:219], v[16:19]
	s_barrier
	s_add_u32 s14, s26, 0x20000
	s_addc_u32 s15, s27, 0
	s_add_i32 s16, s17, s40
	s_mov_b32 m0, s16
	s_nop 0
	global_load_lds_dwordx4 v128, s[14:15]
	s_add_i32 m0, s16, 0x2000
	s_nop 0
	global_load_lds_dwordx4 v152, s[14:15]
	s_waitcnt vmcnt(6)
	s_barrier
	v_mfma_f32_16x16x32_bf16 v[44:47], v[220:223], v[178:181], v[44:47]
	v_mfma_f32_16x16x32_bf16 v[40:43], v[228:231], v[178:181], v[40:43]
	v_mfma_f32_16x16x32_bf16 v[28:31], v[220:223], v[196:199], v[28:31]
	v_mfma_f32_16x16x32_bf16 v[24:27], v[228:231], v[196:199], v[24:27]
	v_mfma_f32_16x16x32_bf16 v[12:15], v[220:223], v[204:207], v[12:15]
	v_mfma_f32_16x16x32_bf16 v[8:11], v[228:231], v[204:207], v[8:11]
	v_mfma_f32_16x16x32_bf16 v[4:7], v[220:223], v[212:215], v[4:7]
	v_mfma_f32_16x16x32_bf16 v[0:3], v[228:231], v[212:215], v[0:3]
	v_mfma_f32_16x16x32_bf16 v[44:47], v[224:227], v[192:195], v[44:47]
	v_mfma_f32_16x16x32_bf16 v[40:43], v[232:235], v[192:195], v[40:43]
	v_mfma_f32_16x16x32_bf16 v[28:31], v[224:227], v[200:203], v[28:31]
	v_mfma_f32_16x16x32_bf16 v[24:27], v[232:235], v[200:203], v[24:27]
	v_mfma_f32_16x16x32_bf16 v[12:15], v[224:227], v[208:211], v[12:15]
	v_mfma_f32_16x16x32_bf16 v[8:11], v[232:235], v[208:211], v[8:11]
	v_mfma_f32_16x16x32_bf16 v[4:7], v[224:227], v[216:219], v[4:7]
	v_mfma_f32_16x16x32_bf16 v[0:3], v[232:235], v[216:219], v[0:3]
	s_add_i32 s16, 0, 0x18000
	v_add_u32_e32 v161, s16, v158
	s_barrier
	ds_read_b128 v[162:165], v161
	ds_read_b128 v[166:169], v161 offset:1024
	ds_read_b128 v[170:173], v161 offset:2048
	ds_read_b128 v[174:177], v161 offset:3072
	s_add_u32 s14, s30, 0x20000
	s_addc_u32 s15, s31, 0
	s_mov_b32 m0, s42
	ds_read_b128 v[178:181], v160 offset:32768
	ds_read_b128 v[192:195], v160 offset:33792
	ds_read_b128 v[196:199], v160 offset:34816
	ds_read_b128 v[200:203], v160 offset:35840
	ds_read_b128 v[204:207], v160 offset:36864
	ds_read_b128 v[208:211], v160 offset:37888
	ds_read_b128 v[212:215], v160 offset:38912
	ds_read_b128 v[216:219], v160 offset:39936
	global_load_lds_dwordx4 v148, s[14:15]
	s_mov_b32 m0, s43
	s_nop 0
	global_load_lds_dwordx4 v150, s[14:15]
	s_waitcnt lgkmcnt(8)
	s_barrier
; #define PG8_STAGE(bufoff, gbase, voff) do { _Pragma("unroll") for (int _i = 0; _i < 2; ++_i) \
;         __builtin_amdgcn_global_load_lds((const unsigned*)((const char*)(gbase) + (voff)[_i]), (PG8_LAS unsigned*)(lds + (bufoff) + ldsw + _i * 8192), 16, 0, 0); } while (0)
; #define PG8_LDA(dst, b, h) do { _Pragma("unroll") for (int m = 0; m < 4; ++m) _Pragma("unroll") for (int k = 0; k < 2; ++k) dst[m][k] = *(const PG8_LAS bf16x8*)(lds + PG8_SA(b, h) + aoff + m * 2048 + k * 1024); } while (0)
; #define PG8_LDB(dst, b, h) do { _Pragma("unroll") for (int n = 0; n < 2; ++n) _Pragma("unroll") for (int k = 0; k < 2; ++k) dst[n][k] = *(const PG8_LAS bf16x8*)(lds + PG8_SB(b, h) + boff + n * 2048 + k * 1024); } while (0)
; #define PG8_MMA(ai, bj, At, Bt) do { __builtin_amdgcn_s_setprio(1); _Pragma("unroll") for (int m = 0; m < 4; ++m) _Pragma("unroll") for (int n = 0; n < 2; ++n) _Pragma("unroll") for (int k = 0; k < 2; ++k) \
;         acc[ai][bj][m][n] = __builtin_amdgcn_mfma_f32_16x16x32_bf16(Bt[n][k], At[m][k], acc[ai][bj][m][n], 0, 0, 0); __builtin_amdgcn_s_setprio(0); } while (0)
; #define PG8_WAIT_V(n) asm volatile("s_waitcnt vmcnt(" #n ")" ::: "memory")
; #define PG8_WAIT_L(n) asm volatile("s_waitcnt lgkmcnt(" #n ")" ::: "memory")
; #define PG8_BAR __builtin_amdgcn_s_barrier()
; #define PG8_SCHED __builtin_amdgcn_sched_barrier(0)
; template <class Epi, class Sched, bool STAMP = false>
; __device__ __forceinline__ void gemm_phase(PG8_LAS unsigned char* lds, const Gemm g, const Sched& S, const Epi& E, unsigned long long* stamps) {
;     ...
;             PG8_WAIT_L(8); PG8_BAR; PG8_WAIT_L(0); PG8_MMA(0, 0, At, B0); PG8_BAR; PG8_SCHED;
;             PG8_LDB(B1, 1, 1); PG8_STAGE(PG8_SB(1, 0), b3, voffB);
;             PG8_BAR; PG8_WAIT_L(0); PG8_MMA(0, 1, At, B1); PG8_BAR;
;             PG8_LDA(At, 1, 1); PG8_STAGE(PG8_SA(1, 0), a3, voffA);
;             PG8_BAR; PG8_WAIT_L(0); PG8_MMA(1, 0, At, B0); PG8_BAR; PG8_SCHED;
;             PG8_STAGE(PG8_SB(1, 1), b3 + hstep, voffB);
;             PG8_WAIT_V(6); PG8_BAR; PG8_MMA(1, 1, At, B1); PG8_BAR;
	s_waitcnt lgkmcnt(0)
	v_mfma_f32_16x16x32_bf16 v[124:127], v[162:165], v[178:181], v[124:127]
	v_mfma_f32_16x16x32_bf16 v[120:123], v[170:173], v[178:181], v[120:123]
	v_mfma_f32_16x16x32_bf16 v[116:119], v[162:165], v[196:199], v[116:119]
	v_mfma_f32_16x16x32_bf16 v[112:115], v[170:173], v[196:199], v[112:115]
	v_mfma_f32_16x16x32_bf16 v[100:103], v[162:165], v[204:207], v[100:103]
	v_mfma_f32_16x16x32_bf16 v[96:99], v[170:173], v[204:207], v[96:99]
	v_mfma_f32_16x16x32_bf16 v[84:87], v[162:165], v[212:215], v[84:87]
	v_mfma_f32_16x16x32_bf16 v[80:83], v[170:173], v[212:215], v[80:83]
	v_mfma_f32_16x16x32_bf16 v[124:127], v[166:169], v[192:195], v[124:127]
	v_mfma_f32_16x16x32_bf16 v[120:123], v[174:177], v[192:195], v[120:123]
	v_mfma_f32_16x16x32_bf16 v[116:119], v[166:169], v[200:203], v[116:119]
	v_mfma_f32_16x16x32_bf16 v[112:115], v[174:177], v[200:203], v[112:115]
	v_mfma_f32_16x16x32_bf16 v[100:103], v[166:169], v[208:211], v[100:103]
	v_mfma_f32_16x16x32_bf16 v[96:99], v[174:177], v[208:211], v[96:99]
	v_mfma_f32_16x16x32_bf16 v[84:87], v[166:169], v[216:219], v[84:87]
	v_mfma_f32_16x16x32_bf16 v[80:83], v[174:177], v[216:219], v[80:83]
	s_barrier
	s_add_i32 s17, 0, 0x1c000
	s_add_i32 s14, s16, s40
	v_add_u32_e32 v161, s17, v158
	s_mov_b32 m0, s14
	ds_read_b128 v[220:223], v161
	ds_read_b128 v[224:227], v161 offset:1024
	ds_read_b128 v[228:231], v161 offset:2048
	ds_read_b128 v[232:235], v161 offset:3072
	global_load_lds_dwordx4 v244, s[26:27]
	s_add_i32 m0, s14, 0x2000
	s_nop 0
	global_load_lds_dwordx4 v245, s[26:27]
	s_barrier
	s_waitcnt lgkmcnt(0)
	v_mfma_f32_16x16x32_bf16 v[108:111], v[220:223], v[178:181], v[108:111]
	v_mfma_f32_16x16x32_bf16 v[104:107], v[228:231], v[178:181], v[104:107]
	v_mfma_f32_16x16x32_bf16 v[92:95], v[220:223], v[196:199], v[92:95]
	v_mfma_f32_16x16x32_bf16 v[88:91], v[228:231], v[196:199], v[88:91]
	v_mfma_f32_16x16x32_bf16 v[76:79], v[220:223], v[204:207], v[76:79]
	v_mfma_f32_16x16x32_bf16 v[72:75], v[228:231], v[204:207], v[72:75]
	v_mfma_f32_16x16x32_bf16 v[68:71], v[220:223], v[212:215], v[68:71]
	v_mfma_f32_16x16x32_bf16 v[64:67], v[228:231], v[212:215], v[64:67]
	v_mfma_f32_16x16x32_bf16 v[108:111], v[224:227], v[192:195], v[108:111]
	v_mfma_f32_16x16x32_bf16 v[104:107], v[232:235], v[192:195], v[104:107]
	v_mfma_f32_16x16x32_bf16 v[92:95], v[224:227], v[200:203], v[92:95]
	v_mfma_f32_16x16x32_bf16 v[88:91], v[232:235], v[200:203], v[88:91]
	v_mfma_f32_16x16x32_bf16 v[76:79], v[224:227], v[208:211], v[76:79]
	v_mfma_f32_16x16x32_bf16 v[72:75], v[232:235], v[208:211], v[72:75]
	v_mfma_f32_16x16x32_bf16 v[68:71], v[224:227], v[216:219], v[68:71]
	v_mfma_f32_16x16x32_bf16 v[64:67], v[232:235], v[216:219], v[64:67]
	s_mov_b32 m0, s46
	s_barrier
	ds_read_b128 v[178:181], v160 offset:49152
	ds_read_b128 v[192:195], v160 offset:50176
	ds_read_b128 v[196:199], v160 offset:51200
	ds_read_b128 v[200:203], v160 offset:52224
	ds_read_b128 v[204:207], v160 offset:53248
	ds_read_b128 v[208:211], v160 offset:54272
	ds_read_b128 v[212:215], v160 offset:55296
	ds_read_b128 v[216:219], v160 offset:56320
	global_load_lds_dwordx4 v246, s[30:31]
	s_mov_b32 m0, s47
	s_nop 0
	global_load_lds_dwordx4 v247, s[30:31]
	s_barrier
	s_waitcnt lgkmcnt(0)
	v_mfma_f32_16x16x32_bf16 v[60:63], v[162:165], v[178:181], v[60:63]
	v_mfma_f32_16x16x32_bf16 v[56:59], v[170:173], v[178:181], v[56:59]
	v_mfma_f32_16x16x32_bf16 v[52:55], v[162:165], v[196:199], v[52:55]
	v_mfma_f32_16x16x32_bf16 v[48:51], v[170:173], v[196:199], v[48:51]
	v_mfma_f32_16x16x32_bf16 v[36:39], v[162:165], v[204:207], v[36:39]
	v_mfma_f32_16x16x32_bf16 v[32:35], v[170:173], v[204:207], v[32:35]
	v_mfma_f32_16x16x32_bf16 v[20:23], v[162:165], v[212:215], v[20:23]
	v_mfma_f32_16x16x32_bf16 v[16:19], v[170:173], v[212:215], v[16:19]
	v_mfma_f32_16x16x32_bf16 v[60:63], v[166:169], v[192:195], v[60:63]
	v_mfma_f32_16x16x32_bf16 v[56:59], v[174:177], v[192:195], v[56:59]
	v_mfma_f32_16x16x32_bf16 v[52:55], v[166:169], v[200:203], v[52:55]
	v_mfma_f32_16x16x32_bf16 v[48:51], v[174:177], v[200:203], v[48:51]
	v_mfma_f32_16x16x32_bf16 v[36:39], v[166:169], v[208:211], v[36:39]
	v_mfma_f32_16x16x32_bf16 v[32:35], v[174:177], v[208:211], v[32:35]
	v_mfma_f32_16x16x32_bf16 v[20:23], v[166:169], v[216:219], v[20:23]
	v_mfma_f32_16x16x32_bf16 v[16:19], v[174:177], v[216:219], v[16:19]
	s_barrier
	s_add_u32 s14, s26, 0x20080
	s_addc_u32 s15, s27, 0
	s_add_i32 s16, s17, s40
	s_mov_b32 m0, s16
	s_nop 0
	global_load_lds_dwordx4 v128, s[14:15]
	s_add_i32 m0, s16, 0x2000
	s_nop 0
	global_load_lds_dwordx4 v152, s[14:15]
	s_waitcnt vmcnt(6)
	s_barrier
	v_mfma_f32_16x16x32_bf16 v[44:47], v[220:223], v[178:181], v[44:47]
	v_mfma_f32_16x16x32_bf16 v[40:43], v[228:231], v[178:181], v[40:43]
	v_mfma_f32_16x16x32_bf16 v[28:31], v[220:223], v[196:199], v[28:31]
	v_mfma_f32_16x16x32_bf16 v[24:27], v[228:231], v[196:199], v[24:27]
	v_mfma_f32_16x16x32_bf16 v[12:15], v[220:223], v[204:207], v[12:15]
	v_mfma_f32_16x16x32_bf16 v[8:11], v[228:231], v[204:207], v[8:11]
	v_mfma_f32_16x16x32_bf16 v[4:7], v[220:223], v[212:215], v[4:7]
	v_mfma_f32_16x16x32_bf16 v[0:3], v[228:231], v[212:215], v[0:3]
	v_mfma_f32_16x16x32_bf16 v[44:47], v[224:227], v[192:195], v[44:47]
	v_mfma_f32_16x16x32_bf16 v[40:43], v[232:235], v[192:195], v[40:43]
	v_mfma_f32_16x16x32_bf16 v[28:31], v[224:227], v[200:203], v[28:31]
	v_mfma_f32_16x16x32_bf16 v[24:27], v[232:235], v[200:203], v[24:27]
	v_mfma_f32_16x16x32_bf16 v[12:15], v[224:227], v[208:211], v[12:15]
	v_mfma_f32_16x16x32_bf16 v[8:11], v[232:235], v[208:211], v[8:11]
	v_mfma_f32_16x16x32_bf16 v[4:7], v[224:227], v[216:219], v[4:7]
	v_mfma_f32_16x16x32_bf16 v[0:3], v[232:235], v[216:219], v[0:3]
	s_add_i32 s59, s59, 2
	s_add_u32 s24, s24, 0x100
	s_addc_u32 s25, s25, 0
	s_add_u32 s57, s57, 0x100
	s_addc_u32 s58, s58, 0
	s_cmp_gt_u32 s59, 5
	s_barrier
; __device__ __forceinline__ unsigned cvt_pk_bf16(float lo, float hi) { const f32x2_cv v = {lo, hi}; const bf16x2_cv b = __builtin_convertvector(v, bf16x2_cv); return __builtin_bit_cast(unsigned, b); }
; __device__ __forceinline__ float rstd_of(const float* rowss, int row) { return rsqrtf(rowss[row] * (1.0f / 1024.0f) + 1e-6f); }
;     __device__ __forceinline__ void operator()(const f32x4 (&acc)[2][2][4][2], const pg8::Unit& u, int wr, int wc, int fr, int fq) const {
;         const int row0 = u.pm * 256 + wr * 64 + fr, col0 = u.pn * 256 + wc * 32 + 8 * fq;
; #pragma unroll
;         for (int ai = 0; ai < 2; ++ai)
; #pragma unroll
;             for (int m = 0; m < 4; ++m) {
;                 const int row = row0 + ai * 128 + m * 16;
;                 const float s = (MODE == 2) ? 1.0f : rstd_of(rowss, row);
;                 bf16_t* rowp = O + (size_t)row * ldc + col0;
; #pragma unroll
;                 for (int bj = 0; bj < 2; ++bj) {
;                     f32x4 v0 = acc[ai][bj][m][0] * s, v1 = acc[ai][bj][m][1] * s;
;                     if (MODE == 1) {
; #pragma unroll
;                         for (int j = 0; j < 4; ++j) { const float a = fmaxf(v0[j], 0.f), b = fmaxf(v1[j], 0.f); v0[j] = a * a; v1[j] = b * b; } }
;                     u32x4 w; w.x = cvt_pk_bf16(v0[0], v0[1]); w.y = cvt_pk_bf16(v0[2], v0[3]); w.z = cvt_pk_bf16(v1[0], v1[1]); w.w = cvt_pk_bf16(v1[2], v1[3]);
;                     *(u32x4*)(rowp + bj * 128) = w; } }
	s_cbranch_scc0 .LBB0_293
	v_lshl_add_u32 v162, s2, 8, v139
	v_lshl_or_b32 v164, s49, 8, v159
	v_ashrrev_i32_e32 v163, 31, v162
	v_ashrrev_i32_e32 v165, 31, v164
	v_lshlrev_b64 v[166:167], 11, v[162:163]
	v_lshl_add_u64 v[166:167], s[0:1], 0, v[166:167]
	v_lshlrev_b64 v[164:165], 1, v[164:165]
	v_lshl_add_u64 v[166:167], v[166:167], 0, v[164:165]
	s_mov_b32 s2, 0x40000
	s_mov_b64 s[14:15], 0x40000
	v_cvt_pk_bf16_f32 v60, v60, v61
	v_cvt_pk_bf16_f32 v61, v62, v63
	v_cvt_pk_bf16_f32 v62, v56, v57
	v_add_co_u32_e32 v56, vcc, s2, v166
	v_cvt_pk_bf16_f32 v68, v68, v69
	v_cvt_pk_bf16_f32 v69, v70, v71
	v_cvt_pk_bf16_f32 v70, v64, v65
	v_lshl_add_u64 v[64:65], v[166:167], 0, s[14:15]
	v_addc_co_u32_e32 v57, vcc, 0, v167, vcc
	v_cvt_pk_bf16_f32 v44, v44, v45
	v_cvt_pk_bf16_f32 v45, v46, v47
	v_cvt_pk_bf16_f32 v46, v40, v41
	v_cvt_pk_bf16_f32 v47, v42, v43
	s_mov_b32 s2, 0x48000
	v_cvt_pk_bf16_f32 v108, v108, v109
	v_cvt_pk_bf16_f32 v109, v110, v111
	v_cvt_pk_bf16_f32 v110, v104, v105
	v_or_b32_e32 v104, 16, v162
	global_store_dwordx4 v[64:65], v[44:47], off offset:256
	s_mov_b64 s[14:15], 0x48000
	v_ashrrev_i32_e32 v105, 31, v104
	v_add_co_u32_e32 v46, vcc, s2, v166
	v_cvt_pk_bf16_f32 v92, v92, v93
	v_cvt_pk_bf16_f32 v93, v94, v95
	v_cvt_pk_bf16_f32 v94, v88, v89
	v_or_b32_e32 v88, 32, v162
	v_lshl_add_u64 v[44:45], v[166:167], 0, s[14:15]
	v_addc_co_u32_e32 v47, vcc, 0, v167, vcc
	v_cvt_pk_bf16_f32 v28, v28, v29
	v_cvt_pk_bf16_f32 v29, v30, v31
	v_cvt_pk_bf16_f32 v30, v24, v25
	v_cvt_pk_bf16_f32 v31, v26, v27
	s_mov_b32 s2, 0x50000
	v_lshlrev_b64 v[104:105], 11, v[104:105]
	v_ashrrev_i32_e32 v89, 31, v88
	v_cvt_pk_bf16_f32 v76, v76, v77
	v_cvt_pk_bf16_f32 v77, v78, v79
	v_cvt_pk_bf16_f32 v78, v72, v73
	v_or_b32_e32 v72, 48, v162
	global_store_dwordx4 v[44:45], v[28:31], off offset:256
	s_mov_b64 s[14:15], 0x50000
	v_cvt_pk_bf16_f32 v111, v106, v107
	v_add_co_u32_e32 v30, vcc, s2, v166
	v_lshl_add_u64 v[104:105], s[0:1], 0, v[104:105]
	v_lshlrev_b64 v[88:89], 11, v[88:89]
	v_ashrrev_i32_e32 v73, 31, v72
	v_lshl_add_u64 v[28:29], v[166:167], 0, s[14:15]
	v_addc_co_u32_e32 v31, vcc, 0, v167, vcc
	v_cvt_pk_bf16_f32 v12, v12, v13
	v_cvt_pk_bf16_f32 v13, v14, v15
	v_cvt_pk_bf16_f32 v14, v8, v9
	v_cvt_pk_bf16_f32 v15, v10, v11
	s_mov_b32 s2, 0x58000
	global_store_dwordx4 v[166:167], v[108:111], off offset:256
	v_cvt_pk_bf16_f32 v95, v90, v91
	v_lshl_add_u64 v[88:89], s[0:1], 0, v[88:89]
	v_lshl_add_u64 v[108:109], v[104:105], 0, v[164:165]
	v_lshlrev_b64 v[72:73], 11, v[72:73]
	global_store_dwordx4 v[28:29], v[12:15], off offset:256
	global_store_dwordx4 v[108:109], v[92:95], off offset:256
	v_cvt_pk_bf16_f32 v79, v74, v75
	v_add_co_u32_e32 v14, vcc, s2, v166
	v_lshl_add_u64 v[92:93], v[88:89], 0, v[164:165]
	v_lshl_add_u64 v[72:73], s[0:1], 0, v[72:73]
	s_mov_b64 s[14:15], 0x58000
	v_addc_co_u32_e32 v15, vcc, 0, v167, vcc
	v_cvt_pk_bf16_f32 v124, v124, v125
	v_cvt_pk_bf16_f32 v125, v126, v127
	v_cvt_pk_bf16_f32 v126, v120, v121
	v_cvt_pk_bf16_f32 v127, v122, v123
	v_cvt_pk_bf16_f32 v104, v116, v117
	v_cvt_pk_bf16_f32 v105, v118, v119
	v_cvt_pk_bf16_f32 v106, v112, v113
	v_cvt_pk_bf16_f32 v107, v114, v115
	v_cvt_pk_bf16_f32 v88, v100, v101
	v_cvt_pk_bf16_f32 v89, v102, v103
	v_cvt_pk_bf16_f32 v90, v96, v97
	v_cvt_pk_bf16_f32 v91, v98, v99
	global_store_dwordx4 v[92:93], v[76:79], off offset:256
	v_cvt_pk_bf16_f32 v74, v80, v81
	v_cvt_pk_bf16_f32 v75, v82, v83
	v_lshl_add_u64 v[76:77], v[72:73], 0, v[164:165]
	v_cvt_pk_bf16_f32 v72, v84, v85
	v_cvt_pk_bf16_f32 v73, v86, v87
	v_cvt_pk_bf16_f32 v71, v66, v67
	v_cvt_pk_bf16_f32 v63, v58, v59
	v_cvt_pk_bf16_f32 v40, v52, v53
	v_cvt_pk_bf16_f32 v41, v54, v55
	v_cvt_pk_bf16_f32 v42, v48, v49
	v_cvt_pk_bf16_f32 v43, v50, v51
	v_cvt_pk_bf16_f32 v24, v36, v37
	v_cvt_pk_bf16_f32 v25, v38, v39
	v_cvt_pk_bf16_f32 v26, v32, v33
	v_cvt_pk_bf16_f32 v27, v34, v35
	v_lshl_add_u64 v[12:13], v[166:167], 0, s[14:15]
	v_cvt_pk_bf16_f32 v8, v20, v21
	v_cvt_pk_bf16_f32 v9, v22, v23
	v_cvt_pk_bf16_f32 v10, v16, v17
	v_cvt_pk_bf16_f32 v11, v18, v19
	v_cvt_pk_bf16_f32 v4, v4, v5
	v_cvt_pk_bf16_f32 v5, v6, v7
	v_cvt_pk_bf16_f32 v6, v0, v1
	v_cvt_pk_bf16_f32 v7, v2, v3
	s_and_b64 vcc, exec, s[38:39]
	s_mov_b32 s49, s4
	s_mov_b32 s2, s6
	s_mov_b64 s[26:27], s[22:23]
	s_mov_b64 s[24:25], s[12:13]
	s_movk_i32 s58, 0xff60
	global_store_dwordx4 v[166:167], v[124:127], off
	global_store_dwordx4 v[108:109], v[104:107], off
	global_store_dwordx4 v[92:93], v[88:91], off
	global_store_dwordx4 v[76:77], v[72:75], off
	global_store_dwordx4 v[76:77], v[68:71], off offset:256
	global_store_dwordx4 v[56:57], v[60:63], off
	global_store_dwordx4 v[46:47], v[40:43], off
	global_store_dwordx4 v[30:31], v[24:27], off
	global_store_dwordx4 v[14:15], v[8:11], off
	global_store_dwordx4 v[12:13], v[4:7], off offset:256
	s_cbranch_vccz .LBB0_286
	s_cmpk_gt_u32 s36, 0xff
	s_cbranch_scc1 .LBB0_297
	s_barrier

; #define PG8_STAGE(bufoff, gbase, voff) do { _Pragma("unroll") for (int _i = 0; _i < 2; ++_i) \
;         __builtin_amdgcn_global_load_lds((const unsigned*)((const char*)(gbase) + (voff)[_i]), (PG8_LAS unsigned*)(lds + (bufoff) + ldsw + _i * 8192), 16, 0, 0); } while (0)
; #define PG8_LDA(dst, b, h) do { _Pragma("unroll") for (int m = 0; m < 4; ++m) _Pragma("unroll") for (int k = 0; k < 2; ++k) dst[m][k] = *(const PG8_LAS bf16x8*)(lds + PG8_SA(b, h) + aoff + m * 2048 + k * 1024); } while (0)
; #define PG8_LDB(dst, b, h) do { _Pragma("unroll") for (int n = 0; n < 2; ++n) _Pragma("unroll") for (int k = 0; k < 2; ++k) dst[n][k] = *(const PG8_LAS bf16x8*)(lds + PG8_SB(b, h) + boff + n * 2048 + k * 1024); } while (0)
; #define PG8_MMA(ai, bj, At, Bt) do { __builtin_amdgcn_s_setprio(1); _Pragma("unroll") for (int m = 0; m < 4; ++m) _Pragma("unroll") for (int n = 0; n < 2; ++n) _Pragma("unroll") for (int k = 0; k < 2; ++k) \
;         acc[ai][bj][m][n] = __builtin_amdgcn_mfma_f32_16x16x32_bf16(Bt[n][k], At[m][k], acc[ai][bj][m][n], 0, 0, 0); __builtin_amdgcn_s_setprio(0); } while (0)
; #define PG8_WAIT_L(n) asm volatile("s_waitcnt lgkmcnt(" #n ")" ::: "memory")
; #define PG8_BAR __builtin_amdgcn_s_barrier()
; #define PG8_SCHED __builtin_amdgcn_sched_barrier(0)
; template <class Epi, class Sched, bool STAMP = false>
; __device__ __forceinline__ void gemm_phase(PG8_LAS unsigned char* lds, const Gemm g, const Sched& S, const Epi& E, unsigned long long* stamps) {
;     ...
;             PG8_LDB(B0, 0, 0); PG8_SCHED; PG8_LDA(At, 0, 0); PG8_STAGE(PG8_SA(1, 1), a1 + hstep, voffA);
;             PG8_WAIT_L(8); PG8_BAR; PG8_WAIT_L(0); PG8_MMA(0, 0, At, B0); PG8_BAR; PG8_SCHED;
;     ...
; #pragma unroll
;         for (int a = 0; a < 2; ++a)
; #pragma unroll
;             for (int b = 0; b < 2; ++b)
; #pragma unroll
;                 for (int m = 0; m < 4; ++m)
; #pragma unroll
;                     for (int n = 0; n < 2; ++n) acc[a][b][m][n] = (f32x4){0.f, 0.f, 0.f, 0.f};
;         cur = nxt; cA = nA; cB = nB; ++ui;
.LBB0_312:
	s_ashr_i32 s31, s30, 31
	s_lshl_b64 s[14:15], s[30:31], 19
	s_add_u32 s48, s42, s14
	v_cmp_lt_i64_e32 vcc, s[24:25], v[136:137]
	s_addc_u32 s49, s43, s15
	s_and_b64 s[14:15], vcc, exec
	s_cselect_b32 s31, s49, s5
	s_cselect_b32 s47, s48, s4
	s_ashr_i32 s7, s6, 31
	s_lshl_b64 s[14:15], s[6:7], 19
	s_add_u32 s24, s22, s14
	s_addc_u32 s25, s23, s15
	s_and_b64 s[14:15], vcc, exec
	s_cselect_b32 s7, s25, s13
	s_cselect_b32 s53, s24, s12
	s_add_u32 s4, s4, 0x40080
	s_addc_u32 s5, s5, 0
	s_add_u32 s62, s12, 0x100
	v_mov_b32_e32 v0, 0
	s_addc_u32 s63, s13, 0
	s_mov_b32 s65, -2
	v_mov_b32_e32 v1, v0
	v_mov_b32_e32 v2, v0
	v_mov_b32_e32 v3, v0
	v_mov_b32_e32 v4, v0
	v_mov_b32_e32 v5, v0
	v_mov_b32_e32 v6, v0
	v_mov_b32_e32 v7, v0
	v_mov_b32_e32 v16, v0
	v_mov_b32_e32 v17, v0
	v_mov_b32_e32 v18, v0
	v_mov_b32_e32 v19, v0
	v_mov_b32_e32 v20, v0
	v_mov_b32_e32 v21, v0
	v_mov_b32_e32 v22, v0
	v_mov_b32_e32 v23, v0
	v_mov_b32_e32 v32, v0
	v_mov_b32_e32 v33, v0
	v_mov_b32_e32 v34, v0
	v_mov_b32_e32 v35, v0
	v_mov_b32_e32 v36, v0
	v_mov_b32_e32 v37, v0
	v_mov_b32_e32 v38, v0
	v_mov_b32_e32 v39, v0
	v_mov_b32_e32 v48, v0
	v_mov_b32_e32 v49, v0
	v_mov_b32_e32 v50, v0
	v_mov_b32_e32 v51, v0
	v_mov_b32_e32 v52, v0
	v_mov_b32_e32 v53, v0
	v_mov_b32_e32 v54, v0
	v_mov_b32_e32 v55, v0
	v_mov_b32_e32 v8, v0
	v_mov_b32_e32 v9, v0
	v_mov_b32_e32 v10, v0
	v_mov_b32_e32 v11, v0
	v_mov_b32_e32 v12, v0
	v_mov_b32_e32 v13, v0
	v_mov_b32_e32 v14, v0
	v_mov_b32_e32 v15, v0
	v_mov_b32_e32 v24, v0
	v_mov_b32_e32 v25, v0
	v_mov_b32_e32 v26, v0
	v_mov_b32_e32 v27, v0
	v_mov_b32_e32 v28, v0
	v_mov_b32_e32 v29, v0
	v_mov_b32_e32 v30, v0
	v_mov_b32_e32 v31, v0
	v_mov_b32_e32 v40, v0
	v_mov_b32_e32 v41, v0
	v_mov_b32_e32 v42, v0
	v_mov_b32_e32 v43, v0
	v_mov_b32_e32 v44, v0
	v_mov_b32_e32 v45, v0
	v_mov_b32_e32 v46, v0
	v_mov_b32_e32 v47, v0
	v_mov_b32_e32 v56, v0
	v_mov_b32_e32 v57, v0
	v_mov_b32_e32 v58, v0
	v_mov_b32_e32 v59, v0
	v_mov_b32_e32 v60, v0
	v_mov_b32_e32 v61, v0
	v_mov_b32_e32 v62, v0
	v_mov_b32_e32 v63, v0
	v_mov_b32_e32 v64, v0
	v_mov_b32_e32 v65, v0
	v_mov_b32_e32 v66, v0
	v_mov_b32_e32 v67, v0
	v_mov_b32_e32 v68, v0
	v_mov_b32_e32 v69, v0
	v_mov_b32_e32 v70, v0
	v_mov_b32_e32 v71, v0
	v_mov_b32_e32 v80, v0
	v_mov_b32_e32 v81, v0
	v_mov_b32_e32 v82, v0
	v_mov_b32_e32 v83, v0
	v_mov_b32_e32 v84, v0
	v_mov_b32_e32 v85, v0
	v_mov_b32_e32 v86, v0
	v_mov_b32_e32 v87, v0
	v_mov_b32_e32 v96, v0
	v_mov_b32_e32 v97, v0
	v_mov_b32_e32 v98, v0
	v_mov_b32_e32 v99, v0
	v_mov_b32_e32 v100, v0
	v_mov_b32_e32 v101, v0
	v_mov_b32_e32 v102, v0
	v_mov_b32_e32 v103, v0
	v_mov_b32_e32 v112, v0
	v_mov_b32_e32 v113, v0
	v_mov_b32_e32 v114, v0
	v_mov_b32_e32 v115, v0
	v_mov_b32_e32 v116, v0
	v_mov_b32_e32 v117, v0
	v_mov_b32_e32 v118, v0
	v_mov_b32_e32 v119, v0
	v_mov_b32_e32 v72, v0
	v_mov_b32_e32 v73, v0
	v_mov_b32_e32 v74, v0
	v_mov_b32_e32 v75, v0
	v_mov_b32_e32 v76, v0
	v_mov_b32_e32 v77, v0
	v_mov_b32_e32 v78, v0
	v_mov_b32_e32 v79, v0
	v_mov_b32_e32 v88, v0
	v_mov_b32_e32 v89, v0
	v_mov_b32_e32 v90, v0
	v_mov_b32_e32 v91, v0
	v_mov_b32_e32 v92, v0
	v_mov_b32_e32 v93, v0
	v_mov_b32_e32 v94, v0
	v_mov_b32_e32 v95, v0
	v_mov_b32_e32 v104, v0
	v_mov_b32_e32 v105, v0
	v_mov_b32_e32 v106, v0
	v_mov_b32_e32 v107, v0
	v_mov_b32_e32 v108, v0
	v_mov_b32_e32 v109, v0
	v_mov_b32_e32 v110, v0
	v_mov_b32_e32 v111, v0
	v_mov_b32_e32 v120, v0
	v_mov_b32_e32 v121, v0
	v_mov_b32_e32 v122, v0
	v_mov_b32_e32 v123, v0
	v_mov_b32_e32 v124, v0
	v_mov_b32_e32 v125, v0
	v_mov_b32_e32 v126, v0
	v_mov_b32_e32 v127, v0
	v_add_u32_e32 v244, 0x80, v128
	v_add_u32_e32 v245, 0x80, v152
	v_add_u32_e32 v246, 0x80, v148
	v_add_u32_e32 v247, 0x80, v150
.LBB0_313:
	s_add_u32 s12, s4, 0xfffc0080
	s_addc_u32 s13, s5, -1
	s_add_i32 s14, 0, 0x10000
	v_add_u32_e32 v166, s14, v167
	ds_read_b128 v[158:161], v166
	ds_read_b128 v[162:165], v166 offset:1024
	ds_read_b128 v[170:173], v166 offset:2048
	ds_read_b128 v[174:177], v166 offset:3072
	s_cmp_eq_u32 s65, 12
	s_cselect_b32 s27, s31, s13
	s_cselect_b32 s26, s47, s12
	s_cselect_b32 s13, s7, s63
	s_cselect_b32 s12, s53, s62
	s_add_i32 m0, s3, 0xc000
	ds_read_b128 v[178:181], v169
	ds_read_b128 v[192:195], v169 offset:1024
	ds_read_b128 v[196:199], v169 offset:2048
	ds_read_b128 v[200:203], v169 offset:3072
	ds_read_b128 v[204:207], v169 offset:4096
	ds_read_b128 v[208:211], v169 offset:5120
	ds_read_b128 v[212:215], v169 offset:6144
	ds_read_b128 v[216:219], v169 offset:7168
	global_load_lds_dwordx4 v154, s[4:5]
	s_add_i32 m0, s3, 0xe000
	s_nop 0
	global_load_lds_dwordx4 v156, s[4:5]
	s_waitcnt lgkmcnt(8)
	s_barrier
	s_waitcnt lgkmcnt(0)
	v_mfma_f32_16x16x32_bf16 v[124:127], v[158:161], v[178:181], v[124:127]
	v_mfma_f32_16x16x32_bf16 v[120:123], v[170:173], v[178:181], v[120:123]
	v_mfma_f32_16x16x32_bf16 v[108:111], v[158:161], v[196:199], v[108:111]
	v_mfma_f32_16x16x32_bf16 v[104:107], v[170:173], v[196:199], v[104:107]
	v_mfma_f32_16x16x32_bf16 v[92:95], v[158:161], v[204:207], v[92:95]
	v_mfma_f32_16x16x32_bf16 v[88:91], v[170:173], v[204:207], v[88:91]
	v_mfma_f32_16x16x32_bf16 v[76:79], v[158:161], v[212:215], v[76:79]
	v_mfma_f32_16x16x32_bf16 v[72:75], v[170:173], v[212:215], v[72:75]
	v_mfma_f32_16x16x32_bf16 v[124:127], v[162:165], v[192:195], v[124:127]
	v_mfma_f32_16x16x32_bf16 v[120:123], v[174:177], v[192:195], v[120:123]
	v_mfma_f32_16x16x32_bf16 v[108:111], v[162:165], v[200:203], v[108:111]
	v_mfma_f32_16x16x32_bf16 v[104:107], v[174:177], v[200:203], v[104:107]
	v_mfma_f32_16x16x32_bf16 v[92:95], v[162:165], v[208:211], v[92:95]
	v_mfma_f32_16x16x32_bf16 v[88:91], v[174:177], v[208:211], v[88:91]
	v_mfma_f32_16x16x32_bf16 v[76:79], v[162:165], v[216:219], v[76:79]
	v_mfma_f32_16x16x32_bf16 v[72:75], v[174:177], v[216:219], v[72:75]
	s_barrier
; #define PG8_STAGE(bufoff, gbase, voff) do { _Pragma("unroll") for (int _i = 0; _i < 2; ++_i) \
;         __builtin_amdgcn_global_load_lds((const unsigned*)((const char*)(gbase) + (voff)[_i]), (PG8_LAS unsigned*)(lds + (bufoff) + ldsw + _i * 8192), 16, 0, 0); } while (0)
; #define PG8_LDA(dst, b, h) do { _Pragma("unroll") for (int m = 0; m < 4; ++m) _Pragma("unroll") for (int k = 0; k < 2; ++k) dst[m][k] = *(const PG8_LAS bf16x8*)(lds + PG8_SA(b, h) + aoff + m * 2048 + k * 1024); } while (0)
; #define PG8_LDB(dst, b, h) do { _Pragma("unroll") for (int n = 0; n < 2; ++n) _Pragma("unroll") for (int k = 0; k < 2; ++k) dst[n][k] = *(const PG8_LAS bf16x8*)(lds + PG8_SB(b, h) + boff + n * 2048 + k * 1024); } while (0)
; #define PG8_MMA(ai, bj, At, Bt) do { __builtin_amdgcn_s_setprio(1); _Pragma("unroll") for (int m = 0; m < 4; ++m) _Pragma("unroll") for (int n = 0; n < 2; ++n) _Pragma("unroll") for (int k = 0; k < 2; ++k) \
;         acc[ai][bj][m][n] = __builtin_amdgcn_mfma_f32_16x16x32_bf16(Bt[n][k], At[m][k], acc[ai][bj][m][n], 0, 0, 0); __builtin_amdgcn_s_setprio(0); } while (0)
; #define PG8_WAIT_V(n) asm volatile("s_waitcnt vmcnt(" #n ")" ::: "memory")
; #define PG8_WAIT_L(n) asm volatile("s_waitcnt lgkmcnt(" #n ")" ::: "memory")
; #define PG8_BAR __builtin_amdgcn_s_barrier()
; #define PG8_SCHED __builtin_amdgcn_sched_barrier(0)
; template <class Epi, class Sched, bool STAMP = false>
; __device__ __forceinline__ void gemm_phase(PG8_LAS unsigned char* lds, const Gemm g, const Sched& S, const Epi& E, unsigned long long* stamps) {
;     ...
;             PG8_LDB(B1, 0, 1); PG8_STAGE(PG8_SB(0, 0), b2, voffB);
;             PG8_BAR; PG8_WAIT_L(0); PG8_MMA(0, 1, At, B1); PG8_BAR;
;             PG8_LDA(At, 0, 1); PG8_STAGE(PG8_SA(0, 0), a2, voffA);
;             PG8_BAR; PG8_WAIT_L(0); PG8_MMA(1, 0, At, B0); PG8_BAR; PG8_SCHED;
;             PG8_STAGE(PG8_SB(0, 1), b2 + hstep, voffB);
;             PG8_WAIT_V(6); PG8_BAR; PG8_MMA(1, 1, At, B1); PG8_BAR;
;             PG8_LDB(B0, 1, 0); PG8_SCHED; PG8_LDA(At, 1, 0); PG8_STAGE(PG8_SA(0, 1), a2 + hstep, voffA);
;             PG8_WAIT_L(8); PG8_BAR; PG8_WAIT_L(0); PG8_MMA(0, 0, At, B0); PG8_BAR; PG8_SCHED;
	s_add_i32 s16, 0, 0x14000
	s_add_i32 s14, s14, s56
	v_add_u32_e32 v166, s16, v167
	s_mov_b32 m0, s14
	ds_read_b128 v[220:223], v166
	ds_read_b128 v[224:227], v166 offset:1024
	ds_read_b128 v[228:231], v166 offset:2048
	ds_read_b128 v[232:235], v166 offset:3072
	global_load_lds_dwordx4 v128, s[12:13]
	s_add_i32 m0, s14, 0x2000
	s_nop 0
	global_load_lds_dwordx4 v152, s[12:13]
	s_barrier
	s_waitcnt lgkmcnt(0)
	v_mfma_f32_16x16x32_bf16 v[116:119], v[220:223], v[178:181], v[116:119]
	v_mfma_f32_16x16x32_bf16 v[112:115], v[228:231], v[178:181], v[112:115]
	v_mfma_f32_16x16x32_bf16 v[100:103], v[220:223], v[196:199], v[100:103]
	v_mfma_f32_16x16x32_bf16 v[96:99], v[228:231], v[196:199], v[96:99]
	v_mfma_f32_16x16x32_bf16 v[84:87], v[220:223], v[204:207], v[84:87]
	v_mfma_f32_16x16x32_bf16 v[80:83], v[228:231], v[204:207], v[80:83]
	v_mfma_f32_16x16x32_bf16 v[68:71], v[220:223], v[212:215], v[68:71]
	v_mfma_f32_16x16x32_bf16 v[64:67], v[228:231], v[212:215], v[64:67]
	v_mfma_f32_16x16x32_bf16 v[116:119], v[224:227], v[192:195], v[116:119]
	v_mfma_f32_16x16x32_bf16 v[112:115], v[232:235], v[192:195], v[112:115]
	v_mfma_f32_16x16x32_bf16 v[100:103], v[224:227], v[200:203], v[100:103]
	v_mfma_f32_16x16x32_bf16 v[96:99], v[232:235], v[200:203], v[96:99]
	v_mfma_f32_16x16x32_bf16 v[84:87], v[224:227], v[208:211], v[84:87]
	v_mfma_f32_16x16x32_bf16 v[80:83], v[232:235], v[208:211], v[80:83]
	v_mfma_f32_16x16x32_bf16 v[68:71], v[224:227], v[216:219], v[68:71]
	v_mfma_f32_16x16x32_bf16 v[64:67], v[232:235], v[216:219], v[64:67]
	s_mov_b32 m0, s3
	s_barrier
	ds_read_b128 v[178:181], v169 offset:16384
	ds_read_b128 v[192:195], v169 offset:17408
	ds_read_b128 v[196:199], v169 offset:18432
	ds_read_b128 v[200:203], v169 offset:19456
	ds_read_b128 v[204:207], v169 offset:20480
	ds_read_b128 v[208:211], v169 offset:21504
	ds_read_b128 v[212:215], v169 offset:22528
	ds_read_b128 v[216:219], v169 offset:23552
	global_load_lds_dwordx4 v148, s[26:27]
	s_mov_b32 m0, s57
	s_nop 0
	global_load_lds_dwordx4 v150, s[26:27]
	s_barrier
	s_waitcnt lgkmcnt(0)
	v_mfma_f32_16x16x32_bf16 v[60:63], v[158:161], v[178:181], v[60:63]
	v_mfma_f32_16x16x32_bf16 v[56:59], v[170:173], v[178:181], v[56:59]
	v_mfma_f32_16x16x32_bf16 v[44:47], v[158:161], v[196:199], v[44:47]
	v_mfma_f32_16x16x32_bf16 v[40:43], v[170:173], v[196:199], v[40:43]
	v_mfma_f32_16x16x32_bf16 v[28:31], v[158:161], v[204:207], v[28:31]
	v_mfma_f32_16x16x32_bf16 v[24:27], v[170:173], v[204:207], v[24:27]
	v_mfma_f32_16x16x32_bf16 v[12:15], v[158:161], v[212:215], v[12:15]
	v_mfma_f32_16x16x32_bf16 v[8:11], v[170:173], v[212:215], v[8:11]
	v_mfma_f32_16x16x32_bf16 v[60:63], v[162:165], v[192:195], v[60:63]
	v_mfma_f32_16x16x32_bf16 v[56:59], v[174:177], v[192:195], v[56:59]
	v_mfma_f32_16x16x32_bf16 v[44:47], v[162:165], v[200:203], v[44:47]
	v_mfma_f32_16x16x32_bf16 v[40:43], v[174:177], v[200:203], v[40:43]
	v_mfma_f32_16x16x32_bf16 v[28:31], v[162:165], v[208:211], v[28:31]
	v_mfma_f32_16x16x32_bf16 v[24:27], v[174:177], v[208:211], v[24:27]
	v_mfma_f32_16x16x32_bf16 v[12:15], v[162:165], v[216:219], v[12:15]
	v_mfma_f32_16x16x32_bf16 v[8:11], v[174:177], v[216:219], v[8:11]
	s_barrier
	s_add_u32 s14, s12, 0x40000
	s_addc_u32 s15, s13, 0
	s_add_i32 s16, s16, s56
	s_mov_b32 m0, s16
	s_nop 0
	global_load_lds_dwordx4 v128, s[14:15]
	s_add_i32 m0, s16, 0x2000
	s_nop 0
	global_load_lds_dwordx4 v152, s[14:15]
	s_waitcnt vmcnt(6)
	s_barrier
	v_mfma_f32_16x16x32_bf16 v[52:55], v[220:223], v[178:181], v[52:55]
	v_mfma_f32_16x16x32_bf16 v[48:51], v[228:231], v[178:181], v[48:51]
	v_mfma_f32_16x16x32_bf16 v[36:39], v[220:223], v[196:199], v[36:39]
	v_mfma_f32_16x16x32_bf16 v[32:35], v[228:231], v[196:199], v[32:35]
	v_mfma_f32_16x16x32_bf16 v[20:23], v[220:223], v[204:207], v[20:23]
	v_mfma_f32_16x16x32_bf16 v[16:19], v[228:231], v[204:207], v[16:19]
	v_mfma_f32_16x16x32_bf16 v[4:7], v[220:223], v[212:215], v[4:7]
	v_mfma_f32_16x16x32_bf16 v[0:3], v[228:231], v[212:215], v[0:3]
	v_mfma_f32_16x16x32_bf16 v[52:55], v[224:227], v[192:195], v[52:55]
	v_mfma_f32_16x16x32_bf16 v[48:51], v[232:235], v[192:195], v[48:51]
	v_mfma_f32_16x16x32_bf16 v[36:39], v[224:227], v[200:203], v[36:39]
	v_mfma_f32_16x16x32_bf16 v[32:35], v[232:235], v[200:203], v[32:35]
	v_mfma_f32_16x16x32_bf16 v[20:23], v[224:227], v[208:211], v[20:23]
	v_mfma_f32_16x16x32_bf16 v[16:19], v[232:235], v[208:211], v[16:19]
	v_mfma_f32_16x16x32_bf16 v[4:7], v[224:227], v[216:219], v[4:7]
	v_mfma_f32_16x16x32_bf16 v[0:3], v[232:235], v[216:219], v[0:3]
	s_add_i32 s16, 0, 0x18000
	v_add_u32_e32 v166, s16, v167
	s_barrier
	ds_read_b128 v[158:161], v166
	ds_read_b128 v[162:165], v166 offset:1024
	ds_read_b128 v[170:173], v166 offset:2048
	ds_read_b128 v[174:177], v166 offset:3072
	s_add_u32 s14, s26, 0x40000
	s_addc_u32 s15, s27, 0
	s_mov_b32 m0, s58
	ds_read_b128 v[178:181], v169 offset:32768
	ds_read_b128 v[192:195], v169 offset:33792
	ds_read_b128 v[196:199], v169 offset:34816
	ds_read_b128 v[200:203], v169 offset:35840
	ds_read_b128 v[204:207], v169 offset:36864
	ds_read_b128 v[208:211], v169 offset:37888
	ds_read_b128 v[212:215], v169 offset:38912
	ds_read_b128 v[216:219], v169 offset:39936
	global_load_lds_dwordx4 v148, s[14:15]
	s_mov_b32 m0, s59
	s_nop 0
	global_load_lds_dwordx4 v150, s[14:15]
	s_waitcnt lgkmcnt(8)
	s_barrier
; #define PG8_STAGE(bufoff, gbase, voff) do { _Pragma("unroll") for (int _i = 0; _i < 2; ++_i) \
;         __builtin_amdgcn_global_load_lds((const unsigned*)((const char*)(gbase) + (voff)[_i]), (PG8_LAS unsigned*)(lds + (bufoff) + ldsw + _i * 8192), 16, 0, 0); } while (0)
; #define PG8_LDA(dst, b, h) do { _Pragma("unroll") for (int m = 0; m < 4; ++m) _Pragma("unroll") for (int k = 0; k < 2; ++k) dst[m][k] = *(const PG8_LAS bf16x8*)(lds + PG8_SA(b, h) + aoff + m * 2048 + k * 1024); } while (0)
; #define PG8_LDB(dst, b, h) do { _Pragma("unroll") for (int n = 0; n < 2; ++n) _Pragma("unroll") for (int k = 0; k < 2; ++k) dst[n][k] = *(const PG8_LAS bf16x8*)(lds + PG8_SB(b, h) + boff + n * 2048 + k * 1024); } while (0)
; #define PG8_MMA(ai, bj, At, Bt) do { __builtin_amdgcn_s_setprio(1); _Pragma("unroll") for (int m = 0; m < 4; ++m) _Pragma("unroll") for (int n = 0; n < 2; ++n) _Pragma("unroll") for (int k = 0; k < 2; ++k) \
;         acc[ai][bj][m][n] = __builtin_amdgcn_mfma_f32_16x16x32_bf16(Bt[n][k], At[m][k], acc[ai][bj][m][n], 0, 0, 0); __builtin_amdgcn_s_setprio(0); } while (0)
; #define PG8_WAIT_V(n) asm volatile("s_waitcnt vmcnt(" #n ")" ::: "memory")
; #define PG8_WAIT_L(n) asm volatile("s_waitcnt lgkmcnt(" #n ")" ::: "memory")
; #define PG8_BAR __builtin_amdgcn_s_barrier()
; #define PG8_SCHED __builtin_amdgcn_sched_barrier(0)
; template <class Epi, class Sched, bool STAMP = false>
; __device__ __forceinline__ void gemm_phase(PG8_LAS unsigned char* lds, const Gemm g, const Sched& S, const Epi& E, unsigned long long* stamps) {
;     ...
;             PG8_WAIT_L(8); PG8_BAR; PG8_WAIT_L(0); PG8_MMA(0, 0, At, B0); PG8_BAR; PG8_SCHED;
;             PG8_LDB(B1, 1, 1); PG8_STAGE(PG8_SB(1, 0), b3, voffB);
;             PG8_BAR; PG8_WAIT_L(0); PG8_MMA(0, 1, At, B1); PG8_BAR;
;             PG8_LDA(At, 1, 1); PG8_STAGE(PG8_SA(1, 0), a3, voffA);
;             PG8_BAR; PG8_WAIT_L(0); PG8_MMA(1, 0, At, B0); PG8_BAR; PG8_SCHED;
;             PG8_STAGE(PG8_SB(1, 1), b3 + hstep, voffB);
;             PG8_WAIT_V(6); PG8_BAR; PG8_MMA(1, 1, At, B1); PG8_BAR;
	s_waitcnt lgkmcnt(0)
	v_mfma_f32_16x16x32_bf16 v[124:127], v[158:161], v[178:181], v[124:127]
	v_mfma_f32_16x16x32_bf16 v[120:123], v[170:173], v[178:181], v[120:123]
	v_mfma_f32_16x16x32_bf16 v[108:111], v[158:161], v[196:199], v[108:111]
	v_mfma_f32_16x16x32_bf16 v[104:107], v[170:173], v[196:199], v[104:107]
	v_mfma_f32_16x16x32_bf16 v[92:95], v[158:161], v[204:207], v[92:95]
	v_mfma_f32_16x16x32_bf16 v[88:91], v[170:173], v[204:207], v[88:91]
	v_mfma_f32_16x16x32_bf16 v[76:79], v[158:161], v[212:215], v[76:79]
	v_mfma_f32_16x16x32_bf16 v[72:75], v[170:173], v[212:215], v[72:75]
	v_mfma_f32_16x16x32_bf16 v[124:127], v[162:165], v[192:195], v[124:127]
	v_mfma_f32_16x16x32_bf16 v[120:123], v[174:177], v[192:195], v[120:123]
	v_mfma_f32_16x16x32_bf16 v[108:111], v[162:165], v[200:203], v[108:111]
	v_mfma_f32_16x16x32_bf16 v[104:107], v[174:177], v[200:203], v[104:107]
	v_mfma_f32_16x16x32_bf16 v[92:95], v[162:165], v[208:211], v[92:95]
	v_mfma_f32_16x16x32_bf16 v[88:91], v[174:177], v[208:211], v[88:91]
	v_mfma_f32_16x16x32_bf16 v[76:79], v[162:165], v[216:219], v[76:79]
	v_mfma_f32_16x16x32_bf16 v[72:75], v[174:177], v[216:219], v[72:75]
	s_barrier
	s_add_i32 s14, 0, 0x1c000
	s_add_i32 s15, s16, s56
	v_add_u32_e32 v166, s14, v167
	s_mov_b32 m0, s15
	ds_read_b128 v[220:223], v166
	ds_read_b128 v[224:227], v166 offset:1024
	ds_read_b128 v[228:231], v166 offset:2048
	ds_read_b128 v[232:235], v166 offset:3072
	global_load_lds_dwordx4 v244, s[12:13]
	s_add_i32 m0, s15, 0x2000
	s_nop 0
	global_load_lds_dwordx4 v245, s[12:13]
	s_barrier
	s_waitcnt lgkmcnt(0)
	v_mfma_f32_16x16x32_bf16 v[116:119], v[220:223], v[178:181], v[116:119]
	v_mfma_f32_16x16x32_bf16 v[112:115], v[228:231], v[178:181], v[112:115]
	v_mfma_f32_16x16x32_bf16 v[100:103], v[220:223], v[196:199], v[100:103]
	v_mfma_f32_16x16x32_bf16 v[96:99], v[228:231], v[196:199], v[96:99]
	v_mfma_f32_16x16x32_bf16 v[84:87], v[220:223], v[204:207], v[84:87]
	v_mfma_f32_16x16x32_bf16 v[80:83], v[228:231], v[204:207], v[80:83]
	v_mfma_f32_16x16x32_bf16 v[68:71], v[220:223], v[212:215], v[68:71]
	v_mfma_f32_16x16x32_bf16 v[64:67], v[228:231], v[212:215], v[64:67]
	v_mfma_f32_16x16x32_bf16 v[116:119], v[224:227], v[192:195], v[116:119]
	v_mfma_f32_16x16x32_bf16 v[112:115], v[232:235], v[192:195], v[112:115]
	v_mfma_f32_16x16x32_bf16 v[100:103], v[224:227], v[200:203], v[100:103]
	v_mfma_f32_16x16x32_bf16 v[96:99], v[232:235], v[200:203], v[96:99]
	v_mfma_f32_16x16x32_bf16 v[84:87], v[224:227], v[208:211], v[84:87]
	v_mfma_f32_16x16x32_bf16 v[80:83], v[232:235], v[208:211], v[80:83]
	v_mfma_f32_16x16x32_bf16 v[68:71], v[224:227], v[216:219], v[68:71]
	v_mfma_f32_16x16x32_bf16 v[64:67], v[232:235], v[216:219], v[64:67]
	s_mov_b32 m0, s60
	s_barrier
	ds_read_b128 v[178:181], v169 offset:49152
	ds_read_b128 v[192:195], v169 offset:50176
	ds_read_b128 v[196:199], v169 offset:51200
	ds_read_b128 v[200:203], v169 offset:52224
	ds_read_b128 v[204:207], v169 offset:53248
	ds_read_b128 v[208:211], v169 offset:54272
	ds_read_b128 v[212:215], v169 offset:55296
	ds_read_b128 v[216:219], v169 offset:56320
	global_load_lds_dwordx4 v246, s[26:27]
	s_mov_b32 m0, s61
	s_nop 0
	global_load_lds_dwordx4 v247, s[26:27]
	s_barrier
	s_waitcnt lgkmcnt(0)
	v_mfma_f32_16x16x32_bf16 v[60:63], v[158:161], v[178:181], v[60:63]
	v_mfma_f32_16x16x32_bf16 v[56:59], v[170:173], v[178:181], v[56:59]
	v_mfma_f32_16x16x32_bf16 v[44:47], v[158:161], v[196:199], v[44:47]
	v_mfma_f32_16x16x32_bf16 v[40:43], v[170:173], v[196:199], v[40:43]
	v_mfma_f32_16x16x32_bf16 v[28:31], v[158:161], v[204:207], v[28:31]
	v_mfma_f32_16x16x32_bf16 v[24:27], v[170:173], v[204:207], v[24:27]
	v_mfma_f32_16x16x32_bf16 v[12:15], v[158:161], v[212:215], v[12:15]
	v_mfma_f32_16x16x32_bf16 v[8:11], v[170:173], v[212:215], v[8:11]
	v_mfma_f32_16x16x32_bf16 v[60:63], v[162:165], v[192:195], v[60:63]
	v_mfma_f32_16x16x32_bf16 v[56:59], v[174:177], v[192:195], v[56:59]
	v_mfma_f32_16x16x32_bf16 v[44:47], v[162:165], v[200:203], v[44:47]
	v_mfma_f32_16x16x32_bf16 v[40:43], v[174:177], v[200:203], v[40:43]
	v_mfma_f32_16x16x32_bf16 v[28:31], v[162:165], v[208:211], v[28:31]
	v_mfma_f32_16x16x32_bf16 v[24:27], v[174:177], v[208:211], v[24:27]
	v_mfma_f32_16x16x32_bf16 v[12:15], v[162:165], v[216:219], v[12:15]
	v_mfma_f32_16x16x32_bf16 v[8:11], v[174:177], v[216:219], v[8:11]
	s_barrier
	s_add_u32 s12, s12, 0x40080
	s_addc_u32 s13, s13, 0
	s_add_i32 s14, s14, s56
	s_mov_b32 m0, s14
	s_nop 0
	global_load_lds_dwordx4 v128, s[12:13]
	s_add_i32 m0, s14, 0x2000
	s_nop 0
	global_load_lds_dwordx4 v152, s[12:13]
	s_waitcnt vmcnt(6)
	s_barrier
	v_mfma_f32_16x16x32_bf16 v[52:55], v[220:223], v[178:181], v[52:55]
	v_mfma_f32_16x16x32_bf16 v[48:51], v[228:231], v[178:181], v[48:51]
	v_mfma_f32_16x16x32_bf16 v[36:39], v[220:223], v[196:199], v[36:39]
	v_mfma_f32_16x16x32_bf16 v[32:35], v[228:231], v[196:199], v[32:35]
	v_mfma_f32_16x16x32_bf16 v[20:23], v[220:223], v[204:207], v[20:23]
	v_mfma_f32_16x16x32_bf16 v[16:19], v[228:231], v[204:207], v[16:19]
	v_mfma_f32_16x16x32_bf16 v[4:7], v[220:223], v[212:215], v[4:7]
	v_mfma_f32_16x16x32_bf16 v[0:3], v[228:231], v[212:215], v[0:3]
	v_mfma_f32_16x16x32_bf16 v[52:55], v[224:227], v[192:195], v[52:55]
	v_mfma_f32_16x16x32_bf16 v[48:51], v[232:235], v[192:195], v[48:51]
	v_mfma_f32_16x16x32_bf16 v[36:39], v[224:227], v[200:203], v[36:39]
	v_mfma_f32_16x16x32_bf16 v[32:35], v[232:235], v[200:203], v[32:35]
	v_mfma_f32_16x16x32_bf16 v[20:23], v[224:227], v[208:211], v[20:23]
	v_mfma_f32_16x16x32_bf16 v[16:19], v[232:235], v[208:211], v[16:19]
	v_mfma_f32_16x16x32_bf16 v[4:7], v[224:227], v[216:219], v[4:7]
	v_mfma_f32_16x16x32_bf16 v[0:3], v[232:235], v[216:219], v[0:3]
	s_add_i32 s65, s65, 2
	s_add_u32 s4, s4, 0x100
	s_addc_u32 s5, s5, 0
	s_add_u32 s62, s62, 0x100
	s_addc_u32 s63, s63, 0
	s_cmp_gt_u32 s65, 13
	s_barrier
; __device__ __forceinline__ unsigned cvt_pk_bf16(float lo, float hi) { const f32x2_cv v = {lo, hi}; const bf16x2_cv b = __builtin_convertvector(v, bf16x2_cv); return __builtin_bit_cast(unsigned, b); }
; __device__ __forceinline__ float sigm(float x) { return __builtin_amdgcn_rcpf(1.0f + __expf(-x)); }
; __device__ __forceinline__ float lo16(unsigned w) { return __uint_as_float(w << 16); }
; __device__ __forceinline__ float hi16(unsigned w) { return __uint_as_float(w & 0xffff0000u); }
; __device__ __forceinline__ float rstd_of(const float* rowss, int row) { return rsqrtf(rowss[row] * (1.0f / 1024.0f) + 1e-6f); }
;     __device__ __forceinline__ void operator()(const f32x4 (&acc)[2][2][4][2], const pg8::Unit& u, int wr, int wc, int fr, int fq) const {
;         const int row0 = u.pm * 256 + wr * 64 + fr, col0 = u.pn * 256 + wc * 32 + 8 * fq;
; #pragma unroll
;         for (int ai = 0; ai < 2; ++ai)
; #pragma unroll
;             for (int m = 0; m < 4; ++m) {
;                 const int row = row0 + ai * 128 + m * 16;
;                 const float s = rstd_of(rowss, row);
; #pragma unroll
;                 for (int bj = 0; bj < 2; ++bj) {
;                     const size_t off = (size_t)row * 1024 + col0 + bj * 128;
;                     const u32x4 tv = *(const u32x4*)(Tm + off);
;                     u32x4 pv = (u32x4){0u, 0u, 0u, 0u};
;                     if (ACC) pv = *(const u32x4*)(M + off);
;                     const f32x4 a0 = acc[ai][bj][m][0] * s, a1 = acc[ai][bj][m][1] * s;
;                     float o[8];
;                     o[0] = sigm(a0[0]) * lo16(tv.x); o[1] = sigm(a0[1]) * hi16(tv.x); o[2] = sigm(a0[2]) * lo16(tv.y); o[3] = sigm(a0[3]) * hi16(tv.y);
;                     o[4] = sigm(a1[0]) * lo16(tv.z); o[5] = sigm(a1[1]) * hi16(tv.z); o[6] = sigm(a1[2]) * lo16(tv.w); o[7] = sigm(a1[3]) * hi16(tv.w);
;                     if (ACC) { o[0] += lo16(pv.x); o[1] += hi16(pv.x); o[2] += lo16(pv.y); o[3] += hi16(pv.y); o[4] += lo16(pv.z); o[5] += hi16(pv.z); o[6] += lo16(pv.w); o[7] += hi16(pv.w); }
;                     u32x4 w; w.x = cvt_pk_bf16(o[0], o[1]); w.y = cvt_pk_bf16(o[2], o[3]); w.z = cvt_pk_bf16(o[4], o[5]); w.w = cvt_pk_bf16(o[6], o[7]);
;                     *(u32x4*)(M + off) = w; } }
;     }
	s_cbranch_scc0 .LBB0_313
	v_lshl_add_u32 v162, s2, 8, v139
	v_ashrrev_i32_e32 v163, 31, v162
	v_lshl_add_u64 v[160:161], v[162:163], 2, s[40:41]
	global_load_dword v164, v[160:161], off
	v_lshl_or_b32 v158, s46, 8, v168
	v_ashrrev_i32_e32 v159, 31, v158
	s_mov_b32 s2, 0x40000
	s_mov_b64 s[4:5], 0x40000
	s_mov_b32 s46, s6
	s_mov_b64 s[12:13], s[24:25]
	s_mov_b32 s62, 0x1800000
	s_waitcnt vmcnt(0)
	v_fmamk_f32 v164, v164, 0x3a800000, v187
	v_cmp_gt_f32_e32 vcc, s67, v164
	v_mul_f32_e32 v165, 0x4b800000, v164
	s_nop 0
	v_cndmask_b32_e32 v164, v164, v165, vcc
	v_rsq_f32_e32 v164, v164
	s_nop 0
	v_mul_f32_e32 v165, 0x45800000, v164
	v_cndmask_b32_e32 v166, v164, v165, vcc
	v_lshlrev_b64 v[164:165], 11, v[162:163]
	v_lshl_add_u64 v[170:171], s[0:1], 0, v[164:165]
	v_lshlrev_b64 v[164:165], 1, v[158:159]
	v_lshl_add_u64 v[158:159], v[170:171], 0, v[164:165]
	v_mov_b32_e32 v170, v158
	v_mov_b32_e32 v171, v159
	global_load_dwordx4 v[192:195], v[170:171], off
	global_load_dwordx4 v[196:199], v[170:171], off offset:256
	v_add_co_u32_e32 v170, vcc, 0x8000, v170
	s_nop 1
	v_addc_co_u32_e32 v171, vcc, 0, v171, vcc
	global_load_dwordx4 v[200:203], v[170:171], off
	global_load_dwordx4 v[204:207], v[170:171], off offset:256
	v_add_co_u32_e32 v170, vcc, 0x8000, v170
	s_nop 1
	v_addc_co_u32_e32 v171, vcc, 0, v171, vcc
	global_load_dwordx4 v[208:211], v[170:171], off
	global_load_dwordx4 v[212:215], v[170:171], off offset:256
	v_add_co_u32_e32 v170, vcc, 0x8000, v170
	s_nop 1
	v_addc_co_u32_e32 v171, vcc, 0, v171, vcc
	global_load_dwordx4 v[216:219], v[170:171], off
	global_load_dwordx4 v[220:223], v[170:171], off offset:256
	v_lshl_add_u64 v[170:171], v[158:159], 0, s[4:5]
	global_load_dwordx4 v[224:227], v[170:171], off
	global_load_dwordx4 v[228:231], v[170:171], off offset:256
	v_add_co_u32_e32 v170, vcc, 0x8000, v170
	s_nop 1
	v_addc_co_u32_e32 v171, vcc, 0, v171, vcc
	global_load_dwordx4 v[232:235], v[170:171], off
	global_load_dwordx4 v[236:239], v[170:171], off offset:256
	v_add_co_u32_e32 v170, vcc, 0x8000, v170
	s_nop 1
	v_addc_co_u32_e32 v171, vcc, 0, v171, vcc
	global_load_dwordx4 v[244:247], v[170:171], off
	global_load_dwordx4 v[248:251], v[170:171], off offset:256
	v_add_co_u32_e32 v170, vcc, 0x8000, v170
	s_nop 1
	v_addc_co_u32_e32 v171, vcc, 0, v171, vcc
	global_load_dwordx4 v[176:179], v[170:171], off
	global_load_dwordx4 v[252:255], v[170:171], off offset:256
	global_load_dword v180, v[160:161], off offset:64
	global_load_dword v181, v[160:161], off offset:128
	global_load_dword v182, v[160:161], off offset:192
	global_load_dword v183, v[160:161], off offset:512
	global_load_dword v240, v[160:161], off offset:576
	global_load_dword v241, v[160:161], off offset:640
	global_load_dword v169, v[160:161], off offset:704
	v_pk_mul_f32 v[126:127], v[126:127], v[166:167] op_sel_hi:[1,0]
	v_pk_mul_f32 v[120:121], v[120:121], v[166:167] op_sel_hi:[1,0]
	v_mul_f32_e32 v126, 0xbfb8aa3b, v126
	v_mul_f32_e32 v127, 0xbfb8aa3b, v127
	v_exp_f32_e32 v126, v126
	v_exp_f32_e32 v127, v127
	v_mul_f32_e32 v120, 0xbfb8aa3b, v120
	v_mul_f32_e32 v121, 0xbfb8aa3b, v121
	v_exp_f32_e32 v120, v120
	v_exp_f32_e32 v121, v121
	v_add_f32_e32 v126, 1.0, v126
	v_add_f32_e32 v127, 1.0, v127
	v_rcp_f32_e32 v126, v126
	v_rcp_f32_e32 v127, v127
	v_add_f32_e32 v120, 1.0, v120
	v_add_f32_e32 v121, 1.0, v121
	v_rcp_f32_e32 v120, v120
	v_rcp_f32_e32 v121, v121
	v_pk_mul_f32 v[124:125], v[124:125], v[166:167] op_sel_hi:[1,0]
	v_pk_mul_f32 v[122:123], v[122:123], v[166:167] op_sel_hi:[1,0]
	v_mul_f32_e32 v124, 0xbfb8aa3b, v124
	v_mul_f32_e32 v125, 0xbfb8aa3b, v125
	v_exp_f32_e32 v124, v124
	v_exp_f32_e32 v125, v125
	v_pk_mul_f32 v[118:119], v[118:119], v[166:167] op_sel_hi:[1,0]
	v_pk_mul_f32 v[112:113], v[112:113], v[166:167] op_sel_hi:[1,0]
	v_add_f32_e32 v124, 1.0, v124
	v_add_f32_e32 v125, 1.0, v125
	v_rcp_f32_e32 v124, v124
	v_rcp_f32_e32 v125, v125
	v_mul_f32_e32 v118, 0xbfb8aa3b, v118
	v_mul_f32_e32 v119, 0xbfb8aa3b, v119
	v_exp_f32_e32 v118, v118
	v_exp_f32_e32 v119, v119
	v_mul_f32_e32 v112, 0xbfb8aa3b, v112
	v_mul_f32_e32 v113, 0xbfb8aa3b, v113
	v_exp_f32_e32 v112, v112
	v_exp_f32_e32 v113, v113
	v_add_f32_e32 v118, 1.0, v118
	v_add_f32_e32 v119, 1.0, v119
	v_rcp_f32_e32 v118, v118
	v_rcp_f32_e32 v119, v119
	v_add_f32_e32 v112, 1.0, v112
	v_add_f32_e32 v113, 1.0, v113
	v_rcp_f32_e32 v112, v112
	v_rcp_f32_e32 v113, v113
	v_pk_mul_f32 v[116:117], v[116:117], v[166:167] op_sel_hi:[1,0]
	v_pk_mul_f32 v[114:115], v[114:115], v[166:167] op_sel_hi:[1,0]
	v_mul_f32_e32 v116, 0xbfb8aa3b, v116
	v_mul_f32_e32 v117, 0xbfb8aa3b, v117
	v_exp_f32_e32 v116, v116
	v_exp_f32_e32 v117, v117
	v_add_f32_e32 v116, 1.0, v116
	v_add_f32_e32 v117, 1.0, v117
	v_rcp_f32_e32 v116, v116
	v_rcp_f32_e32 v117, v117
	s_waitcnt vmcnt(0)
; __device__ __forceinline__ unsigned cvt_pk_bf16(float lo, float hi) { const f32x2_cv v = {lo, hi}; const bf16x2_cv b = __builtin_convertvector(v, bf16x2_cv); return __builtin_bit_cast(unsigned, b); }
; __device__ __forceinline__ float sigm(float x) { return __builtin_amdgcn_rcpf(1.0f + __expf(-x)); }
; __device__ __forceinline__ float lo16(unsigned w) { return __uint_as_float(w << 16); }
; __device__ __forceinline__ float hi16(unsigned w) { return __uint_as_float(w & 0xffff0000u); }
; __device__ __forceinline__ float rstd_of(const float* rowss, int row) { return rsqrtf(rowss[row] * (1.0f / 1024.0f) + 1e-6f); }
;     __device__ __forceinline__ void operator()(const f32x4 (&acc)[2][2][4][2], const pg8::Unit& u, int wr, int wc, int fr, int fq) const {
;         const int row0 = u.pm * 256 + wr * 64 + fr, col0 = u.pn * 256 + wc * 32 + 8 * fq;
; #pragma unroll
;         for (int ai = 0; ai < 2; ++ai)
; #pragma unroll
;             for (int m = 0; m < 4; ++m) {
;                 const int row = row0 + ai * 128 + m * 16;
;                 const float s = rstd_of(rowss, row);
; #pragma unroll
;                 for (int bj = 0; bj < 2; ++bj) {
;                     const size_t off = (size_t)row * 1024 + col0 + bj * 128;
;                     const u32x4 tv = *(const u32x4*)(Tm + off);
;                     u32x4 pv = (u32x4){0u, 0u, 0u, 0u};
;                     if (ACC) pv = *(const u32x4*)(M + off);
;                     const f32x4 a0 = acc[ai][bj][m][0] * s, a1 = acc[ai][bj][m][1] * s;
;                     float o[8];
;                     o[0] = sigm(a0[0]) * lo16(tv.x); o[1] = sigm(a0[1]) * hi16(tv.x); o[2] = sigm(a0[2]) * lo16(tv.y); o[3] = sigm(a0[3]) * hi16(tv.y);
;                     o[4] = sigm(a1[0]) * lo16(tv.z); o[5] = sigm(a1[1]) * hi16(tv.z); o[6] = sigm(a1[2]) * lo16(tv.w); o[7] = sigm(a1[3]) * hi16(tv.w);
;                     if (ACC) { o[0] += lo16(pv.x); o[1] += hi16(pv.x); o[2] += lo16(pv.y); o[3] += hi16(pv.y); o[4] += lo16(pv.z); o[5] += hi16(pv.z); o[6] += lo16(pv.w); o[7] += hi16(pv.w); }
;                     u32x4 w; w.x = cvt_pk_bf16(o[0], o[1]); w.y = cvt_pk_bf16(o[2], o[3]); w.z = cvt_pk_bf16(o[4], o[5]); w.w = cvt_pk_bf16(o[6], o[7]);
;                     *(u32x4*)(M + off) = w; } }
;     }
	v_mov_b32_e32 v170, v192
	v_mov_b32_e32 v171, v193
	v_mov_b32_e32 v172, v194
	v_mov_b32_e32 v173, v195
	v_lshlrev_b32_e32 v174, 16, v170
	v_and_b32_e32 v175, 0xffff0000, v170
	v_lshlrev_b32_e32 v170, 16, v171
	v_and_b32_e32 v171, 0xffff0000, v171
	v_pk_mul_f32 v[126:127], v[126:127], v[170:171]
	v_lshlrev_b32_e32 v170, 16, v172
	v_and_b32_e32 v171, 0xffff0000, v172
	v_pk_mul_f32 v[170:171], v[120:121], v[170:171]
	v_mul_f32_e32 v120, 0xbfb8aa3b, v122
	v_mul_f32_e32 v121, 0xbfb8aa3b, v123
	v_exp_f32_e32 v120, v120
	v_exp_f32_e32 v121, v121
	v_lshlrev_b32_e32 v122, 16, v173
	v_and_b32_e32 v123, 0xffff0000, v173
	v_add_f32_e32 v120, 1.0, v120
	v_add_f32_e32 v121, 1.0, v121
	v_rcp_f32_e32 v120, v120
	v_rcp_f32_e32 v121, v121
	v_pk_mul_f32 v[124:125], v[124:125], v[174:175]
	v_pk_mul_f32 v[172:173], v[120:121], v[122:123]
	v_cvt_pk_bf16_f32 v120, v124, v125
	v_cvt_pk_bf16_f32 v121, v126, v127
	v_cvt_pk_bf16_f32 v122, v170, v171
	v_cvt_pk_bf16_f32 v123, v172, v173
	global_store_dwordx4 v[158:159], v[120:123], off
	s_nop 1
	v_mov_b32_e32 v120, v196
	v_mov_b32_e32 v121, v197
	v_mov_b32_e32 v122, v198
	v_mov_b32_e32 v123, v199
	v_lshlrev_b32_e32 v124, 16, v120
	v_and_b32_e32 v125, 0xffff0000, v120
	v_lshlrev_b32_e32 v120, 16, v121
	v_and_b32_e32 v121, 0xffff0000, v121
	v_pk_mul_f32 v[118:119], v[118:119], v[120:121]
	v_lshlrev_b32_e32 v120, 16, v122
	v_and_b32_e32 v121, 0xffff0000, v122
	v_pk_mul_f32 v[120:121], v[112:113], v[120:121]
	v_mul_f32_e32 v112, 0xbfb8aa3b, v114
	v_mul_f32_e32 v113, 0xbfb8aa3b, v115
	v_exp_f32_e32 v112, v112
	v_exp_f32_e32 v113, v113
	v_lshlrev_b32_e32 v114, 16, v123
	v_and_b32_e32 v115, 0xffff0000, v123
	v_add_f32_e32 v112, 1.0, v112
	v_add_f32_e32 v113, 1.0, v113
	v_rcp_f32_e32 v112, v112
	v_rcp_f32_e32 v113, v113
	v_pk_mul_f32 v[116:117], v[116:117], v[124:125]
	v_pk_mul_f32 v[122:123], v[112:113], v[114:115]
	v_cvt_pk_bf16_f32 v112, v116, v117
	v_cvt_pk_bf16_f32 v113, v118, v119
	v_cvt_pk_bf16_f32 v114, v120, v121
	v_cvt_pk_bf16_f32 v115, v122, v123
	global_store_dwordx4 v[158:159], v[112:115], off offset:256
	s_nop 1
	v_mov_b32_e32 v114, v180
	s_nop 0
	v_or_b32_e32 v112, 16, v162
	v_ashrrev_i32_e32 v113, 31, v112
	v_lshlrev_b64 v[112:113], 11, v[112:113]
	v_lshl_add_u64 v[112:113], s[0:1], 0, v[112:113]
	v_lshl_add_u64 v[112:113], v[112:113], 0, v[164:165]
	s_nop 1
	v_mov_b32_e32 v116, v200
	v_mov_b32_e32 v117, v201
	v_mov_b32_e32 v118, v202
	v_mov_b32_e32 v119, v203
	v_fmamk_f32 v114, v114, 0x3a800000, v187
	v_cmp_gt_f32_e32 vcc, s67, v114
	v_mul_f32_e32 v115, 0x4b800000, v114
	v_lshlrev_b32_e32 v120, 16, v116
	v_cndmask_b32_e32 v114, v114, v115, vcc
	v_rsq_f32_e32 v114, v114
	v_and_b32_e32 v121, 0xffff0000, v116
	v_lshlrev_b32_e32 v116, 16, v117
	v_and_b32_e32 v117, 0xffff0000, v117
	v_mul_f32_e32 v115, 0x45800000, v114
	v_cndmask_b32_e32 v114, v114, v115, vcc
	v_pk_mul_f32 v[110:111], v[110:111], v[114:115] op_sel_hi:[1,0]
	v_pk_mul_f32 v[104:105], v[104:105], v[114:115] op_sel_hi:[1,0]
	v_mul_f32_e32 v110, 0xbfb8aa3b, v110
	v_mul_f32_e32 v111, 0xbfb8aa3b, v111
	v_exp_f32_e32 v110, v110
	v_exp_f32_e32 v111, v111
	v_mul_f32_e32 v104, 0xbfb8aa3b, v104
	v_mul_f32_e32 v105, 0xbfb8aa3b, v105
	v_exp_f32_e32 v104, v104
	v_exp_f32_e32 v105, v105
	v_add_f32_e32 v110, 1.0, v110
	v_add_f32_e32 v111, 1.0, v111
	v_rcp_f32_e32 v110, v110
	v_rcp_f32_e32 v111, v111
	v_add_f32_e32 v104, 1.0, v104
	v_add_f32_e32 v105, 1.0, v105
	v_rcp_f32_e32 v104, v104
	v_rcp_f32_e32 v105, v105
	v_pk_mul_f32 v[108:109], v[108:109], v[114:115] op_sel_hi:[1,0]
	v_pk_mul_f32 v[106:107], v[106:107], v[114:115] op_sel_hi:[1,0]
	v_pk_mul_f32 v[110:111], v[110:111], v[116:117]
	v_lshlrev_b32_e32 v116, 16, v118
	v_and_b32_e32 v117, 0xffff0000, v118
	v_mul_f32_e32 v108, 0xbfb8aa3b, v108
	v_mul_f32_e32 v109, 0xbfb8aa3b, v109
	v_pk_mul_f32 v[116:117], v[104:105], v[116:117]
	v_mul_f32_e32 v104, 0xbfb8aa3b, v106
	v_mul_f32_e32 v105, 0xbfb8aa3b, v107
	v_exp_f32_e32 v108, v108
	v_exp_f32_e32 v109, v109
	v_exp_f32_e32 v104, v104
	v_exp_f32_e32 v105, v105
	v_add_f32_e32 v108, 1.0, v108
	v_add_f32_e32 v109, 1.0, v109
	v_add_f32_e32 v104, 1.0, v104
	v_add_f32_e32 v105, 1.0, v105
	v_rcp_f32_e32 v108, v108
	v_rcp_f32_e32 v109, v109
	v_rcp_f32_e32 v104, v104
	v_rcp_f32_e32 v105, v105
	v_lshlrev_b32_e32 v106, 16, v119
	v_and_b32_e32 v107, 0xffff0000, v119
	v_pk_mul_f32 v[108:109], v[108:109], v[120:121]
	v_pk_mul_f32 v[118:119], v[104:105], v[106:107]
	v_cvt_pk_bf16_f32 v104, v108, v109
	v_cvt_pk_bf16_f32 v105, v110, v111
	v_cvt_pk_bf16_f32 v106, v116, v117
	v_cvt_pk_bf16_f32 v107, v118, v119
	global_store_dwordx4 v[112:113], v[104:107], off
	s_nop 1
	v_mov_b32_e32 v104, v204
	v_mov_b32_e32 v105, v205
	v_mov_b32_e32 v106, v206
	v_mov_b32_e32 v107, v207
	v_pk_mul_f32 v[102:103], v[102:103], v[114:115] op_sel_hi:[1,0]
	v_pk_mul_f32 v[96:97], v[96:97], v[114:115] op_sel_hi:[1,0]
	v_mul_f32_e32 v102, 0xbfb8aa3b, v102
	v_mul_f32_e32 v103, 0xbfb8aa3b, v103
	v_exp_f32_e32 v102, v102
	v_exp_f32_e32 v103, v103
	v_mul_f32_e32 v96, 0xbfb8aa3b, v96
	v_mul_f32_e32 v97, 0xbfb8aa3b, v97
	v_exp_f32_e32 v96, v96
	v_exp_f32_e32 v97, v97
	v_add_f32_e32 v102, 1.0, v102
	v_add_f32_e32 v103, 1.0, v103
	v_rcp_f32_e32 v102, v102
	v_rcp_f32_e32 v103, v103
	v_add_f32_e32 v96, 1.0, v96
	v_add_f32_e32 v97, 1.0, v97
	v_rcp_f32_e32 v96, v96
	v_rcp_f32_e32 v97, v97
	v_pk_mul_f32 v[100:101], v[100:101], v[114:115] op_sel_hi:[1,0]
	v_pk_mul_f32 v[98:99], v[98:99], v[114:115] op_sel_hi:[1,0]
	v_mul_f32_e32 v100, 0xbfb8aa3b, v100
	v_mul_f32_e32 v101, 0xbfb8aa3b, v101
	v_exp_f32_e32 v100, v100
	v_exp_f32_e32 v101, v101
	v_add_f32_e32 v100, 1.0, v100
	v_add_f32_e32 v101, 1.0, v101
	v_rcp_f32_e32 v100, v100
; __device__ __forceinline__ unsigned cvt_pk_bf16(float lo, float hi) { const f32x2_cv v = {lo, hi}; const bf16x2_cv b = __builtin_convertvector(v, bf16x2_cv); return __builtin_bit_cast(unsigned, b); }
; __device__ __forceinline__ float sigm(float x) { return __builtin_amdgcn_rcpf(1.0f + __expf(-x)); }
; __device__ __forceinline__ float lo16(unsigned w) { return __uint_as_float(w << 16); }
; __device__ __forceinline__ float hi16(unsigned w) { return __uint_as_float(w & 0xffff0000u); }
; __device__ __forceinline__ float rstd_of(const float* rowss, int row) { return rsqrtf(rowss[row] * (1.0f / 1024.0f) + 1e-6f); }
;     __device__ __forceinline__ void operator()(const f32x4 (&acc)[2][2][4][2], const pg8::Unit& u, int wr, int wc, int fr, int fq) const {
;         const int row0 = u.pm * 256 + wr * 64 + fr, col0 = u.pn * 256 + wc * 32 + 8 * fq;
; #pragma unroll
;         for (int ai = 0; ai < 2; ++ai)
; #pragma unroll
;             for (int m = 0; m < 4; ++m) {
;                 const int row = row0 + ai * 128 + m * 16;
;                 const float s = rstd_of(rowss, row);
; #pragma unroll
;                 for (int bj = 0; bj < 2; ++bj) {
;                     const size_t off = (size_t)row * 1024 + col0 + bj * 128;
;                     const u32x4 tv = *(const u32x4*)(Tm + off);
;                     u32x4 pv = (u32x4){0u, 0u, 0u, 0u};
;                     if (ACC) pv = *(const u32x4*)(M + off);
;                     const f32x4 a0 = acc[ai][bj][m][0] * s, a1 = acc[ai][bj][m][1] * s;
;                     float o[8];
;                     o[0] = sigm(a0[0]) * lo16(tv.x); o[1] = sigm(a0[1]) * hi16(tv.x); o[2] = sigm(a0[2]) * lo16(tv.y); o[3] = sigm(a0[3]) * hi16(tv.y);
;                     o[4] = sigm(a1[0]) * lo16(tv.z); o[5] = sigm(a1[1]) * hi16(tv.z); o[6] = sigm(a1[2]) * lo16(tv.w); o[7] = sigm(a1[3]) * hi16(tv.w);
;                     if (ACC) { o[0] += lo16(pv.x); o[1] += hi16(pv.x); o[2] += lo16(pv.y); o[3] += hi16(pv.y); o[4] += lo16(pv.z); o[5] += hi16(pv.z); o[6] += lo16(pv.w); o[7] += hi16(pv.w); }
;                     u32x4 w; w.x = cvt_pk_bf16(o[0], o[1]); w.y = cvt_pk_bf16(o[2], o[3]); w.z = cvt_pk_bf16(o[4], o[5]); w.w = cvt_pk_bf16(o[6], o[7]);
;                     *(u32x4*)(M + off) = w; } }
;     }
	v_rcp_f32_e32 v101, v101
	v_lshlrev_b32_e32 v108, 16, v104
	v_and_b32_e32 v109, 0xffff0000, v104
	v_lshlrev_b32_e32 v104, 16, v105
	v_and_b32_e32 v105, 0xffff0000, v105
	v_pk_mul_f32 v[102:103], v[102:103], v[104:105]
	v_lshlrev_b32_e32 v104, 16, v106
	v_and_b32_e32 v105, 0xffff0000, v106
	v_pk_mul_f32 v[104:105], v[96:97], v[104:105]
	v_mul_f32_e32 v96, 0xbfb8aa3b, v98
	v_mul_f32_e32 v97, 0xbfb8aa3b, v99
	v_exp_f32_e32 v96, v96
	v_exp_f32_e32 v97, v97
	v_lshlrev_b32_e32 v98, 16, v107
	v_and_b32_e32 v99, 0xffff0000, v107
	v_add_f32_e32 v96, 1.0, v96
	v_add_f32_e32 v97, 1.0, v97
	v_rcp_f32_e32 v96, v96
	v_rcp_f32_e32 v97, v97
	v_pk_mul_f32 v[100:101], v[100:101], v[108:109]
	v_pk_mul_f32 v[106:107], v[96:97], v[98:99]
	v_cvt_pk_bf16_f32 v96, v100, v101
	v_cvt_pk_bf16_f32 v97, v102, v103
	v_cvt_pk_bf16_f32 v98, v104, v105
	v_cvt_pk_bf16_f32 v99, v106, v107
	global_store_dwordx4 v[112:113], v[96:99], off offset:256
	s_nop 1
	v_mov_b32_e32 v98, v181
	s_nop 0
	v_or_b32_e32 v96, 32, v162
	v_ashrrev_i32_e32 v97, 31, v96
	v_lshlrev_b64 v[96:97], 11, v[96:97]
	v_lshl_add_u64 v[96:97], s[0:1], 0, v[96:97]
	v_lshl_add_u64 v[96:97], v[96:97], 0, v[164:165]
	s_nop 1
	v_mov_b32_e32 v100, v208
	v_mov_b32_e32 v101, v209
	v_mov_b32_e32 v102, v210
	v_mov_b32_e32 v103, v211
	v_fmamk_f32 v98, v98, 0x3a800000, v187
	v_cmp_gt_f32_e32 vcc, s67, v98
	v_mul_f32_e32 v99, 0x4b800000, v98
	v_lshlrev_b32_e32 v104, 16, v100
	v_cndmask_b32_e32 v98, v98, v99, vcc
	v_rsq_f32_e32 v98, v98
	v_and_b32_e32 v105, 0xffff0000, v100
	v_lshlrev_b32_e32 v100, 16, v101
	v_and_b32_e32 v101, 0xffff0000, v101
	v_mul_f32_e32 v99, 0x45800000, v98
	v_cndmask_b32_e32 v98, v98, v99, vcc
	v_pk_mul_f32 v[94:95], v[94:95], v[98:99] op_sel_hi:[1,0]
	v_pk_mul_f32 v[88:89], v[88:89], v[98:99] op_sel_hi:[1,0]
	v_mul_f32_e32 v94, 0xbfb8aa3b, v94
	v_mul_f32_e32 v95, 0xbfb8aa3b, v95
	v_exp_f32_e32 v94, v94
	v_exp_f32_e32 v95, v95
	v_mul_f32_e32 v88, 0xbfb8aa3b, v88
	v_mul_f32_e32 v89, 0xbfb8aa3b, v89
	v_exp_f32_e32 v88, v88
	v_exp_f32_e32 v89, v89
	v_add_f32_e32 v94, 1.0, v94
	v_add_f32_e32 v95, 1.0, v95
	v_rcp_f32_e32 v94, v94
	v_rcp_f32_e32 v95, v95
	v_add_f32_e32 v88, 1.0, v88
	v_add_f32_e32 v89, 1.0, v89
	v_rcp_f32_e32 v88, v88
	v_rcp_f32_e32 v89, v89
	v_pk_mul_f32 v[92:93], v[92:93], v[98:99] op_sel_hi:[1,0]
	v_pk_mul_f32 v[90:91], v[90:91], v[98:99] op_sel_hi:[1,0]
	v_pk_mul_f32 v[94:95], v[94:95], v[100:101]
	v_lshlrev_b32_e32 v100, 16, v102
	v_and_b32_e32 v101, 0xffff0000, v102
	v_mul_f32_e32 v92, 0xbfb8aa3b, v92
	v_mul_f32_e32 v93, 0xbfb8aa3b, v93
	v_pk_mul_f32 v[100:101], v[88:89], v[100:101]
	v_mul_f32_e32 v88, 0xbfb8aa3b, v90
	v_mul_f32_e32 v89, 0xbfb8aa3b, v91
	v_exp_f32_e32 v92, v92
	v_exp_f32_e32 v93, v93
	v_exp_f32_e32 v88, v88
	v_exp_f32_e32 v89, v89
	v_add_f32_e32 v92, 1.0, v92
	v_add_f32_e32 v93, 1.0, v93
	v_add_f32_e32 v88, 1.0, v88
	v_add_f32_e32 v89, 1.0, v89
	v_rcp_f32_e32 v92, v92
	v_rcp_f32_e32 v93, v93
	v_rcp_f32_e32 v88, v88
	v_rcp_f32_e32 v89, v89
	v_lshlrev_b32_e32 v90, 16, v103
	v_and_b32_e32 v91, 0xffff0000, v103
	v_pk_mul_f32 v[92:93], v[92:93], v[104:105]
	v_pk_mul_f32 v[102:103], v[88:89], v[90:91]
	v_cvt_pk_bf16_f32 v88, v92, v93
	v_cvt_pk_bf16_f32 v89, v94, v95
	v_cvt_pk_bf16_f32 v90, v100, v101
	v_cvt_pk_bf16_f32 v91, v102, v103
	global_store_dwordx4 v[96:97], v[88:91], off
	s_nop 1
	v_mov_b32_e32 v88, v212
	v_mov_b32_e32 v89, v213
	v_mov_b32_e32 v90, v214
	v_mov_b32_e32 v91, v215
	v_pk_mul_f32 v[86:87], v[86:87], v[98:99] op_sel_hi:[1,0]
	v_pk_mul_f32 v[80:81], v[80:81], v[98:99] op_sel_hi:[1,0]
	v_mul_f32_e32 v86, 0xbfb8aa3b, v86
	v_mul_f32_e32 v87, 0xbfb8aa3b, v87
	v_exp_f32_e32 v86, v86
	v_exp_f32_e32 v87, v87
	v_mul_f32_e32 v80, 0xbfb8aa3b, v80
	v_mul_f32_e32 v81, 0xbfb8aa3b, v81
	v_exp_f32_e32 v80, v80
	v_exp_f32_e32 v81, v81
	v_add_f32_e32 v86, 1.0, v86
	v_add_f32_e32 v87, 1.0, v87
	v_rcp_f32_e32 v86, v86
	v_rcp_f32_e32 v87, v87
	v_add_f32_e32 v80, 1.0, v80
	v_add_f32_e32 v81, 1.0, v81
	v_rcp_f32_e32 v80, v80
	v_rcp_f32_e32 v81, v81
	v_pk_mul_f32 v[84:85], v[84:85], v[98:99] op_sel_hi:[1,0]
	v_pk_mul_f32 v[82:83], v[82:83], v[98:99] op_sel_hi:[1,0]
	v_mul_f32_e32 v84, 0xbfb8aa3b, v84
	v_mul_f32_e32 v85, 0xbfb8aa3b, v85
	v_exp_f32_e32 v84, v84
	v_exp_f32_e32 v85, v85
	v_add_f32_e32 v84, 1.0, v84
	v_add_f32_e32 v85, 1.0, v85
	v_rcp_f32_e32 v84, v84
	v_rcp_f32_e32 v85, v85
	v_lshlrev_b32_e32 v92, 16, v88
	v_and_b32_e32 v93, 0xffff0000, v88
	v_lshlrev_b32_e32 v88, 16, v89
	v_and_b32_e32 v89, 0xffff0000, v89
	v_pk_mul_f32 v[86:87], v[86:87], v[88:89]
	v_lshlrev_b32_e32 v88, 16, v90
	v_and_b32_e32 v89, 0xffff0000, v90
	v_pk_mul_f32 v[88:89], v[80:81], v[88:89]
	v_mul_f32_e32 v80, 0xbfb8aa3b, v82
	v_mul_f32_e32 v81, 0xbfb8aa3b, v83
	v_exp_f32_e32 v80, v80
	v_exp_f32_e32 v81, v81
	v_lshlrev_b32_e32 v82, 16, v91
	v_and_b32_e32 v83, 0xffff0000, v91
	v_add_f32_e32 v80, 1.0, v80
	v_add_f32_e32 v81, 1.0, v81
	v_rcp_f32_e32 v80, v80
	v_rcp_f32_e32 v81, v81
	v_pk_mul_f32 v[84:85], v[84:85], v[92:93]
	v_pk_mul_f32 v[90:91], v[80:81], v[82:83]
	v_cvt_pk_bf16_f32 v80, v84, v85
	v_cvt_pk_bf16_f32 v81, v86, v87
	v_cvt_pk_bf16_f32 v82, v88, v89
	v_cvt_pk_bf16_f32 v83, v90, v91
	global_store_dwordx4 v[96:97], v[80:83], off offset:256
	s_nop 1
	v_mov_b32_e32 v82, v182
	s_nop 0
	v_or_b32_e32 v80, 48, v162
	v_ashrrev_i32_e32 v81, 31, v80
	v_lshlrev_b64 v[80:81], 11, v[80:81]
	v_lshl_add_u64 v[80:81], s[0:1], 0, v[80:81]
	v_lshl_add_u64 v[80:81], v[80:81], 0, v[164:165]
	s_nop 1
	v_mov_b32_e32 v84, v216
	v_mov_b32_e32 v85, v217
	v_mov_b32_e32 v86, v218
	v_mov_b32_e32 v87, v219
	v_fmamk_f32 v82, v82, 0x3a800000, v187
	v_cmp_gt_f32_e32 vcc, s67, v82
	v_mul_f32_e32 v83, 0x4b800000, v82
; __device__ __forceinline__ unsigned cvt_pk_bf16(float lo, float hi) { const f32x2_cv v = {lo, hi}; const bf16x2_cv b = __builtin_convertvector(v, bf16x2_cv); return __builtin_bit_cast(unsigned, b); }
; __device__ __forceinline__ float sigm(float x) { return __builtin_amdgcn_rcpf(1.0f + __expf(-x)); }
; __device__ __forceinline__ float lo16(unsigned w) { return __uint_as_float(w << 16); }
; __device__ __forceinline__ float hi16(unsigned w) { return __uint_as_float(w & 0xffff0000u); }
; __device__ __forceinline__ float rstd_of(const float* rowss, int row) { return rsqrtf(rowss[row] * (1.0f / 1024.0f) + 1e-6f); }
;     __device__ __forceinline__ void operator()(const f32x4 (&acc)[2][2][4][2], const pg8::Unit& u, int wr, int wc, int fr, int fq) const {
;         const int row0 = u.pm * 256 + wr * 64 + fr, col0 = u.pn * 256 + wc * 32 + 8 * fq;
; #pragma unroll
;         for (int ai = 0; ai < 2; ++ai)
; #pragma unroll
;             for (int m = 0; m < 4; ++m) {
;                 const int row = row0 + ai * 128 + m * 16;
;                 const float s = rstd_of(rowss, row);
; #pragma unroll
;                 for (int bj = 0; bj < 2; ++bj) {
;                     const size_t off = (size_t)row * 1024 + col0 + bj * 128;
;                     const u32x4 tv = *(const u32x4*)(Tm + off);
;                     u32x4 pv = (u32x4){0u, 0u, 0u, 0u};
;                     if (ACC) pv = *(const u32x4*)(M + off);
;                     const f32x4 a0 = acc[ai][bj][m][0] * s, a1 = acc[ai][bj][m][1] * s;
;                     float o[8];
;                     o[0] = sigm(a0[0]) * lo16(tv.x); o[1] = sigm(a0[1]) * hi16(tv.x); o[2] = sigm(a0[2]) * lo16(tv.y); o[3] = sigm(a0[3]) * hi16(tv.y);
;                     o[4] = sigm(a1[0]) * lo16(tv.z); o[5] = sigm(a1[1]) * hi16(tv.z); o[6] = sigm(a1[2]) * lo16(tv.w); o[7] = sigm(a1[3]) * hi16(tv.w);
;                     if (ACC) { o[0] += lo16(pv.x); o[1] += hi16(pv.x); o[2] += lo16(pv.y); o[3] += hi16(pv.y); o[4] += lo16(pv.z); o[5] += hi16(pv.z); o[6] += lo16(pv.w); o[7] += hi16(pv.w); }
;                     u32x4 w; w.x = cvt_pk_bf16(o[0], o[1]); w.y = cvt_pk_bf16(o[2], o[3]); w.z = cvt_pk_bf16(o[4], o[5]); w.w = cvt_pk_bf16(o[6], o[7]);
;                     *(u32x4*)(M + off) = w; } }
;     }
	v_lshlrev_b32_e32 v88, 16, v84
	v_cndmask_b32_e32 v82, v82, v83, vcc
	v_rsq_f32_e32 v82, v82
	v_and_b32_e32 v89, 0xffff0000, v84
	v_lshlrev_b32_e32 v84, 16, v85
	v_and_b32_e32 v85, 0xffff0000, v85
	v_mul_f32_e32 v83, 0x45800000, v82
	v_cndmask_b32_e32 v82, v82, v83, vcc
	v_pk_mul_f32 v[78:79], v[78:79], v[82:83] op_sel_hi:[1,0]
	v_pk_mul_f32 v[72:73], v[72:73], v[82:83] op_sel_hi:[1,0]
	v_mul_f32_e32 v78, 0xbfb8aa3b, v78
	v_mul_f32_e32 v79, 0xbfb8aa3b, v79
	v_exp_f32_e32 v78, v78
	v_exp_f32_e32 v79, v79
	v_mul_f32_e32 v72, 0xbfb8aa3b, v72
	v_mul_f32_e32 v73, 0xbfb8aa3b, v73
	v_exp_f32_e32 v72, v72
	v_exp_f32_e32 v73, v73
	v_add_f32_e32 v78, 1.0, v78
	v_add_f32_e32 v79, 1.0, v79
	v_rcp_f32_e32 v78, v78
	v_rcp_f32_e32 v79, v79
	v_add_f32_e32 v72, 1.0, v72
	v_add_f32_e32 v73, 1.0, v73
	v_rcp_f32_e32 v72, v72
	v_rcp_f32_e32 v73, v73
	v_pk_mul_f32 v[76:77], v[76:77], v[82:83] op_sel_hi:[1,0]
	v_pk_mul_f32 v[74:75], v[74:75], v[82:83] op_sel_hi:[1,0]
	v_pk_mul_f32 v[78:79], v[78:79], v[84:85]
	v_lshlrev_b32_e32 v84, 16, v86
	v_and_b32_e32 v85, 0xffff0000, v86
	v_mul_f32_e32 v76, 0xbfb8aa3b, v76
	v_mul_f32_e32 v77, 0xbfb8aa3b, v77
	v_pk_mul_f32 v[84:85], v[72:73], v[84:85]
	v_mul_f32_e32 v72, 0xbfb8aa3b, v74
	v_mul_f32_e32 v73, 0xbfb8aa3b, v75
	v_exp_f32_e32 v76, v76
	v_exp_f32_e32 v77, v77
	v_exp_f32_e32 v72, v72
	v_exp_f32_e32 v73, v73
	v_add_f32_e32 v76, 1.0, v76
	v_add_f32_e32 v77, 1.0, v77
	v_add_f32_e32 v72, 1.0, v72
	v_add_f32_e32 v73, 1.0, v73
	v_rcp_f32_e32 v76, v76
	v_rcp_f32_e32 v77, v77
	v_rcp_f32_e32 v72, v72
	v_rcp_f32_e32 v73, v73
	v_lshlrev_b32_e32 v74, 16, v87
	v_and_b32_e32 v75, 0xffff0000, v87
	v_pk_mul_f32 v[76:77], v[76:77], v[88:89]
	v_pk_mul_f32 v[86:87], v[72:73], v[74:75]
	v_cvt_pk_bf16_f32 v72, v76, v77
	v_cvt_pk_bf16_f32 v73, v78, v79
	v_cvt_pk_bf16_f32 v74, v84, v85
	v_cvt_pk_bf16_f32 v75, v86, v87
	global_store_dwordx4 v[80:81], v[72:75], off
	s_nop 1
	v_mov_b32_e32 v72, v220
	v_mov_b32_e32 v73, v221
	v_mov_b32_e32 v74, v222
	v_mov_b32_e32 v75, v223
	v_pk_mul_f32 v[70:71], v[70:71], v[82:83] op_sel_hi:[1,0]
	v_pk_mul_f32 v[64:65], v[64:65], v[82:83] op_sel_hi:[1,0]
	v_mul_f32_e32 v70, 0xbfb8aa3b, v70
	v_mul_f32_e32 v71, 0xbfb8aa3b, v71
	v_exp_f32_e32 v70, v70
	v_exp_f32_e32 v71, v71
	v_mul_f32_e32 v64, 0xbfb8aa3b, v64
	v_mul_f32_e32 v65, 0xbfb8aa3b, v65
	v_exp_f32_e32 v64, v64
	v_exp_f32_e32 v65, v65
	v_add_f32_e32 v70, 1.0, v70
	v_add_f32_e32 v71, 1.0, v71
	v_rcp_f32_e32 v70, v70
	v_rcp_f32_e32 v71, v71
	v_add_f32_e32 v64, 1.0, v64
	v_add_f32_e32 v65, 1.0, v65
	v_rcp_f32_e32 v64, v64
	v_rcp_f32_e32 v65, v65
	v_pk_mul_f32 v[68:69], v[68:69], v[82:83] op_sel_hi:[1,0]
	v_pk_mul_f32 v[66:67], v[66:67], v[82:83] op_sel_hi:[1,0]
	v_mul_f32_e32 v68, 0xbfb8aa3b, v68
	v_mul_f32_e32 v69, 0xbfb8aa3b, v69
	v_exp_f32_e32 v68, v68
	v_exp_f32_e32 v69, v69
	v_add_f32_e32 v68, 1.0, v68
	v_add_f32_e32 v69, 1.0, v69
	v_rcp_f32_e32 v68, v68
	v_rcp_f32_e32 v69, v69
	v_lshlrev_b32_e32 v76, 16, v72
	v_and_b32_e32 v77, 0xffff0000, v72
	v_lshlrev_b32_e32 v72, 16, v73
	v_and_b32_e32 v73, 0xffff0000, v73
	v_pk_mul_f32 v[70:71], v[70:71], v[72:73]
	v_lshlrev_b32_e32 v72, 16, v74
	v_and_b32_e32 v73, 0xffff0000, v74
	v_pk_mul_f32 v[72:73], v[64:65], v[72:73]
	v_mul_f32_e32 v64, 0xbfb8aa3b, v66
	v_mul_f32_e32 v65, 0xbfb8aa3b, v67
	v_exp_f32_e32 v64, v64
	v_exp_f32_e32 v65, v65
	v_lshlrev_b32_e32 v66, 16, v75
	v_and_b32_e32 v67, 0xffff0000, v75
	v_add_f32_e32 v64, 1.0, v64
	v_add_f32_e32 v65, 1.0, v65
	v_rcp_f32_e32 v64, v64
	v_rcp_f32_e32 v65, v65
	v_pk_mul_f32 v[68:69], v[68:69], v[76:77]
	v_pk_mul_f32 v[74:75], v[64:65], v[66:67]
	v_cvt_pk_bf16_f32 v64, v68, v69
	v_cvt_pk_bf16_f32 v65, v70, v71
	v_cvt_pk_bf16_f32 v66, v72, v73
	v_cvt_pk_bf16_f32 v67, v74, v75
	global_store_dwordx4 v[80:81], v[64:67], off offset:256
	s_nop 1
	v_mov_b32_e32 v64, v183
	v_fmamk_f32 v64, v64, 0x3a800000, v187
	v_cmp_gt_f32_e32 vcc, s67, v64
	v_mul_f32_e32 v65, 0x4b800000, v64
	s_nop 0
	v_cndmask_b32_e32 v64, v64, v65, vcc
	v_rsq_f32_e32 v64, v64
	s_nop 0
	v_mul_f32_e32 v65, 0x45800000, v64
	v_cndmask_b32_e32 v66, v64, v65, vcc
	v_add_co_u32_e32 v72, vcc, s2, v158
	v_pk_mul_f32 v[62:63], v[62:63], v[66:67] op_sel_hi:[1,0]
	s_nop 0
	v_addc_co_u32_e32 v73, vcc, 0, v159, vcc
	s_nop 1
	v_mov_b32_e32 v68, v224
	v_mov_b32_e32 v69, v225
	v_mov_b32_e32 v70, v226
	v_mov_b32_e32 v71, v227
	v_pk_mul_f32 v[56:57], v[56:57], v[66:67] op_sel_hi:[1,0]
	v_mul_f32_e32 v62, 0xbfb8aa3b, v62
	v_mul_f32_e32 v63, 0xbfb8aa3b, v63
	v_exp_f32_e32 v62, v62
	v_exp_f32_e32 v63, v63
	v_mul_f32_e32 v56, 0xbfb8aa3b, v56
	v_mul_f32_e32 v57, 0xbfb8aa3b, v57
	v_exp_f32_e32 v56, v56
	v_exp_f32_e32 v57, v57
	v_add_f32_e32 v62, 1.0, v62
	v_add_f32_e32 v63, 1.0, v63
	v_rcp_f32_e32 v62, v62
	v_rcp_f32_e32 v63, v63
	v_add_f32_e32 v56, 1.0, v56
	v_add_f32_e32 v57, 1.0, v57
	v_rcp_f32_e32 v56, v56
	v_rcp_f32_e32 v57, v57
	v_pk_mul_f32 v[60:61], v[60:61], v[66:67] op_sel_hi:[1,0]
	v_pk_mul_f32 v[58:59], v[58:59], v[66:67] op_sel_hi:[1,0]
	v_mul_f32_e32 v60, 0xbfb8aa3b, v60
	v_mul_f32_e32 v61, 0xbfb8aa3b, v61
	v_exp_f32_e32 v60, v60
	v_exp_f32_e32 v61, v61
	v_lshl_add_u64 v[64:65], v[158:159], 0, s[4:5]
	v_pk_mul_f32 v[54:55], v[54:55], v[66:67] op_sel_hi:[1,0]
	v_add_f32_e32 v60, 1.0, v60
	v_add_f32_e32 v61, 1.0, v61
	v_rcp_f32_e32 v60, v60
	v_rcp_f32_e32 v61, v61
	v_pk_mul_f32 v[48:49], v[48:49], v[66:67] op_sel_hi:[1,0]
	v_mul_f32_e32 v54, 0xbfb8aa3b, v54
	v_mul_f32_e32 v55, 0xbfb8aa3b, v55
	v_exp_f32_e32 v54, v54
	v_exp_f32_e32 v55, v55
	v_mul_f32_e32 v48, 0xbfb8aa3b, v48
	v_mul_f32_e32 v49, 0xbfb8aa3b, v49
	v_exp_f32_e32 v48, v48
	v_exp_f32_e32 v49, v49
	v_add_f32_e32 v54, 1.0, v54
	v_add_f32_e32 v55, 1.0, v55
; __device__ __forceinline__ unsigned cvt_pk_bf16(float lo, float hi) { const f32x2_cv v = {lo, hi}; const bf16x2_cv b = __builtin_convertvector(v, bf16x2_cv); return __builtin_bit_cast(unsigned, b); }
; __device__ __forceinline__ float sigm(float x) { return __builtin_amdgcn_rcpf(1.0f + __expf(-x)); }
; __device__ __forceinline__ float lo16(unsigned w) { return __uint_as_float(w << 16); }
; __device__ __forceinline__ float hi16(unsigned w) { return __uint_as_float(w & 0xffff0000u); }
; __device__ __forceinline__ float rstd_of(const float* rowss, int row) { return rsqrtf(rowss[row] * (1.0f / 1024.0f) + 1e-6f); }
;     __device__ __forceinline__ void operator()(const f32x4 (&acc)[2][2][4][2], const pg8::Unit& u, int wr, int wc, int fr, int fq) const {
;         const int row0 = u.pm * 256 + wr * 64 + fr, col0 = u.pn * 256 + wc * 32 + 8 * fq;
; #pragma unroll
;         for (int ai = 0; ai < 2; ++ai)
; #pragma unroll
;             for (int m = 0; m < 4; ++m) {
;                 const int row = row0 + ai * 128 + m * 16;
;                 const float s = rstd_of(rowss, row);
; #pragma unroll
;                 for (int bj = 0; bj < 2; ++bj) {
;                     const size_t off = (size_t)row * 1024 + col0 + bj * 128;
;                     const u32x4 tv = *(const u32x4*)(Tm + off);
;                     u32x4 pv = (u32x4){0u, 0u, 0u, 0u};
;                     if (ACC) pv = *(const u32x4*)(M + off);
;                     const f32x4 a0 = acc[ai][bj][m][0] * s, a1 = acc[ai][bj][m][1] * s;
;                     float o[8];
;                     o[0] = sigm(a0[0]) * lo16(tv.x); o[1] = sigm(a0[1]) * hi16(tv.x); o[2] = sigm(a0[2]) * lo16(tv.y); o[3] = sigm(a0[3]) * hi16(tv.y);
;                     o[4] = sigm(a1[0]) * lo16(tv.z); o[5] = sigm(a1[1]) * hi16(tv.z); o[6] = sigm(a1[2]) * lo16(tv.w); o[7] = sigm(a1[3]) * hi16(tv.w);
;                     if (ACC) { o[0] += lo16(pv.x); o[1] += hi16(pv.x); o[2] += lo16(pv.y); o[3] += hi16(pv.y); o[4] += lo16(pv.z); o[5] += hi16(pv.z); o[6] += lo16(pv.w); o[7] += hi16(pv.w); }
;                     u32x4 w; w.x = cvt_pk_bf16(o[0], o[1]); w.y = cvt_pk_bf16(o[2], o[3]); w.z = cvt_pk_bf16(o[4], o[5]); w.w = cvt_pk_bf16(o[6], o[7]);
;                     *(u32x4*)(M + off) = w; } }
;     }
	v_rcp_f32_e32 v54, v54
	v_rcp_f32_e32 v55, v55
	v_add_f32_e32 v48, 1.0, v48
	v_add_f32_e32 v49, 1.0, v49
	v_rcp_f32_e32 v48, v48
	v_rcp_f32_e32 v49, v49
	v_pk_mul_f32 v[52:53], v[52:53], v[66:67] op_sel_hi:[1,0]
	v_pk_mul_f32 v[50:51], v[50:51], v[66:67] op_sel_hi:[1,0]
	v_mul_f32_e32 v52, 0xbfb8aa3b, v52
	v_mul_f32_e32 v53, 0xbfb8aa3b, v53
	v_exp_f32_e32 v52, v52
	v_exp_f32_e32 v53, v53
	s_mov_b32 s2, 0x48000
	s_mov_b64 s[4:5], 0x48000
	v_add_f32_e32 v52, 1.0, v52
	v_add_f32_e32 v53, 1.0, v53
	v_rcp_f32_e32 v52, v52
	v_rcp_f32_e32 v53, v53
	v_lshlrev_b32_e32 v74, 16, v68
	v_and_b32_e32 v75, 0xffff0000, v68
	v_lshlrev_b32_e32 v68, 16, v69
	v_and_b32_e32 v69, 0xffff0000, v69
	v_pk_mul_f32 v[62:63], v[62:63], v[68:69]
	v_lshlrev_b32_e32 v68, 16, v70
	v_and_b32_e32 v69, 0xffff0000, v70
	v_pk_mul_f32 v[68:69], v[56:57], v[68:69]
	v_mul_f32_e32 v56, 0xbfb8aa3b, v58
	v_mul_f32_e32 v57, 0xbfb8aa3b, v59
	v_exp_f32_e32 v56, v56
	v_exp_f32_e32 v57, v57
	v_lshlrev_b32_e32 v58, 16, v71
	v_and_b32_e32 v59, 0xffff0000, v71
	v_add_f32_e32 v56, 1.0, v56
	v_add_f32_e32 v57, 1.0, v57
	v_rcp_f32_e32 v56, v56
	v_rcp_f32_e32 v57, v57
	v_pk_mul_f32 v[60:61], v[60:61], v[74:75]
	v_pk_mul_f32 v[70:71], v[56:57], v[58:59]
	v_cvt_pk_bf16_f32 v56, v60, v61
	v_cvt_pk_bf16_f32 v57, v62, v63
	v_cvt_pk_bf16_f32 v58, v68, v69
	v_cvt_pk_bf16_f32 v59, v70, v71
	global_store_dwordx4 v[72:73], v[56:59], off
	s_nop 1
	v_mov_b32_e32 v56, v228
	v_mov_b32_e32 v57, v229
	v_mov_b32_e32 v58, v230
	v_mov_b32_e32 v59, v231
	v_lshlrev_b32_e32 v60, 16, v56
	v_and_b32_e32 v61, 0xffff0000, v56
	v_lshlrev_b32_e32 v56, 16, v57
	v_and_b32_e32 v57, 0xffff0000, v57
	v_pk_mul_f32 v[54:55], v[54:55], v[56:57]
	v_lshlrev_b32_e32 v56, 16, v58
	v_and_b32_e32 v57, 0xffff0000, v58
	v_pk_mul_f32 v[56:57], v[48:49], v[56:57]
	v_mul_f32_e32 v48, 0xbfb8aa3b, v50
	v_mul_f32_e32 v49, 0xbfb8aa3b, v51
	v_exp_f32_e32 v48, v48
	v_exp_f32_e32 v49, v49
	v_lshlrev_b32_e32 v50, 16, v59
	v_and_b32_e32 v51, 0xffff0000, v59
	v_add_f32_e32 v48, 1.0, v48
	v_add_f32_e32 v49, 1.0, v49
	v_rcp_f32_e32 v48, v48
	v_rcp_f32_e32 v49, v49
	v_pk_mul_f32 v[52:53], v[52:53], v[60:61]
	v_pk_mul_f32 v[58:59], v[48:49], v[50:51]
	v_cvt_pk_bf16_f32 v48, v52, v53
	v_cvt_pk_bf16_f32 v49, v54, v55
	v_cvt_pk_bf16_f32 v50, v56, v57
	v_cvt_pk_bf16_f32 v51, v58, v59
	global_store_dwordx4 v[64:65], v[48:51], off offset:256
	s_nop 1
	v_mov_b32_e32 v48, v240
	v_fmamk_f32 v48, v48, 0x3a800000, v187
	v_cmp_gt_f32_e32 vcc, s67, v48
	v_mul_f32_e32 v49, 0x4b800000, v48
	s_nop 0
	v_cndmask_b32_e32 v48, v48, v49, vcc
	v_rsq_f32_e32 v48, v48
	s_nop 0
	v_mul_f32_e32 v49, 0x45800000, v48
	v_cndmask_b32_e32 v50, v48, v49, vcc
	v_add_co_u32_e32 v56, vcc, s2, v158
	v_pk_mul_f32 v[46:47], v[46:47], v[50:51] op_sel_hi:[1,0]
	s_nop 0
	v_addc_co_u32_e32 v57, vcc, 0, v159, vcc
	s_nop 1
	v_mov_b32_e32 v52, v232
	v_mov_b32_e32 v53, v233
	v_mov_b32_e32 v54, v234
	v_mov_b32_e32 v55, v235
	v_pk_mul_f32 v[40:41], v[40:41], v[50:51] op_sel_hi:[1,0]
	v_mul_f32_e32 v46, 0xbfb8aa3b, v46
	v_mul_f32_e32 v47, 0xbfb8aa3b, v47
	v_exp_f32_e32 v46, v46
	v_exp_f32_e32 v47, v47
	v_mul_f32_e32 v40, 0xbfb8aa3b, v40
	v_mul_f32_e32 v41, 0xbfb8aa3b, v41
	v_exp_f32_e32 v40, v40
	v_exp_f32_e32 v41, v41
	v_add_f32_e32 v46, 1.0, v46
	v_add_f32_e32 v47, 1.0, v47
	v_rcp_f32_e32 v46, v46
	v_rcp_f32_e32 v47, v47
	v_add_f32_e32 v40, 1.0, v40
	v_add_f32_e32 v41, 1.0, v41
	v_rcp_f32_e32 v40, v40
	v_rcp_f32_e32 v41, v41
	v_pk_mul_f32 v[44:45], v[44:45], v[50:51] op_sel_hi:[1,0]
	v_pk_mul_f32 v[42:43], v[42:43], v[50:51] op_sel_hi:[1,0]
	v_mul_f32_e32 v44, 0xbfb8aa3b, v44
	v_mul_f32_e32 v45, 0xbfb8aa3b, v45
	v_exp_f32_e32 v44, v44
	v_exp_f32_e32 v45, v45
	v_lshl_add_u64 v[48:49], v[158:159], 0, s[4:5]
	v_pk_mul_f32 v[38:39], v[38:39], v[50:51] op_sel_hi:[1,0]
	v_add_f32_e32 v44, 1.0, v44
	v_add_f32_e32 v45, 1.0, v45
	v_rcp_f32_e32 v44, v44
	v_rcp_f32_e32 v45, v45
	v_pk_mul_f32 v[32:33], v[32:33], v[50:51] op_sel_hi:[1,0]
	v_mul_f32_e32 v38, 0xbfb8aa3b, v38
	v_mul_f32_e32 v39, 0xbfb8aa3b, v39
	v_exp_f32_e32 v38, v38
	v_exp_f32_e32 v39, v39
	v_mul_f32_e32 v32, 0xbfb8aa3b, v32
	v_mul_f32_e32 v33, 0xbfb8aa3b, v33
	v_exp_f32_e32 v32, v32
	v_exp_f32_e32 v33, v33
	v_add_f32_e32 v38, 1.0, v38
	v_add_f32_e32 v39, 1.0, v39
	v_rcp_f32_e32 v38, v38
	v_rcp_f32_e32 v39, v39
	v_add_f32_e32 v32, 1.0, v32
	v_add_f32_e32 v33, 1.0, v33
	v_rcp_f32_e32 v32, v32
	v_rcp_f32_e32 v33, v33
	v_pk_mul_f32 v[36:37], v[36:37], v[50:51] op_sel_hi:[1,0]
	v_pk_mul_f32 v[34:35], v[34:35], v[50:51] op_sel_hi:[1,0]
	v_mul_f32_e32 v36, 0xbfb8aa3b, v36
	v_mul_f32_e32 v37, 0xbfb8aa3b, v37
	v_exp_f32_e32 v36, v36
	v_exp_f32_e32 v37, v37
	s_mov_b32 s2, 0x50000
	s_mov_b64 s[4:5], 0x50000
	v_add_f32_e32 v36, 1.0, v36
	v_add_f32_e32 v37, 1.0, v37
	v_rcp_f32_e32 v36, v36
	v_rcp_f32_e32 v37, v37
	v_lshlrev_b32_e32 v58, 16, v52
	v_and_b32_e32 v59, 0xffff0000, v52
	v_lshlrev_b32_e32 v52, 16, v53
	v_and_b32_e32 v53, 0xffff0000, v53
	v_pk_mul_f32 v[46:47], v[46:47], v[52:53]
	v_lshlrev_b32_e32 v52, 16, v54
	v_and_b32_e32 v53, 0xffff0000, v54
	v_pk_mul_f32 v[52:53], v[40:41], v[52:53]
	v_mul_f32_e32 v40, 0xbfb8aa3b, v42
	v_mul_f32_e32 v41, 0xbfb8aa3b, v43
	v_exp_f32_e32 v40, v40
	v_exp_f32_e32 v41, v41
	v_lshlrev_b32_e32 v42, 16, v55
	v_and_b32_e32 v43, 0xffff0000, v55
	v_add_f32_e32 v40, 1.0, v40
	v_add_f32_e32 v41, 1.0, v41
	v_rcp_f32_e32 v40, v40
	v_rcp_f32_e32 v41, v41
	v_pk_mul_f32 v[44:45], v[44:45], v[58:59]
	v_pk_mul_f32 v[54:55], v[40:41], v[42:43]
	v_cvt_pk_bf16_f32 v40, v44, v45
	v_cvt_pk_bf16_f32 v41, v46, v47
	v_cvt_pk_bf16_f32 v42, v52, v53
	v_cvt_pk_bf16_f32 v43, v54, v55
	global_store_dwordx4 v[56:57], v[40:43], off
	s_nop 1
; __device__ __forceinline__ unsigned cvt_pk_bf16(float lo, float hi) { const f32x2_cv v = {lo, hi}; const bf16x2_cv b = __builtin_convertvector(v, bf16x2_cv); return __builtin_bit_cast(unsigned, b); }
; __device__ __forceinline__ float sigm(float x) { return __builtin_amdgcn_rcpf(1.0f + __expf(-x)); }
; __device__ __forceinline__ float lo16(unsigned w) { return __uint_as_float(w << 16); }
; __device__ __forceinline__ float hi16(unsigned w) { return __uint_as_float(w & 0xffff0000u); }
; __device__ __forceinline__ float rstd_of(const float* rowss, int row) { return rsqrtf(rowss[row] * (1.0f / 1024.0f) + 1e-6f); }
;     __device__ __forceinline__ void operator()(const f32x4 (&acc)[2][2][4][2], const pg8::Unit& u, int wr, int wc, int fr, int fq) const {
;         const int row0 = u.pm * 256 + wr * 64 + fr, col0 = u.pn * 256 + wc * 32 + 8 * fq;
; #pragma unroll
;         for (int ai = 0; ai < 2; ++ai)
; #pragma unroll
;             for (int m = 0; m < 4; ++m) {
;                 const int row = row0 + ai * 128 + m * 16;
;                 const float s = rstd_of(rowss, row);
; #pragma unroll
;                 for (int bj = 0; bj < 2; ++bj) {
;                     const size_t off = (size_t)row * 1024 + col0 + bj * 128;
;                     const u32x4 tv = *(const u32x4*)(Tm + off);
;                     u32x4 pv = (u32x4){0u, 0u, 0u, 0u};
;                     if (ACC) pv = *(const u32x4*)(M + off);
;                     const f32x4 a0 = acc[ai][bj][m][0] * s, a1 = acc[ai][bj][m][1] * s;
;                     float o[8];
;                     o[0] = sigm(a0[0]) * lo16(tv.x); o[1] = sigm(a0[1]) * hi16(tv.x); o[2] = sigm(a0[2]) * lo16(tv.y); o[3] = sigm(a0[3]) * hi16(tv.y);
;                     o[4] = sigm(a1[0]) * lo16(tv.z); o[5] = sigm(a1[1]) * hi16(tv.z); o[6] = sigm(a1[2]) * lo16(tv.w); o[7] = sigm(a1[3]) * hi16(tv.w);
;                     if (ACC) { o[0] += lo16(pv.x); o[1] += hi16(pv.x); o[2] += lo16(pv.y); o[3] += hi16(pv.y); o[4] += lo16(pv.z); o[5] += hi16(pv.z); o[6] += lo16(pv.w); o[7] += hi16(pv.w); }
;                     u32x4 w; w.x = cvt_pk_bf16(o[0], o[1]); w.y = cvt_pk_bf16(o[2], o[3]); w.z = cvt_pk_bf16(o[4], o[5]); w.w = cvt_pk_bf16(o[6], o[7]);
;                     *(u32x4*)(M + off) = w; } }
;     }
	v_mov_b32_e32 v40, v236
	v_mov_b32_e32 v41, v237
	v_mov_b32_e32 v42, v238
	v_mov_b32_e32 v43, v239
	v_lshlrev_b32_e32 v44, 16, v40
	v_and_b32_e32 v45, 0xffff0000, v40
	v_lshlrev_b32_e32 v40, 16, v41
	v_and_b32_e32 v41, 0xffff0000, v41
	v_pk_mul_f32 v[38:39], v[38:39], v[40:41]
	v_lshlrev_b32_e32 v40, 16, v42
	v_and_b32_e32 v41, 0xffff0000, v42
	v_pk_mul_f32 v[40:41], v[32:33], v[40:41]
	v_mul_f32_e32 v32, 0xbfb8aa3b, v34
	v_mul_f32_e32 v33, 0xbfb8aa3b, v35
	v_exp_f32_e32 v32, v32
	v_exp_f32_e32 v33, v33
	v_lshlrev_b32_e32 v34, 16, v43
	v_and_b32_e32 v35, 0xffff0000, v43
	v_add_f32_e32 v32, 1.0, v32
	v_add_f32_e32 v33, 1.0, v33
	v_rcp_f32_e32 v32, v32
	v_rcp_f32_e32 v33, v33
	v_pk_mul_f32 v[36:37], v[36:37], v[44:45]
	v_pk_mul_f32 v[42:43], v[32:33], v[34:35]
	v_cvt_pk_bf16_f32 v32, v36, v37
	v_cvt_pk_bf16_f32 v33, v38, v39
	v_cvt_pk_bf16_f32 v34, v40, v41
	v_cvt_pk_bf16_f32 v35, v42, v43
	global_store_dwordx4 v[48:49], v[32:35], off offset:256
	s_nop 1
	v_mov_b32_e32 v32, v241
	v_fmamk_f32 v32, v32, 0x3a800000, v187
	v_cmp_gt_f32_e32 vcc, s67, v32
	v_mul_f32_e32 v33, 0x4b800000, v32
	s_nop 0
	v_cndmask_b32_e32 v32, v32, v33, vcc
	v_rsq_f32_e32 v32, v32
	s_nop 0
	v_mul_f32_e32 v33, 0x45800000, v32
	v_cndmask_b32_e32 v34, v32, v33, vcc
	v_add_co_u32_e32 v40, vcc, s2, v158
	v_pk_mul_f32 v[30:31], v[30:31], v[34:35] op_sel_hi:[1,0]
	s_nop 0
	v_addc_co_u32_e32 v41, vcc, 0, v159, vcc
	s_nop 1
	v_mov_b32_e32 v36, v244
	v_mov_b32_e32 v37, v245
	v_mov_b32_e32 v38, v246
	v_mov_b32_e32 v39, v247
	v_pk_mul_f32 v[24:25], v[24:25], v[34:35] op_sel_hi:[1,0]
	v_mul_f32_e32 v30, 0xbfb8aa3b, v30
	v_mul_f32_e32 v31, 0xbfb8aa3b, v31
	v_exp_f32_e32 v30, v30
	v_exp_f32_e32 v31, v31
	v_mul_f32_e32 v24, 0xbfb8aa3b, v24
	v_mul_f32_e32 v25, 0xbfb8aa3b, v25
	v_exp_f32_e32 v24, v24
	v_exp_f32_e32 v25, v25
	v_add_f32_e32 v30, 1.0, v30
	v_add_f32_e32 v31, 1.0, v31
	v_rcp_f32_e32 v30, v30
	v_rcp_f32_e32 v31, v31
	v_add_f32_e32 v24, 1.0, v24
	v_add_f32_e32 v25, 1.0, v25
	v_rcp_f32_e32 v24, v24
	v_rcp_f32_e32 v25, v25
	v_pk_mul_f32 v[28:29], v[28:29], v[34:35] op_sel_hi:[1,0]
	v_pk_mul_f32 v[26:27], v[26:27], v[34:35] op_sel_hi:[1,0]
	v_mul_f32_e32 v28, 0xbfb8aa3b, v28
	v_mul_f32_e32 v29, 0xbfb8aa3b, v29
	v_exp_f32_e32 v28, v28
	v_exp_f32_e32 v29, v29
	v_lshl_add_u64 v[32:33], v[158:159], 0, s[4:5]
	v_pk_mul_f32 v[22:23], v[22:23], v[34:35] op_sel_hi:[1,0]
	v_add_f32_e32 v28, 1.0, v28
	v_add_f32_e32 v29, 1.0, v29
	v_rcp_f32_e32 v28, v28
	v_rcp_f32_e32 v29, v29
	v_pk_mul_f32 v[16:17], v[16:17], v[34:35] op_sel_hi:[1,0]
	v_mul_f32_e32 v22, 0xbfb8aa3b, v22
	v_mul_f32_e32 v23, 0xbfb8aa3b, v23
	v_exp_f32_e32 v22, v22
	v_exp_f32_e32 v23, v23
	v_mul_f32_e32 v16, 0xbfb8aa3b, v16
	v_mul_f32_e32 v17, 0xbfb8aa3b, v17
	v_exp_f32_e32 v16, v16
	v_exp_f32_e32 v17, v17
	v_add_f32_e32 v22, 1.0, v22
	v_add_f32_e32 v23, 1.0, v23
	v_rcp_f32_e32 v22, v22
	v_rcp_f32_e32 v23, v23
	v_add_f32_e32 v16, 1.0, v16
	v_add_f32_e32 v17, 1.0, v17
	v_rcp_f32_e32 v16, v16
	v_rcp_f32_e32 v17, v17
	v_pk_mul_f32 v[20:21], v[20:21], v[34:35] op_sel_hi:[1,0]
	v_pk_mul_f32 v[18:19], v[18:19], v[34:35] op_sel_hi:[1,0]
	v_mul_f32_e32 v20, 0xbfb8aa3b, v20
	v_mul_f32_e32 v21, 0xbfb8aa3b, v21
	v_exp_f32_e32 v20, v20
	v_exp_f32_e32 v21, v21
	s_mov_b32 s2, 0x58000
	s_mov_b64 s[4:5], 0x58000
	v_add_f32_e32 v20, 1.0, v20
	v_add_f32_e32 v21, 1.0, v21
	v_rcp_f32_e32 v20, v20
	v_rcp_f32_e32 v21, v21
	v_lshlrev_b32_e32 v42, 16, v36
	v_and_b32_e32 v43, 0xffff0000, v36
	v_lshlrev_b32_e32 v36, 16, v37
	v_and_b32_e32 v37, 0xffff0000, v37
	v_pk_mul_f32 v[30:31], v[30:31], v[36:37]
	v_lshlrev_b32_e32 v36, 16, v38
	v_and_b32_e32 v37, 0xffff0000, v38
	v_pk_mul_f32 v[36:37], v[24:25], v[36:37]
	v_mul_f32_e32 v24, 0xbfb8aa3b, v26
	v_mul_f32_e32 v25, 0xbfb8aa3b, v27
	v_exp_f32_e32 v24, v24
	v_exp_f32_e32 v25, v25
	v_lshlrev_b32_e32 v26, 16, v39
	v_and_b32_e32 v27, 0xffff0000, v39
	v_add_f32_e32 v24, 1.0, v24
	v_add_f32_e32 v25, 1.0, v25
	v_rcp_f32_e32 v24, v24
	v_rcp_f32_e32 v25, v25
	v_pk_mul_f32 v[28:29], v[28:29], v[42:43]
	v_pk_mul_f32 v[38:39], v[24:25], v[26:27]
	v_cvt_pk_bf16_f32 v24, v28, v29
	v_cvt_pk_bf16_f32 v25, v30, v31
	v_cvt_pk_bf16_f32 v26, v36, v37
	v_cvt_pk_bf16_f32 v27, v38, v39
	global_store_dwordx4 v[40:41], v[24:27], off
	s_nop 1
	v_mov_b32_e32 v24, v248
	v_mov_b32_e32 v25, v249
	v_mov_b32_e32 v26, v250
	v_mov_b32_e32 v27, v251
	v_lshlrev_b32_e32 v28, 16, v24
	v_and_b32_e32 v29, 0xffff0000, v24
	v_lshlrev_b32_e32 v24, 16, v25
	v_and_b32_e32 v25, 0xffff0000, v25
	v_pk_mul_f32 v[22:23], v[22:23], v[24:25]
	v_lshlrev_b32_e32 v24, 16, v26
	v_and_b32_e32 v25, 0xffff0000, v26
	v_pk_mul_f32 v[24:25], v[16:17], v[24:25]
	v_mul_f32_e32 v16, 0xbfb8aa3b, v18
	v_mul_f32_e32 v17, 0xbfb8aa3b, v19
; __device__ __forceinline__ unsigned cvt_pk_bf16(float lo, float hi) { const f32x2_cv v = {lo, hi}; const bf16x2_cv b = __builtin_convertvector(v, bf16x2_cv); return __builtin_bit_cast(unsigned, b); }
; __device__ __forceinline__ float sigm(float x) { return __builtin_amdgcn_rcpf(1.0f + __expf(-x)); }
; __device__ __forceinline__ float lo16(unsigned w) { return __uint_as_float(w << 16); }
; __device__ __forceinline__ float hi16(unsigned w) { return __uint_as_float(w & 0xffff0000u); }
; __device__ __forceinline__ float rstd_of(const float* rowss, int row) { return rsqrtf(rowss[row] * (1.0f / 1024.0f) + 1e-6f); }
;     __device__ __forceinline__ void operator()(const f32x4 (&acc)[2][2][4][2], const pg8::Unit& u, int wr, int wc, int fr, int fq) const {
;         const int row0 = u.pm * 256 + wr * 64 + fr, col0 = u.pn * 256 + wc * 32 + 8 * fq;
; #pragma unroll
;         for (int ai = 0; ai < 2; ++ai)
; #pragma unroll
;             for (int m = 0; m < 4; ++m) {
;                 const int row = row0 + ai * 128 + m * 16;
;                 const float s = rstd_of(rowss, row);
; #pragma unroll
;                 for (int bj = 0; bj < 2; ++bj) {
;                     const size_t off = (size_t)row * 1024 + col0 + bj * 128;
;                     const u32x4 tv = *(const u32x4*)(Tm + off);
;                     u32x4 pv = (u32x4){0u, 0u, 0u, 0u};
;                     if (ACC) pv = *(const u32x4*)(M + off);
;                     const f32x4 a0 = acc[ai][bj][m][0] * s, a1 = acc[ai][bj][m][1] * s;
;                     float o[8];
;                     o[0] = sigm(a0[0]) * lo16(tv.x); o[1] = sigm(a0[1]) * hi16(tv.x); o[2] = sigm(a0[2]) * lo16(tv.y); o[3] = sigm(a0[3]) * hi16(tv.y);
;                     o[4] = sigm(a1[0]) * lo16(tv.z); o[5] = sigm(a1[1]) * hi16(tv.z); o[6] = sigm(a1[2]) * lo16(tv.w); o[7] = sigm(a1[3]) * hi16(tv.w);
;                     if (ACC) { o[0] += lo16(pv.x); o[1] += hi16(pv.x); o[2] += lo16(pv.y); o[3] += hi16(pv.y); o[4] += lo16(pv.z); o[5] += hi16(pv.z); o[6] += lo16(pv.w); o[7] += hi16(pv.w); }
;                     u32x4 w; w.x = cvt_pk_bf16(o[0], o[1]); w.y = cvt_pk_bf16(o[2], o[3]); w.z = cvt_pk_bf16(o[4], o[5]); w.w = cvt_pk_bf16(o[6], o[7]);
;                     *(u32x4*)(M + off) = w; } }
;     }
	v_exp_f32_e32 v16, v16
	v_exp_f32_e32 v17, v17
	v_lshlrev_b32_e32 v18, 16, v27
	v_and_b32_e32 v19, 0xffff0000, v27
	v_add_f32_e32 v16, 1.0, v16
	v_add_f32_e32 v17, 1.0, v17
	v_rcp_f32_e32 v16, v16
	v_rcp_f32_e32 v17, v17
	v_pk_mul_f32 v[20:21], v[20:21], v[28:29]
	v_pk_mul_f32 v[26:27], v[16:17], v[18:19]
	v_cvt_pk_bf16_f32 v16, v20, v21
	v_cvt_pk_bf16_f32 v17, v22, v23
	v_cvt_pk_bf16_f32 v18, v24, v25
	v_cvt_pk_bf16_f32 v19, v26, v27
	global_store_dwordx4 v[32:33], v[16:19], off offset:256
	s_nop 1
	v_mov_b32_e32 v16, v169
	v_fmamk_f32 v16, v16, 0x3a800000, v187
	v_cmp_gt_f32_e32 vcc, s67, v16
	v_mul_f32_e32 v17, 0x4b800000, v16
	s_nop 0
	v_cndmask_b32_e32 v16, v16, v17, vcc
	v_rsq_f32_e32 v16, v16
	s_nop 0
	v_mul_f32_e32 v17, 0x45800000, v16
	v_cndmask_b32_e32 v18, v16, v17, vcc
	v_add_co_u32_e32 v24, vcc, s2, v158
	v_pk_mul_f32 v[14:15], v[14:15], v[18:19] op_sel_hi:[1,0]
	s_nop 0
	v_addc_co_u32_e32 v25, vcc, 0, v159, vcc
	s_nop 1
	v_mov_b32_e32 v20, v176
	v_mov_b32_e32 v21, v177
	v_mov_b32_e32 v22, v178
	v_mov_b32_e32 v23, v179
	v_pk_mul_f32 v[8:9], v[8:9], v[18:19] op_sel_hi:[1,0]
	v_mul_f32_e32 v14, 0xbfb8aa3b, v14
	v_mul_f32_e32 v15, 0xbfb8aa3b, v15
	v_exp_f32_e32 v14, v14
	v_exp_f32_e32 v15, v15
	v_mul_f32_e32 v8, 0xbfb8aa3b, v8
	v_mul_f32_e32 v9, 0xbfb8aa3b, v9
	v_exp_f32_e32 v8, v8
	v_exp_f32_e32 v9, v9
	v_add_f32_e32 v14, 1.0, v14
	v_add_f32_e32 v15, 1.0, v15
	v_rcp_f32_e32 v14, v14
	v_rcp_f32_e32 v15, v15
	v_add_f32_e32 v8, 1.0, v8
	v_add_f32_e32 v9, 1.0, v9
	v_rcp_f32_e32 v8, v8
	v_rcp_f32_e32 v9, v9
	v_pk_mul_f32 v[12:13], v[12:13], v[18:19] op_sel_hi:[1,0]
	v_pk_mul_f32 v[10:11], v[10:11], v[18:19] op_sel_hi:[1,0]
	v_mul_f32_e32 v12, 0xbfb8aa3b, v12
	v_mul_f32_e32 v13, 0xbfb8aa3b, v13
	v_exp_f32_e32 v12, v12
	v_exp_f32_e32 v13, v13
	v_lshl_add_u64 v[16:17], v[158:159], 0, s[4:5]
	v_pk_mul_f32 v[6:7], v[6:7], v[18:19] op_sel_hi:[1,0]
	v_add_f32_e32 v12, 1.0, v12
	v_add_f32_e32 v13, 1.0, v13
	v_rcp_f32_e32 v12, v12
	v_rcp_f32_e32 v13, v13
	v_pk_mul_f32 v[0:1], v[0:1], v[18:19] op_sel_hi:[1,0]
	v_mul_f32_e32 v6, 0xbfb8aa3b, v6
	v_mul_f32_e32 v7, 0xbfb8aa3b, v7
	v_exp_f32_e32 v6, v6
	v_exp_f32_e32 v7, v7
	v_mul_f32_e32 v0, 0xbfb8aa3b, v0
	v_mul_f32_e32 v1, 0xbfb8aa3b, v1
	v_exp_f32_e32 v0, v0
	v_exp_f32_e32 v1, v1
	v_add_f32_e32 v6, 1.0, v6
	v_add_f32_e32 v7, 1.0, v7
	v_rcp_f32_e32 v6, v6
	v_rcp_f32_e32 v7, v7
	v_add_f32_e32 v0, 1.0, v0
	v_add_f32_e32 v1, 1.0, v1
	v_rcp_f32_e32 v0, v0
	v_rcp_f32_e32 v1, v1
	v_pk_mul_f32 v[4:5], v[4:5], v[18:19] op_sel_hi:[1,0]
	v_pk_mul_f32 v[2:3], v[2:3], v[18:19] op_sel_hi:[1,0]
	v_mul_f32_e32 v4, 0xbfb8aa3b, v4
	v_mul_f32_e32 v5, 0xbfb8aa3b, v5
	v_exp_f32_e32 v4, v4
	v_exp_f32_e32 v5, v5
	s_and_b64 vcc, exec, s[38:39]
	s_mov_b32 s2, s30
	v_add_f32_e32 v4, 1.0, v4
	v_add_f32_e32 v5, 1.0, v5
	v_rcp_f32_e32 v4, v4
	v_rcp_f32_e32 v5, v5
	s_mov_b64 s[4:5], s[48:49]
	v_lshlrev_b32_e32 v26, 16, v20
	v_and_b32_e32 v27, 0xffff0000, v20
	v_lshlrev_b32_e32 v20, 16, v21
	v_and_b32_e32 v21, 0xffff0000, v21
	v_pk_mul_f32 v[14:15], v[14:15], v[20:21]
	v_lshlrev_b32_e32 v20, 16, v22
	v_and_b32_e32 v21, 0xffff0000, v22
	v_pk_mul_f32 v[20:21], v[8:9], v[20:21]
	v_mul_f32_e32 v8, 0xbfb8aa3b, v10
	v_mul_f32_e32 v9, 0xbfb8aa3b, v11
	v_exp_f32_e32 v8, v8
	v_exp_f32_e32 v9, v9
	v_lshlrev_b32_e32 v10, 16, v23
	v_and_b32_e32 v11, 0xffff0000, v23
	v_add_f32_e32 v8, 1.0, v8
	v_add_f32_e32 v9, 1.0, v9
	v_rcp_f32_e32 v8, v8
	v_rcp_f32_e32 v9, v9
	v_pk_mul_f32 v[12:13], v[12:13], v[26:27]
	v_pk_mul_f32 v[22:23], v[8:9], v[10:11]
	v_cvt_pk_bf16_f32 v8, v12, v13
	v_cvt_pk_bf16_f32 v9, v14, v15
	v_cvt_pk_bf16_f32 v10, v20, v21
	v_cvt_pk_bf16_f32 v11, v22, v23
	global_store_dwordx4 v[24:25], v[8:11], off
	s_nop 1
	v_mov_b32_e32 v8, v252
	v_mov_b32_e32 v9, v253
	v_mov_b32_e32 v10, v254
	v_mov_b32_e32 v11, v255
	v_lshlrev_b32_e32 v12, 16, v8
	v_and_b32_e32 v13, 0xffff0000, v8
	v_lshlrev_b32_e32 v8, 16, v9
	v_and_b32_e32 v9, 0xffff0000, v9
	v_pk_mul_f32 v[6:7], v[6:7], v[8:9]
	v_lshlrev_b32_e32 v8, 16, v10
	v_and_b32_e32 v9, 0xffff0000, v10
	v_pk_mul_f32 v[8:9], v[0:1], v[8:9]
	v_mul_f32_e32 v0, 0xbfb8aa3b, v2
	v_mul_f32_e32 v1, 0xbfb8aa3b, v3
	v_exp_f32_e32 v0, v0
	v_exp_f32_e32 v1, v1
	v_lshlrev_b32_e32 v2, 16, v11
	v_and_b32_e32 v3, 0xffff0000, v11
	v_add_f32_e32 v0, 1.0, v0
	v_add_f32_e32 v1, 1.0, v1
	v_rcp_f32_e32 v0, v0
	v_rcp_f32_e32 v1, v1
	v_pk_mul_f32 v[4:5], v[4:5], v[12:13]
	v_pk_mul_f32 v[10:11], v[0:1], v[2:3]
	v_cvt_pk_bf16_f32 v0, v4, v5
	v_cvt_pk_bf16_f32 v1, v6, v7
	v_cvt_pk_bf16_f32 v2, v8, v9
	v_cvt_pk_bf16_f32 v3, v10, v11
	global_store_dwordx4 v[16:17], v[0:3], off offset:256
	s_cbranch_vccz .LBB0_306
	s_cmpk_gt_u32 s36, 0xff
	s_cbranch_scc1 .LBB0_317
	s_barrier

; #define PG8_STAGE(bufoff, gbase, voff) do { _Pragma("unroll") for (int _i = 0; _i < 2; ++_i) \
;         __builtin_amdgcn_global_load_lds((const unsigned*)((const char*)(gbase) + (voff)[_i]), (PG8_LAS unsigned*)(lds + (bufoff) + ldsw + _i * 8192), 16, 0, 0); } while (0)
; #define PG8_LDA(dst, b, h) do { _Pragma("unroll") for (int m = 0; m < 4; ++m) _Pragma("unroll") for (int k = 0; k < 2; ++k) dst[m][k] = *(const PG8_LAS bf16x8*)(lds + PG8_SA(b, h) + aoff + m * 2048 + k * 1024); } while (0)
; #define PG8_LDB(dst, b, h) do { _Pragma("unroll") for (int n = 0; n < 2; ++n) _Pragma("unroll") for (int k = 0; k < 2; ++k) dst[n][k] = *(const PG8_LAS bf16x8*)(lds + PG8_SB(b, h) + boff + n * 2048 + k * 1024); } while (0)
; #define PG8_MMA(ai, bj, At, Bt) do { __builtin_amdgcn_s_setprio(1); _Pragma("unroll") for (int m = 0; m < 4; ++m) _Pragma("unroll") for (int n = 0; n < 2; ++n) _Pragma("unroll") for (int k = 0; k < 2; ++k) \
;         acc[ai][bj][m][n] = __builtin_amdgcn_mfma_f32_16x16x32_bf16(Bt[n][k], At[m][k], acc[ai][bj][m][n], 0, 0, 0); __builtin_amdgcn_s_setprio(0); } while (0)
; #define PG8_WAIT_L(n) asm volatile("s_waitcnt lgkmcnt(" #n ")" ::: "memory")
; #define PG8_BAR __builtin_amdgcn_s_barrier()
; #define PG8_SCHED __builtin_amdgcn_sched_barrier(0)
; template <class Epi, class Sched, bool STAMP = false>
; __device__ __forceinline__ void gemm_phase(PG8_LAS unsigned char* lds, const Gemm g, const Sched& S, const Epi& E, unsigned long long* stamps) {
;     ...
;             PG8_LDB(B0, 0, 0); PG8_SCHED; PG8_LDA(At, 0, 0); PG8_STAGE(PG8_SA(1, 1), a1 + hstep, voffA);
;             PG8_WAIT_L(8); PG8_BAR; PG8_WAIT_L(0); PG8_MMA(0, 0, At, B0); PG8_BAR; PG8_SCHED;
;     ...
; #pragma unroll
;         for (int a = 0; a < 2; ++a)
; #pragma unroll
;             for (int b = 0; b < 2; ++b)
; #pragma unroll
;                 for (int m = 0; m < 4; ++m)
; #pragma unroll
;                     for (int n = 0; n < 2; ++n) acc[a][b][m][n] = (f32x4){0.f, 0.f, 0.f, 0.f};
;         cur = nxt; cA = nA; cB = nB; ++ui;
.LBB0_332:
	s_ashr_i32 s13, s12, 31
	s_lshl_b64 s[14:15], s[12:13], 18
	v_cmp_lt_i64_e32 vcc, s[24:25], v[136:137]
	s_add_u32 s24, s48, s14
	s_addc_u32 s25, s49, s15
	s_and_b64 s[14:15], vcc, exec
	s_cselect_b32 s13, s25, s37
	s_cselect_b32 s77, s24, s36
	s_ashr_i32 s5, s4, 31
	s_lshl_b64 s[14:15], s[4:5], 18
	s_add_u32 s26, s6, s14
	s_addc_u32 s27, s7, s15
	s_and_b64 s[14:15], vcc, exec
	s_cselect_b32 s5, s27, s57
	s_cselect_b32 s88, s26, s56
	s_add_u32 s36, s36, 0x20080
	s_addc_u32 s37, s37, 0
	s_add_u32 s89, s56, 0x100
	v_mov_b32_e32 v0, 0
	s_addc_u32 s96, s57, 0
	s_mov_b32 s97, -2
	v_mov_b32_e32 v1, v0
	v_mov_b32_e32 v2, v0
	v_mov_b32_e32 v3, v0
	v_mov_b32_e32 v4, v0
	v_mov_b32_e32 v5, v0
	v_mov_b32_e32 v6, v0
	v_mov_b32_e32 v7, v0
	v_mov_b32_e32 v8, v0
	v_mov_b32_e32 v9, v0
	v_mov_b32_e32 v10, v0
	v_mov_b32_e32 v11, v0
	v_mov_b32_e32 v12, v0
	v_mov_b32_e32 v13, v0
	v_mov_b32_e32 v14, v0
	v_mov_b32_e32 v15, v0
	v_mov_b32_e32 v24, v0
	v_mov_b32_e32 v25, v0
	v_mov_b32_e32 v26, v0
	v_mov_b32_e32 v27, v0
	v_mov_b32_e32 v28, v0
	v_mov_b32_e32 v29, v0
	v_mov_b32_e32 v30, v0
	v_mov_b32_e32 v31, v0
	v_mov_b32_e32 v40, v0
	v_mov_b32_e32 v41, v0
	v_mov_b32_e32 v42, v0
	v_mov_b32_e32 v43, v0
	v_mov_b32_e32 v44, v0
	v_mov_b32_e32 v45, v0
	v_mov_b32_e32 v46, v0
	v_mov_b32_e32 v47, v0
	v_mov_b32_e32 v16, v0
	v_mov_b32_e32 v17, v0
	v_mov_b32_e32 v18, v0
	v_mov_b32_e32 v19, v0
	v_mov_b32_e32 v20, v0
	v_mov_b32_e32 v21, v0
	v_mov_b32_e32 v22, v0
	v_mov_b32_e32 v23, v0
	v_mov_b32_e32 v32, v0
	v_mov_b32_e32 v33, v0
	v_mov_b32_e32 v34, v0
	v_mov_b32_e32 v35, v0
	v_mov_b32_e32 v36, v0
	v_mov_b32_e32 v37, v0
	v_mov_b32_e32 v38, v0
	v_mov_b32_e32 v39, v0
	v_mov_b32_e32 v48, v0
	v_mov_b32_e32 v49, v0
	v_mov_b32_e32 v50, v0
	v_mov_b32_e32 v51, v0
	v_mov_b32_e32 v52, v0
	v_mov_b32_e32 v53, v0
	v_mov_b32_e32 v54, v0
	v_mov_b32_e32 v55, v0
	v_mov_b32_e32 v56, v0
	v_mov_b32_e32 v57, v0
	v_mov_b32_e32 v58, v0
	v_mov_b32_e32 v59, v0
	v_mov_b32_e32 v60, v0
	v_mov_b32_e32 v61, v0
	v_mov_b32_e32 v62, v0
	v_mov_b32_e32 v63, v0
	v_mov_b32_e32 v64, v0
	v_mov_b32_e32 v65, v0
	v_mov_b32_e32 v66, v0
	v_mov_b32_e32 v67, v0
	v_mov_b32_e32 v68, v0
	v_mov_b32_e32 v69, v0
	v_mov_b32_e32 v70, v0
	v_mov_b32_e32 v71, v0
	v_mov_b32_e32 v72, v0
	v_mov_b32_e32 v73, v0
	v_mov_b32_e32 v74, v0
	v_mov_b32_e32 v75, v0
	v_mov_b32_e32 v76, v0
	v_mov_b32_e32 v77, v0
	v_mov_b32_e32 v78, v0
	v_mov_b32_e32 v79, v0
	v_mov_b32_e32 v88, v0
	v_mov_b32_e32 v89, v0
	v_mov_b32_e32 v90, v0
	v_mov_b32_e32 v91, v0
	v_mov_b32_e32 v92, v0
	v_mov_b32_e32 v93, v0
	v_mov_b32_e32 v94, v0
	v_mov_b32_e32 v95, v0
	v_mov_b32_e32 v104, v0
	v_mov_b32_e32 v105, v0
	v_mov_b32_e32 v106, v0
	v_mov_b32_e32 v107, v0
	v_mov_b32_e32 v108, v0
	v_mov_b32_e32 v109, v0
	v_mov_b32_e32 v110, v0
	v_mov_b32_e32 v111, v0
	v_mov_b32_e32 v80, v0
	v_mov_b32_e32 v81, v0
	v_mov_b32_e32 v82, v0
	v_mov_b32_e32 v83, v0
	v_mov_b32_e32 v84, v0
	v_mov_b32_e32 v85, v0
	v_mov_b32_e32 v86, v0
	v_mov_b32_e32 v87, v0
	v_mov_b32_e32 v96, v0
	v_mov_b32_e32 v97, v0
	v_mov_b32_e32 v98, v0
	v_mov_b32_e32 v99, v0
	v_mov_b32_e32 v100, v0
	v_mov_b32_e32 v101, v0
	v_mov_b32_e32 v102, v0
	v_mov_b32_e32 v103, v0
	v_mov_b32_e32 v112, v0
	v_mov_b32_e32 v113, v0
	v_mov_b32_e32 v114, v0
	v_mov_b32_e32 v115, v0
	v_mov_b32_e32 v116, v0
	v_mov_b32_e32 v117, v0
	v_mov_b32_e32 v118, v0
	v_mov_b32_e32 v119, v0
	v_mov_b32_e32 v120, v0
	v_mov_b32_e32 v121, v0
	v_mov_b32_e32 v122, v0
	v_mov_b32_e32 v123, v0
	v_mov_b32_e32 v124, v0
	v_mov_b32_e32 v125, v0
	v_mov_b32_e32 v126, v0
	v_mov_b32_e32 v127, v0
	v_add_u32_e32 v244, 0x80, v128
	v_add_u32_e32 v245, 0x80, v152
	v_add_u32_e32 v246, 0x80, v148
	v_add_u32_e32 v247, 0x80, v150
.LBB0_333:
	s_add_u32 s14, s36, 0xfffe0080
	s_addc_u32 s15, s37, -1
	s_add_i32 s16, 0, 0x10000
	v_add_u32_e32 v161, s16, v158
	ds_read_b128 v[162:165], v161
	ds_read_b128 v[166:169], v161 offset:1024
	ds_read_b128 v[170:173], v161 offset:2048
	ds_read_b128 v[174:177], v161 offset:3072
	s_cmp_eq_u32 s97, 4
	s_cselect_b32 s59, s13, s15
	s_cselect_b32 s58, s77, s14
	s_cselect_b32 s57, s5, s96
	s_cselect_b32 s56, s88, s89
	s_add_i32 m0, s3, 0xc000
	ds_read_b128 v[178:181], v160
	ds_read_b128 v[192:195], v160 offset:1024
	ds_read_b128 v[196:199], v160 offset:2048
	ds_read_b128 v[200:203], v160 offset:3072
	ds_read_b128 v[204:207], v160 offset:4096
	ds_read_b128 v[208:211], v160 offset:5120
	ds_read_b128 v[212:215], v160 offset:6144
	ds_read_b128 v[216:219], v160 offset:7168
	global_load_lds_dwordx4 v154, s[36:37]
	s_add_i32 m0, s3, 0xe000
	s_nop 0
	global_load_lds_dwordx4 v156, s[36:37]
	s_waitcnt lgkmcnt(8)
	s_barrier
	s_waitcnt lgkmcnt(0)
	v_mfma_f32_16x16x32_bf16 v[124:127], v[162:165], v[178:181], v[124:127]
	v_mfma_f32_16x16x32_bf16 v[120:123], v[170:173], v[178:181], v[120:123]
	v_mfma_f32_16x16x32_bf16 v[116:119], v[162:165], v[196:199], v[116:119]
	v_mfma_f32_16x16x32_bf16 v[112:115], v[170:173], v[196:199], v[112:115]
	v_mfma_f32_16x16x32_bf16 v[100:103], v[162:165], v[204:207], v[100:103]
	v_mfma_f32_16x16x32_bf16 v[96:99], v[170:173], v[204:207], v[96:99]
	v_mfma_f32_16x16x32_bf16 v[84:87], v[162:165], v[212:215], v[84:87]
	v_mfma_f32_16x16x32_bf16 v[80:83], v[170:173], v[212:215], v[80:83]
	v_mfma_f32_16x16x32_bf16 v[124:127], v[166:169], v[192:195], v[124:127]
	v_mfma_f32_16x16x32_bf16 v[120:123], v[174:177], v[192:195], v[120:123]
	v_mfma_f32_16x16x32_bf16 v[116:119], v[166:169], v[200:203], v[116:119]
	v_mfma_f32_16x16x32_bf16 v[112:115], v[174:177], v[200:203], v[112:115]
	v_mfma_f32_16x16x32_bf16 v[100:103], v[166:169], v[208:211], v[100:103]
	v_mfma_f32_16x16x32_bf16 v[96:99], v[174:177], v[208:211], v[96:99]
	v_mfma_f32_16x16x32_bf16 v[84:87], v[166:169], v[216:219], v[84:87]
	v_mfma_f32_16x16x32_bf16 v[80:83], v[174:177], v[216:219], v[80:83]
	s_barrier
; #define PG8_STAGE(bufoff, gbase, voff) do { _Pragma("unroll") for (int _i = 0; _i < 2; ++_i) \
;         __builtin_amdgcn_global_load_lds((const unsigned*)((const char*)(gbase) + (voff)[_i]), (PG8_LAS unsigned*)(lds + (bufoff) + ldsw + _i * 8192), 16, 0, 0); } while (0)
; #define PG8_LDA(dst, b, h) do { _Pragma("unroll") for (int m = 0; m < 4; ++m) _Pragma("unroll") for (int k = 0; k < 2; ++k) dst[m][k] = *(const PG8_LAS bf16x8*)(lds + PG8_SA(b, h) + aoff + m * 2048 + k * 1024); } while (0)
; #define PG8_LDB(dst, b, h) do { _Pragma("unroll") for (int n = 0; n < 2; ++n) _Pragma("unroll") for (int k = 0; k < 2; ++k) dst[n][k] = *(const PG8_LAS bf16x8*)(lds + PG8_SB(b, h) + boff + n * 2048 + k * 1024); } while (0)
; #define PG8_MMA(ai, bj, At, Bt) do { __builtin_amdgcn_s_setprio(1); _Pragma("unroll") for (int m = 0; m < 4; ++m) _Pragma("unroll") for (int n = 0; n < 2; ++n) _Pragma("unroll") for (int k = 0; k < 2; ++k) \
;         acc[ai][bj][m][n] = __builtin_amdgcn_mfma_f32_16x16x32_bf16(Bt[n][k], At[m][k], acc[ai][bj][m][n], 0, 0, 0); __builtin_amdgcn_s_setprio(0); } while (0)
; #define PG8_WAIT_V(n) asm volatile("s_waitcnt vmcnt(" #n ")" ::: "memory")
; #define PG8_WAIT_L(n) asm volatile("s_waitcnt lgkmcnt(" #n ")" ::: "memory")
; #define PG8_BAR __builtin_amdgcn_s_barrier()
; #define PG8_SCHED __builtin_amdgcn_sched_barrier(0)
; template <class Epi, class Sched, bool STAMP = false>
; __device__ __forceinline__ void gemm_phase(PG8_LAS unsigned char* lds, const Gemm g, const Sched& S, const Epi& E, unsigned long long* stamps) {
;     ...
;             PG8_LDB(B1, 0, 1); PG8_STAGE(PG8_SB(0, 0), b2, voffB);
;             PG8_BAR; PG8_WAIT_L(0); PG8_MMA(0, 1, At, B1); PG8_BAR;
;             PG8_LDA(At, 0, 1); PG8_STAGE(PG8_SA(0, 0), a2, voffA);
;             PG8_BAR; PG8_WAIT_L(0); PG8_MMA(1, 0, At, B0); PG8_BAR; PG8_SCHED;
;             PG8_STAGE(PG8_SB(0, 1), b2 + hstep, voffB);
;             PG8_WAIT_V(6); PG8_BAR; PG8_MMA(1, 1, At, B1); PG8_BAR;
;             PG8_LDB(B0, 1, 0); PG8_SCHED; PG8_LDA(At, 1, 0); PG8_STAGE(PG8_SA(0, 1), a2 + hstep, voffA);
;             PG8_WAIT_L(8); PG8_BAR; PG8_WAIT_L(0); PG8_MMA(0, 0, At, B0); PG8_BAR; PG8_SCHED;
	s_add_i32 s17, 0, 0x14000
	s_add_i32 s14, s16, s53
	v_add_u32_e32 v161, s17, v158
	s_mov_b32 m0, s14
	ds_read_b128 v[220:223], v161
	ds_read_b128 v[224:227], v161 offset:1024
	ds_read_b128 v[228:231], v161 offset:2048
	ds_read_b128 v[232:235], v161 offset:3072
	global_load_lds_dwordx4 v128, s[56:57]
	s_add_i32 m0, s14, 0x2000
	s_nop 0
	global_load_lds_dwordx4 v152, s[56:57]
	s_barrier
	s_waitcnt lgkmcnt(0)
	v_mfma_f32_16x16x32_bf16 v[108:111], v[220:223], v[178:181], v[108:111]
	v_mfma_f32_16x16x32_bf16 v[104:107], v[228:231], v[178:181], v[104:107]
	v_mfma_f32_16x16x32_bf16 v[92:95], v[220:223], v[196:199], v[92:95]
	v_mfma_f32_16x16x32_bf16 v[88:91], v[228:231], v[196:199], v[88:91]
	v_mfma_f32_16x16x32_bf16 v[76:79], v[220:223], v[204:207], v[76:79]
	v_mfma_f32_16x16x32_bf16 v[72:75], v[228:231], v[204:207], v[72:75]
	v_mfma_f32_16x16x32_bf16 v[68:71], v[220:223], v[212:215], v[68:71]
	v_mfma_f32_16x16x32_bf16 v[64:67], v[228:231], v[212:215], v[64:67]
	v_mfma_f32_16x16x32_bf16 v[108:111], v[224:227], v[192:195], v[108:111]
	v_mfma_f32_16x16x32_bf16 v[104:107], v[232:235], v[192:195], v[104:107]
	v_mfma_f32_16x16x32_bf16 v[92:95], v[224:227], v[200:203], v[92:95]
	v_mfma_f32_16x16x32_bf16 v[88:91], v[232:235], v[200:203], v[88:91]
	v_mfma_f32_16x16x32_bf16 v[76:79], v[224:227], v[208:211], v[76:79]
	v_mfma_f32_16x16x32_bf16 v[72:75], v[232:235], v[208:211], v[72:75]
	v_mfma_f32_16x16x32_bf16 v[68:71], v[224:227], v[216:219], v[68:71]
	v_mfma_f32_16x16x32_bf16 v[64:67], v[232:235], v[216:219], v[64:67]
	s_mov_b32 m0, s3
	s_barrier
	ds_read_b128 v[178:181], v160 offset:16384
	ds_read_b128 v[192:195], v160 offset:17408
	ds_read_b128 v[196:199], v160 offset:18432
	ds_read_b128 v[200:203], v160 offset:19456
	ds_read_b128 v[204:207], v160 offset:20480
	ds_read_b128 v[208:211], v160 offset:21504
	ds_read_b128 v[212:215], v160 offset:22528
	ds_read_b128 v[216:219], v160 offset:23552
	global_load_lds_dwordx4 v148, s[58:59]
	s_mov_b32 m0, s60
	s_nop 0
	global_load_lds_dwordx4 v150, s[58:59]
	s_barrier
	s_waitcnt lgkmcnt(0)
	v_mfma_f32_16x16x32_bf16 v[60:63], v[162:165], v[178:181], v[60:63]
	v_mfma_f32_16x16x32_bf16 v[56:59], v[170:173], v[178:181], v[56:59]
	v_mfma_f32_16x16x32_bf16 v[52:55], v[162:165], v[196:199], v[52:55]
	v_mfma_f32_16x16x32_bf16 v[48:51], v[170:173], v[196:199], v[48:51]
	v_mfma_f32_16x16x32_bf16 v[36:39], v[162:165], v[204:207], v[36:39]
	v_mfma_f32_16x16x32_bf16 v[32:35], v[170:173], v[204:207], v[32:35]
	v_mfma_f32_16x16x32_bf16 v[20:23], v[162:165], v[212:215], v[20:23]
	v_mfma_f32_16x16x32_bf16 v[16:19], v[170:173], v[212:215], v[16:19]
	v_mfma_f32_16x16x32_bf16 v[60:63], v[166:169], v[192:195], v[60:63]
	v_mfma_f32_16x16x32_bf16 v[56:59], v[174:177], v[192:195], v[56:59]
	v_mfma_f32_16x16x32_bf16 v[52:55], v[166:169], v[200:203], v[52:55]
	v_mfma_f32_16x16x32_bf16 v[48:51], v[174:177], v[200:203], v[48:51]
	v_mfma_f32_16x16x32_bf16 v[36:39], v[166:169], v[208:211], v[36:39]
	v_mfma_f32_16x16x32_bf16 v[32:35], v[174:177], v[208:211], v[32:35]
	v_mfma_f32_16x16x32_bf16 v[20:23], v[166:169], v[216:219], v[20:23]
	v_mfma_f32_16x16x32_bf16 v[16:19], v[174:177], v[216:219], v[16:19]
	s_barrier
	s_add_u32 s14, s56, 0x20000
	s_addc_u32 s15, s57, 0
	s_add_i32 s16, s17, s53
	s_mov_b32 m0, s16
	s_nop 0
	global_load_lds_dwordx4 v128, s[14:15]
	s_add_i32 m0, s16, 0x2000
	s_nop 0
	global_load_lds_dwordx4 v152, s[14:15]
	s_waitcnt vmcnt(6)
	s_barrier
	v_mfma_f32_16x16x32_bf16 v[44:47], v[220:223], v[178:181], v[44:47]
	v_mfma_f32_16x16x32_bf16 v[40:43], v[228:231], v[178:181], v[40:43]
	v_mfma_f32_16x16x32_bf16 v[28:31], v[220:223], v[196:199], v[28:31]
	v_mfma_f32_16x16x32_bf16 v[24:27], v[228:231], v[196:199], v[24:27]
	v_mfma_f32_16x16x32_bf16 v[12:15], v[220:223], v[204:207], v[12:15]
	v_mfma_f32_16x16x32_bf16 v[8:11], v[228:231], v[204:207], v[8:11]
	v_mfma_f32_16x16x32_bf16 v[4:7], v[220:223], v[212:215], v[4:7]
	v_mfma_f32_16x16x32_bf16 v[0:3], v[228:231], v[212:215], v[0:3]
	v_mfma_f32_16x16x32_bf16 v[44:47], v[224:227], v[192:195], v[44:47]
	v_mfma_f32_16x16x32_bf16 v[40:43], v[232:235], v[192:195], v[40:43]
	v_mfma_f32_16x16x32_bf16 v[28:31], v[224:227], v[200:203], v[28:31]
	v_mfma_f32_16x16x32_bf16 v[24:27], v[232:235], v[200:203], v[24:27]
	v_mfma_f32_16x16x32_bf16 v[12:15], v[224:227], v[208:211], v[12:15]
	v_mfma_f32_16x16x32_bf16 v[8:11], v[232:235], v[208:211], v[8:11]
	v_mfma_f32_16x16x32_bf16 v[4:7], v[224:227], v[216:219], v[4:7]
	v_mfma_f32_16x16x32_bf16 v[0:3], v[232:235], v[216:219], v[0:3]
	s_add_i32 s16, 0, 0x18000
	v_add_u32_e32 v161, s16, v158
	s_barrier
	ds_read_b128 v[162:165], v161
	ds_read_b128 v[166:169], v161 offset:1024
	ds_read_b128 v[170:173], v161 offset:2048
	ds_read_b128 v[174:177], v161 offset:3072
	s_add_u32 s14, s58, 0x20000
	s_addc_u32 s15, s59, 0
	s_mov_b32 m0, s61
	ds_read_b128 v[178:181], v160 offset:32768
	ds_read_b128 v[192:195], v160 offset:33792
	ds_read_b128 v[196:199], v160 offset:34816
	ds_read_b128 v[200:203], v160 offset:35840
	ds_read_b128 v[204:207], v160 offset:36864
	ds_read_b128 v[208:211], v160 offset:37888
	ds_read_b128 v[212:215], v160 offset:38912
	ds_read_b128 v[216:219], v160 offset:39936
	global_load_lds_dwordx4 v148, s[14:15]
	s_mov_b32 m0, s62
	s_nop 0
	global_load_lds_dwordx4 v150, s[14:15]
	s_waitcnt lgkmcnt(8)
	s_barrier
; #define PG8_STAGE(bufoff, gbase, voff) do { _Pragma("unroll") for (int _i = 0; _i < 2; ++_i) \
;         __builtin_amdgcn_global_load_lds((const unsigned*)((const char*)(gbase) + (voff)[_i]), (PG8_LAS unsigned*)(lds + (bufoff) + ldsw + _i * 8192), 16, 0, 0); } while (0)
; #define PG8_LDA(dst, b, h) do { _Pragma("unroll") for (int m = 0; m < 4; ++m) _Pragma("unroll") for (int k = 0; k < 2; ++k) dst[m][k] = *(const PG8_LAS bf16x8*)(lds + PG8_SA(b, h) + aoff + m * 2048 + k * 1024); } while (0)
; #define PG8_LDB(dst, b, h) do { _Pragma("unroll") for (int n = 0; n < 2; ++n) _Pragma("unroll") for (int k = 0; k < 2; ++k) dst[n][k] = *(const PG8_LAS bf16x8*)(lds + PG8_SB(b, h) + boff + n * 2048 + k * 1024); } while (0)
; #define PG8_MMA(ai, bj, At, Bt) do { __builtin_amdgcn_s_setprio(1); _Pragma("unroll") for (int m = 0; m < 4; ++m) _Pragma("unroll") for (int n = 0; n < 2; ++n) _Pragma("unroll") for (int k = 0; k < 2; ++k) \
;         acc[ai][bj][m][n] = __builtin_amdgcn_mfma_f32_16x16x32_bf16(Bt[n][k], At[m][k], acc[ai][bj][m][n], 0, 0, 0); __builtin_amdgcn_s_setprio(0); } while (0)
; #define PG8_WAIT_V(n) asm volatile("s_waitcnt vmcnt(" #n ")" ::: "memory")
; #define PG8_WAIT_L(n) asm volatile("s_waitcnt lgkmcnt(" #n ")" ::: "memory")
; #define PG8_BAR __builtin_amdgcn_s_barrier()
; #define PG8_SCHED __builtin_amdgcn_sched_barrier(0)
; template <class Epi, class Sched, bool STAMP = false>
; __device__ __forceinline__ void gemm_phase(PG8_LAS unsigned char* lds, const Gemm g, const Sched& S, const Epi& E, unsigned long long* stamps) {
;     ...
;             PG8_WAIT_L(8); PG8_BAR; PG8_WAIT_L(0); PG8_MMA(0, 0, At, B0); PG8_BAR; PG8_SCHED;
;             PG8_LDB(B1, 1, 1); PG8_STAGE(PG8_SB(1, 0), b3, voffB);
;             PG8_BAR; PG8_WAIT_L(0); PG8_MMA(0, 1, At, B1); PG8_BAR;
;             PG8_LDA(At, 1, 1); PG8_STAGE(PG8_SA(1, 0), a3, voffA);
;             PG8_BAR; PG8_WAIT_L(0); PG8_MMA(1, 0, At, B0); PG8_BAR; PG8_SCHED;
;             PG8_STAGE(PG8_SB(1, 1), b3 + hstep, voffB);
;             PG8_WAIT_V(6); PG8_BAR; PG8_MMA(1, 1, At, B1); PG8_BAR;
	s_waitcnt lgkmcnt(0)
	v_mfma_f32_16x16x32_bf16 v[124:127], v[162:165], v[178:181], v[124:127]
	v_mfma_f32_16x16x32_bf16 v[120:123], v[170:173], v[178:181], v[120:123]
	v_mfma_f32_16x16x32_bf16 v[116:119], v[162:165], v[196:199], v[116:119]
	v_mfma_f32_16x16x32_bf16 v[112:115], v[170:173], v[196:199], v[112:115]
	v_mfma_f32_16x16x32_bf16 v[100:103], v[162:165], v[204:207], v[100:103]
	v_mfma_f32_16x16x32_bf16 v[96:99], v[170:173], v[204:207], v[96:99]
	v_mfma_f32_16x16x32_bf16 v[84:87], v[162:165], v[212:215], v[84:87]
	v_mfma_f32_16x16x32_bf16 v[80:83], v[170:173], v[212:215], v[80:83]
	v_mfma_f32_16x16x32_bf16 v[124:127], v[166:169], v[192:195], v[124:127]
	v_mfma_f32_16x16x32_bf16 v[120:123], v[174:177], v[192:195], v[120:123]
	v_mfma_f32_16x16x32_bf16 v[116:119], v[166:169], v[200:203], v[116:119]
	v_mfma_f32_16x16x32_bf16 v[112:115], v[174:177], v[200:203], v[112:115]
	v_mfma_f32_16x16x32_bf16 v[100:103], v[166:169], v[208:211], v[100:103]
	v_mfma_f32_16x16x32_bf16 v[96:99], v[174:177], v[208:211], v[96:99]
	v_mfma_f32_16x16x32_bf16 v[84:87], v[166:169], v[216:219], v[84:87]
	v_mfma_f32_16x16x32_bf16 v[80:83], v[174:177], v[216:219], v[80:83]
	s_barrier
	s_add_i32 s17, 0, 0x1c000
	s_add_i32 s14, s16, s53
	v_add_u32_e32 v161, s17, v158
	s_mov_b32 m0, s14
	ds_read_b128 v[220:223], v161
	ds_read_b128 v[224:227], v161 offset:1024
	ds_read_b128 v[228:231], v161 offset:2048
	ds_read_b128 v[232:235], v161 offset:3072
	global_load_lds_dwordx4 v244, s[56:57]
	s_add_i32 m0, s14, 0x2000
	s_nop 0
	global_load_lds_dwordx4 v245, s[56:57]
	s_barrier
	s_waitcnt lgkmcnt(0)
	v_mfma_f32_16x16x32_bf16 v[108:111], v[220:223], v[178:181], v[108:111]
	v_mfma_f32_16x16x32_bf16 v[104:107], v[228:231], v[178:181], v[104:107]
	v_mfma_f32_16x16x32_bf16 v[92:95], v[220:223], v[196:199], v[92:95]
	v_mfma_f32_16x16x32_bf16 v[88:91], v[228:231], v[196:199], v[88:91]
	v_mfma_f32_16x16x32_bf16 v[76:79], v[220:223], v[204:207], v[76:79]
	v_mfma_f32_16x16x32_bf16 v[72:75], v[228:231], v[204:207], v[72:75]
	v_mfma_f32_16x16x32_bf16 v[68:71], v[220:223], v[212:215], v[68:71]
	v_mfma_f32_16x16x32_bf16 v[64:67], v[228:231], v[212:215], v[64:67]
	v_mfma_f32_16x16x32_bf16 v[108:111], v[224:227], v[192:195], v[108:111]
	v_mfma_f32_16x16x32_bf16 v[104:107], v[232:235], v[192:195], v[104:107]
	v_mfma_f32_16x16x32_bf16 v[92:95], v[224:227], v[200:203], v[92:95]
	v_mfma_f32_16x16x32_bf16 v[88:91], v[232:235], v[200:203], v[88:91]
	v_mfma_f32_16x16x32_bf16 v[76:79], v[224:227], v[208:211], v[76:79]
	v_mfma_f32_16x16x32_bf16 v[72:75], v[232:235], v[208:211], v[72:75]
	v_mfma_f32_16x16x32_bf16 v[68:71], v[224:227], v[216:219], v[68:71]
	v_mfma_f32_16x16x32_bf16 v[64:67], v[232:235], v[216:219], v[64:67]
	s_mov_b32 m0, s63
	s_barrier
	ds_read_b128 v[178:181], v160 offset:49152
	ds_read_b128 v[192:195], v160 offset:50176
	ds_read_b128 v[196:199], v160 offset:51200
	ds_read_b128 v[200:203], v160 offset:52224
	ds_read_b128 v[204:207], v160 offset:53248
	ds_read_b128 v[208:211], v160 offset:54272
	ds_read_b128 v[212:215], v160 offset:55296
	ds_read_b128 v[216:219], v160 offset:56320
	global_load_lds_dwordx4 v246, s[58:59]
	s_mov_b32 m0, s64
	s_nop 0
	global_load_lds_dwordx4 v247, s[58:59]
	s_barrier
	s_waitcnt lgkmcnt(0)
	v_mfma_f32_16x16x32_bf16 v[60:63], v[162:165], v[178:181], v[60:63]
	v_mfma_f32_16x16x32_bf16 v[56:59], v[170:173], v[178:181], v[56:59]
	v_mfma_f32_16x16x32_bf16 v[52:55], v[162:165], v[196:199], v[52:55]
	v_mfma_f32_16x16x32_bf16 v[48:51], v[170:173], v[196:199], v[48:51]
	v_mfma_f32_16x16x32_bf16 v[36:39], v[162:165], v[204:207], v[36:39]
	v_mfma_f32_16x16x32_bf16 v[32:35], v[170:173], v[204:207], v[32:35]
	v_mfma_f32_16x16x32_bf16 v[20:23], v[162:165], v[212:215], v[20:23]
	v_mfma_f32_16x16x32_bf16 v[16:19], v[170:173], v[212:215], v[16:19]
	v_mfma_f32_16x16x32_bf16 v[60:63], v[166:169], v[192:195], v[60:63]
	v_mfma_f32_16x16x32_bf16 v[56:59], v[174:177], v[192:195], v[56:59]
	v_mfma_f32_16x16x32_bf16 v[52:55], v[166:169], v[200:203], v[52:55]
	v_mfma_f32_16x16x32_bf16 v[48:51], v[174:177], v[200:203], v[48:51]
	v_mfma_f32_16x16x32_bf16 v[36:39], v[166:169], v[208:211], v[36:39]
	v_mfma_f32_16x16x32_bf16 v[32:35], v[174:177], v[208:211], v[32:35]
	v_mfma_f32_16x16x32_bf16 v[20:23], v[166:169], v[216:219], v[20:23]
	v_mfma_f32_16x16x32_bf16 v[16:19], v[174:177], v[216:219], v[16:19]
	s_barrier
	s_add_u32 s14, s56, 0x20080
	s_addc_u32 s15, s57, 0
	s_add_i32 s16, s17, s53
	s_mov_b32 m0, s16
	s_nop 0
	global_load_lds_dwordx4 v128, s[14:15]
	s_add_i32 m0, s16, 0x2000
	s_nop 0
	global_load_lds_dwordx4 v152, s[14:15]
	s_waitcnt vmcnt(6)
	s_barrier
	v_mfma_f32_16x16x32_bf16 v[44:47], v[220:223], v[178:181], v[44:47]
	v_mfma_f32_16x16x32_bf16 v[40:43], v[228:231], v[178:181], v[40:43]
	v_mfma_f32_16x16x32_bf16 v[28:31], v[220:223], v[196:199], v[28:31]
	v_mfma_f32_16x16x32_bf16 v[24:27], v[228:231], v[196:199], v[24:27]
	v_mfma_f32_16x16x32_bf16 v[12:15], v[220:223], v[204:207], v[12:15]
	v_mfma_f32_16x16x32_bf16 v[8:11], v[228:231], v[204:207], v[8:11]
	v_mfma_f32_16x16x32_bf16 v[4:7], v[220:223], v[212:215], v[4:7]
	v_mfma_f32_16x16x32_bf16 v[0:3], v[228:231], v[212:215], v[0:3]
	v_mfma_f32_16x16x32_bf16 v[44:47], v[224:227], v[192:195], v[44:47]
	v_mfma_f32_16x16x32_bf16 v[40:43], v[232:235], v[192:195], v[40:43]
	v_mfma_f32_16x16x32_bf16 v[28:31], v[224:227], v[200:203], v[28:31]
	v_mfma_f32_16x16x32_bf16 v[24:27], v[232:235], v[200:203], v[24:27]
	v_mfma_f32_16x16x32_bf16 v[12:15], v[224:227], v[208:211], v[12:15]
	v_mfma_f32_16x16x32_bf16 v[8:11], v[232:235], v[208:211], v[8:11]
	v_mfma_f32_16x16x32_bf16 v[4:7], v[224:227], v[216:219], v[4:7]
	v_mfma_f32_16x16x32_bf16 v[0:3], v[232:235], v[216:219], v[0:3]
	s_add_i32 s97, s97, 2
	s_add_u32 s36, s36, 0x100
	s_addc_u32 s37, s37, 0
	s_add_u32 s89, s89, 0x100
	s_addc_u32 s96, s96, 0
	s_cmp_gt_u32 s97, 5
	s_barrier
; __device__ __forceinline__ unsigned cvt_pk_bf16(float lo, float hi) { const f32x2_cv v = {lo, hi}; const bf16x2_cv b = __builtin_convertvector(v, bf16x2_cv); return __builtin_bit_cast(unsigned, b); }
; __device__ __forceinline__ float rstd_of(const float* rowss, int row) { return rsqrtf(rowss[row] * (1.0f / 1024.0f) + 1e-6f); }
;     __device__ __forceinline__ void operator()(const f32x4 (&acc)[2][2][4][2], const pg8::Unit& u, int wr, int wc, int fr, int fq) const {
;         const int row0 = u.pm * 256 + wr * 64 + fr, col0 = u.pn * 256 + wc * 32 + 8 * fq;
; #pragma unroll
;         for (int ai = 0; ai < 2; ++ai)
; #pragma unroll
;             for (int m = 0; m < 4; ++m) {
;                 const int row = row0 + ai * 128 + m * 16;
;                 const float s = (MODE == 2) ? 1.0f : rstd_of(rowss, row);
;                 bf16_t* rowp = O + (size_t)row * ldc + col0;
; #pragma unroll
;                 for (int bj = 0; bj < 2; ++bj) {
;                     f32x4 v0 = acc[ai][bj][m][0] * s, v1 = acc[ai][bj][m][1] * s;
;                     if (MODE == 1) {
; #pragma unroll
;                         for (int j = 0; j < 4; ++j) { const float a = fmaxf(v0[j], 0.f), b = fmaxf(v1[j], 0.f); v0[j] = a * a; v1[j] = b * b; } }
;                     u32x4 w; w.x = cvt_pk_bf16(v0[0], v0[1]); w.y = cvt_pk_bf16(v0[2], v0[3]); w.z = cvt_pk_bf16(v1[0], v1[1]); w.w = cvt_pk_bf16(v1[2], v1[3]);
;                     *(u32x4*)(rowp + bj * 128) = w; } }
	s_cbranch_scc0 .LBB0_333
	v_lshl_add_u32 v162, s2, 8, v139
	v_lshl_or_b32 v164, s76, 8, v159
	v_ashrrev_i32_e32 v163, 31, v162
	v_ashrrev_i32_e32 v165, 31, v164
	v_lshlrev_b64 v[166:167], 11, v[162:163]
	v_lshl_add_u64 v[166:167], s[30:31], 0, v[166:167]
	v_lshlrev_b64 v[164:165], 1, v[164:165]
	v_lshl_add_u64 v[166:167], v[166:167], 0, v[164:165]
	s_mov_b32 s2, 0x40000
	s_mov_b64 s[14:15], 0x40000
	v_cvt_pk_bf16_f32 v60, v60, v61
	v_cvt_pk_bf16_f32 v61, v62, v63
	v_cvt_pk_bf16_f32 v62, v56, v57
	v_add_co_u32_e32 v56, vcc, s2, v166
	v_cvt_pk_bf16_f32 v68, v68, v69
	v_cvt_pk_bf16_f32 v69, v70, v71
	v_cvt_pk_bf16_f32 v70, v64, v65
	v_lshl_add_u64 v[64:65], v[166:167], 0, s[14:15]
	v_addc_co_u32_e32 v57, vcc, 0, v167, vcc
	v_cvt_pk_bf16_f32 v44, v44, v45
	v_cvt_pk_bf16_f32 v45, v46, v47
	v_cvt_pk_bf16_f32 v46, v40, v41
	v_cvt_pk_bf16_f32 v47, v42, v43
	s_mov_b32 s2, 0x48000
	v_cvt_pk_bf16_f32 v108, v108, v109
	v_cvt_pk_bf16_f32 v109, v110, v111
	v_cvt_pk_bf16_f32 v110, v104, v105
	v_or_b32_e32 v104, 16, v162
	global_store_dwordx4 v[64:65], v[44:47], off offset:256
	s_mov_b64 s[14:15], 0x48000
	v_ashrrev_i32_e32 v105, 31, v104
	v_add_co_u32_e32 v46, vcc, s2, v166
	v_cvt_pk_bf16_f32 v92, v92, v93
	v_cvt_pk_bf16_f32 v93, v94, v95
	v_cvt_pk_bf16_f32 v94, v88, v89
	v_or_b32_e32 v88, 32, v162
	v_lshl_add_u64 v[44:45], v[166:167], 0, s[14:15]
	v_addc_co_u32_e32 v47, vcc, 0, v167, vcc
	v_cvt_pk_bf16_f32 v28, v28, v29
	v_cvt_pk_bf16_f32 v29, v30, v31
	v_cvt_pk_bf16_f32 v30, v24, v25
	v_cvt_pk_bf16_f32 v31, v26, v27
	s_mov_b32 s2, 0x50000
	v_lshlrev_b64 v[104:105], 11, v[104:105]
	v_ashrrev_i32_e32 v89, 31, v88
	v_cvt_pk_bf16_f32 v76, v76, v77
	v_cvt_pk_bf16_f32 v77, v78, v79
	v_cvt_pk_bf16_f32 v78, v72, v73
	v_or_b32_e32 v72, 48, v162
	global_store_dwordx4 v[44:45], v[28:31], off offset:256
	s_mov_b64 s[14:15], 0x50000
	v_cvt_pk_bf16_f32 v111, v106, v107
	v_add_co_u32_e32 v30, vcc, s2, v166
	v_lshl_add_u64 v[104:105], s[30:31], 0, v[104:105]
	v_lshlrev_b64 v[88:89], 11, v[88:89]
	v_ashrrev_i32_e32 v73, 31, v72
	v_lshl_add_u64 v[28:29], v[166:167], 0, s[14:15]
	v_addc_co_u32_e32 v31, vcc, 0, v167, vcc
	v_cvt_pk_bf16_f32 v12, v12, v13
	v_cvt_pk_bf16_f32 v13, v14, v15
	v_cvt_pk_bf16_f32 v14, v8, v9
	v_cvt_pk_bf16_f32 v15, v10, v11
	s_mov_b32 s2, 0x58000
	global_store_dwordx4 v[166:167], v[108:111], off offset:256
	v_cvt_pk_bf16_f32 v95, v90, v91
	v_lshl_add_u64 v[88:89], s[30:31], 0, v[88:89]
	v_lshl_add_u64 v[108:109], v[104:105], 0, v[164:165]
	v_lshlrev_b64 v[72:73], 11, v[72:73]
	global_store_dwordx4 v[28:29], v[12:15], off offset:256
	global_store_dwordx4 v[108:109], v[92:95], off offset:256
	v_cvt_pk_bf16_f32 v79, v74, v75
	v_add_co_u32_e32 v14, vcc, s2, v166
	v_lshl_add_u64 v[92:93], v[88:89], 0, v[164:165]
	v_lshl_add_u64 v[72:73], s[30:31], 0, v[72:73]
	s_mov_b64 s[14:15], 0x58000
	v_addc_co_u32_e32 v15, vcc, 0, v167, vcc
	v_readlane_b32 s88, v242, 39
	v_cvt_pk_bf16_f32 v124, v124, v125
	v_cvt_pk_bf16_f32 v125, v126, v127
	v_cvt_pk_bf16_f32 v126, v120, v121
	v_cvt_pk_bf16_f32 v127, v122, v123
	v_cvt_pk_bf16_f32 v104, v116, v117
	v_cvt_pk_bf16_f32 v105, v118, v119
	v_cvt_pk_bf16_f32 v106, v112, v113
	v_cvt_pk_bf16_f32 v107, v114, v115
	v_cvt_pk_bf16_f32 v88, v100, v101
	v_cvt_pk_bf16_f32 v89, v102, v103
	v_cvt_pk_bf16_f32 v90, v96, v97
	v_cvt_pk_bf16_f32 v91, v98, v99
	global_store_dwordx4 v[92:93], v[76:79], off offset:256
	v_cvt_pk_bf16_f32 v74, v80, v81
	v_cvt_pk_bf16_f32 v75, v82, v83
	v_lshl_add_u64 v[76:77], v[72:73], 0, v[164:165]
	v_cvt_pk_bf16_f32 v72, v84, v85
	v_cvt_pk_bf16_f32 v73, v86, v87
	v_cvt_pk_bf16_f32 v71, v66, v67
	v_cvt_pk_bf16_f32 v63, v58, v59
	v_cvt_pk_bf16_f32 v40, v52, v53
	v_cvt_pk_bf16_f32 v41, v54, v55
	v_cvt_pk_bf16_f32 v42, v48, v49
	v_cvt_pk_bf16_f32 v43, v50, v51
	v_cvt_pk_bf16_f32 v24, v36, v37
	v_cvt_pk_bf16_f32 v25, v38, v39
	v_cvt_pk_bf16_f32 v26, v32, v33
	v_cvt_pk_bf16_f32 v27, v34, v35
	v_lshl_add_u64 v[12:13], v[166:167], 0, s[14:15]
	v_cvt_pk_bf16_f32 v8, v20, v21
	v_cvt_pk_bf16_f32 v9, v22, v23
	v_cvt_pk_bf16_f32 v10, v16, v17
	v_cvt_pk_bf16_f32 v11, v18, v19
	v_cvt_pk_bf16_f32 v4, v4, v5
	v_cvt_pk_bf16_f32 v5, v6, v7
	v_cvt_pk_bf16_f32 v6, v0, v1
	v_cvt_pk_bf16_f32 v7, v2, v3
	s_and_b64 vcc, exec, s[38:39]
	s_mov_b32 s76, s4
	s_mov_b32 s2, s12
	s_mov_b64 s[56:57], s[26:27]
	s_mov_b64 s[36:37], s[24:25]
	s_movk_i32 s77, 0xa0
	s_movk_i32 s58, 0xff60
	v_readlane_b32 s89, v242, 40
	global_store_dwordx4 v[166:167], v[124:127], off
	global_store_dwordx4 v[108:109], v[104:107], off
	global_store_dwordx4 v[92:93], v[88:91], off
	global_store_dwordx4 v[76:77], v[72:75], off
	global_store_dwordx4 v[76:77], v[68:71], off offset:256
	global_store_dwordx4 v[56:57], v[60:63], off
	global_store_dwordx4 v[46:47], v[40:43], off
	global_store_dwordx4 v[30:31], v[24:27], off
	global_store_dwordx4 v[14:15], v[8:11], off
	global_store_dwordx4 v[12:13], v[4:7], off offset:256
	s_cbranch_vccz .LBB0_326
	s_cmpk_gt_u32 s46, 0xff
	s_cbranch_scc1 .LBB0_337
	s_barrier

; #define PG8_STAGE(bufoff, gbase, voff) do { _Pragma("unroll") for (int _i = 0; _i < 2; ++_i) \
;         __builtin_amdgcn_global_load_lds((const unsigned*)((const char*)(gbase) + (voff)[_i]), (PG8_LAS unsigned*)(lds + (bufoff) + ldsw + _i * 8192), 16, 0, 0); } while (0)
; #define PG8_LDA(dst, b, h) do { _Pragma("unroll") for (int m = 0; m < 4; ++m) _Pragma("unroll") for (int k = 0; k < 2; ++k) dst[m][k] = *(const PG8_LAS bf16x8*)(lds + PG8_SA(b, h) + aoff + m * 2048 + k * 1024); } while (0)
; #define PG8_LDB(dst, b, h) do { _Pragma("unroll") for (int n = 0; n < 2; ++n) _Pragma("unroll") for (int k = 0; k < 2; ++k) dst[n][k] = *(const PG8_LAS bf16x8*)(lds + PG8_SB(b, h) + boff + n * 2048 + k * 1024); } while (0)
; #define PG8_MMA(ai, bj, At, Bt) do { __builtin_amdgcn_s_setprio(1); _Pragma("unroll") for (int m = 0; m < 4; ++m) _Pragma("unroll") for (int n = 0; n < 2; ++n) _Pragma("unroll") for (int k = 0; k < 2; ++k) \
;         acc[ai][bj][m][n] = __builtin_amdgcn_mfma_f32_16x16x32_bf16(Bt[n][k], At[m][k], acc[ai][bj][m][n], 0, 0, 0); __builtin_amdgcn_s_setprio(0); } while (0)
; #define PG8_WAIT_L(n) asm volatile("s_waitcnt lgkmcnt(" #n ")" ::: "memory")
; #define PG8_BAR __builtin_amdgcn_s_barrier()
; #define PG8_SCHED __builtin_amdgcn_sched_barrier(0)
; template <class Epi, class Sched, bool STAMP = false>
; __device__ __forceinline__ void gemm_phase(PG8_LAS unsigned char* lds, const Gemm g, const Sched& S, const Epi& E, unsigned long long* stamps) {
;     ...
;             PG8_LDB(B0, 0, 0); PG8_SCHED; PG8_LDA(At, 0, 0); PG8_STAGE(PG8_SA(1, 1), a1 + hstep, voffA);
;             PG8_WAIT_L(8); PG8_BAR; PG8_WAIT_L(0); PG8_MMA(0, 0, At, B0); PG8_BAR; PG8_SCHED;
;     ...
; #pragma unroll
;         for (int a = 0; a < 2; ++a)
; #pragma unroll
;             for (int b = 0; b < 2; ++b)
; #pragma unroll
;                 for (int m = 0; m < 4; ++m)
; #pragma unroll
;                     for (int n = 0; n < 2; ++n) acc[a][b][m][n] = (f32x4){0.f, 0.f, 0.f, 0.f};
;         cur = nxt; cA = nA; cB = nB; ++ui;
.LBB0_352:
	s_ashr_i32 s13, s12, 31
	v_cmp_lt_i64_e32 vcc, s[4:5], v[136:137]
	s_lshl_b64 s[4:5], s[12:13], 19
	s_add_u32 s4, s42, s4
	s_addc_u32 s5, s43, s5
	s_and_b64 s[14:15], vcc, exec
	s_cselect_b32 s13, s5, s57
	s_cselect_b32 s47, s4, s56
	s_ashr_i32 s27, s26, 31
	s_lshl_b64 s[14:15], s[26:27], 19
	s_add_u32 s36, s24, s14
	s_addc_u32 s37, s25, s15
	s_and_b64 s[14:15], vcc, exec
	s_cselect_b32 s27, s37, s59
	s_cselect_b32 s53, s36, s58
	s_add_u32 s56, s56, 0x40080
	s_addc_u32 s57, s57, 0
	s_add_u32 s76, s58, 0x100
	v_mov_b32_e32 v0, 0
	s_addc_u32 s77, s59, 0
	s_mov_b32 vcc_lo, -2
	v_mov_b32_e32 v1, v0
	v_mov_b32_e32 v2, v0
	v_mov_b32_e32 v3, v0
	v_mov_b32_e32 v4, v0
	v_mov_b32_e32 v5, v0
	v_mov_b32_e32 v6, v0
	v_mov_b32_e32 v7, v0
	v_mov_b32_e32 v16, v0
	v_mov_b32_e32 v17, v0
	v_mov_b32_e32 v18, v0
	v_mov_b32_e32 v19, v0
	v_mov_b32_e32 v20, v0
	v_mov_b32_e32 v21, v0
	v_mov_b32_e32 v22, v0
	v_mov_b32_e32 v23, v0
	v_mov_b32_e32 v32, v0
	v_mov_b32_e32 v33, v0
	v_mov_b32_e32 v34, v0
	v_mov_b32_e32 v35, v0
	v_mov_b32_e32 v36, v0
	v_mov_b32_e32 v37, v0
	v_mov_b32_e32 v38, v0
	v_mov_b32_e32 v39, v0
	v_mov_b32_e32 v48, v0
	v_mov_b32_e32 v49, v0
	v_mov_b32_e32 v50, v0
	v_mov_b32_e32 v51, v0
	v_mov_b32_e32 v52, v0
	v_mov_b32_e32 v53, v0
	v_mov_b32_e32 v54, v0
	v_mov_b32_e32 v55, v0
	v_mov_b32_e32 v8, v0
	v_mov_b32_e32 v9, v0
	v_mov_b32_e32 v10, v0
	v_mov_b32_e32 v11, v0
	v_mov_b32_e32 v12, v0
	v_mov_b32_e32 v13, v0
	v_mov_b32_e32 v14, v0
	v_mov_b32_e32 v15, v0
	v_mov_b32_e32 v24, v0
	v_mov_b32_e32 v25, v0
	v_mov_b32_e32 v26, v0
	v_mov_b32_e32 v27, v0
	v_mov_b32_e32 v28, v0
	v_mov_b32_e32 v29, v0
	v_mov_b32_e32 v30, v0
	v_mov_b32_e32 v31, v0
	v_mov_b32_e32 v40, v0
	v_mov_b32_e32 v41, v0
	v_mov_b32_e32 v42, v0
	v_mov_b32_e32 v43, v0
	v_mov_b32_e32 v44, v0
	v_mov_b32_e32 v45, v0
	v_mov_b32_e32 v46, v0
	v_mov_b32_e32 v47, v0
	v_mov_b32_e32 v56, v0
	v_mov_b32_e32 v57, v0
	v_mov_b32_e32 v58, v0
	v_mov_b32_e32 v59, v0
	v_mov_b32_e32 v60, v0
	v_mov_b32_e32 v61, v0
	v_mov_b32_e32 v62, v0
	v_mov_b32_e32 v63, v0
	v_mov_b32_e32 v64, v0
	v_mov_b32_e32 v65, v0
	v_mov_b32_e32 v66, v0
	v_mov_b32_e32 v67, v0
	v_mov_b32_e32 v68, v0
	v_mov_b32_e32 v69, v0
	v_mov_b32_e32 v70, v0
	v_mov_b32_e32 v71, v0
	v_mov_b32_e32 v80, v0
	v_mov_b32_e32 v81, v0
	v_mov_b32_e32 v82, v0
	v_mov_b32_e32 v83, v0
	v_mov_b32_e32 v84, v0
	v_mov_b32_e32 v85, v0
	v_mov_b32_e32 v86, v0
	v_mov_b32_e32 v87, v0
	v_mov_b32_e32 v96, v0
	v_mov_b32_e32 v97, v0
	v_mov_b32_e32 v98, v0
	v_mov_b32_e32 v99, v0
	v_mov_b32_e32 v100, v0
	v_mov_b32_e32 v101, v0
	v_mov_b32_e32 v102, v0
	v_mov_b32_e32 v103, v0
	v_mov_b32_e32 v112, v0
	v_mov_b32_e32 v113, v0
	v_mov_b32_e32 v114, v0
	v_mov_b32_e32 v115, v0
	v_mov_b32_e32 v116, v0
	v_mov_b32_e32 v117, v0
	v_mov_b32_e32 v118, v0
	v_mov_b32_e32 v119, v0
	v_mov_b32_e32 v72, v0
	v_mov_b32_e32 v73, v0
	v_mov_b32_e32 v74, v0
	v_mov_b32_e32 v75, v0
	v_mov_b32_e32 v76, v0
	v_mov_b32_e32 v77, v0
	v_mov_b32_e32 v78, v0
	v_mov_b32_e32 v79, v0
	v_mov_b32_e32 v88, v0
	v_mov_b32_e32 v89, v0
	v_mov_b32_e32 v90, v0
	v_mov_b32_e32 v91, v0
	v_mov_b32_e32 v92, v0
	v_mov_b32_e32 v93, v0
	v_mov_b32_e32 v94, v0
	v_mov_b32_e32 v95, v0
	v_mov_b32_e32 v104, v0
	v_mov_b32_e32 v105, v0
	v_mov_b32_e32 v106, v0
	v_mov_b32_e32 v107, v0
	v_mov_b32_e32 v108, v0
	v_mov_b32_e32 v109, v0
	v_mov_b32_e32 v110, v0
	v_mov_b32_e32 v111, v0
	v_mov_b32_e32 v120, v0
	v_mov_b32_e32 v121, v0
	v_mov_b32_e32 v122, v0
	v_mov_b32_e32 v123, v0
	v_mov_b32_e32 v124, v0
	v_mov_b32_e32 v125, v0
	v_mov_b32_e32 v126, v0
	v_mov_b32_e32 v127, v0
	v_add_u32_e32 v244, 0x80, v128
	v_add_u32_e32 v245, 0x80, v152
	v_add_u32_e32 v246, 0x80, v148
	v_add_u32_e32 v247, 0x80, v150
.LBB0_353:
	s_add_u32 s14, s56, 0xfffc0080
	s_addc_u32 s15, s57, -1
	s_add_i32 s16, 0, 0x10000
	v_add_u32_e32 v166, s16, v167
	ds_read_b128 v[158:161], v166
	ds_read_b128 v[162:165], v166 offset:1024
	ds_read_b128 v[172:175], v166 offset:2048
	ds_read_b128 v[176:179], v166 offset:3072
	s_cmp_eq_u32 vcc_lo, 12
	s_cselect_b32 s61, s13, s15
	s_cselect_b32 s60, s47, s14
	s_cselect_b32 s59, s27, s77
	s_cselect_b32 s58, s53, s76
	s_add_i32 m0, s89, 0xc000
	ds_read_b128 v[180:183], v171
	ds_read_b128 v[192:195], v171 offset:1024
	ds_read_b128 v[196:199], v171 offset:2048
	ds_read_b128 v[200:203], v171 offset:3072
	ds_read_b128 v[204:207], v171 offset:4096
	ds_read_b128 v[208:211], v171 offset:5120
	ds_read_b128 v[212:215], v171 offset:6144
	ds_read_b128 v[216:219], v171 offset:7168
	global_load_lds_dwordx4 v154, s[56:57]
	s_add_i32 m0, s89, 0xe000
	s_nop 0
	global_load_lds_dwordx4 v156, s[56:57]
	s_waitcnt lgkmcnt(8)
	s_barrier
	s_waitcnt lgkmcnt(0)
	v_mfma_f32_16x16x32_bf16 v[124:127], v[158:161], v[180:183], v[124:127]
	v_mfma_f32_16x16x32_bf16 v[120:123], v[172:175], v[180:183], v[120:123]
	v_mfma_f32_16x16x32_bf16 v[108:111], v[158:161], v[196:199], v[108:111]
	v_mfma_f32_16x16x32_bf16 v[104:107], v[172:175], v[196:199], v[104:107]
	v_mfma_f32_16x16x32_bf16 v[92:95], v[158:161], v[204:207], v[92:95]
	v_mfma_f32_16x16x32_bf16 v[88:91], v[172:175], v[204:207], v[88:91]
	v_mfma_f32_16x16x32_bf16 v[76:79], v[158:161], v[212:215], v[76:79]
	v_mfma_f32_16x16x32_bf16 v[72:75], v[172:175], v[212:215], v[72:75]
	v_mfma_f32_16x16x32_bf16 v[124:127], v[162:165], v[192:195], v[124:127]
	v_mfma_f32_16x16x32_bf16 v[120:123], v[176:179], v[192:195], v[120:123]
	v_mfma_f32_16x16x32_bf16 v[108:111], v[162:165], v[200:203], v[108:111]
	v_mfma_f32_16x16x32_bf16 v[104:107], v[176:179], v[200:203], v[104:107]
	v_mfma_f32_16x16x32_bf16 v[92:95], v[162:165], v[208:211], v[92:95]
	v_mfma_f32_16x16x32_bf16 v[88:91], v[176:179], v[208:211], v[88:91]
	v_mfma_f32_16x16x32_bf16 v[76:79], v[162:165], v[216:219], v[76:79]
	v_mfma_f32_16x16x32_bf16 v[72:75], v[176:179], v[216:219], v[72:75]
	s_barrier
; #define PG8_STAGE(bufoff, gbase, voff) do { _Pragma("unroll") for (int _i = 0; _i < 2; ++_i) \
;         __builtin_amdgcn_global_load_lds((const unsigned*)((const char*)(gbase) + (voff)[_i]), (PG8_LAS unsigned*)(lds + (bufoff) + ldsw + _i * 8192), 16, 0, 0); } while (0)
; #define PG8_LDA(dst, b, h) do { _Pragma("unroll") for (int m = 0; m < 4; ++m) _Pragma("unroll") for (int k = 0; k < 2; ++k) dst[m][k] = *(const PG8_LAS bf16x8*)(lds + PG8_SA(b, h) + aoff + m * 2048 + k * 1024); } while (0)
; #define PG8_LDB(dst, b, h) do { _Pragma("unroll") for (int n = 0; n < 2; ++n) _Pragma("unroll") for (int k = 0; k < 2; ++k) dst[n][k] = *(const PG8_LAS bf16x8*)(lds + PG8_SB(b, h) + boff + n * 2048 + k * 1024); } while (0)
; #define PG8_MMA(ai, bj, At, Bt) do { __builtin_amdgcn_s_setprio(1); _Pragma("unroll") for (int m = 0; m < 4; ++m) _Pragma("unroll") for (int n = 0; n < 2; ++n) _Pragma("unroll") for (int k = 0; k < 2; ++k) \
;         acc[ai][bj][m][n] = __builtin_amdgcn_mfma_f32_16x16x32_bf16(Bt[n][k], At[m][k], acc[ai][bj][m][n], 0, 0, 0); __builtin_amdgcn_s_setprio(0); } while (0)
; #define PG8_WAIT_V(n) asm volatile("s_waitcnt vmcnt(" #n ")" ::: "memory")
; #define PG8_WAIT_L(n) asm volatile("s_waitcnt lgkmcnt(" #n ")" ::: "memory")
; #define PG8_BAR __builtin_amdgcn_s_barrier()
; #define PG8_SCHED __builtin_amdgcn_sched_barrier(0)
; template <class Epi, class Sched, bool STAMP = false>
; __device__ __forceinline__ void gemm_phase(PG8_LAS unsigned char* lds, const Gemm g, const Sched& S, const Epi& E, unsigned long long* stamps) {
;     ...
;             PG8_LDB(B1, 0, 1); PG8_STAGE(PG8_SB(0, 0), b2, voffB);
;             PG8_BAR; PG8_WAIT_L(0); PG8_MMA(0, 1, At, B1); PG8_BAR;
;             PG8_LDA(At, 0, 1); PG8_STAGE(PG8_SA(0, 0), a2, voffA);
;             PG8_BAR; PG8_WAIT_L(0); PG8_MMA(1, 0, At, B0); PG8_BAR; PG8_SCHED;
;             PG8_STAGE(PG8_SB(0, 1), b2 + hstep, voffB);
;             PG8_WAIT_V(6); PG8_BAR; PG8_MMA(1, 1, At, B1); PG8_BAR;
;             PG8_LDB(B0, 1, 0); PG8_SCHED; PG8_LDA(At, 1, 0); PG8_STAGE(PG8_SA(0, 1), a2 + hstep, voffA);
;             PG8_WAIT_L(8); PG8_BAR; PG8_WAIT_L(0); PG8_MMA(0, 0, At, B0); PG8_BAR; PG8_SCHED;
	s_add_i32 s17, 0, 0x14000
	s_add_i32 s14, s16, s88
	v_add_u32_e32 v166, s17, v167
	s_mov_b32 m0, s14
	ds_read_b128 v[220:223], v166
	ds_read_b128 v[224:227], v166 offset:1024
	ds_read_b128 v[228:231], v166 offset:2048
	ds_read_b128 v[232:235], v166 offset:3072
	global_load_lds_dwordx4 v128, s[58:59]
	s_add_i32 m0, s14, 0x2000
	s_nop 0
	global_load_lds_dwordx4 v152, s[58:59]
	s_barrier
	s_waitcnt lgkmcnt(0)
	v_mfma_f32_16x16x32_bf16 v[116:119], v[220:223], v[180:183], v[116:119]
	v_mfma_f32_16x16x32_bf16 v[112:115], v[228:231], v[180:183], v[112:115]
	v_mfma_f32_16x16x32_bf16 v[100:103], v[220:223], v[196:199], v[100:103]
	v_mfma_f32_16x16x32_bf16 v[96:99], v[228:231], v[196:199], v[96:99]
	v_mfma_f32_16x16x32_bf16 v[84:87], v[220:223], v[204:207], v[84:87]
	v_mfma_f32_16x16x32_bf16 v[80:83], v[228:231], v[204:207], v[80:83]
	v_mfma_f32_16x16x32_bf16 v[68:71], v[220:223], v[212:215], v[68:71]
	v_mfma_f32_16x16x32_bf16 v[64:67], v[228:231], v[212:215], v[64:67]
	v_mfma_f32_16x16x32_bf16 v[116:119], v[224:227], v[192:195], v[116:119]
	v_mfma_f32_16x16x32_bf16 v[112:115], v[232:235], v[192:195], v[112:115]
	v_mfma_f32_16x16x32_bf16 v[100:103], v[224:227], v[200:203], v[100:103]
	v_mfma_f32_16x16x32_bf16 v[96:99], v[232:235], v[200:203], v[96:99]
	v_mfma_f32_16x16x32_bf16 v[84:87], v[224:227], v[208:211], v[84:87]
	v_mfma_f32_16x16x32_bf16 v[80:83], v[232:235], v[208:211], v[80:83]
	v_mfma_f32_16x16x32_bf16 v[68:71], v[224:227], v[216:219], v[68:71]
	v_mfma_f32_16x16x32_bf16 v[64:67], v[232:235], v[216:219], v[64:67]
	s_mov_b32 m0, s89
	s_barrier
	ds_read_b128 v[180:183], v171 offset:16384
	ds_read_b128 v[192:195], v171 offset:17408
	ds_read_b128 v[196:199], v171 offset:18432
	ds_read_b128 v[200:203], v171 offset:19456
	ds_read_b128 v[204:207], v171 offset:20480
	ds_read_b128 v[208:211], v171 offset:21504
	ds_read_b128 v[212:215], v171 offset:22528
	ds_read_b128 v[216:219], v171 offset:23552
	global_load_lds_dwordx4 v148, s[60:61]
	s_mov_b32 m0, s96
	s_nop 0
	global_load_lds_dwordx4 v150, s[60:61]
	s_barrier
	s_waitcnt lgkmcnt(0)
	v_mfma_f32_16x16x32_bf16 v[60:63], v[158:161], v[180:183], v[60:63]
	v_mfma_f32_16x16x32_bf16 v[56:59], v[172:175], v[180:183], v[56:59]
	v_mfma_f32_16x16x32_bf16 v[44:47], v[158:161], v[196:199], v[44:47]
	v_mfma_f32_16x16x32_bf16 v[40:43], v[172:175], v[196:199], v[40:43]
	v_mfma_f32_16x16x32_bf16 v[28:31], v[158:161], v[204:207], v[28:31]
	v_mfma_f32_16x16x32_bf16 v[24:27], v[172:175], v[204:207], v[24:27]
	v_mfma_f32_16x16x32_bf16 v[12:15], v[158:161], v[212:215], v[12:15]
	v_mfma_f32_16x16x32_bf16 v[8:11], v[172:175], v[212:215], v[8:11]
	v_mfma_f32_16x16x32_bf16 v[60:63], v[162:165], v[192:195], v[60:63]
	v_mfma_f32_16x16x32_bf16 v[56:59], v[176:179], v[192:195], v[56:59]
	v_mfma_f32_16x16x32_bf16 v[44:47], v[162:165], v[200:203], v[44:47]
	v_mfma_f32_16x16x32_bf16 v[40:43], v[176:179], v[200:203], v[40:43]
	v_mfma_f32_16x16x32_bf16 v[28:31], v[162:165], v[208:211], v[28:31]
	v_mfma_f32_16x16x32_bf16 v[24:27], v[176:179], v[208:211], v[24:27]
	v_mfma_f32_16x16x32_bf16 v[12:15], v[162:165], v[216:219], v[12:15]
	v_mfma_f32_16x16x32_bf16 v[8:11], v[176:179], v[216:219], v[8:11]
	s_barrier
	s_add_u32 s14, s58, 0x40000
	s_addc_u32 s15, s59, 0
	s_add_i32 s16, s17, s88
	s_mov_b32 m0, s16
	s_nop 0
	global_load_lds_dwordx4 v128, s[14:15]
	s_add_i32 m0, s16, 0x2000
	s_nop 0
	global_load_lds_dwordx4 v152, s[14:15]
	s_waitcnt vmcnt(6)
	s_barrier
	v_mfma_f32_16x16x32_bf16 v[52:55], v[220:223], v[180:183], v[52:55]
	v_mfma_f32_16x16x32_bf16 v[48:51], v[228:231], v[180:183], v[48:51]
	v_mfma_f32_16x16x32_bf16 v[36:39], v[220:223], v[196:199], v[36:39]
	v_mfma_f32_16x16x32_bf16 v[32:35], v[228:231], v[196:199], v[32:35]
	v_mfma_f32_16x16x32_bf16 v[20:23], v[220:223], v[204:207], v[20:23]
	v_mfma_f32_16x16x32_bf16 v[16:19], v[228:231], v[204:207], v[16:19]
	v_mfma_f32_16x16x32_bf16 v[4:7], v[220:223], v[212:215], v[4:7]
	v_mfma_f32_16x16x32_bf16 v[0:3], v[228:231], v[212:215], v[0:3]
	v_mfma_f32_16x16x32_bf16 v[52:55], v[224:227], v[192:195], v[52:55]
	v_mfma_f32_16x16x32_bf16 v[48:51], v[232:235], v[192:195], v[48:51]
	v_mfma_f32_16x16x32_bf16 v[36:39], v[224:227], v[200:203], v[36:39]
	v_mfma_f32_16x16x32_bf16 v[32:35], v[232:235], v[200:203], v[32:35]
	v_mfma_f32_16x16x32_bf16 v[20:23], v[224:227], v[208:211], v[20:23]
	v_mfma_f32_16x16x32_bf16 v[16:19], v[232:235], v[208:211], v[16:19]
	v_mfma_f32_16x16x32_bf16 v[4:7], v[224:227], v[216:219], v[4:7]
	v_mfma_f32_16x16x32_bf16 v[0:3], v[232:235], v[216:219], v[0:3]
	s_add_i32 s16, 0, 0x18000
	v_add_u32_e32 v166, s16, v167
	s_barrier
	ds_read_b128 v[158:161], v166
	ds_read_b128 v[162:165], v166 offset:1024
	ds_read_b128 v[172:175], v166 offset:2048
	ds_read_b128 v[176:179], v166 offset:3072
	s_add_u32 s14, s60, 0x40000
	s_addc_u32 s15, s61, 0
	s_mov_b32 m0, s97
	ds_read_b128 v[180:183], v171 offset:32768
	ds_read_b128 v[192:195], v171 offset:33792
	ds_read_b128 v[196:199], v171 offset:34816
	ds_read_b128 v[200:203], v171 offset:35840
	ds_read_b128 v[204:207], v171 offset:36864
	ds_read_b128 v[208:211], v171 offset:37888
	ds_read_b128 v[212:215], v171 offset:38912
	ds_read_b128 v[216:219], v171 offset:39936
	global_load_lds_dwordx4 v148, s[14:15]
	s_mov_b32 m0, s64
	s_nop 0
	global_load_lds_dwordx4 v150, s[14:15]
	s_waitcnt lgkmcnt(8)
	s_barrier
; #define PG8_STAGE(bufoff, gbase, voff) do { _Pragma("unroll") for (int _i = 0; _i < 2; ++_i) \
;         __builtin_amdgcn_global_load_lds((const unsigned*)((const char*)(gbase) + (voff)[_i]), (PG8_LAS unsigned*)(lds + (bufoff) + ldsw + _i * 8192), 16, 0, 0); } while (0)
; #define PG8_LDA(dst, b, h) do { _Pragma("unroll") for (int m = 0; m < 4; ++m) _Pragma("unroll") for (int k = 0; k < 2; ++k) dst[m][k] = *(const PG8_LAS bf16x8*)(lds + PG8_SA(b, h) + aoff + m * 2048 + k * 1024); } while (0)
; #define PG8_LDB(dst, b, h) do { _Pragma("unroll") for (int n = 0; n < 2; ++n) _Pragma("unroll") for (int k = 0; k < 2; ++k) dst[n][k] = *(const PG8_LAS bf16x8*)(lds + PG8_SB(b, h) + boff + n * 2048 + k * 1024); } while (0)
; #define PG8_MMA(ai, bj, At, Bt) do { __builtin_amdgcn_s_setprio(1); _Pragma("unroll") for (int m = 0; m < 4; ++m) _Pragma("unroll") for (int n = 0; n < 2; ++n) _Pragma("unroll") for (int k = 0; k < 2; ++k) \
;         acc[ai][bj][m][n] = __builtin_amdgcn_mfma_f32_16x16x32_bf16(Bt[n][k], At[m][k], acc[ai][bj][m][n], 0, 0, 0); __builtin_amdgcn_s_setprio(0); } while (0)
; #define PG8_WAIT_V(n) asm volatile("s_waitcnt vmcnt(" #n ")" ::: "memory")
; #define PG8_WAIT_L(n) asm volatile("s_waitcnt lgkmcnt(" #n ")" ::: "memory")
; #define PG8_BAR __builtin_amdgcn_s_barrier()
; #define PG8_SCHED __builtin_amdgcn_sched_barrier(0)
; template <class Epi, class Sched, bool STAMP = false>
; __device__ __forceinline__ void gemm_phase(PG8_LAS unsigned char* lds, const Gemm g, const Sched& S, const Epi& E, unsigned long long* stamps) {
;     ...
;             PG8_WAIT_L(8); PG8_BAR; PG8_WAIT_L(0); PG8_MMA(0, 0, At, B0); PG8_BAR; PG8_SCHED;
;             PG8_LDB(B1, 1, 1); PG8_STAGE(PG8_SB(1, 0), b3, voffB);
;             PG8_BAR; PG8_WAIT_L(0); PG8_MMA(0, 1, At, B1); PG8_BAR;
;             PG8_LDA(At, 1, 1); PG8_STAGE(PG8_SA(1, 0), a3, voffA);
;             PG8_BAR; PG8_WAIT_L(0); PG8_MMA(1, 0, At, B0); PG8_BAR; PG8_SCHED;
;             PG8_STAGE(PG8_SB(1, 1), b3 + hstep, voffB);
;             PG8_WAIT_V(6); PG8_BAR; PG8_MMA(1, 1, At, B1); PG8_BAR;
	s_waitcnt lgkmcnt(0)
	v_mfma_f32_16x16x32_bf16 v[124:127], v[158:161], v[180:183], v[124:127]
	v_mfma_f32_16x16x32_bf16 v[120:123], v[172:175], v[180:183], v[120:123]
	v_mfma_f32_16x16x32_bf16 v[108:111], v[158:161], v[196:199], v[108:111]
	v_mfma_f32_16x16x32_bf16 v[104:107], v[172:175], v[196:199], v[104:107]
	v_mfma_f32_16x16x32_bf16 v[92:95], v[158:161], v[204:207], v[92:95]
	v_mfma_f32_16x16x32_bf16 v[88:91], v[172:175], v[204:207], v[88:91]
	v_mfma_f32_16x16x32_bf16 v[76:79], v[158:161], v[212:215], v[76:79]
	v_mfma_f32_16x16x32_bf16 v[72:75], v[172:175], v[212:215], v[72:75]
	v_mfma_f32_16x16x32_bf16 v[124:127], v[162:165], v[192:195], v[124:127]
	v_mfma_f32_16x16x32_bf16 v[120:123], v[176:179], v[192:195], v[120:123]
	v_mfma_f32_16x16x32_bf16 v[108:111], v[162:165], v[200:203], v[108:111]
	v_mfma_f32_16x16x32_bf16 v[104:107], v[176:179], v[200:203], v[104:107]
	v_mfma_f32_16x16x32_bf16 v[92:95], v[162:165], v[208:211], v[92:95]
	v_mfma_f32_16x16x32_bf16 v[88:91], v[176:179], v[208:211], v[88:91]
	v_mfma_f32_16x16x32_bf16 v[76:79], v[162:165], v[216:219], v[76:79]
	v_mfma_f32_16x16x32_bf16 v[72:75], v[176:179], v[216:219], v[72:75]
	s_barrier
	s_add_i32 s17, 0, 0x1c000
	s_add_i32 s14, s16, s88
	v_add_u32_e32 v166, s17, v167
	s_mov_b32 m0, s14
	ds_read_b128 v[220:223], v166
	ds_read_b128 v[224:227], v166 offset:1024
	ds_read_b128 v[228:231], v166 offset:2048
	ds_read_b128 v[232:235], v166 offset:3072
	global_load_lds_dwordx4 v244, s[58:59]
	s_add_i32 m0, s14, 0x2000
	s_nop 0
	global_load_lds_dwordx4 v245, s[58:59]
	s_barrier
	s_waitcnt lgkmcnt(0)
	v_mfma_f32_16x16x32_bf16 v[116:119], v[220:223], v[180:183], v[116:119]
	v_mfma_f32_16x16x32_bf16 v[112:115], v[228:231], v[180:183], v[112:115]
	v_mfma_f32_16x16x32_bf16 v[100:103], v[220:223], v[196:199], v[100:103]
	v_mfma_f32_16x16x32_bf16 v[96:99], v[228:231], v[196:199], v[96:99]
	v_mfma_f32_16x16x32_bf16 v[84:87], v[220:223], v[204:207], v[84:87]
	v_mfma_f32_16x16x32_bf16 v[80:83], v[228:231], v[204:207], v[80:83]
	v_mfma_f32_16x16x32_bf16 v[68:71], v[220:223], v[212:215], v[68:71]
	v_mfma_f32_16x16x32_bf16 v[64:67], v[228:231], v[212:215], v[64:67]
	v_mfma_f32_16x16x32_bf16 v[116:119], v[224:227], v[192:195], v[116:119]
	v_mfma_f32_16x16x32_bf16 v[112:115], v[232:235], v[192:195], v[112:115]
	v_mfma_f32_16x16x32_bf16 v[100:103], v[224:227], v[200:203], v[100:103]
	v_mfma_f32_16x16x32_bf16 v[96:99], v[232:235], v[200:203], v[96:99]
	v_mfma_f32_16x16x32_bf16 v[84:87], v[224:227], v[208:211], v[84:87]
	v_mfma_f32_16x16x32_bf16 v[80:83], v[232:235], v[208:211], v[80:83]
	v_mfma_f32_16x16x32_bf16 v[68:71], v[224:227], v[216:219], v[68:71]
	v_mfma_f32_16x16x32_bf16 v[64:67], v[232:235], v[216:219], v[64:67]
	s_mov_b32 m0, s62
	s_barrier
	ds_read_b128 v[180:183], v171 offset:49152
	ds_read_b128 v[192:195], v171 offset:50176
	ds_read_b128 v[196:199], v171 offset:51200
	ds_read_b128 v[200:203], v171 offset:52224
	ds_read_b128 v[204:207], v171 offset:53248
	ds_read_b128 v[208:211], v171 offset:54272
	ds_read_b128 v[212:215], v171 offset:55296
	ds_read_b128 v[216:219], v171 offset:56320
	global_load_lds_dwordx4 v246, s[60:61]
	s_mov_b32 m0, s63
	s_nop 0
	global_load_lds_dwordx4 v247, s[60:61]
	s_barrier
	s_waitcnt lgkmcnt(0)
	v_mfma_f32_16x16x32_bf16 v[60:63], v[158:161], v[180:183], v[60:63]
	v_mfma_f32_16x16x32_bf16 v[56:59], v[172:175], v[180:183], v[56:59]
	v_mfma_f32_16x16x32_bf16 v[44:47], v[158:161], v[196:199], v[44:47]
	v_mfma_f32_16x16x32_bf16 v[40:43], v[172:175], v[196:199], v[40:43]
	v_mfma_f32_16x16x32_bf16 v[28:31], v[158:161], v[204:207], v[28:31]
	v_mfma_f32_16x16x32_bf16 v[24:27], v[172:175], v[204:207], v[24:27]
	v_mfma_f32_16x16x32_bf16 v[12:15], v[158:161], v[212:215], v[12:15]
	v_mfma_f32_16x16x32_bf16 v[8:11], v[172:175], v[212:215], v[8:11]
	v_mfma_f32_16x16x32_bf16 v[60:63], v[162:165], v[192:195], v[60:63]
	v_mfma_f32_16x16x32_bf16 v[56:59], v[176:179], v[192:195], v[56:59]
	v_mfma_f32_16x16x32_bf16 v[44:47], v[162:165], v[200:203], v[44:47]
	v_mfma_f32_16x16x32_bf16 v[40:43], v[176:179], v[200:203], v[40:43]
	v_mfma_f32_16x16x32_bf16 v[28:31], v[162:165], v[208:211], v[28:31]
	v_mfma_f32_16x16x32_bf16 v[24:27], v[176:179], v[208:211], v[24:27]
	v_mfma_f32_16x16x32_bf16 v[12:15], v[162:165], v[216:219], v[12:15]
	v_mfma_f32_16x16x32_bf16 v[8:11], v[176:179], v[216:219], v[8:11]
	s_barrier
	s_add_u32 s14, s58, 0x40080
	s_addc_u32 s15, s59, 0
	s_add_i32 s16, s17, s88
	s_mov_b32 m0, s16
	s_nop 0
	global_load_lds_dwordx4 v128, s[14:15]
	s_add_i32 m0, s16, 0x2000
	s_nop 0
	global_load_lds_dwordx4 v152, s[14:15]
	s_waitcnt vmcnt(6)
	s_barrier
	v_mfma_f32_16x16x32_bf16 v[52:55], v[220:223], v[180:183], v[52:55]
	v_mfma_f32_16x16x32_bf16 v[48:51], v[228:231], v[180:183], v[48:51]
	v_mfma_f32_16x16x32_bf16 v[36:39], v[220:223], v[196:199], v[36:39]
	v_mfma_f32_16x16x32_bf16 v[32:35], v[228:231], v[196:199], v[32:35]
	v_mfma_f32_16x16x32_bf16 v[20:23], v[220:223], v[204:207], v[20:23]
	v_mfma_f32_16x16x32_bf16 v[16:19], v[228:231], v[204:207], v[16:19]
	v_mfma_f32_16x16x32_bf16 v[4:7], v[220:223], v[212:215], v[4:7]
	v_mfma_f32_16x16x32_bf16 v[0:3], v[228:231], v[212:215], v[0:3]
	v_mfma_f32_16x16x32_bf16 v[52:55], v[224:227], v[192:195], v[52:55]
	v_mfma_f32_16x16x32_bf16 v[48:51], v[232:235], v[192:195], v[48:51]
	v_mfma_f32_16x16x32_bf16 v[36:39], v[224:227], v[200:203], v[36:39]
	v_mfma_f32_16x16x32_bf16 v[32:35], v[232:235], v[200:203], v[32:35]
	v_mfma_f32_16x16x32_bf16 v[20:23], v[224:227], v[208:211], v[20:23]
	v_mfma_f32_16x16x32_bf16 v[16:19], v[232:235], v[208:211], v[16:19]
	v_mfma_f32_16x16x32_bf16 v[4:7], v[224:227], v[216:219], v[4:7]
	v_mfma_f32_16x16x32_bf16 v[0:3], v[232:235], v[216:219], v[0:3]
	s_add_i32 vcc_lo, vcc_lo, 2
	s_add_u32 s56, s56, 0x100
	s_addc_u32 s57, s57, 0
	s_add_u32 s76, s76, 0x100
	s_addc_u32 s77, s77, 0
	s_cmp_gt_u32 vcc_lo, 13
	s_barrier
; __device__ __forceinline__ unsigned cvt_pk_bf16(float lo, float hi) { const f32x2_cv v = {lo, hi}; const bf16x2_cv b = __builtin_convertvector(v, bf16x2_cv); return __builtin_bit_cast(unsigned, b); }
; __device__ __forceinline__ float sigm(float x) { return __builtin_amdgcn_rcpf(1.0f + __expf(-x)); }
; __device__ __forceinline__ float lo16(unsigned w) { return __uint_as_float(w << 16); }
; __device__ __forceinline__ float hi16(unsigned w) { return __uint_as_float(w & 0xffff0000u); }
; __device__ __forceinline__ float rstd_of(const float* rowss, int row) { return rsqrtf(rowss[row] * (1.0f / 1024.0f) + 1e-6f); }
;     __device__ __forceinline__ void operator()(const f32x4 (&acc)[2][2][4][2], const pg8::Unit& u, int wr, int wc, int fr, int fq) const {
;         const int row0 = u.pm * 256 + wr * 64 + fr, col0 = u.pn * 256 + wc * 32 + 8 * fq;
; #pragma unroll
;         for (int ai = 0; ai < 2; ++ai)
; #pragma unroll
;             for (int m = 0; m < 4; ++m) {
;                 const int row = row0 + ai * 128 + m * 16;
;                 const float s = rstd_of(rowss, row);
; #pragma unroll
;                 for (int bj = 0; bj < 2; ++bj) {
;                     const size_t off = (size_t)row * 1024 + col0 + bj * 128;
;                     const u32x4 tv = *(const u32x4*)(Tm + off);
;                     u32x4 pv = (u32x4){0u, 0u, 0u, 0u};
;                     if (ACC) pv = *(const u32x4*)(M + off);
;                     const f32x4 a0 = acc[ai][bj][m][0] * s, a1 = acc[ai][bj][m][1] * s;
;                     float o[8];
;                     o[0] = sigm(a0[0]) * lo16(tv.x); o[1] = sigm(a0[1]) * hi16(tv.x); o[2] = sigm(a0[2]) * lo16(tv.y); o[3] = sigm(a0[3]) * hi16(tv.y);
;                     o[4] = sigm(a1[0]) * lo16(tv.z); o[5] = sigm(a1[1]) * hi16(tv.z); o[6] = sigm(a1[2]) * lo16(tv.w); o[7] = sigm(a1[3]) * hi16(tv.w);
;                     if (ACC) { o[0] += lo16(pv.x); o[1] += hi16(pv.x); o[2] += lo16(pv.y); o[3] += hi16(pv.y); o[4] += lo16(pv.z); o[5] += hi16(pv.z); o[6] += lo16(pv.w); o[7] += hi16(pv.w); }
;                     u32x4 w; w.x = cvt_pk_bf16(o[0], o[1]); w.y = cvt_pk_bf16(o[2], o[3]); w.z = cvt_pk_bf16(o[4], o[5]); w.w = cvt_pk_bf16(o[6], o[7]);
;                     *(u32x4*)(M + off) = w; } }
	s_cbranch_scc0 .LBB0_353
	v_lshl_add_u32 v164, s2, 8, v139
	v_ashrrev_i32_e32 v165, 31, v164
	v_lshl_add_u64 v[160:161], v[164:165], 2, s[40:41]
	global_load_dword v158, v[160:161], off
	v_lshl_or_b32 v162, s3, 8, v170
	v_ashrrev_i32_e32 v163, 31, v162
	s_mov_b64 s[2:3], 0x40000
	s_mov_b64 s[58:59], s[36:37]
	s_mov_b64 s[56:57], s[4:5]
	s_waitcnt vmcnt(0)
	v_fmamk_f32 v158, v158, 0x3a800000, v187
	v_cmp_gt_f32_e32 vcc, s67, v158
	v_mul_f32_e32 v159, 0x4b800000, v158
	s_nop 0
	v_cndmask_b32_e32 v158, v158, v159, vcc
	v_rsq_f32_e32 v158, v158
	s_nop 0
	v_mul_f32_e32 v159, 0x45800000, v158
	v_cndmask_b32_e32 v166, v158, v159, vcc
	v_lshlrev_b64 v[158:159], 10, v[164:165]
	v_lshl_add_u64 v[158:159], v[158:159], 0, v[162:163]
	v_lshlrev_b64 v[158:159], 1, v[158:159]
	v_lshl_add_u64 v[168:169], s[30:31], 0, v[158:159]
	v_mov_b32_e32 v249, v158
	v_mov_b32_e32 v250, v249
	global_load_dwordx4 v[192:195], v250, s[30:31]
	global_load_dwordx4 v[196:199], v250, s[0:1]
	global_load_dwordx4 v[200:203], v250, s[30:31] offset:256
	global_load_dwordx4 v[204:207], v250, s[0:1] offset:256
	v_add_u32_e32 v250, 0x8000, v249
	global_load_dwordx4 v[208:211], v250, s[30:31]
	global_load_dwordx4 v[212:215], v250, s[0:1]
	global_load_dwordx4 v[216:219], v250, s[30:31] offset:256
	global_load_dwordx4 v[220:223], v250, s[0:1] offset:256
	v_add_u32_e32 v250, 0x10000, v249
	global_load_dwordx4 v[224:227], v250, s[30:31]
	global_load_dwordx4 v[228:231], v250, s[0:1]
	global_load_dwordx4 v[232:235], v250, s[30:31] offset:256
	global_load_dwordx4 v[236:239], v250, s[0:1] offset:256
	global_load_dword v240, v[160:161], off offset:64
	global_load_dword v241, v[160:161], off offset:128
	global_load_dword v244, v[160:161], off offset:192
	global_load_dword v245, v[160:161], off offset:512
	global_load_dword v246, v[160:161], off offset:576
	global_load_dword v247, v[160:161], off offset:640
	global_load_dword v248, v[160:161], off offset:704
	v_lshl_add_u64 v[168:169], s[0:1], 0, v[158:159]
	v_pk_mul_f32 v[126:127], v[126:127], v[166:167] op_sel_hi:[1,0]
	v_pk_mul_f32 v[120:121], v[120:121], v[166:167] op_sel_hi:[1,0]
	v_mul_f32_e32 v126, 0xbfb8aa3b, v126
	v_mul_f32_e32 v127, 0xbfb8aa3b, v127
	v_pk_mul_f32 v[124:125], v[124:125], v[166:167] op_sel_hi:[1,0]
	v_pk_mul_f32 v[122:123], v[122:123], v[166:167] op_sel_hi:[1,0]
	v_exp_f32_e32 v126, v126
	v_exp_f32_e32 v127, v127
	v_mul_f32_e32 v120, 0xbfb8aa3b, v120
	v_mul_f32_e32 v121, 0xbfb8aa3b, v121
	v_mul_f32_e32 v124, 0xbfb8aa3b, v124
	v_mul_f32_e32 v125, 0xbfb8aa3b, v125
	v_exp_f32_e32 v120, v120
	v_exp_f32_e32 v121, v121
	v_mul_f32_e32 v122, 0xbfb8aa3b, v122
	v_mul_f32_e32 v123, 0xbfb8aa3b, v123
	v_exp_f32_e32 v124, v124
	v_exp_f32_e32 v125, v125
	v_exp_f32_e32 v122, v122
	v_exp_f32_e32 v123, v123
	v_add_f32_e32 v126, 1.0, v126
	v_add_f32_e32 v127, 1.0, v127
	v_rcp_f32_e32 v126, v126
	v_rcp_f32_e32 v127, v127
	v_add_f32_e32 v120, 1.0, v120
	v_add_f32_e32 v121, 1.0, v121
	v_add_f32_e32 v124, 1.0, v124
	v_add_f32_e32 v125, 1.0, v125
	v_rcp_f32_e32 v120, v120
	v_rcp_f32_e32 v121, v121
	v_add_f32_e32 v122, 1.0, v122
	v_add_f32_e32 v123, 1.0, v123
	v_rcp_f32_e32 v124, v124
	v_rcp_f32_e32 v125, v125
	v_rcp_f32_e32 v122, v122
	v_rcp_f32_e32 v123, v123
	v_pk_mul_f32 v[116:117], v[116:117], v[166:167] op_sel_hi:[1,0]
	v_pk_mul_f32 v[114:115], v[114:115], v[166:167] op_sel_hi:[1,0]
	s_waitcnt vmcnt(0)
	v_mov_b32_e32 v172, v192
	v_mov_b32_e32 v173, v193
	v_mov_b32_e32 v174, v194
	v_mov_b32_e32 v175, v195
	v_mov_b32_e32 v176, v196
	v_mov_b32_e32 v177, v197
	v_mov_b32_e32 v178, v198
	v_mov_b32_e32 v179, v199
	v_lshlrev_b32_e32 v180, 16, v172
	v_and_b32_e32 v181, 0xffff0000, v172
	v_lshlrev_b32_e32 v182, 16, v176
	v_and_b32_e32 v183, 0xffff0000, v176
	v_lshlrev_b32_e32 v172, 16, v173
	v_and_b32_e32 v173, 0xffff0000, v173
	v_lshlrev_b32_e32 v176, 16, v177
	v_and_b32_e32 v177, 0xffff0000, v177
	v_pk_fma_f32 v[126:127], v[126:127], v[172:173], v[176:177]
	v_lshlrev_b32_e32 v172, 16, v174
	v_and_b32_e32 v173, 0xffff0000, v174
	v_lshlrev_b32_e32 v176, 16, v178
	v_and_b32_e32 v177, 0xffff0000, v178
	v_pk_fma_f32 v[172:173], v[120:121], v[172:173], v[176:177]
	v_lshlrev_b32_e32 v120, 16, v175
	v_and_b32_e32 v121, 0xffff0000, v175
	v_lshlrev_b32_e32 v174, 16, v179
	v_and_b32_e32 v175, 0xffff0000, v179
	v_pk_fma_f32 v[124:125], v[124:125], v[180:181], v[182:183]
	v_pk_fma_f32 v[174:175], v[122:123], v[120:121], v[174:175]
	v_cvt_pk_bf16_f32 v120, v124, v125
	v_cvt_pk_bf16_f32 v121, v126, v127
	v_cvt_pk_bf16_f32 v122, v172, v173
	v_cvt_pk_bf16_f32 v123, v174, v175
	v_or_b32_e32 v124, 0x100, v158
	v_mov_b32_e32 v125, v159
	global_store_dwordx4 v[168:169], v[120:123], off
	v_lshl_add_u64 v[168:169], s[0:1], 0, v[124:125]
	v_pk_mul_f32 v[172:173], v[118:119], v[166:167] op_sel_hi:[1,0]
	v_lshl_add_u64 v[120:121], s[30:31], 0, v[124:125]
	s_nop 1
	v_mov_b32_e32 v120, v200
	v_mov_b32_e32 v121, v201
	v_mov_b32_e32 v122, v202
	v_mov_b32_e32 v123, v203
	v_pk_mul_f32 v[118:119], v[112:113], v[166:167] op_sel_hi:[1,0]
	s_nop 1
	v_mov_b32_e32 v124, v204
	v_mov_b32_e32 v125, v205
	v_mov_b32_e32 v126, v206
	v_mov_b32_e32 v127, v207
	v_add_u32_e32 v250, 0x18000, v249
	global_load_dwordx4 v[192:195], v250, s[30:31]
	global_load_dwordx4 v[196:199], v250, s[0:1]
	global_load_dwordx4 v[200:203], v250, s[30:31] offset:256
	global_load_dwordx4 v[204:207], v250, s[0:1] offset:256
	v_mul_f32_e32 v112, 0xbfb8aa3b, v116
	v_mul_f32_e32 v113, 0xbfb8aa3b, v117
	v_mul_f32_e32 v116, 0xbfb8aa3b, v172
	v_mul_f32_e32 v117, 0xbfb8aa3b, v173
	v_exp_f32_e32 v116, v116
	v_exp_f32_e32 v117, v117
	v_mul_f32_e32 v118, 0xbfb8aa3b, v118
	v_mul_f32_e32 v119, 0xbfb8aa3b, v119
; __device__ __forceinline__ unsigned cvt_pk_bf16(float lo, float hi) { const f32x2_cv v = {lo, hi}; const bf16x2_cv b = __builtin_convertvector(v, bf16x2_cv); return __builtin_bit_cast(unsigned, b); }
; __device__ __forceinline__ float sigm(float x) { return __builtin_amdgcn_rcpf(1.0f + __expf(-x)); }
; __device__ __forceinline__ float lo16(unsigned w) { return __uint_as_float(w << 16); }
; __device__ __forceinline__ float hi16(unsigned w) { return __uint_as_float(w & 0xffff0000u); }
; __device__ __forceinline__ float rstd_of(const float* rowss, int row) { return rsqrtf(rowss[row] * (1.0f / 1024.0f) + 1e-6f); }
;     __device__ __forceinline__ void operator()(const f32x4 (&acc)[2][2][4][2], const pg8::Unit& u, int wr, int wc, int fr, int fq) const {
;     ...
;                 const int row = row0 + ai * 128 + m * 16;
;                 const float s = rstd_of(rowss, row);
; #pragma unroll
;                 for (int bj = 0; bj < 2; ++bj) {
;                     const size_t off = (size_t)row * 1024 + col0 + bj * 128;
;                     const u32x4 tv = *(const u32x4*)(Tm + off);
;                     u32x4 pv = (u32x4){0u, 0u, 0u, 0u};
;                     if (ACC) pv = *(const u32x4*)(M + off);
;                     const f32x4 a0 = acc[ai][bj][m][0] * s, a1 = acc[ai][bj][m][1] * s;
;                     float o[8];
;                     o[0] = sigm(a0[0]) * lo16(tv.x); o[1] = sigm(a0[1]) * hi16(tv.x); o[2] = sigm(a0[2]) * lo16(tv.y); o[3] = sigm(a0[3]) * hi16(tv.y);
;                     o[4] = sigm(a1[0]) * lo16(tv.z); o[5] = sigm(a1[1]) * hi16(tv.z); o[6] = sigm(a1[2]) * lo16(tv.w); o[7] = sigm(a1[3]) * hi16(tv.w);
;                     if (ACC) { o[0] += lo16(pv.x); o[1] += hi16(pv.x); o[2] += lo16(pv.y); o[3] += hi16(pv.y); o[4] += lo16(pv.z); o[5] += hi16(pv.z); o[6] += lo16(pv.w); o[7] += hi16(pv.w); }
;                     u32x4 w; w.x = cvt_pk_bf16(o[0], o[1]); w.y = cvt_pk_bf16(o[2], o[3]); w.z = cvt_pk_bf16(o[4], o[5]); w.w = cvt_pk_bf16(o[6], o[7]);
;                     *(u32x4*)(M + off) = w; } }
	v_exp_f32_e32 v118, v118
	v_exp_f32_e32 v119, v119
	v_mul_f32_e32 v114, 0xbfb8aa3b, v114
	v_mul_f32_e32 v115, 0xbfb8aa3b, v115
	v_exp_f32_e32 v112, v112
	v_exp_f32_e32 v113, v113
	v_exp_f32_e32 v114, v114
	v_exp_f32_e32 v115, v115
	v_add_f32_e32 v116, 1.0, v116
	v_add_f32_e32 v117, 1.0, v117
	v_rcp_f32_e32 v116, v116
	v_rcp_f32_e32 v117, v117
	v_add_f32_e32 v118, 1.0, v118
	v_add_f32_e32 v119, 1.0, v119
	v_add_f32_e32 v112, 1.0, v112
	v_add_f32_e32 v113, 1.0, v113
	v_rcp_f32_e32 v118, v118
	v_rcp_f32_e32 v119, v119
	v_add_f32_e32 v114, 1.0, v114
	v_add_f32_e32 v115, 1.0, v115
	v_rcp_f32_e32 v112, v112
	v_rcp_f32_e32 v113, v113
	v_rcp_f32_e32 v114, v114
	v_rcp_f32_e32 v115, v115
	v_lshlrev_b32_e32 v172, 16, v120
	v_and_b32_e32 v173, 0xffff0000, v120
	v_lshlrev_b32_e32 v174, 16, v124
	v_and_b32_e32 v175, 0xffff0000, v124
	v_lshlrev_b32_e32 v120, 16, v121
	v_and_b32_e32 v121, 0xffff0000, v121
	v_lshlrev_b32_e32 v124, 16, v125
	v_and_b32_e32 v125, 0xffff0000, v125
	v_pk_fma_f32 v[116:117], v[116:117], v[120:121], v[124:125]
	v_lshlrev_b32_e32 v120, 16, v122
	v_and_b32_e32 v121, 0xffff0000, v122
	v_lshlrev_b32_e32 v124, 16, v126
	v_and_b32_e32 v125, 0xffff0000, v126
	v_pk_fma_f32 v[118:119], v[118:119], v[120:121], v[124:125]
	v_lshlrev_b32_e32 v120, 16, v123
	v_and_b32_e32 v121, 0xffff0000, v123
	v_lshlrev_b32_e32 v122, 16, v127
	v_and_b32_e32 v123, 0xffff0000, v127
	v_pk_fma_f32 v[112:113], v[112:113], v[172:173], v[174:175]
	v_pk_fma_f32 v[120:121], v[114:115], v[120:121], v[122:123]
	v_cvt_pk_bf16_f32 v112, v112, v113
	v_cvt_pk_bf16_f32 v113, v116, v117
	v_cvt_pk_bf16_f32 v114, v118, v119
	v_cvt_pk_bf16_f32 v115, v120, v121
	global_store_dwordx4 v[168:169], v[112:115], off
	s_nop 1
	v_mov_b32_e32 v112, v240
	s_nop 0
	v_or_b32_e32 v114, 16, v164
	v_ashrrev_i32_e32 v115, 31, v114
	v_lshlrev_b64 v[114:115], 10, v[114:115]
	v_lshl_add_u64 v[114:115], v[114:115], 0, v[162:163]
	v_lshlrev_b64 v[114:115], 1, v[114:115]
	v_lshl_add_u64 v[116:117], s[30:31], 0, v[114:115]
	v_lshl_add_u64 v[124:125], s[0:1], 0, v[114:115]
	s_nop 1
	v_mov_b32_e32 v116, v208
	v_mov_b32_e32 v117, v209
	v_mov_b32_e32 v118, v210
	v_mov_b32_e32 v119, v211
	v_or_b32_e32 v114, 0x100, v114
	s_nop 1
	v_mov_b32_e32 v120, v212
	v_mov_b32_e32 v121, v213
	v_mov_b32_e32 v122, v214
	v_mov_b32_e32 v123, v215
	v_fmamk_f32 v112, v112, 0x3a800000, v187
	v_cmp_gt_f32_e32 vcc, s67, v112
	v_mul_f32_e32 v113, 0x4b800000, v112
	v_lshlrev_b32_e32 v126, 16, v116
	v_cndmask_b32_e32 v112, v112, v113, vcc
	v_rsq_f32_e32 v112, v112
	v_and_b32_e32 v127, 0xffff0000, v116
	v_lshlrev_b32_e32 v168, 16, v120
	v_and_b32_e32 v169, 0xffff0000, v120
	v_mul_f32_e32 v113, 0x45800000, v112
	v_cndmask_b32_e32 v112, v112, v113, vcc
	v_pk_mul_f32 v[110:111], v[110:111], v[112:113] op_sel_hi:[1,0]
	v_pk_mul_f32 v[104:105], v[104:105], v[112:113] op_sel_hi:[1,0]
	v_mul_f32_e32 v110, 0xbfb8aa3b, v110
	v_mul_f32_e32 v111, 0xbfb8aa3b, v111
	v_pk_mul_f32 v[108:109], v[108:109], v[112:113] op_sel_hi:[1,0]
	v_pk_mul_f32 v[106:107], v[106:107], v[112:113] op_sel_hi:[1,0]
	v_exp_f32_e32 v110, v110
	v_exp_f32_e32 v111, v111
	v_mul_f32_e32 v104, 0xbfb8aa3b, v104
	v_mul_f32_e32 v105, 0xbfb8aa3b, v105
	v_mul_f32_e32 v108, 0xbfb8aa3b, v108
	v_mul_f32_e32 v109, 0xbfb8aa3b, v109
	v_exp_f32_e32 v104, v104
	v_exp_f32_e32 v105, v105
	v_mul_f32_e32 v106, 0xbfb8aa3b, v106
	v_mul_f32_e32 v107, 0xbfb8aa3b, v107
	v_exp_f32_e32 v108, v108
	v_exp_f32_e32 v109, v109
	v_exp_f32_e32 v106, v106
	v_exp_f32_e32 v107, v107
	v_add_f32_e32 v110, 1.0, v110
	v_add_f32_e32 v111, 1.0, v111
	v_rcp_f32_e32 v110, v110
	v_rcp_f32_e32 v111, v111
	v_add_f32_e32 v104, 1.0, v104
	v_add_f32_e32 v105, 1.0, v105
	v_add_f32_e32 v108, 1.0, v108
	v_add_f32_e32 v109, 1.0, v109
	v_rcp_f32_e32 v104, v104
	v_rcp_f32_e32 v105, v105
	v_add_f32_e32 v106, 1.0, v106
	v_add_f32_e32 v107, 1.0, v107
	v_rcp_f32_e32 v108, v108
	v_rcp_f32_e32 v109, v109
	v_rcp_f32_e32 v106, v106
	v_rcp_f32_e32 v107, v107
	v_lshlrev_b32_e32 v116, 16, v117
	v_and_b32_e32 v117, 0xffff0000, v117
	v_lshlrev_b32_e32 v120, 16, v121
	v_and_b32_e32 v121, 0xffff0000, v121
	v_pk_fma_f32 v[110:111], v[110:111], v[116:117], v[120:121]
	v_lshlrev_b32_e32 v116, 16, v118
	v_and_b32_e32 v117, 0xffff0000, v118
	v_lshlrev_b32_e32 v120, 16, v122
	v_and_b32_e32 v121, 0xffff0000, v122
	v_pk_fma_f32 v[116:117], v[104:105], v[116:117], v[120:121]
	v_lshlrev_b32_e32 v104, 16, v119
	v_and_b32_e32 v105, 0xffff0000, v119
	v_lshlrev_b32_e32 v118, 16, v123
	v_and_b32_e32 v119, 0xffff0000, v123
	v_pk_fma_f32 v[108:109], v[108:109], v[126:127], v[168:169]
	v_pk_fma_f32 v[118:119], v[106:107], v[104:105], v[118:119]
	v_cvt_pk_bf16_f32 v104, v108, v109
	v_cvt_pk_bf16_f32 v105, v110, v111
	v_cvt_pk_bf16_f32 v106, v116, v117
	v_cvt_pk_bf16_f32 v107, v118, v119
	global_store_dwordx4 v[124:125], v[104:107], off
	v_pk_mul_f32 v[102:103], v[102:103], v[112:113] op_sel_hi:[1,0]
	v_pk_mul_f32 v[96:97], v[96:97], v[112:113] op_sel_hi:[1,0]
	v_lshl_add_u64 v[104:105], s[30:31], 0, v[114:115]
	v_lshl_add_u64 v[114:115], s[0:1], 0, v[114:115]
	s_nop 1
	v_mov_b32_e32 v104, v216
	v_mov_b32_e32 v105, v217
	v_mov_b32_e32 v106, v218
	v_mov_b32_e32 v107, v219
	v_mul_f32_e32 v102, 0xbfb8aa3b, v102
	s_nop 1
	v_mov_b32_e32 v108, v220
	v_mov_b32_e32 v109, v221
	v_mov_b32_e32 v110, v222
	v_mov_b32_e32 v111, v223
	v_add_u32_e32 v250, 0x40000, v249
	global_load_dwordx4 v[208:211], v250, s[30:31]
	global_load_dwordx4 v[212:215], v250, s[0:1]
	global_load_dwordx4 v[216:219], v250, s[30:31] offset:256
	global_load_dwordx4 v[220:223], v250, s[0:1] offset:256
	v_mul_f32_e32 v103, 0xbfb8aa3b, v103
	v_pk_mul_f32 v[100:101], v[100:101], v[112:113] op_sel_hi:[1,0]
; __device__ __forceinline__ unsigned cvt_pk_bf16(float lo, float hi) { const f32x2_cv v = {lo, hi}; const bf16x2_cv b = __builtin_convertvector(v, bf16x2_cv); return __builtin_bit_cast(unsigned, b); }
; __device__ __forceinline__ float sigm(float x) { return __builtin_amdgcn_rcpf(1.0f + __expf(-x)); }
; __device__ __forceinline__ float lo16(unsigned w) { return __uint_as_float(w << 16); }
; __device__ __forceinline__ float hi16(unsigned w) { return __uint_as_float(w & 0xffff0000u); }
; __device__ __forceinline__ float rstd_of(const float* rowss, int row) { return rsqrtf(rowss[row] * (1.0f / 1024.0f) + 1e-6f); }
;     __device__ __forceinline__ void operator()(const f32x4 (&acc)[2][2][4][2], const pg8::Unit& u, int wr, int wc, int fr, int fq) const {
;     ...
;                 const int row = row0 + ai * 128 + m * 16;
;                 const float s = rstd_of(rowss, row);
; #pragma unroll
;                 for (int bj = 0; bj < 2; ++bj) {
;                     const size_t off = (size_t)row * 1024 + col0 + bj * 128;
;                     const u32x4 tv = *(const u32x4*)(Tm + off);
;                     u32x4 pv = (u32x4){0u, 0u, 0u, 0u};
;                     if (ACC) pv = *(const u32x4*)(M + off);
;                     const f32x4 a0 = acc[ai][bj][m][0] * s, a1 = acc[ai][bj][m][1] * s;
;                     float o[8];
;                     o[0] = sigm(a0[0]) * lo16(tv.x); o[1] = sigm(a0[1]) * hi16(tv.x); o[2] = sigm(a0[2]) * lo16(tv.y); o[3] = sigm(a0[3]) * hi16(tv.y);
;                     o[4] = sigm(a1[0]) * lo16(tv.z); o[5] = sigm(a1[1]) * hi16(tv.z); o[6] = sigm(a1[2]) * lo16(tv.w); o[7] = sigm(a1[3]) * hi16(tv.w);
;                     if (ACC) { o[0] += lo16(pv.x); o[1] += hi16(pv.x); o[2] += lo16(pv.y); o[3] += hi16(pv.y); o[4] += lo16(pv.z); o[5] += hi16(pv.z); o[6] += lo16(pv.w); o[7] += hi16(pv.w); }
;                     u32x4 w; w.x = cvt_pk_bf16(o[0], o[1]); w.y = cvt_pk_bf16(o[2], o[3]); w.z = cvt_pk_bf16(o[4], o[5]); w.w = cvt_pk_bf16(o[6], o[7]);
;                     *(u32x4*)(M + off) = w; } }
	v_pk_mul_f32 v[98:99], v[98:99], v[112:113] op_sel_hi:[1,0]
	v_exp_f32_e32 v102, v102
	v_exp_f32_e32 v103, v103
	v_mul_f32_e32 v96, 0xbfb8aa3b, v96
	v_mul_f32_e32 v97, 0xbfb8aa3b, v97
	v_mul_f32_e32 v100, 0xbfb8aa3b, v100
	v_mul_f32_e32 v101, 0xbfb8aa3b, v101
	v_exp_f32_e32 v96, v96
	v_exp_f32_e32 v97, v97
	v_mul_f32_e32 v98, 0xbfb8aa3b, v98
	v_mul_f32_e32 v99, 0xbfb8aa3b, v99
	v_exp_f32_e32 v100, v100
	v_exp_f32_e32 v101, v101
	v_exp_f32_e32 v98, v98
	v_exp_f32_e32 v99, v99
	v_add_f32_e32 v102, 1.0, v102
	v_add_f32_e32 v103, 1.0, v103
	v_rcp_f32_e32 v102, v102
	v_rcp_f32_e32 v103, v103
	v_add_f32_e32 v96, 1.0, v96
	v_add_f32_e32 v97, 1.0, v97
	v_add_f32_e32 v100, 1.0, v100
	v_add_f32_e32 v101, 1.0, v101
	v_rcp_f32_e32 v96, v96
	v_rcp_f32_e32 v97, v97
	v_add_f32_e32 v98, 1.0, v98
	v_add_f32_e32 v99, 1.0, v99
	v_rcp_f32_e32 v100, v100
	v_rcp_f32_e32 v101, v101
	v_rcp_f32_e32 v98, v98
	v_rcp_f32_e32 v99, v99
	v_lshlrev_b32_e32 v112, 16, v104
	v_and_b32_e32 v113, 0xffff0000, v104
	v_lshlrev_b32_e32 v116, 16, v108
	v_and_b32_e32 v117, 0xffff0000, v108
	v_lshlrev_b32_e32 v104, 16, v105
	v_and_b32_e32 v105, 0xffff0000, v105
	v_lshlrev_b32_e32 v108, 16, v109
	v_and_b32_e32 v109, 0xffff0000, v109
	v_pk_fma_f32 v[102:103], v[102:103], v[104:105], v[108:109]
	v_lshlrev_b32_e32 v104, 16, v106
	v_and_b32_e32 v105, 0xffff0000, v106
	v_lshlrev_b32_e32 v108, 16, v110
	v_and_b32_e32 v109, 0xffff0000, v110
	v_pk_fma_f32 v[104:105], v[96:97], v[104:105], v[108:109]
	v_lshlrev_b32_e32 v96, 16, v107
	v_and_b32_e32 v97, 0xffff0000, v107
	v_lshlrev_b32_e32 v106, 16, v111
	v_and_b32_e32 v107, 0xffff0000, v111
	v_pk_fma_f32 v[100:101], v[100:101], v[112:113], v[116:117]
	v_pk_fma_f32 v[106:107], v[98:99], v[96:97], v[106:107]
	v_cvt_pk_bf16_f32 v96, v100, v101
	v_cvt_pk_bf16_f32 v97, v102, v103
	v_cvt_pk_bf16_f32 v98, v104, v105
	v_cvt_pk_bf16_f32 v99, v106, v107
	global_store_dwordx4 v[114:115], v[96:99], off
	s_nop 1
	v_mov_b32_e32 v96, v241
	s_nop 0
	v_or_b32_e32 v98, 32, v164
	v_ashrrev_i32_e32 v99, 31, v98
	v_lshlrev_b64 v[98:99], 10, v[98:99]
	v_lshl_add_u64 v[98:99], v[98:99], 0, v[162:163]
	v_lshlrev_b64 v[98:99], 1, v[98:99]
	v_lshl_add_u64 v[100:101], s[30:31], 0, v[98:99]
	v_lshl_add_u64 v[108:109], s[0:1], 0, v[98:99]
	s_nop 1
	v_mov_b32_e32 v100, v224
	v_mov_b32_e32 v101, v225
	v_mov_b32_e32 v102, v226
	v_mov_b32_e32 v103, v227
	v_or_b32_e32 v98, 0x100, v98
	s_nop 1
	v_mov_b32_e32 v104, v228
	v_mov_b32_e32 v105, v229
	v_mov_b32_e32 v106, v230
	v_mov_b32_e32 v107, v231
	v_fmamk_f32 v96, v96, 0x3a800000, v187
	v_cmp_gt_f32_e32 vcc, s67, v96
	v_mul_f32_e32 v97, 0x4b800000, v96
	v_lshlrev_b32_e32 v110, 16, v100
	v_cndmask_b32_e32 v96, v96, v97, vcc
	v_rsq_f32_e32 v96, v96
	v_and_b32_e32 v111, 0xffff0000, v100
	v_lshlrev_b32_e32 v112, 16, v104
	v_and_b32_e32 v113, 0xffff0000, v104
	v_mul_f32_e32 v97, 0x45800000, v96
	v_cndmask_b32_e32 v96, v96, v97, vcc
	v_pk_mul_f32 v[94:95], v[94:95], v[96:97] op_sel_hi:[1,0]
	v_pk_mul_f32 v[88:89], v[88:89], v[96:97] op_sel_hi:[1,0]
	v_mul_f32_e32 v94, 0xbfb8aa3b, v94
	v_mul_f32_e32 v95, 0xbfb8aa3b, v95
	v_pk_mul_f32 v[92:93], v[92:93], v[96:97] op_sel_hi:[1,0]
	v_pk_mul_f32 v[90:91], v[90:91], v[96:97] op_sel_hi:[1,0]
	v_exp_f32_e32 v94, v94
	v_exp_f32_e32 v95, v95
	v_mul_f32_e32 v88, 0xbfb8aa3b, v88
	v_mul_f32_e32 v89, 0xbfb8aa3b, v89
	v_mul_f32_e32 v92, 0xbfb8aa3b, v92
	v_mul_f32_e32 v93, 0xbfb8aa3b, v93
	v_exp_f32_e32 v88, v88
	v_exp_f32_e32 v89, v89
	v_mul_f32_e32 v90, 0xbfb8aa3b, v90
	v_mul_f32_e32 v91, 0xbfb8aa3b, v91
	v_exp_f32_e32 v92, v92
	v_exp_f32_e32 v93, v93
	v_exp_f32_e32 v90, v90
	v_exp_f32_e32 v91, v91
	v_add_f32_e32 v94, 1.0, v94
	v_add_f32_e32 v95, 1.0, v95
	v_rcp_f32_e32 v94, v94
	v_rcp_f32_e32 v95, v95
	v_add_f32_e32 v88, 1.0, v88
	v_add_f32_e32 v89, 1.0, v89
	v_add_f32_e32 v92, 1.0, v92
	v_add_f32_e32 v93, 1.0, v93
	v_rcp_f32_e32 v88, v88
	v_rcp_f32_e32 v89, v89
	v_add_f32_e32 v90, 1.0, v90
	v_add_f32_e32 v91, 1.0, v91
	v_rcp_f32_e32 v92, v92
	v_rcp_f32_e32 v93, v93
	v_rcp_f32_e32 v90, v90
	v_rcp_f32_e32 v91, v91
	v_lshlrev_b32_e32 v100, 16, v101
	v_and_b32_e32 v101, 0xffff0000, v101
	v_lshlrev_b32_e32 v104, 16, v105
	v_and_b32_e32 v105, 0xffff0000, v105
	v_pk_fma_f32 v[94:95], v[94:95], v[100:101], v[104:105]
	v_lshlrev_b32_e32 v100, 16, v102
	v_and_b32_e32 v101, 0xffff0000, v102
	v_lshlrev_b32_e32 v104, 16, v106
	v_and_b32_e32 v105, 0xffff0000, v106
	v_pk_fma_f32 v[100:101], v[88:89], v[100:101], v[104:105]
	v_lshlrev_b32_e32 v88, 16, v103
	v_and_b32_e32 v89, 0xffff0000, v103
	v_lshlrev_b32_e32 v102, 16, v107
	v_and_b32_e32 v103, 0xffff0000, v107
	v_pk_fma_f32 v[92:93], v[92:93], v[110:111], v[112:113]
	v_pk_fma_f32 v[102:103], v[90:91], v[88:89], v[102:103]
	v_cvt_pk_bf16_f32 v88, v92, v93
	v_cvt_pk_bf16_f32 v89, v94, v95
	v_cvt_pk_bf16_f32 v90, v100, v101
	v_cvt_pk_bf16_f32 v91, v102, v103
	global_store_dwordx4 v[108:109], v[88:91], off
	v_pk_mul_f32 v[86:87], v[86:87], v[96:97] op_sel_hi:[1,0]
	v_pk_mul_f32 v[80:81], v[80:81], v[96:97] op_sel_hi:[1,0]
	v_lshl_add_u64 v[88:89], s[30:31], 0, v[98:99]
	v_lshl_add_u64 v[98:99], s[0:1], 0, v[98:99]
	s_nop 1
	v_mov_b32_e32 v92, v232
	v_mov_b32_e32 v93, v233
	v_mov_b32_e32 v94, v234
	v_mov_b32_e32 v95, v235
	v_mul_f32_e32 v86, 0xbfb8aa3b, v86
	s_nop 1
	v_mov_b32_e32 v88, v236
	v_mov_b32_e32 v89, v237
	v_mov_b32_e32 v90, v238
	v_mov_b32_e32 v91, v239
	v_add_u32_e32 v250, 0x48000, v249
	global_load_dwordx4 v[224:227], v250, s[30:31]
	global_load_dwordx4 v[228:231], v250, s[0:1]
	global_load_dwordx4 v[232:235], v250, s[30:31] offset:256
	global_load_dwordx4 v[236:239], v250, s[0:1] offset:256
	v_mul_f32_e32 v87, 0xbfb8aa3b, v87
; __device__ __forceinline__ unsigned cvt_pk_bf16(float lo, float hi) { const f32x2_cv v = {lo, hi}; const bf16x2_cv b = __builtin_convertvector(v, bf16x2_cv); return __builtin_bit_cast(unsigned, b); }
; __device__ __forceinline__ float sigm(float x) { return __builtin_amdgcn_rcpf(1.0f + __expf(-x)); }
; __device__ __forceinline__ float lo16(unsigned w) { return __uint_as_float(w << 16); }
; __device__ __forceinline__ float hi16(unsigned w) { return __uint_as_float(w & 0xffff0000u); }
; __device__ __forceinline__ float rstd_of(const float* rowss, int row) { return rsqrtf(rowss[row] * (1.0f / 1024.0f) + 1e-6f); }
;     __device__ __forceinline__ void operator()(const f32x4 (&acc)[2][2][4][2], const pg8::Unit& u, int wr, int wc, int fr, int fq) const {
;     ...
;                 const int row = row0 + ai * 128 + m * 16;
;                 const float s = rstd_of(rowss, row);
; #pragma unroll
;                 for (int bj = 0; bj < 2; ++bj) {
;                     const size_t off = (size_t)row * 1024 + col0 + bj * 128;
;                     const u32x4 tv = *(const u32x4*)(Tm + off);
;                     u32x4 pv = (u32x4){0u, 0u, 0u, 0u};
;                     if (ACC) pv = *(const u32x4*)(M + off);
;                     const f32x4 a0 = acc[ai][bj][m][0] * s, a1 = acc[ai][bj][m][1] * s;
;                     float o[8];
;                     o[0] = sigm(a0[0]) * lo16(tv.x); o[1] = sigm(a0[1]) * hi16(tv.x); o[2] = sigm(a0[2]) * lo16(tv.y); o[3] = sigm(a0[3]) * hi16(tv.y);
;                     o[4] = sigm(a1[0]) * lo16(tv.z); o[5] = sigm(a1[1]) * hi16(tv.z); o[6] = sigm(a1[2]) * lo16(tv.w); o[7] = sigm(a1[3]) * hi16(tv.w);
;                     if (ACC) { o[0] += lo16(pv.x); o[1] += hi16(pv.x); o[2] += lo16(pv.y); o[3] += hi16(pv.y); o[4] += lo16(pv.z); o[5] += hi16(pv.z); o[6] += lo16(pv.w); o[7] += hi16(pv.w); }
;                     u32x4 w; w.x = cvt_pk_bf16(o[0], o[1]); w.y = cvt_pk_bf16(o[2], o[3]); w.z = cvt_pk_bf16(o[4], o[5]); w.w = cvt_pk_bf16(o[6], o[7]);
;                     *(u32x4*)(M + off) = w; } }
	v_pk_mul_f32 v[84:85], v[84:85], v[96:97] op_sel_hi:[1,0]
	v_pk_mul_f32 v[82:83], v[82:83], v[96:97] op_sel_hi:[1,0]
	v_exp_f32_e32 v86, v86
	v_exp_f32_e32 v87, v87
	v_mul_f32_e32 v80, 0xbfb8aa3b, v80
	v_mul_f32_e32 v81, 0xbfb8aa3b, v81
	v_mul_f32_e32 v84, 0xbfb8aa3b, v84
	v_mul_f32_e32 v85, 0xbfb8aa3b, v85
	v_exp_f32_e32 v80, v80
	v_exp_f32_e32 v81, v81
	v_mul_f32_e32 v82, 0xbfb8aa3b, v82
	v_mul_f32_e32 v83, 0xbfb8aa3b, v83
	v_exp_f32_e32 v84, v84
	v_exp_f32_e32 v85, v85
	v_exp_f32_e32 v82, v82
	v_exp_f32_e32 v83, v83
	v_add_f32_e32 v86, 1.0, v86
	v_add_f32_e32 v87, 1.0, v87
	v_rcp_f32_e32 v86, v86
	v_rcp_f32_e32 v87, v87
	v_add_f32_e32 v80, 1.0, v80
	v_add_f32_e32 v81, 1.0, v81
	v_add_f32_e32 v84, 1.0, v84
	v_add_f32_e32 v85, 1.0, v85
	v_rcp_f32_e32 v80, v80
	v_rcp_f32_e32 v81, v81
	v_add_f32_e32 v82, 1.0, v82
	v_add_f32_e32 v83, 1.0, v83
	v_rcp_f32_e32 v84, v84
	v_rcp_f32_e32 v85, v85
	v_rcp_f32_e32 v82, v82
	v_rcp_f32_e32 v83, v83
	v_lshlrev_b32_e32 v96, 16, v92
	v_and_b32_e32 v97, 0xffff0000, v92
	v_lshlrev_b32_e32 v100, 16, v88
	v_and_b32_e32 v101, 0xffff0000, v88
	v_lshlrev_b32_e32 v92, 16, v93
	v_and_b32_e32 v93, 0xffff0000, v93
	v_lshlrev_b32_e32 v88, 16, v89
	v_and_b32_e32 v89, 0xffff0000, v89
	v_pk_fma_f32 v[86:87], v[86:87], v[92:93], v[88:89]
	v_lshlrev_b32_e32 v88, 16, v94
	v_and_b32_e32 v89, 0xffff0000, v94
	v_lshlrev_b32_e32 v92, 16, v90
	v_and_b32_e32 v93, 0xffff0000, v90
	v_pk_fma_f32 v[88:89], v[80:81], v[88:89], v[92:93]
	v_lshlrev_b32_e32 v80, 16, v95
	v_and_b32_e32 v81, 0xffff0000, v95
	v_lshlrev_b32_e32 v90, 16, v91
	v_and_b32_e32 v91, 0xffff0000, v91
	v_pk_fma_f32 v[84:85], v[84:85], v[96:97], v[100:101]
	v_pk_fma_f32 v[90:91], v[82:83], v[80:81], v[90:91]
	v_cvt_pk_bf16_f32 v80, v84, v85
	v_cvt_pk_bf16_f32 v81, v86, v87
	v_cvt_pk_bf16_f32 v82, v88, v89
	v_cvt_pk_bf16_f32 v83, v90, v91
	global_store_dwordx4 v[98:99], v[80:83], off
	s_nop 1
	v_mov_b32_e32 v80, v244
	s_nop 0
	v_or_b32_e32 v82, 48, v164
	v_ashrrev_i32_e32 v83, 31, v82
	v_lshlrev_b64 v[82:83], 10, v[82:83]
	v_lshl_add_u64 v[82:83], v[82:83], 0, v[162:163]
	v_lshlrev_b64 v[82:83], 1, v[82:83]
	v_lshl_add_u64 v[84:85], s[30:31], 0, v[82:83]
	v_lshl_add_u64 v[92:93], s[0:1], 0, v[82:83]
	s_waitcnt vmcnt(13)
	s_nop 1
	v_mov_b32_e32 v84, v192
	v_mov_b32_e32 v85, v193
	v_mov_b32_e32 v86, v194
	v_mov_b32_e32 v87, v195
	v_or_b32_e32 v82, 0x100, v82
	s_nop 1
	v_mov_b32_e32 v88, v196
	v_mov_b32_e32 v89, v197
	v_mov_b32_e32 v90, v198
	v_mov_b32_e32 v91, v199
	v_fmamk_f32 v80, v80, 0x3a800000, v187
	v_cmp_gt_f32_e32 vcc, s67, v80
	v_mul_f32_e32 v81, 0x4b800000, v80
	v_lshlrev_b32_e32 v94, 16, v84
	v_cndmask_b32_e32 v80, v80, v81, vcc
	v_rsq_f32_e32 v80, v80
	v_and_b32_e32 v95, 0xffff0000, v84
	v_lshlrev_b32_e32 v96, 16, v88
	v_and_b32_e32 v97, 0xffff0000, v88
	v_mul_f32_e32 v81, 0x45800000, v80
	v_cndmask_b32_e32 v80, v80, v81, vcc
	v_pk_mul_f32 v[78:79], v[78:79], v[80:81] op_sel_hi:[1,0]
	v_pk_mul_f32 v[72:73], v[72:73], v[80:81] op_sel_hi:[1,0]
	v_mul_f32_e32 v78, 0xbfb8aa3b, v78
	v_mul_f32_e32 v79, 0xbfb8aa3b, v79
	v_pk_mul_f32 v[76:77], v[76:77], v[80:81] op_sel_hi:[1,0]
	v_pk_mul_f32 v[74:75], v[74:75], v[80:81] op_sel_hi:[1,0]
	v_exp_f32_e32 v78, v78
	v_exp_f32_e32 v79, v79
	v_mul_f32_e32 v72, 0xbfb8aa3b, v72
	v_mul_f32_e32 v73, 0xbfb8aa3b, v73
	v_mul_f32_e32 v76, 0xbfb8aa3b, v76
	v_mul_f32_e32 v77, 0xbfb8aa3b, v77
	v_exp_f32_e32 v72, v72
	v_exp_f32_e32 v73, v73
	v_mul_f32_e32 v74, 0xbfb8aa3b, v74
	v_mul_f32_e32 v75, 0xbfb8aa3b, v75
	v_exp_f32_e32 v76, v76
	v_exp_f32_e32 v77, v77
	v_exp_f32_e32 v74, v74
	v_exp_f32_e32 v75, v75
	v_add_f32_e32 v78, 1.0, v78
	v_add_f32_e32 v79, 1.0, v79
	v_rcp_f32_e32 v78, v78
	v_rcp_f32_e32 v79, v79
	v_add_f32_e32 v72, 1.0, v72
	v_add_f32_e32 v73, 1.0, v73
	v_add_f32_e32 v76, 1.0, v76
	v_add_f32_e32 v77, 1.0, v77
	v_rcp_f32_e32 v72, v72
	v_rcp_f32_e32 v73, v73
	v_add_f32_e32 v74, 1.0, v74
	v_add_f32_e32 v75, 1.0, v75
	v_rcp_f32_e32 v76, v76
	v_rcp_f32_e32 v77, v77
	v_rcp_f32_e32 v74, v74
	v_rcp_f32_e32 v75, v75
	v_lshlrev_b32_e32 v84, 16, v85
	v_and_b32_e32 v85, 0xffff0000, v85
	v_lshlrev_b32_e32 v88, 16, v89
	v_and_b32_e32 v89, 0xffff0000, v89
	v_pk_fma_f32 v[78:79], v[78:79], v[84:85], v[88:89]
	v_lshlrev_b32_e32 v84, 16, v86
	v_and_b32_e32 v85, 0xffff0000, v86
	v_lshlrev_b32_e32 v88, 16, v90
	v_and_b32_e32 v89, 0xffff0000, v90
	v_pk_fma_f32 v[84:85], v[72:73], v[84:85], v[88:89]
	v_lshlrev_b32_e32 v72, 16, v87
	v_and_b32_e32 v73, 0xffff0000, v87
	v_lshlrev_b32_e32 v86, 16, v91
	v_and_b32_e32 v87, 0xffff0000, v91
	v_pk_fma_f32 v[76:77], v[76:77], v[94:95], v[96:97]
	v_pk_fma_f32 v[86:87], v[74:75], v[72:73], v[86:87]
	v_cvt_pk_bf16_f32 v72, v76, v77
	v_cvt_pk_bf16_f32 v73, v78, v79
	v_cvt_pk_bf16_f32 v74, v84, v85
	v_cvt_pk_bf16_f32 v75, v86, v87
	global_store_dwordx4 v[92:93], v[72:75], off
	v_pk_mul_f32 v[70:71], v[70:71], v[80:81] op_sel_hi:[1,0]
	v_pk_mul_f32 v[64:65], v[64:65], v[80:81] op_sel_hi:[1,0]
	v_lshl_add_u64 v[72:73], s[30:31], 0, v[82:83]
	v_lshl_add_u64 v[82:83], s[0:1], 0, v[82:83]
	s_nop 1
	v_mov_b32_e32 v76, v200
	v_mov_b32_e32 v77, v201
	v_mov_b32_e32 v78, v202
	v_mov_b32_e32 v79, v203
	v_mul_f32_e32 v70, 0xbfb8aa3b, v70
	s_nop 1
	v_mov_b32_e32 v72, v204
	v_mov_b32_e32 v73, v205
	v_mov_b32_e32 v74, v206
	v_mov_b32_e32 v75, v207
	v_add_u32_e32 v250, 0x50000, v249
	global_load_dwordx4 v[192:195], v250, s[30:31]
	global_load_dwordx4 v[196:199], v250, s[0:1]
	global_load_dwordx4 v[200:203], v250, s[30:31] offset:256
	global_load_dwordx4 v[204:207], v250, s[0:1] offset:256
	v_mul_f32_e32 v71, 0xbfb8aa3b, v71
	v_pk_mul_f32 v[68:69], v[68:69], v[80:81] op_sel_hi:[1,0]
	v_pk_mul_f32 v[66:67], v[66:67], v[80:81] op_sel_hi:[1,0]
; __device__ __forceinline__ unsigned cvt_pk_bf16(float lo, float hi) { const f32x2_cv v = {lo, hi}; const bf16x2_cv b = __builtin_convertvector(v, bf16x2_cv); return __builtin_bit_cast(unsigned, b); }
; __device__ __forceinline__ float sigm(float x) { return __builtin_amdgcn_rcpf(1.0f + __expf(-x)); }
; __device__ __forceinline__ float lo16(unsigned w) { return __uint_as_float(w << 16); }
; __device__ __forceinline__ float hi16(unsigned w) { return __uint_as_float(w & 0xffff0000u); }
; __device__ __forceinline__ float rstd_of(const float* rowss, int row) { return rsqrtf(rowss[row] * (1.0f / 1024.0f) + 1e-6f); }
;     __device__ __forceinline__ void operator()(const f32x4 (&acc)[2][2][4][2], const pg8::Unit& u, int wr, int wc, int fr, int fq) const {
;     ...
;                 const int row = row0 + ai * 128 + m * 16;
;                 const float s = rstd_of(rowss, row);
; #pragma unroll
;                 for (int bj = 0; bj < 2; ++bj) {
;                     const size_t off = (size_t)row * 1024 + col0 + bj * 128;
;                     const u32x4 tv = *(const u32x4*)(Tm + off);
;                     u32x4 pv = (u32x4){0u, 0u, 0u, 0u};
;                     if (ACC) pv = *(const u32x4*)(M + off);
;                     const f32x4 a0 = acc[ai][bj][m][0] * s, a1 = acc[ai][bj][m][1] * s;
;                     float o[8];
;                     o[0] = sigm(a0[0]) * lo16(tv.x); o[1] = sigm(a0[1]) * hi16(tv.x); o[2] = sigm(a0[2]) * lo16(tv.y); o[3] = sigm(a0[3]) * hi16(tv.y);
;                     o[4] = sigm(a1[0]) * lo16(tv.z); o[5] = sigm(a1[1]) * hi16(tv.z); o[6] = sigm(a1[2]) * lo16(tv.w); o[7] = sigm(a1[3]) * hi16(tv.w);
;                     if (ACC) { o[0] += lo16(pv.x); o[1] += hi16(pv.x); o[2] += lo16(pv.y); o[3] += hi16(pv.y); o[4] += lo16(pv.z); o[5] += hi16(pv.z); o[6] += lo16(pv.w); o[7] += hi16(pv.w); }
;                     u32x4 w; w.x = cvt_pk_bf16(o[0], o[1]); w.y = cvt_pk_bf16(o[2], o[3]); w.z = cvt_pk_bf16(o[4], o[5]); w.w = cvt_pk_bf16(o[6], o[7]);
;                     *(u32x4*)(M + off) = w; } }
	v_exp_f32_e32 v70, v70
	v_exp_f32_e32 v71, v71
	v_mul_f32_e32 v64, 0xbfb8aa3b, v64
	v_mul_f32_e32 v65, 0xbfb8aa3b, v65
	v_mul_f32_e32 v68, 0xbfb8aa3b, v68
	v_mul_f32_e32 v69, 0xbfb8aa3b, v69
	v_exp_f32_e32 v64, v64
	v_exp_f32_e32 v65, v65
	v_mul_f32_e32 v66, 0xbfb8aa3b, v66
	v_mul_f32_e32 v67, 0xbfb8aa3b, v67
	v_exp_f32_e32 v68, v68
	v_exp_f32_e32 v69, v69
	v_exp_f32_e32 v66, v66
	v_exp_f32_e32 v67, v67
	v_add_f32_e32 v70, 1.0, v70
	v_add_f32_e32 v71, 1.0, v71
	v_rcp_f32_e32 v70, v70
	v_rcp_f32_e32 v71, v71
	v_add_f32_e32 v64, 1.0, v64
	v_add_f32_e32 v65, 1.0, v65
	v_add_f32_e32 v68, 1.0, v68
	v_add_f32_e32 v69, 1.0, v69
	v_rcp_f32_e32 v64, v64
	v_rcp_f32_e32 v65, v65
	v_add_f32_e32 v66, 1.0, v66
	v_add_f32_e32 v67, 1.0, v67
	v_rcp_f32_e32 v68, v68
	v_rcp_f32_e32 v69, v69
	v_rcp_f32_e32 v66, v66
	v_rcp_f32_e32 v67, v67
	v_lshlrev_b32_e32 v80, 16, v76
	v_and_b32_e32 v81, 0xffff0000, v76
	v_lshlrev_b32_e32 v84, 16, v72
	v_and_b32_e32 v85, 0xffff0000, v72
	v_lshlrev_b32_e32 v76, 16, v77
	v_and_b32_e32 v77, 0xffff0000, v77
	v_lshlrev_b32_e32 v72, 16, v73
	v_and_b32_e32 v73, 0xffff0000, v73
	v_pk_fma_f32 v[70:71], v[70:71], v[76:77], v[72:73]
	v_lshlrev_b32_e32 v72, 16, v78
	v_and_b32_e32 v73, 0xffff0000, v78
	v_lshlrev_b32_e32 v76, 16, v74
	v_and_b32_e32 v77, 0xffff0000, v74
	v_pk_fma_f32 v[72:73], v[64:65], v[72:73], v[76:77]
	v_lshlrev_b32_e32 v64, 16, v79
	v_and_b32_e32 v65, 0xffff0000, v79
	v_lshlrev_b32_e32 v74, 16, v75
	v_and_b32_e32 v75, 0xffff0000, v75
	v_pk_fma_f32 v[68:69], v[68:69], v[80:81], v[84:85]
	v_pk_fma_f32 v[74:75], v[66:67], v[64:65], v[74:75]
	v_cvt_pk_bf16_f32 v64, v68, v69
	v_cvt_pk_bf16_f32 v65, v70, v71
	v_cvt_pk_bf16_f32 v66, v72, v73
	v_cvt_pk_bf16_f32 v67, v74, v75
	global_store_dwordx4 v[82:83], v[64:67], off
	s_nop 1
	v_mov_b32_e32 v64, v245
	v_lshl_add_u64 v[70:71], v[158:159], 0, s[2:3]
	v_lshl_add_u64 v[66:67], s[30:31], 0, v[70:71]
	v_lshl_add_u64 v[74:75], s[0:1], 0, v[70:71]
	s_waitcnt vmcnt(13)
	s_nop 1
	v_mov_b32_e32 v66, v208
	v_mov_b32_e32 v67, v209
	v_mov_b32_e32 v68, v210
	v_mov_b32_e32 v69, v211
	s_mov_b64 s[2:3], 0x40100
	s_nop 1
	v_mov_b32_e32 v70, v212
	v_mov_b32_e32 v71, v213
	v_mov_b32_e32 v72, v214
	v_mov_b32_e32 v73, v215
	v_fmamk_f32 v64, v64, 0x3a800000, v187
	v_cmp_gt_f32_e32 vcc, s67, v64
	v_mul_f32_e32 v65, 0x4b800000, v64
	v_lshlrev_b32_e32 v76, 16, v66
	v_cndmask_b32_e32 v64, v64, v65, vcc
	v_rsq_f32_e32 v64, v64
	v_and_b32_e32 v77, 0xffff0000, v66
	v_lshlrev_b32_e32 v78, 16, v70
	v_and_b32_e32 v79, 0xffff0000, v70
	v_mul_f32_e32 v65, 0x45800000, v64
	v_cndmask_b32_e32 v64, v64, v65, vcc
	v_pk_mul_f32 v[62:63], v[62:63], v[64:65] op_sel_hi:[1,0]
	v_pk_mul_f32 v[56:57], v[56:57], v[64:65] op_sel_hi:[1,0]
	v_mul_f32_e32 v62, 0xbfb8aa3b, v62
	v_mul_f32_e32 v63, 0xbfb8aa3b, v63
	v_pk_mul_f32 v[60:61], v[60:61], v[64:65] op_sel_hi:[1,0]
	v_pk_mul_f32 v[58:59], v[58:59], v[64:65] op_sel_hi:[1,0]
	v_exp_f32_e32 v62, v62
	v_exp_f32_e32 v63, v63
	v_mul_f32_e32 v56, 0xbfb8aa3b, v56
	v_mul_f32_e32 v57, 0xbfb8aa3b, v57
	v_mul_f32_e32 v60, 0xbfb8aa3b, v60
	v_mul_f32_e32 v61, 0xbfb8aa3b, v61
	v_exp_f32_e32 v56, v56
	v_exp_f32_e32 v57, v57
	v_mul_f32_e32 v58, 0xbfb8aa3b, v58
	v_mul_f32_e32 v59, 0xbfb8aa3b, v59
	v_exp_f32_e32 v60, v60
	v_exp_f32_e32 v61, v61
	v_exp_f32_e32 v58, v58
	v_exp_f32_e32 v59, v59
	v_add_f32_e32 v62, 1.0, v62
	v_add_f32_e32 v63, 1.0, v63
	v_rcp_f32_e32 v62, v62
	v_rcp_f32_e32 v63, v63
	v_add_f32_e32 v56, 1.0, v56
	v_add_f32_e32 v57, 1.0, v57
	v_add_f32_e32 v60, 1.0, v60
	v_add_f32_e32 v61, 1.0, v61
	v_rcp_f32_e32 v56, v56
	v_rcp_f32_e32 v57, v57
	v_add_f32_e32 v58, 1.0, v58
	v_add_f32_e32 v59, 1.0, v59
	v_rcp_f32_e32 v60, v60
	v_rcp_f32_e32 v61, v61
	v_rcp_f32_e32 v58, v58
	v_rcp_f32_e32 v59, v59
	v_lshlrev_b32_e32 v66, 16, v67
	v_and_b32_e32 v67, 0xffff0000, v67
	v_lshlrev_b32_e32 v70, 16, v71
	v_and_b32_e32 v71, 0xffff0000, v71
	v_pk_fma_f32 v[62:63], v[62:63], v[66:67], v[70:71]
	v_lshlrev_b32_e32 v66, 16, v68
	v_and_b32_e32 v67, 0xffff0000, v68
	v_lshlrev_b32_e32 v70, 16, v72
	v_and_b32_e32 v71, 0xffff0000, v72
	v_pk_fma_f32 v[66:67], v[56:57], v[66:67], v[70:71]
	v_lshlrev_b32_e32 v56, 16, v69
	v_and_b32_e32 v57, 0xffff0000, v69
	v_lshlrev_b32_e32 v68, 16, v73
	v_and_b32_e32 v69, 0xffff0000, v73
	v_pk_fma_f32 v[60:61], v[60:61], v[76:77], v[78:79]
	v_pk_fma_f32 v[68:69], v[58:59], v[56:57], v[68:69]
	v_cvt_pk_bf16_f32 v56, v60, v61
	v_cvt_pk_bf16_f32 v57, v62, v63
	v_cvt_pk_bf16_f32 v58, v66, v67
	v_cvt_pk_bf16_f32 v59, v68, v69
	global_store_dwordx4 v[74:75], v[56:59], off
	v_pk_mul_f32 v[54:55], v[54:55], v[64:65] op_sel_hi:[1,0]
	v_pk_mul_f32 v[48:49], v[48:49], v[64:65] op_sel_hi:[1,0]
	v_lshl_add_u64 v[56:57], v[158:159], 0, s[2:3]
	v_lshl_add_u64 v[58:59], s[30:31], 0, v[56:57]
	v_lshl_add_u64 v[66:67], s[0:1], 0, v[56:57]
	s_nop 1
	v_mov_b32_e32 v60, v216
	v_mov_b32_e32 v61, v217
	v_mov_b32_e32 v62, v218
	v_mov_b32_e32 v63, v219
	v_mul_f32_e32 v54, 0xbfb8aa3b, v54
	s_nop 1
	v_mov_b32_e32 v56, v220
	v_mov_b32_e32 v57, v221
	v_mov_b32_e32 v58, v222
	v_mov_b32_e32 v59, v223
	v_add_u32_e32 v250, 0x58000, v249
	global_load_dwordx4 v[208:211], v250, s[30:31]
	global_load_dwordx4 v[212:215], v250, s[0:1]
	global_load_dwordx4 v[216:219], v250, s[30:31] offset:256
	global_load_dwordx4 v[220:223], v250, s[0:1] offset:256
	v_mul_f32_e32 v55, 0xbfb8aa3b, v55
	v_pk_mul_f32 v[52:53], v[52:53], v[64:65] op_sel_hi:[1,0]
	v_pk_mul_f32 v[50:51], v[50:51], v[64:65] op_sel_hi:[1,0]
	v_exp_f32_e32 v54, v54
	v_exp_f32_e32 v55, v55
	v_mul_f32_e32 v48, 0xbfb8aa3b, v48
	v_mul_f32_e32 v49, 0xbfb8aa3b, v49
	v_mul_f32_e32 v52, 0xbfb8aa3b, v52
	v_mul_f32_e32 v53, 0xbfb8aa3b, v53
; __device__ __forceinline__ unsigned cvt_pk_bf16(float lo, float hi) { const f32x2_cv v = {lo, hi}; const bf16x2_cv b = __builtin_convertvector(v, bf16x2_cv); return __builtin_bit_cast(unsigned, b); }
; __device__ __forceinline__ float sigm(float x) { return __builtin_amdgcn_rcpf(1.0f + __expf(-x)); }
; __device__ __forceinline__ float lo16(unsigned w) { return __uint_as_float(w << 16); }
; __device__ __forceinline__ float hi16(unsigned w) { return __uint_as_float(w & 0xffff0000u); }
; __device__ __forceinline__ float rstd_of(const float* rowss, int row) { return rsqrtf(rowss[row] * (1.0f / 1024.0f) + 1e-6f); }
;     __device__ __forceinline__ void operator()(const f32x4 (&acc)[2][2][4][2], const pg8::Unit& u, int wr, int wc, int fr, int fq) const {
;     ...
;                 const int row = row0 + ai * 128 + m * 16;
;                 const float s = rstd_of(rowss, row);
; #pragma unroll
;                 for (int bj = 0; bj < 2; ++bj) {
;                     const size_t off = (size_t)row * 1024 + col0 + bj * 128;
;                     const u32x4 tv = *(const u32x4*)(Tm + off);
;                     u32x4 pv = (u32x4){0u, 0u, 0u, 0u};
;                     if (ACC) pv = *(const u32x4*)(M + off);
;                     const f32x4 a0 = acc[ai][bj][m][0] * s, a1 = acc[ai][bj][m][1] * s;
;                     float o[8];
;                     o[0] = sigm(a0[0]) * lo16(tv.x); o[1] = sigm(a0[1]) * hi16(tv.x); o[2] = sigm(a0[2]) * lo16(tv.y); o[3] = sigm(a0[3]) * hi16(tv.y);
;                     o[4] = sigm(a1[0]) * lo16(tv.z); o[5] = sigm(a1[1]) * hi16(tv.z); o[6] = sigm(a1[2]) * lo16(tv.w); o[7] = sigm(a1[3]) * hi16(tv.w);
;                     if (ACC) { o[0] += lo16(pv.x); o[1] += hi16(pv.x); o[2] += lo16(pv.y); o[3] += hi16(pv.y); o[4] += lo16(pv.z); o[5] += hi16(pv.z); o[6] += lo16(pv.w); o[7] += hi16(pv.w); }
;                     u32x4 w; w.x = cvt_pk_bf16(o[0], o[1]); w.y = cvt_pk_bf16(o[2], o[3]); w.z = cvt_pk_bf16(o[4], o[5]); w.w = cvt_pk_bf16(o[6], o[7]);
;                     *(u32x4*)(M + off) = w; } }
	v_exp_f32_e32 v48, v48
	v_exp_f32_e32 v49, v49
	v_mul_f32_e32 v50, 0xbfb8aa3b, v50
	v_mul_f32_e32 v51, 0xbfb8aa3b, v51
	v_exp_f32_e32 v52, v52
	v_exp_f32_e32 v53, v53
	v_exp_f32_e32 v50, v50
	v_exp_f32_e32 v51, v51
	v_add_f32_e32 v54, 1.0, v54
	v_add_f32_e32 v55, 1.0, v55
	v_rcp_f32_e32 v54, v54
	v_rcp_f32_e32 v55, v55
	v_add_f32_e32 v48, 1.0, v48
	v_add_f32_e32 v49, 1.0, v49
	v_add_f32_e32 v52, 1.0, v52
	v_add_f32_e32 v53, 1.0, v53
	v_rcp_f32_e32 v48, v48
	v_rcp_f32_e32 v49, v49
	v_add_f32_e32 v50, 1.0, v50
	v_add_f32_e32 v51, 1.0, v51
	v_rcp_f32_e32 v52, v52
	v_rcp_f32_e32 v53, v53
	v_rcp_f32_e32 v50, v50
	v_rcp_f32_e32 v51, v51
	s_mov_b64 s[2:3], 0x48000
	v_lshlrev_b32_e32 v64, 16, v60
	v_and_b32_e32 v65, 0xffff0000, v60
	v_lshlrev_b32_e32 v68, 16, v56
	v_and_b32_e32 v69, 0xffff0000, v56
	v_lshlrev_b32_e32 v60, 16, v61
	v_and_b32_e32 v61, 0xffff0000, v61
	v_lshlrev_b32_e32 v56, 16, v57
	v_and_b32_e32 v57, 0xffff0000, v57
	v_pk_fma_f32 v[54:55], v[54:55], v[60:61], v[56:57]
	v_lshlrev_b32_e32 v56, 16, v62
	v_and_b32_e32 v57, 0xffff0000, v62
	v_lshlrev_b32_e32 v60, 16, v58
	v_and_b32_e32 v61, 0xffff0000, v58
	v_pk_fma_f32 v[56:57], v[48:49], v[56:57], v[60:61]
	v_lshlrev_b32_e32 v48, 16, v63
	v_and_b32_e32 v49, 0xffff0000, v63
	v_lshlrev_b32_e32 v58, 16, v59
	v_and_b32_e32 v59, 0xffff0000, v59
	v_pk_fma_f32 v[52:53], v[52:53], v[64:65], v[68:69]
	v_pk_fma_f32 v[58:59], v[50:51], v[48:49], v[58:59]
	v_cvt_pk_bf16_f32 v48, v52, v53
	v_cvt_pk_bf16_f32 v49, v54, v55
	v_cvt_pk_bf16_f32 v50, v56, v57
	v_cvt_pk_bf16_f32 v51, v58, v59
	global_store_dwordx4 v[66:67], v[48:51], off
	s_nop 1
	v_mov_b32_e32 v48, v246
	v_lshl_add_u64 v[54:55], v[158:159], 0, s[2:3]
	v_lshl_add_u64 v[50:51], s[30:31], 0, v[54:55]
	v_lshl_add_u64 v[58:59], s[0:1], 0, v[54:55]
	s_waitcnt vmcnt(13)
	s_nop 1
	v_mov_b32_e32 v50, v224
	v_mov_b32_e32 v51, v225
	v_mov_b32_e32 v52, v226
	v_mov_b32_e32 v53, v227
	s_mov_b64 s[2:3], 0x48100
	s_nop 1
	v_mov_b32_e32 v54, v228
	v_mov_b32_e32 v55, v229
	v_mov_b32_e32 v56, v230
	v_mov_b32_e32 v57, v231
	v_fmamk_f32 v48, v48, 0x3a800000, v187
	v_cmp_gt_f32_e32 vcc, s67, v48
	v_mul_f32_e32 v49, 0x4b800000, v48
	v_lshlrev_b32_e32 v60, 16, v50
	v_cndmask_b32_e32 v48, v48, v49, vcc
	v_rsq_f32_e32 v48, v48
	v_and_b32_e32 v61, 0xffff0000, v50
	v_lshlrev_b32_e32 v62, 16, v54
	v_and_b32_e32 v63, 0xffff0000, v54
	v_mul_f32_e32 v49, 0x45800000, v48
	v_cndmask_b32_e32 v48, v48, v49, vcc
	v_pk_mul_f32 v[46:47], v[46:47], v[48:49] op_sel_hi:[1,0]
	v_pk_mul_f32 v[40:41], v[40:41], v[48:49] op_sel_hi:[1,0]
	v_mul_f32_e32 v46, 0xbfb8aa3b, v46
	v_mul_f32_e32 v47, 0xbfb8aa3b, v47
	v_pk_mul_f32 v[44:45], v[44:45], v[48:49] op_sel_hi:[1,0]
	v_pk_mul_f32 v[42:43], v[42:43], v[48:49] op_sel_hi:[1,0]
	v_exp_f32_e32 v46, v46
	v_exp_f32_e32 v47, v47
	v_mul_f32_e32 v40, 0xbfb8aa3b, v40
	v_mul_f32_e32 v41, 0xbfb8aa3b, v41
	v_mul_f32_e32 v44, 0xbfb8aa3b, v44
	v_mul_f32_e32 v45, 0xbfb8aa3b, v45
	v_exp_f32_e32 v40, v40
	v_exp_f32_e32 v41, v41
	v_mul_f32_e32 v42, 0xbfb8aa3b, v42
	v_mul_f32_e32 v43, 0xbfb8aa3b, v43
	v_exp_f32_e32 v44, v44
	v_exp_f32_e32 v45, v45
	v_exp_f32_e32 v42, v42
	v_exp_f32_e32 v43, v43
	v_add_f32_e32 v46, 1.0, v46
	v_add_f32_e32 v47, 1.0, v47
	v_rcp_f32_e32 v46, v46
	v_rcp_f32_e32 v47, v47
	v_add_f32_e32 v40, 1.0, v40
	v_add_f32_e32 v41, 1.0, v41
	v_add_f32_e32 v44, 1.0, v44
	v_add_f32_e32 v45, 1.0, v45
	v_rcp_f32_e32 v40, v40
	v_rcp_f32_e32 v41, v41
	v_add_f32_e32 v42, 1.0, v42
	v_add_f32_e32 v43, 1.0, v43
	v_rcp_f32_e32 v44, v44
	v_rcp_f32_e32 v45, v45
	v_rcp_f32_e32 v42, v42
	v_rcp_f32_e32 v43, v43
	v_lshlrev_b32_e32 v50, 16, v51
	v_and_b32_e32 v51, 0xffff0000, v51
	v_lshlrev_b32_e32 v54, 16, v55
	v_and_b32_e32 v55, 0xffff0000, v55
	v_pk_fma_f32 v[46:47], v[46:47], v[50:51], v[54:55]
	v_lshlrev_b32_e32 v50, 16, v52
	v_and_b32_e32 v51, 0xffff0000, v52
	v_lshlrev_b32_e32 v54, 16, v56
	v_and_b32_e32 v55, 0xffff0000, v56
	v_pk_fma_f32 v[50:51], v[40:41], v[50:51], v[54:55]
	v_lshlrev_b32_e32 v40, 16, v53
	v_and_b32_e32 v41, 0xffff0000, v53
	v_lshlrev_b32_e32 v52, 16, v57
	v_and_b32_e32 v53, 0xffff0000, v57
	v_pk_fma_f32 v[44:45], v[44:45], v[60:61], v[62:63]
	v_pk_fma_f32 v[52:53], v[42:43], v[40:41], v[52:53]
	v_cvt_pk_bf16_f32 v40, v44, v45
	v_cvt_pk_bf16_f32 v41, v46, v47
	v_cvt_pk_bf16_f32 v42, v50, v51
	v_cvt_pk_bf16_f32 v43, v52, v53
	global_store_dwordx4 v[58:59], v[40:43], off
	v_pk_mul_f32 v[38:39], v[38:39], v[48:49] op_sel_hi:[1,0]
	v_pk_mul_f32 v[32:33], v[32:33], v[48:49] op_sel_hi:[1,0]
	v_lshl_add_u64 v[40:41], v[158:159], 0, s[2:3]
	v_lshl_add_u64 v[42:43], s[30:31], 0, v[40:41]
	v_lshl_add_u64 v[50:51], s[0:1], 0, v[40:41]
	s_nop 1
	v_mov_b32_e32 v44, v232
	v_mov_b32_e32 v45, v233
	v_mov_b32_e32 v46, v234
	v_mov_b32_e32 v47, v235
	v_mul_f32_e32 v38, 0xbfb8aa3b, v38
	s_nop 1
	v_mov_b32_e32 v40, v236
	v_mov_b32_e32 v41, v237
	v_mov_b32_e32 v42, v238
	v_mov_b32_e32 v43, v239
	v_mul_f32_e32 v39, 0xbfb8aa3b, v39
	v_pk_mul_f32 v[36:37], v[36:37], v[48:49] op_sel_hi:[1,0]
	v_pk_mul_f32 v[34:35], v[34:35], v[48:49] op_sel_hi:[1,0]
	v_exp_f32_e32 v38, v38
	v_exp_f32_e32 v39, v39
	v_mul_f32_e32 v32, 0xbfb8aa3b, v32
	v_mul_f32_e32 v33, 0xbfb8aa3b, v33
	v_mul_f32_e32 v36, 0xbfb8aa3b, v36
	v_mul_f32_e32 v37, 0xbfb8aa3b, v37
	v_exp_f32_e32 v32, v32
	v_exp_f32_e32 v33, v33
	v_mul_f32_e32 v34, 0xbfb8aa3b, v34
	v_mul_f32_e32 v35, 0xbfb8aa3b, v35
	v_exp_f32_e32 v36, v36
	v_exp_f32_e32 v37, v37
	v_exp_f32_e32 v34, v34
	v_exp_f32_e32 v35, v35
	v_add_f32_e32 v38, 1.0, v38
	v_add_f32_e32 v39, 1.0, v39
	v_rcp_f32_e32 v38, v38
	v_rcp_f32_e32 v39, v39
	v_add_f32_e32 v32, 1.0, v32
	v_add_f32_e32 v33, 1.0, v33
	v_add_f32_e32 v36, 1.0, v36
	v_add_f32_e32 v37, 1.0, v37
	v_rcp_f32_e32 v32, v32
	v_rcp_f32_e32 v33, v33
	v_add_f32_e32 v34, 1.0, v34
	v_add_f32_e32 v35, 1.0, v35
	v_rcp_f32_e32 v36, v36
	v_rcp_f32_e32 v37, v37
	v_rcp_f32_e32 v34, v34
	v_rcp_f32_e32 v35, v35
	s_mov_b64 s[2:3], 0x50000
	v_lshlrev_b32_e32 v48, 16, v44
	v_and_b32_e32 v49, 0xffff0000, v44
	v_lshlrev_b32_e32 v52, 16, v40
	v_and_b32_e32 v53, 0xffff0000, v40
	v_lshlrev_b32_e32 v44, 16, v45
	v_and_b32_e32 v45, 0xffff0000, v45
	v_lshlrev_b32_e32 v40, 16, v41
	v_and_b32_e32 v41, 0xffff0000, v41
	v_pk_fma_f32 v[38:39], v[38:39], v[44:45], v[40:41]
	v_lshlrev_b32_e32 v40, 16, v46
	v_and_b32_e32 v41, 0xffff0000, v46
	v_lshlrev_b32_e32 v44, 16, v42
	v_and_b32_e32 v45, 0xffff0000, v42
	v_pk_fma_f32 v[40:41], v[32:33], v[40:41], v[44:45]
	v_lshlrev_b32_e32 v32, 16, v47
	v_and_b32_e32 v33, 0xffff0000, v47
	v_lshlrev_b32_e32 v42, 16, v43
	v_and_b32_e32 v43, 0xffff0000, v43
	v_pk_fma_f32 v[36:37], v[36:37], v[48:49], v[52:53]
	v_pk_fma_f32 v[42:43], v[34:35], v[32:33], v[42:43]
	v_cvt_pk_bf16_f32 v32, v36, v37
	v_cvt_pk_bf16_f32 v33, v38, v39
	v_cvt_pk_bf16_f32 v34, v40, v41
	v_cvt_pk_bf16_f32 v35, v42, v43
	global_store_dwordx4 v[50:51], v[32:35], off
	s_nop 1
	v_mov_b32_e32 v32, v247
	v_lshl_add_u64 v[38:39], v[158:159], 0, s[2:3]
	v_lshl_add_u64 v[34:35], s[30:31], 0, v[38:39]
	v_lshl_add_u64 v[42:43], s[0:1], 0, v[38:39]
	s_waitcnt vmcnt(9)
; __device__ __forceinline__ unsigned cvt_pk_bf16(float lo, float hi) { const f32x2_cv v = {lo, hi}; const bf16x2_cv b = __builtin_convertvector(v, bf16x2_cv); return __builtin_bit_cast(unsigned, b); }
; __device__ __forceinline__ float sigm(float x) { return __builtin_amdgcn_rcpf(1.0f + __expf(-x)); }
; __device__ __forceinline__ float lo16(unsigned w) { return __uint_as_float(w << 16); }
; __device__ __forceinline__ float hi16(unsigned w) { return __uint_as_float(w & 0xffff0000u); }
; __device__ __forceinline__ float rstd_of(const float* rowss, int row) { return rsqrtf(rowss[row] * (1.0f / 1024.0f) + 1e-6f); }
;     __device__ __forceinline__ void operator()(const f32x4 (&acc)[2][2][4][2], const pg8::Unit& u, int wr, int wc, int fr, int fq) const {
;     ...
;                 const int row = row0 + ai * 128 + m * 16;
;                 const float s = rstd_of(rowss, row);
; #pragma unroll
;                 for (int bj = 0; bj < 2; ++bj) {
;                     const size_t off = (size_t)row * 1024 + col0 + bj * 128;
;                     const u32x4 tv = *(const u32x4*)(Tm + off);
;                     u32x4 pv = (u32x4){0u, 0u, 0u, 0u};
;                     if (ACC) pv = *(const u32x4*)(M + off);
;                     const f32x4 a0 = acc[ai][bj][m][0] * s, a1 = acc[ai][bj][m][1] * s;
;                     float o[8];
;                     o[0] = sigm(a0[0]) * lo16(tv.x); o[1] = sigm(a0[1]) * hi16(tv.x); o[2] = sigm(a0[2]) * lo16(tv.y); o[3] = sigm(a0[3]) * hi16(tv.y);
;                     o[4] = sigm(a1[0]) * lo16(tv.z); o[5] = sigm(a1[1]) * hi16(tv.z); o[6] = sigm(a1[2]) * lo16(tv.w); o[7] = sigm(a1[3]) * hi16(tv.w);
;                     if (ACC) { o[0] += lo16(pv.x); o[1] += hi16(pv.x); o[2] += lo16(pv.y); o[3] += hi16(pv.y); o[4] += lo16(pv.z); o[5] += hi16(pv.z); o[6] += lo16(pv.w); o[7] += hi16(pv.w); }
;                     u32x4 w; w.x = cvt_pk_bf16(o[0], o[1]); w.y = cvt_pk_bf16(o[2], o[3]); w.z = cvt_pk_bf16(o[4], o[5]); w.w = cvt_pk_bf16(o[6], o[7]);
;                     *(u32x4*)(M + off) = w; } }
	s_nop 1
	v_mov_b32_e32 v34, v192
	v_mov_b32_e32 v35, v193
	v_mov_b32_e32 v36, v194
	v_mov_b32_e32 v37, v195
	s_mov_b64 s[2:3], 0x50100
	s_nop 1
	v_mov_b32_e32 v38, v196
	v_mov_b32_e32 v39, v197
	v_mov_b32_e32 v40, v198
	v_mov_b32_e32 v41, v199
	v_fmamk_f32 v32, v32, 0x3a800000, v187
	v_cmp_gt_f32_e32 vcc, s67, v32
	v_mul_f32_e32 v33, 0x4b800000, v32
	v_lshlrev_b32_e32 v44, 16, v34
	v_cndmask_b32_e32 v32, v32, v33, vcc
	v_rsq_f32_e32 v32, v32
	v_and_b32_e32 v45, 0xffff0000, v34
	v_lshlrev_b32_e32 v46, 16, v38
	v_and_b32_e32 v47, 0xffff0000, v38
	v_mul_f32_e32 v33, 0x45800000, v32
	v_cndmask_b32_e32 v32, v32, v33, vcc
	v_pk_mul_f32 v[30:31], v[30:31], v[32:33] op_sel_hi:[1,0]
	v_pk_mul_f32 v[24:25], v[24:25], v[32:33] op_sel_hi:[1,0]
	v_mul_f32_e32 v30, 0xbfb8aa3b, v30
	v_mul_f32_e32 v31, 0xbfb8aa3b, v31
	v_pk_mul_f32 v[28:29], v[28:29], v[32:33] op_sel_hi:[1,0]
	v_pk_mul_f32 v[26:27], v[26:27], v[32:33] op_sel_hi:[1,0]
	v_exp_f32_e32 v30, v30
	v_exp_f32_e32 v31, v31
	v_mul_f32_e32 v24, 0xbfb8aa3b, v24
	v_mul_f32_e32 v25, 0xbfb8aa3b, v25
	v_mul_f32_e32 v28, 0xbfb8aa3b, v28
	v_mul_f32_e32 v29, 0xbfb8aa3b, v29
	v_exp_f32_e32 v24, v24
	v_exp_f32_e32 v25, v25
	v_mul_f32_e32 v26, 0xbfb8aa3b, v26
	v_mul_f32_e32 v27, 0xbfb8aa3b, v27
	v_exp_f32_e32 v28, v28
	v_exp_f32_e32 v29, v29
	v_exp_f32_e32 v26, v26
	v_exp_f32_e32 v27, v27
	v_add_f32_e32 v30, 1.0, v30
	v_add_f32_e32 v31, 1.0, v31
	v_rcp_f32_e32 v30, v30
	v_rcp_f32_e32 v31, v31
	v_add_f32_e32 v24, 1.0, v24
	v_add_f32_e32 v25, 1.0, v25
	v_add_f32_e32 v28, 1.0, v28
	v_add_f32_e32 v29, 1.0, v29
	v_rcp_f32_e32 v24, v24
	v_rcp_f32_e32 v25, v25
	v_add_f32_e32 v26, 1.0, v26
	v_add_f32_e32 v27, 1.0, v27
	v_rcp_f32_e32 v28, v28
	v_rcp_f32_e32 v29, v29
	v_rcp_f32_e32 v26, v26
	v_rcp_f32_e32 v27, v27
	v_lshlrev_b32_e32 v34, 16, v35
	v_and_b32_e32 v35, 0xffff0000, v35
	v_lshlrev_b32_e32 v38, 16, v39
	v_and_b32_e32 v39, 0xffff0000, v39
	v_pk_fma_f32 v[30:31], v[30:31], v[34:35], v[38:39]
	v_lshlrev_b32_e32 v34, 16, v36
	v_and_b32_e32 v35, 0xffff0000, v36
	v_lshlrev_b32_e32 v38, 16, v40
	v_and_b32_e32 v39, 0xffff0000, v40
	v_pk_fma_f32 v[34:35], v[24:25], v[34:35], v[38:39]
	v_lshlrev_b32_e32 v24, 16, v37
	v_and_b32_e32 v25, 0xffff0000, v37
	v_lshlrev_b32_e32 v36, 16, v41
	v_and_b32_e32 v37, 0xffff0000, v41
	v_pk_fma_f32 v[28:29], v[28:29], v[44:45], v[46:47]
	v_pk_fma_f32 v[36:37], v[26:27], v[24:25], v[36:37]
	v_cvt_pk_bf16_f32 v24, v28, v29
	v_cvt_pk_bf16_f32 v25, v30, v31
	v_cvt_pk_bf16_f32 v26, v34, v35
	v_cvt_pk_bf16_f32 v27, v36, v37
	global_store_dwordx4 v[42:43], v[24:27], off
	v_pk_mul_f32 v[22:23], v[22:23], v[32:33] op_sel_hi:[1,0]
	v_pk_mul_f32 v[16:17], v[16:17], v[32:33] op_sel_hi:[1,0]
	v_lshl_add_u64 v[24:25], v[158:159], 0, s[2:3]
	v_lshl_add_u64 v[26:27], s[30:31], 0, v[24:25]
	v_lshl_add_u64 v[34:35], s[0:1], 0, v[24:25]
	s_nop 1
	v_mov_b32_e32 v28, v200
	v_mov_b32_e32 v29, v201
	v_mov_b32_e32 v30, v202
	v_mov_b32_e32 v31, v203
	v_mul_f32_e32 v22, 0xbfb8aa3b, v22
	s_nop 1
	v_mov_b32_e32 v24, v204
	v_mov_b32_e32 v25, v205
	v_mov_b32_e32 v26, v206
	v_mov_b32_e32 v27, v207
	v_mul_f32_e32 v23, 0xbfb8aa3b, v23
	v_pk_mul_f32 v[20:21], v[20:21], v[32:33] op_sel_hi:[1,0]
	v_pk_mul_f32 v[18:19], v[18:19], v[32:33] op_sel_hi:[1,0]
	v_exp_f32_e32 v22, v22
	v_exp_f32_e32 v23, v23
	v_mul_f32_e32 v16, 0xbfb8aa3b, v16
	v_mul_f32_e32 v17, 0xbfb8aa3b, v17
	v_mul_f32_e32 v20, 0xbfb8aa3b, v20
	v_mul_f32_e32 v21, 0xbfb8aa3b, v21
	v_exp_f32_e32 v16, v16
	v_exp_f32_e32 v17, v17
	v_mul_f32_e32 v18, 0xbfb8aa3b, v18
	v_mul_f32_e32 v19, 0xbfb8aa3b, v19
	v_exp_f32_e32 v20, v20
	v_exp_f32_e32 v21, v21
	v_exp_f32_e32 v18, v18
	v_exp_f32_e32 v19, v19
	v_add_f32_e32 v22, 1.0, v22
	v_add_f32_e32 v23, 1.0, v23
	v_rcp_f32_e32 v22, v22
	v_rcp_f32_e32 v23, v23
	v_add_f32_e32 v16, 1.0, v16
	v_add_f32_e32 v17, 1.0, v17
	v_add_f32_e32 v20, 1.0, v20
	v_add_f32_e32 v21, 1.0, v21
	v_rcp_f32_e32 v16, v16
	v_rcp_f32_e32 v17, v17
	v_add_f32_e32 v18, 1.0, v18
	v_add_f32_e32 v19, 1.0, v19
	v_rcp_f32_e32 v20, v20
	v_rcp_f32_e32 v21, v21
	v_rcp_f32_e32 v18, v18
	v_rcp_f32_e32 v19, v19
	s_mov_b64 s[2:3], 0x58000
	v_lshlrev_b32_e32 v32, 16, v28
	v_and_b32_e32 v33, 0xffff0000, v28
	v_lshlrev_b32_e32 v36, 16, v24
	v_and_b32_e32 v37, 0xffff0000, v24
	v_lshlrev_b32_e32 v28, 16, v29
	v_and_b32_e32 v29, 0xffff0000, v29
	v_lshlrev_b32_e32 v24, 16, v25
	v_and_b32_e32 v25, 0xffff0000, v25
	v_pk_fma_f32 v[22:23], v[22:23], v[28:29], v[24:25]
	v_lshlrev_b32_e32 v24, 16, v30
	v_and_b32_e32 v25, 0xffff0000, v30
	v_lshlrev_b32_e32 v28, 16, v26
	v_and_b32_e32 v29, 0xffff0000, v26
	v_pk_fma_f32 v[24:25], v[16:17], v[24:25], v[28:29]
	v_lshlrev_b32_e32 v16, 16, v31
	v_and_b32_e32 v17, 0xffff0000, v31
	v_lshlrev_b32_e32 v26, 16, v27
	v_and_b32_e32 v27, 0xffff0000, v27
	v_pk_fma_f32 v[20:21], v[20:21], v[32:33], v[36:37]
	v_pk_fma_f32 v[26:27], v[18:19], v[16:17], v[26:27]
	v_cvt_pk_bf16_f32 v16, v20, v21
	v_cvt_pk_bf16_f32 v17, v22, v23
	v_cvt_pk_bf16_f32 v18, v24, v25
	v_cvt_pk_bf16_f32 v19, v26, v27
	global_store_dwordx4 v[34:35], v[16:19], off
	s_nop 1
	v_mov_b32_e32 v16, v248
	v_lshl_add_u64 v[22:23], v[158:159], 0, s[2:3]
	v_lshl_add_u64 v[18:19], s[30:31], 0, v[22:23]
	v_lshl_add_u64 v[26:27], s[0:1], 0, v[22:23]
	s_waitcnt vmcnt(5)
; __device__ __forceinline__ unsigned cvt_pk_bf16(float lo, float hi) { const f32x2_cv v = {lo, hi}; const bf16x2_cv b = __builtin_convertvector(v, bf16x2_cv); return __builtin_bit_cast(unsigned, b); }
; __device__ __forceinline__ float sigm(float x) { return __builtin_amdgcn_rcpf(1.0f + __expf(-x)); }
; __device__ __forceinline__ float lo16(unsigned w) { return __uint_as_float(w << 16); }
; __device__ __forceinline__ float hi16(unsigned w) { return __uint_as_float(w & 0xffff0000u); }
; __device__ __forceinline__ float rstd_of(const float* rowss, int row) { return rsqrtf(rowss[row] * (1.0f / 1024.0f) + 1e-6f); }
;     __device__ __forceinline__ void operator()(const f32x4 (&acc)[2][2][4][2], const pg8::Unit& u, int wr, int wc, int fr, int fq) const {
;     ...
;                 const int row = row0 + ai * 128 + m * 16;
;                 const float s = rstd_of(rowss, row);
; #pragma unroll
;                 for (int bj = 0; bj < 2; ++bj) {
;                     const size_t off = (size_t)row * 1024 + col0 + bj * 128;
;                     const u32x4 tv = *(const u32x4*)(Tm + off);
;                     u32x4 pv = (u32x4){0u, 0u, 0u, 0u};
;                     if (ACC) pv = *(const u32x4*)(M + off);
;                     const f32x4 a0 = acc[ai][bj][m][0] * s, a1 = acc[ai][bj][m][1] * s;
;                     float o[8];
;                     o[0] = sigm(a0[0]) * lo16(tv.x); o[1] = sigm(a0[1]) * hi16(tv.x); o[2] = sigm(a0[2]) * lo16(tv.y); o[3] = sigm(a0[3]) * hi16(tv.y);
;                     o[4] = sigm(a1[0]) * lo16(tv.z); o[5] = sigm(a1[1]) * hi16(tv.z); o[6] = sigm(a1[2]) * lo16(tv.w); o[7] = sigm(a1[3]) * hi16(tv.w);
;                     if (ACC) { o[0] += lo16(pv.x); o[1] += hi16(pv.x); o[2] += lo16(pv.y); o[3] += hi16(pv.y); o[4] += lo16(pv.z); o[5] += hi16(pv.z); o[6] += lo16(pv.w); o[7] += hi16(pv.w); }
;                     u32x4 w; w.x = cvt_pk_bf16(o[0], o[1]); w.y = cvt_pk_bf16(o[2], o[3]); w.z = cvt_pk_bf16(o[4], o[5]); w.w = cvt_pk_bf16(o[6], o[7]);
;                     *(u32x4*)(M + off) = w; } }
	s_nop 1
	v_mov_b32_e32 v18, v208
	v_mov_b32_e32 v19, v209
	v_mov_b32_e32 v20, v210
	v_mov_b32_e32 v21, v211
	s_mov_b64 s[2:3], 0x58100
	s_nop 1
	v_mov_b32_e32 v22, v212
	v_mov_b32_e32 v23, v213
	v_mov_b32_e32 v24, v214
	v_mov_b32_e32 v25, v215
	v_fmamk_f32 v16, v16, 0x3a800000, v187
	v_cmp_gt_f32_e32 vcc, s67, v16
	v_mul_f32_e32 v17, 0x4b800000, v16
	v_lshlrev_b32_e32 v28, 16, v18
	v_cndmask_b32_e32 v16, v16, v17, vcc
	v_rsq_f32_e32 v16, v16
	v_and_b32_e32 v29, 0xffff0000, v18
	v_lshlrev_b32_e32 v30, 16, v22
	v_and_b32_e32 v31, 0xffff0000, v22
	v_mul_f32_e32 v17, 0x45800000, v16
	v_cndmask_b32_e32 v16, v16, v17, vcc
	v_pk_mul_f32 v[14:15], v[14:15], v[16:17] op_sel_hi:[1,0]
	v_pk_mul_f32 v[8:9], v[8:9], v[16:17] op_sel_hi:[1,0]
	v_mul_f32_e32 v14, 0xbfb8aa3b, v14
	v_mul_f32_e32 v15, 0xbfb8aa3b, v15
	v_pk_mul_f32 v[12:13], v[12:13], v[16:17] op_sel_hi:[1,0]
	v_pk_mul_f32 v[10:11], v[10:11], v[16:17] op_sel_hi:[1,0]
	v_exp_f32_e32 v14, v14
	v_exp_f32_e32 v15, v15
	v_mul_f32_e32 v8, 0xbfb8aa3b, v8
	v_mul_f32_e32 v9, 0xbfb8aa3b, v9
	v_mul_f32_e32 v12, 0xbfb8aa3b, v12
	v_mul_f32_e32 v13, 0xbfb8aa3b, v13
	v_exp_f32_e32 v8, v8
	v_exp_f32_e32 v9, v9
	v_mul_f32_e32 v10, 0xbfb8aa3b, v10
	v_mul_f32_e32 v11, 0xbfb8aa3b, v11
	v_exp_f32_e32 v12, v12
	v_exp_f32_e32 v13, v13
	v_exp_f32_e32 v10, v10
	v_exp_f32_e32 v11, v11
	v_add_f32_e32 v14, 1.0, v14
	v_add_f32_e32 v15, 1.0, v15
	v_rcp_f32_e32 v14, v14
	v_rcp_f32_e32 v15, v15
	v_add_f32_e32 v8, 1.0, v8
	v_add_f32_e32 v9, 1.0, v9
	v_add_f32_e32 v12, 1.0, v12
	v_add_f32_e32 v13, 1.0, v13
	v_rcp_f32_e32 v8, v8
	v_rcp_f32_e32 v9, v9
	v_add_f32_e32 v10, 1.0, v10
	v_add_f32_e32 v11, 1.0, v11
	v_rcp_f32_e32 v12, v12
	v_rcp_f32_e32 v13, v13
	v_rcp_f32_e32 v10, v10
	v_rcp_f32_e32 v11, v11
	v_lshlrev_b32_e32 v18, 16, v19
	v_and_b32_e32 v19, 0xffff0000, v19
	v_lshlrev_b32_e32 v22, 16, v23
	v_and_b32_e32 v23, 0xffff0000, v23
	v_pk_fma_f32 v[14:15], v[14:15], v[18:19], v[22:23]
	v_lshlrev_b32_e32 v18, 16, v20
	v_and_b32_e32 v19, 0xffff0000, v20
	v_lshlrev_b32_e32 v22, 16, v24
	v_and_b32_e32 v23, 0xffff0000, v24
	v_pk_fma_f32 v[18:19], v[8:9], v[18:19], v[22:23]
	v_lshlrev_b32_e32 v8, 16, v21
	v_and_b32_e32 v9, 0xffff0000, v21
	v_lshlrev_b32_e32 v20, 16, v25
	v_and_b32_e32 v21, 0xffff0000, v25
	v_pk_fma_f32 v[12:13], v[12:13], v[28:29], v[30:31]
	v_pk_fma_f32 v[20:21], v[10:11], v[8:9], v[20:21]
	v_cvt_pk_bf16_f32 v8, v12, v13
	v_cvt_pk_bf16_f32 v9, v14, v15
	v_cvt_pk_bf16_f32 v10, v18, v19
	v_cvt_pk_bf16_f32 v11, v20, v21
	global_store_dwordx4 v[26:27], v[8:11], off
	v_pk_mul_f32 v[6:7], v[6:7], v[16:17] op_sel_hi:[1,0]
	v_pk_mul_f32 v[0:1], v[0:1], v[16:17] op_sel_hi:[1,0]
	v_lshl_add_u64 v[8:9], v[158:159], 0, s[2:3]
	v_lshl_add_u64 v[10:11], s[30:31], 0, v[8:9]
	v_lshl_add_u64 v[18:19], s[0:1], 0, v[8:9]
	s_nop 1
	v_mov_b32_e32 v12, v216
	v_mov_b32_e32 v13, v217
	v_mov_b32_e32 v14, v218
	v_mov_b32_e32 v15, v219
	v_mul_f32_e32 v6, 0xbfb8aa3b, v6
	s_nop 1
	v_mov_b32_e32 v8, v220
	v_mov_b32_e32 v9, v221
	v_mov_b32_e32 v10, v222
	v_mov_b32_e32 v11, v223
	v_mul_f32_e32 v7, 0xbfb8aa3b, v7
	v_pk_mul_f32 v[4:5], v[4:5], v[16:17] op_sel_hi:[1,0]
	v_pk_mul_f32 v[2:3], v[2:3], v[16:17] op_sel_hi:[1,0]
	v_exp_f32_e32 v6, v6
	v_exp_f32_e32 v7, v7
	v_mul_f32_e32 v0, 0xbfb8aa3b, v0
	v_mul_f32_e32 v1, 0xbfb8aa3b, v1
	v_mul_f32_e32 v4, 0xbfb8aa3b, v4
	v_mul_f32_e32 v5, 0xbfb8aa3b, v5
	v_exp_f32_e32 v0, v0
	v_exp_f32_e32 v1, v1
	v_mul_f32_e32 v2, 0xbfb8aa3b, v2
	v_mul_f32_e32 v3, 0xbfb8aa3b, v3
	v_exp_f32_e32 v4, v4
	v_exp_f32_e32 v5, v5
	v_exp_f32_e32 v2, v2
	v_exp_f32_e32 v3, v3
	v_add_f32_e32 v6, 1.0, v6
	v_add_f32_e32 v7, 1.0, v7
	v_rcp_f32_e32 v6, v6
	v_rcp_f32_e32 v7, v7
	v_add_f32_e32 v0, 1.0, v0
	v_add_f32_e32 v1, 1.0, v1
	v_add_f32_e32 v4, 1.0, v4
	v_add_f32_e32 v5, 1.0, v5
	v_rcp_f32_e32 v0, v0
	v_rcp_f32_e32 v1, v1
	v_add_f32_e32 v2, 1.0, v2
	v_add_f32_e32 v3, 1.0, v3
	v_rcp_f32_e32 v4, v4
	v_rcp_f32_e32 v5, v5
	v_rcp_f32_e32 v2, v2
	v_rcp_f32_e32 v3, v3
	s_and_b64 vcc, exec, s[38:39]
	s_mov_b32 s3, s26
	s_mov_b32 s2, s12
	v_lshlrev_b32_e32 v16, 16, v12
	v_and_b32_e32 v17, 0xffff0000, v12
	v_lshlrev_b32_e32 v20, 16, v8
	v_and_b32_e32 v21, 0xffff0000, v8
	v_lshlrev_b32_e32 v12, 16, v13
	v_and_b32_e32 v13, 0xffff0000, v13
	v_lshlrev_b32_e32 v8, 16, v9
	v_and_b32_e32 v9, 0xffff0000, v9
	v_pk_fma_f32 v[6:7], v[6:7], v[12:13], v[8:9]
	v_lshlrev_b32_e32 v8, 16, v14
	v_and_b32_e32 v9, 0xffff0000, v14
	v_lshlrev_b32_e32 v12, 16, v10
	v_and_b32_e32 v13, 0xffff0000, v10
	v_pk_fma_f32 v[8:9], v[0:1], v[8:9], v[12:13]
	v_lshlrev_b32_e32 v0, 16, v15
	v_and_b32_e32 v1, 0xffff0000, v15
	v_lshlrev_b32_e32 v10, 16, v11
	v_and_b32_e32 v11, 0xffff0000, v11
	v_pk_fma_f32 v[4:5], v[4:5], v[16:17], v[20:21]
	v_pk_fma_f32 v[10:11], v[2:3], v[0:1], v[10:11]
	v_cvt_pk_bf16_f32 v0, v4, v5
	v_cvt_pk_bf16_f32 v1, v6, v7
	v_cvt_pk_bf16_f32 v2, v8, v9
	v_cvt_pk_bf16_f32 v3, v10, v11
	global_store_dwordx4 v[18:19], v[0:3], off
	s_cbranch_vccz .LBB0_346
	s_cmpk_gt_u32 s70, 0xff
	s_cbranch_scc1 .LBB0_357
	s_barrier

; #define PG8_STAGE(bufoff, gbase, voff) do { _Pragma("unroll") for (int _i = 0; _i < 2; ++_i) \
;         __builtin_amdgcn_global_load_lds((const unsigned*)((const char*)(gbase) + (voff)[_i]), (PG8_LAS unsigned*)(lds + (bufoff) + ldsw + _i * 8192), 16, 0, 0); } while (0)
; #define PG8_WAIT_V(n) asm volatile("s_waitcnt vmcnt(" #n ")" ::: "memory")
; #define PG8_BAR __builtin_amdgcn_s_barrier()
;     __device__ bool next(int i, pg8::Unit& u) const { if (i != 0 || !valid) return false; u.pm = pm; u.pn = pn; return true; }
; template <class Epi, class Sched, bool STAMP = false>
; __device__ __forceinline__ void gemm_phase(PG8_LAS unsigned char* lds, const Gemm g, const Sched& S, const Epi& E, unsigned long long* stamps) {
;     ...
;     Unit cur, nxt; int ui = 0;
;     if (!S.next(0, cur)) return;
;     f32x4 acc[2][2][4][2];
; #pragma unroll
;     for (int a = 0; a < 2; ++a)
; #pragma unroll
;         for (int b = 0; b < 2; ++b)
; #pragma unroll
;             for (int m = 0; m < 4; ++m)
; #pragma unroll
;                 for (int n = 0; n < 2; ++n) acc[a][b][m][n] = (f32x4){0.f, 0.f, 0.f, 0.f};
;     bf16x8 At[4][2], B0[2][2], B1[2][2];
;     const char* cA = (const char*)g.A + (size_t)cur.pm * tstep; const char* cB = (const char*)g.Bt + (size_t)cur.pn * tstep;
;     S.a_ready(cur);
;     PG8_STAGE(PG8_SB(0, 0), cB, voffB); PG8_STAGE(PG8_SA(0, 0), cA, voffA); PG8_STAGE(PG8_SB(0, 1), cB + hstep, voffB); PG8_STAGE(PG8_SA(0, 1), cA + hstep, voffA);
;     if (wr == 1) PG8_BAR;
;     PG8_WAIT_V(4); PG8_BAR;
;     PG8_STAGE(PG8_SB(1, 0), cB + kstep, voffB); PG8_STAGE(PG8_SA(1, 0), cA + kstep, voffA); PG8_STAGE(PG8_SB(1, 1), cB + hstep + kstep, voffB);
;     PG8_WAIT_V(6); PG8_BAR;
.LBB0_373:
	v_bfe_u32 v139, v0, 4, 2
	s_lshl_b32 s14, s14, 5
	v_and_b32_e32 v150, 15, v0
	v_lshlrev_b32_e32 v1, 4, v139
	v_lshlrev_b32_e32 v0, 2, v0
	s_and_b32 s53, s14, 0x60
	v_lshl_add_u64 v[2:3], s[4:5], 0, v[128:129]
	v_mov_b32_e32 v149, v129
	s_lshl_b32 s49, s15, 6
	v_lshl_or_b32 v1, v150, 6, v1
	s_lshl_b32 s15, s15, 13
	v_and_b32_e32 v0, 32, v0
	s_lshl_b32 s14, s53, 7
	v_lshl_add_u64 v[4:5], s[4:5], 0, v[148:149]
	v_bitop3_b32 v14, v1, s15, v0 bitop3:0xde
	v_bitop3_b32 v151, v1, s14, v0 bitop3:0xde
	s_add_i32 m0, s42, 0x18000
	v_lshl_add_u64 v[0:1], v[2:3], 0, s[18:19]
	v_lshl_add_u64 v[6:7], s[6:7], 0, v[128:129]
	s_waitcnt vmcnt(4)
	s_barrier
	global_load_lds_dwordx4 v[0:1], off
	v_lshl_add_u64 v[0:1], v[4:5], 0, s[18:19]
	s_add_i32 m0, s42, 0x1a000
	s_add_i32 s56, s42, 0x8000
	v_lshl_add_u64 v[8:9], s[6:7], 0, v[148:149]
	global_load_lds_dwordx4 v[0:1], off
	v_lshl_add_u64 v[0:1], v[6:7], 0, s[18:19]
	s_mov_b32 m0, s56
	s_add_i32 s57, s42, 0xa000
	v_lshl_add_u64 v[10:11], s[20:21], 0, v[128:129]
	global_load_lds_dwordx4 v[0:1], off
	v_lshl_add_u64 v[0:1], v[8:9], 0, s[18:19]
	s_mov_b32 m0, s57
	v_lshl_add_u64 v[12:13], s[20:21], 0, v[148:149]
	global_load_lds_dwordx4 v[0:1], off
	s_add_i32 m0, s42, 0x1c000
	v_lshl_add_u64 v[0:1], v[10:11], 0, s[18:19]
	global_load_lds_dwordx4 v[0:1], off
	v_lshl_add_u64 v[0:1], v[12:13], 0, s[18:19]
	s_add_i32 m0, s42, 0x1e000
	s_mov_b32 s14, 0
	global_load_lds_dwordx4 v[0:1], off
	s_waitcnt vmcnt(6)
	v_mov_b32_e32 v0, 0
	s_mov_b64 s[20:21], -1
	s_mov_b64 s[22:23], 0
	v_add_u32_e32 v152, 0, v14
	v_mov_b32_e32 v1, v0
	v_mov_b32_e32 v2, v0
	v_mov_b32_e32 v3, v0
	v_mov_b32_e32 v4, v0
	v_mov_b32_e32 v5, v0
	v_mov_b32_e32 v6, v0
	v_mov_b32_e32 v7, v0
	v_mov_b32_e32 v8, v0
	v_mov_b32_e32 v9, v0
	v_mov_b32_e32 v10, v0
	v_mov_b32_e32 v11, v0
	v_mov_b32_e32 v12, v0
	v_mov_b32_e32 v13, v0
	v_mov_b32_e32 v14, v0
	v_mov_b32_e32 v15, v0
	v_mov_b32_e32 v24, v0
	v_mov_b32_e32 v25, v0
	v_mov_b32_e32 v26, v0
	v_mov_b32_e32 v27, v0
	v_mov_b32_e32 v28, v0
	v_mov_b32_e32 v29, v0
	v_mov_b32_e32 v30, v0
	v_mov_b32_e32 v31, v0
	v_mov_b32_e32 v40, v0
	v_mov_b32_e32 v41, v0
	v_mov_b32_e32 v42, v0
	v_mov_b32_e32 v43, v0
	v_mov_b32_e32 v44, v0
	v_mov_b32_e32 v45, v0
	v_mov_b32_e32 v46, v0
	v_mov_b32_e32 v47, v0
	v_mov_b32_e32 v16, v0
	v_mov_b32_e32 v17, v0
	v_mov_b32_e32 v18, v0
	v_mov_b32_e32 v19, v0
	v_mov_b32_e32 v20, v0
	v_mov_b32_e32 v21, v0
	v_mov_b32_e32 v22, v0
	v_mov_b32_e32 v23, v0
	v_mov_b32_e32 v32, v0
	v_mov_b32_e32 v33, v0
	v_mov_b32_e32 v34, v0
	v_mov_b32_e32 v35, v0
	v_mov_b32_e32 v36, v0
	v_mov_b32_e32 v37, v0
	v_mov_b32_e32 v38, v0
	v_mov_b32_e32 v39, v0
	v_mov_b32_e32 v48, v0
	v_mov_b32_e32 v49, v0
	v_mov_b32_e32 v50, v0
	v_mov_b32_e32 v51, v0
	v_mov_b32_e32 v52, v0
	v_mov_b32_e32 v53, v0
	v_mov_b32_e32 v54, v0
	v_mov_b32_e32 v55, v0
	v_mov_b32_e32 v56, v0
	v_mov_b32_e32 v57, v0
	v_mov_b32_e32 v58, v0
	v_mov_b32_e32 v59, v0
	v_mov_b32_e32 v60, v0
	v_mov_b32_e32 v61, v0
	v_mov_b32_e32 v62, v0
	v_mov_b32_e32 v63, v0
	v_mov_b32_e32 v64, v0
	v_mov_b32_e32 v65, v0
	v_mov_b32_e32 v66, v0
	v_mov_b32_e32 v67, v0
	v_mov_b32_e32 v68, v0
	v_mov_b32_e32 v69, v0
	v_mov_b32_e32 v70, v0
	v_mov_b32_e32 v71, v0
	v_mov_b32_e32 v72, v0
	v_mov_b32_e32 v73, v0
	v_mov_b32_e32 v74, v0
	v_mov_b32_e32 v75, v0
	v_mov_b32_e32 v76, v0
	v_mov_b32_e32 v77, v0
	v_mov_b32_e32 v78, v0
	v_mov_b32_e32 v79, v0
	v_mov_b32_e32 v84, v0
	v_mov_b32_e32 v85, v0
	v_mov_b32_e32 v86, v0
	v_mov_b32_e32 v87, v0
	v_mov_b32_e32 v92, v0
	v_mov_b32_e32 v93, v0
	v_mov_b32_e32 v94, v0
	v_mov_b32_e32 v95, v0
	v_mov_b32_e32 v100, v0
	v_mov_b32_e32 v101, v0
	v_mov_b32_e32 v102, v0
	v_mov_b32_e32 v103, v0
	v_mov_b32_e32 v108, v0
	v_mov_b32_e32 v109, v0
	v_mov_b32_e32 v110, v0
	v_mov_b32_e32 v111, v0
	v_mov_b32_e32 v80, v0
	v_mov_b32_e32 v81, v0
	v_mov_b32_e32 v82, v0
	v_mov_b32_e32 v83, v0
	v_mov_b32_e32 v88, v0
	v_mov_b32_e32 v89, v0
	v_mov_b32_e32 v90, v0
	v_mov_b32_e32 v91, v0
	v_mov_b32_e32 v96, v0
	v_mov_b32_e32 v97, v0
	v_mov_b32_e32 v98, v0
	v_mov_b32_e32 v99, v0
	v_mov_b32_e32 v104, v0
	v_mov_b32_e32 v105, v0
	v_mov_b32_e32 v106, v0
	v_mov_b32_e32 v107, v0
	v_mov_b32_e32 v112, v0
	v_mov_b32_e32 v113, v0
	v_mov_b32_e32 v114, v0
	v_mov_b32_e32 v115, v0
	v_mov_b32_e32 v116, v0
	v_mov_b32_e32 v117, v0
	v_mov_b32_e32 v118, v0
	v_mov_b32_e32 v119, v0
	v_mov_b32_e32 v120, v0
	v_mov_b32_e32 v121, v0
	v_mov_b32_e32 v122, v0
	v_mov_b32_e32 v123, v0
	v_mov_b32_e32 v124, v0
	v_mov_b32_e32 v125, v0
	v_mov_b32_e32 v126, v0
	v_mov_b32_e32 v127, v0
	s_barrier
	v_add_u32_e32 v244, 0x80, v128
	v_add_u32_e32 v245, 0x80, v148
; #define PG8_STAGE(bufoff, gbase, voff) do { _Pragma("unroll") for (int _i = 0; _i < 2; ++_i) \
;         __builtin_amdgcn_global_load_lds((const unsigned*)((const char*)(gbase) + (voff)[_i]), (PG8_LAS unsigned*)(lds + (bufoff) + ldsw + _i * 8192), 16, 0, 0); } while (0)
; #define PG8_LDA(dst, b, h) do { _Pragma("unroll") for (int m = 0; m < 4; ++m) _Pragma("unroll") for (int k = 0; k < 2; ++k) dst[m][k] = *(const PG8_LAS bf16x8*)(lds + PG8_SA(b, h) + aoff + m * 2048 + k * 1024); } while (0)
; #define PG8_LDB(dst, b, h) do { _Pragma("unroll") for (int n = 0; n < 2; ++n) _Pragma("unroll") for (int k = 0; k < 2; ++k) dst[n][k] = *(const PG8_LAS bf16x8*)(lds + PG8_SB(b, h) + boff + n * 2048 + k * 1024); } while (0)
; #define PG8_MMA(ai, bj, At, Bt) do { __builtin_amdgcn_s_setprio(1); _Pragma("unroll") for (int m = 0; m < 4; ++m) _Pragma("unroll") for (int n = 0; n < 2; ++n) _Pragma("unroll") for (int k = 0; k < 2; ++k) \
;         acc[ai][bj][m][n] = __builtin_amdgcn_mfma_f32_16x16x32_bf16(Bt[n][k], At[m][k], acc[ai][bj][m][n], 0, 0, 0); __builtin_amdgcn_s_setprio(0); } while (0)
; #define PG8_BAR __builtin_amdgcn_s_barrier()
; template <class Epi, class Sched, bool STAMP = false>
; __device__ __forceinline__ void gemm_phase(PG8_LAS unsigned char* lds, const Gemm g, const Sched& S, const Epi& E, unsigned long long* stamps) {
;     ...
;         for (int t = 0; t < nt; t += 2) {
;             const bool last = (t == nt - 2);
;             const char* a1 = cA + (size_t)(t + 1) * kstep;
;             const char* a2 = last ? nA : cA + (size_t)(t + 2) * kstep; const char* b2 = last ? nB : cB + (size_t)(t + 2) * kstep;
;             const char* a3 = a2 + kstep; const char* b3 = b2 + kstep;
;             if (last && has_next) S.a_ready(nxt);
;             PG8_LDB(B0, 0, 0); PG8_SCHED; PG8_LDA(At, 0, 0); PG8_STAGE(PG8_SA(1, 1), a1 + hstep, voffA);
;             PG8_WAIT_L(8); PG8_BAR; PG8_WAIT_L(0); PG8_MMA(0, 0, At, B0); PG8_BAR; PG8_SCHED;
;             PG8_LDB(B1, 0, 1); PG8_STAGE(PG8_SB(0, 0), b2, voffB);
;             PG8_BAR; PG8_WAIT_L(0); PG8_MMA(0, 1, At, B1); PG8_BAR;
;             PG8_LDA(At, 0, 1); PG8_STAGE(PG8_SA(0, 0), a2, voffA);
;             PG8_BAR; PG8_WAIT_L(0); PG8_MMA(1, 0, At, B0); PG8_BAR; PG8_SCHED;
;             PG8_STAGE(PG8_SB(0, 1), b2 + hstep, voffB);
;             PG8_WAIT_V(6); PG8_BAR; PG8_MMA(1, 1, At, B1); PG8_BAR;
.LBB0_374:
	s_add_i32 s15, s14, 0x100
	s_and_b64 s[16:17], s[22:23], exec
	s_cselect_b32 s15, 0, s15
	s_cselect_b32 s16, 0, 0
	s_add_u32 s26, s6, s15
	s_addc_u32 s27, s7, s16
	s_add_i32 s52, 0, 0x10000
	s_add_u32 s30, s4, s15
	s_addc_u32 s31, s5, s16
	s_add_u32 s36, s12, s14
	s_addc_u32 s37, s13, 0
	s_add_i32 s62, s52, s46
	v_add_u32_e32 v153, s52, v151
	s_add_i32 m0, s42, 0xc000
	s_add_i32 s61, s42, 0xe000
	s_add_i32 s60, 0, 0x14000
	s_add_i32 s59, s62, 0x2000
	ds_read_b128 v[154:157], v153
	ds_read_b128 v[158:161], v153 offset:1024
	ds_read_b128 v[162:165], v153 offset:2048
	ds_read_b128 v[166:169], v153 offset:3072
	s_add_u32 s24, s30, s45
	s_addc_u32 s25, s31, 0
	s_add_i32 s29, s60, s46
	s_add_i32 s17, s29, 0x2000
	s_add_i32 s16, 0, 0x18000
	s_add_u32 s22, s26, s45
	s_addc_u32 s23, s27, 0
	s_add_i32 s14, 0, 0x1c000
	s_add_i32 s15, s16, s46
	s_add_i32 s58, s14, s46
	s_add_i32 s63, s15, 0x2000
	s_add_i32 s52, s58, 0x2000
	v_lshl_add_u64 v[182:183], s[36:37], 0, v[128:129]
	v_lshl_add_u64 v[182:183], v[182:183], 0, s[18:19]
	ds_read_b128 v[170:173], v152
	ds_read_b128 v[174:177], v152 offset:1024
	ds_read_b128 v[178:181], v152 offset:2048
	ds_read_b128 v[192:195], v152 offset:3072
	ds_read_b128 v[196:199], v152 offset:4096
	ds_read_b128 v[200:203], v152 offset:5120
	ds_read_b128 v[204:207], v152 offset:6144
	ds_read_b128 v[208:211], v152 offset:7168
	global_load_lds_dwordx4 v244, s[36:37]
	v_lshl_add_u64 v[182:183], s[36:37], 0, v[148:149]
	v_lshl_add_u64 v[182:183], v[182:183], 0, s[18:19]
	s_mov_b32 m0, s61
	s_nop 0
	global_load_lds_dwordx4 v245, s[36:37]
	s_waitcnt lgkmcnt(8)
	s_barrier
	s_waitcnt lgkmcnt(0)
	v_mfma_f32_16x16x32_bf16 v[124:127], v[154:157], v[170:173], v[124:127]
	v_mfma_f32_16x16x32_bf16 v[120:123], v[162:165], v[170:173], v[120:123]
	v_mfma_f32_16x16x32_bf16 v[116:119], v[154:157], v[178:181], v[116:119]
	v_mfma_f32_16x16x32_bf16 v[112:115], v[162:165], v[178:181], v[112:115]
	v_mfma_f32_16x16x32_bf16 v[104:107], v[154:157], v[196:199], v[104:107]
	v_mfma_f32_16x16x32_bf16 v[96:99], v[162:165], v[196:199], v[96:99]
	v_mfma_f32_16x16x32_bf16 v[88:91], v[154:157], v[204:207], v[88:91]
	v_mfma_f32_16x16x32_bf16 v[80:83], v[162:165], v[204:207], v[80:83]
	v_mfma_f32_16x16x32_bf16 v[124:127], v[158:161], v[174:177], v[124:127]
	v_mfma_f32_16x16x32_bf16 v[120:123], v[166:169], v[174:177], v[120:123]
	v_mfma_f32_16x16x32_bf16 v[116:119], v[158:161], v[192:195], v[116:119]
	v_mfma_f32_16x16x32_bf16 v[112:115], v[166:169], v[192:195], v[112:115]
	v_mfma_f32_16x16x32_bf16 v[104:107], v[158:161], v[200:203], v[104:107]
	v_mfma_f32_16x16x32_bf16 v[96:99], v[166:169], v[200:203], v[96:99]
	v_mfma_f32_16x16x32_bf16 v[88:91], v[158:161], v[208:211], v[88:91]
	v_mfma_f32_16x16x32_bf16 v[80:83], v[166:169], v[208:211], v[80:83]
	s_barrier
	s_mov_b32 m0, s62
	v_add_u32_e32 v153, s60, v151
	v_lshl_add_u64 v[182:183], s[30:31], 0, v[128:129]
	ds_read_b128 v[212:215], v153
	ds_read_b128 v[216:219], v153 offset:1024
	ds_read_b128 v[220:223], v153 offset:2048
	ds_read_b128 v[224:227], v153 offset:3072
	global_load_lds_dwordx4 v128, s[30:31]
	v_lshl_add_u64 v[228:229], s[30:31], 0, v[148:149]
	s_mov_b32 m0, s59
	s_nop 0
	global_load_lds_dwordx4 v148, s[30:31]
	s_barrier
	s_waitcnt lgkmcnt(0)
	v_mfma_f32_16x16x32_bf16 v[108:111], v[212:215], v[170:173], v[108:111]
	v_mfma_f32_16x16x32_bf16 v[100:103], v[220:223], v[170:173], v[100:103]
	v_mfma_f32_16x16x32_bf16 v[92:95], v[212:215], v[178:181], v[92:95]
	v_mfma_f32_16x16x32_bf16 v[84:87], v[220:223], v[178:181], v[84:87]
	v_mfma_f32_16x16x32_bf16 v[76:79], v[212:215], v[196:199], v[76:79]
	v_mfma_f32_16x16x32_bf16 v[72:75], v[220:223], v[196:199], v[72:75]
	v_mfma_f32_16x16x32_bf16 v[68:71], v[212:215], v[204:207], v[68:71]
	v_mfma_f32_16x16x32_bf16 v[64:67], v[220:223], v[204:207], v[64:67]
	v_mfma_f32_16x16x32_bf16 v[108:111], v[216:219], v[174:177], v[108:111]
	v_mfma_f32_16x16x32_bf16 v[100:103], v[224:227], v[174:177], v[100:103]
	v_mfma_f32_16x16x32_bf16 v[92:95], v[216:219], v[192:195], v[92:95]
	v_mfma_f32_16x16x32_bf16 v[84:87], v[224:227], v[192:195], v[84:87]
	v_mfma_f32_16x16x32_bf16 v[76:79], v[216:219], v[200:203], v[76:79]
	v_mfma_f32_16x16x32_bf16 v[72:75], v[224:227], v[200:203], v[72:75]
	v_mfma_f32_16x16x32_bf16 v[68:71], v[216:219], v[208:211], v[68:71]
	v_mfma_f32_16x16x32_bf16 v[64:67], v[224:227], v[208:211], v[64:67]
	s_mov_b32 m0, s42
	v_lshl_add_u64 v[230:231], s[26:27], 0, v[128:129]
	s_barrier
	ds_read_b128 v[170:173], v152 offset:16384
	ds_read_b128 v[174:177], v152 offset:17408
	ds_read_b128 v[178:181], v152 offset:18432
	ds_read_b128 v[192:195], v152 offset:19456
	ds_read_b128 v[196:199], v152 offset:20480
	ds_read_b128 v[200:203], v152 offset:21504
	ds_read_b128 v[204:207], v152 offset:22528
	ds_read_b128 v[208:211], v152 offset:23552
	global_load_lds_dwordx4 v128, s[26:27]
	v_lshl_add_u64 v[232:233], s[26:27], 0, v[148:149]
	s_mov_b32 m0, s43
	s_nop 0
	global_load_lds_dwordx4 v148, s[26:27]
	s_barrier
	s_waitcnt lgkmcnt(0)
	v_mfma_f32_16x16x32_bf16 v[60:63], v[154:157], v[170:173], v[60:63]
	v_mfma_f32_16x16x32_bf16 v[56:59], v[162:165], v[170:173], v[56:59]
	v_mfma_f32_16x16x32_bf16 v[52:55], v[154:157], v[178:181], v[52:55]
	v_mfma_f32_16x16x32_bf16 v[48:51], v[162:165], v[178:181], v[48:51]
	v_mfma_f32_16x16x32_bf16 v[36:39], v[154:157], v[196:199], v[36:39]
	v_mfma_f32_16x16x32_bf16 v[32:35], v[162:165], v[196:199], v[32:35]
	v_mfma_f32_16x16x32_bf16 v[20:23], v[154:157], v[204:207], v[20:23]
	v_mfma_f32_16x16x32_bf16 v[16:19], v[162:165], v[204:207], v[16:19]
	v_mfma_f32_16x16x32_bf16 v[60:63], v[158:161], v[174:177], v[60:63]
	v_mfma_f32_16x16x32_bf16 v[56:59], v[166:169], v[174:177], v[56:59]
	v_mfma_f32_16x16x32_bf16 v[52:55], v[158:161], v[192:195], v[52:55]
	v_mfma_f32_16x16x32_bf16 v[48:51], v[166:169], v[192:195], v[48:51]
	v_mfma_f32_16x16x32_bf16 v[36:39], v[158:161], v[200:203], v[36:39]
	v_mfma_f32_16x16x32_bf16 v[32:35], v[166:169], v[200:203], v[32:35]
	v_mfma_f32_16x16x32_bf16 v[20:23], v[158:161], v[208:211], v[20:23]
	v_mfma_f32_16x16x32_bf16 v[16:19], v[166:169], v[208:211], v[16:19]
	s_barrier
; #define PG8_STAGE(bufoff, gbase, voff) do { _Pragma("unroll") for (int _i = 0; _i < 2; ++_i) \
;         __builtin_amdgcn_global_load_lds((const unsigned*)((const char*)(gbase) + (voff)[_i]), (PG8_LAS unsigned*)(lds + (bufoff) + ldsw + _i * 8192), 16, 0, 0); } while (0)
; #define PG8_LDA(dst, b, h) do { _Pragma("unroll") for (int m = 0; m < 4; ++m) _Pragma("unroll") for (int k = 0; k < 2; ++k) dst[m][k] = *(const PG8_LAS bf16x8*)(lds + PG8_SA(b, h) + aoff + m * 2048 + k * 1024); } while (0)
; #define PG8_LDB(dst, b, h) do { _Pragma("unroll") for (int n = 0; n < 2; ++n) _Pragma("unroll") for (int k = 0; k < 2; ++k) dst[n][k] = *(const PG8_LAS bf16x8*)(lds + PG8_SB(b, h) + boff + n * 2048 + k * 1024); } while (0)
; #define PG8_MMA(ai, bj, At, Bt) do { __builtin_amdgcn_s_setprio(1); _Pragma("unroll") for (int m = 0; m < 4; ++m) _Pragma("unroll") for (int n = 0; n < 2; ++n) _Pragma("unroll") for (int k = 0; k < 2; ++k) \
;         acc[ai][bj][m][n] = __builtin_amdgcn_mfma_f32_16x16x32_bf16(Bt[n][k], At[m][k], acc[ai][bj][m][n], 0, 0, 0); __builtin_amdgcn_s_setprio(0); } while (0)
; #define PG8_WAIT_V(n) asm volatile("s_waitcnt vmcnt(" #n ")" ::: "memory")
; #define PG8_WAIT_L(n) asm volatile("s_waitcnt lgkmcnt(" #n ")" ::: "memory")
; #define PG8_BAR __builtin_amdgcn_s_barrier()
; #define PG8_SCHED __builtin_amdgcn_sched_barrier(0)
; template <class Epi, class Sched, bool STAMP = false>
; __device__ __forceinline__ void gemm_phase(PG8_LAS unsigned char* lds, const Gemm g, const Sched& S, const Epi& E, unsigned long long* stamps) {
;     ...
;             PG8_WAIT_V(6); PG8_BAR; PG8_MMA(1, 1, At, B1); PG8_BAR;
;             PG8_LDB(B0, 1, 0); PG8_SCHED; PG8_LDA(At, 1, 0); PG8_STAGE(PG8_SA(0, 1), a2 + hstep, voffA);
;             PG8_WAIT_L(8); PG8_BAR; PG8_WAIT_L(0); PG8_MMA(0, 0, At, B0); PG8_BAR; PG8_SCHED;
;             PG8_LDB(B1, 1, 1); PG8_STAGE(PG8_SB(1, 0), b3, voffB);
;             PG8_BAR; PG8_WAIT_L(0); PG8_MMA(0, 1, At, B1); PG8_BAR;
;             PG8_LDA(At, 1, 1); PG8_STAGE(PG8_SA(1, 0), a3, voffA);
;             PG8_BAR; PG8_WAIT_L(0); PG8_MMA(1, 0, At, B0); PG8_BAR; PG8_SCHED;
	s_mov_b32 m0, s29
	s_nop 0
	global_load_lds_dwordx4 v128, s[24:25]
	s_mov_b32 m0, s17
	s_nop 0
	global_load_lds_dwordx4 v148, s[24:25]
	s_waitcnt vmcnt(6)
	s_barrier
	v_mfma_f32_16x16x32_bf16 v[44:47], v[212:215], v[170:173], v[44:47]
	v_mfma_f32_16x16x32_bf16 v[40:43], v[220:223], v[170:173], v[40:43]
	v_mfma_f32_16x16x32_bf16 v[28:31], v[212:215], v[178:181], v[28:31]
	v_mfma_f32_16x16x32_bf16 v[24:27], v[220:223], v[178:181], v[24:27]
	v_mfma_f32_16x16x32_bf16 v[12:15], v[212:215], v[196:199], v[12:15]
	v_mfma_f32_16x16x32_bf16 v[8:11], v[220:223], v[196:199], v[8:11]
	v_mfma_f32_16x16x32_bf16 v[4:7], v[212:215], v[204:207], v[4:7]
	v_mfma_f32_16x16x32_bf16 v[0:3], v[220:223], v[204:207], v[0:3]
	v_mfma_f32_16x16x32_bf16 v[44:47], v[216:219], v[174:177], v[44:47]
	v_mfma_f32_16x16x32_bf16 v[40:43], v[224:227], v[174:177], v[40:43]
	v_mfma_f32_16x16x32_bf16 v[28:31], v[216:219], v[192:195], v[28:31]
	v_mfma_f32_16x16x32_bf16 v[24:27], v[224:227], v[192:195], v[24:27]
	v_mfma_f32_16x16x32_bf16 v[12:15], v[216:219], v[200:203], v[12:15]
	v_mfma_f32_16x16x32_bf16 v[8:11], v[224:227], v[200:203], v[8:11]
	v_mfma_f32_16x16x32_bf16 v[4:7], v[216:219], v[208:211], v[4:7]
	v_mfma_f32_16x16x32_bf16 v[0:3], v[224:227], v[208:211], v[0:3]
	v_add_u32_e32 v153, s16, v151
	s_barrier
	ds_read_b128 v[154:157], v153
	ds_read_b128 v[158:161], v153 offset:1024
	ds_read_b128 v[162:165], v153 offset:2048
	ds_read_b128 v[166:169], v153 offset:3072
	s_mov_b32 m0, s47
	ds_read_b128 v[170:173], v152 offset:32768
	ds_read_b128 v[174:177], v152 offset:33792
	ds_read_b128 v[178:181], v152 offset:34816
	ds_read_b128 v[192:195], v152 offset:35840
	ds_read_b128 v[196:199], v152 offset:36864
	ds_read_b128 v[200:203], v152 offset:37888
	ds_read_b128 v[204:207], v152 offset:38912
	ds_read_b128 v[208:211], v152 offset:39936
	global_load_lds_dwordx4 v128, s[22:23]
	s_mov_b32 m0, s48
	s_nop 0
	global_load_lds_dwordx4 v148, s[22:23]
	s_waitcnt lgkmcnt(8)
	s_barrier
	s_waitcnt lgkmcnt(0)
	v_mfma_f32_16x16x32_bf16 v[124:127], v[154:157], v[170:173], v[124:127]
	v_mfma_f32_16x16x32_bf16 v[120:123], v[162:165], v[170:173], v[120:123]
	v_mfma_f32_16x16x32_bf16 v[116:119], v[154:157], v[178:181], v[116:119]
	v_mfma_f32_16x16x32_bf16 v[112:115], v[162:165], v[178:181], v[112:115]
	v_mfma_f32_16x16x32_bf16 v[104:107], v[154:157], v[196:199], v[104:107]
	v_mfma_f32_16x16x32_bf16 v[96:99], v[162:165], v[196:199], v[96:99]
	v_mfma_f32_16x16x32_bf16 v[88:91], v[154:157], v[204:207], v[88:91]
	v_mfma_f32_16x16x32_bf16 v[80:83], v[162:165], v[204:207], v[80:83]
	v_mfma_f32_16x16x32_bf16 v[124:127], v[158:161], v[174:177], v[124:127]
	v_mfma_f32_16x16x32_bf16 v[120:123], v[166:169], v[174:177], v[120:123]
	v_mfma_f32_16x16x32_bf16 v[116:119], v[158:161], v[192:195], v[116:119]
	v_mfma_f32_16x16x32_bf16 v[112:115], v[166:169], v[192:195], v[112:115]
	v_mfma_f32_16x16x32_bf16 v[104:107], v[158:161], v[200:203], v[104:107]
	v_mfma_f32_16x16x32_bf16 v[96:99], v[166:169], v[200:203], v[96:99]
	v_mfma_f32_16x16x32_bf16 v[88:91], v[158:161], v[208:211], v[88:91]
	v_mfma_f32_16x16x32_bf16 v[80:83], v[166:169], v[208:211], v[80:83]
	s_barrier
	s_mov_b32 m0, s15
	v_add_u32_e32 v153, s14, v151
	v_lshl_add_u64 v[182:183], v[182:183], 0, s[18:19]
	ds_read_b128 v[212:215], v153
	ds_read_b128 v[216:219], v153 offset:1024
	ds_read_b128 v[220:223], v153 offset:2048
	ds_read_b128 v[224:227], v153 offset:3072
	global_load_lds_dwordx4 v244, s[30:31]
	v_lshl_add_u64 v[182:183], v[228:229], 0, s[18:19]
	s_mov_b32 m0, s63
	s_nop 0
	global_load_lds_dwordx4 v245, s[30:31]
	s_barrier
	s_waitcnt lgkmcnt(0)
	v_mfma_f32_16x16x32_bf16 v[108:111], v[212:215], v[170:173], v[108:111]
	v_mfma_f32_16x16x32_bf16 v[100:103], v[220:223], v[170:173], v[100:103]
	v_mfma_f32_16x16x32_bf16 v[92:95], v[212:215], v[178:181], v[92:95]
	v_mfma_f32_16x16x32_bf16 v[84:87], v[220:223], v[178:181], v[84:87]
	v_mfma_f32_16x16x32_bf16 v[76:79], v[212:215], v[196:199], v[76:79]
	v_mfma_f32_16x16x32_bf16 v[72:75], v[220:223], v[196:199], v[72:75]
	v_mfma_f32_16x16x32_bf16 v[68:71], v[212:215], v[204:207], v[68:71]
	v_mfma_f32_16x16x32_bf16 v[64:67], v[220:223], v[204:207], v[64:67]
	v_mfma_f32_16x16x32_bf16 v[108:111], v[216:219], v[174:177], v[108:111]
	v_mfma_f32_16x16x32_bf16 v[100:103], v[224:227], v[174:177], v[100:103]
	v_mfma_f32_16x16x32_bf16 v[92:95], v[216:219], v[192:195], v[92:95]
	v_mfma_f32_16x16x32_bf16 v[84:87], v[224:227], v[192:195], v[84:87]
	v_mfma_f32_16x16x32_bf16 v[76:79], v[216:219], v[200:203], v[76:79]
	v_mfma_f32_16x16x32_bf16 v[72:75], v[224:227], v[200:203], v[72:75]
	v_mfma_f32_16x16x32_bf16 v[68:71], v[216:219], v[208:211], v[68:71]
	v_mfma_f32_16x16x32_bf16 v[64:67], v[224:227], v[208:211], v[64:67]
	s_mov_b32 m0, s56
	v_lshl_add_u64 v[182:183], v[230:231], 0, s[18:19]
	s_barrier
	ds_read_b128 v[170:173], v152 offset:49152
	ds_read_b128 v[174:177], v152 offset:50176
	ds_read_b128 v[178:181], v152 offset:51200
	ds_read_b128 v[192:195], v152 offset:52224
	ds_read_b128 v[196:199], v152 offset:53248
	ds_read_b128 v[200:203], v152 offset:54272
	ds_read_b128 v[204:207], v152 offset:55296
	ds_read_b128 v[208:211], v152 offset:56320
	global_load_lds_dwordx4 v244, s[26:27]
	v_lshl_add_u64 v[182:183], v[232:233], 0, s[18:19]
	s_mov_b32 m0, s57
	s_nop 0
	global_load_lds_dwordx4 v245, s[26:27]
	s_barrier
; #define PG8_STAGE(bufoff, gbase, voff) do { _Pragma("unroll") for (int _i = 0; _i < 2; ++_i) \
;         __builtin_amdgcn_global_load_lds((const unsigned*)((const char*)(gbase) + (voff)[_i]), (PG8_LAS unsigned*)(lds + (bufoff) + ldsw + _i * 8192), 16, 0, 0); } while (0)
; #define PG8_MMA(ai, bj, At, Bt) do { __builtin_amdgcn_s_setprio(1); _Pragma("unroll") for (int m = 0; m < 4; ++m) _Pragma("unroll") for (int n = 0; n < 2; ++n) _Pragma("unroll") for (int k = 0; k < 2; ++k) \
;         acc[ai][bj][m][n] = __builtin_amdgcn_mfma_f32_16x16x32_bf16(Bt[n][k], At[m][k], acc[ai][bj][m][n], 0, 0, 0); __builtin_amdgcn_s_setprio(0); } while (0)
; #define PG8_WAIT_V(n) asm volatile("s_waitcnt vmcnt(" #n ")" ::: "memory")
; #define PG8_WAIT_L(n) asm volatile("s_waitcnt lgkmcnt(" #n ")" ::: "memory")
; #define PG8_BAR __builtin_amdgcn_s_barrier()
; #define PG8_SCHED __builtin_amdgcn_sched_barrier(0)
; template <class Epi, class Sched, bool STAMP = false>
; __device__ __forceinline__ void gemm_phase(PG8_LAS unsigned char* lds, const Gemm g, const Sched& S, const Epi& E, unsigned long long* stamps) {
;     ...
;             PG8_BAR; PG8_WAIT_L(0); PG8_MMA(1, 0, At, B0); PG8_BAR; PG8_SCHED;
;             PG8_STAGE(PG8_SB(1, 1), b3 + hstep, voffB);
;             PG8_WAIT_V(6); PG8_BAR; PG8_MMA(1, 1, At, B1); PG8_BAR;
;     __device__ __forceinline__ void operator()(const f32x4 (&acc)[2][2][4][2], const pg8::Unit& u, int wr, int wc, int fr, int fq) const {
;         const int row0 = (u.pm - 64) * 256 + wr * 64 + fr, col0 = u.pn * 256 + wc * 32 + 4 * fq;
; #pragma unroll
;         for (int ai = 0; ai < 2; ++ai)
; #pragma unroll
;             for (int m = 0; m < 4; ++m) { float* xp = PART + (size_t)(row0 + ai * 128 + m * 16) * ldp + col0;
; #pragma unroll
;                 for (int bj = 0; bj < 2; ++bj)
; #pragma unroll
;                     for (int n = 0; n < 2; ++n) *(f32x4*)(xp + bj * 128 + n * 16) = acc[ai][bj][m][n]; }
	s_waitcnt lgkmcnt(0)
	v_mfma_f32_16x16x32_bf16 v[60:63], v[154:157], v[170:173], v[60:63]
	v_mfma_f32_16x16x32_bf16 v[56:59], v[162:165], v[170:173], v[56:59]
	v_mfma_f32_16x16x32_bf16 v[52:55], v[154:157], v[178:181], v[52:55]
	v_mfma_f32_16x16x32_bf16 v[48:51], v[162:165], v[178:181], v[48:51]
	v_mfma_f32_16x16x32_bf16 v[36:39], v[154:157], v[196:199], v[36:39]
	v_mfma_f32_16x16x32_bf16 v[32:35], v[162:165], v[196:199], v[32:35]
	v_mfma_f32_16x16x32_bf16 v[20:23], v[154:157], v[204:207], v[20:23]
	v_mfma_f32_16x16x32_bf16 v[16:19], v[162:165], v[204:207], v[16:19]
	v_mfma_f32_16x16x32_bf16 v[60:63], v[158:161], v[174:177], v[60:63]
	v_mfma_f32_16x16x32_bf16 v[56:59], v[166:169], v[174:177], v[56:59]
	v_mfma_f32_16x16x32_bf16 v[52:55], v[158:161], v[192:195], v[52:55]
	v_mfma_f32_16x16x32_bf16 v[48:51], v[166:169], v[192:195], v[48:51]
	v_mfma_f32_16x16x32_bf16 v[36:39], v[158:161], v[200:203], v[36:39]
	v_mfma_f32_16x16x32_bf16 v[32:35], v[166:169], v[200:203], v[32:35]
	v_mfma_f32_16x16x32_bf16 v[20:23], v[158:161], v[208:211], v[20:23]
	v_mfma_f32_16x16x32_bf16 v[16:19], v[166:169], v[208:211], v[16:19]
	s_barrier
	s_mov_b32 m0, s58
	s_nop 0
	global_load_lds_dwordx4 v244, s[24:25]
	s_mov_b32 m0, s52
	s_nop 0
	global_load_lds_dwordx4 v245, s[24:25]
	s_waitcnt vmcnt(6)
	s_barrier
	v_mfma_f32_16x16x32_bf16 v[44:47], v[212:215], v[170:173], v[44:47]
	v_mfma_f32_16x16x32_bf16 v[40:43], v[220:223], v[170:173], v[40:43]
	v_mfma_f32_16x16x32_bf16 v[28:31], v[212:215], v[178:181], v[28:31]
	v_mfma_f32_16x16x32_bf16 v[24:27], v[220:223], v[178:181], v[24:27]
	v_mfma_f32_16x16x32_bf16 v[12:15], v[212:215], v[196:199], v[12:15]
	v_mfma_f32_16x16x32_bf16 v[8:11], v[220:223], v[196:199], v[8:11]
	v_mfma_f32_16x16x32_bf16 v[4:7], v[212:215], v[204:207], v[4:7]
	v_mfma_f32_16x16x32_bf16 v[0:3], v[220:223], v[204:207], v[0:3]
	v_mfma_f32_16x16x32_bf16 v[44:47], v[216:219], v[174:177], v[44:47]
	v_mfma_f32_16x16x32_bf16 v[40:43], v[224:227], v[174:177], v[40:43]
	v_mfma_f32_16x16x32_bf16 v[28:31], v[216:219], v[192:195], v[28:31]
	v_mfma_f32_16x16x32_bf16 v[24:27], v[224:227], v[192:195], v[24:27]
	v_mfma_f32_16x16x32_bf16 v[12:15], v[216:219], v[200:203], v[12:15]
	v_mfma_f32_16x16x32_bf16 v[8:11], v[224:227], v[200:203], v[8:11]
	v_mfma_f32_16x16x32_bf16 v[4:7], v[216:219], v[208:211], v[4:7]
	v_mfma_f32_16x16x32_bf16 v[0:3], v[224:227], v[208:211], v[0:3]
	s_andn2_b64 vcc, exec, s[20:21]
	s_mov_b64 s[22:23], -1
	s_mov_b64 s[20:21], 0
	s_movk_i32 s14, 0x100
	s_barrier
	s_cbranch_vccz .LBB0_374
	s_lshl_b64 s[4:5], s[10:11], 22
	s_add_u32 s4, s2, s4
	s_addc_u32 s5, s3, s5
	s_lshl_b32 s6, s44, 8
	s_addk_i32 s6, 0xc000
	v_or_b32_e32 v128, s6, v150
	v_add_u32_e32 v148, s49, v128
	s_lshl_b32 s6, s39, 8
	v_lshl_or_b32 v128, v139, 2, s6
	v_ashrrev_i32_e32 v149, 31, v148
	v_or_b32_e32 v128, s53, v128
	v_lshlrev_b64 v[150:151], 12, v[148:149]
	v_lshl_add_u64 v[150:151], s[4:5], 0, v[150:151]
	v_lshlrev_b32_e32 v128, 2, v128
	v_lshl_add_u64 v[150:151], v[150:151], 0, v[128:129]
	global_store_dwordx4 v[150:151], v[124:127], off
	global_store_dwordx4 v[150:151], v[120:123], off offset:64
	global_store_dwordx4 v[150:151], v[108:111], off offset:512
	global_store_dwordx4 v[150:151], v[100:103], off offset:576
	s_cmpk_lt_u32 s38, 0x100
	s_nop 0
	v_or_b32_e32 v100, 16, v148
	v_ashrrev_i32_e32 v101, 31, v100
	v_lshlrev_b64 v[100:101], 12, v[100:101]
	v_lshl_add_u64 v[100:101], s[4:5], 0, v[100:101]
	v_lshl_add_u64 v[100:101], v[100:101], 0, v[128:129]
	global_store_dwordx4 v[100:101], v[116:119], off
	global_store_dwordx4 v[100:101], v[112:115], off offset:64
	global_store_dwordx4 v[100:101], v[92:95], off offset:512
	global_store_dwordx4 v[100:101], v[84:87], off offset:576
	s_nop 1
	v_or_b32_e32 v84, 32, v148
	v_ashrrev_i32_e32 v85, 31, v84
	v_lshlrev_b64 v[84:85], 12, v[84:85]
	v_lshl_add_u64 v[84:85], s[4:5], 0, v[84:85]
	v_lshl_add_u64 v[84:85], v[84:85], 0, v[128:129]
	global_store_dwordx4 v[84:85], v[104:107], off
	global_store_dwordx4 v[84:85], v[96:99], off offset:64
	global_store_dwordx4 v[84:85], v[76:79], off offset:512
	global_store_dwordx4 v[84:85], v[72:75], off offset:576
	s_nop 1
	v_or_b32_e32 v72, 48, v148
	v_ashrrev_i32_e32 v73, 31, v72
	v_lshlrev_b64 v[72:73], 12, v[72:73]
	v_lshl_add_u64 v[72:73], s[4:5], 0, v[72:73]
	v_lshl_add_u64 v[72:73], v[72:73], 0, v[128:129]
	s_mov_b64 s[4:5], 0x80000
	global_store_dwordx4 v[72:73], v[88:91], off
	global_store_dwordx4 v[72:73], v[80:83], off offset:64
	global_store_dwordx4 v[72:73], v[68:71], off offset:512
	global_store_dwordx4 v[72:73], v[64:67], off offset:576
	s_nop 1
	v_lshl_add_u64 v[64:65], v[150:151], 0, s[4:5]
	s_mov_b32 s4, 0x80000
	v_add_co_u32_e32 v66, vcc, s4, v150
	s_mov_b64 s[4:5], 0x90000
	s_nop 0
	v_addc_co_u32_e32 v67, vcc, 0, v151, vcc
	global_store_dwordx4 v[66:67], v[60:63], off
	global_store_dwordx4 v[64:65], v[56:59], off offset:64
	global_store_dwordx4 v[64:65], v[44:47], off offset:512
	global_store_dwordx4 v[64:65], v[40:43], off offset:576
	s_nop 1
	v_lshl_add_u64 v[40:41], v[150:151], 0, s[4:5]
	s_mov_b32 s4, 0x90000
	v_add_co_u32_e32 v42, vcc, s4, v150
	s_mov_b64 s[4:5], 0xa0000
	s_nop 0
	v_addc_co_u32_e32 v43, vcc, 0, v151, vcc
	global_store_dwordx4 v[42:43], v[52:55], off
	global_store_dwordx4 v[40:41], v[48:51], off offset:64
	global_store_dwordx4 v[40:41], v[28:31], off offset:512
	global_store_dwordx4 v[40:41], v[24:27], off offset:576
	s_nop 1
	v_lshl_add_u64 v[24:25], v[150:151], 0, s[4:5]
	s_mov_b32 s4, 0xa0000
	v_add_co_u32_e32 v26, vcc, s4, v150
	s_mov_b64 s[4:5], 0xb0000
	s_nop 0
	v_addc_co_u32_e32 v27, vcc, 0, v151, vcc
	global_store_dwordx4 v[26:27], v[36:39], off
	global_store_dwordx4 v[24:25], v[32:35], off offset:64
	global_store_dwordx4 v[24:25], v[12:15], off offset:512
	global_store_dwordx4 v[24:25], v[8:11], off offset:576
	s_nop 1
	v_add_co_u32_e32 v10, vcc, 0xb0000, v150
	v_lshl_add_u64 v[8:9], v[150:151], 0, s[4:5]
	s_nop 0
	v_addc_co_u32_e32 v11, vcc, 0, v151, vcc
	global_store_dwordx4 v[10:11], v[20:23], off
	global_store_dwordx4 v[8:9], v[16:19], off offset:64
	global_store_dwordx4 v[8:9], v[4:7], off offset:512
	global_store_dwordx4 v[8:9], v[0:3], off offset:576
	s_waitcnt vmcnt(0)
	s_cbranch_scc0 .LBB0_377
	s_barrier

; #define PG8_STAGE(bufoff, gbase, voff) do { _Pragma("unroll") for (int _i = 0; _i < 2; ++_i) \
;         __builtin_amdgcn_global_load_lds((const unsigned*)((const char*)(gbase) + (voff)[_i]), (PG8_LAS unsigned*)(lds + (bufoff) + ldsw + _i * 8192), 16, 0, 0); } while (0)
; #define PG8_LDA(dst, b, h) do { _Pragma("unroll") for (int m = 0; m < 4; ++m) _Pragma("unroll") for (int k = 0; k < 2; ++k) dst[m][k] = *(const PG8_LAS bf16x8*)(lds + PG8_SA(b, h) + aoff + m * 2048 + k * 1024); } while (0)
; #define PG8_LDB(dst, b, h) do { _Pragma("unroll") for (int n = 0; n < 2; ++n) _Pragma("unroll") for (int k = 0; k < 2; ++k) dst[n][k] = *(const PG8_LAS bf16x8*)(lds + PG8_SB(b, h) + boff + n * 2048 + k * 1024); } while (0)
; #define PG8_WAIT_L(n) asm volatile("s_waitcnt lgkmcnt(" #n ")" ::: "memory")
; #define PG8_BAR __builtin_amdgcn_s_barrier()
; #define PG8_SCHED __builtin_amdgcn_sched_barrier(0)
;     __device__ bool next(int i, pg8::Unit& u) const { if (i != 0 || !valid) return false; u.pm = pm; u.pn = pn; return true; }
; template <class Epi, class Sched, bool STAMP = false>
; __device__ __forceinline__ void gemm_phase(PG8_LAS unsigned char* lds, const Gemm g, const Sched& S, const Epi& E, unsigned long long* stamps) {
;     ...
;         const bool has_next = S.next(ui + 1, nxt);
;         const char* nA = has_next ? (const char*)g.A + (size_t)nxt.pm * tstep : cA; const char* nB = has_next ? (const char*)g.Bt + (size_t)nxt.pn * tstep : cB;
;         for (int t = 0; t < nt; t += 2) {
;             const bool last = (t == nt - 2);
;             const char* a1 = cA + (size_t)(t + 1) * kstep;
;             const char* a2 = last ? nA : cA + (size_t)(t + 2) * kstep; const char* b2 = last ? nB : cB + (size_t)(t + 2) * kstep;
;             const char* a3 = a2 + kstep; const char* b3 = b2 + kstep;
;             if (last && has_next) S.a_ready(nxt);
;             PG8_LDB(B0, 0, 0); PG8_SCHED; PG8_LDA(At, 0, 0); PG8_STAGE(PG8_SA(1, 1), a1 + hstep, voffA);
;             PG8_WAIT_L(8); PG8_BAR; PG8_WAIT_L(0); PG8_MMA(0, 0, At, B0); PG8_BAR; PG8_SCHED;
;     ...
; #pragma unroll
;         for (int a = 0; a < 2; ++a)
; #pragma unroll
;             for (int b = 0; b < 2; ++b)
; #pragma unroll
;                 for (int m = 0; m < 4; ++m)
; #pragma unroll
;                     for (int n = 0; n < 2; ++n) acc[a][b][m][n] = (f32x4){0.f, 0.f, 0.f, 0.f};
;         cur = nxt; cA = nA; cB = nB; ++ui;
.LBB0_494:
	s_ashr_i32 s7, s6, 31
	v_cmp_lt_i64_e32 vcc, s[12:13], v[142:143]
	s_lshl_b64 s[12:13], s[6:7], 19
	s_add_u32 s12, s37, s12
	s_addc_u32 s13, s40, s13
	s_and_b64 s[14:15], vcc, exec
	s_cselect_b32 s7, s13, s25
	s_cselect_b32 s57, s12, s24
	s_ashr_i32 s5, s4, 31
	s_lshl_b64 s[14:15], s[4:5], 19
	s_add_u32 s20, s41, s14
	s_addc_u32 s21, s42, s15
	s_and_b64 s[14:15], vcc, exec
	s_cselect_b32 s5, s21, s27
	s_cselect_b32 s58, s20, s26
	s_add_u32 s24, s24, 0x40080
	s_addc_u32 s25, s25, 0
	s_add_u32 s59, s26, 0x100
	v_mov_b32_e32 v0, 0
	s_addc_u32 s60, s27, 0
	s_mov_b32 s61, -2
	v_mov_b32_e32 v1, v0
	v_mov_b32_e32 v2, v0
	v_mov_b32_e32 v3, v0
	v_mov_b32_e32 v4, v0
	v_mov_b32_e32 v5, v0
	v_mov_b32_e32 v6, v0
	v_mov_b32_e32 v7, v0
	v_mov_b32_e32 v16, v0
	v_mov_b32_e32 v17, v0
	v_mov_b32_e32 v18, v0
	v_mov_b32_e32 v19, v0
	v_mov_b32_e32 v20, v0
	v_mov_b32_e32 v21, v0
	v_mov_b32_e32 v22, v0
	v_mov_b32_e32 v23, v0
	v_mov_b32_e32 v32, v0
	v_mov_b32_e32 v33, v0
	v_mov_b32_e32 v34, v0
	v_mov_b32_e32 v35, v0
	v_mov_b32_e32 v36, v0
	v_mov_b32_e32 v37, v0
	v_mov_b32_e32 v38, v0
	v_mov_b32_e32 v39, v0
	v_mov_b32_e32 v48, v0
	v_mov_b32_e32 v49, v0
	v_mov_b32_e32 v50, v0
	v_mov_b32_e32 v51, v0
	v_mov_b32_e32 v52, v0
	v_mov_b32_e32 v53, v0
	v_mov_b32_e32 v54, v0
	v_mov_b32_e32 v55, v0
	v_mov_b32_e32 v8, v0
	v_mov_b32_e32 v9, v0
	v_mov_b32_e32 v10, v0
	v_mov_b32_e32 v11, v0
	v_mov_b32_e32 v12, v0
	v_mov_b32_e32 v13, v0
	v_mov_b32_e32 v14, v0
	v_mov_b32_e32 v15, v0
	v_mov_b32_e32 v24, v0
	v_mov_b32_e32 v25, v0
	v_mov_b32_e32 v26, v0
	v_mov_b32_e32 v27, v0
	v_mov_b32_e32 v28, v0
	v_mov_b32_e32 v29, v0
	v_mov_b32_e32 v30, v0
	v_mov_b32_e32 v31, v0
	v_mov_b32_e32 v40, v0
	v_mov_b32_e32 v41, v0
	v_mov_b32_e32 v42, v0
	v_mov_b32_e32 v43, v0
	v_mov_b32_e32 v44, v0
	v_mov_b32_e32 v45, v0
	v_mov_b32_e32 v46, v0
	v_mov_b32_e32 v47, v0
	v_mov_b32_e32 v56, v0
	v_mov_b32_e32 v57, v0
	v_mov_b32_e32 v58, v0
	v_mov_b32_e32 v59, v0
	v_mov_b32_e32 v60, v0
	v_mov_b32_e32 v61, v0
	v_mov_b32_e32 v62, v0
	v_mov_b32_e32 v63, v0
	v_mov_b32_e32 v64, v0
	v_mov_b32_e32 v65, v0
	v_mov_b32_e32 v66, v0
	v_mov_b32_e32 v67, v0
	v_mov_b32_e32 v68, v0
	v_mov_b32_e32 v69, v0
	v_mov_b32_e32 v70, v0
	v_mov_b32_e32 v71, v0
	v_mov_b32_e32 v80, v0
	v_mov_b32_e32 v81, v0
	v_mov_b32_e32 v82, v0
	v_mov_b32_e32 v83, v0
	v_mov_b32_e32 v84, v0
	v_mov_b32_e32 v85, v0
	v_mov_b32_e32 v86, v0
	v_mov_b32_e32 v87, v0
	v_mov_b32_e32 v96, v0
	v_mov_b32_e32 v97, v0
	v_mov_b32_e32 v98, v0
	v_mov_b32_e32 v99, v0
	v_mov_b32_e32 v100, v0
	v_mov_b32_e32 v101, v0
	v_mov_b32_e32 v102, v0
	v_mov_b32_e32 v103, v0
	v_mov_b32_e32 v112, v0
	v_mov_b32_e32 v113, v0
	v_mov_b32_e32 v114, v0
	v_mov_b32_e32 v115, v0
	v_mov_b32_e32 v116, v0
	v_mov_b32_e32 v117, v0
	v_mov_b32_e32 v118, v0
	v_mov_b32_e32 v119, v0
	v_mov_b32_e32 v72, v0
	v_mov_b32_e32 v73, v0
	v_mov_b32_e32 v74, v0
	v_mov_b32_e32 v75, v0
	v_mov_b32_e32 v76, v0
	v_mov_b32_e32 v77, v0
	v_mov_b32_e32 v78, v0
	s_waitcnt vmcnt(0)
	v_mov_b32_e32 v79, v0
	v_mov_b32_e32 v88, v0
	v_mov_b32_e32 v89, v0
	v_mov_b32_e32 v90, v0
	v_mov_b32_e32 v91, v0
	v_mov_b32_e32 v92, v0
	v_mov_b32_e32 v93, v0
	v_mov_b32_e32 v94, v0
	v_mov_b32_e32 v95, v0
	v_mov_b32_e32 v104, v0
	v_mov_b32_e32 v105, v0
	v_mov_b32_e32 v106, v0
	v_mov_b32_e32 v107, v0
	v_mov_b32_e32 v108, v0
	v_mov_b32_e32 v109, v0
	v_mov_b32_e32 v110, v0
	v_mov_b32_e32 v111, v0
	v_mov_b32_e32 v120, v0
	v_mov_b32_e32 v121, v0
	v_mov_b32_e32 v122, v0
	v_mov_b32_e32 v123, v0
	v_mov_b32_e32 v124, v0
	v_mov_b32_e32 v125, v0
	v_mov_b32_e32 v126, v0
	v_mov_b32_e32 v127, v0
	v_add_u32_e32 v244, 0x80, v128
	v_add_u32_e32 v245, 0x80, v148
	v_add_u32_e32 v246, 0x80, v152
	v_add_u32_e32 v247, 0x80, v150
.LBB0_495:
	s_add_u32 s14, s24, 0xfffc0080
	s_addc_u32 s15, s25, -1
	s_add_i32 s16, 0, 0x10000
	v_add_u32_e32 v169, s16, v166
	ds_read_b128 v[158:161], v169
	ds_read_b128 v[162:165], v169 offset:1024
	ds_read_b128 v[170:173], v169 offset:2048
	ds_read_b128 v[174:177], v169 offset:3072
	s_cmp_eq_u32 s61, 12
	s_cselect_b32 s31, s7, s15
	s_cselect_b32 s30, s57, s14
	s_cselect_b32 s27, s5, s60
	s_cselect_b32 s26, s58, s59
	s_add_i32 m0, s23, 0xc000
	ds_read_b128 v[178:181], v168
	ds_read_b128 v[192:195], v168 offset:1024
	ds_read_b128 v[196:199], v168 offset:2048
	ds_read_b128 v[200:203], v168 offset:3072
	ds_read_b128 v[204:207], v168 offset:4096
	ds_read_b128 v[208:211], v168 offset:5120
	ds_read_b128 v[212:215], v168 offset:6144
	ds_read_b128 v[216:219], v168 offset:7168
	global_load_lds_dwordx4 v154, s[24:25]
	s_add_i32 m0, s23, 0xe000
	s_nop 0
	global_load_lds_dwordx4 v156, s[24:25]
	s_waitcnt lgkmcnt(8)
	s_barrier
	s_waitcnt lgkmcnt(0)
	v_mfma_f32_16x16x32_bf16 v[124:127], v[158:161], v[178:181], v[124:127]
	v_mfma_f32_16x16x32_bf16 v[120:123], v[170:173], v[178:181], v[120:123]
	v_mfma_f32_16x16x32_bf16 v[108:111], v[158:161], v[196:199], v[108:111]
	v_mfma_f32_16x16x32_bf16 v[104:107], v[170:173], v[196:199], v[104:107]
	v_mfma_f32_16x16x32_bf16 v[92:95], v[158:161], v[204:207], v[92:95]
	v_mfma_f32_16x16x32_bf16 v[88:91], v[170:173], v[204:207], v[88:91]
	v_mfma_f32_16x16x32_bf16 v[76:79], v[158:161], v[212:215], v[76:79]
	v_mfma_f32_16x16x32_bf16 v[72:75], v[170:173], v[212:215], v[72:75]
	v_mfma_f32_16x16x32_bf16 v[124:127], v[162:165], v[192:195], v[124:127]
	v_mfma_f32_16x16x32_bf16 v[120:123], v[174:177], v[192:195], v[120:123]
	v_mfma_f32_16x16x32_bf16 v[108:111], v[162:165], v[200:203], v[108:111]
	v_mfma_f32_16x16x32_bf16 v[104:107], v[174:177], v[200:203], v[104:107]
	v_mfma_f32_16x16x32_bf16 v[92:95], v[162:165], v[208:211], v[92:95]
	v_mfma_f32_16x16x32_bf16 v[88:91], v[174:177], v[208:211], v[88:91]
	v_mfma_f32_16x16x32_bf16 v[76:79], v[162:165], v[216:219], v[76:79]
	v_mfma_f32_16x16x32_bf16 v[72:75], v[174:177], v[216:219], v[72:75]
	s_barrier
; #define PG8_STAGE(bufoff, gbase, voff) do { _Pragma("unroll") for (int _i = 0; _i < 2; ++_i) \
;         __builtin_amdgcn_global_load_lds((const unsigned*)((const char*)(gbase) + (voff)[_i]), (PG8_LAS unsigned*)(lds + (bufoff) + ldsw + _i * 8192), 16, 0, 0); } while (0)
; #define PG8_LDA(dst, b, h) do { _Pragma("unroll") for (int m = 0; m < 4; ++m) _Pragma("unroll") for (int k = 0; k < 2; ++k) dst[m][k] = *(const PG8_LAS bf16x8*)(lds + PG8_SA(b, h) + aoff + m * 2048 + k * 1024); } while (0)
; #define PG8_LDB(dst, b, h) do { _Pragma("unroll") for (int n = 0; n < 2; ++n) _Pragma("unroll") for (int k = 0; k < 2; ++k) dst[n][k] = *(const PG8_LAS bf16x8*)(lds + PG8_SB(b, h) + boff + n * 2048 + k * 1024); } while (0)
; #define PG8_MMA(ai, bj, At, Bt) do { __builtin_amdgcn_s_setprio(1); _Pragma("unroll") for (int m = 0; m < 4; ++m) _Pragma("unroll") for (int n = 0; n < 2; ++n) _Pragma("unroll") for (int k = 0; k < 2; ++k) \
;         acc[ai][bj][m][n] = __builtin_amdgcn_mfma_f32_16x16x32_bf16(Bt[n][k], At[m][k], acc[ai][bj][m][n], 0, 0, 0); __builtin_amdgcn_s_setprio(0); } while (0)
; #define PG8_WAIT_V(n) asm volatile("s_waitcnt vmcnt(" #n ")" ::: "memory")
; #define PG8_WAIT_L(n) asm volatile("s_waitcnt lgkmcnt(" #n ")" ::: "memory")
; #define PG8_BAR __builtin_amdgcn_s_barrier()
; #define PG8_SCHED __builtin_amdgcn_sched_barrier(0)
; template <class Epi, class Sched, bool STAMP = false>
; __device__ __forceinline__ void gemm_phase(PG8_LAS unsigned char* lds, const Gemm g, const Sched& S, const Epi& E, unsigned long long* stamps) {
;     ...
;             PG8_LDB(B1, 0, 1); PG8_STAGE(PG8_SB(0, 0), b2, voffB);
;             PG8_BAR; PG8_WAIT_L(0); PG8_MMA(0, 1, At, B1); PG8_BAR;
;             PG8_LDA(At, 0, 1); PG8_STAGE(PG8_SA(0, 0), a2, voffA);
;             PG8_BAR; PG8_WAIT_L(0); PG8_MMA(1, 0, At, B0); PG8_BAR; PG8_SCHED;
;             PG8_STAGE(PG8_SB(0, 1), b2 + hstep, voffB);
;             PG8_WAIT_V(6); PG8_BAR; PG8_MMA(1, 1, At, B1); PG8_BAR;
;             PG8_LDB(B0, 1, 0); PG8_SCHED; PG8_LDA(At, 1, 0); PG8_STAGE(PG8_SA(0, 1), a2 + hstep, voffA);
;             PG8_WAIT_L(8); PG8_BAR; PG8_WAIT_L(0); PG8_MMA(0, 0, At, B0); PG8_BAR; PG8_SCHED;
	s_add_i32 s17, 0, 0x14000
	s_add_i32 s14, s16, s43
	v_add_u32_e32 v169, s17, v166
	s_mov_b32 m0, s14
	ds_read_b128 v[220:223], v169
	ds_read_b128 v[224:227], v169 offset:1024
	ds_read_b128 v[228:231], v169 offset:2048
	ds_read_b128 v[232:235], v169 offset:3072
	global_load_lds_dwordx4 v128, s[26:27]
	s_add_i32 m0, s14, 0x2000
	s_nop 0
	global_load_lds_dwordx4 v148, s[26:27]
	s_barrier
	s_waitcnt lgkmcnt(0)
	v_mfma_f32_16x16x32_bf16 v[116:119], v[220:223], v[178:181], v[116:119]
	v_mfma_f32_16x16x32_bf16 v[112:115], v[228:231], v[178:181], v[112:115]
	v_mfma_f32_16x16x32_bf16 v[100:103], v[220:223], v[196:199], v[100:103]
	v_mfma_f32_16x16x32_bf16 v[96:99], v[228:231], v[196:199], v[96:99]
	v_mfma_f32_16x16x32_bf16 v[84:87], v[220:223], v[204:207], v[84:87]
	v_mfma_f32_16x16x32_bf16 v[80:83], v[228:231], v[204:207], v[80:83]
	v_mfma_f32_16x16x32_bf16 v[68:71], v[220:223], v[212:215], v[68:71]
	v_mfma_f32_16x16x32_bf16 v[64:67], v[228:231], v[212:215], v[64:67]
	v_mfma_f32_16x16x32_bf16 v[116:119], v[224:227], v[192:195], v[116:119]
	v_mfma_f32_16x16x32_bf16 v[112:115], v[232:235], v[192:195], v[112:115]
	v_mfma_f32_16x16x32_bf16 v[100:103], v[224:227], v[200:203], v[100:103]
	v_mfma_f32_16x16x32_bf16 v[96:99], v[232:235], v[200:203], v[96:99]
	v_mfma_f32_16x16x32_bf16 v[84:87], v[224:227], v[208:211], v[84:87]
	v_mfma_f32_16x16x32_bf16 v[80:83], v[232:235], v[208:211], v[80:83]
	v_mfma_f32_16x16x32_bf16 v[68:71], v[224:227], v[216:219], v[68:71]
	v_mfma_f32_16x16x32_bf16 v[64:67], v[232:235], v[216:219], v[64:67]
	s_mov_b32 m0, s23
	s_barrier
	ds_read_b128 v[178:181], v168 offset:16384
	ds_read_b128 v[192:195], v168 offset:17408
	ds_read_b128 v[196:199], v168 offset:18432
	ds_read_b128 v[200:203], v168 offset:19456
	ds_read_b128 v[204:207], v168 offset:20480
	ds_read_b128 v[208:211], v168 offset:21504
	ds_read_b128 v[212:215], v168 offset:22528
	ds_read_b128 v[216:219], v168 offset:23552
	global_load_lds_dwordx4 v152, s[30:31]
	s_mov_b32 m0, s45
	s_nop 0
	global_load_lds_dwordx4 v150, s[30:31]
	s_barrier
	s_waitcnt lgkmcnt(0)
	v_mfma_f32_16x16x32_bf16 v[60:63], v[158:161], v[178:181], v[60:63]
	v_mfma_f32_16x16x32_bf16 v[56:59], v[170:173], v[178:181], v[56:59]
	v_mfma_f32_16x16x32_bf16 v[44:47], v[158:161], v[196:199], v[44:47]
	v_mfma_f32_16x16x32_bf16 v[40:43], v[170:173], v[196:199], v[40:43]
	v_mfma_f32_16x16x32_bf16 v[28:31], v[158:161], v[204:207], v[28:31]
	v_mfma_f32_16x16x32_bf16 v[24:27], v[170:173], v[204:207], v[24:27]
	v_mfma_f32_16x16x32_bf16 v[12:15], v[158:161], v[212:215], v[12:15]
	v_mfma_f32_16x16x32_bf16 v[8:11], v[170:173], v[212:215], v[8:11]
	v_mfma_f32_16x16x32_bf16 v[60:63], v[162:165], v[192:195], v[60:63]
	v_mfma_f32_16x16x32_bf16 v[56:59], v[174:177], v[192:195], v[56:59]
	v_mfma_f32_16x16x32_bf16 v[44:47], v[162:165], v[200:203], v[44:47]
	v_mfma_f32_16x16x32_bf16 v[40:43], v[174:177], v[200:203], v[40:43]
	v_mfma_f32_16x16x32_bf16 v[28:31], v[162:165], v[208:211], v[28:31]
	v_mfma_f32_16x16x32_bf16 v[24:27], v[174:177], v[208:211], v[24:27]
	v_mfma_f32_16x16x32_bf16 v[12:15], v[162:165], v[216:219], v[12:15]
	v_mfma_f32_16x16x32_bf16 v[8:11], v[174:177], v[216:219], v[8:11]
	s_barrier
	s_add_u32 s14, s26, 0x40000
	s_addc_u32 s15, s27, 0
	s_add_i32 s16, s17, s43
	s_mov_b32 m0, s16
	s_nop 0
	global_load_lds_dwordx4 v128, s[14:15]
	s_add_i32 m0, s16, 0x2000
	s_nop 0
	global_load_lds_dwordx4 v148, s[14:15]
	s_waitcnt vmcnt(6)
	s_barrier
	v_mfma_f32_16x16x32_bf16 v[52:55], v[220:223], v[178:181], v[52:55]
	v_mfma_f32_16x16x32_bf16 v[48:51], v[228:231], v[178:181], v[48:51]
	v_mfma_f32_16x16x32_bf16 v[36:39], v[220:223], v[196:199], v[36:39]
	v_mfma_f32_16x16x32_bf16 v[32:35], v[228:231], v[196:199], v[32:35]
	v_mfma_f32_16x16x32_bf16 v[20:23], v[220:223], v[204:207], v[20:23]
	v_mfma_f32_16x16x32_bf16 v[16:19], v[228:231], v[204:207], v[16:19]
	v_mfma_f32_16x16x32_bf16 v[4:7], v[220:223], v[212:215], v[4:7]
	v_mfma_f32_16x16x32_bf16 v[0:3], v[228:231], v[212:215], v[0:3]
	v_mfma_f32_16x16x32_bf16 v[52:55], v[224:227], v[192:195], v[52:55]
	v_mfma_f32_16x16x32_bf16 v[48:51], v[232:235], v[192:195], v[48:51]
	v_mfma_f32_16x16x32_bf16 v[36:39], v[224:227], v[200:203], v[36:39]
	v_mfma_f32_16x16x32_bf16 v[32:35], v[232:235], v[200:203], v[32:35]
	v_mfma_f32_16x16x32_bf16 v[20:23], v[224:227], v[208:211], v[20:23]
	v_mfma_f32_16x16x32_bf16 v[16:19], v[232:235], v[208:211], v[16:19]
	v_mfma_f32_16x16x32_bf16 v[4:7], v[224:227], v[216:219], v[4:7]
	v_mfma_f32_16x16x32_bf16 v[0:3], v[232:235], v[216:219], v[0:3]
	s_add_i32 s16, 0, 0x18000
	v_add_u32_e32 v169, s16, v166
	s_barrier
	ds_read_b128 v[158:161], v169
	ds_read_b128 v[162:165], v169 offset:1024
	ds_read_b128 v[170:173], v169 offset:2048
	ds_read_b128 v[174:177], v169 offset:3072
	s_add_u32 s14, s30, 0x40000
	s_addc_u32 s15, s31, 0
	s_mov_b32 m0, s46
	ds_read_b128 v[178:181], v168 offset:32768
	ds_read_b128 v[192:195], v168 offset:33792
	ds_read_b128 v[196:199], v168 offset:34816
	ds_read_b128 v[200:203], v168 offset:35840
	ds_read_b128 v[204:207], v168 offset:36864
	ds_read_b128 v[208:211], v168 offset:37888
	ds_read_b128 v[212:215], v168 offset:38912
	ds_read_b128 v[216:219], v168 offset:39936
	global_load_lds_dwordx4 v152, s[14:15]
	s_mov_b32 m0, s47
	s_nop 0
	global_load_lds_dwordx4 v150, s[14:15]
	s_waitcnt lgkmcnt(8)
	s_barrier
; #define PG8_STAGE(bufoff, gbase, voff) do { _Pragma("unroll") for (int _i = 0; _i < 2; ++_i) \
;         __builtin_amdgcn_global_load_lds((const unsigned*)((const char*)(gbase) + (voff)[_i]), (PG8_LAS unsigned*)(lds + (bufoff) + ldsw + _i * 8192), 16, 0, 0); } while (0)
; #define PG8_LDA(dst, b, h) do { _Pragma("unroll") for (int m = 0; m < 4; ++m) _Pragma("unroll") for (int k = 0; k < 2; ++k) dst[m][k] = *(const PG8_LAS bf16x8*)(lds + PG8_SA(b, h) + aoff + m * 2048 + k * 1024); } while (0)
; #define PG8_LDB(dst, b, h) do { _Pragma("unroll") for (int n = 0; n < 2; ++n) _Pragma("unroll") for (int k = 0; k < 2; ++k) dst[n][k] = *(const PG8_LAS bf16x8*)(lds + PG8_SB(b, h) + boff + n * 2048 + k * 1024); } while (0)
; #define PG8_MMA(ai, bj, At, Bt) do { __builtin_amdgcn_s_setprio(1); _Pragma("unroll") for (int m = 0; m < 4; ++m) _Pragma("unroll") for (int n = 0; n < 2; ++n) _Pragma("unroll") for (int k = 0; k < 2; ++k) \
;         acc[ai][bj][m][n] = __builtin_amdgcn_mfma_f32_16x16x32_bf16(Bt[n][k], At[m][k], acc[ai][bj][m][n], 0, 0, 0); __builtin_amdgcn_s_setprio(0); } while (0)
; #define PG8_WAIT_V(n) asm volatile("s_waitcnt vmcnt(" #n ")" ::: "memory")
; #define PG8_WAIT_L(n) asm volatile("s_waitcnt lgkmcnt(" #n ")" ::: "memory")
; #define PG8_BAR __builtin_amdgcn_s_barrier()
; #define PG8_SCHED __builtin_amdgcn_sched_barrier(0)
; template <class Epi, class Sched, bool STAMP = false>
; __device__ __forceinline__ void gemm_phase(PG8_LAS unsigned char* lds, const Gemm g, const Sched& S, const Epi& E, unsigned long long* stamps) {
;     ...
;             PG8_WAIT_L(8); PG8_BAR; PG8_WAIT_L(0); PG8_MMA(0, 0, At, B0); PG8_BAR; PG8_SCHED;
;             PG8_LDB(B1, 1, 1); PG8_STAGE(PG8_SB(1, 0), b3, voffB);
;             PG8_BAR; PG8_WAIT_L(0); PG8_MMA(0, 1, At, B1); PG8_BAR;
;             PG8_LDA(At, 1, 1); PG8_STAGE(PG8_SA(1, 0), a3, voffA);
;             PG8_BAR; PG8_WAIT_L(0); PG8_MMA(1, 0, At, B0); PG8_BAR; PG8_SCHED;
;             PG8_STAGE(PG8_SB(1, 1), b3 + hstep, voffB);
;             PG8_WAIT_V(6); PG8_BAR; PG8_MMA(1, 1, At, B1); PG8_BAR;
	s_waitcnt lgkmcnt(0)
	v_mfma_f32_16x16x32_bf16 v[124:127], v[158:161], v[178:181], v[124:127]
	v_mfma_f32_16x16x32_bf16 v[120:123], v[170:173], v[178:181], v[120:123]
	v_mfma_f32_16x16x32_bf16 v[108:111], v[158:161], v[196:199], v[108:111]
	v_mfma_f32_16x16x32_bf16 v[104:107], v[170:173], v[196:199], v[104:107]
	v_mfma_f32_16x16x32_bf16 v[92:95], v[158:161], v[204:207], v[92:95]
	v_mfma_f32_16x16x32_bf16 v[88:91], v[170:173], v[204:207], v[88:91]
	v_mfma_f32_16x16x32_bf16 v[76:79], v[158:161], v[212:215], v[76:79]
	v_mfma_f32_16x16x32_bf16 v[72:75], v[170:173], v[212:215], v[72:75]
	v_mfma_f32_16x16x32_bf16 v[124:127], v[162:165], v[192:195], v[124:127]
	v_mfma_f32_16x16x32_bf16 v[120:123], v[174:177], v[192:195], v[120:123]
	v_mfma_f32_16x16x32_bf16 v[108:111], v[162:165], v[200:203], v[108:111]
	v_mfma_f32_16x16x32_bf16 v[104:107], v[174:177], v[200:203], v[104:107]
	v_mfma_f32_16x16x32_bf16 v[92:95], v[162:165], v[208:211], v[92:95]
	v_mfma_f32_16x16x32_bf16 v[88:91], v[174:177], v[208:211], v[88:91]
	v_mfma_f32_16x16x32_bf16 v[76:79], v[162:165], v[216:219], v[76:79]
	v_mfma_f32_16x16x32_bf16 v[72:75], v[174:177], v[216:219], v[72:75]
	s_barrier
	s_add_i32 s17, 0, 0x1c000
	s_add_i32 s14, s16, s43
	v_add_u32_e32 v169, s17, v166
	s_mov_b32 m0, s14
	ds_read_b128 v[220:223], v169
	ds_read_b128 v[224:227], v169 offset:1024
	ds_read_b128 v[228:231], v169 offset:2048
	ds_read_b128 v[232:235], v169 offset:3072
	global_load_lds_dwordx4 v244, s[26:27]
	s_add_i32 m0, s14, 0x2000
	s_nop 0
	global_load_lds_dwordx4 v245, s[26:27]
	s_barrier
	s_waitcnt lgkmcnt(0)
	v_mfma_f32_16x16x32_bf16 v[116:119], v[220:223], v[178:181], v[116:119]
	v_mfma_f32_16x16x32_bf16 v[112:115], v[228:231], v[178:181], v[112:115]
	v_mfma_f32_16x16x32_bf16 v[100:103], v[220:223], v[196:199], v[100:103]
	v_mfma_f32_16x16x32_bf16 v[96:99], v[228:231], v[196:199], v[96:99]
	v_mfma_f32_16x16x32_bf16 v[84:87], v[220:223], v[204:207], v[84:87]
	v_mfma_f32_16x16x32_bf16 v[80:83], v[228:231], v[204:207], v[80:83]
	v_mfma_f32_16x16x32_bf16 v[68:71], v[220:223], v[212:215], v[68:71]
	v_mfma_f32_16x16x32_bf16 v[64:67], v[228:231], v[212:215], v[64:67]
	v_mfma_f32_16x16x32_bf16 v[116:119], v[224:227], v[192:195], v[116:119]
	v_mfma_f32_16x16x32_bf16 v[112:115], v[232:235], v[192:195], v[112:115]
	v_mfma_f32_16x16x32_bf16 v[100:103], v[224:227], v[200:203], v[100:103]
	v_mfma_f32_16x16x32_bf16 v[96:99], v[232:235], v[200:203], v[96:99]
	v_mfma_f32_16x16x32_bf16 v[84:87], v[224:227], v[208:211], v[84:87]
	v_mfma_f32_16x16x32_bf16 v[80:83], v[232:235], v[208:211], v[80:83]
	v_mfma_f32_16x16x32_bf16 v[68:71], v[224:227], v[216:219], v[68:71]
	v_mfma_f32_16x16x32_bf16 v[64:67], v[232:235], v[216:219], v[64:67]
	s_mov_b32 m0, s49
	s_barrier
	ds_read_b128 v[178:181], v168 offset:49152
	ds_read_b128 v[192:195], v168 offset:50176
	ds_read_b128 v[196:199], v168 offset:51200
	ds_read_b128 v[200:203], v168 offset:52224
	ds_read_b128 v[204:207], v168 offset:53248
	ds_read_b128 v[208:211], v168 offset:54272
	ds_read_b128 v[212:215], v168 offset:55296
	ds_read_b128 v[216:219], v168 offset:56320
	global_load_lds_dwordx4 v246, s[30:31]
	s_mov_b32 m0, s53
	s_nop 0
	global_load_lds_dwordx4 v247, s[30:31]
	s_barrier
	s_waitcnt lgkmcnt(0)
	v_mfma_f32_16x16x32_bf16 v[60:63], v[158:161], v[178:181], v[60:63]
	v_mfma_f32_16x16x32_bf16 v[56:59], v[170:173], v[178:181], v[56:59]
	v_mfma_f32_16x16x32_bf16 v[44:47], v[158:161], v[196:199], v[44:47]
	v_mfma_f32_16x16x32_bf16 v[40:43], v[170:173], v[196:199], v[40:43]
	v_mfma_f32_16x16x32_bf16 v[28:31], v[158:161], v[204:207], v[28:31]
	v_mfma_f32_16x16x32_bf16 v[24:27], v[170:173], v[204:207], v[24:27]
	v_mfma_f32_16x16x32_bf16 v[12:15], v[158:161], v[212:215], v[12:15]
	v_mfma_f32_16x16x32_bf16 v[8:11], v[170:173], v[212:215], v[8:11]
	v_mfma_f32_16x16x32_bf16 v[60:63], v[162:165], v[192:195], v[60:63]
	v_mfma_f32_16x16x32_bf16 v[56:59], v[174:177], v[192:195], v[56:59]
	v_mfma_f32_16x16x32_bf16 v[44:47], v[162:165], v[200:203], v[44:47]
	v_mfma_f32_16x16x32_bf16 v[40:43], v[174:177], v[200:203], v[40:43]
	v_mfma_f32_16x16x32_bf16 v[28:31], v[162:165], v[208:211], v[28:31]
	v_mfma_f32_16x16x32_bf16 v[24:27], v[174:177], v[208:211], v[24:27]
	v_mfma_f32_16x16x32_bf16 v[12:15], v[162:165], v[216:219], v[12:15]
	v_mfma_f32_16x16x32_bf16 v[8:11], v[174:177], v[216:219], v[8:11]
	s_barrier
	s_add_u32 s14, s26, 0x40080
	s_addc_u32 s15, s27, 0
	s_add_i32 s16, s17, s43
	s_mov_b32 m0, s16
	s_nop 0
	global_load_lds_dwordx4 v128, s[14:15]
	s_add_i32 m0, s16, 0x2000
	s_nop 0
	global_load_lds_dwordx4 v148, s[14:15]
	s_waitcnt vmcnt(6)
	s_barrier
	v_mfma_f32_16x16x32_bf16 v[52:55], v[220:223], v[178:181], v[52:55]
	v_mfma_f32_16x16x32_bf16 v[48:51], v[228:231], v[178:181], v[48:51]
	v_mfma_f32_16x16x32_bf16 v[36:39], v[220:223], v[196:199], v[36:39]
	v_mfma_f32_16x16x32_bf16 v[32:35], v[228:231], v[196:199], v[32:35]
	v_mfma_f32_16x16x32_bf16 v[20:23], v[220:223], v[204:207], v[20:23]
	v_mfma_f32_16x16x32_bf16 v[16:19], v[228:231], v[204:207], v[16:19]
	v_mfma_f32_16x16x32_bf16 v[4:7], v[220:223], v[212:215], v[4:7]
	v_mfma_f32_16x16x32_bf16 v[0:3], v[228:231], v[212:215], v[0:3]
	v_mfma_f32_16x16x32_bf16 v[52:55], v[224:227], v[192:195], v[52:55]
	v_mfma_f32_16x16x32_bf16 v[48:51], v[232:235], v[192:195], v[48:51]
	v_mfma_f32_16x16x32_bf16 v[36:39], v[224:227], v[200:203], v[36:39]
	v_mfma_f32_16x16x32_bf16 v[32:35], v[232:235], v[200:203], v[32:35]
	v_mfma_f32_16x16x32_bf16 v[20:23], v[224:227], v[208:211], v[20:23]
	v_mfma_f32_16x16x32_bf16 v[16:19], v[232:235], v[208:211], v[16:19]
	v_mfma_f32_16x16x32_bf16 v[4:7], v[224:227], v[216:219], v[4:7]
	v_mfma_f32_16x16x32_bf16 v[0:3], v[232:235], v[216:219], v[0:3]
	s_add_i32 s61, s61, 2
	s_add_u32 s24, s24, 0x100
	s_addc_u32 s25, s25, 0
	s_add_u32 s59, s59, 0x100
	s_addc_u32 s60, s60, 0
	s_cmp_gt_u32 s61, 13
	s_barrier
; __device__ __forceinline__ unsigned cvt_pk_bf16(float lo, float hi) { const f32x2_cv v = {lo, hi}; const bf16x2_cv b = __builtin_convertvector(v, bf16x2_cv); return __builtin_bit_cast(unsigned, b); }
; __device__ __forceinline__ float rstd_of(const float* rowss, int row) { return rsqrtf(rowss[row] * (1.0f / 1024.0f) + 1e-6f); }
;     __device__ __forceinline__ void operator()(const f32x4 (&acc)[2][2][4][2], const pg8::Unit& u, int wr, int wc, int fr, int fq) const {
;         const int row0 = u.pm * 256 + wr * 64 + fr, col0 = u.pn * 256 + wc * 32 + 8 * fq;
; #pragma unroll
;         for (int ai = 0; ai < 2; ++ai)
; #pragma unroll
;             for (int m = 0; m < 4; ++m) {
;                 const int row = row0 + ai * 128 + m * 16;
;                 const float s = (MODE == 2) ? 1.0f : rstd_of(rowss, row);
;                 bf16_t* rowp = O + (size_t)row * ldc + col0;
; #pragma unroll
;                 for (int bj = 0; bj < 2; ++bj) {
;                     f32x4 v0 = acc[ai][bj][m][0] * s, v1 = acc[ai][bj][m][1] * s;
;                     if (MODE == 1) {
; #pragma unroll
;                         for (int j = 0; j < 4; ++j) { const float a = fmaxf(v0[j], 0.f), b = fmaxf(v1[j], 0.f); v0[j] = a * a; v1[j] = b * b; } }
;                     u32x4 w; w.x = cvt_pk_bf16(v0[0], v0[1]); w.y = cvt_pk_bf16(v0[2], v0[3]); w.z = cvt_pk_bf16(v1[0], v1[1]); w.w = cvt_pk_bf16(v1[2], v1[3]);
;                     *(u32x4*)(rowp + bj * 128) = w; } }
	s_cbranch_scc0 .LBB0_495
	v_lshl_add_u32 v162, s22, 8, v139
	v_ashrrev_i32_e32 v163, 31, v162
	v_lshl_add_u64 v[158:159], v[162:163], 2, s[0:1]
	global_load_dword v164, v[158:159], off
	global_load_dword v193, v[158:159], off offset:64
	global_load_dword v194, v[158:159], off offset:128
	global_load_dword v195, v[158:159], off offset:192
	global_load_dword v196, v[158:159], off offset:512
	global_load_dword v197, v[158:159], off offset:576
	global_load_dword v198, v[158:159], off offset:640
	global_load_dword v199, v[158:159], off offset:704
	v_lshl_or_b32 v160, s56, 8, v167
	v_ashrrev_i32_e32 v161, 31, v160
	s_mov_b32 s5, 0x80000
	s_mov_b64 s[14:15], 0x80000
	s_mov_b32 s56, s4
	s_mov_b32 s22, s6
	s_mov_b64 s[26:27], s[20:21]
	s_mov_b64 s[24:25], s[12:13]
	s_waitcnt vmcnt(0)
	v_fmamk_f32 v164, v164, 0x3a800000, v187
	v_cmp_gt_f32_e32 vcc, s67, v164
	v_mul_f32_e32 v165, 0x4b800000, v164
	s_nop 0
	v_cndmask_b32_e32 v164, v164, v165, vcc
	v_rsq_f32_e32 v164, v164
	s_nop 0
	v_mul_f32_e32 v165, 0x45800000, v164
	v_cndmask_b32_e32 v170, v164, v165, vcc
	v_lshlrev_b64 v[164:165], 12, v[162:163]
	v_lshl_add_u64 v[172:173], s[2:3], 0, v[164:165]
	v_lshlrev_b64 v[164:165], 1, v[160:161]
	v_lshl_add_u64 v[160:161], v[172:173], 0, v[164:165]
	v_pk_mul_f32 v[126:127], v[126:127], v[170:171] op_sel_hi:[1,0]
	v_pk_mul_f32 v[124:125], v[124:125], v[170:171] op_sel_hi:[1,0]
	v_pk_mul_f32 v[172:173], v[122:123], v[170:171] op_sel_hi:[1,0]
	v_pk_mul_f32 v[122:123], v[120:121], v[170:171] op_sel_hi:[1,0]
	v_cvt_pk_bf16_f32 v120, v124, v125
	v_cvt_pk_bf16_f32 v121, v126, v127
	v_cvt_pk_bf16_f32 v122, v122, v123
	v_cvt_pk_bf16_f32 v123, v172, v173
	global_store_dwordx4 v[160:161], v[120:123], off
	v_pk_mul_f32 v[118:119], v[118:119], v[170:171] op_sel_hi:[1,0]
	v_pk_mul_f32 v[116:117], v[116:117], v[170:171] op_sel_hi:[1,0]
	v_pk_mul_f32 v[120:121], v[114:115], v[170:171] op_sel_hi:[1,0]
	v_pk_mul_f32 v[114:115], v[112:113], v[170:171] op_sel_hi:[1,0]
	v_cvt_pk_bf16_f32 v112, v116, v117
	v_cvt_pk_bf16_f32 v113, v118, v119
	v_cvt_pk_bf16_f32 v114, v114, v115
	v_cvt_pk_bf16_f32 v115, v120, v121
	global_store_dwordx4 v[160:161], v[112:115], off offset:256
	s_nop 1
	v_mov_b32_e32 v114, v193
	s_nop 0
	v_or_b32_e32 v112, 16, v162
	v_ashrrev_i32_e32 v113, 31, v112
	v_lshlrev_b64 v[112:113], 12, v[112:113]
	v_lshl_add_u64 v[112:113], s[2:3], 0, v[112:113]
	v_lshl_add_u64 v[112:113], v[112:113], 0, v[164:165]
	v_fmamk_f32 v114, v114, 0x3a800000, v187
	v_cmp_gt_f32_e32 vcc, s67, v114
	v_mul_f32_e32 v115, 0x4b800000, v114
	s_nop 0
	v_cndmask_b32_e32 v114, v114, v115, vcc
	v_rsq_f32_e32 v114, v114
	s_nop 0
	v_mul_f32_e32 v115, 0x45800000, v114
	v_cndmask_b32_e32 v114, v114, v115, vcc
	v_pk_mul_f32 v[110:111], v[110:111], v[114:115] op_sel_hi:[1,0]
	v_pk_mul_f32 v[108:109], v[108:109], v[114:115] op_sel_hi:[1,0]
	v_pk_mul_f32 v[116:117], v[106:107], v[114:115] op_sel_hi:[1,0]
	v_pk_mul_f32 v[106:107], v[104:105], v[114:115] op_sel_hi:[1,0]
	v_cvt_pk_bf16_f32 v104, v108, v109
	v_cvt_pk_bf16_f32 v105, v110, v111
	v_cvt_pk_bf16_f32 v106, v106, v107
	v_cvt_pk_bf16_f32 v107, v116, v117
	global_store_dwordx4 v[112:113], v[104:107], off
	v_pk_mul_f32 v[102:103], v[102:103], v[114:115] op_sel_hi:[1,0]
	v_pk_mul_f32 v[100:101], v[100:101], v[114:115] op_sel_hi:[1,0]
	v_pk_mul_f32 v[104:105], v[98:99], v[114:115] op_sel_hi:[1,0]
	v_pk_mul_f32 v[98:99], v[96:97], v[114:115] op_sel_hi:[1,0]
	v_cvt_pk_bf16_f32 v96, v100, v101
	v_cvt_pk_bf16_f32 v97, v102, v103
	v_cvt_pk_bf16_f32 v98, v98, v99
	v_cvt_pk_bf16_f32 v99, v104, v105
	global_store_dwordx4 v[112:113], v[96:99], off offset:256
	s_nop 1
	v_mov_b32_e32 v98, v194
	s_nop 0
	v_or_b32_e32 v96, 32, v162
	v_ashrrev_i32_e32 v97, 31, v96
	v_lshlrev_b64 v[96:97], 12, v[96:97]
	v_lshl_add_u64 v[96:97], s[2:3], 0, v[96:97]
	v_lshl_add_u64 v[96:97], v[96:97], 0, v[164:165]
	v_fmamk_f32 v98, v98, 0x3a800000, v187
	v_cmp_gt_f32_e32 vcc, s67, v98
	v_mul_f32_e32 v99, 0x4b800000, v98
	s_nop 0
	v_cndmask_b32_e32 v98, v98, v99, vcc
	v_rsq_f32_e32 v98, v98
	s_nop 0
	v_mul_f32_e32 v99, 0x45800000, v98
	v_cndmask_b32_e32 v98, v98, v99, vcc
	v_pk_mul_f32 v[94:95], v[94:95], v[98:99] op_sel_hi:[1,0]
	v_pk_mul_f32 v[92:93], v[92:93], v[98:99] op_sel_hi:[1,0]
	v_pk_mul_f32 v[100:101], v[90:91], v[98:99] op_sel_hi:[1,0]
	v_pk_mul_f32 v[90:91], v[88:89], v[98:99] op_sel_hi:[1,0]
	v_cvt_pk_bf16_f32 v88, v92, v93
	v_cvt_pk_bf16_f32 v89, v94, v95
	v_cvt_pk_bf16_f32 v90, v90, v91
	v_cvt_pk_bf16_f32 v91, v100, v101
	global_store_dwordx4 v[96:97], v[88:91], off
	v_pk_mul_f32 v[86:87], v[86:87], v[98:99] op_sel_hi:[1,0]
	v_pk_mul_f32 v[84:85], v[84:85], v[98:99] op_sel_hi:[1,0]
	v_pk_mul_f32 v[88:89], v[82:83], v[98:99] op_sel_hi:[1,0]
	v_pk_mul_f32 v[82:83], v[80:81], v[98:99] op_sel_hi:[1,0]
	v_cvt_pk_bf16_f32 v80, v84, v85
	v_cvt_pk_bf16_f32 v81, v86, v87
	v_cvt_pk_bf16_f32 v82, v82, v83
	v_cvt_pk_bf16_f32 v83, v88, v89
	global_store_dwordx4 v[96:97], v[80:83], off offset:256
	s_nop 1
	v_mov_b32_e32 v82, v195
	s_nop 0
	v_or_b32_e32 v80, 48, v162
	v_ashrrev_i32_e32 v81, 31, v80
	v_lshlrev_b64 v[80:81], 12, v[80:81]
	v_lshl_add_u64 v[80:81], s[2:3], 0, v[80:81]
	v_lshl_add_u64 v[80:81], v[80:81], 0, v[164:165]
	v_fmamk_f32 v82, v82, 0x3a800000, v187
	v_cmp_gt_f32_e32 vcc, s67, v82
	v_mul_f32_e32 v83, 0x4b800000, v82
	s_nop 0
	v_cndmask_b32_e32 v82, v82, v83, vcc
	v_rsq_f32_e32 v82, v82
	s_nop 0
	v_mul_f32_e32 v83, 0x45800000, v82
	v_cndmask_b32_e32 v82, v82, v83, vcc
	v_pk_mul_f32 v[78:79], v[78:79], v[82:83] op_sel_hi:[1,0]
	v_pk_mul_f32 v[76:77], v[76:77], v[82:83] op_sel_hi:[1,0]
	v_pk_mul_f32 v[84:85], v[74:75], v[82:83] op_sel_hi:[1,0]
; __device__ __forceinline__ unsigned cvt_pk_bf16(float lo, float hi) { const f32x2_cv v = {lo, hi}; const bf16x2_cv b = __builtin_convertvector(v, bf16x2_cv); return __builtin_bit_cast(unsigned, b); }
; #define PG8_WAIT_V(n) asm volatile("s_waitcnt vmcnt(" #n ")" ::: "memory")
; #define PG8_BAR __builtin_amdgcn_s_barrier()
; __device__ __forceinline__ float rstd_of(const float* rowss, int row) { return rsqrtf(rowss[row] * (1.0f / 1024.0f) + 1e-6f); }
; template <class Epi, class Sched, bool STAMP = false>
; __device__ __forceinline__ void gemm_phase(PG8_LAS unsigned char* lds, const Gemm g, const Sched& S, const Epi& E, unsigned long long* stamps) {
;     ...
;     PG8_WAIT_V(0);
;     if (wr == 0) PG8_BAR;
;     __device__ __forceinline__ void operator()(const f32x4 (&acc)[2][2][4][2], const pg8::Unit& u, int wr, int wc, int fr, int fq) const {
;     ...
;             for (int m = 0; m < 4; ++m) {
;                 const int row = row0 + ai * 128 + m * 16;
;                 const float s = (MODE == 2) ? 1.0f : rstd_of(rowss, row);
;                 bf16_t* rowp = O + (size_t)row * ldc + col0;
; #pragma unroll
;                 for (int bj = 0; bj < 2; ++bj) {
;                     f32x4 v0 = acc[ai][bj][m][0] * s, v1 = acc[ai][bj][m][1] * s;
;                     if (MODE == 1) {
; #pragma unroll
;                         for (int j = 0; j < 4; ++j) { const float a = fmaxf(v0[j], 0.f), b = fmaxf(v1[j], 0.f); v0[j] = a * a; v1[j] = b * b; } }
;                     u32x4 w; w.x = cvt_pk_bf16(v0[0], v0[1]); w.y = cvt_pk_bf16(v0[2], v0[3]); w.z = cvt_pk_bf16(v1[0], v1[1]); w.w = cvt_pk_bf16(v1[2], v1[3]);
;                     *(u32x4*)(rowp + bj * 128) = w; } }
	v_pk_mul_f32 v[74:75], v[72:73], v[82:83] op_sel_hi:[1,0]
	v_cvt_pk_bf16_f32 v72, v76, v77
	v_cvt_pk_bf16_f32 v73, v78, v79
	v_cvt_pk_bf16_f32 v74, v74, v75
	v_cvt_pk_bf16_f32 v75, v84, v85
	global_store_dwordx4 v[80:81], v[72:75], off
	v_pk_mul_f32 v[70:71], v[70:71], v[82:83] op_sel_hi:[1,0]
	v_pk_mul_f32 v[68:69], v[68:69], v[82:83] op_sel_hi:[1,0]
	v_pk_mul_f32 v[72:73], v[66:67], v[82:83] op_sel_hi:[1,0]
	v_pk_mul_f32 v[66:67], v[64:65], v[82:83] op_sel_hi:[1,0]
	v_cvt_pk_bf16_f32 v64, v68, v69
	v_cvt_pk_bf16_f32 v65, v70, v71
	v_cvt_pk_bf16_f32 v66, v66, v67
	v_cvt_pk_bf16_f32 v67, v72, v73
	global_store_dwordx4 v[80:81], v[64:67], off offset:256
	s_nop 1
	v_mov_b32_e32 v64, v196
	s_nop 0
	v_lshl_add_u64 v[66:67], v[160:161], 0, s[14:15]
	s_mov_b64 s[14:15], 0x90000
	v_fmamk_f32 v64, v64, 0x3a800000, v187
	v_cmp_gt_f32_e32 vcc, s67, v64
	v_mul_f32_e32 v65, 0x4b800000, v64
	s_nop 0
	v_cndmask_b32_e32 v64, v64, v65, vcc
	v_rsq_f32_e32 v64, v64
	s_nop 0
	v_mul_f32_e32 v65, 0x45800000, v64
	v_cndmask_b32_e32 v64, v64, v65, vcc
	v_pk_mul_f32 v[60:61], v[60:61], v[64:65] op_sel_hi:[1,0]
	v_pk_mul_f32 v[62:63], v[62:63], v[64:65] op_sel_hi:[1,0]
	v_pk_mul_f32 v[68:69], v[58:59], v[64:65] op_sel_hi:[1,0]
	v_pk_mul_f32 v[58:59], v[56:57], v[64:65] op_sel_hi:[1,0]
	v_cvt_pk_bf16_f32 v56, v60, v61
	v_add_co_u32_e32 v60, vcc, s5, v160
	v_cvt_pk_bf16_f32 v57, v62, v63
	v_cvt_pk_bf16_f32 v58, v58, v59
	v_cvt_pk_bf16_f32 v59, v68, v69
	v_addc_co_u32_e32 v61, vcc, 0, v161, vcc
	global_store_dwordx4 v[60:61], v[56:59], off
	v_pk_mul_f32 v[54:55], v[54:55], v[64:65] op_sel_hi:[1,0]
	v_pk_mul_f32 v[52:53], v[52:53], v[64:65] op_sel_hi:[1,0]
	v_pk_mul_f32 v[56:57], v[50:51], v[64:65] op_sel_hi:[1,0]
	v_pk_mul_f32 v[50:51], v[48:49], v[64:65] op_sel_hi:[1,0]
	v_cvt_pk_bf16_f32 v48, v52, v53
	v_cvt_pk_bf16_f32 v49, v54, v55
	v_cvt_pk_bf16_f32 v50, v50, v51
	v_cvt_pk_bf16_f32 v51, v56, v57
	global_store_dwordx4 v[66:67], v[48:51], off offset:256
	s_nop 1
	v_mov_b32_e32 v48, v197
	s_mov_b32 s5, 0x90000
	v_lshl_add_u64 v[50:51], v[160:161], 0, s[14:15]
	s_mov_b64 s[14:15], 0xa0000
	v_fmamk_f32 v48, v48, 0x3a800000, v187
	v_cmp_gt_f32_e32 vcc, s67, v48
	v_mul_f32_e32 v49, 0x4b800000, v48
	s_nop 0
	v_cndmask_b32_e32 v48, v48, v49, vcc
	v_rsq_f32_e32 v48, v48
	s_nop 0
	v_mul_f32_e32 v49, 0x45800000, v48
	v_cndmask_b32_e32 v48, v48, v49, vcc
	v_pk_mul_f32 v[44:45], v[44:45], v[48:49] op_sel_hi:[1,0]
	v_pk_mul_f32 v[46:47], v[46:47], v[48:49] op_sel_hi:[1,0]
	v_pk_mul_f32 v[52:53], v[42:43], v[48:49] op_sel_hi:[1,0]
	v_pk_mul_f32 v[42:43], v[40:41], v[48:49] op_sel_hi:[1,0]
	v_cvt_pk_bf16_f32 v40, v44, v45
	v_add_co_u32_e32 v44, vcc, s5, v160
	v_cvt_pk_bf16_f32 v41, v46, v47
	v_cvt_pk_bf16_f32 v42, v42, v43
	v_cvt_pk_bf16_f32 v43, v52, v53
	v_addc_co_u32_e32 v45, vcc, 0, v161, vcc
	global_store_dwordx4 v[44:45], v[40:43], off
	v_pk_mul_f32 v[38:39], v[38:39], v[48:49] op_sel_hi:[1,0]
	v_pk_mul_f32 v[36:37], v[36:37], v[48:49] op_sel_hi:[1,0]
	v_pk_mul_f32 v[40:41], v[34:35], v[48:49] op_sel_hi:[1,0]
	v_pk_mul_f32 v[34:35], v[32:33], v[48:49] op_sel_hi:[1,0]
	v_cvt_pk_bf16_f32 v32, v36, v37
	v_cvt_pk_bf16_f32 v33, v38, v39
	v_cvt_pk_bf16_f32 v34, v34, v35
	v_cvt_pk_bf16_f32 v35, v40, v41
	global_store_dwordx4 v[50:51], v[32:35], off offset:256
	s_nop 1
	v_mov_b32_e32 v32, v198
	s_mov_b32 s5, 0xa0000
	v_lshl_add_u64 v[34:35], v[160:161], 0, s[14:15]
	s_mov_b64 s[14:15], 0xb0000
	v_fmamk_f32 v32, v32, 0x3a800000, v187
	v_cmp_gt_f32_e32 vcc, s67, v32
	v_mul_f32_e32 v33, 0x4b800000, v32
	s_nop 0
	v_cndmask_b32_e32 v32, v32, v33, vcc
	v_rsq_f32_e32 v32, v32
	s_nop 0
	v_mul_f32_e32 v33, 0x45800000, v32
	v_cndmask_b32_e32 v32, v32, v33, vcc
	v_pk_mul_f32 v[28:29], v[28:29], v[32:33] op_sel_hi:[1,0]
	v_pk_mul_f32 v[30:31], v[30:31], v[32:33] op_sel_hi:[1,0]
	v_pk_mul_f32 v[36:37], v[26:27], v[32:33] op_sel_hi:[1,0]
	v_pk_mul_f32 v[26:27], v[24:25], v[32:33] op_sel_hi:[1,0]
	v_cvt_pk_bf16_f32 v24, v28, v29
	v_add_co_u32_e32 v28, vcc, s5, v160
	v_cvt_pk_bf16_f32 v25, v30, v31
	v_cvt_pk_bf16_f32 v26, v26, v27
	v_cvt_pk_bf16_f32 v27, v36, v37
	v_addc_co_u32_e32 v29, vcc, 0, v161, vcc
	global_store_dwordx4 v[28:29], v[24:27], off
	v_pk_mul_f32 v[22:23], v[22:23], v[32:33] op_sel_hi:[1,0]
	v_pk_mul_f32 v[20:21], v[20:21], v[32:33] op_sel_hi:[1,0]
	v_pk_mul_f32 v[24:25], v[18:19], v[32:33] op_sel_hi:[1,0]
	v_pk_mul_f32 v[18:19], v[16:17], v[32:33] op_sel_hi:[1,0]
	v_cvt_pk_bf16_f32 v16, v20, v21
	v_cvt_pk_bf16_f32 v17, v22, v23
	v_cvt_pk_bf16_f32 v18, v18, v19
	v_cvt_pk_bf16_f32 v19, v24, v25
	global_store_dwordx4 v[34:35], v[16:19], off offset:256
	s_nop 1
	v_mov_b32_e32 v16, v199
	s_mov_b32 s5, 0xb0000
	v_lshl_add_u64 v[18:19], v[160:161], 0, s[14:15]
	v_fmamk_f32 v16, v16, 0x3a800000, v187
	v_cmp_gt_f32_e32 vcc, s67, v16
	v_mul_f32_e32 v17, 0x4b800000, v16
	s_nop 0
	v_cndmask_b32_e32 v16, v16, v17, vcc
	v_rsq_f32_e32 v16, v16
	s_nop 0
	v_mul_f32_e32 v17, 0x45800000, v16
	v_cndmask_b32_e32 v16, v16, v17, vcc
	v_pk_mul_f32 v[12:13], v[12:13], v[16:17] op_sel_hi:[1,0]
	v_pk_mul_f32 v[14:15], v[14:15], v[16:17] op_sel_hi:[1,0]
	v_pk_mul_f32 v[20:21], v[10:11], v[16:17] op_sel_hi:[1,0]
	v_pk_mul_f32 v[10:11], v[8:9], v[16:17] op_sel_hi:[1,0]
	v_cvt_pk_bf16_f32 v8, v12, v13
	v_add_co_u32_e32 v12, vcc, s5, v160
	v_cvt_pk_bf16_f32 v9, v14, v15
	v_cvt_pk_bf16_f32 v10, v10, v11
	v_cvt_pk_bf16_f32 v11, v20, v21
	v_addc_co_u32_e32 v13, vcc, 0, v161, vcc
	global_store_dwordx4 v[12:13], v[8:11], off
	v_pk_mul_f32 v[6:7], v[6:7], v[16:17] op_sel_hi:[1,0]
	v_pk_mul_f32 v[4:5], v[4:5], v[16:17] op_sel_hi:[1,0]
	v_pk_mul_f32 v[8:9], v[2:3], v[16:17] op_sel_hi:[1,0]
	v_pk_mul_f32 v[2:3], v[0:1], v[16:17] op_sel_hi:[1,0]
	v_cvt_pk_bf16_f32 v0, v4, v5
	v_cvt_pk_bf16_f32 v1, v6, v7
	v_cvt_pk_bf16_f32 v2, v2, v3
	v_cvt_pk_bf16_f32 v3, v8, v9
	s_and_b64 vcc, exec, s[38:39]
	global_store_dwordx4 v[18:19], v[0:3], off offset:256
	s_cbranch_vccz .LBB0_492
	s_waitcnt vmcnt(0)
	s_cmpk_gt_u32 s36, 0xff
	s_cbranch_scc1 .LBB0_499
	s_barrier

; #define PG8_STAGE(bufoff, gbase, voff) do { _Pragma("unroll") for (int _i = 0; _i < 2; ++_i) \
;         __builtin_amdgcn_global_load_lds((const unsigned*)((const char*)(gbase) + (voff)[_i]), (PG8_LAS unsigned*)(lds + (bufoff) + ldsw + _i * 8192), 16, 0, 0); } while (0)
; #define PG8_LDA(dst, b, h) do { _Pragma("unroll") for (int m = 0; m < 4; ++m) _Pragma("unroll") for (int k = 0; k < 2; ++k) dst[m][k] = *(const PG8_LAS bf16x8*)(lds + PG8_SA(b, h) + aoff + m * 2048 + k * 1024); } while (0)
; #define PG8_LDB(dst, b, h) do { _Pragma("unroll") for (int n = 0; n < 2; ++n) _Pragma("unroll") for (int k = 0; k < 2; ++k) dst[n][k] = *(const PG8_LAS bf16x8*)(lds + PG8_SB(b, h) + boff + n * 2048 + k * 1024); } while (0)
; #define PG8_WAIT_L(n) asm volatile("s_waitcnt lgkmcnt(" #n ")" ::: "memory")
; #define PG8_BAR __builtin_amdgcn_s_barrier()
; #define PG8_SCHED __builtin_amdgcn_sched_barrier(0)
;     __device__ bool next(int i, pg8::Unit& u) const { if (i != 0 || !valid) return false; u.pm = pm; u.pn = pn; return true; }
; template <class Epi, class Sched, bool STAMP = false>
; __device__ __forceinline__ void gemm_phase(PG8_LAS unsigned char* lds, const Gemm g, const Sched& S, const Epi& E, unsigned long long* stamps) {
;     ...
;         const bool has_next = S.next(ui + 1, nxt);
;         const char* nA = has_next ? (const char*)g.A + (size_t)nxt.pm * tstep : cA; const char* nB = has_next ? (const char*)g.Bt + (size_t)nxt.pn * tstep : cB;
;         for (int t = 0; t < nt; t += 2) {
;             const bool last = (t == nt - 2);
;             const char* a1 = cA + (size_t)(t + 1) * kstep;
;             const char* a2 = last ? nA : cA + (size_t)(t + 2) * kstep; const char* b2 = last ? nB : cB + (size_t)(t + 2) * kstep;
;             const char* a3 = a2 + kstep; const char* b3 = b2 + kstep;
;             if (last && has_next) S.a_ready(nxt);
;             PG8_LDB(B0, 0, 0); PG8_SCHED; PG8_LDA(At, 0, 0); PG8_STAGE(PG8_SA(1, 1), a1 + hstep, voffA);
;             PG8_WAIT_L(8); PG8_BAR; PG8_WAIT_L(0); PG8_MMA(0, 0, At, B0); PG8_BAR; PG8_SCHED;
;     ...
; #pragma unroll
;         for (int a = 0; a < 2; ++a)
; #pragma unroll
;             for (int b = 0; b < 2; ++b)
; #pragma unroll
;                 for (int m = 0; m < 4; ++m)
; #pragma unroll
;                     for (int n = 0; n < 2; ++n) acc[a][b][m][n] = (f32x4){0.f, 0.f, 0.f, 0.f};
;         cur = nxt; cA = nA; cB = nB; ++ui;
.LBB0_1182:
	s_ashr_i32 s7, s6, 31
	v_cmp_lt_i64_e32 vcc, s[12:13], v[136:137]
	s_lshl_b64 s[12:13], s[6:7], 21
	s_add_u32 s12, s45, s12
	s_addc_u32 s13, s46, s13
	s_and_b64 s[14:15], vcc, exec
	s_cselect_b32 s7, s13, s27
	s_cselect_b32 s23, s12, s26
	s_ashr_i32 s5, s4, 31
	s_lshl_b64 s[14:15], s[4:5], 21
	s_add_u32 s20, s47, s14
	s_addc_u32 s21, s48, s15
	s_and_b64 s[14:15], vcc, exec
	s_cselect_b32 s5, s21, s31
	s_cselect_b32 s62, s20, s30
	s_add_u32 s63, s30, 0x100
	v_mov_b32_e32 v0, 0
	s_addc_u32 s64, s31, 0
	s_mov_b32 s65, -2
	s_waitcnt lgkmcnt(0)
	v_mov_b32_e32 v1, v0
	v_mov_b32_e32 v2, v0
	v_mov_b32_e32 v3, v0
	v_mov_b32_e32 v4, v0
	v_mov_b32_e32 v5, v0
	v_mov_b32_e32 v6, v0
	v_mov_b32_e32 v7, v0
	v_mov_b32_e32 v16, v0
	v_mov_b32_e32 v17, v0
	v_mov_b32_e32 v18, v0
	v_mov_b32_e32 v19, v0
	v_mov_b32_e32 v20, v0
	v_mov_b32_e32 v21, v0
	v_mov_b32_e32 v22, v0
	v_mov_b32_e32 v23, v0
	v_mov_b32_e32 v32, v0
	v_mov_b32_e32 v33, v0
	v_mov_b32_e32 v34, v0
	v_mov_b32_e32 v35, v0
	v_mov_b32_e32 v36, v0
	v_mov_b32_e32 v37, v0
	v_mov_b32_e32 v38, v0
	v_mov_b32_e32 v39, v0
	v_mov_b32_e32 v48, v0
	v_mov_b32_e32 v49, v0
	v_mov_b32_e32 v50, v0
	v_mov_b32_e32 v51, v0
	v_mov_b32_e32 v52, v0
	v_mov_b32_e32 v53, v0
	v_mov_b32_e32 v54, v0
	v_mov_b32_e32 v55, v0
	v_mov_b32_e32 v8, v0
	v_mov_b32_e32 v9, v0
	v_mov_b32_e32 v10, v0
	v_mov_b32_e32 v11, v0
	v_mov_b32_e32 v12, v0
	v_mov_b32_e32 v13, v0
	v_mov_b32_e32 v14, v0
	v_mov_b32_e32 v15, v0
	v_mov_b32_e32 v24, v0
	v_mov_b32_e32 v25, v0
	v_mov_b32_e32 v26, v0
	v_mov_b32_e32 v27, v0
	v_mov_b32_e32 v28, v0
	v_mov_b32_e32 v29, v0
	v_mov_b32_e32 v30, v0
	v_mov_b32_e32 v31, v0
	v_mov_b32_e32 v40, v0
	v_mov_b32_e32 v41, v0
	v_mov_b32_e32 v42, v0
	v_mov_b32_e32 v43, v0
	v_mov_b32_e32 v44, v0
	v_mov_b32_e32 v45, v0
	v_mov_b32_e32 v46, v0
	v_mov_b32_e32 v47, v0
	v_mov_b32_e32 v56, v0
	v_mov_b32_e32 v57, v0
	v_mov_b32_e32 v58, v0
	v_mov_b32_e32 v59, v0
	v_mov_b32_e32 v60, v0
	v_mov_b32_e32 v61, v0
	v_mov_b32_e32 v62, v0
	v_mov_b32_e32 v63, v0
	v_mov_b32_e32 v64, v0
	v_mov_b32_e32 v65, v0
	v_mov_b32_e32 v66, v0
	v_mov_b32_e32 v67, v0
	v_mov_b32_e32 v68, v0
	v_mov_b32_e32 v69, v0
	v_mov_b32_e32 v70, v0
	v_mov_b32_e32 v71, v0
	v_mov_b32_e32 v80, v0
	v_mov_b32_e32 v81, v0
	v_mov_b32_e32 v82, v0
	v_mov_b32_e32 v83, v0
	v_mov_b32_e32 v84, v0
	v_mov_b32_e32 v85, v0
	v_mov_b32_e32 v86, v0
	v_mov_b32_e32 v87, v0
	v_mov_b32_e32 v96, v0
	v_mov_b32_e32 v97, v0
	s_waitcnt vmcnt(0)
	v_mov_b32_e32 v98, v0
	v_mov_b32_e32 v99, v0
	v_mov_b32_e32 v100, v0
	v_mov_b32_e32 v101, v0
	v_mov_b32_e32 v102, v0
	v_mov_b32_e32 v103, v0
	v_mov_b32_e32 v112, v0
	v_mov_b32_e32 v113, v0
	v_mov_b32_e32 v114, v0
	v_mov_b32_e32 v115, v0
	v_mov_b32_e32 v116, v0
	v_mov_b32_e32 v117, v0
	v_mov_b32_e32 v118, v0
	v_mov_b32_e32 v119, v0
	v_mov_b32_e32 v72, v0
	v_mov_b32_e32 v73, v0
	v_mov_b32_e32 v74, v0
	v_mov_b32_e32 v75, v0
	v_mov_b32_e32 v76, v0
	v_mov_b32_e32 v77, v0
	v_mov_b32_e32 v78, v0
	v_mov_b32_e32 v79, v0
	v_mov_b32_e32 v88, v0
	v_mov_b32_e32 v89, v0
	v_mov_b32_e32 v90, v0
	v_mov_b32_e32 v91, v0
	v_mov_b32_e32 v92, v0
	v_mov_b32_e32 v93, v0
	v_mov_b32_e32 v94, v0
	v_mov_b32_e32 v95, v0
	v_mov_b32_e32 v104, v0
	v_mov_b32_e32 v105, v0
	v_mov_b32_e32 v106, v0
	v_mov_b32_e32 v107, v0
	v_mov_b32_e32 v108, v0
	v_mov_b32_e32 v109, v0
	v_mov_b32_e32 v110, v0
	v_mov_b32_e32 v111, v0
	v_mov_b32_e32 v120, v0
	v_mov_b32_e32 v121, v0
	v_mov_b32_e32 v122, v0
	v_mov_b32_e32 v123, v0
	v_mov_b32_e32 v124, v0
	v_mov_b32_e32 v125, v0
	v_mov_b32_e32 v126, v0
	v_mov_b32_e32 v127, v0
	v_add_u32_e32 v244, 0x80, v128
	v_add_u32_e32 v245, 0x80, v148
.LBB0_1183:
	s_add_u32 s30, s26, 0x100
	s_addc_u32 s31, s27, 0
	s_add_i32 s14, 0, 0x10000
	v_add_u32_e32 v161, s14, v158
	ds_read_b128 v[154:157], v161
	ds_read_b128 v[162:165], v161 offset:1024
	ds_read_b128 v[166:169], v161 offset:2048
	ds_read_b128 v[170:173], v161 offset:3072
	s_cmp_eq_u32 s65, 60
	s_cselect_b32 s37, s7, s31
	s_cselect_b32 s36, s23, s30
	s_cselect_b32 s35, s5, s64
	s_cselect_b32 s34, s62, s63
	s_add_i32 m0, s25, 0xc000
	ds_read_b128 v[174:177], v160
	ds_read_b128 v[178:181], v160 offset:1024
	ds_read_b128 v[192:195], v160 offset:2048
	ds_read_b128 v[196:199], v160 offset:3072
	ds_read_b128 v[200:203], v160 offset:4096
	ds_read_b128 v[204:207], v160 offset:5120
	ds_read_b128 v[208:211], v160 offset:6144
	ds_read_b128 v[212:215], v160 offset:7168
	global_load_lds_dwordx4 v150, s[26:27]
	s_add_i32 m0, s25, 0xe000
	s_nop 0
	global_load_lds_dwordx4 v152, s[26:27]
	s_waitcnt lgkmcnt(8)
	s_barrier
	s_waitcnt lgkmcnt(0)
	v_mfma_f32_16x16x32_bf16 v[124:127], v[154:157], v[174:177], v[124:127]
	v_mfma_f32_16x16x32_bf16 v[120:123], v[166:169], v[174:177], v[120:123]
	v_mfma_f32_16x16x32_bf16 v[108:111], v[154:157], v[192:195], v[108:111]
	v_mfma_f32_16x16x32_bf16 v[104:107], v[166:169], v[192:195], v[104:107]
	v_mfma_f32_16x16x32_bf16 v[92:95], v[154:157], v[200:203], v[92:95]
	v_mfma_f32_16x16x32_bf16 v[88:91], v[166:169], v[200:203], v[88:91]
	v_mfma_f32_16x16x32_bf16 v[76:79], v[154:157], v[208:211], v[76:79]
	v_mfma_f32_16x16x32_bf16 v[72:75], v[166:169], v[208:211], v[72:75]
	v_mfma_f32_16x16x32_bf16 v[124:127], v[162:165], v[178:181], v[124:127]
	v_mfma_f32_16x16x32_bf16 v[120:123], v[170:173], v[178:181], v[120:123]
	v_mfma_f32_16x16x32_bf16 v[108:111], v[162:165], v[196:199], v[108:111]
	v_mfma_f32_16x16x32_bf16 v[104:107], v[170:173], v[196:199], v[104:107]
	v_mfma_f32_16x16x32_bf16 v[92:95], v[162:165], v[204:207], v[92:95]
	v_mfma_f32_16x16x32_bf16 v[88:91], v[170:173], v[204:207], v[88:91]
	v_mfma_f32_16x16x32_bf16 v[76:79], v[162:165], v[212:215], v[76:79]
	v_mfma_f32_16x16x32_bf16 v[72:75], v[170:173], v[212:215], v[72:75]
	s_barrier
; #define PG8_STAGE(bufoff, gbase, voff) do { _Pragma("unroll") for (int _i = 0; _i < 2; ++_i) \
;         __builtin_amdgcn_global_load_lds((const unsigned*)((const char*)(gbase) + (voff)[_i]), (PG8_LAS unsigned*)(lds + (bufoff) + ldsw + _i * 8192), 16, 0, 0); } while (0)
; #define PG8_LDA(dst, b, h) do { _Pragma("unroll") for (int m = 0; m < 4; ++m) _Pragma("unroll") for (int k = 0; k < 2; ++k) dst[m][k] = *(const PG8_LAS bf16x8*)(lds + PG8_SA(b, h) + aoff + m * 2048 + k * 1024); } while (0)
; #define PG8_LDB(dst, b, h) do { _Pragma("unroll") for (int n = 0; n < 2; ++n) _Pragma("unroll") for (int k = 0; k < 2; ++k) dst[n][k] = *(const PG8_LAS bf16x8*)(lds + PG8_SB(b, h) + boff + n * 2048 + k * 1024); } while (0)
; #define PG8_MMA(ai, bj, At, Bt) do { __builtin_amdgcn_s_setprio(1); _Pragma("unroll") for (int m = 0; m < 4; ++m) _Pragma("unroll") for (int n = 0; n < 2; ++n) _Pragma("unroll") for (int k = 0; k < 2; ++k) \
;         acc[ai][bj][m][n] = __builtin_amdgcn_mfma_f32_16x16x32_bf16(Bt[n][k], At[m][k], acc[ai][bj][m][n], 0, 0, 0); __builtin_amdgcn_s_setprio(0); } while (0)
; #define PG8_WAIT_V(n) asm volatile("s_waitcnt vmcnt(" #n ")" ::: "memory")
; #define PG8_WAIT_L(n) asm volatile("s_waitcnt lgkmcnt(" #n ")" ::: "memory")
; #define PG8_BAR __builtin_amdgcn_s_barrier()
; #define PG8_SCHED __builtin_amdgcn_sched_barrier(0)
; template <class Epi, class Sched, bool STAMP = false>
; __device__ __forceinline__ void gemm_phase(PG8_LAS unsigned char* lds, const Gemm g, const Sched& S, const Epi& E, unsigned long long* stamps) {
;     ...
;             PG8_LDB(B1, 0, 1); PG8_STAGE(PG8_SB(0, 0), b2, voffB);
;             PG8_BAR; PG8_WAIT_L(0); PG8_MMA(0, 1, At, B1); PG8_BAR;
;             PG8_LDA(At, 0, 1); PG8_STAGE(PG8_SA(0, 0), a2, voffA);
;             PG8_BAR; PG8_WAIT_L(0); PG8_MMA(1, 0, At, B0); PG8_BAR; PG8_SCHED;
;             PG8_STAGE(PG8_SB(0, 1), b2 + hstep, voffB);
;             PG8_WAIT_V(6); PG8_BAR; PG8_MMA(1, 1, At, B1); PG8_BAR;
;             PG8_LDB(B0, 1, 0); PG8_SCHED; PG8_LDA(At, 1, 0); PG8_STAGE(PG8_SA(0, 1), a2 + hstep, voffA);
;             PG8_WAIT_L(8); PG8_BAR; PG8_WAIT_L(0); PG8_MMA(0, 0, At, B0); PG8_BAR; PG8_SCHED;
	s_add_i32 s16, 0, 0x14000
	s_add_i32 s14, s14, s49
	v_add_u32_e32 v161, s16, v158
	s_mov_b32 m0, s14
	ds_read_b128 v[216:219], v161
	ds_read_b128 v[220:223], v161 offset:1024
	ds_read_b128 v[224:227], v161 offset:2048
	ds_read_b128 v[228:231], v161 offset:3072
	global_load_lds_dwordx4 v128, s[34:35]
	s_add_i32 m0, s14, 0x2000
	s_nop 0
	global_load_lds_dwordx4 v148, s[34:35]
	s_barrier
	s_waitcnt lgkmcnt(0)
	v_mfma_f32_16x16x32_bf16 v[116:119], v[216:219], v[174:177], v[116:119]
	v_mfma_f32_16x16x32_bf16 v[112:115], v[224:227], v[174:177], v[112:115]
	v_mfma_f32_16x16x32_bf16 v[100:103], v[216:219], v[192:195], v[100:103]
	v_mfma_f32_16x16x32_bf16 v[96:99], v[224:227], v[192:195], v[96:99]
	v_mfma_f32_16x16x32_bf16 v[84:87], v[216:219], v[200:203], v[84:87]
	v_mfma_f32_16x16x32_bf16 v[80:83], v[224:227], v[200:203], v[80:83]
	v_mfma_f32_16x16x32_bf16 v[68:71], v[216:219], v[208:211], v[68:71]
	v_mfma_f32_16x16x32_bf16 v[64:67], v[224:227], v[208:211], v[64:67]
	v_mfma_f32_16x16x32_bf16 v[116:119], v[220:223], v[178:181], v[116:119]
	v_mfma_f32_16x16x32_bf16 v[112:115], v[228:231], v[178:181], v[112:115]
	v_mfma_f32_16x16x32_bf16 v[100:103], v[220:223], v[196:199], v[100:103]
	v_mfma_f32_16x16x32_bf16 v[96:99], v[228:231], v[196:199], v[96:99]
	v_mfma_f32_16x16x32_bf16 v[84:87], v[220:223], v[204:207], v[84:87]
	v_mfma_f32_16x16x32_bf16 v[80:83], v[228:231], v[204:207], v[80:83]
	v_mfma_f32_16x16x32_bf16 v[68:71], v[220:223], v[212:215], v[68:71]
	v_mfma_f32_16x16x32_bf16 v[64:67], v[228:231], v[212:215], v[64:67]
	s_mov_b32 m0, s25
	s_barrier
	ds_read_b128 v[174:177], v160 offset:16384
	ds_read_b128 v[178:181], v160 offset:17408
	ds_read_b128 v[192:195], v160 offset:18432
	ds_read_b128 v[196:199], v160 offset:19456
	ds_read_b128 v[200:203], v160 offset:20480
	ds_read_b128 v[204:207], v160 offset:21504
	ds_read_b128 v[208:211], v160 offset:22528
	ds_read_b128 v[212:215], v160 offset:23552
	global_load_lds_dwordx4 v128, s[36:37]
	s_mov_b32 m0, s53
	s_nop 0
	global_load_lds_dwordx4 v148, s[36:37]
	s_barrier
	s_waitcnt lgkmcnt(0)
	v_mfma_f32_16x16x32_bf16 v[60:63], v[154:157], v[174:177], v[60:63]
	v_mfma_f32_16x16x32_bf16 v[56:59], v[166:169], v[174:177], v[56:59]
	v_mfma_f32_16x16x32_bf16 v[44:47], v[154:157], v[192:195], v[44:47]
	v_mfma_f32_16x16x32_bf16 v[40:43], v[166:169], v[192:195], v[40:43]
	v_mfma_f32_16x16x32_bf16 v[28:31], v[154:157], v[200:203], v[28:31]
	v_mfma_f32_16x16x32_bf16 v[24:27], v[166:169], v[200:203], v[24:27]
	v_mfma_f32_16x16x32_bf16 v[12:15], v[154:157], v[208:211], v[12:15]
	v_mfma_f32_16x16x32_bf16 v[8:11], v[166:169], v[208:211], v[8:11]
	v_mfma_f32_16x16x32_bf16 v[60:63], v[162:165], v[178:181], v[60:63]
	v_mfma_f32_16x16x32_bf16 v[56:59], v[170:173], v[178:181], v[56:59]
	v_mfma_f32_16x16x32_bf16 v[44:47], v[162:165], v[196:199], v[44:47]
	v_mfma_f32_16x16x32_bf16 v[40:43], v[170:173], v[196:199], v[40:43]
	v_mfma_f32_16x16x32_bf16 v[28:31], v[162:165], v[204:207], v[28:31]
	v_mfma_f32_16x16x32_bf16 v[24:27], v[170:173], v[204:207], v[24:27]
	v_mfma_f32_16x16x32_bf16 v[12:15], v[162:165], v[212:215], v[12:15]
	v_mfma_f32_16x16x32_bf16 v[8:11], v[170:173], v[212:215], v[8:11]
	s_barrier
	s_add_u32 s14, s34, 0x100000
	s_addc_u32 s15, s35, 0
	s_add_i32 s16, s16, s49
	s_mov_b32 m0, s16
	s_nop 0
	global_load_lds_dwordx4 v128, s[14:15]
	s_add_i32 m0, s16, 0x2000
	s_nop 0
	global_load_lds_dwordx4 v148, s[14:15]
	s_waitcnt vmcnt(6)
	s_barrier
	v_mfma_f32_16x16x32_bf16 v[52:55], v[216:219], v[174:177], v[52:55]
	v_mfma_f32_16x16x32_bf16 v[48:51], v[224:227], v[174:177], v[48:51]
	v_mfma_f32_16x16x32_bf16 v[36:39], v[216:219], v[192:195], v[36:39]
	v_mfma_f32_16x16x32_bf16 v[32:35], v[224:227], v[192:195], v[32:35]
	v_mfma_f32_16x16x32_bf16 v[20:23], v[216:219], v[200:203], v[20:23]
	v_mfma_f32_16x16x32_bf16 v[16:19], v[224:227], v[200:203], v[16:19]
	v_mfma_f32_16x16x32_bf16 v[4:7], v[216:219], v[208:211], v[4:7]
	v_mfma_f32_16x16x32_bf16 v[0:3], v[224:227], v[208:211], v[0:3]
	v_mfma_f32_16x16x32_bf16 v[52:55], v[220:223], v[178:181], v[52:55]
	v_mfma_f32_16x16x32_bf16 v[48:51], v[228:231], v[178:181], v[48:51]
	v_mfma_f32_16x16x32_bf16 v[36:39], v[220:223], v[196:199], v[36:39]
	v_mfma_f32_16x16x32_bf16 v[32:35], v[228:231], v[196:199], v[32:35]
	v_mfma_f32_16x16x32_bf16 v[20:23], v[220:223], v[204:207], v[20:23]
	v_mfma_f32_16x16x32_bf16 v[16:19], v[228:231], v[204:207], v[16:19]
	v_mfma_f32_16x16x32_bf16 v[4:7], v[220:223], v[212:215], v[4:7]
	v_mfma_f32_16x16x32_bf16 v[0:3], v[228:231], v[212:215], v[0:3]
	s_add_i32 s16, 0, 0x18000
	v_add_u32_e32 v161, s16, v158
	s_barrier
	ds_read_b128 v[154:157], v161
	ds_read_b128 v[162:165], v161 offset:1024
	ds_read_b128 v[166:169], v161 offset:2048
	ds_read_b128 v[170:173], v161 offset:3072
	s_add_u32 s14, s36, 0x100000
	s_addc_u32 s15, s37, 0
	s_mov_b32 m0, s56
	ds_read_b128 v[174:177], v160 offset:32768
	ds_read_b128 v[178:181], v160 offset:33792
	ds_read_b128 v[192:195], v160 offset:34816
	ds_read_b128 v[196:199], v160 offset:35840
	ds_read_b128 v[200:203], v160 offset:36864
	ds_read_b128 v[204:207], v160 offset:37888
	ds_read_b128 v[208:211], v160 offset:38912
	ds_read_b128 v[212:215], v160 offset:39936
	global_load_lds_dwordx4 v128, s[14:15]
	s_mov_b32 m0, s57
	s_nop 0
	global_load_lds_dwordx4 v148, s[14:15]
	s_waitcnt lgkmcnt(8)
	s_barrier
; #define PG8_STAGE(bufoff, gbase, voff) do { _Pragma("unroll") for (int _i = 0; _i < 2; ++_i) \
;         __builtin_amdgcn_global_load_lds((const unsigned*)((const char*)(gbase) + (voff)[_i]), (PG8_LAS unsigned*)(lds + (bufoff) + ldsw + _i * 8192), 16, 0, 0); } while (0)
; #define PG8_LDA(dst, b, h) do { _Pragma("unroll") for (int m = 0; m < 4; ++m) _Pragma("unroll") for (int k = 0; k < 2; ++k) dst[m][k] = *(const PG8_LAS bf16x8*)(lds + PG8_SA(b, h) + aoff + m * 2048 + k * 1024); } while (0)
; #define PG8_LDB(dst, b, h) do { _Pragma("unroll") for (int n = 0; n < 2; ++n) _Pragma("unroll") for (int k = 0; k < 2; ++k) dst[n][k] = *(const PG8_LAS bf16x8*)(lds + PG8_SB(b, h) + boff + n * 2048 + k * 1024); } while (0)
; #define PG8_MMA(ai, bj, At, Bt) do { __builtin_amdgcn_s_setprio(1); _Pragma("unroll") for (int m = 0; m < 4; ++m) _Pragma("unroll") for (int n = 0; n < 2; ++n) _Pragma("unroll") for (int k = 0; k < 2; ++k) \
;         acc[ai][bj][m][n] = __builtin_amdgcn_mfma_f32_16x16x32_bf16(Bt[n][k], At[m][k], acc[ai][bj][m][n], 0, 0, 0); __builtin_amdgcn_s_setprio(0); } while (0)
; #define PG8_WAIT_V(n) asm volatile("s_waitcnt vmcnt(" #n ")" ::: "memory")
; #define PG8_WAIT_L(n) asm volatile("s_waitcnt lgkmcnt(" #n ")" ::: "memory")
; #define PG8_BAR __builtin_amdgcn_s_barrier()
; #define PG8_SCHED __builtin_amdgcn_sched_barrier(0)
; template <class Epi, class Sched, bool STAMP = false>
; __device__ __forceinline__ void gemm_phase(PG8_LAS unsigned char* lds, const Gemm g, const Sched& S, const Epi& E, unsigned long long* stamps) {
;     ...
;             PG8_WAIT_L(8); PG8_BAR; PG8_WAIT_L(0); PG8_MMA(0, 0, At, B0); PG8_BAR; PG8_SCHED;
;             PG8_LDB(B1, 1, 1); PG8_STAGE(PG8_SB(1, 0), b3, voffB);
;             PG8_BAR; PG8_WAIT_L(0); PG8_MMA(0, 1, At, B1); PG8_BAR;
;             PG8_LDA(At, 1, 1); PG8_STAGE(PG8_SA(1, 0), a3, voffA);
;             PG8_BAR; PG8_WAIT_L(0); PG8_MMA(1, 0, At, B0); PG8_BAR; PG8_SCHED;
;             PG8_STAGE(PG8_SB(1, 1), b3 + hstep, voffB);
;             PG8_WAIT_V(6); PG8_BAR; PG8_MMA(1, 1, At, B1); PG8_BAR;
	s_waitcnt lgkmcnt(0)
	v_mfma_f32_16x16x32_bf16 v[124:127], v[154:157], v[174:177], v[124:127]
	v_mfma_f32_16x16x32_bf16 v[120:123], v[166:169], v[174:177], v[120:123]
	v_mfma_f32_16x16x32_bf16 v[108:111], v[154:157], v[192:195], v[108:111]
	v_mfma_f32_16x16x32_bf16 v[104:107], v[166:169], v[192:195], v[104:107]
	v_mfma_f32_16x16x32_bf16 v[92:95], v[154:157], v[200:203], v[92:95]
	v_mfma_f32_16x16x32_bf16 v[88:91], v[166:169], v[200:203], v[88:91]
	v_mfma_f32_16x16x32_bf16 v[76:79], v[154:157], v[208:211], v[76:79]
	v_mfma_f32_16x16x32_bf16 v[72:75], v[166:169], v[208:211], v[72:75]
	v_mfma_f32_16x16x32_bf16 v[124:127], v[162:165], v[178:181], v[124:127]
	v_mfma_f32_16x16x32_bf16 v[120:123], v[170:173], v[178:181], v[120:123]
	v_mfma_f32_16x16x32_bf16 v[108:111], v[162:165], v[196:199], v[108:111]
	v_mfma_f32_16x16x32_bf16 v[104:107], v[170:173], v[196:199], v[104:107]
	v_mfma_f32_16x16x32_bf16 v[92:95], v[162:165], v[204:207], v[92:95]
	v_mfma_f32_16x16x32_bf16 v[88:91], v[170:173], v[204:207], v[88:91]
	v_mfma_f32_16x16x32_bf16 v[76:79], v[162:165], v[212:215], v[76:79]
	v_mfma_f32_16x16x32_bf16 v[72:75], v[170:173], v[212:215], v[72:75]
	s_barrier
	s_add_i32 s17, 0, 0x1c000
	s_add_i32 s14, s16, s49
	v_add_u32_e32 v161, s17, v158
	s_mov_b32 m0, s14
	ds_read_b128 v[216:219], v161
	ds_read_b128 v[220:223], v161 offset:1024
	ds_read_b128 v[224:227], v161 offset:2048
	ds_read_b128 v[228:231], v161 offset:3072
	global_load_lds_dwordx4 v244, s[34:35]
	s_add_i32 m0, s14, 0x2000
	s_nop 0
	global_load_lds_dwordx4 v245, s[34:35]
	s_barrier
	s_waitcnt lgkmcnt(0)
	v_mfma_f32_16x16x32_bf16 v[116:119], v[216:219], v[174:177], v[116:119]
	v_mfma_f32_16x16x32_bf16 v[112:115], v[224:227], v[174:177], v[112:115]
	v_mfma_f32_16x16x32_bf16 v[100:103], v[216:219], v[192:195], v[100:103]
	v_mfma_f32_16x16x32_bf16 v[96:99], v[224:227], v[192:195], v[96:99]
	v_mfma_f32_16x16x32_bf16 v[84:87], v[216:219], v[200:203], v[84:87]
	v_mfma_f32_16x16x32_bf16 v[80:83], v[224:227], v[200:203], v[80:83]
	v_mfma_f32_16x16x32_bf16 v[68:71], v[216:219], v[208:211], v[68:71]
	v_mfma_f32_16x16x32_bf16 v[64:67], v[224:227], v[208:211], v[64:67]
	v_mfma_f32_16x16x32_bf16 v[116:119], v[220:223], v[178:181], v[116:119]
	v_mfma_f32_16x16x32_bf16 v[112:115], v[228:231], v[178:181], v[112:115]
	v_mfma_f32_16x16x32_bf16 v[100:103], v[220:223], v[196:199], v[100:103]
	v_mfma_f32_16x16x32_bf16 v[96:99], v[228:231], v[196:199], v[96:99]
	v_mfma_f32_16x16x32_bf16 v[84:87], v[220:223], v[204:207], v[84:87]
	v_mfma_f32_16x16x32_bf16 v[80:83], v[228:231], v[204:207], v[80:83]
	v_mfma_f32_16x16x32_bf16 v[68:71], v[220:223], v[212:215], v[68:71]
	v_mfma_f32_16x16x32_bf16 v[64:67], v[228:231], v[212:215], v[64:67]
	s_mov_b32 m0, s59
	s_barrier
	ds_read_b128 v[174:177], v160 offset:49152
	ds_read_b128 v[178:181], v160 offset:50176
	ds_read_b128 v[192:195], v160 offset:51200
	ds_read_b128 v[196:199], v160 offset:52224
	ds_read_b128 v[200:203], v160 offset:53248
	ds_read_b128 v[204:207], v160 offset:54272
	ds_read_b128 v[208:211], v160 offset:55296
	ds_read_b128 v[212:215], v160 offset:56320
	global_load_lds_dwordx4 v244, s[36:37]
	s_mov_b32 m0, s60
	s_nop 0
	global_load_lds_dwordx4 v245, s[36:37]
	s_barrier
	s_waitcnt lgkmcnt(0)
	v_mfma_f32_16x16x32_bf16 v[60:63], v[154:157], v[174:177], v[60:63]
	v_mfma_f32_16x16x32_bf16 v[56:59], v[166:169], v[174:177], v[56:59]
	v_mfma_f32_16x16x32_bf16 v[44:47], v[154:157], v[192:195], v[44:47]
	v_mfma_f32_16x16x32_bf16 v[40:43], v[166:169], v[192:195], v[40:43]
	v_mfma_f32_16x16x32_bf16 v[28:31], v[154:157], v[200:203], v[28:31]
	v_mfma_f32_16x16x32_bf16 v[24:27], v[166:169], v[200:203], v[24:27]
	v_mfma_f32_16x16x32_bf16 v[12:15], v[154:157], v[208:211], v[12:15]
	v_mfma_f32_16x16x32_bf16 v[8:11], v[166:169], v[208:211], v[8:11]
	v_mfma_f32_16x16x32_bf16 v[60:63], v[162:165], v[178:181], v[60:63]
	v_mfma_f32_16x16x32_bf16 v[56:59], v[170:173], v[178:181], v[56:59]
	v_mfma_f32_16x16x32_bf16 v[44:47], v[162:165], v[196:199], v[44:47]
	v_mfma_f32_16x16x32_bf16 v[40:43], v[170:173], v[196:199], v[40:43]
	v_mfma_f32_16x16x32_bf16 v[28:31], v[162:165], v[204:207], v[28:31]
	v_mfma_f32_16x16x32_bf16 v[24:27], v[170:173], v[204:207], v[24:27]
	v_mfma_f32_16x16x32_bf16 v[12:15], v[162:165], v[212:215], v[12:15]
	v_mfma_f32_16x16x32_bf16 v[8:11], v[170:173], v[212:215], v[8:11]
	s_barrier
	s_add_u32 s14, s34, 0x100080
	s_addc_u32 s15, s35, 0
	s_add_i32 s16, s17, s49
	s_mov_b32 m0, s16
	s_nop 0
	global_load_lds_dwordx4 v128, s[14:15]
	s_add_i32 m0, s16, 0x2000
	s_nop 0
	global_load_lds_dwordx4 v148, s[14:15]
	s_waitcnt vmcnt(6)
	s_barrier
; __device__ __forceinline__ unsigned cvt_pk_bf16(float lo, float hi) { const f32x2_cv v = {lo, hi}; const bf16x2_cv b = __builtin_convertvector(v, bf16x2_cv); return __builtin_bit_cast(unsigned, b); }
; #define PG8_MMA(ai, bj, At, Bt) do { __builtin_amdgcn_s_setprio(1); _Pragma("unroll") for (int m = 0; m < 4; ++m) _Pragma("unroll") for (int n = 0; n < 2; ++n) _Pragma("unroll") for (int k = 0; k < 2; ++k) \
;         acc[ai][bj][m][n] = __builtin_amdgcn_mfma_f32_16x16x32_bf16(Bt[n][k], At[m][k], acc[ai][bj][m][n], 0, 0, 0); __builtin_amdgcn_s_setprio(0); } while (0)
; #define PG8_WAIT_V(n) asm volatile("s_waitcnt vmcnt(" #n ")" ::: "memory")
; #define PG8_BAR __builtin_amdgcn_s_barrier()
; template <class Epi, class Sched, bool STAMP = false>
; __device__ __forceinline__ void gemm_phase(PG8_LAS unsigned char* lds, const Gemm g, const Sched& S, const Epi& E, unsigned long long* stamps) {
;     ...
;             PG8_WAIT_V(6); PG8_BAR; PG8_MMA(1, 1, At, B1); PG8_BAR;
;         }
;     __device__ __forceinline__ void operator()(const f32x4 (&acc)[2][2][4][2], const pg8::Unit& u, int wr, int wc, int fr, int fq) const {
;         const int row0 = u.pm * 256 + wr * 64 + fr, col0 = u.pn * 256 + wc * 32 + 4 * fq;
; #pragma unroll
;         for (int ai = 0; ai < 2; ++ai)
; #pragma unroll
;             for (int m = 0; m < 4; ++m) {
;                 const int row = row0 + ai * 128 + m * 16;
;                 float* xp = X + (size_t)row * 1024 + col0; bf16_t* bp = XB + (size_t)row * 1024 + col0;
;                 const float* xi = Xp0 ? (row < T_P ? Xp0 + (size_t)row * 1024 + col0 : Xs0 + (size_t)(row - T_P) * 1024 + col0) : xp;
;                 float ss = 0.f;
; #pragma unroll
;                 for (int bj = 0; bj < 2; ++bj)
; #pragma unroll
;                     for (int n = 0; n < 2; ++n) {
;                         f32x4 xv = *(const f32x4*)(xi + bj * 128 + n * 16) + acc[ai][bj][m][n];
;                         *(f32x4*)(xp + bj * 128 + n * 16) = xv;
;                         ss += (xv[0] * xv[0] + xv[1] * xv[1]) + (xv[2] * xv[2] + xv[3] * xv[3]);
;                         u32x2 w; w.x = cvt_pk_bf16(xv[0], xv[1]); w.y = cvt_pk_bf16(xv[2], xv[3]);
;                         *(u32x2*)(bp + bj * 128 + n * 16) = w; }
;                 ss += __shfl_xor(ss, 16); ss += __shfl_xor(ss, 32);
;                 if (fq == 0) atomicAdd(rowss_out + row, ss); }
	v_mfma_f32_16x16x32_bf16 v[52:55], v[216:219], v[174:177], v[52:55]
	v_mfma_f32_16x16x32_bf16 v[48:51], v[224:227], v[174:177], v[48:51]
	v_mfma_f32_16x16x32_bf16 v[36:39], v[216:219], v[192:195], v[36:39]
	v_mfma_f32_16x16x32_bf16 v[32:35], v[224:227], v[192:195], v[32:35]
	v_mfma_f32_16x16x32_bf16 v[20:23], v[216:219], v[200:203], v[20:23]
	v_mfma_f32_16x16x32_bf16 v[16:19], v[224:227], v[200:203], v[16:19]
	v_mfma_f32_16x16x32_bf16 v[4:7], v[216:219], v[208:211], v[4:7]
	v_mfma_f32_16x16x32_bf16 v[0:3], v[224:227], v[208:211], v[0:3]
	v_mfma_f32_16x16x32_bf16 v[52:55], v[220:223], v[178:181], v[52:55]
	v_mfma_f32_16x16x32_bf16 v[48:51], v[228:231], v[178:181], v[48:51]
	v_mfma_f32_16x16x32_bf16 v[36:39], v[220:223], v[196:199], v[36:39]
	v_mfma_f32_16x16x32_bf16 v[32:35], v[228:231], v[196:199], v[32:35]
	v_mfma_f32_16x16x32_bf16 v[20:23], v[220:223], v[204:207], v[20:23]
	v_mfma_f32_16x16x32_bf16 v[16:19], v[228:231], v[204:207], v[16:19]
	v_mfma_f32_16x16x32_bf16 v[4:7], v[220:223], v[212:215], v[4:7]
	v_mfma_f32_16x16x32_bf16 v[0:3], v[228:231], v[212:215], v[0:3]
	s_add_i32 s65, s65, 2
	s_add_u32 s63, s63, 0x100
	s_addc_u32 s64, s64, 0
	s_cmp_gt_u32 s65, 61
	s_mov_b64 s[26:27], s[30:31]
	s_barrier
	s_cbranch_scc0 .LBB0_1183
	v_lshl_add_u32 v156, s22, 8, v139
	v_ashrrev_i32_e32 v157, 31, v156
	v_lshl_or_b32 v154, s24, 8, v159
	v_lshlrev_b64 v[162:163], 12, v[156:157]
	v_ashrrev_i32_e32 v155, 31, v154
	v_lshl_add_u64 v[162:163], s[84:85], 0, v[162:163]
	v_lshl_add_u64 v[170:171], v[154:155], 2, v[162:163]
	global_load_dwordx4 v[192:195], v[170:171], off
	global_load_dwordx4 v[196:199], v[170:171], off offset:64
	global_load_dwordx4 v[200:203], v[170:171], off offset:512
	global_load_dwordx4 v[204:207], v[170:171], off offset:576
	v_add_co_u32_e32 v224, vcc, 0x10000, v170
	s_nop 1
	v_addc_co_u32_e32 v225, vcc, 0, v171, vcc
	global_load_dwordx4 v[208:211], v[224:225], off
	global_load_dwordx4 v[212:215], v[224:225], off offset:64
	global_load_dwordx4 v[216:219], v[224:225], off offset:512
	global_load_dwordx4 v[220:223], v[224:225], off offset:576
	v_lshlrev_b64 v[166:167], 11, v[156:157]
	v_lshl_add_u64 v[166:167], s[0:1], 0, v[166:167]
	v_lshl_add_u64 v[172:173], v[154:155], 1, v[166:167]
	v_xor_b32_e32 v161, 32, v189
	s_waitcnt vmcnt(4)
	v_mov_b32_e32 v162, v192
	v_mov_b32_e32 v163, v193
	v_mov_b32_e32 v164, v194
	v_mov_b32_e32 v165, v195
	v_pk_add_f32 v[126:127], v[126:127], v[164:165]
	v_pk_add_f32 v[124:125], v[124:125], v[162:163]
	v_cvt_pk_bf16_f32 v163, v126, v127
	v_cvt_pk_bf16_f32 v162, v124, v125
	global_store_dwordx4 v[170:171], v[124:127], off
	global_store_dwordx2 v[172:173], v[162:163], off
	s_nop 1
	v_mov_b32_e32 v162, v196
	v_mov_b32_e32 v163, v197
	v_mov_b32_e32 v164, v198
	v_mov_b32_e32 v165, v199
	v_pk_add_f32 v[122:123], v[122:123], v[164:165]
	v_pk_add_f32 v[120:121], v[120:121], v[162:163]
	v_cvt_pk_bf16_f32 v163, v122, v123
	v_cvt_pk_bf16_f32 v162, v120, v121
	global_store_dwordx4 v[170:171], v[120:123], off offset:64
	global_store_dwordx2 v[172:173], v[162:163], off offset:32
	s_nop 1
	v_mov_b32_e32 v162, v200
	v_mov_b32_e32 v163, v201
	v_mov_b32_e32 v164, v202
	v_mov_b32_e32 v165, v203
	v_pk_add_f32 v[164:165], v[118:119], v[164:165]
	v_pk_add_f32 v[162:163], v[116:117], v[162:163]
	v_cvt_pk_bf16_f32 v117, v164, v165
	v_cvt_pk_bf16_f32 v116, v162, v163
	global_store_dwordx4 v[170:171], v[162:165], off offset:512
	global_store_dwordx2 v[172:173], v[116:117], off offset:256
	s_nop 1
	v_mov_b32_e32 v166, v204
	v_mov_b32_e32 v167, v205
	v_mov_b32_e32 v168, v206
	v_mov_b32_e32 v169, v207
	v_mul_f32_e32 v118, v125, v125
	v_mul_f32_e32 v119, v127, v127
	v_fmac_f32_e32 v118, v124, v124
	v_fmac_f32_e32 v119, v126, v126
	v_add_f32_e32 v118, v118, v119
	v_mul_f32_e32 v119, v121, v121
	v_mul_f32_e32 v121, v123, v123
	v_fmac_f32_e32 v119, v120, v120
	v_fmac_f32_e32 v121, v122, v122
	v_add_f32_e32 v119, v119, v121
	v_add_f32_e32 v118, v118, v119
	v_mul_f32_e32 v119, v163, v163
	v_mul_f32_e32 v120, v165, v165
	v_fmac_f32_e32 v119, v162, v162
	v_fmac_f32_e32 v120, v164, v164
	v_add_f32_e32 v119, v119, v120
	v_and_b32_e32 v117, 64, v189
	v_add_f32_e32 v122, v118, v119
	v_xor_b32_e32 v116, 16, v189
	v_add_u32_e32 v117, 64, v117
	v_cmp_lt_i32_e32 vcc, v116, v117
	v_pk_add_f32 v[120:121], v[114:115], v[168:169]
	v_pk_add_f32 v[118:119], v[112:113], v[166:167]
	v_mul_f32_e32 v113, v121, v121
	v_mul_f32_e32 v112, v119, v119
	v_fmac_f32_e32 v112, v118, v118
	v_fmac_f32_e32 v113, v120, v120
	v_cndmask_b32_e32 v116, v189, v116, vcc
	v_add_f32_e32 v112, v112, v113
	v_lshlrev_b32_e32 v116, 2, v116
	v_add_f32_e32 v112, v122, v112
	ds_bpermute_b32 v113, v116, v112
	v_cmp_lt_i32_e32 vcc, v161, v117
	global_store_dwordx4 v[170:171], v[118:121], off offset:576
	s_waitcnt lgkmcnt(0)
	v_add_f32_e32 v115, v112, v113
	v_cndmask_b32_e32 v114, v189, v161, vcc
	v_lshlrev_b32_e32 v114, 2, v114
	ds_bpermute_b32 v117, v114, v115
	v_cvt_pk_bf16_f32 v112, v118, v119
	v_cvt_pk_bf16_f32 v113, v120, v121
	global_store_dwordx2 v[172:173], v[112:113], off offset:288
	v_lshl_add_u64 v[112:113], v[156:157], 2, s[2:3]
	s_and_saveexec_b64 s[22:23], s[38:39]
	s_cbranch_execz .LBB0_1186
	s_waitcnt lgkmcnt(0)
	v_add_f32_e32 v115, v115, v117
	global_atomic_add_f32 v[112:113], v115, off

; #define PG8_STAGE(bufoff, gbase, voff) do { _Pragma("unroll") for (int _i = 0; _i < 2; ++_i) \
;         __builtin_amdgcn_global_load_lds((const unsigned*)((const char*)(gbase) + (voff)[_i]), (PG8_LAS unsigned*)(lds + (bufoff) + ldsw + _i * 8192), 16, 0, 0); } while (0)
; #define PG8_WAIT_V(n) asm volatile("s_waitcnt vmcnt(" #n ")" ::: "memory")
; #define PG8_BAR __builtin_amdgcn_s_barrier()
; template <class Epi, class Sched, bool STAMP = false>
; __device__ __forceinline__ void gemm_phase(PG8_LAS unsigned char* lds, const Gemm g, const Sched& S, const Epi& E, unsigned long long* stamps) {
;     ...
;     f32x4 acc[2][2][4][2];
; #pragma unroll
;     for (int a = 0; a < 2; ++a)
; #pragma unroll
;         for (int b = 0; b < 2; ++b)
; #pragma unroll
;             for (int m = 0; m < 4; ++m)
; #pragma unroll
;                 for (int n = 0; n < 2; ++n) acc[a][b][m][n] = (f32x4){0.f, 0.f, 0.f, 0.f};
;     bf16x8 At[4][2], B0[2][2], B1[2][2];
;     const char* cA = (const char*)g.A + (size_t)cur.pm * tstep; const char* cB = (const char*)g.Bt + (size_t)cur.pn * tstep;
;     S.a_ready(cur);
;     PG8_STAGE(PG8_SB(0, 0), cB, voffB); PG8_STAGE(PG8_SA(0, 0), cA, voffA); PG8_STAGE(PG8_SB(0, 1), cB + hstep, voffB); PG8_STAGE(PG8_SA(0, 1), cA + hstep, voffA);
;     if (wr == 1) PG8_BAR;
;     PG8_WAIT_V(4); PG8_BAR;
;     PG8_STAGE(PG8_SB(1, 0), cB + kstep, voffB); PG8_STAGE(PG8_SA(1, 0), cA + kstep, voffA); PG8_STAGE(PG8_SB(1, 1), cB + hstep + kstep, voffB);
;     PG8_WAIT_V(6); PG8_BAR;
.LBB0_1206:
	v_bfe_u32 v139, v12, 4, 2
	s_lshl_b32 s6, s6, 5
	v_and_b32_e32 v154, 15, v12
	v_lshlrev_b32_e32 v17, 4, v139
	v_lshlrev_b32_e32 v12, 2, v12
	s_and_b32 s36, s6, 0x60
	s_add_i32 m0, s27, 0x18000
	v_lshl_add_u64 v[6:7], v[6:7], 0, s[18:19]
	s_lshl_b32 s35, s7, 6
	v_lshl_or_b32 v17, v154, 6, v17
	s_lshl_b32 s7, s7, 13
	v_and_b32_e32 v12, 32, v12
	s_lshl_b32 s6, s36, 7
	s_waitcnt vmcnt(4)
	s_barrier
	global_load_lds_dwordx4 v[6:7], off
	v_lshl_add_u64 v[4:5], v[4:5], 0, s[18:19]
	s_add_i32 m0, s27, 0x1a000
	s_add_i32 s37, s27, 0x8000
	s_add_i32 s38, s27, 0xa000
	v_bitop3_b32 v155, v17, s6, v12 bitop3:0xde
	global_load_lds_dwordx4 v[4:5], off
	v_lshl_add_u64 v[2:3], v[2:3], 0, s[18:19]
	s_mov_b32 m0, s37
	s_add_u32 s6, s0, 0x100080
	v_bitop3_b32 v18, v17, s7, v12 bitop3:0xde
	global_load_lds_dwordx4 v[2:3], off
	v_lshl_add_u64 v[0:1], v[0:1], 0, s[18:19]
	s_mov_b32 m0, s38
	s_addc_u32 s7, s1, 0
	global_load_lds_dwordx4 v[0:1], off
	s_add_i32 m0, s27, 0x1c000
	v_lshl_add_u64 v[0:1], s[6:7], 0, v[128:129]
	global_load_lds_dwordx4 v[0:1], off
	v_lshl_add_u64 v[0:1], s[6:7], 0, v[148:149]
	s_add_i32 m0, s27, 0x1e000
	s_lshl_b32 s4, s4, 16
	global_load_lds_dwordx4 v[0:1], off
	s_and_b32 s4, s4, 0x600000
	s_or_b32 s4, s4, s5
	v_lshlrev_b32_e32 v0, 15, v14
	v_and_b32_e32 v0, 0x7fff0000, v0
	s_add_u32 s4, s10, s4
	v_lshl_add_u32 v0, v13, 12, v0
	s_addc_u32 s5, s42, 0
	v_or_b32_e32 v0, v0, v15
	s_add_u32 s4, s4, 0xd600080
	v_add_lshl_u32 v0, v0, v16, 1
	v_mov_b32_e32 v1, v129
	s_addc_u32 s5, s5, 0
	v_lshl_add_u64 v[150:151], s[4:5], 0, v[0:1]
	v_lshlrev_b32_e32 v0, 15, v8
	v_and_b32_e32 v0, 0x7fff0000, v0
	v_lshl_add_u32 v0, v9, 12, v0
	v_or_b32_e32 v0, v0, v10
	s_waitcnt vmcnt(6)
	v_add_lshl_u32 v0, v0, v11, 1
	v_lshl_add_u64 v[152:153], s[4:5], 0, v[0:1]
	v_mov_b32_e32 v0, 0
	s_mov_b32 s39, -2
	s_mov_b64 s[4:5], 0
	v_add_u32_e32 v156, 0, v18
	v_mov_b32_e32 v1, v0
	v_mov_b32_e32 v2, v0
	v_mov_b32_e32 v3, v0
	v_mov_b32_e32 v4, v0
	v_mov_b32_e32 v5, v0
	v_mov_b32_e32 v6, v0
	v_mov_b32_e32 v7, v0
	v_mov_b32_e32 v8, v0
	v_mov_b32_e32 v9, v0
	v_mov_b32_e32 v10, v0
	v_mov_b32_e32 v11, v0
	v_mov_b32_e32 v12, v0
	v_mov_b32_e32 v13, v0
	v_mov_b32_e32 v14, v0
	v_mov_b32_e32 v15, v0
	v_mov_b32_e32 v24, v0
	v_mov_b32_e32 v25, v0
	v_mov_b32_e32 v26, v0
	v_mov_b32_e32 v27, v0
	v_mov_b32_e32 v28, v0
	v_mov_b32_e32 v29, v0
	v_mov_b32_e32 v30, v0
	v_mov_b32_e32 v31, v0
	v_mov_b32_e32 v40, v0
	v_mov_b32_e32 v41, v0
	v_mov_b32_e32 v42, v0
	v_mov_b32_e32 v43, v0
	v_mov_b32_e32 v44, v0
	v_mov_b32_e32 v45, v0
	v_mov_b32_e32 v46, v0
	v_mov_b32_e32 v47, v0
	v_mov_b32_e32 v16, v0
	v_mov_b32_e32 v17, v0
	v_mov_b32_e32 v18, v0
	v_mov_b32_e32 v19, v0
	v_mov_b32_e32 v20, v0
	v_mov_b32_e32 v21, v0
	v_mov_b32_e32 v22, v0
	v_mov_b32_e32 v23, v0
	v_mov_b32_e32 v32, v0
	v_mov_b32_e32 v33, v0
	v_mov_b32_e32 v34, v0
	v_mov_b32_e32 v35, v0
	v_mov_b32_e32 v36, v0
	v_mov_b32_e32 v37, v0
	v_mov_b32_e32 v38, v0
	v_mov_b32_e32 v39, v0
	v_mov_b32_e32 v48, v0
	v_mov_b32_e32 v49, v0
	v_mov_b32_e32 v50, v0
	v_mov_b32_e32 v51, v0
	v_mov_b32_e32 v52, v0
	v_mov_b32_e32 v53, v0
	v_mov_b32_e32 v54, v0
	v_mov_b32_e32 v55, v0
	v_mov_b32_e32 v56, v0
	v_mov_b32_e32 v57, v0
	v_mov_b32_e32 v58, v0
	v_mov_b32_e32 v59, v0
	v_mov_b32_e32 v60, v0
	v_mov_b32_e32 v61, v0
	v_mov_b32_e32 v62, v0
	v_mov_b32_e32 v63, v0
	v_mov_b32_e32 v64, v0
	v_mov_b32_e32 v65, v0
	v_mov_b32_e32 v66, v0
	v_mov_b32_e32 v67, v0
	v_mov_b32_e32 v68, v0
	v_mov_b32_e32 v69, v0
	v_mov_b32_e32 v70, v0
	v_mov_b32_e32 v71, v0
	v_mov_b32_e32 v72, v0
	v_mov_b32_e32 v73, v0
	v_mov_b32_e32 v74, v0
	v_mov_b32_e32 v75, v0
	v_mov_b32_e32 v76, v0
	v_mov_b32_e32 v77, v0
	v_mov_b32_e32 v78, v0
	s_waitcnt vmcnt(0)
	v_mov_b32_e32 v79, v0
	v_mov_b32_e32 v84, v0
	v_mov_b32_e32 v85, v0
	v_mov_b32_e32 v86, v0
	v_mov_b32_e32 v87, v0
	v_mov_b32_e32 v92, v0
	v_mov_b32_e32 v93, v0
	v_mov_b32_e32 v94, v0
	v_mov_b32_e32 v95, v0
	v_mov_b32_e32 v100, v0
	v_mov_b32_e32 v101, v0
	v_mov_b32_e32 v102, v0
	v_mov_b32_e32 v103, v0
	v_mov_b32_e32 v108, v0
	v_mov_b32_e32 v109, v0
	v_mov_b32_e32 v110, v0
	v_mov_b32_e32 v111, v0
	v_mov_b32_e32 v80, v0
	v_mov_b32_e32 v81, v0
	v_mov_b32_e32 v82, v0
	v_mov_b32_e32 v83, v0
	v_mov_b32_e32 v88, v0
	v_mov_b32_e32 v89, v0
	v_mov_b32_e32 v90, v0
	v_mov_b32_e32 v91, v0
	v_mov_b32_e32 v96, v0
	v_mov_b32_e32 v97, v0
	v_mov_b32_e32 v98, v0
	v_mov_b32_e32 v99, v0
	v_mov_b32_e32 v104, v0
	v_mov_b32_e32 v105, v0
	v_mov_b32_e32 v106, v0
	v_mov_b32_e32 v107, v0
	v_mov_b32_e32 v112, v0
	v_mov_b32_e32 v113, v0
	v_mov_b32_e32 v114, v0
	v_mov_b32_e32 v115, v0
	v_mov_b32_e32 v116, v0
	v_mov_b32_e32 v117, v0
	v_mov_b32_e32 v118, v0
	v_mov_b32_e32 v119, v0
	v_mov_b32_e32 v120, v0
	v_mov_b32_e32 v121, v0
	v_mov_b32_e32 v122, v0
	v_mov_b32_e32 v123, v0
	v_mov_b32_e32 v124, v0
	v_mov_b32_e32 v125, v0
	v_mov_b32_e32 v126, v0
	v_mov_b32_e32 v127, v0
	s_barrier
	v_add_u32_e32 v244, 0x80, v128
	v_add_u32_e32 v245, 0x80, v148
; #define PG8_STAGE(bufoff, gbase, voff) do { _Pragma("unroll") for (int _i = 0; _i < 2; ++_i) \
;         __builtin_amdgcn_global_load_lds((const unsigned*)((const char*)(gbase) + (voff)[_i]), (PG8_LAS unsigned*)(lds + (bufoff) + ldsw + _i * 8192), 16, 0, 0); } while (0)
; #define PG8_LDA(dst, b, h) do { _Pragma("unroll") for (int m = 0; m < 4; ++m) _Pragma("unroll") for (int k = 0; k < 2; ++k) dst[m][k] = *(const PG8_LAS bf16x8*)(lds + PG8_SA(b, h) + aoff + m * 2048 + k * 1024); } while (0)
; #define PG8_LDB(dst, b, h) do { _Pragma("unroll") for (int n = 0; n < 2; ++n) _Pragma("unroll") for (int k = 0; k < 2; ++k) dst[n][k] = *(const PG8_LAS bf16x8*)(lds + PG8_SB(b, h) + boff + n * 2048 + k * 1024); } while (0)
; #define PG8_MMA(ai, bj, At, Bt) do { __builtin_amdgcn_s_setprio(1); _Pragma("unroll") for (int m = 0; m < 4; ++m) _Pragma("unroll") for (int n = 0; n < 2; ++n) _Pragma("unroll") for (int k = 0; k < 2; ++k) \
;         acc[ai][bj][m][n] = __builtin_amdgcn_mfma_f32_16x16x32_bf16(Bt[n][k], At[m][k], acc[ai][bj][m][n], 0, 0, 0); __builtin_amdgcn_s_setprio(0); } while (0)
; #define PG8_WAIT_L(n) asm volatile("s_waitcnt lgkmcnt(" #n ")" ::: "memory")
; #define PG8_BAR __builtin_amdgcn_s_barrier()
; #define PG8_SCHED __builtin_amdgcn_sched_barrier(0)
; template <class Epi, class Sched, bool STAMP = false>
; __device__ __forceinline__ void gemm_phase(PG8_LAS unsigned char* lds, const Gemm g, const Sched& S, const Epi& E, unsigned long long* stamps) {
;     ...
;         for (int t = 0; t < nt; t += 2) {
;             const bool last = (t == nt - 2);
;             const char* a1 = cA + (size_t)(t + 1) * kstep;
;             const char* a2 = last ? nA : cA + (size_t)(t + 2) * kstep; const char* b2 = last ? nB : cB + (size_t)(t + 2) * kstep;
;             const char* a3 = a2 + kstep; const char* b3 = b2 + kstep;
;             if (last && has_next) S.a_ready(nxt);
;             PG8_LDB(B0, 0, 0); PG8_SCHED; PG8_LDA(At, 0, 0); PG8_STAGE(PG8_SA(1, 1), a1 + hstep, voffA);
;             PG8_WAIT_L(8); PG8_BAR; PG8_WAIT_L(0); PG8_MMA(0, 0, At, B0); PG8_BAR; PG8_SCHED;
;             PG8_LDB(B1, 0, 1); PG8_STAGE(PG8_SB(0, 0), b2, voffB);
;             PG8_BAR; PG8_WAIT_L(0); PG8_MMA(0, 1, At, B1); PG8_BAR;
;             PG8_LDA(At, 0, 1); PG8_STAGE(PG8_SA(0, 0), a2, voffA);
;             PG8_BAR; PG8_WAIT_L(0); PG8_MMA(1, 0, At, B0); PG8_BAR; PG8_SCHED;
.LBB0_1207:
	s_add_u32 s6, s4, 0x100
	s_addc_u32 s7, s5, 0
	s_cmp_lg_u32 s39, 4
	s_cselect_b32 s12, s6, 0
	s_cselect_b32 s13, s7, 0
	s_add_u32 s20, s2, s12
	s_addc_u32 s21, s3, s13
	s_add_i32 s14, 0, 0x10000
	v_add_u32_e32 v157, s14, v155
	ds_read_b128 v[158:161], v157
	ds_read_b128 v[162:165], v157 offset:1024
	ds_read_b128 v[166:169], v157 offset:2048
	ds_read_b128 v[170:173], v157 offset:3072
	s_add_u32 s12, s0, s12
	s_addc_u32 s13, s1, s13
	v_lshl_add_u64 v[182:183], v[150:151], 0, s[4:5]
	s_add_i32 m0, s27, 0xc000
	ds_read_b128 v[174:177], v156
	ds_read_b128 v[178:181], v156 offset:1024
	ds_read_b128 v[192:195], v156 offset:2048
	ds_read_b128 v[196:199], v156 offset:3072
	ds_read_b128 v[200:203], v156 offset:4096
	ds_read_b128 v[204:207], v156 offset:5120
	ds_read_b128 v[208:211], v156 offset:6144
	ds_read_b128 v[212:215], v156 offset:7168
	global_load_lds_dwordx4 v[182:183], off
	v_lshl_add_u64 v[182:183], v[152:153], 0, s[4:5]
	s_add_i32 m0, s27, 0xe000
	s_nop 0
	global_load_lds_dwordx4 v[182:183], off
	s_waitcnt lgkmcnt(8)
	s_barrier
	s_waitcnt lgkmcnt(0)
	v_mfma_f32_16x16x32_bf16 v[124:127], v[158:161], v[174:177], v[124:127]
	v_mfma_f32_16x16x32_bf16 v[120:123], v[166:169], v[174:177], v[120:123]
	v_mfma_f32_16x16x32_bf16 v[116:119], v[158:161], v[192:195], v[116:119]
	v_mfma_f32_16x16x32_bf16 v[112:115], v[166:169], v[192:195], v[112:115]
	v_mfma_f32_16x16x32_bf16 v[104:107], v[158:161], v[200:203], v[104:107]
	v_mfma_f32_16x16x32_bf16 v[96:99], v[166:169], v[200:203], v[96:99]
	v_mfma_f32_16x16x32_bf16 v[88:91], v[158:161], v[208:211], v[88:91]
	v_mfma_f32_16x16x32_bf16 v[80:83], v[166:169], v[208:211], v[80:83]
	v_mfma_f32_16x16x32_bf16 v[124:127], v[162:165], v[178:181], v[124:127]
	v_mfma_f32_16x16x32_bf16 v[120:123], v[170:173], v[178:181], v[120:123]
	v_mfma_f32_16x16x32_bf16 v[116:119], v[162:165], v[196:199], v[116:119]
	v_mfma_f32_16x16x32_bf16 v[112:115], v[170:173], v[196:199], v[112:115]
	v_mfma_f32_16x16x32_bf16 v[104:107], v[162:165], v[204:207], v[104:107]
	v_mfma_f32_16x16x32_bf16 v[96:99], v[170:173], v[204:207], v[96:99]
	v_mfma_f32_16x16x32_bf16 v[88:91], v[162:165], v[212:215], v[88:91]
	v_mfma_f32_16x16x32_bf16 v[80:83], v[170:173], v[212:215], v[80:83]
	s_barrier
	s_add_i32 s15, 0, 0x14000
	s_add_i32 s4, s14, s26
	v_add_u32_e32 v157, s15, v155
	v_lshl_add_u64 v[182:183], s[12:13], 0, v[128:129]
	s_mov_b32 m0, s4
	ds_read_b128 v[216:219], v157
	ds_read_b128 v[220:223], v157 offset:1024
	ds_read_b128 v[224:227], v157 offset:2048
	ds_read_b128 v[228:231], v157 offset:3072
	global_load_lds_dwordx4 v128, s[12:13]
	v_lshl_add_u64 v[232:233], s[12:13], 0, v[148:149]
	s_add_i32 m0, s4, 0x2000
	s_nop 0
	global_load_lds_dwordx4 v148, s[12:13]
	s_barrier
	s_waitcnt lgkmcnt(0)
	v_mfma_f32_16x16x32_bf16 v[108:111], v[216:219], v[174:177], v[108:111]
	v_mfma_f32_16x16x32_bf16 v[100:103], v[224:227], v[174:177], v[100:103]
	v_mfma_f32_16x16x32_bf16 v[92:95], v[216:219], v[192:195], v[92:95]
	v_mfma_f32_16x16x32_bf16 v[84:87], v[224:227], v[192:195], v[84:87]
	v_mfma_f32_16x16x32_bf16 v[76:79], v[216:219], v[200:203], v[76:79]
	v_mfma_f32_16x16x32_bf16 v[72:75], v[224:227], v[200:203], v[72:75]
	v_mfma_f32_16x16x32_bf16 v[68:71], v[216:219], v[208:211], v[68:71]
	v_mfma_f32_16x16x32_bf16 v[64:67], v[224:227], v[208:211], v[64:67]
	v_mfma_f32_16x16x32_bf16 v[108:111], v[220:223], v[178:181], v[108:111]
	v_mfma_f32_16x16x32_bf16 v[100:103], v[228:231], v[178:181], v[100:103]
	v_mfma_f32_16x16x32_bf16 v[92:95], v[220:223], v[196:199], v[92:95]
	v_mfma_f32_16x16x32_bf16 v[84:87], v[228:231], v[196:199], v[84:87]
	v_mfma_f32_16x16x32_bf16 v[76:79], v[220:223], v[204:207], v[76:79]
	v_mfma_f32_16x16x32_bf16 v[72:75], v[228:231], v[204:207], v[72:75]
	v_mfma_f32_16x16x32_bf16 v[68:71], v[220:223], v[212:215], v[68:71]
	v_mfma_f32_16x16x32_bf16 v[64:67], v[228:231], v[212:215], v[64:67]
	s_mov_b32 m0, s27
	v_lshl_add_u64 v[234:235], s[20:21], 0, v[128:129]
	s_barrier
	ds_read_b128 v[174:177], v156 offset:16384
	ds_read_b128 v[178:181], v156 offset:17408
	ds_read_b128 v[192:195], v156 offset:18432
	ds_read_b128 v[196:199], v156 offset:19456
	ds_read_b128 v[200:203], v156 offset:20480
	ds_read_b128 v[204:207], v156 offset:21504
	ds_read_b128 v[208:211], v156 offset:22528
	ds_read_b128 v[212:215], v156 offset:23552
	global_load_lds_dwordx4 v128, s[20:21]
	v_lshl_add_u64 v[236:237], s[20:21], 0, v[148:149]
	s_mov_b32 m0, s30
	s_nop 0
	global_load_lds_dwordx4 v148, s[20:21]
	s_barrier
	s_waitcnt lgkmcnt(0)
	v_mfma_f32_16x16x32_bf16 v[60:63], v[158:161], v[174:177], v[60:63]
	v_mfma_f32_16x16x32_bf16 v[56:59], v[166:169], v[174:177], v[56:59]
	v_mfma_f32_16x16x32_bf16 v[52:55], v[158:161], v[192:195], v[52:55]
	v_mfma_f32_16x16x32_bf16 v[48:51], v[166:169], v[192:195], v[48:51]
	v_mfma_f32_16x16x32_bf16 v[36:39], v[158:161], v[200:203], v[36:39]
	v_mfma_f32_16x16x32_bf16 v[32:35], v[166:169], v[200:203], v[32:35]
	v_mfma_f32_16x16x32_bf16 v[20:23], v[158:161], v[208:211], v[20:23]
	v_mfma_f32_16x16x32_bf16 v[16:19], v[166:169], v[208:211], v[16:19]
	v_mfma_f32_16x16x32_bf16 v[60:63], v[162:165], v[178:181], v[60:63]
	v_mfma_f32_16x16x32_bf16 v[56:59], v[170:173], v[178:181], v[56:59]
	v_mfma_f32_16x16x32_bf16 v[52:55], v[162:165], v[196:199], v[52:55]
	v_mfma_f32_16x16x32_bf16 v[48:51], v[170:173], v[196:199], v[48:51]
	v_mfma_f32_16x16x32_bf16 v[36:39], v[162:165], v[204:207], v[36:39]
	v_mfma_f32_16x16x32_bf16 v[32:35], v[170:173], v[204:207], v[32:35]
	v_mfma_f32_16x16x32_bf16 v[20:23], v[162:165], v[212:215], v[20:23]
	v_mfma_f32_16x16x32_bf16 v[16:19], v[170:173], v[212:215], v[16:19]
	s_barrier
; #define PG8_STAGE(bufoff, gbase, voff) do { _Pragma("unroll") for (int _i = 0; _i < 2; ++_i) \
;         __builtin_amdgcn_global_load_lds((const unsigned*)((const char*)(gbase) + (voff)[_i]), (PG8_LAS unsigned*)(lds + (bufoff) + ldsw + _i * 8192), 16, 0, 0); } while (0)
; #define PG8_LDA(dst, b, h) do { _Pragma("unroll") for (int m = 0; m < 4; ++m) _Pragma("unroll") for (int k = 0; k < 2; ++k) dst[m][k] = *(const PG8_LAS bf16x8*)(lds + PG8_SA(b, h) + aoff + m * 2048 + k * 1024); } while (0)
; #define PG8_LDB(dst, b, h) do { _Pragma("unroll") for (int n = 0; n < 2; ++n) _Pragma("unroll") for (int k = 0; k < 2; ++k) dst[n][k] = *(const PG8_LAS bf16x8*)(lds + PG8_SB(b, h) + boff + n * 2048 + k * 1024); } while (0)
; #define PG8_MMA(ai, bj, At, Bt) do { __builtin_amdgcn_s_setprio(1); _Pragma("unroll") for (int m = 0; m < 4; ++m) _Pragma("unroll") for (int n = 0; n < 2; ++n) _Pragma("unroll") for (int k = 0; k < 2; ++k) \
;         acc[ai][bj][m][n] = __builtin_amdgcn_mfma_f32_16x16x32_bf16(Bt[n][k], At[m][k], acc[ai][bj][m][n], 0, 0, 0); __builtin_amdgcn_s_setprio(0); } while (0)
; #define PG8_WAIT_V(n) asm volatile("s_waitcnt vmcnt(" #n ")" ::: "memory")
; #define PG8_WAIT_L(n) asm volatile("s_waitcnt lgkmcnt(" #n ")" ::: "memory")
; #define PG8_BAR __builtin_amdgcn_s_barrier()
; #define PG8_SCHED __builtin_amdgcn_sched_barrier(0)
; template <class Epi, class Sched, bool STAMP = false>
; __device__ __forceinline__ void gemm_phase(PG8_LAS unsigned char* lds, const Gemm g, const Sched& S, const Epi& E, unsigned long long* stamps) {
;     ...
;             PG8_STAGE(PG8_SB(0, 1), b2 + hstep, voffB);
;             PG8_WAIT_V(6); PG8_BAR; PG8_MMA(1, 1, At, B1); PG8_BAR;
;             PG8_LDB(B0, 1, 0); PG8_SCHED; PG8_LDA(At, 1, 0); PG8_STAGE(PG8_SA(0, 1), a2 + hstep, voffA);
;             PG8_WAIT_L(8); PG8_BAR; PG8_WAIT_L(0); PG8_MMA(0, 0, At, B0); PG8_BAR; PG8_SCHED;
;             PG8_LDB(B1, 1, 1); PG8_STAGE(PG8_SB(1, 0), b3, voffB);
;             PG8_BAR; PG8_WAIT_L(0); PG8_MMA(0, 1, At, B1); PG8_BAR;
;             PG8_LDA(At, 1, 1); PG8_STAGE(PG8_SA(1, 0), a3, voffA);
	s_add_u32 s4, s12, 0x100000
	s_addc_u32 s5, s13, 0
	s_add_i32 s14, s15, s26
	s_mov_b32 m0, s14
	s_nop 0
	global_load_lds_dwordx4 v128, s[4:5]
	s_add_i32 m0, s14, 0x2000
	s_nop 0
	global_load_lds_dwordx4 v148, s[4:5]
	s_waitcnt vmcnt(6)
	s_barrier
	v_mfma_f32_16x16x32_bf16 v[44:47], v[216:219], v[174:177], v[44:47]
	v_mfma_f32_16x16x32_bf16 v[40:43], v[224:227], v[174:177], v[40:43]
	v_mfma_f32_16x16x32_bf16 v[28:31], v[216:219], v[192:195], v[28:31]
	v_mfma_f32_16x16x32_bf16 v[24:27], v[224:227], v[192:195], v[24:27]
	v_mfma_f32_16x16x32_bf16 v[12:15], v[216:219], v[200:203], v[12:15]
	v_mfma_f32_16x16x32_bf16 v[8:11], v[224:227], v[200:203], v[8:11]
	v_mfma_f32_16x16x32_bf16 v[4:7], v[216:219], v[208:211], v[4:7]
	v_mfma_f32_16x16x32_bf16 v[0:3], v[224:227], v[208:211], v[0:3]
	v_mfma_f32_16x16x32_bf16 v[44:47], v[220:223], v[178:181], v[44:47]
	v_mfma_f32_16x16x32_bf16 v[40:43], v[228:231], v[178:181], v[40:43]
	v_mfma_f32_16x16x32_bf16 v[28:31], v[220:223], v[196:199], v[28:31]
	v_mfma_f32_16x16x32_bf16 v[24:27], v[228:231], v[196:199], v[24:27]
	v_mfma_f32_16x16x32_bf16 v[12:15], v[220:223], v[204:207], v[12:15]
	v_mfma_f32_16x16x32_bf16 v[8:11], v[228:231], v[204:207], v[8:11]
	v_mfma_f32_16x16x32_bf16 v[4:7], v[220:223], v[212:215], v[4:7]
	v_mfma_f32_16x16x32_bf16 v[0:3], v[228:231], v[212:215], v[0:3]
	s_add_i32 s14, 0, 0x18000
	v_add_u32_e32 v157, s14, v155
	s_barrier
	ds_read_b128 v[158:161], v157
	ds_read_b128 v[162:165], v157 offset:1024
	ds_read_b128 v[166:169], v157 offset:2048
	ds_read_b128 v[170:173], v157 offset:3072
	s_add_u32 s4, s20, 0x100000
	s_addc_u32 s5, s21, 0
	s_mov_b32 m0, s31
	ds_read_b128 v[174:177], v156 offset:32768
	ds_read_b128 v[178:181], v156 offset:33792
	ds_read_b128 v[192:195], v156 offset:34816
	ds_read_b128 v[196:199], v156 offset:35840
	ds_read_b128 v[200:203], v156 offset:36864
	ds_read_b128 v[204:207], v156 offset:37888
	ds_read_b128 v[208:211], v156 offset:38912
	ds_read_b128 v[212:215], v156 offset:39936
	global_load_lds_dwordx4 v128, s[4:5]
	s_mov_b32 m0, s34
	s_nop 0
	global_load_lds_dwordx4 v148, s[4:5]
	s_waitcnt lgkmcnt(8)
	s_barrier
	s_waitcnt lgkmcnt(0)
	v_mfma_f32_16x16x32_bf16 v[124:127], v[158:161], v[174:177], v[124:127]
	v_mfma_f32_16x16x32_bf16 v[120:123], v[166:169], v[174:177], v[120:123]
	v_mfma_f32_16x16x32_bf16 v[116:119], v[158:161], v[192:195], v[116:119]
	v_mfma_f32_16x16x32_bf16 v[112:115], v[166:169], v[192:195], v[112:115]
	v_mfma_f32_16x16x32_bf16 v[104:107], v[158:161], v[200:203], v[104:107]
	v_mfma_f32_16x16x32_bf16 v[96:99], v[166:169], v[200:203], v[96:99]
	v_mfma_f32_16x16x32_bf16 v[88:91], v[158:161], v[208:211], v[88:91]
	v_mfma_f32_16x16x32_bf16 v[80:83], v[166:169], v[208:211], v[80:83]
	v_mfma_f32_16x16x32_bf16 v[124:127], v[162:165], v[178:181], v[124:127]
	v_mfma_f32_16x16x32_bf16 v[120:123], v[170:173], v[178:181], v[120:123]
	v_mfma_f32_16x16x32_bf16 v[116:119], v[162:165], v[196:199], v[116:119]
	v_mfma_f32_16x16x32_bf16 v[112:115], v[170:173], v[196:199], v[112:115]
	v_mfma_f32_16x16x32_bf16 v[104:107], v[162:165], v[204:207], v[104:107]
	v_mfma_f32_16x16x32_bf16 v[96:99], v[170:173], v[204:207], v[96:99]
	v_mfma_f32_16x16x32_bf16 v[88:91], v[162:165], v[212:215], v[88:91]
	v_mfma_f32_16x16x32_bf16 v[80:83], v[170:173], v[212:215], v[80:83]
	s_barrier
	s_add_i32 s15, 0, 0x1c000
	s_add_i32 s4, s14, s26
	v_add_u32_e32 v157, s15, v155
	v_lshl_add_u64 v[182:183], v[182:183], 0, s[18:19]
	s_mov_b32 m0, s4
	ds_read_b128 v[216:219], v157
	ds_read_b128 v[220:223], v157 offset:1024
	ds_read_b128 v[224:227], v157 offset:2048
	ds_read_b128 v[228:231], v157 offset:3072
	global_load_lds_dwordx4 v244, s[12:13]
	v_lshl_add_u64 v[182:183], v[232:233], 0, s[18:19]
	s_add_i32 m0, s4, 0x2000
	s_nop 0
	global_load_lds_dwordx4 v245, s[12:13]
	s_barrier
	s_waitcnt lgkmcnt(0)
	v_mfma_f32_16x16x32_bf16 v[108:111], v[216:219], v[174:177], v[108:111]
	v_mfma_f32_16x16x32_bf16 v[100:103], v[224:227], v[174:177], v[100:103]
	v_mfma_f32_16x16x32_bf16 v[92:95], v[216:219], v[192:195], v[92:95]
	v_mfma_f32_16x16x32_bf16 v[84:87], v[224:227], v[192:195], v[84:87]
	v_mfma_f32_16x16x32_bf16 v[76:79], v[216:219], v[200:203], v[76:79]
	v_mfma_f32_16x16x32_bf16 v[72:75], v[224:227], v[200:203], v[72:75]
	v_mfma_f32_16x16x32_bf16 v[68:71], v[216:219], v[208:211], v[68:71]
	v_mfma_f32_16x16x32_bf16 v[64:67], v[224:227], v[208:211], v[64:67]
	v_mfma_f32_16x16x32_bf16 v[108:111], v[220:223], v[178:181], v[108:111]
	v_mfma_f32_16x16x32_bf16 v[100:103], v[228:231], v[178:181], v[100:103]
	v_mfma_f32_16x16x32_bf16 v[92:95], v[220:223], v[196:199], v[92:95]
	v_mfma_f32_16x16x32_bf16 v[84:87], v[228:231], v[196:199], v[84:87]
	v_mfma_f32_16x16x32_bf16 v[76:79], v[220:223], v[204:207], v[76:79]
	v_mfma_f32_16x16x32_bf16 v[72:75], v[228:231], v[204:207], v[72:75]
	v_mfma_f32_16x16x32_bf16 v[68:71], v[220:223], v[212:215], v[68:71]
	v_mfma_f32_16x16x32_bf16 v[64:67], v[228:231], v[212:215], v[64:67]
	s_mov_b32 m0, s37
	v_lshl_add_u64 v[182:183], v[234:235], 0, s[18:19]
	s_barrier
	ds_read_b128 v[174:177], v156 offset:49152
	ds_read_b128 v[178:181], v156 offset:50176
	ds_read_b128 v[192:195], v156 offset:51200
	ds_read_b128 v[196:199], v156 offset:52224
	ds_read_b128 v[200:203], v156 offset:53248
	ds_read_b128 v[204:207], v156 offset:54272
	ds_read_b128 v[208:211], v156 offset:55296
	ds_read_b128 v[212:215], v156 offset:56320
	global_load_lds_dwordx4 v244, s[20:21]
	v_lshl_add_u64 v[182:183], v[236:237], 0, s[18:19]
	s_mov_b32 m0, s38
	s_nop 0
	global_load_lds_dwordx4 v245, s[20:21]
	s_barrier
; #define PG8_STAGE(bufoff, gbase, voff) do { _Pragma("unroll") for (int _i = 0; _i < 2; ++_i) \
;         __builtin_amdgcn_global_load_lds((const unsigned*)((const char*)(gbase) + (voff)[_i]), (PG8_LAS unsigned*)(lds + (bufoff) + ldsw + _i * 8192), 16, 0, 0); } while (0)
; #define PG8_MMA(ai, bj, At, Bt) do { __builtin_amdgcn_s_setprio(1); _Pragma("unroll") for (int m = 0; m < 4; ++m) _Pragma("unroll") for (int n = 0; n < 2; ++n) _Pragma("unroll") for (int k = 0; k < 2; ++k) \
;         acc[ai][bj][m][n] = __builtin_amdgcn_mfma_f32_16x16x32_bf16(Bt[n][k], At[m][k], acc[ai][bj][m][n], 0, 0, 0); __builtin_amdgcn_s_setprio(0); } while (0)
; #define PG8_WAIT_V(n) asm volatile("s_waitcnt vmcnt(" #n ")" ::: "memory")
; #define PG8_WAIT_L(n) asm volatile("s_waitcnt lgkmcnt(" #n ")" ::: "memory")
; #define PG8_BAR __builtin_amdgcn_s_barrier()
; #define PG8_SCHED __builtin_amdgcn_sched_barrier(0)
; template <class Epi, class Sched, bool STAMP = false>
; __device__ __forceinline__ void gemm_phase(PG8_LAS unsigned char* lds, const Gemm g, const Sched& S, const Epi& E, unsigned long long* stamps) {
;     ...
;             PG8_BAR; PG8_WAIT_L(0); PG8_MMA(1, 0, At, B0); PG8_BAR; PG8_SCHED;
;             PG8_STAGE(PG8_SB(1, 1), b3 + hstep, voffB);
;             PG8_WAIT_V(6); PG8_BAR; PG8_MMA(1, 1, At, B1); PG8_BAR;
;         }
;     __device__ __forceinline__ void operator()(const f32x4 (&acc)[2][2][4][2], const pg8::Unit& u, int wr, int wc, int fr, int fq) const {
;         const int row0 = (u.pm - 64) * 256 + wr * 64 + fr, col0 = u.pn * 256 + wc * 32 + 4 * fq;
; #pragma unroll
;         for (int ai = 0; ai < 2; ++ai)
; #pragma unroll
;             for (int m = 0; m < 4; ++m) { float* xp = PART + (size_t)(row0 + ai * 128 + m * 16) * ldp + col0;
; #pragma unroll
;                 for (int bj = 0; bj < 2; ++bj)
; #pragma unroll
;                     for (int n = 0; n < 2; ++n) *(f32x4*)(xp + bj * 128 + n * 16) = acc[ai][bj][m][n]; }
	s_waitcnt lgkmcnt(0)
	v_mfma_f32_16x16x32_bf16 v[60:63], v[158:161], v[174:177], v[60:63]
	v_mfma_f32_16x16x32_bf16 v[56:59], v[166:169], v[174:177], v[56:59]
	v_mfma_f32_16x16x32_bf16 v[52:55], v[158:161], v[192:195], v[52:55]
	v_mfma_f32_16x16x32_bf16 v[48:51], v[166:169], v[192:195], v[48:51]
	v_mfma_f32_16x16x32_bf16 v[36:39], v[158:161], v[200:203], v[36:39]
	v_mfma_f32_16x16x32_bf16 v[32:35], v[166:169], v[200:203], v[32:35]
	v_mfma_f32_16x16x32_bf16 v[20:23], v[158:161], v[208:211], v[20:23]
	v_mfma_f32_16x16x32_bf16 v[16:19], v[166:169], v[208:211], v[16:19]
	v_mfma_f32_16x16x32_bf16 v[60:63], v[162:165], v[178:181], v[60:63]
	v_mfma_f32_16x16x32_bf16 v[56:59], v[170:173], v[178:181], v[56:59]
	v_mfma_f32_16x16x32_bf16 v[52:55], v[162:165], v[196:199], v[52:55]
	v_mfma_f32_16x16x32_bf16 v[48:51], v[170:173], v[196:199], v[48:51]
	v_mfma_f32_16x16x32_bf16 v[36:39], v[162:165], v[204:207], v[36:39]
	v_mfma_f32_16x16x32_bf16 v[32:35], v[170:173], v[204:207], v[32:35]
	v_mfma_f32_16x16x32_bf16 v[20:23], v[162:165], v[212:215], v[20:23]
	v_mfma_f32_16x16x32_bf16 v[16:19], v[170:173], v[212:215], v[16:19]
	s_barrier
	s_add_u32 s4, s12, 0x100080
	s_addc_u32 s5, s13, 0
	s_add_i32 s12, s15, s26
	s_mov_b32 m0, s12
	s_nop 0
	global_load_lds_dwordx4 v128, s[4:5]
	s_add_i32 m0, s12, 0x2000
	s_nop 0
	global_load_lds_dwordx4 v148, s[4:5]
	s_waitcnt vmcnt(6)
	s_barrier
	v_mfma_f32_16x16x32_bf16 v[44:47], v[216:219], v[174:177], v[44:47]
	v_mfma_f32_16x16x32_bf16 v[40:43], v[224:227], v[174:177], v[40:43]
	v_mfma_f32_16x16x32_bf16 v[28:31], v[216:219], v[192:195], v[28:31]
	v_mfma_f32_16x16x32_bf16 v[24:27], v[224:227], v[192:195], v[24:27]
	v_mfma_f32_16x16x32_bf16 v[12:15], v[216:219], v[200:203], v[12:15]
	v_mfma_f32_16x16x32_bf16 v[8:11], v[224:227], v[200:203], v[8:11]
	v_mfma_f32_16x16x32_bf16 v[4:7], v[216:219], v[208:211], v[4:7]
	v_mfma_f32_16x16x32_bf16 v[0:3], v[224:227], v[208:211], v[0:3]
	v_mfma_f32_16x16x32_bf16 v[44:47], v[220:223], v[178:181], v[44:47]
	v_mfma_f32_16x16x32_bf16 v[40:43], v[228:231], v[178:181], v[40:43]
	v_mfma_f32_16x16x32_bf16 v[28:31], v[220:223], v[196:199], v[28:31]
	v_mfma_f32_16x16x32_bf16 v[24:27], v[228:231], v[196:199], v[24:27]
	v_mfma_f32_16x16x32_bf16 v[12:15], v[220:223], v[204:207], v[12:15]
	v_mfma_f32_16x16x32_bf16 v[8:11], v[228:231], v[204:207], v[8:11]
	v_mfma_f32_16x16x32_bf16 v[4:7], v[220:223], v[212:215], v[4:7]
	v_mfma_f32_16x16x32_bf16 v[0:3], v[228:231], v[212:215], v[0:3]
	s_add_i32 s39, s39, 2
	s_cmp_gt_u32 s39, 5
	s_mov_b64 s[4:5], s[6:7]
	s_barrier
	s_cbranch_scc0 .LBB0_1207
	s_lshl_b32 s0, s25, 22
	s_add_u32 s0, s10, s0
	s_addc_u32 s1, s42, 0
	s_add_u32 s0, s0, 0xdd00000
	s_addc_u32 s1, s1, 0
	s_lshl_b32 s2, s24, 8
	s_add_i32 s2, s2, s35
	v_add_u32_e32 v150, s2, v154
	v_add_u32_e32 v148, 0xffffc000, v150
	s_lshl_b32 s2, s23, 8
	v_lshl_or_b32 v128, v139, 2, s2
	v_ashrrev_i32_e32 v149, 31, v148
	v_or_b32_e32 v128, s36, v128
	v_lshlrev_b64 v[148:149], 12, v[148:149]
	v_lshl_add_u64 v[148:149], s[0:1], 0, v[148:149]
	v_lshlrev_b32_e32 v128, 2, v128
	v_lshl_add_u64 v[148:149], v[148:149], 0, v[128:129]
	global_store_dwordx4 v[148:149], v[124:127], off
	global_store_dwordx4 v[148:149], v[120:123], off offset:64
	global_store_dwordx4 v[148:149], v[108:111], off offset:512
	global_store_dwordx4 v[148:149], v[100:103], off offset:576
	s_cmpk_lt_u32 s22, 0x100
	v_readlane_b32 s39, v242, 28
	v_add_u32_e32 v100, 0xffffc010, v150
	v_ashrrev_i32_e32 v101, 31, v100
	v_lshlrev_b64 v[100:101], 12, v[100:101]
	v_lshl_add_u64 v[100:101], s[0:1], 0, v[100:101]
	v_lshl_add_u64 v[100:101], v[100:101], 0, v[128:129]
	global_store_dwordx4 v[100:101], v[116:119], off
	global_store_dwordx4 v[100:101], v[112:115], off offset:64
	global_store_dwordx4 v[100:101], v[92:95], off offset:512
	global_store_dwordx4 v[100:101], v[84:87], off offset:576
	s_mov_b32 s38, 0x1ffff
	s_nop 0
	v_add_u32_e32 v84, 0xffffc020, v150
	v_ashrrev_i32_e32 v85, 31, v84
	v_lshlrev_b64 v[84:85], 12, v[84:85]
	v_lshl_add_u64 v[84:85], s[0:1], 0, v[84:85]
	v_lshl_add_u64 v[84:85], v[84:85], 0, v[128:129]
	global_store_dwordx4 v[84:85], v[104:107], off
	global_store_dwordx4 v[84:85], v[96:99], off offset:64
	global_store_dwordx4 v[84:85], v[76:79], off offset:512
	global_store_dwordx4 v[84:85], v[72:75], off offset:576
	s_nop 1
	v_add_u32_e32 v72, 0xffffc030, v150
	v_ashrrev_i32_e32 v73, 31, v72
	v_lshlrev_b64 v[72:73], 12, v[72:73]
	v_lshl_add_u64 v[72:73], s[0:1], 0, v[72:73]
	v_lshl_add_u64 v[72:73], v[72:73], 0, v[128:129]
	s_mov_b64 s[0:1], 0x80000
	global_store_dwordx4 v[72:73], v[88:91], off
	global_store_dwordx4 v[72:73], v[80:83], off offset:64
	global_store_dwordx4 v[72:73], v[68:71], off offset:512
	global_store_dwordx4 v[72:73], v[64:67], off offset:576
	s_nop 1
	v_lshl_add_u64 v[64:65], v[148:149], 0, s[0:1]
	s_mov_b32 s0, 0x80000
	v_add_co_u32_e32 v66, vcc, s0, v148
	s_mov_b64 s[0:1], 0x90000
	s_nop 0
	v_addc_co_u32_e32 v67, vcc, 0, v149, vcc
	global_store_dwordx4 v[66:67], v[60:63], off
	global_store_dwordx4 v[64:65], v[56:59], off offset:64
	global_store_dwordx4 v[64:65], v[44:47], off offset:512
	global_store_dwordx4 v[64:65], v[40:43], off offset:576
	s_nop 1
	v_lshl_add_u64 v[40:41], v[148:149], 0, s[0:1]
	s_mov_b32 s0, 0x90000
	v_add_co_u32_e32 v42, vcc, s0, v148
	s_mov_b64 s[0:1], 0xa0000
	s_nop 0
	v_addc_co_u32_e32 v43, vcc, 0, v149, vcc
	global_store_dwordx4 v[42:43], v[52:55], off
	global_store_dwordx4 v[40:41], v[48:51], off offset:64
	global_store_dwordx4 v[40:41], v[28:31], off offset:512
	global_store_dwordx4 v[40:41], v[24:27], off offset:576
	s_nop 1
	v_lshl_add_u64 v[24:25], v[148:149], 0, s[0:1]
	s_mov_b32 s0, 0xa0000
	v_add_co_u32_e32 v26, vcc, s0, v148
	s_mov_b64 s[0:1], 0xb0000
	s_nop 0
	v_addc_co_u32_e32 v27, vcc, 0, v149, vcc
	global_store_dwordx4 v[26:27], v[36:39], off
	global_store_dwordx4 v[24:25], v[32:35], off offset:64
	global_store_dwordx4 v[24:25], v[12:15], off offset:512
	global_store_dwordx4 v[24:25], v[8:11], off offset:576
	s_nop 1
	v_add_co_u32_e32 v10, vcc, 0xb0000, v148
	v_lshl_add_u64 v[8:9], v[148:149], 0, s[0:1]
	s_nop 0
	v_addc_co_u32_e32 v11, vcc, 0, v149, vcc
	global_store_dwordx4 v[10:11], v[20:23], off
	global_store_dwordx4 v[8:9], v[16:19], off offset:64
	global_store_dwordx4 v[8:9], v[4:7], off offset:512
	global_store_dwordx4 v[8:9], v[0:3], off offset:576
	s_waitcnt vmcnt(0)
	s_cbranch_scc0 .LBB0_1210
	s_barrier

; #define PG8_STAGE(bufoff, gbase, voff) do { _Pragma("unroll") for (int _i = 0; _i < 2; ++_i) \
;         __builtin_amdgcn_global_load_lds((const unsigned*)((const char*)(gbase) + (voff)[_i]), (PG8_LAS unsigned*)(lds + (bufoff) + ldsw + _i * 8192), 16, 0, 0); } while (0)
; #define PG8_LDA(dst, b, h) do { _Pragma("unroll") for (int m = 0; m < 4; ++m) _Pragma("unroll") for (int k = 0; k < 2; ++k) dst[m][k] = *(const PG8_LAS bf16x8*)(lds + PG8_SA(b, h) + aoff + m * 2048 + k * 1024); } while (0)
; #define PG8_LDB(dst, b, h) do { _Pragma("unroll") for (int n = 0; n < 2; ++n) _Pragma("unroll") for (int k = 0; k < 2; ++k) dst[n][k] = *(const PG8_LAS bf16x8*)(lds + PG8_SB(b, h) + boff + n * 2048 + k * 1024); } while (0)
; #define PG8_WAIT_L(n) asm volatile("s_waitcnt lgkmcnt(" #n ")" ::: "memory")
; #define PG8_BAR __builtin_amdgcn_s_barrier()
; #define PG8_SCHED __builtin_amdgcn_sched_barrier(0)
;     __device__ bool next(int i, pg8::Unit& u) const { if (i != 0 || !valid) return false; u.pm = pm; u.pn = pn; return true; }
; template <class Epi, class Sched, bool STAMP = false>
; __device__ __forceinline__ void gemm_phase(PG8_LAS unsigned char* lds, const Gemm g, const Sched& S, const Epi& E, unsigned long long* stamps) {
;     ...
;         const bool has_next = S.next(ui + 1, nxt);
;         const char* nA = has_next ? (const char*)g.A + (size_t)nxt.pm * tstep : cA; const char* nB = has_next ? (const char*)g.Bt + (size_t)nxt.pn * tstep : cB;
;         for (int t = 0; t < nt; t += 2) {
;             const bool last = (t == nt - 2);
;             const char* a1 = cA + (size_t)(t + 1) * kstep;
;             const char* a2 = last ? nA : cA + (size_t)(t + 2) * kstep; const char* b2 = last ? nB : cB + (size_t)(t + 2) * kstep;
;             const char* a3 = a2 + kstep; const char* b3 = b2 + kstep;
;             if (last && has_next) S.a_ready(nxt);
;             PG8_LDB(B0, 0, 0); PG8_SCHED; PG8_LDA(At, 0, 0); PG8_STAGE(PG8_SA(1, 1), a1 + hstep, voffA);
;             PG8_WAIT_L(8); PG8_BAR; PG8_WAIT_L(0); PG8_MMA(0, 0, At, B0); PG8_BAR; PG8_SCHED;
;     ...
; #pragma unroll
;         for (int a = 0; a < 2; ++a)
; #pragma unroll
;             for (int b = 0; b < 2; ++b)
; #pragma unroll
;                 for (int m = 0; m < 4; ++m)
; #pragma unroll
;                     for (int n = 0; n < 2; ++n) acc[a][b][m][n] = (f32x4){0.f, 0.f, 0.f, 0.f};
;         cur = nxt; cA = nA; cB = nB; ++ui;
.LBB0_1339:
	s_ashr_i32 s7, s6, 31
	v_cmp_lt_i64_e32 vcc, s[12:13], v[146:147]
	s_lshl_b64 s[12:13], s[6:7], 19
	s_add_u32 s12, s37, s12
	s_addc_u32 s13, s40, s13
	s_and_b64 s[14:15], vcc, exec
	s_cselect_b32 s7, s13, s25
	s_cselect_b32 s57, s12, s24
	s_ashr_i32 s5, s4, 31
	s_lshl_b64 s[14:15], s[4:5], 19
	s_add_u32 s20, s36, s14
	s_addc_u32 s21, s10, s15
	s_and_b64 s[14:15], vcc, exec
	s_cselect_b32 s5, s21, s27
	s_cselect_b32 s58, s20, s26
	s_add_u32 s24, s24, 0x40080
	s_addc_u32 s25, s25, 0
	s_add_u32 s59, s26, 0x100
	v_mov_b32_e32 v0, 0
	s_addc_u32 s60, s27, 0
	s_mov_b32 s61, -2
	v_mov_b32_e32 v1, v0
	v_mov_b32_e32 v2, v0
	v_mov_b32_e32 v3, v0
	v_mov_b32_e32 v4, v0
	v_mov_b32_e32 v5, v0
	v_mov_b32_e32 v6, v0
	v_mov_b32_e32 v7, v0
	v_mov_b32_e32 v16, v0
	v_mov_b32_e32 v17, v0
	v_mov_b32_e32 v18, v0
	v_mov_b32_e32 v19, v0
	v_mov_b32_e32 v20, v0
	v_mov_b32_e32 v21, v0
	v_mov_b32_e32 v22, v0
	v_mov_b32_e32 v23, v0
	v_mov_b32_e32 v32, v0
	v_mov_b32_e32 v33, v0
	v_mov_b32_e32 v34, v0
	v_mov_b32_e32 v35, v0
	v_mov_b32_e32 v36, v0
	v_mov_b32_e32 v37, v0
	v_mov_b32_e32 v38, v0
	v_mov_b32_e32 v39, v0
	v_mov_b32_e32 v48, v0
	v_mov_b32_e32 v49, v0
	v_mov_b32_e32 v50, v0
	v_mov_b32_e32 v51, v0
	v_mov_b32_e32 v52, v0
	v_mov_b32_e32 v53, v0
	v_mov_b32_e32 v54, v0
	v_mov_b32_e32 v55, v0
	v_mov_b32_e32 v8, v0
	v_mov_b32_e32 v9, v0
	v_mov_b32_e32 v10, v0
	v_mov_b32_e32 v11, v0
	v_mov_b32_e32 v12, v0
	v_mov_b32_e32 v13, v0
	v_mov_b32_e32 v14, v0
	v_mov_b32_e32 v15, v0
	v_mov_b32_e32 v24, v0
	v_mov_b32_e32 v25, v0
	v_mov_b32_e32 v26, v0
	v_mov_b32_e32 v27, v0
	v_mov_b32_e32 v28, v0
	v_mov_b32_e32 v29, v0
	v_mov_b32_e32 v30, v0
	v_mov_b32_e32 v31, v0
	v_mov_b32_e32 v40, v0
	v_mov_b32_e32 v41, v0
	v_mov_b32_e32 v42, v0
	v_mov_b32_e32 v43, v0
	v_mov_b32_e32 v44, v0
	v_mov_b32_e32 v45, v0
	v_mov_b32_e32 v46, v0
	v_mov_b32_e32 v47, v0
	v_mov_b32_e32 v56, v0
	v_mov_b32_e32 v57, v0
	v_mov_b32_e32 v58, v0
	v_mov_b32_e32 v59, v0
	v_mov_b32_e32 v60, v0
	v_mov_b32_e32 v61, v0
	v_mov_b32_e32 v62, v0
	v_mov_b32_e32 v63, v0
	v_mov_b32_e32 v64, v0
	v_mov_b32_e32 v65, v0
	v_mov_b32_e32 v66, v0
	v_mov_b32_e32 v67, v0
	v_mov_b32_e32 v68, v0
	v_mov_b32_e32 v69, v0
	v_mov_b32_e32 v70, v0
	v_mov_b32_e32 v71, v0
	v_mov_b32_e32 v80, v0
	v_mov_b32_e32 v81, v0
	v_mov_b32_e32 v82, v0
	v_mov_b32_e32 v83, v0
	v_mov_b32_e32 v84, v0
	v_mov_b32_e32 v85, v0
	v_mov_b32_e32 v86, v0
	v_mov_b32_e32 v87, v0
	v_mov_b32_e32 v96, v0
	v_mov_b32_e32 v97, v0
	s_waitcnt vmcnt(0)
	v_mov_b32_e32 v98, v0
	v_mov_b32_e32 v99, v0
	v_mov_b32_e32 v100, v0
	v_mov_b32_e32 v101, v0
	v_mov_b32_e32 v102, v0
	v_mov_b32_e32 v103, v0
	v_mov_b32_e32 v112, v0
	v_mov_b32_e32 v113, v0
	v_mov_b32_e32 v114, v0
	v_mov_b32_e32 v115, v0
	v_mov_b32_e32 v116, v0
	v_mov_b32_e32 v117, v0
	v_mov_b32_e32 v118, v0
	v_mov_b32_e32 v119, v0
	v_mov_b32_e32 v72, v0
	v_mov_b32_e32 v73, v0
	v_mov_b32_e32 v74, v0
	v_mov_b32_e32 v75, v0
	v_mov_b32_e32 v76, v0
	v_mov_b32_e32 v77, v0
	v_mov_b32_e32 v78, v0
	v_mov_b32_e32 v79, v0
	v_mov_b32_e32 v88, v0
	v_mov_b32_e32 v89, v0
	v_mov_b32_e32 v90, v0
	v_mov_b32_e32 v91, v0
	v_mov_b32_e32 v92, v0
	v_mov_b32_e32 v93, v0
	v_mov_b32_e32 v94, v0
	v_mov_b32_e32 v95, v0
	v_mov_b32_e32 v104, v0
	v_mov_b32_e32 v105, v0
	v_mov_b32_e32 v106, v0
	v_mov_b32_e32 v107, v0
	v_mov_b32_e32 v108, v0
	v_mov_b32_e32 v109, v0
	v_mov_b32_e32 v110, v0
	v_mov_b32_e32 v111, v0
	v_mov_b32_e32 v120, v0
	v_mov_b32_e32 v121, v0
	v_mov_b32_e32 v122, v0
	v_mov_b32_e32 v123, v0
	v_mov_b32_e32 v124, v0
	v_mov_b32_e32 v125, v0
	v_mov_b32_e32 v126, v0
	v_mov_b32_e32 v127, v0
	v_add_u32_e32 v244, 0x80, v128
	v_add_u32_e32 v245, 0x80, v148
	v_add_u32_e32 v246, 0x80, v152
	v_add_u32_e32 v247, 0x80, v150
.LBB0_1340:
	s_add_u32 s14, s24, 0xfffc0080
	s_addc_u32 s15, s25, -1
	s_add_i32 s16, 0, 0x10000
	v_add_u32_e32 v169, s16, v166
	ds_read_b128 v[158:161], v169
	ds_read_b128 v[162:165], v169 offset:1024
	ds_read_b128 v[170:173], v169 offset:2048
	ds_read_b128 v[174:177], v169 offset:3072
	s_cmp_eq_u32 s61, 12
	s_cselect_b32 s31, s7, s15
	s_cselect_b32 s30, s57, s14
	s_cselect_b32 s27, s5, s60
	s_cselect_b32 s26, s58, s59
	s_add_i32 m0, s23, 0xc000
	ds_read_b128 v[178:181], v168
	ds_read_b128 v[192:195], v168 offset:1024
	ds_read_b128 v[196:199], v168 offset:2048
	ds_read_b128 v[200:203], v168 offset:3072
	ds_read_b128 v[204:207], v168 offset:4096
	ds_read_b128 v[208:211], v168 offset:5120
	ds_read_b128 v[212:215], v168 offset:6144
	ds_read_b128 v[216:219], v168 offset:7168
	global_load_lds_dwordx4 v154, s[24:25]
	s_add_i32 m0, s23, 0xe000
	s_nop 0
	global_load_lds_dwordx4 v156, s[24:25]
	s_waitcnt lgkmcnt(8)
	s_barrier
	s_waitcnt lgkmcnt(0)
	v_mfma_f32_16x16x32_bf16 v[124:127], v[158:161], v[178:181], v[124:127]
	v_mfma_f32_16x16x32_bf16 v[120:123], v[170:173], v[178:181], v[120:123]
	v_mfma_f32_16x16x32_bf16 v[108:111], v[158:161], v[196:199], v[108:111]
	v_mfma_f32_16x16x32_bf16 v[104:107], v[170:173], v[196:199], v[104:107]
	v_mfma_f32_16x16x32_bf16 v[92:95], v[158:161], v[204:207], v[92:95]
	v_mfma_f32_16x16x32_bf16 v[88:91], v[170:173], v[204:207], v[88:91]
	v_mfma_f32_16x16x32_bf16 v[76:79], v[158:161], v[212:215], v[76:79]
	v_mfma_f32_16x16x32_bf16 v[72:75], v[170:173], v[212:215], v[72:75]
	v_mfma_f32_16x16x32_bf16 v[124:127], v[162:165], v[192:195], v[124:127]
	v_mfma_f32_16x16x32_bf16 v[120:123], v[174:177], v[192:195], v[120:123]
	v_mfma_f32_16x16x32_bf16 v[108:111], v[162:165], v[200:203], v[108:111]
	v_mfma_f32_16x16x32_bf16 v[104:107], v[174:177], v[200:203], v[104:107]
	v_mfma_f32_16x16x32_bf16 v[92:95], v[162:165], v[208:211], v[92:95]
	v_mfma_f32_16x16x32_bf16 v[88:91], v[174:177], v[208:211], v[88:91]
	v_mfma_f32_16x16x32_bf16 v[76:79], v[162:165], v[216:219], v[76:79]
	v_mfma_f32_16x16x32_bf16 v[72:75], v[174:177], v[216:219], v[72:75]
	s_barrier
; #define PG8_STAGE(bufoff, gbase, voff) do { _Pragma("unroll") for (int _i = 0; _i < 2; ++_i) \
;         __builtin_amdgcn_global_load_lds((const unsigned*)((const char*)(gbase) + (voff)[_i]), (PG8_LAS unsigned*)(lds + (bufoff) + ldsw + _i * 8192), 16, 0, 0); } while (0)
; #define PG8_LDA(dst, b, h) do { _Pragma("unroll") for (int m = 0; m < 4; ++m) _Pragma("unroll") for (int k = 0; k < 2; ++k) dst[m][k] = *(const PG8_LAS bf16x8*)(lds + PG8_SA(b, h) + aoff + m * 2048 + k * 1024); } while (0)
; #define PG8_LDB(dst, b, h) do { _Pragma("unroll") for (int n = 0; n < 2; ++n) _Pragma("unroll") for (int k = 0; k < 2; ++k) dst[n][k] = *(const PG8_LAS bf16x8*)(lds + PG8_SB(b, h) + boff + n * 2048 + k * 1024); } while (0)
; #define PG8_MMA(ai, bj, At, Bt) do { __builtin_amdgcn_s_setprio(1); _Pragma("unroll") for (int m = 0; m < 4; ++m) _Pragma("unroll") for (int n = 0; n < 2; ++n) _Pragma("unroll") for (int k = 0; k < 2; ++k) \
;         acc[ai][bj][m][n] = __builtin_amdgcn_mfma_f32_16x16x32_bf16(Bt[n][k], At[m][k], acc[ai][bj][m][n], 0, 0, 0); __builtin_amdgcn_s_setprio(0); } while (0)
; #define PG8_WAIT_V(n) asm volatile("s_waitcnt vmcnt(" #n ")" ::: "memory")
; #define PG8_WAIT_L(n) asm volatile("s_waitcnt lgkmcnt(" #n ")" ::: "memory")
; #define PG8_BAR __builtin_amdgcn_s_barrier()
; #define PG8_SCHED __builtin_amdgcn_sched_barrier(0)
; template <class Epi, class Sched, bool STAMP = false>
; __device__ __forceinline__ void gemm_phase(PG8_LAS unsigned char* lds, const Gemm g, const Sched& S, const Epi& E, unsigned long long* stamps) {
;     ...
;             PG8_LDB(B1, 0, 1); PG8_STAGE(PG8_SB(0, 0), b2, voffB);
;             PG8_BAR; PG8_WAIT_L(0); PG8_MMA(0, 1, At, B1); PG8_BAR;
;             PG8_LDA(At, 0, 1); PG8_STAGE(PG8_SA(0, 0), a2, voffA);
;             PG8_BAR; PG8_WAIT_L(0); PG8_MMA(1, 0, At, B0); PG8_BAR; PG8_SCHED;
;             PG8_STAGE(PG8_SB(0, 1), b2 + hstep, voffB);
;             PG8_WAIT_V(6); PG8_BAR; PG8_MMA(1, 1, At, B1); PG8_BAR;
;             PG8_LDB(B0, 1, 0); PG8_SCHED; PG8_LDA(At, 1, 0); PG8_STAGE(PG8_SA(0, 1), a2 + hstep, voffA);
;             PG8_WAIT_L(8); PG8_BAR; PG8_WAIT_L(0); PG8_MMA(0, 0, At, B0); PG8_BAR; PG8_SCHED;
	s_add_i32 s17, 0, 0x14000
	s_add_i32 s14, s16, s43
	v_add_u32_e32 v169, s17, v166
	s_mov_b32 m0, s14
	ds_read_b128 v[220:223], v169
	ds_read_b128 v[224:227], v169 offset:1024
	ds_read_b128 v[228:231], v169 offset:2048
	ds_read_b128 v[232:235], v169 offset:3072
	global_load_lds_dwordx4 v128, s[26:27]
	s_add_i32 m0, s14, 0x2000
	s_nop 0
	global_load_lds_dwordx4 v148, s[26:27]
	s_barrier
	s_waitcnt lgkmcnt(0)
	v_mfma_f32_16x16x32_bf16 v[116:119], v[220:223], v[178:181], v[116:119]
	v_mfma_f32_16x16x32_bf16 v[112:115], v[228:231], v[178:181], v[112:115]
	v_mfma_f32_16x16x32_bf16 v[100:103], v[220:223], v[196:199], v[100:103]
	v_mfma_f32_16x16x32_bf16 v[96:99], v[228:231], v[196:199], v[96:99]
	v_mfma_f32_16x16x32_bf16 v[84:87], v[220:223], v[204:207], v[84:87]
	v_mfma_f32_16x16x32_bf16 v[80:83], v[228:231], v[204:207], v[80:83]
	v_mfma_f32_16x16x32_bf16 v[68:71], v[220:223], v[212:215], v[68:71]
	v_mfma_f32_16x16x32_bf16 v[64:67], v[228:231], v[212:215], v[64:67]
	v_mfma_f32_16x16x32_bf16 v[116:119], v[224:227], v[192:195], v[116:119]
	v_mfma_f32_16x16x32_bf16 v[112:115], v[232:235], v[192:195], v[112:115]
	v_mfma_f32_16x16x32_bf16 v[100:103], v[224:227], v[200:203], v[100:103]
	v_mfma_f32_16x16x32_bf16 v[96:99], v[232:235], v[200:203], v[96:99]
	v_mfma_f32_16x16x32_bf16 v[84:87], v[224:227], v[208:211], v[84:87]
	v_mfma_f32_16x16x32_bf16 v[80:83], v[232:235], v[208:211], v[80:83]
	v_mfma_f32_16x16x32_bf16 v[68:71], v[224:227], v[216:219], v[68:71]
	v_mfma_f32_16x16x32_bf16 v[64:67], v[232:235], v[216:219], v[64:67]
	s_mov_b32 m0, s23
	s_barrier
	ds_read_b128 v[178:181], v168 offset:16384
	ds_read_b128 v[192:195], v168 offset:17408
	ds_read_b128 v[196:199], v168 offset:18432
	ds_read_b128 v[200:203], v168 offset:19456
	ds_read_b128 v[204:207], v168 offset:20480
	ds_read_b128 v[208:211], v168 offset:21504
	ds_read_b128 v[212:215], v168 offset:22528
	ds_read_b128 v[216:219], v168 offset:23552
	global_load_lds_dwordx4 v152, s[30:31]
	s_mov_b32 m0, s45
	s_nop 0
	global_load_lds_dwordx4 v150, s[30:31]
	s_barrier
	s_waitcnt lgkmcnt(0)
	v_mfma_f32_16x16x32_bf16 v[60:63], v[158:161], v[178:181], v[60:63]
	v_mfma_f32_16x16x32_bf16 v[56:59], v[170:173], v[178:181], v[56:59]
	v_mfma_f32_16x16x32_bf16 v[44:47], v[158:161], v[196:199], v[44:47]
	v_mfma_f32_16x16x32_bf16 v[40:43], v[170:173], v[196:199], v[40:43]
	v_mfma_f32_16x16x32_bf16 v[28:31], v[158:161], v[204:207], v[28:31]
	v_mfma_f32_16x16x32_bf16 v[24:27], v[170:173], v[204:207], v[24:27]
	v_mfma_f32_16x16x32_bf16 v[12:15], v[158:161], v[212:215], v[12:15]
	v_mfma_f32_16x16x32_bf16 v[8:11], v[170:173], v[212:215], v[8:11]
	v_mfma_f32_16x16x32_bf16 v[60:63], v[162:165], v[192:195], v[60:63]
	v_mfma_f32_16x16x32_bf16 v[56:59], v[174:177], v[192:195], v[56:59]
	v_mfma_f32_16x16x32_bf16 v[44:47], v[162:165], v[200:203], v[44:47]
	v_mfma_f32_16x16x32_bf16 v[40:43], v[174:177], v[200:203], v[40:43]
	v_mfma_f32_16x16x32_bf16 v[28:31], v[162:165], v[208:211], v[28:31]
	v_mfma_f32_16x16x32_bf16 v[24:27], v[174:177], v[208:211], v[24:27]
	v_mfma_f32_16x16x32_bf16 v[12:15], v[162:165], v[216:219], v[12:15]
	v_mfma_f32_16x16x32_bf16 v[8:11], v[174:177], v[216:219], v[8:11]
	s_barrier
	s_add_u32 s14, s26, 0x40000
	s_addc_u32 s15, s27, 0
	s_add_i32 s16, s17, s43
	s_mov_b32 m0, s16
	s_nop 0
	global_load_lds_dwordx4 v128, s[14:15]
	s_add_i32 m0, s16, 0x2000
	s_nop 0
	global_load_lds_dwordx4 v148, s[14:15]
	s_waitcnt vmcnt(6)
	s_barrier
	v_mfma_f32_16x16x32_bf16 v[52:55], v[220:223], v[178:181], v[52:55]
	v_mfma_f32_16x16x32_bf16 v[48:51], v[228:231], v[178:181], v[48:51]
	v_mfma_f32_16x16x32_bf16 v[36:39], v[220:223], v[196:199], v[36:39]
	v_mfma_f32_16x16x32_bf16 v[32:35], v[228:231], v[196:199], v[32:35]
	v_mfma_f32_16x16x32_bf16 v[20:23], v[220:223], v[204:207], v[20:23]
	v_mfma_f32_16x16x32_bf16 v[16:19], v[228:231], v[204:207], v[16:19]
	v_mfma_f32_16x16x32_bf16 v[4:7], v[220:223], v[212:215], v[4:7]
	v_mfma_f32_16x16x32_bf16 v[0:3], v[228:231], v[212:215], v[0:3]
	v_mfma_f32_16x16x32_bf16 v[52:55], v[224:227], v[192:195], v[52:55]
	v_mfma_f32_16x16x32_bf16 v[48:51], v[232:235], v[192:195], v[48:51]
	v_mfma_f32_16x16x32_bf16 v[36:39], v[224:227], v[200:203], v[36:39]
	v_mfma_f32_16x16x32_bf16 v[32:35], v[232:235], v[200:203], v[32:35]
	v_mfma_f32_16x16x32_bf16 v[20:23], v[224:227], v[208:211], v[20:23]
	v_mfma_f32_16x16x32_bf16 v[16:19], v[232:235], v[208:211], v[16:19]
	v_mfma_f32_16x16x32_bf16 v[4:7], v[224:227], v[216:219], v[4:7]
	v_mfma_f32_16x16x32_bf16 v[0:3], v[232:235], v[216:219], v[0:3]
	s_add_i32 s16, 0, 0x18000
	v_add_u32_e32 v169, s16, v166
	s_barrier
	ds_read_b128 v[158:161], v169
	ds_read_b128 v[162:165], v169 offset:1024
	ds_read_b128 v[170:173], v169 offset:2048
	ds_read_b128 v[174:177], v169 offset:3072
	s_add_u32 s14, s30, 0x40000
	s_addc_u32 s15, s31, 0
	s_mov_b32 m0, s46
	ds_read_b128 v[178:181], v168 offset:32768
	ds_read_b128 v[192:195], v168 offset:33792
	ds_read_b128 v[196:199], v168 offset:34816
	ds_read_b128 v[200:203], v168 offset:35840
	ds_read_b128 v[204:207], v168 offset:36864
	ds_read_b128 v[208:211], v168 offset:37888
	ds_read_b128 v[212:215], v168 offset:38912
	ds_read_b128 v[216:219], v168 offset:39936
	global_load_lds_dwordx4 v152, s[14:15]
	s_mov_b32 m0, s47
	s_nop 0
	global_load_lds_dwordx4 v150, s[14:15]
	s_waitcnt lgkmcnt(8)
	s_barrier
; #define PG8_STAGE(bufoff, gbase, voff) do { _Pragma("unroll") for (int _i = 0; _i < 2; ++_i) \
;         __builtin_amdgcn_global_load_lds((const unsigned*)((const char*)(gbase) + (voff)[_i]), (PG8_LAS unsigned*)(lds + (bufoff) + ldsw + _i * 8192), 16, 0, 0); } while (0)
; #define PG8_LDA(dst, b, h) do { _Pragma("unroll") for (int m = 0; m < 4; ++m) _Pragma("unroll") for (int k = 0; k < 2; ++k) dst[m][k] = *(const PG8_LAS bf16x8*)(lds + PG8_SA(b, h) + aoff + m * 2048 + k * 1024); } while (0)
; #define PG8_LDB(dst, b, h) do { _Pragma("unroll") for (int n = 0; n < 2; ++n) _Pragma("unroll") for (int k = 0; k < 2; ++k) dst[n][k] = *(const PG8_LAS bf16x8*)(lds + PG8_SB(b, h) + boff + n * 2048 + k * 1024); } while (0)
; #define PG8_MMA(ai, bj, At, Bt) do { __builtin_amdgcn_s_setprio(1); _Pragma("unroll") for (int m = 0; m < 4; ++m) _Pragma("unroll") for (int n = 0; n < 2; ++n) _Pragma("unroll") for (int k = 0; k < 2; ++k) \
;         acc[ai][bj][m][n] = __builtin_amdgcn_mfma_f32_16x16x32_bf16(Bt[n][k], At[m][k], acc[ai][bj][m][n], 0, 0, 0); __builtin_amdgcn_s_setprio(0); } while (0)
; #define PG8_WAIT_V(n) asm volatile("s_waitcnt vmcnt(" #n ")" ::: "memory")
; #define PG8_WAIT_L(n) asm volatile("s_waitcnt lgkmcnt(" #n ")" ::: "memory")
; #define PG8_BAR __builtin_amdgcn_s_barrier()
; #define PG8_SCHED __builtin_amdgcn_sched_barrier(0)
; template <class Epi, class Sched, bool STAMP = false>
; __device__ __forceinline__ void gemm_phase(PG8_LAS unsigned char* lds, const Gemm g, const Sched& S, const Epi& E, unsigned long long* stamps) {
;     ...
;             PG8_WAIT_L(8); PG8_BAR; PG8_WAIT_L(0); PG8_MMA(0, 0, At, B0); PG8_BAR; PG8_SCHED;
;             PG8_LDB(B1, 1, 1); PG8_STAGE(PG8_SB(1, 0), b3, voffB);
;             PG8_BAR; PG8_WAIT_L(0); PG8_MMA(0, 1, At, B1); PG8_BAR;
;             PG8_LDA(At, 1, 1); PG8_STAGE(PG8_SA(1, 0), a3, voffA);
;             PG8_BAR; PG8_WAIT_L(0); PG8_MMA(1, 0, At, B0); PG8_BAR; PG8_SCHED;
;             PG8_STAGE(PG8_SB(1, 1), b3 + hstep, voffB);
;             PG8_WAIT_V(6); PG8_BAR; PG8_MMA(1, 1, At, B1); PG8_BAR;
	s_waitcnt lgkmcnt(0)
	v_mfma_f32_16x16x32_bf16 v[124:127], v[158:161], v[178:181], v[124:127]
	v_mfma_f32_16x16x32_bf16 v[120:123], v[170:173], v[178:181], v[120:123]
	v_mfma_f32_16x16x32_bf16 v[108:111], v[158:161], v[196:199], v[108:111]
	v_mfma_f32_16x16x32_bf16 v[104:107], v[170:173], v[196:199], v[104:107]
	v_mfma_f32_16x16x32_bf16 v[92:95], v[158:161], v[204:207], v[92:95]
	v_mfma_f32_16x16x32_bf16 v[88:91], v[170:173], v[204:207], v[88:91]
	v_mfma_f32_16x16x32_bf16 v[76:79], v[158:161], v[212:215], v[76:79]
	v_mfma_f32_16x16x32_bf16 v[72:75], v[170:173], v[212:215], v[72:75]
	v_mfma_f32_16x16x32_bf16 v[124:127], v[162:165], v[192:195], v[124:127]
	v_mfma_f32_16x16x32_bf16 v[120:123], v[174:177], v[192:195], v[120:123]
	v_mfma_f32_16x16x32_bf16 v[108:111], v[162:165], v[200:203], v[108:111]
	v_mfma_f32_16x16x32_bf16 v[104:107], v[174:177], v[200:203], v[104:107]
	v_mfma_f32_16x16x32_bf16 v[92:95], v[162:165], v[208:211], v[92:95]
	v_mfma_f32_16x16x32_bf16 v[88:91], v[174:177], v[208:211], v[88:91]
	v_mfma_f32_16x16x32_bf16 v[76:79], v[162:165], v[216:219], v[76:79]
	v_mfma_f32_16x16x32_bf16 v[72:75], v[174:177], v[216:219], v[72:75]
	s_barrier
	s_add_i32 s17, 0, 0x1c000
	s_add_i32 s14, s16, s43
	v_add_u32_e32 v169, s17, v166
	s_mov_b32 m0, s14
	ds_read_b128 v[220:223], v169
	ds_read_b128 v[224:227], v169 offset:1024
	ds_read_b128 v[228:231], v169 offset:2048
	ds_read_b128 v[232:235], v169 offset:3072
	global_load_lds_dwordx4 v244, s[26:27]
	s_add_i32 m0, s14, 0x2000
	s_nop 0
	global_load_lds_dwordx4 v245, s[26:27]
	s_barrier
	s_waitcnt lgkmcnt(0)
	v_mfma_f32_16x16x32_bf16 v[116:119], v[220:223], v[178:181], v[116:119]
	v_mfma_f32_16x16x32_bf16 v[112:115], v[228:231], v[178:181], v[112:115]
	v_mfma_f32_16x16x32_bf16 v[100:103], v[220:223], v[196:199], v[100:103]
	v_mfma_f32_16x16x32_bf16 v[96:99], v[228:231], v[196:199], v[96:99]
	v_mfma_f32_16x16x32_bf16 v[84:87], v[220:223], v[204:207], v[84:87]
	v_mfma_f32_16x16x32_bf16 v[80:83], v[228:231], v[204:207], v[80:83]
	v_mfma_f32_16x16x32_bf16 v[68:71], v[220:223], v[212:215], v[68:71]
	v_mfma_f32_16x16x32_bf16 v[64:67], v[228:231], v[212:215], v[64:67]
	v_mfma_f32_16x16x32_bf16 v[116:119], v[224:227], v[192:195], v[116:119]
	v_mfma_f32_16x16x32_bf16 v[112:115], v[232:235], v[192:195], v[112:115]
	v_mfma_f32_16x16x32_bf16 v[100:103], v[224:227], v[200:203], v[100:103]
	v_mfma_f32_16x16x32_bf16 v[96:99], v[232:235], v[200:203], v[96:99]
	v_mfma_f32_16x16x32_bf16 v[84:87], v[224:227], v[208:211], v[84:87]
	v_mfma_f32_16x16x32_bf16 v[80:83], v[232:235], v[208:211], v[80:83]
	v_mfma_f32_16x16x32_bf16 v[68:71], v[224:227], v[216:219], v[68:71]
	v_mfma_f32_16x16x32_bf16 v[64:67], v[232:235], v[216:219], v[64:67]
	s_mov_b32 m0, s48
	s_barrier
	ds_read_b128 v[178:181], v168 offset:49152
	ds_read_b128 v[192:195], v168 offset:50176
	ds_read_b128 v[196:199], v168 offset:51200
	ds_read_b128 v[200:203], v168 offset:52224
	ds_read_b128 v[204:207], v168 offset:53248
	ds_read_b128 v[208:211], v168 offset:54272
	ds_read_b128 v[212:215], v168 offset:55296
	ds_read_b128 v[216:219], v168 offset:56320
	global_load_lds_dwordx4 v246, s[30:31]
	s_mov_b32 m0, s49
	s_nop 0
	global_load_lds_dwordx4 v247, s[30:31]
	s_barrier
	s_waitcnt lgkmcnt(0)
	v_mfma_f32_16x16x32_bf16 v[60:63], v[158:161], v[178:181], v[60:63]
	v_mfma_f32_16x16x32_bf16 v[56:59], v[170:173], v[178:181], v[56:59]
	v_mfma_f32_16x16x32_bf16 v[44:47], v[158:161], v[196:199], v[44:47]
	v_mfma_f32_16x16x32_bf16 v[40:43], v[170:173], v[196:199], v[40:43]
	v_mfma_f32_16x16x32_bf16 v[28:31], v[158:161], v[204:207], v[28:31]
	v_mfma_f32_16x16x32_bf16 v[24:27], v[170:173], v[204:207], v[24:27]
	v_mfma_f32_16x16x32_bf16 v[12:15], v[158:161], v[212:215], v[12:15]
	v_mfma_f32_16x16x32_bf16 v[8:11], v[170:173], v[212:215], v[8:11]
	v_mfma_f32_16x16x32_bf16 v[60:63], v[162:165], v[192:195], v[60:63]
	v_mfma_f32_16x16x32_bf16 v[56:59], v[174:177], v[192:195], v[56:59]
	v_mfma_f32_16x16x32_bf16 v[44:47], v[162:165], v[200:203], v[44:47]
	v_mfma_f32_16x16x32_bf16 v[40:43], v[174:177], v[200:203], v[40:43]
	v_mfma_f32_16x16x32_bf16 v[28:31], v[162:165], v[208:211], v[28:31]
	v_mfma_f32_16x16x32_bf16 v[24:27], v[174:177], v[208:211], v[24:27]
	v_mfma_f32_16x16x32_bf16 v[12:15], v[162:165], v[216:219], v[12:15]
	v_mfma_f32_16x16x32_bf16 v[8:11], v[174:177], v[216:219], v[8:11]
	s_barrier
	s_add_u32 s14, s26, 0x40080
	s_addc_u32 s15, s27, 0
	s_add_i32 s16, s17, s43
	s_mov_b32 m0, s16
	s_nop 0
	global_load_lds_dwordx4 v128, s[14:15]
	s_add_i32 m0, s16, 0x2000
	s_nop 0
	global_load_lds_dwordx4 v148, s[14:15]
	s_waitcnt vmcnt(6)
	s_barrier
	v_mfma_f32_16x16x32_bf16 v[52:55], v[220:223], v[178:181], v[52:55]
	v_mfma_f32_16x16x32_bf16 v[48:51], v[228:231], v[178:181], v[48:51]
	v_mfma_f32_16x16x32_bf16 v[36:39], v[220:223], v[196:199], v[36:39]
	v_mfma_f32_16x16x32_bf16 v[32:35], v[228:231], v[196:199], v[32:35]
	v_mfma_f32_16x16x32_bf16 v[20:23], v[220:223], v[204:207], v[20:23]
	v_mfma_f32_16x16x32_bf16 v[16:19], v[228:231], v[204:207], v[16:19]
	v_mfma_f32_16x16x32_bf16 v[4:7], v[220:223], v[212:215], v[4:7]
	v_mfma_f32_16x16x32_bf16 v[0:3], v[228:231], v[212:215], v[0:3]
	v_mfma_f32_16x16x32_bf16 v[52:55], v[224:227], v[192:195], v[52:55]
	v_mfma_f32_16x16x32_bf16 v[48:51], v[232:235], v[192:195], v[48:51]
	v_mfma_f32_16x16x32_bf16 v[36:39], v[224:227], v[200:203], v[36:39]
	v_mfma_f32_16x16x32_bf16 v[32:35], v[232:235], v[200:203], v[32:35]
	v_mfma_f32_16x16x32_bf16 v[20:23], v[224:227], v[208:211], v[20:23]
	v_mfma_f32_16x16x32_bf16 v[16:19], v[232:235], v[208:211], v[16:19]
	v_mfma_f32_16x16x32_bf16 v[4:7], v[224:227], v[216:219], v[4:7]
	v_mfma_f32_16x16x32_bf16 v[0:3], v[232:235], v[216:219], v[0:3]
	s_add_i32 s61, s61, 2
	s_add_u32 s24, s24, 0x100
	s_addc_u32 s25, s25, 0
	s_add_u32 s59, s59, 0x100
	s_addc_u32 s60, s60, 0
	s_cmp_gt_u32 s61, 13
	s_barrier
; __device__ __forceinline__ unsigned cvt_pk_bf16(float lo, float hi) { const f32x2_cv v = {lo, hi}; const bf16x2_cv b = __builtin_convertvector(v, bf16x2_cv); return __builtin_bit_cast(unsigned, b); }
; __device__ __forceinline__ float rstd_of(const float* rowss, int row) { return rsqrtf(rowss[row] * (1.0f / 1024.0f) + 1e-6f); }
;     __device__ __forceinline__ void operator()(const f32x4 (&acc)[2][2][4][2], const pg8::Unit& u, int wr, int wc, int fr, int fq) const {
;         const int row0 = u.pm * 256 + wr * 64 + fr, col0 = u.pn * 256 + wc * 32 + 8 * fq;
; #pragma unroll
;         for (int ai = 0; ai < 2; ++ai)
; #pragma unroll
;             for (int m = 0; m < 4; ++m) {
;                 const int row = row0 + ai * 128 + m * 16;
;                 const float s = (MODE == 2) ? 1.0f : rstd_of(rowss, row);
;                 bf16_t* rowp = O + (size_t)row * ldc + col0;
; #pragma unroll
;                 for (int bj = 0; bj < 2; ++bj) {
;                     f32x4 v0 = acc[ai][bj][m][0] * s, v1 = acc[ai][bj][m][1] * s;
;                     if (MODE == 1) {
; #pragma unroll
;                         for (int j = 0; j < 4; ++j) { const float a = fmaxf(v0[j], 0.f), b = fmaxf(v1[j], 0.f); v0[j] = a * a; v1[j] = b * b; } }
;                     u32x4 w; w.x = cvt_pk_bf16(v0[0], v0[1]); w.y = cvt_pk_bf16(v0[2], v0[3]); w.z = cvt_pk_bf16(v1[0], v1[1]); w.w = cvt_pk_bf16(v1[2], v1[3]);
;                     *(u32x4*)(rowp + bj * 128) = w; } }
	s_cbranch_scc0 .LBB0_1340
	v_lshl_add_u32 v162, s22, 8, v139
	v_ashrrev_i32_e32 v163, 31, v162
	v_lshl_add_u64 v[158:159], v[162:163], 2, s[0:1]
	global_load_dword v164, v[158:159], off
	global_load_dword v231, v[158:159], off offset:64
	global_load_dword v232, v[158:159], off offset:128
	global_load_dword v233, v[158:159], off offset:192
	global_load_dword v234, v[158:159], off offset:512
	global_load_dword v235, v[158:159], off offset:576
	global_load_dword v236, v[158:159], off offset:640
	global_load_dword v237, v[158:159], off offset:704
	v_lshl_or_b32 v160, s56, 8, v167
	v_ashrrev_i32_e32 v161, 31, v160
	s_mov_b32 s5, 0x80000
	s_mov_b64 s[14:15], 0x80000
	s_mov_b32 s56, s4
	s_mov_b32 s22, s6
	s_mov_b64 s[26:27], s[20:21]
	s_mov_b64 s[24:25], s[12:13]
	s_waitcnt vmcnt(0)
	v_fmamk_f32 v164, v164, 0x3a800000, v187
	v_cmp_gt_f32_e32 vcc, s67, v164
	v_mul_f32_e32 v165, 0x4b800000, v164
	s_nop 0
	v_cndmask_b32_e32 v164, v164, v165, vcc
	v_rsq_f32_e32 v164, v164
	s_nop 0
	v_mul_f32_e32 v165, 0x45800000, v164
	v_cndmask_b32_e32 v170, v164, v165, vcc
	v_lshlrev_b64 v[164:165], 12, v[162:163]
	v_lshl_add_u64 v[172:173], s[2:3], 0, v[164:165]
	v_lshlrev_b64 v[164:165], 1, v[160:161]
	v_lshl_add_u64 v[160:161], v[172:173], 0, v[164:165]
	v_pk_mul_f32 v[126:127], v[126:127], v[170:171] op_sel_hi:[1,0]
	v_pk_mul_f32 v[124:125], v[124:125], v[170:171] op_sel_hi:[1,0]
	v_pk_mul_f32 v[172:173], v[122:123], v[170:171] op_sel_hi:[1,0]
	v_pk_mul_f32 v[122:123], v[120:121], v[170:171] op_sel_hi:[1,0]
	v_cvt_pk_bf16_f32 v120, v124, v125
	v_cvt_pk_bf16_f32 v121, v126, v127
	v_cvt_pk_bf16_f32 v122, v122, v123
	v_cvt_pk_bf16_f32 v123, v172, v173
	global_store_dwordx4 v[160:161], v[120:123], off
	v_pk_mul_f32 v[118:119], v[118:119], v[170:171] op_sel_hi:[1,0]
	v_pk_mul_f32 v[116:117], v[116:117], v[170:171] op_sel_hi:[1,0]
	v_pk_mul_f32 v[120:121], v[114:115], v[170:171] op_sel_hi:[1,0]
	v_pk_mul_f32 v[114:115], v[112:113], v[170:171] op_sel_hi:[1,0]
	v_cvt_pk_bf16_f32 v112, v116, v117
	v_cvt_pk_bf16_f32 v113, v118, v119
	v_cvt_pk_bf16_f32 v114, v114, v115
	v_cvt_pk_bf16_f32 v115, v120, v121
	global_store_dwordx4 v[160:161], v[112:115], off offset:256
	s_nop 1
	v_mov_b32_e32 v114, v231
	s_nop 0
	v_or_b32_e32 v112, 16, v162
	v_ashrrev_i32_e32 v113, 31, v112
	v_lshlrev_b64 v[112:113], 12, v[112:113]
	v_lshl_add_u64 v[112:113], s[2:3], 0, v[112:113]
	v_lshl_add_u64 v[112:113], v[112:113], 0, v[164:165]
	v_fmamk_f32 v114, v114, 0x3a800000, v187
	v_cmp_gt_f32_e32 vcc, s67, v114
	v_mul_f32_e32 v115, 0x4b800000, v114
	s_nop 0
	v_cndmask_b32_e32 v114, v114, v115, vcc
	v_rsq_f32_e32 v114, v114
	s_nop 0
	v_mul_f32_e32 v115, 0x45800000, v114
	v_cndmask_b32_e32 v114, v114, v115, vcc
	v_pk_mul_f32 v[110:111], v[110:111], v[114:115] op_sel_hi:[1,0]
	v_pk_mul_f32 v[108:109], v[108:109], v[114:115] op_sel_hi:[1,0]
	v_pk_mul_f32 v[116:117], v[106:107], v[114:115] op_sel_hi:[1,0]
	v_pk_mul_f32 v[106:107], v[104:105], v[114:115] op_sel_hi:[1,0]
	v_cvt_pk_bf16_f32 v104, v108, v109
	v_cvt_pk_bf16_f32 v105, v110, v111
	v_cvt_pk_bf16_f32 v106, v106, v107
	v_cvt_pk_bf16_f32 v107, v116, v117
	global_store_dwordx4 v[112:113], v[104:107], off
	v_pk_mul_f32 v[102:103], v[102:103], v[114:115] op_sel_hi:[1,0]
	v_pk_mul_f32 v[100:101], v[100:101], v[114:115] op_sel_hi:[1,0]
	v_pk_mul_f32 v[104:105], v[98:99], v[114:115] op_sel_hi:[1,0]
	v_pk_mul_f32 v[98:99], v[96:97], v[114:115] op_sel_hi:[1,0]
	v_cvt_pk_bf16_f32 v96, v100, v101
	v_cvt_pk_bf16_f32 v97, v102, v103
	v_cvt_pk_bf16_f32 v98, v98, v99
	v_cvt_pk_bf16_f32 v99, v104, v105
	global_store_dwordx4 v[112:113], v[96:99], off offset:256
	s_nop 1
	v_mov_b32_e32 v98, v232
	s_nop 0
	v_or_b32_e32 v96, 32, v162
	v_ashrrev_i32_e32 v97, 31, v96
	v_lshlrev_b64 v[96:97], 12, v[96:97]
	v_lshl_add_u64 v[96:97], s[2:3], 0, v[96:97]
	v_lshl_add_u64 v[96:97], v[96:97], 0, v[164:165]
	v_fmamk_f32 v98, v98, 0x3a800000, v187
	v_cmp_gt_f32_e32 vcc, s67, v98
	v_mul_f32_e32 v99, 0x4b800000, v98
	s_nop 0
	v_cndmask_b32_e32 v98, v98, v99, vcc
	v_rsq_f32_e32 v98, v98
	s_nop 0
	v_mul_f32_e32 v99, 0x45800000, v98
	v_cndmask_b32_e32 v98, v98, v99, vcc
	v_pk_mul_f32 v[94:95], v[94:95], v[98:99] op_sel_hi:[1,0]
	v_pk_mul_f32 v[92:93], v[92:93], v[98:99] op_sel_hi:[1,0]
	v_pk_mul_f32 v[100:101], v[90:91], v[98:99] op_sel_hi:[1,0]
	v_pk_mul_f32 v[90:91], v[88:89], v[98:99] op_sel_hi:[1,0]
	v_cvt_pk_bf16_f32 v88, v92, v93
	v_cvt_pk_bf16_f32 v89, v94, v95
	v_cvt_pk_bf16_f32 v90, v90, v91
	v_cvt_pk_bf16_f32 v91, v100, v101
	global_store_dwordx4 v[96:97], v[88:91], off
	v_pk_mul_f32 v[86:87], v[86:87], v[98:99] op_sel_hi:[1,0]
	v_pk_mul_f32 v[84:85], v[84:85], v[98:99] op_sel_hi:[1,0]
	v_pk_mul_f32 v[88:89], v[82:83], v[98:99] op_sel_hi:[1,0]
	v_pk_mul_f32 v[82:83], v[80:81], v[98:99] op_sel_hi:[1,0]
	v_cvt_pk_bf16_f32 v80, v84, v85
	v_cvt_pk_bf16_f32 v81, v86, v87
	v_cvt_pk_bf16_f32 v82, v82, v83
	v_cvt_pk_bf16_f32 v83, v88, v89
	global_store_dwordx4 v[96:97], v[80:83], off offset:256
	s_nop 1
	v_mov_b32_e32 v82, v233
	s_nop 0
	v_or_b32_e32 v80, 48, v162
	v_ashrrev_i32_e32 v81, 31, v80
	v_lshlrev_b64 v[80:81], 12, v[80:81]
	v_lshl_add_u64 v[80:81], s[2:3], 0, v[80:81]
	v_lshl_add_u64 v[80:81], v[80:81], 0, v[164:165]
	v_fmamk_f32 v82, v82, 0x3a800000, v187
	v_cmp_gt_f32_e32 vcc, s67, v82
	v_mul_f32_e32 v83, 0x4b800000, v82
	s_nop 0
	v_cndmask_b32_e32 v82, v82, v83, vcc
	v_rsq_f32_e32 v82, v82
	s_nop 0
	v_mul_f32_e32 v83, 0x45800000, v82
	v_cndmask_b32_e32 v82, v82, v83, vcc
	v_pk_mul_f32 v[78:79], v[78:79], v[82:83] op_sel_hi:[1,0]
	v_pk_mul_f32 v[76:77], v[76:77], v[82:83] op_sel_hi:[1,0]
	v_pk_mul_f32 v[84:85], v[74:75], v[82:83] op_sel_hi:[1,0]
; __device__ __forceinline__ unsigned cvt_pk_bf16(float lo, float hi) { const f32x2_cv v = {lo, hi}; const bf16x2_cv b = __builtin_convertvector(v, bf16x2_cv); return __builtin_bit_cast(unsigned, b); }
; #define PG8_WAIT_V(n) asm volatile("s_waitcnt vmcnt(" #n ")" ::: "memory")
; #define PG8_BAR __builtin_amdgcn_s_barrier()
; template <class Epi, class Sched, bool STAMP = false>
; __device__ __forceinline__ void gemm_phase(PG8_LAS unsigned char* lds, const Gemm g, const Sched& S, const Epi& E, unsigned long long* stamps) {
;     ...
;         if constexpr (!Epi::AFTER_DRAIN) { E(acc, cur, wr, wc, fr, fq); S.done(cur); }
;         if (!has_next) break;
; #pragma unroll
;         for (int a = 0; a < 2; ++a)
; #pragma unroll
;             for (int b = 0; b < 2; ++b)
; #pragma unroll
;                 for (int m = 0; m < 4; ++m)
; #pragma unroll
;                     for (int n = 0; n < 2; ++n) acc[a][b][m][n] = (f32x4){0.f, 0.f, 0.f, 0.f};
;         cur = nxt; cA = nA; cB = nB; ++ui;
;     }
;     PG8_WAIT_V(0);
;     if (wr == 0) PG8_BAR;
;     PG8_BAR;
;     __device__ __forceinline__ void operator()(const f32x4 (&acc)[2][2][4][2], const pg8::Unit& u, int wr, int wc, int fr, int fq) const {
;     ...
;                     f32x4 v0 = acc[ai][bj][m][0] * s, v1 = acc[ai][bj][m][1] * s;
;                     if (MODE == 1) {
; #pragma unroll
;                         for (int j = 0; j < 4; ++j) { const float a = fmaxf(v0[j], 0.f), b = fmaxf(v1[j], 0.f); v0[j] = a * a; v1[j] = b * b; } }
;                     u32x4 w; w.x = cvt_pk_bf16(v0[0], v0[1]); w.y = cvt_pk_bf16(v0[2], v0[3]); w.z = cvt_pk_bf16(v1[0], v1[1]); w.w = cvt_pk_bf16(v1[2], v1[3]);
;                     *(u32x4*)(rowp + bj * 128) = w; } }
	v_pk_mul_f32 v[74:75], v[72:73], v[82:83] op_sel_hi:[1,0]
	v_cvt_pk_bf16_f32 v72, v76, v77
	v_cvt_pk_bf16_f32 v73, v78, v79
	v_cvt_pk_bf16_f32 v74, v74, v75
	v_cvt_pk_bf16_f32 v75, v84, v85
	global_store_dwordx4 v[80:81], v[72:75], off
	v_pk_mul_f32 v[70:71], v[70:71], v[82:83] op_sel_hi:[1,0]
	v_pk_mul_f32 v[68:69], v[68:69], v[82:83] op_sel_hi:[1,0]
	v_pk_mul_f32 v[72:73], v[66:67], v[82:83] op_sel_hi:[1,0]
	v_pk_mul_f32 v[66:67], v[64:65], v[82:83] op_sel_hi:[1,0]
	v_cvt_pk_bf16_f32 v64, v68, v69
	v_cvt_pk_bf16_f32 v65, v70, v71
	v_cvt_pk_bf16_f32 v66, v66, v67
	v_cvt_pk_bf16_f32 v67, v72, v73
	global_store_dwordx4 v[80:81], v[64:67], off offset:256
	s_nop 1
	v_mov_b32_e32 v64, v234
	s_nop 0
	v_lshl_add_u64 v[66:67], v[160:161], 0, s[14:15]
	s_mov_b64 s[14:15], 0x90000
	v_fmamk_f32 v64, v64, 0x3a800000, v187
	v_cmp_gt_f32_e32 vcc, s67, v64
	v_mul_f32_e32 v65, 0x4b800000, v64
	s_nop 0
	v_cndmask_b32_e32 v64, v64, v65, vcc
	v_rsq_f32_e32 v64, v64
	s_nop 0
	v_mul_f32_e32 v65, 0x45800000, v64
	v_cndmask_b32_e32 v64, v64, v65, vcc
	v_pk_mul_f32 v[60:61], v[60:61], v[64:65] op_sel_hi:[1,0]
	v_pk_mul_f32 v[62:63], v[62:63], v[64:65] op_sel_hi:[1,0]
	v_pk_mul_f32 v[68:69], v[58:59], v[64:65] op_sel_hi:[1,0]
	v_pk_mul_f32 v[58:59], v[56:57], v[64:65] op_sel_hi:[1,0]
	v_cvt_pk_bf16_f32 v56, v60, v61
	v_add_co_u32_e32 v60, vcc, s5, v160
	v_cvt_pk_bf16_f32 v57, v62, v63
	v_cvt_pk_bf16_f32 v58, v58, v59
	v_cvt_pk_bf16_f32 v59, v68, v69
	v_addc_co_u32_e32 v61, vcc, 0, v161, vcc
	global_store_dwordx4 v[60:61], v[56:59], off
	v_pk_mul_f32 v[54:55], v[54:55], v[64:65] op_sel_hi:[1,0]
	v_pk_mul_f32 v[52:53], v[52:53], v[64:65] op_sel_hi:[1,0]
	v_pk_mul_f32 v[56:57], v[50:51], v[64:65] op_sel_hi:[1,0]
	v_pk_mul_f32 v[50:51], v[48:49], v[64:65] op_sel_hi:[1,0]
	v_cvt_pk_bf16_f32 v48, v52, v53
	v_cvt_pk_bf16_f32 v49, v54, v55
	v_cvt_pk_bf16_f32 v50, v50, v51
	v_cvt_pk_bf16_f32 v51, v56, v57
	global_store_dwordx4 v[66:67], v[48:51], off offset:256
	s_nop 1
	v_mov_b32_e32 v48, v235
	s_mov_b32 s5, 0x90000
	v_lshl_add_u64 v[50:51], v[160:161], 0, s[14:15]
	s_mov_b64 s[14:15], 0xa0000
	v_fmamk_f32 v48, v48, 0x3a800000, v187
	v_cmp_gt_f32_e32 vcc, s67, v48
	v_mul_f32_e32 v49, 0x4b800000, v48
	s_nop 0
	v_cndmask_b32_e32 v48, v48, v49, vcc
	v_rsq_f32_e32 v48, v48
	s_nop 0
	v_mul_f32_e32 v49, 0x45800000, v48
	v_cndmask_b32_e32 v48, v48, v49, vcc
	v_pk_mul_f32 v[44:45], v[44:45], v[48:49] op_sel_hi:[1,0]
	v_pk_mul_f32 v[46:47], v[46:47], v[48:49] op_sel_hi:[1,0]
	v_pk_mul_f32 v[52:53], v[42:43], v[48:49] op_sel_hi:[1,0]
	v_pk_mul_f32 v[42:43], v[40:41], v[48:49] op_sel_hi:[1,0]
	v_cvt_pk_bf16_f32 v40, v44, v45
	v_add_co_u32_e32 v44, vcc, s5, v160
	v_cvt_pk_bf16_f32 v41, v46, v47
	v_cvt_pk_bf16_f32 v42, v42, v43
	v_cvt_pk_bf16_f32 v43, v52, v53
	v_addc_co_u32_e32 v45, vcc, 0, v161, vcc
	global_store_dwordx4 v[44:45], v[40:43], off
	v_pk_mul_f32 v[38:39], v[38:39], v[48:49] op_sel_hi:[1,0]
	v_pk_mul_f32 v[36:37], v[36:37], v[48:49] op_sel_hi:[1,0]
	v_pk_mul_f32 v[40:41], v[34:35], v[48:49] op_sel_hi:[1,0]
	v_pk_mul_f32 v[34:35], v[32:33], v[48:49] op_sel_hi:[1,0]
	v_cvt_pk_bf16_f32 v32, v36, v37
	v_cvt_pk_bf16_f32 v33, v38, v39
	v_cvt_pk_bf16_f32 v34, v34, v35
	v_cvt_pk_bf16_f32 v35, v40, v41
	global_store_dwordx4 v[50:51], v[32:35], off offset:256
	s_nop 1
	v_mov_b32_e32 v32, v236
	s_mov_b32 s5, 0xa0000
	v_lshl_add_u64 v[34:35], v[160:161], 0, s[14:15]
	s_mov_b64 s[14:15], 0xb0000
	v_fmamk_f32 v32, v32, 0x3a800000, v187
	v_cmp_gt_f32_e32 vcc, s67, v32
	v_mul_f32_e32 v33, 0x4b800000, v32
	s_nop 0
	v_cndmask_b32_e32 v32, v32, v33, vcc
	v_rsq_f32_e32 v32, v32
	s_nop 0
	v_mul_f32_e32 v33, 0x45800000, v32
	v_cndmask_b32_e32 v32, v32, v33, vcc
	v_pk_mul_f32 v[28:29], v[28:29], v[32:33] op_sel_hi:[1,0]
	v_pk_mul_f32 v[30:31], v[30:31], v[32:33] op_sel_hi:[1,0]
	v_pk_mul_f32 v[36:37], v[26:27], v[32:33] op_sel_hi:[1,0]
	v_pk_mul_f32 v[26:27], v[24:25], v[32:33] op_sel_hi:[1,0]
	v_cvt_pk_bf16_f32 v24, v28, v29
	v_add_co_u32_e32 v28, vcc, s5, v160
	v_cvt_pk_bf16_f32 v25, v30, v31
	v_cvt_pk_bf16_f32 v26, v26, v27
	v_cvt_pk_bf16_f32 v27, v36, v37
	v_addc_co_u32_e32 v29, vcc, 0, v161, vcc
	global_store_dwordx4 v[28:29], v[24:27], off
	v_pk_mul_f32 v[22:23], v[22:23], v[32:33] op_sel_hi:[1,0]
	v_pk_mul_f32 v[20:21], v[20:21], v[32:33] op_sel_hi:[1,0]
	v_pk_mul_f32 v[24:25], v[18:19], v[32:33] op_sel_hi:[1,0]
	v_pk_mul_f32 v[18:19], v[16:17], v[32:33] op_sel_hi:[1,0]
	v_cvt_pk_bf16_f32 v16, v20, v21
	v_cvt_pk_bf16_f32 v17, v22, v23
	v_cvt_pk_bf16_f32 v18, v18, v19
	v_cvt_pk_bf16_f32 v19, v24, v25
	global_store_dwordx4 v[34:35], v[16:19], off offset:256
	s_nop 1
	v_mov_b32_e32 v16, v237
	s_mov_b32 s5, 0xb0000
	v_lshl_add_u64 v[18:19], v[160:161], 0, s[14:15]
	v_fmamk_f32 v16, v16, 0x3a800000, v187
	v_cmp_gt_f32_e32 vcc, s67, v16
	v_mul_f32_e32 v17, 0x4b800000, v16
	s_nop 0
	v_cndmask_b32_e32 v16, v16, v17, vcc
	v_rsq_f32_e32 v16, v16
	s_nop 0
	v_mul_f32_e32 v17, 0x45800000, v16
	v_cndmask_b32_e32 v16, v16, v17, vcc
	v_pk_mul_f32 v[12:13], v[12:13], v[16:17] op_sel_hi:[1,0]
	v_pk_mul_f32 v[14:15], v[14:15], v[16:17] op_sel_hi:[1,0]
	v_pk_mul_f32 v[20:21], v[10:11], v[16:17] op_sel_hi:[1,0]
	v_pk_mul_f32 v[10:11], v[8:9], v[16:17] op_sel_hi:[1,0]
	v_cvt_pk_bf16_f32 v8, v12, v13
	v_add_co_u32_e32 v12, vcc, s5, v160
	v_cvt_pk_bf16_f32 v9, v14, v15
	v_cvt_pk_bf16_f32 v10, v10, v11
	v_cvt_pk_bf16_f32 v11, v20, v21
	v_addc_co_u32_e32 v13, vcc, 0, v161, vcc
	global_store_dwordx4 v[12:13], v[8:11], off
	v_pk_mul_f32 v[6:7], v[6:7], v[16:17] op_sel_hi:[1,0]
	v_pk_mul_f32 v[4:5], v[4:5], v[16:17] op_sel_hi:[1,0]
	v_pk_mul_f32 v[8:9], v[2:3], v[16:17] op_sel_hi:[1,0]
	v_pk_mul_f32 v[2:3], v[0:1], v[16:17] op_sel_hi:[1,0]
	v_cvt_pk_bf16_f32 v0, v4, v5
	v_cvt_pk_bf16_f32 v1, v6, v7
	v_cvt_pk_bf16_f32 v2, v2, v3
	v_cvt_pk_bf16_f32 v3, v8, v9
	s_and_b64 vcc, exec, s[38:39]
	global_store_dwordx4 v[18:19], v[0:3], off offset:256
	s_cbranch_vccz .LBB0_1337
	s_waitcnt vmcnt(0)
	s_cmpk_gt_u32 s42, 0xff
	s_cbranch_scc1 .LBB0_1344
	s_barrier

; #define PG8_STAGE(bufoff, gbase, voff) do { _Pragma("unroll") for (int _i = 0; _i < 2; ++_i) \
;         __builtin_amdgcn_global_load_lds((const unsigned*)((const char*)(gbase) + (voff)[_i]), (PG8_LAS unsigned*)(lds + (bufoff) + ldsw + _i * 8192), 16, 0, 0); } while (0)
; #define PG8_WAIT_V(n) asm volatile("s_waitcnt vmcnt(" #n ")" ::: "memory")
; #define PG8_BAR __builtin_amdgcn_s_barrier()
; template <class Epi, class Sched, bool STAMP = false>
; __device__ __forceinline__ void gemm_phase(PG8_LAS unsigned char* lds, const Gemm g, const Sched& S, const Epi& E, unsigned long long* stamps) {
;     ...
;     f32x4 acc[2][2][4][2];
; #pragma unroll
;     for (int a = 0; a < 2; ++a)
; #pragma unroll
;         for (int b = 0; b < 2; ++b)
; #pragma unroll
;             for (int m = 0; m < 4; ++m)
; #pragma unroll
;                 for (int n = 0; n < 2; ++n) acc[a][b][m][n] = (f32x4){0.f, 0.f, 0.f, 0.f};
;     bf16x8 At[4][2], B0[2][2], B1[2][2];
;     const char* cA = (const char*)g.A + (size_t)cur.pm * tstep; const char* cB = (const char*)g.Bt + (size_t)cur.pn * tstep;
;     S.a_ready(cur);
;     PG8_STAGE(PG8_SB(0, 0), cB, voffB); PG8_STAGE(PG8_SA(0, 0), cA, voffA); PG8_STAGE(PG8_SB(0, 1), cB + hstep, voffB); PG8_STAGE(PG8_SA(0, 1), cA + hstep, voffA);
;     if (wr == 1) PG8_BAR;
;     PG8_WAIT_V(4); PG8_BAR;
;     PG8_STAGE(PG8_SB(1, 0), cB + kstep, voffB); PG8_STAGE(PG8_SA(1, 0), cA + kstep, voffA); PG8_STAGE(PG8_SB(1, 1), cB + hstep + kstep, voffB);
;     PG8_WAIT_V(6); PG8_BAR;
.LBB0_1348:
	v_bfe_u32 v139, v0, 4, 2
	s_lshl_b32 s14, s14, 5
	v_and_b32_e32 v150, 15, v0
	v_lshlrev_b32_e32 v1, 4, v139
	v_lshlrev_b32_e32 v0, 2, v0
	s_and_b32 s56, s14, 0x60
	v_lshl_add_u64 v[2:3], s[6:7], 0, v[128:129]
	v_mov_b32_e32 v149, v129
	s_lshl_b32 s53, s15, 6
	v_lshl_or_b32 v1, v150, 6, v1
	s_lshl_b32 s15, s15, 13
	v_and_b32_e32 v0, 32, v0
	s_lshl_b32 s14, s56, 7
	v_lshl_add_u64 v[4:5], s[6:7], 0, v[148:149]
	v_bitop3_b32 v10, v1, s15, v0 bitop3:0xde
	v_bitop3_b32 v151, v1, s14, v0 bitop3:0xde
	s_add_i32 m0, s10, 0x18000
	v_lshl_add_u64 v[0:1], v[2:3], 0, s[18:19]
	v_lshl_add_u64 v[6:7], s[12:13], 0, v[128:129]
	s_waitcnt vmcnt(4)
	s_barrier
	global_load_lds_dwordx4 v[0:1], off
	v_lshl_add_u64 v[0:1], v[4:5], 0, s[18:19]
	s_add_i32 m0, s10, 0x1a000
	s_add_i32 s57, s10, 0x8000
	s_add_i32 s58, s10, 0xa000
	v_lshl_add_u64 v[8:9], s[12:13], 0, v[148:149]
	global_load_lds_dwordx4 v[0:1], off
	v_lshl_add_u64 v[0:1], v[6:7], 0, s[18:19]
	s_mov_b32 m0, s57
	s_add_u32 s14, s6, 0x40080
	global_load_lds_dwordx4 v[0:1], off
	v_lshl_add_u64 v[0:1], v[8:9], 0, s[18:19]
	s_mov_b32 m0, s58
	s_addc_u32 s15, s7, 0
	global_load_lds_dwordx4 v[0:1], off
	s_add_i32 m0, s10, 0x1c000
	v_lshl_add_u64 v[0:1], s[14:15], 0, v[128:129]
	global_load_lds_dwordx4 v[0:1], off
	v_lshl_add_u64 v[0:1], s[14:15], 0, v[148:149]
	s_add_i32 m0, s10, 0x1e000
	s_mov_b32 s14, 0
	global_load_lds_dwordx4 v[0:1], off
	s_waitcnt vmcnt(6)
	v_mov_b32_e32 v0, 0
	s_mov_b64 s[22:23], -1
	s_mov_b64 s[24:25], 0
	v_add_u32_e32 v152, 0, v10
	v_mov_b32_e32 v1, v0
	v_mov_b32_e32 v2, v0
	v_mov_b32_e32 v3, v0
	v_mov_b32_e32 v4, v0
	v_mov_b32_e32 v5, v0
	v_mov_b32_e32 v6, v0
	v_mov_b32_e32 v7, v0
	v_mov_b32_e32 v8, v0
	v_mov_b32_e32 v9, v0
	v_mov_b32_e32 v10, v0
	v_mov_b32_e32 v11, v0
	v_mov_b32_e32 v12, v0
	v_mov_b32_e32 v13, v0
	v_mov_b32_e32 v14, v0
	v_mov_b32_e32 v15, v0
	v_mov_b32_e32 v24, v0
	v_mov_b32_e32 v25, v0
	v_mov_b32_e32 v26, v0
	v_mov_b32_e32 v27, v0
	v_mov_b32_e32 v28, v0
	v_mov_b32_e32 v29, v0
	v_mov_b32_e32 v30, v0
	v_mov_b32_e32 v31, v0
	v_mov_b32_e32 v40, v0
	v_mov_b32_e32 v41, v0
	v_mov_b32_e32 v42, v0
	v_mov_b32_e32 v43, v0
	v_mov_b32_e32 v44, v0
	v_mov_b32_e32 v45, v0
	v_mov_b32_e32 v46, v0
	v_mov_b32_e32 v47, v0
	v_mov_b32_e32 v16, v0
	v_mov_b32_e32 v17, v0
	v_mov_b32_e32 v18, v0
	v_mov_b32_e32 v19, v0
	v_mov_b32_e32 v20, v0
	v_mov_b32_e32 v21, v0
	v_mov_b32_e32 v22, v0
	v_mov_b32_e32 v23, v0
	v_mov_b32_e32 v32, v0
	v_mov_b32_e32 v33, v0
	v_mov_b32_e32 v34, v0
	v_mov_b32_e32 v35, v0
	v_mov_b32_e32 v36, v0
	v_mov_b32_e32 v37, v0
	v_mov_b32_e32 v38, v0
	v_mov_b32_e32 v39, v0
	v_mov_b32_e32 v48, v0
	v_mov_b32_e32 v49, v0
	v_mov_b32_e32 v50, v0
	v_mov_b32_e32 v51, v0
	v_mov_b32_e32 v52, v0
	v_mov_b32_e32 v53, v0
	v_mov_b32_e32 v54, v0
	v_mov_b32_e32 v55, v0
	v_mov_b32_e32 v56, v0
	v_mov_b32_e32 v57, v0
	v_mov_b32_e32 v58, v0
	v_mov_b32_e32 v59, v0
	v_mov_b32_e32 v60, v0
	v_mov_b32_e32 v61, v0
	v_mov_b32_e32 v62, v0
	v_mov_b32_e32 v63, v0
	v_mov_b32_e32 v64, v0
	v_mov_b32_e32 v65, v0
	v_mov_b32_e32 v66, v0
	v_mov_b32_e32 v67, v0
	v_mov_b32_e32 v68, v0
	v_mov_b32_e32 v69, v0
	v_mov_b32_e32 v70, v0
	v_mov_b32_e32 v71, v0
	v_mov_b32_e32 v72, v0
	v_mov_b32_e32 v73, v0
	v_mov_b32_e32 v74, v0
	v_mov_b32_e32 v75, v0
	v_mov_b32_e32 v76, v0
	v_mov_b32_e32 v77, v0
	v_mov_b32_e32 v78, v0
	s_waitcnt vmcnt(0)
	v_mov_b32_e32 v79, v0
	v_mov_b32_e32 v84, v0
	v_mov_b32_e32 v85, v0
	v_mov_b32_e32 v86, v0
	v_mov_b32_e32 v87, v0
	v_mov_b32_e32 v92, v0
	v_mov_b32_e32 v93, v0
	v_mov_b32_e32 v94, v0
	v_mov_b32_e32 v95, v0
	v_mov_b32_e32 v100, v0
	v_mov_b32_e32 v101, v0
	v_mov_b32_e32 v102, v0
	v_mov_b32_e32 v103, v0
	v_mov_b32_e32 v108, v0
	v_mov_b32_e32 v109, v0
	v_mov_b32_e32 v110, v0
	v_mov_b32_e32 v111, v0
	v_mov_b32_e32 v80, v0
	v_mov_b32_e32 v81, v0
	v_mov_b32_e32 v82, v0
	v_mov_b32_e32 v83, v0
	v_mov_b32_e32 v88, v0
	v_mov_b32_e32 v89, v0
	v_mov_b32_e32 v90, v0
	v_mov_b32_e32 v91, v0
	v_mov_b32_e32 v96, v0
	v_mov_b32_e32 v97, v0
	v_mov_b32_e32 v98, v0
	v_mov_b32_e32 v99, v0
	v_mov_b32_e32 v104, v0
	v_mov_b32_e32 v105, v0
	v_mov_b32_e32 v106, v0
	v_mov_b32_e32 v107, v0
	v_mov_b32_e32 v112, v0
	v_mov_b32_e32 v113, v0
	v_mov_b32_e32 v114, v0
	v_mov_b32_e32 v115, v0
	v_mov_b32_e32 v116, v0
	v_mov_b32_e32 v117, v0
	v_mov_b32_e32 v118, v0
	v_mov_b32_e32 v119, v0
	v_mov_b32_e32 v120, v0
	v_mov_b32_e32 v121, v0
	v_mov_b32_e32 v122, v0
	v_mov_b32_e32 v123, v0
	v_mov_b32_e32 v124, v0
	v_mov_b32_e32 v125, v0
	v_mov_b32_e32 v126, v0
	v_mov_b32_e32 v127, v0
	s_barrier
	v_add_u32_e32 v244, 0x80, v128
	v_add_u32_e32 v245, 0x80, v148
; #define PG8_STAGE(bufoff, gbase, voff) do { _Pragma("unroll") for (int _i = 0; _i < 2; ++_i) \
;         __builtin_amdgcn_global_load_lds((const unsigned*)((const char*)(gbase) + (voff)[_i]), (PG8_LAS unsigned*)(lds + (bufoff) + ldsw + _i * 8192), 16, 0, 0); } while (0)
; #define PG8_LDA(dst, b, h) do { _Pragma("unroll") for (int m = 0; m < 4; ++m) _Pragma("unroll") for (int k = 0; k < 2; ++k) dst[m][k] = *(const PG8_LAS bf16x8*)(lds + PG8_SA(b, h) + aoff + m * 2048 + k * 1024); } while (0)
; #define PG8_LDB(dst, b, h) do { _Pragma("unroll") for (int n = 0; n < 2; ++n) _Pragma("unroll") for (int k = 0; k < 2; ++k) dst[n][k] = *(const PG8_LAS bf16x8*)(lds + PG8_SB(b, h) + boff + n * 2048 + k * 1024); } while (0)
; #define PG8_MMA(ai, bj, At, Bt) do { __builtin_amdgcn_s_setprio(1); _Pragma("unroll") for (int m = 0; m < 4; ++m) _Pragma("unroll") for (int n = 0; n < 2; ++n) _Pragma("unroll") for (int k = 0; k < 2; ++k) \
;         acc[ai][bj][m][n] = __builtin_amdgcn_mfma_f32_16x16x32_bf16(Bt[n][k], At[m][k], acc[ai][bj][m][n], 0, 0, 0); __builtin_amdgcn_s_setprio(0); } while (0)
; #define PG8_WAIT_L(n) asm volatile("s_waitcnt lgkmcnt(" #n ")" ::: "memory")
; #define PG8_BAR __builtin_amdgcn_s_barrier()
; #define PG8_SCHED __builtin_amdgcn_sched_barrier(0)
; template <class Epi, class Sched, bool STAMP = false>
; __device__ __forceinline__ void gemm_phase(PG8_LAS unsigned char* lds, const Gemm g, const Sched& S, const Epi& E, unsigned long long* stamps) {
;     ...
;         for (int t = 0; t < nt; t += 2) {
;             const bool last = (t == nt - 2);
;             const char* a1 = cA + (size_t)(t + 1) * kstep;
;             const char* a2 = last ? nA : cA + (size_t)(t + 2) * kstep; const char* b2 = last ? nB : cB + (size_t)(t + 2) * kstep;
;             const char* a3 = a2 + kstep; const char* b3 = b2 + kstep;
;             if (last && has_next) S.a_ready(nxt);
;             PG8_LDB(B0, 0, 0); PG8_SCHED; PG8_LDA(At, 0, 0); PG8_STAGE(PG8_SA(1, 1), a1 + hstep, voffA);
;             PG8_WAIT_L(8); PG8_BAR; PG8_WAIT_L(0); PG8_MMA(0, 0, At, B0); PG8_BAR; PG8_SCHED;
;             PG8_LDB(B1, 0, 1); PG8_STAGE(PG8_SB(0, 0), b2, voffB);
;             PG8_BAR; PG8_WAIT_L(0); PG8_MMA(0, 1, At, B1); PG8_BAR;
;             PG8_LDA(At, 0, 1); PG8_STAGE(PG8_SA(0, 0), a2, voffA);
;             PG8_BAR; PG8_WAIT_L(0); PG8_MMA(1, 0, At, B0); PG8_BAR; PG8_SCHED;
.LBB0_1349:
	s_add_i32 s15, s14, 0x100
	s_and_b64 s[16:17], s[24:25], exec
	s_cselect_b32 s15, 0, s15
	s_cselect_b32 s16, 0, 0
	s_add_u32 s36, s12, s15
	s_addc_u32 s37, s13, s16
	s_add_i32 s25, 0, 0x10000
	s_add_u32 s38, s6, s15
	s_addc_u32 s39, s7, s16
	s_add_u32 s40, s20, s14
	s_addc_u32 s41, s21, 0
	s_add_i32 s63, s25, s46
	s_add_i32 m0, s10, 0xc000
	s_add_i32 s64, s10, 0xe000
	s_add_i32 s62, 0, 0x14000
	s_add_i32 s61, s63, 0x2000
	s_add_u32 s30, s38, 0x40000
	v_add_u32_e32 v153, s25, v151
	s_addc_u32 s31, s39, 0
	s_add_i32 s52, s62, s46
	ds_read_b128 v[154:157], v153
	ds_read_b128 v[158:161], v153 offset:1024
	ds_read_b128 v[162:165], v153 offset:2048
	ds_read_b128 v[166:169], v153 offset:3072
	s_add_i32 s29, s52, 0x2000
	s_add_i32 s17, 0, 0x18000
	s_add_u32 s26, s36, 0x40000
	s_addc_u32 s27, s37, 0
	s_add_i32 s16, s17, s46
	s_add_i32 s15, 0, 0x1c000
	s_add_i32 s14, s16, 0x2000
	s_add_u32 s24, s38, 0x40080
	s_addc_u32 s25, s39, 0
	s_add_i32 s60, s15, s46
	s_add_i32 s59, s60, 0x2000
	v_lshl_add_u64 v[182:183], s[40:41], 0, v[128:129]
	v_lshl_add_u64 v[182:183], v[182:183], 0, s[18:19]
	ds_read_b128 v[170:173], v152
	ds_read_b128 v[174:177], v152 offset:1024
	ds_read_b128 v[178:181], v152 offset:2048
	ds_read_b128 v[192:195], v152 offset:3072
	ds_read_b128 v[196:199], v152 offset:4096
	ds_read_b128 v[200:203], v152 offset:5120
	ds_read_b128 v[204:207], v152 offset:6144
	ds_read_b128 v[208:211], v152 offset:7168
	global_load_lds_dwordx4 v244, s[40:41]
	v_lshl_add_u64 v[182:183], s[40:41], 0, v[148:149]
	v_lshl_add_u64 v[182:183], v[182:183], 0, s[18:19]
	s_mov_b32 m0, s64
	s_nop 0
	global_load_lds_dwordx4 v245, s[40:41]
	s_waitcnt lgkmcnt(8)
	s_barrier
	s_waitcnt lgkmcnt(0)
	v_mfma_f32_16x16x32_bf16 v[124:127], v[154:157], v[170:173], v[124:127]
	v_mfma_f32_16x16x32_bf16 v[120:123], v[162:165], v[170:173], v[120:123]
	v_mfma_f32_16x16x32_bf16 v[116:119], v[154:157], v[178:181], v[116:119]
	v_mfma_f32_16x16x32_bf16 v[112:115], v[162:165], v[178:181], v[112:115]
	v_mfma_f32_16x16x32_bf16 v[104:107], v[154:157], v[196:199], v[104:107]
	v_mfma_f32_16x16x32_bf16 v[96:99], v[162:165], v[196:199], v[96:99]
	v_mfma_f32_16x16x32_bf16 v[88:91], v[154:157], v[204:207], v[88:91]
	v_mfma_f32_16x16x32_bf16 v[80:83], v[162:165], v[204:207], v[80:83]
	v_mfma_f32_16x16x32_bf16 v[124:127], v[158:161], v[174:177], v[124:127]
	v_mfma_f32_16x16x32_bf16 v[120:123], v[166:169], v[174:177], v[120:123]
	v_mfma_f32_16x16x32_bf16 v[116:119], v[158:161], v[192:195], v[116:119]
	v_mfma_f32_16x16x32_bf16 v[112:115], v[166:169], v[192:195], v[112:115]
	v_mfma_f32_16x16x32_bf16 v[104:107], v[158:161], v[200:203], v[104:107]
	v_mfma_f32_16x16x32_bf16 v[96:99], v[166:169], v[200:203], v[96:99]
	v_mfma_f32_16x16x32_bf16 v[88:91], v[158:161], v[208:211], v[88:91]
	v_mfma_f32_16x16x32_bf16 v[80:83], v[166:169], v[208:211], v[80:83]
	s_barrier
	s_mov_b32 m0, s63
	v_add_u32_e32 v153, s62, v151
	v_lshl_add_u64 v[182:183], s[38:39], 0, v[128:129]
	ds_read_b128 v[212:215], v153
	ds_read_b128 v[216:219], v153 offset:1024
	ds_read_b128 v[220:223], v153 offset:2048
	ds_read_b128 v[224:227], v153 offset:3072
	global_load_lds_dwordx4 v128, s[38:39]
	v_lshl_add_u64 v[228:229], s[38:39], 0, v[148:149]
	s_mov_b32 m0, s61
	s_nop 0
	global_load_lds_dwordx4 v148, s[38:39]
	s_barrier
	s_waitcnt lgkmcnt(0)
	v_mfma_f32_16x16x32_bf16 v[108:111], v[212:215], v[170:173], v[108:111]
	v_mfma_f32_16x16x32_bf16 v[100:103], v[220:223], v[170:173], v[100:103]
	v_mfma_f32_16x16x32_bf16 v[92:95], v[212:215], v[178:181], v[92:95]
	v_mfma_f32_16x16x32_bf16 v[84:87], v[220:223], v[178:181], v[84:87]
	v_mfma_f32_16x16x32_bf16 v[76:79], v[212:215], v[196:199], v[76:79]
	v_mfma_f32_16x16x32_bf16 v[72:75], v[220:223], v[196:199], v[72:75]
	v_mfma_f32_16x16x32_bf16 v[68:71], v[212:215], v[204:207], v[68:71]
	v_mfma_f32_16x16x32_bf16 v[64:67], v[220:223], v[204:207], v[64:67]
	v_mfma_f32_16x16x32_bf16 v[108:111], v[216:219], v[174:177], v[108:111]
	v_mfma_f32_16x16x32_bf16 v[100:103], v[224:227], v[174:177], v[100:103]
	v_mfma_f32_16x16x32_bf16 v[92:95], v[216:219], v[192:195], v[92:95]
	v_mfma_f32_16x16x32_bf16 v[84:87], v[224:227], v[192:195], v[84:87]
	v_mfma_f32_16x16x32_bf16 v[76:79], v[216:219], v[200:203], v[76:79]
	v_mfma_f32_16x16x32_bf16 v[72:75], v[224:227], v[200:203], v[72:75]
	v_mfma_f32_16x16x32_bf16 v[68:71], v[216:219], v[208:211], v[68:71]
	v_mfma_f32_16x16x32_bf16 v[64:67], v[224:227], v[208:211], v[64:67]
	s_mov_b32 m0, s10
	v_lshl_add_u64 v[230:231], s[36:37], 0, v[128:129]
	s_barrier
	ds_read_b128 v[170:173], v152 offset:16384
	ds_read_b128 v[174:177], v152 offset:17408
	ds_read_b128 v[178:181], v152 offset:18432
	ds_read_b128 v[192:195], v152 offset:19456
	ds_read_b128 v[196:199], v152 offset:20480
	ds_read_b128 v[200:203], v152 offset:21504
	ds_read_b128 v[204:207], v152 offset:22528
	ds_read_b128 v[208:211], v152 offset:23552
	global_load_lds_dwordx4 v128, s[36:37]
	v_lshl_add_u64 v[232:233], s[36:37], 0, v[148:149]
	s_mov_b32 m0, s47
	s_nop 0
	global_load_lds_dwordx4 v148, s[36:37]
	s_barrier
	s_waitcnt lgkmcnt(0)
	v_mfma_f32_16x16x32_bf16 v[60:63], v[154:157], v[170:173], v[60:63]
	v_mfma_f32_16x16x32_bf16 v[56:59], v[162:165], v[170:173], v[56:59]
	v_mfma_f32_16x16x32_bf16 v[52:55], v[154:157], v[178:181], v[52:55]
	v_mfma_f32_16x16x32_bf16 v[48:51], v[162:165], v[178:181], v[48:51]
	v_mfma_f32_16x16x32_bf16 v[36:39], v[154:157], v[196:199], v[36:39]
	v_mfma_f32_16x16x32_bf16 v[32:35], v[162:165], v[196:199], v[32:35]
	v_mfma_f32_16x16x32_bf16 v[20:23], v[154:157], v[204:207], v[20:23]
	v_mfma_f32_16x16x32_bf16 v[16:19], v[162:165], v[204:207], v[16:19]
	v_mfma_f32_16x16x32_bf16 v[60:63], v[158:161], v[174:177], v[60:63]
	v_mfma_f32_16x16x32_bf16 v[56:59], v[166:169], v[174:177], v[56:59]
	v_mfma_f32_16x16x32_bf16 v[52:55], v[158:161], v[192:195], v[52:55]
	v_mfma_f32_16x16x32_bf16 v[48:51], v[166:169], v[192:195], v[48:51]
	v_mfma_f32_16x16x32_bf16 v[36:39], v[158:161], v[200:203], v[36:39]
	v_mfma_f32_16x16x32_bf16 v[32:35], v[166:169], v[200:203], v[32:35]
	v_mfma_f32_16x16x32_bf16 v[20:23], v[158:161], v[208:211], v[20:23]
	v_mfma_f32_16x16x32_bf16 v[16:19], v[166:169], v[208:211], v[16:19]
	s_barrier
; #define PG8_STAGE(bufoff, gbase, voff) do { _Pragma("unroll") for (int _i = 0; _i < 2; ++_i) \
;         __builtin_amdgcn_global_load_lds((const unsigned*)((const char*)(gbase) + (voff)[_i]), (PG8_LAS unsigned*)(lds + (bufoff) + ldsw + _i * 8192), 16, 0, 0); } while (0)
; #define PG8_LDA(dst, b, h) do { _Pragma("unroll") for (int m = 0; m < 4; ++m) _Pragma("unroll") for (int k = 0; k < 2; ++k) dst[m][k] = *(const PG8_LAS bf16x8*)(lds + PG8_SA(b, h) + aoff + m * 2048 + k * 1024); } while (0)
; #define PG8_LDB(dst, b, h) do { _Pragma("unroll") for (int n = 0; n < 2; ++n) _Pragma("unroll") for (int k = 0; k < 2; ++k) dst[n][k] = *(const PG8_LAS bf16x8*)(lds + PG8_SB(b, h) + boff + n * 2048 + k * 1024); } while (0)
; #define PG8_MMA(ai, bj, At, Bt) do { __builtin_amdgcn_s_setprio(1); _Pragma("unroll") for (int m = 0; m < 4; ++m) _Pragma("unroll") for (int n = 0; n < 2; ++n) _Pragma("unroll") for (int k = 0; k < 2; ++k) \
;         acc[ai][bj][m][n] = __builtin_amdgcn_mfma_f32_16x16x32_bf16(Bt[n][k], At[m][k], acc[ai][bj][m][n], 0, 0, 0); __builtin_amdgcn_s_setprio(0); } while (0)
; #define PG8_WAIT_V(n) asm volatile("s_waitcnt vmcnt(" #n ")" ::: "memory")
; #define PG8_WAIT_L(n) asm volatile("s_waitcnt lgkmcnt(" #n ")" ::: "memory")
; #define PG8_BAR __builtin_amdgcn_s_barrier()
; #define PG8_SCHED __builtin_amdgcn_sched_barrier(0)
; template <class Epi, class Sched, bool STAMP = false>
; __device__ __forceinline__ void gemm_phase(PG8_LAS unsigned char* lds, const Gemm g, const Sched& S, const Epi& E, unsigned long long* stamps) {
;     ...
;             PG8_STAGE(PG8_SB(0, 1), b2 + hstep, voffB);
;             PG8_WAIT_V(6); PG8_BAR; PG8_MMA(1, 1, At, B1); PG8_BAR;
;             PG8_LDB(B0, 1, 0); PG8_SCHED; PG8_LDA(At, 1, 0); PG8_STAGE(PG8_SA(0, 1), a2 + hstep, voffA);
;             PG8_WAIT_L(8); PG8_BAR; PG8_WAIT_L(0); PG8_MMA(0, 0, At, B0); PG8_BAR; PG8_SCHED;
;             PG8_LDB(B1, 1, 1); PG8_STAGE(PG8_SB(1, 0), b3, voffB);
;             PG8_BAR; PG8_WAIT_L(0); PG8_MMA(0, 1, At, B1); PG8_BAR;
;             PG8_LDA(At, 1, 1); PG8_STAGE(PG8_SA(1, 0), a3, voffA);
	s_mov_b32 m0, s52
	s_nop 0
	global_load_lds_dwordx4 v128, s[30:31]
	s_mov_b32 m0, s29
	s_nop 0
	global_load_lds_dwordx4 v148, s[30:31]
	s_waitcnt vmcnt(6)
	s_barrier
	v_mfma_f32_16x16x32_bf16 v[44:47], v[212:215], v[170:173], v[44:47]
	v_mfma_f32_16x16x32_bf16 v[40:43], v[220:223], v[170:173], v[40:43]
	v_mfma_f32_16x16x32_bf16 v[28:31], v[212:215], v[178:181], v[28:31]
	v_mfma_f32_16x16x32_bf16 v[24:27], v[220:223], v[178:181], v[24:27]
	v_mfma_f32_16x16x32_bf16 v[12:15], v[212:215], v[196:199], v[12:15]
	v_mfma_f32_16x16x32_bf16 v[8:11], v[220:223], v[196:199], v[8:11]
	v_mfma_f32_16x16x32_bf16 v[4:7], v[212:215], v[204:207], v[4:7]
	v_mfma_f32_16x16x32_bf16 v[0:3], v[220:223], v[204:207], v[0:3]
	v_mfma_f32_16x16x32_bf16 v[44:47], v[216:219], v[174:177], v[44:47]
	v_mfma_f32_16x16x32_bf16 v[40:43], v[224:227], v[174:177], v[40:43]
	v_mfma_f32_16x16x32_bf16 v[28:31], v[216:219], v[192:195], v[28:31]
	v_mfma_f32_16x16x32_bf16 v[24:27], v[224:227], v[192:195], v[24:27]
	v_mfma_f32_16x16x32_bf16 v[12:15], v[216:219], v[200:203], v[12:15]
	v_mfma_f32_16x16x32_bf16 v[8:11], v[224:227], v[200:203], v[8:11]
	v_mfma_f32_16x16x32_bf16 v[4:7], v[216:219], v[208:211], v[4:7]
	v_mfma_f32_16x16x32_bf16 v[0:3], v[224:227], v[208:211], v[0:3]
	v_add_u32_e32 v153, s17, v151
	s_barrier
	ds_read_b128 v[154:157], v153
	ds_read_b128 v[158:161], v153 offset:1024
	ds_read_b128 v[162:165], v153 offset:2048
	ds_read_b128 v[166:169], v153 offset:3072
	s_mov_b32 m0, s48
	ds_read_b128 v[170:173], v152 offset:32768
	ds_read_b128 v[174:177], v152 offset:33792
	ds_read_b128 v[178:181], v152 offset:34816
	ds_read_b128 v[192:195], v152 offset:35840
	ds_read_b128 v[196:199], v152 offset:36864
	ds_read_b128 v[200:203], v152 offset:37888
	ds_read_b128 v[204:207], v152 offset:38912
	ds_read_b128 v[208:211], v152 offset:39936
	global_load_lds_dwordx4 v128, s[26:27]
	s_mov_b32 m0, s49
	s_nop 0
	global_load_lds_dwordx4 v148, s[26:27]
	s_waitcnt lgkmcnt(8)
	s_barrier
	s_waitcnt lgkmcnt(0)
	v_mfma_f32_16x16x32_bf16 v[124:127], v[154:157], v[170:173], v[124:127]
	v_mfma_f32_16x16x32_bf16 v[120:123], v[162:165], v[170:173], v[120:123]
	v_mfma_f32_16x16x32_bf16 v[116:119], v[154:157], v[178:181], v[116:119]
	v_mfma_f32_16x16x32_bf16 v[112:115], v[162:165], v[178:181], v[112:115]
	v_mfma_f32_16x16x32_bf16 v[104:107], v[154:157], v[196:199], v[104:107]
	v_mfma_f32_16x16x32_bf16 v[96:99], v[162:165], v[196:199], v[96:99]
	v_mfma_f32_16x16x32_bf16 v[88:91], v[154:157], v[204:207], v[88:91]
	v_mfma_f32_16x16x32_bf16 v[80:83], v[162:165], v[204:207], v[80:83]
	v_mfma_f32_16x16x32_bf16 v[124:127], v[158:161], v[174:177], v[124:127]
	v_mfma_f32_16x16x32_bf16 v[120:123], v[166:169], v[174:177], v[120:123]
	v_mfma_f32_16x16x32_bf16 v[116:119], v[158:161], v[192:195], v[116:119]
	v_mfma_f32_16x16x32_bf16 v[112:115], v[166:169], v[192:195], v[112:115]
	v_mfma_f32_16x16x32_bf16 v[104:107], v[158:161], v[200:203], v[104:107]
	v_mfma_f32_16x16x32_bf16 v[96:99], v[166:169], v[200:203], v[96:99]
	v_mfma_f32_16x16x32_bf16 v[88:91], v[158:161], v[208:211], v[88:91]
	v_mfma_f32_16x16x32_bf16 v[80:83], v[166:169], v[208:211], v[80:83]
	s_barrier
	s_mov_b32 m0, s16
	v_add_u32_e32 v153, s15, v151
	v_lshl_add_u64 v[182:183], v[182:183], 0, s[18:19]
	ds_read_b128 v[212:215], v153
	ds_read_b128 v[216:219], v153 offset:1024
	ds_read_b128 v[220:223], v153 offset:2048
	ds_read_b128 v[224:227], v153 offset:3072
	global_load_lds_dwordx4 v244, s[38:39]
	v_lshl_add_u64 v[182:183], v[228:229], 0, s[18:19]
	s_mov_b32 m0, s14
	s_nop 0
	global_load_lds_dwordx4 v245, s[38:39]
	s_barrier
	s_waitcnt lgkmcnt(0)
	v_mfma_f32_16x16x32_bf16 v[108:111], v[212:215], v[170:173], v[108:111]
	v_mfma_f32_16x16x32_bf16 v[100:103], v[220:223], v[170:173], v[100:103]
	v_mfma_f32_16x16x32_bf16 v[92:95], v[212:215], v[178:181], v[92:95]
	v_mfma_f32_16x16x32_bf16 v[84:87], v[220:223], v[178:181], v[84:87]
	v_mfma_f32_16x16x32_bf16 v[76:79], v[212:215], v[196:199], v[76:79]
	v_mfma_f32_16x16x32_bf16 v[72:75], v[220:223], v[196:199], v[72:75]
	v_mfma_f32_16x16x32_bf16 v[68:71], v[212:215], v[204:207], v[68:71]
	v_mfma_f32_16x16x32_bf16 v[64:67], v[220:223], v[204:207], v[64:67]
	v_mfma_f32_16x16x32_bf16 v[108:111], v[216:219], v[174:177], v[108:111]
	v_mfma_f32_16x16x32_bf16 v[100:103], v[224:227], v[174:177], v[100:103]
	v_mfma_f32_16x16x32_bf16 v[92:95], v[216:219], v[192:195], v[92:95]
	v_mfma_f32_16x16x32_bf16 v[84:87], v[224:227], v[192:195], v[84:87]
	v_mfma_f32_16x16x32_bf16 v[76:79], v[216:219], v[200:203], v[76:79]
	v_mfma_f32_16x16x32_bf16 v[72:75], v[224:227], v[200:203], v[72:75]
	v_mfma_f32_16x16x32_bf16 v[68:71], v[216:219], v[208:211], v[68:71]
	v_mfma_f32_16x16x32_bf16 v[64:67], v[224:227], v[208:211], v[64:67]
	s_mov_b32 m0, s57
	v_lshl_add_u64 v[182:183], v[230:231], 0, s[18:19]
	s_barrier
	ds_read_b128 v[170:173], v152 offset:49152
	ds_read_b128 v[174:177], v152 offset:50176
	ds_read_b128 v[178:181], v152 offset:51200
	ds_read_b128 v[192:195], v152 offset:52224
	ds_read_b128 v[196:199], v152 offset:53248
	ds_read_b128 v[200:203], v152 offset:54272
	ds_read_b128 v[204:207], v152 offset:55296
	ds_read_b128 v[208:211], v152 offset:56320
	global_load_lds_dwordx4 v244, s[36:37]
	v_lshl_add_u64 v[182:183], v[232:233], 0, s[18:19]
	s_mov_b32 m0, s58
	s_nop 0
	global_load_lds_dwordx4 v245, s[36:37]
	s_barrier
; #define PG8_STAGE(bufoff, gbase, voff) do { _Pragma("unroll") for (int _i = 0; _i < 2; ++_i) \
;         __builtin_amdgcn_global_load_lds((const unsigned*)((const char*)(gbase) + (voff)[_i]), (PG8_LAS unsigned*)(lds + (bufoff) + ldsw + _i * 8192), 16, 0, 0); } while (0)
; #define PG8_MMA(ai, bj, At, Bt) do { __builtin_amdgcn_s_setprio(1); _Pragma("unroll") for (int m = 0; m < 4; ++m) _Pragma("unroll") for (int n = 0; n < 2; ++n) _Pragma("unroll") for (int k = 0; k < 2; ++k) \
;         acc[ai][bj][m][n] = __builtin_amdgcn_mfma_f32_16x16x32_bf16(Bt[n][k], At[m][k], acc[ai][bj][m][n], 0, 0, 0); __builtin_amdgcn_s_setprio(0); } while (0)
; #define PG8_WAIT_V(n) asm volatile("s_waitcnt vmcnt(" #n ")" ::: "memory")
; #define PG8_WAIT_L(n) asm volatile("s_waitcnt lgkmcnt(" #n ")" ::: "memory")
; #define PG8_BAR __builtin_amdgcn_s_barrier()
; #define PG8_SCHED __builtin_amdgcn_sched_barrier(0)
; template <class Epi, class Sched, bool STAMP = false>
; __device__ __forceinline__ void gemm_phase(PG8_LAS unsigned char* lds, const Gemm g, const Sched& S, const Epi& E, unsigned long long* stamps) {
;     ...
;             PG8_BAR; PG8_WAIT_L(0); PG8_MMA(1, 0, At, B0); PG8_BAR; PG8_SCHED;
;             PG8_STAGE(PG8_SB(1, 1), b3 + hstep, voffB);
;             PG8_WAIT_V(6); PG8_BAR; PG8_MMA(1, 1, At, B1); PG8_BAR;
;         }
;     __device__ __forceinline__ void operator()(const f32x4 (&acc)[2][2][4][2], const pg8::Unit& u, int wr, int wc, int fr, int fq) const {
;         const int row0 = (u.pm - 64) * 256 + wr * 64 + fr, col0 = u.pn * 256 + wc * 32 + 4 * fq;
; #pragma unroll
;         for (int ai = 0; ai < 2; ++ai)
; #pragma unroll
;             for (int m = 0; m < 4; ++m) { float* xp = PART + (size_t)(row0 + ai * 128 + m * 16) * ldp + col0;
; #pragma unroll
;                 for (int bj = 0; bj < 2; ++bj)
; #pragma unroll
;                     for (int n = 0; n < 2; ++n) *(f32x4*)(xp + bj * 128 + n * 16) = acc[ai][bj][m][n]; }
	s_waitcnt lgkmcnt(0)
	v_mfma_f32_16x16x32_bf16 v[60:63], v[154:157], v[170:173], v[60:63]
	v_mfma_f32_16x16x32_bf16 v[56:59], v[162:165], v[170:173], v[56:59]
	v_mfma_f32_16x16x32_bf16 v[52:55], v[154:157], v[178:181], v[52:55]
	v_mfma_f32_16x16x32_bf16 v[48:51], v[162:165], v[178:181], v[48:51]
	v_mfma_f32_16x16x32_bf16 v[36:39], v[154:157], v[196:199], v[36:39]
	v_mfma_f32_16x16x32_bf16 v[32:35], v[162:165], v[196:199], v[32:35]
	v_mfma_f32_16x16x32_bf16 v[20:23], v[154:157], v[204:207], v[20:23]
	v_mfma_f32_16x16x32_bf16 v[16:19], v[162:165], v[204:207], v[16:19]
	v_mfma_f32_16x16x32_bf16 v[60:63], v[158:161], v[174:177], v[60:63]
	v_mfma_f32_16x16x32_bf16 v[56:59], v[166:169], v[174:177], v[56:59]
	v_mfma_f32_16x16x32_bf16 v[52:55], v[158:161], v[192:195], v[52:55]
	v_mfma_f32_16x16x32_bf16 v[48:51], v[166:169], v[192:195], v[48:51]
	v_mfma_f32_16x16x32_bf16 v[36:39], v[158:161], v[200:203], v[36:39]
	v_mfma_f32_16x16x32_bf16 v[32:35], v[166:169], v[200:203], v[32:35]
	v_mfma_f32_16x16x32_bf16 v[20:23], v[158:161], v[208:211], v[20:23]
	v_mfma_f32_16x16x32_bf16 v[16:19], v[166:169], v[208:211], v[16:19]
	s_barrier
	s_mov_b32 m0, s60
	s_nop 0
	global_load_lds_dwordx4 v128, s[24:25]
	s_mov_b32 m0, s59
	s_nop 0
	global_load_lds_dwordx4 v148, s[24:25]
	s_waitcnt vmcnt(6)
	s_barrier
	v_mfma_f32_16x16x32_bf16 v[44:47], v[212:215], v[170:173], v[44:47]
	v_mfma_f32_16x16x32_bf16 v[40:43], v[220:223], v[170:173], v[40:43]
	v_mfma_f32_16x16x32_bf16 v[28:31], v[212:215], v[178:181], v[28:31]
	v_mfma_f32_16x16x32_bf16 v[24:27], v[220:223], v[178:181], v[24:27]
	v_mfma_f32_16x16x32_bf16 v[12:15], v[212:215], v[196:199], v[12:15]
	v_mfma_f32_16x16x32_bf16 v[8:11], v[220:223], v[196:199], v[8:11]
	v_mfma_f32_16x16x32_bf16 v[4:7], v[212:215], v[204:207], v[4:7]
	v_mfma_f32_16x16x32_bf16 v[0:3], v[220:223], v[204:207], v[0:3]
	v_mfma_f32_16x16x32_bf16 v[44:47], v[216:219], v[174:177], v[44:47]
	v_mfma_f32_16x16x32_bf16 v[40:43], v[224:227], v[174:177], v[40:43]
	v_mfma_f32_16x16x32_bf16 v[28:31], v[216:219], v[192:195], v[28:31]
	v_mfma_f32_16x16x32_bf16 v[24:27], v[224:227], v[192:195], v[24:27]
	v_mfma_f32_16x16x32_bf16 v[12:15], v[216:219], v[200:203], v[12:15]
	v_mfma_f32_16x16x32_bf16 v[8:11], v[224:227], v[200:203], v[8:11]
	v_mfma_f32_16x16x32_bf16 v[4:7], v[216:219], v[208:211], v[4:7]
	v_mfma_f32_16x16x32_bf16 v[0:3], v[224:227], v[208:211], v[0:3]
	s_andn2_b64 vcc, exec, s[22:23]
	s_mov_b64 s[24:25], -1
	s_mov_b64 s[22:23], 0
	s_movk_i32 s14, 0x100
	s_barrier
	s_cbranch_vccz .LBB0_1349
	s_lshl_b32 s6, s45, 23
	s_add_u32 s6, s4, s6
	s_addc_u32 s7, s5, 0
	s_lshl_b32 s10, s44, 8
	s_add_i32 s10, s10, s53
	v_add_u32_e32 v150, s10, v150
	v_add_u32_e32 v148, 0xffffc000, v150
	s_lshl_b32 s10, s43, 8
	v_lshl_or_b32 v128, v139, 2, s10
	v_ashrrev_i32_e32 v149, 31, v148
	v_or_b32_e32 v128, s56, v128
	v_lshlrev_b64 v[148:149], 13, v[148:149]
	v_lshl_add_u64 v[148:149], s[6:7], 0, v[148:149]
	v_lshlrev_b32_e32 v128, 2, v128
	v_lshl_add_u64 v[148:149], v[148:149], 0, v[128:129]
	global_store_dwordx4 v[148:149], v[124:127], off
	global_store_dwordx4 v[148:149], v[120:123], off offset:64
	global_store_dwordx4 v[148:149], v[108:111], off offset:512
	global_store_dwordx4 v[148:149], v[100:103], off offset:576
	s_cmpk_lt_u32 s42, 0x100
	s_movk_i32 s58, 0xff60
	v_add_u32_e32 v100, 0xffffc010, v150
	v_ashrrev_i32_e32 v101, 31, v100
	v_lshlrev_b64 v[100:101], 13, v[100:101]
	v_lshl_add_u64 v[100:101], s[6:7], 0, v[100:101]
	v_lshl_add_u64 v[100:101], v[100:101], 0, v[128:129]
	global_store_dwordx4 v[100:101], v[116:119], off
	global_store_dwordx4 v[100:101], v[112:115], off offset:64
	global_store_dwordx4 v[100:101], v[92:95], off offset:512
	global_store_dwordx4 v[100:101], v[84:87], off offset:576
	s_nop 1
	v_add_u32_e32 v84, 0xffffc020, v150
	v_ashrrev_i32_e32 v85, 31, v84
	v_lshlrev_b64 v[84:85], 13, v[84:85]
	v_lshl_add_u64 v[84:85], s[6:7], 0, v[84:85]
	v_lshl_add_u64 v[84:85], v[84:85], 0, v[128:129]
	global_store_dwordx4 v[84:85], v[104:107], off
	global_store_dwordx4 v[84:85], v[96:99], off offset:64
	global_store_dwordx4 v[84:85], v[76:79], off offset:512
	global_store_dwordx4 v[84:85], v[72:75], off offset:576
	s_nop 1
	v_add_u32_e32 v72, 0xffffc030, v150
	v_ashrrev_i32_e32 v73, 31, v72
	v_lshlrev_b64 v[72:73], 13, v[72:73]
	v_lshl_add_u64 v[72:73], s[6:7], 0, v[72:73]
	v_lshl_add_u64 v[72:73], v[72:73], 0, v[128:129]
	s_mov_b64 s[6:7], 0x100000
	global_store_dwordx4 v[72:73], v[88:91], off
	global_store_dwordx4 v[72:73], v[80:83], off offset:64
	global_store_dwordx4 v[72:73], v[68:71], off offset:512
	global_store_dwordx4 v[72:73], v[64:67], off offset:576
	s_nop 1
	v_lshl_add_u64 v[64:65], v[148:149], 0, s[6:7]
	s_mov_b32 s6, 0x100000
	v_add_co_u32_e32 v66, vcc, s6, v148
	s_mov_b64 s[6:7], 0x120000
	s_nop 0
	v_addc_co_u32_e32 v67, vcc, 0, v149, vcc
	global_store_dwordx4 v[66:67], v[60:63], off
	global_store_dwordx4 v[64:65], v[56:59], off offset:64
	global_store_dwordx4 v[64:65], v[44:47], off offset:512
	global_store_dwordx4 v[64:65], v[40:43], off offset:576
	s_nop 1
	v_lshl_add_u64 v[40:41], v[148:149], 0, s[6:7]
	s_mov_b32 s6, 0x120000
	v_add_co_u32_e32 v42, vcc, s6, v148
	s_mov_b64 s[6:7], 0x140000
	s_nop 0
	v_addc_co_u32_e32 v43, vcc, 0, v149, vcc
	global_store_dwordx4 v[42:43], v[52:55], off
	global_store_dwordx4 v[40:41], v[48:51], off offset:64
	global_store_dwordx4 v[40:41], v[28:31], off offset:512
	global_store_dwordx4 v[40:41], v[24:27], off offset:576
	s_nop 1
	v_lshl_add_u64 v[24:25], v[148:149], 0, s[6:7]
	s_mov_b32 s6, 0x140000
	v_add_co_u32_e32 v26, vcc, s6, v148
	s_mov_b64 s[6:7], 0x160000
	s_nop 0
	v_addc_co_u32_e32 v27, vcc, 0, v149, vcc
	global_store_dwordx4 v[26:27], v[36:39], off
	global_store_dwordx4 v[24:25], v[32:35], off offset:64
	global_store_dwordx4 v[24:25], v[12:15], off offset:512
	global_store_dwordx4 v[24:25], v[8:11], off offset:576
	s_nop 1
	v_add_co_u32_e32 v10, vcc, 0x160000, v148
	v_lshl_add_u64 v[8:9], v[148:149], 0, s[6:7]
	s_nop 0
	v_addc_co_u32_e32 v11, vcc, 0, v149, vcc
	global_store_dwordx4 v[10:11], v[20:23], off
	global_store_dwordx4 v[8:9], v[16:19], off offset:64
	global_store_dwordx4 v[8:9], v[4:7], off offset:512
	global_store_dwordx4 v[8:9], v[0:3], off offset:576
	s_waitcnt vmcnt(0)
	s_cbranch_scc0 .LBB0_1352
	s_barrier
